# cache policy: drop nt hint on all 352 global stores (v31 base)
# baseline (speedup 1.0000x reference)
; DI void stg16_nt(void* p, u32x4 v) { __builtin_nontemporal_store(v, (u32x4*)p); }
; DI void epi_seg(const f32x16 (&acc)[4][2], const Seg& sg0, const Seg& sg1, int m0, int n0, const float* rs, const float2* cs64, const float2* cs32, bf16_t* stg) {
;     ...
; #pragma unroll
;   for (int it = 0; it < 16; ++it) {
;     const int idx = tid + NTHR * it, rr = idx >> 5, c = idx & 31;
;     const Seg& fs = (c >> 4) ? sg1 : sg0;
;     const int lcc = n0 + c * 8 - fs.cbase;
;     if (fs.kind != K_NONE && lcc < fs.nvalid) {
;       const int row = m0 + rr;
;       size_t off;
;       if (fs.kind == K_KC2) { const int b = row >> 9, n = (row >> 2) & 127, g = row & 3; off = ((size_t)((b * 4 + g) * 128 + n)) * 64 + lcc; }
;       else off = (size_t)row * fs.ld + lcc;
;       stg16_nt(fs.dst + off, stage_read16(stg, rr, c));
;     }
;   }
.LBB0_268:
	s_or_b64 exec, exec, s[46:47]
	v_mov_b32_e32 v161, s63
	v_mov_b32_e32 v162, s62
	v_cmp_gt_u32_e32 vcc, 16, v194
	v_lshl_or_b32 v160, v194, 3, s39
	s_waitcnt lgkmcnt(0)
	v_cndmask_b32_e32 v161, v161, v162, vcc
	v_sub_u32_e32 v160, v160, v161
	v_cmp_gt_i32_e64 s[0:1], 2.0, v160
	s_barrier
	s_and_saveexec_b64 s[46:47], s[0:1]
	s_cbranch_execz .LBB0_270
	v_ashrrev_i32_e32 v164, 5, v193
	v_mov_b32_e32 v162, s38
	v_mov_b32_e32 v163, s40
	v_mov_b32_e32 v165, s43
	v_mov_b32_e32 v166, s37
	v_add_u32_e32 v161, s41, v164
	v_cndmask_b32_e32 v169, v162, v163, vcc
	v_cndmask_b32_e32 v171, v165, v166, vcc
	v_mov_b32_e32 v165, s42
	v_mov_b32_e32 v166, s36
	v_lshlrev_b32_e32 v168, 4, v194
	v_mad_i64_i32 v[162:163], s[0:1], v169, v161, 0
	v_ashrrev_i32_e32 v161, 31, v160
	v_cndmask_b32_e32 v170, v165, v166, vcc
	v_lshl_add_u64 v[162:163], v[162:163], 1, v[170:171]
	v_lshlrev_b64 v[172:173], 1, v[160:161]
	v_mad_u64_u32 v[160:161], s[0:1], v164, s59, v[168:169]
	v_lshl_add_u64 v[174:175], v[162:163], 0, v[172:173]
	ds_read2_b64 v[160:163], v160 offset1:1
	v_add_u32_e32 v164, 0x200, v193
	v_ashrrev_i32_e32 v176, 5, v164
	v_mad_u64_u32 v[164:165], s[0:1], v176, s59, v[168:169]
	ds_read2_b64 v[164:167], v164 offset1:1
	s_waitcnt lgkmcnt(1)
	global_store_dwordx4 v[174:175], v[160:163], off
	s_nop 1
	v_add_u32_e32 v160, s41, v176
	v_mad_i64_i32 v[160:161], s[0:1], v169, v160, 0
	v_lshl_add_u64 v[160:161], v[160:161], 1, v[170:171]
	v_lshl_add_u64 v[160:161], v[160:161], 0, v[172:173]
	s_waitcnt lgkmcnt(0)
	global_store_dwordx4 v[160:161], v[164:167], off
	v_add_u32_e32 v160, 0x400, v193
	v_ashrrev_i32_e32 v162, 5, v160
	v_add_u32_e32 v160, s41, v162
	v_mad_i64_i32 v[160:161], s[0:1], v169, v160, 0
	v_lshl_add_u64 v[160:161], v[160:161], 1, v[170:171]
	v_lshl_add_u64 v[174:175], v[160:161], 0, v[172:173]
	v_mad_u64_u32 v[160:161], s[0:1], v162, s59, v[168:169]
	ds_read2_b64 v[160:163], v160 offset1:1
	v_add_u32_e32 v164, 0x600, v193
	v_ashrrev_i32_e32 v176, 5, v164
	v_mad_u64_u32 v[164:165], s[0:1], v176, s59, v[168:169]
	ds_read2_b64 v[164:167], v164 offset1:1
	s_waitcnt lgkmcnt(1)
	global_store_dwordx4 v[174:175], v[160:163], off
	s_nop 1
	v_add_u32_e32 v160, s41, v176
	v_mad_i64_i32 v[160:161], s[0:1], v169, v160, 0
	v_lshl_add_u64 v[160:161], v[160:161], 1, v[170:171]
	v_lshl_add_u64 v[160:161], v[160:161], 0, v[172:173]
	s_waitcnt lgkmcnt(0)
	global_store_dwordx4 v[160:161], v[164:167], off
	v_add_u32_e32 v160, 0x800, v193
	v_ashrrev_i32_e32 v162, 5, v160
	v_add_u32_e32 v160, s41, v162
	v_mad_i64_i32 v[160:161], s[0:1], v169, v160, 0
	v_lshl_add_u64 v[160:161], v[160:161], 1, v[170:171]
	v_lshl_add_u64 v[174:175], v[160:161], 0, v[172:173]
	v_mad_u64_u32 v[160:161], s[0:1], v162, s59, v[168:169]
	ds_read2_b64 v[160:163], v160 offset1:1
	v_add_u32_e32 v164, 0xa00, v193
	v_ashrrev_i32_e32 v176, 5, v164
	v_mad_u64_u32 v[164:165], s[0:1], v176, s59, v[168:169]
	ds_read2_b64 v[164:167], v164 offset1:1
	s_waitcnt lgkmcnt(1)
	global_store_dwordx4 v[174:175], v[160:163], off
	s_nop 1
	v_add_u32_e32 v160, s41, v176
	v_mad_i64_i32 v[160:161], s[0:1], v169, v160, 0
	v_lshl_add_u64 v[160:161], v[160:161], 1, v[170:171]
	v_lshl_add_u64 v[160:161], v[160:161], 0, v[172:173]
	s_waitcnt lgkmcnt(0)
	global_store_dwordx4 v[160:161], v[164:167], off
	v_add_u32_e32 v160, 0xc00, v193
	v_ashrrev_i32_e32 v162, 5, v160
	v_add_u32_e32 v160, s41, v162
	v_mad_i64_i32 v[160:161], s[0:1], v169, v160, 0
	v_lshl_add_u64 v[160:161], v[160:161], 1, v[170:171]
	v_lshl_add_u64 v[174:175], v[160:161], 0, v[172:173]
	v_mad_u64_u32 v[160:161], s[0:1], v162, s59, v[168:169]
	ds_read2_b64 v[160:163], v160 offset1:1
	v_add_u32_e32 v164, 0xe00, v193
	v_ashrrev_i32_e32 v176, 5, v164
	v_mad_u64_u32 v[164:165], s[0:1], v176, s59, v[168:169]
	ds_read2_b64 v[164:167], v164 offset1:1
	s_waitcnt lgkmcnt(1)
; DI void stg16_nt(void* p, u32x4 v) { __builtin_nontemporal_store(v, (u32x4*)p); }
; DI void epi_seg(const f32x16 (&acc)[4][2], const Seg& sg0, const Seg& sg1, int m0, int n0, const float* rs, const float2* cs64, const float2* cs32, bf16_t* stg) {
;     ...
; #pragma unroll
;   for (int it = 0; it < 16; ++it) {
;     const int idx = tid + NTHR * it, rr = idx >> 5, c = idx & 31;
;     const Seg& fs = (c >> 4) ? sg1 : sg0;
;     const int lcc = n0 + c * 8 - fs.cbase;
;     if (fs.kind != K_NONE && lcc < fs.nvalid) {
;       const int row = m0 + rr;
;       size_t off;
;       if (fs.kind == K_KC2) { const int b = row >> 9, n = (row >> 2) & 127, g = row & 3; off = ((size_t)((b * 4 + g) * 128 + n)) * 64 + lcc; }
;       else off = (size_t)row * fs.ld + lcc;
;       stg16_nt(fs.dst + off, stage_read16(stg, rr, c));
;     }
;   }
	global_store_dwordx4 v[174:175], v[160:163], off
	s_nop 1
	v_add_u32_e32 v160, s41, v176
	v_mad_i64_i32 v[160:161], s[0:1], v169, v160, 0
	v_lshl_add_u64 v[160:161], v[160:161], 1, v[170:171]
	v_lshl_add_u64 v[160:161], v[160:161], 0, v[172:173]
	s_waitcnt lgkmcnt(0)
	global_store_dwordx4 v[160:161], v[164:167], off
	v_add_u32_e32 v160, 0x1000, v193
	v_ashrrev_i32_e32 v162, 5, v160
	v_add_u32_e32 v160, s41, v162
	v_mad_i64_i32 v[160:161], s[0:1], v169, v160, 0
	v_lshl_add_u64 v[160:161], v[160:161], 1, v[170:171]
	v_lshl_add_u64 v[174:175], v[160:161], 0, v[172:173]
	v_mad_u64_u32 v[160:161], s[0:1], v162, s59, v[168:169]
	ds_read2_b64 v[160:163], v160 offset1:1
	v_add_u32_e32 v164, 0x1200, v193
	v_ashrrev_i32_e32 v176, 5, v164
	v_mad_u64_u32 v[164:165], s[0:1], v176, s59, v[168:169]
	ds_read2_b64 v[164:167], v164 offset1:1
	s_waitcnt lgkmcnt(1)
	global_store_dwordx4 v[174:175], v[160:163], off
	s_nop 1
	v_add_u32_e32 v160, s41, v176
	v_mad_i64_i32 v[160:161], s[0:1], v169, v160, 0
	v_lshl_add_u64 v[160:161], v[160:161], 1, v[170:171]
	v_lshl_add_u64 v[160:161], v[160:161], 0, v[172:173]
	s_waitcnt lgkmcnt(0)
	global_store_dwordx4 v[160:161], v[164:167], off
	v_add_u32_e32 v160, 0x1400, v193
	v_ashrrev_i32_e32 v162, 5, v160
	v_add_u32_e32 v160, s41, v162
	v_mad_i64_i32 v[160:161], s[0:1], v169, v160, 0
	v_lshl_add_u64 v[160:161], v[160:161], 1, v[170:171]
	v_lshl_add_u64 v[174:175], v[160:161], 0, v[172:173]
	v_mad_u64_u32 v[160:161], s[0:1], v162, s59, v[168:169]
	ds_read2_b64 v[160:163], v160 offset1:1
	v_add_u32_e32 v164, 0x1600, v193
	v_ashrrev_i32_e32 v176, 5, v164
	v_mad_u64_u32 v[164:165], s[0:1], v176, s59, v[168:169]
	ds_read2_b64 v[164:167], v164 offset1:1
	s_waitcnt lgkmcnt(1)
	global_store_dwordx4 v[174:175], v[160:163], off
	s_nop 1
	v_add_u32_e32 v160, s41, v176
	v_mad_i64_i32 v[160:161], s[0:1], v169, v160, 0
	v_lshl_add_u64 v[160:161], v[160:161], 1, v[170:171]
	v_lshl_add_u64 v[160:161], v[160:161], 0, v[172:173]
	s_waitcnt lgkmcnt(0)
	global_store_dwordx4 v[160:161], v[164:167], off
	v_add_u32_e32 v160, 0x1800, v193
	v_ashrrev_i32_e32 v162, 5, v160
	v_add_u32_e32 v160, s41, v162
	v_mad_i64_i32 v[160:161], s[0:1], v169, v160, 0
	v_lshl_add_u64 v[160:161], v[160:161], 1, v[170:171]
	v_lshl_add_u64 v[174:175], v[160:161], 0, v[172:173]
	v_mad_u64_u32 v[160:161], s[0:1], v162, s59, v[168:169]
	ds_read2_b64 v[160:163], v160 offset1:1
	v_add_u32_e32 v164, 0x1a00, v193
	v_ashrrev_i32_e32 v176, 5, v164
	v_mad_u64_u32 v[164:165], s[0:1], v176, s59, v[168:169]
	ds_read2_b64 v[164:167], v164 offset1:1
	s_waitcnt lgkmcnt(1)
	global_store_dwordx4 v[174:175], v[160:163], off
	s_nop 1
	v_add_u32_e32 v160, s41, v176
	v_mad_i64_i32 v[160:161], s[0:1], v169, v160, 0
	v_lshl_add_u64 v[160:161], v[160:161], 1, v[170:171]
	v_lshl_add_u64 v[160:161], v[160:161], 0, v[172:173]
	s_waitcnt lgkmcnt(0)
	global_store_dwordx4 v[160:161], v[164:167], off
	v_add_u32_e32 v160, 0x1c00, v193
	v_ashrrev_i32_e32 v162, 5, v160
	v_add_u32_e32 v160, s41, v162
	v_mad_i64_i32 v[160:161], s[0:1], v169, v160, 0
	v_lshl_add_u64 v[160:161], v[160:161], 1, v[170:171]
	v_lshl_add_u64 v[174:175], v[160:161], 0, v[172:173]
	v_mad_u64_u32 v[160:161], s[0:1], v162, s59, v[168:169]
	ds_read2_b64 v[160:163], v160 offset1:1
	v_add_u32_e32 v164, 0x1e00, v193
	v_ashrrev_i32_e32 v176, 5, v164
	v_mad_u64_u32 v[164:165], s[0:1], v176, s59, v[168:169]
	ds_read2_b64 v[164:167], v164 offset1:1
	s_waitcnt lgkmcnt(1)
	global_store_dwordx4 v[174:175], v[160:163], off
	s_nop 1
	v_add_u32_e32 v160, s41, v176
	v_mad_i64_i32 v[160:161], s[0:1], v169, v160, 0
	v_lshl_add_u64 v[160:161], v[160:161], 1, v[170:171]
	v_lshl_add_u64 v[160:161], v[160:161], 0, v[172:173]
	s_waitcnt lgkmcnt(0)
	global_store_dwordx4 v[160:161], v[164:167], off

; DI unsigned pack2(float a, float b) { f32x2_t v = {a, b}; bf16x2_t r = __builtin_convertvector(v, bf16x2_t); return __builtin_bit_cast(unsigned, r); }
; DI void epi_seg(const f32x16 (&acc)[4][2], const Seg& sg0, const Seg& sg1, int m0, int n0, const float* rs, const float2* cs64, const float2* cs32, bf16_t* stg) {
;     ...
;   if (kind0 == K_VT) {
; #pragma unroll
;     for (int i = 0; i < 4; ++i)
; #pragma unroll
;       for (int q4 = 0; q4 < 4; ++q4) {
;         const int t0l = wm * 128 + i * 32 + 8 * q4 + 4 * h;
;         float s0 = 1.f, s1 = 1.f, s2 = 1.f, s3 = 1.f;
;         if (rs) { s0 = rs[t0l]; s1 = rs[t0l + 1]; s2 = rs[t0l + 2]; s3 = rs[t0l + 3]; }
; #pragma unroll
;         for (int j = 0; j < 2; ++j)
;           *(uint2*)(stg + (wn * 64 + j * 32 + r) * STG + t0l) =
;               make_uint2(pack2(acc[i][j][4 * q4] * s0, acc[i][j][4 * q4 + 1] * s1), pack2(acc[i][j][4 * q4 + 2] * s2, acc[i][j][4 * q4 + 3] * s3));
;       }
;     __syncthreads();
;     const int b = m0 >> 11, s0 = m0 & (SEQ - 1);
; #pragma unroll
;     for (int it = 0; it < 16; ++it) {
;       const int idx = tid + NTHR * it, rr = idx >> 5, c = idx & 31;
;       const int lc = n0 + rr - sg0.cbase, g = lc >> 6, d = lc & 63;
.LBB0_271:
	v_and_b32_e32 v161, 0xffffff00, v193
	v_lshl_or_b32 v160, v196, 6, v194
	v_lshl_or_b32 v161, v195, 3, v161
	v_cvt_pk_bf16_f32 v0, v0, v1
	v_cvt_pk_bf16_f32 v1, v2, v3
	v_mad_u32_u24 v160, v160, s59, v161
	v_cvt_pk_bf16_f32 v4, v4, v5
	v_cvt_pk_bf16_f32 v5, v6, v7
	v_cvt_pk_bf16_f32 v2, v112, v113
	v_cvt_pk_bf16_f32 v3, v114, v115
	ds_write2_b64 v160, v[0:1], v[4:5] offset1:2
	v_cvt_pk_bf16_f32 v0, v116, v117
	v_cvt_pk_bf16_f32 v1, v118, v119
	v_add_u32_e32 v6, 0x4000, v160
	ds_write2_b64 v6, v[2:3], v[0:1] offset0:32 offset1:34
	v_cvt_pk_bf16_f32 v0, v8, v9
	v_cvt_pk_bf16_f32 v1, v10, v11
	v_cvt_pk_bf16_f32 v4, v12, v13
	v_cvt_pk_bf16_f32 v5, v14, v15
	v_cvt_pk_bf16_f32 v2, v120, v121
	v_cvt_pk_bf16_f32 v3, v122, v123
	ds_write2_b64 v160, v[0:1], v[4:5] offset0:4 offset1:6
	v_cvt_pk_bf16_f32 v0, v124, v125
	v_cvt_pk_bf16_f32 v1, v126, v127
	ds_write2_b64 v6, v[2:3], v[0:1] offset0:36 offset1:38
	v_cvt_pk_bf16_f32 v0, v48, v49
	v_cvt_pk_bf16_f32 v1, v50, v51
	v_cvt_pk_bf16_f32 v4, v52, v53
	v_cvt_pk_bf16_f32 v5, v54, v55
	v_cvt_pk_bf16_f32 v2, v96, v97
	v_cvt_pk_bf16_f32 v3, v98, v99
	ds_write2_b64 v160, v[0:1], v[4:5] offset0:8 offset1:10
	v_cvt_pk_bf16_f32 v0, v100, v101
	v_cvt_pk_bf16_f32 v1, v102, v103
	ds_write2_b64 v6, v[2:3], v[0:1] offset0:40 offset1:42
	v_cvt_pk_bf16_f32 v0, v56, v57
	v_cvt_pk_bf16_f32 v1, v58, v59
	v_cvt_pk_bf16_f32 v4, v60, v61
	v_cvt_pk_bf16_f32 v5, v62, v63
	v_cvt_pk_bf16_f32 v2, v104, v105
	v_cvt_pk_bf16_f32 v3, v106, v107
	ds_write2_b64 v160, v[0:1], v[4:5] offset0:12 offset1:14
	v_cvt_pk_bf16_f32 v0, v108, v109
	v_cvt_pk_bf16_f32 v1, v110, v111
	ds_write2_b64 v6, v[2:3], v[0:1] offset0:44 offset1:46
	v_cvt_pk_bf16_f32 v0, v32, v33
	v_cvt_pk_bf16_f32 v1, v34, v35
	v_cvt_pk_bf16_f32 v4, v36, v37
	v_cvt_pk_bf16_f32 v5, v38, v39
	v_cvt_pk_bf16_f32 v2, v80, v81
	v_cvt_pk_bf16_f32 v3, v82, v83
	ds_write2_b64 v160, v[0:1], v[4:5] offset0:16 offset1:18
	v_cvt_pk_bf16_f32 v0, v84, v85
	v_cvt_pk_bf16_f32 v1, v86, v87
	ds_write2_b64 v6, v[2:3], v[0:1] offset0:48 offset1:50
	v_cvt_pk_bf16_f32 v0, v40, v41
	v_cvt_pk_bf16_f32 v1, v42, v43
	v_cvt_pk_bf16_f32 v4, v44, v45
	v_cvt_pk_bf16_f32 v5, v46, v47
	v_cvt_pk_bf16_f32 v2, v88, v89
	v_cvt_pk_bf16_f32 v3, v90, v91
	ds_write2_b64 v160, v[0:1], v[4:5] offset0:20 offset1:22
	v_cvt_pk_bf16_f32 v0, v92, v93
	v_cvt_pk_bf16_f32 v1, v94, v95
	ds_write2_b64 v6, v[2:3], v[0:1] offset0:52 offset1:54
	v_cvt_pk_bf16_f32 v0, v16, v17
	v_cvt_pk_bf16_f32 v1, v18, v19
	v_cvt_pk_bf16_f32 v4, v20, v21
	v_cvt_pk_bf16_f32 v5, v22, v23
	v_cvt_pk_bf16_f32 v2, v64, v65
	v_cvt_pk_bf16_f32 v3, v66, v67
	ds_write2_b64 v160, v[0:1], v[4:5] offset0:24 offset1:26
	v_cvt_pk_bf16_f32 v0, v68, v69
	v_cvt_pk_bf16_f32 v1, v70, v71
	ds_write2_b64 v6, v[2:3], v[0:1] offset0:56 offset1:58
	v_cvt_pk_bf16_f32 v0, v24, v25
	v_cvt_pk_bf16_f32 v1, v26, v27
	v_cvt_pk_bf16_f32 v4, v28, v29
	v_cvt_pk_bf16_f32 v5, v30, v31
	s_lshl_b32 s0, s34, 5
	v_cvt_pk_bf16_f32 v2, v72, v73
	v_cvt_pk_bf16_f32 v3, v74, v75
	ds_write2_b64 v160, v[0:1], v[4:5] offset0:28 offset1:30
	v_cvt_pk_bf16_f32 v0, v76, v77
	v_cvt_pk_bf16_f32 v1, v78, v79
	s_and_b32 s0, s0, 0xffffff00
	s_sub_i32 s34, s39, s62
	ds_write2_b64 v6, v[2:3], v[0:1] offset0:60 offset1:62
	v_ashrrev_i32_e32 v2, 5, v193
	s_add_i32 s0, s34, s0
	v_add_u32_e32 v0, s0, v2
	v_ashrrev_i32_e32 v1, 31, v0
	s_and_b32 s1, s41, 0x700
	v_lshlrev_b64 v[0:1], 12, v[0:1]
	v_lshl_add_u64 v[0:1], s[36:37], 0, v[0:1]
	s_lshl_b32 s34, s1, 1
	v_lshlrev_b32_e32 v184, 4, v194
	v_lshl_add_u64 v[0:1], v[0:1], 0, s[34:35]
	v_lshl_add_u64 v[8:9], v[0:1], 0, v[184:185]
	v_mad_u64_u32 v[0:1], s[38:39], v2, s59, v[184:185]
	s_waitcnt lgkmcnt(0)
	s_barrier
; DI void stg16_nt(void* p, u32x4 v) { __builtin_nontemporal_store(v, (u32x4*)p); }
; DI void epi_seg(const f32x16 (&acc)[4][2], const Seg& sg0, const Seg& sg1, int m0, int n0, const float* rs, const float2* cs64, const float2* cs32, bf16_t* stg) {
;     ...
;     const int b = m0 >> 11, s0 = m0 & (SEQ - 1);
; #pragma unroll
;     for (int it = 0; it < 16; ++it) {
;       const int idx = tid + NTHR * it, rr = idx >> 5, c = idx & 31;
;       const int lc = n0 + rr - sg0.cbase, g = lc >> 6, d = lc & 63;
;       stg16_nt(sg0.dst + ((size_t)((b * sg0.G + g) * 64 + d)) * SEQ + s0 + c * 8, stage_read16(stg, rr, c));
;     }
;     __syncthreads();
;     return;
	ds_read2_b64 v[0:3], v0 offset1:1
	v_add_u32_e32 v4, 0x200, v193
	v_ashrrev_i32_e32 v10, 5, v4
	v_mad_u64_u32 v[4:5], s[38:39], v10, s59, v[184:185]
	ds_read2_b64 v[4:7], v4 offset1:1
	s_waitcnt lgkmcnt(1)
	global_store_dwordx4 v[8:9], v[0:3], off
	s_nop 1
	v_add_u32_e32 v0, s0, v10
	v_ashrrev_i32_e32 v1, 31, v0
	v_lshlrev_b64 v[0:1], 12, v[0:1]
	v_lshl_add_u64 v[0:1], s[36:37], 0, v[0:1]
	v_lshl_add_u64 v[0:1], v[0:1], 0, s[34:35]
	v_lshl_add_u64 v[0:1], v[0:1], 0, v[184:185]
	s_waitcnt lgkmcnt(0)
	global_store_dwordx4 v[0:1], v[4:7], off
	v_add_u32_e32 v0, 0x400, v193
	v_ashrrev_i32_e32 v2, 5, v0
	v_add_u32_e32 v0, s0, v2
	v_ashrrev_i32_e32 v1, 31, v0
	v_lshlrev_b64 v[0:1], 12, v[0:1]
	v_lshl_add_u64 v[0:1], s[36:37], 0, v[0:1]
	v_lshl_add_u64 v[0:1], v[0:1], 0, s[34:35]
	v_lshl_add_u64 v[8:9], v[0:1], 0, v[184:185]
	v_mad_u64_u32 v[0:1], s[38:39], v2, s59, v[184:185]
	ds_read2_b64 v[0:3], v0 offset1:1
	v_add_u32_e32 v4, 0x600, v193
	v_ashrrev_i32_e32 v10, 5, v4
	v_mad_u64_u32 v[4:5], s[38:39], v10, s59, v[184:185]
	ds_read2_b64 v[4:7], v4 offset1:1
	s_waitcnt lgkmcnt(1)
	global_store_dwordx4 v[8:9], v[0:3], off
	s_nop 1
	v_add_u32_e32 v0, s0, v10
	v_ashrrev_i32_e32 v1, 31, v0
	v_lshlrev_b64 v[0:1], 12, v[0:1]
	v_lshl_add_u64 v[0:1], s[36:37], 0, v[0:1]
	v_lshl_add_u64 v[0:1], v[0:1], 0, s[34:35]
	v_lshl_add_u64 v[0:1], v[0:1], 0, v[184:185]
	s_waitcnt lgkmcnt(0)
	global_store_dwordx4 v[0:1], v[4:7], off
	v_add_u32_e32 v0, 0x800, v193
	v_ashrrev_i32_e32 v2, 5, v0
	v_add_u32_e32 v0, s0, v2
	v_ashrrev_i32_e32 v1, 31, v0
	v_lshlrev_b64 v[0:1], 12, v[0:1]
	v_lshl_add_u64 v[0:1], s[36:37], 0, v[0:1]
	v_lshl_add_u64 v[0:1], v[0:1], 0, s[34:35]
	v_lshl_add_u64 v[8:9], v[0:1], 0, v[184:185]
	v_mad_u64_u32 v[0:1], s[38:39], v2, s59, v[184:185]
	ds_read2_b64 v[0:3], v0 offset1:1
	v_add_u32_e32 v4, 0xa00, v193
	v_ashrrev_i32_e32 v10, 5, v4
	v_mad_u64_u32 v[4:5], s[38:39], v10, s59, v[184:185]
	ds_read2_b64 v[4:7], v4 offset1:1
	s_waitcnt lgkmcnt(1)
	global_store_dwordx4 v[8:9], v[0:3], off
	s_nop 1
	v_add_u32_e32 v0, s0, v10
	v_ashrrev_i32_e32 v1, 31, v0
	v_lshlrev_b64 v[0:1], 12, v[0:1]
	v_lshl_add_u64 v[0:1], s[36:37], 0, v[0:1]
	v_lshl_add_u64 v[0:1], v[0:1], 0, s[34:35]
	v_lshl_add_u64 v[0:1], v[0:1], 0, v[184:185]
	s_waitcnt lgkmcnt(0)
	global_store_dwordx4 v[0:1], v[4:7], off
	v_add_u32_e32 v0, 0xc00, v193
	v_ashrrev_i32_e32 v2, 5, v0
	v_add_u32_e32 v0, s0, v2
	v_ashrrev_i32_e32 v1, 31, v0
	v_lshlrev_b64 v[0:1], 12, v[0:1]
	v_lshl_add_u64 v[0:1], s[36:37], 0, v[0:1]
	v_lshl_add_u64 v[0:1], v[0:1], 0, s[34:35]
	v_lshl_add_u64 v[8:9], v[0:1], 0, v[184:185]
	v_mad_u64_u32 v[0:1], s[38:39], v2, s59, v[184:185]
	ds_read2_b64 v[0:3], v0 offset1:1
	v_add_u32_e32 v4, 0xe00, v193
	v_ashrrev_i32_e32 v10, 5, v4
	v_mad_u64_u32 v[4:5], s[38:39], v10, s59, v[184:185]
	ds_read2_b64 v[4:7], v4 offset1:1
	s_waitcnt lgkmcnt(1)
	global_store_dwordx4 v[8:9], v[0:3], off
	s_nop 1
	v_add_u32_e32 v0, s0, v10
	v_ashrrev_i32_e32 v1, 31, v0
	v_lshlrev_b64 v[0:1], 12, v[0:1]
	v_lshl_add_u64 v[0:1], s[36:37], 0, v[0:1]
	v_lshl_add_u64 v[0:1], v[0:1], 0, s[34:35]
	v_lshl_add_u64 v[0:1], v[0:1], 0, v[184:185]
	s_waitcnt lgkmcnt(0)
	global_store_dwordx4 v[0:1], v[4:7], off
	v_add_u32_e32 v0, 0x1000, v193
	v_ashrrev_i32_e32 v2, 5, v0
	v_add_u32_e32 v0, s0, v2
	v_ashrrev_i32_e32 v1, 31, v0
	v_lshlrev_b64 v[0:1], 12, v[0:1]
	v_lshl_add_u64 v[0:1], s[36:37], 0, v[0:1]
	v_lshl_add_u64 v[0:1], v[0:1], 0, s[34:35]
	v_lshl_add_u64 v[8:9], v[0:1], 0, v[184:185]
	v_mad_u64_u32 v[0:1], s[38:39], v2, s59, v[184:185]
	ds_read2_b64 v[0:3], v0 offset1:1
	v_add_u32_e32 v4, 0x1200, v193
	v_ashrrev_i32_e32 v10, 5, v4
	v_mad_u64_u32 v[4:5], s[38:39], v10, s59, v[184:185]
	ds_read2_b64 v[4:7], v4 offset1:1
	s_waitcnt lgkmcnt(1)
	global_store_dwordx4 v[8:9], v[0:3], off
	s_nop 1
	v_add_u32_e32 v0, s0, v10
	v_ashrrev_i32_e32 v1, 31, v0
	v_lshlrev_b64 v[0:1], 12, v[0:1]
	v_lshl_add_u64 v[0:1], s[36:37], 0, v[0:1]
	v_lshl_add_u64 v[0:1], v[0:1], 0, s[34:35]
	v_lshl_add_u64 v[0:1], v[0:1], 0, v[184:185]
	s_waitcnt lgkmcnt(0)
	global_store_dwordx4 v[0:1], v[4:7], off
	v_add_u32_e32 v0, 0x1400, v193
	v_ashrrev_i32_e32 v2, 5, v0
	v_add_u32_e32 v0, s0, v2
	v_ashrrev_i32_e32 v1, 31, v0
	v_lshlrev_b64 v[0:1], 12, v[0:1]
	v_lshl_add_u64 v[0:1], s[36:37], 0, v[0:1]
	v_lshl_add_u64 v[0:1], v[0:1], 0, s[34:35]
	v_lshl_add_u64 v[8:9], v[0:1], 0, v[184:185]
	v_mad_u64_u32 v[0:1], s[38:39], v2, s59, v[184:185]
	ds_read2_b64 v[0:3], v0 offset1:1
	v_add_u32_e32 v4, 0x1600, v193
	v_ashrrev_i32_e32 v10, 5, v4
	v_mad_u64_u32 v[4:5], s[38:39], v10, s59, v[184:185]
	ds_read2_b64 v[4:7], v4 offset1:1
	s_waitcnt lgkmcnt(1)
	global_store_dwordx4 v[8:9], v[0:3], off
	s_nop 1
	v_add_u32_e32 v0, s0, v10
	v_ashrrev_i32_e32 v1, 31, v0
	v_lshlrev_b64 v[0:1], 12, v[0:1]
	v_lshl_add_u64 v[0:1], s[36:37], 0, v[0:1]
	v_lshl_add_u64 v[0:1], v[0:1], 0, s[34:35]
	v_lshl_add_u64 v[0:1], v[0:1], 0, v[184:185]
	s_waitcnt lgkmcnt(0)
	global_store_dwordx4 v[0:1], v[4:7], off
	v_add_u32_e32 v0, 0x1800, v193
	v_ashrrev_i32_e32 v2, 5, v0
	v_add_u32_e32 v0, s0, v2
	v_ashrrev_i32_e32 v1, 31, v0
	v_lshlrev_b64 v[0:1], 12, v[0:1]
	v_lshl_add_u64 v[0:1], s[36:37], 0, v[0:1]
	v_lshl_add_u64 v[0:1], v[0:1], 0, s[34:35]
	v_lshl_add_u64 v[8:9], v[0:1], 0, v[184:185]
	v_mad_u64_u32 v[0:1], s[38:39], v2, s59, v[184:185]
	ds_read2_b64 v[0:3], v0 offset1:1
	v_add_u32_e32 v4, 0x1a00, v193
	v_ashrrev_i32_e32 v10, 5, v4
	v_mad_u64_u32 v[4:5], s[38:39], v10, s59, v[184:185]
	ds_read2_b64 v[4:7], v4 offset1:1
	s_waitcnt lgkmcnt(1)
	global_store_dwordx4 v[8:9], v[0:3], off
	s_nop 1
	v_add_u32_e32 v0, s0, v10
	v_ashrrev_i32_e32 v1, 31, v0
	v_lshlrev_b64 v[0:1], 12, v[0:1]
	v_lshl_add_u64 v[0:1], s[36:37], 0, v[0:1]
	v_lshl_add_u64 v[0:1], v[0:1], 0, s[34:35]
	v_lshl_add_u64 v[0:1], v[0:1], 0, v[184:185]
	s_waitcnt lgkmcnt(0)
	global_store_dwordx4 v[0:1], v[4:7], off
	v_add_u32_e32 v0, 0x1c00, v193
	v_ashrrev_i32_e32 v2, 5, v0
	v_add_u32_e32 v0, s0, v2
	v_ashrrev_i32_e32 v1, 31, v0
	v_lshlrev_b64 v[0:1], 12, v[0:1]
	v_lshl_add_u64 v[0:1], s[36:37], 0, v[0:1]
	v_lshl_add_u64 v[0:1], v[0:1], 0, s[34:35]
	v_lshl_add_u64 v[8:9], v[0:1], 0, v[184:185]
	v_mad_u64_u32 v[0:1], s[38:39], v2, s59, v[184:185]
	ds_read2_b64 v[0:3], v0 offset1:1
	v_add_u32_e32 v4, 0x1e00, v193
	v_ashrrev_i32_e32 v10, 5, v4
	v_mad_u64_u32 v[4:5], s[38:39], v10, s59, v[184:185]
	ds_read2_b64 v[4:7], v4 offset1:1
	s_waitcnt lgkmcnt(1)
	global_store_dwordx4 v[8:9], v[0:3], off
	s_nop 1
	v_add_u32_e32 v0, s0, v10
	v_ashrrev_i32_e32 v1, 31, v0
	v_lshlrev_b64 v[0:1], 12, v[0:1]
	v_lshl_add_u64 v[0:1], s[36:37], 0, v[0:1]
	v_lshl_add_u64 v[0:1], v[0:1], 0, s[34:35]
	v_lshl_add_u64 v[0:1], v[0:1], 0, v[184:185]
	s_waitcnt lgkmcnt(0)
	global_store_dwordx4 v[0:1], v[4:7], off
	s_barrier
	s_branch .LBB0_241

; DI int otid() { int t = threadIdx.x; asm volatile("" : "+v"(t)); return t; }
; DI void stg16_nt(void* p, u32x4 v) { __builtin_nontemporal_store(v, (u32x4*)p); }
; DI void stage_store_tile(const bf16_t* stg, bf16_t* tilebase) {
;   const int tid = otid();
;   const int r0 = tid >> 5, c = tid & 31;
;   const unsigned o0 = (unsigned)(r0 * 1024 + c * 8);
; #pragma unroll
;   for (int it = 0; it < 16; ++it) stg16_nt(tilebase + (o0 + (unsigned)(it * 16 * 1024)), stage_read16(stg, r0 + 16 * it, c));
; }
.LBB0_406:
	s_or_b64 exec, exec, s[40:41]
	v_mov_b32_e32 v0, v192
	s_waitcnt lgkmcnt(0)
	s_barrier
	s_lshl_b64 s[36:37], s[36:37], 18
	v_ashrrev_i32_e32 v4, 5, v0
	v_and_b32_e32 v0, 31, v0
	v_mul_lo_u32 v1, v4, s48
	s_lshl_b64 s[36:37], s[36:37], 1
	v_lshl_add_u32 v10, v0, 4, v1
	s_add_u32 s36, s76, s36
	v_lshlrev_b32_e32 v5, 3, v0
	ds_read2_b64 v[0:3], v10 offset1:1
	s_addc_u32 s37, s77, s37
	v_lshl_or_b32 v160, v4, 10, v5
	v_add_u32_e32 v4, 0x2080, v10
	s_add_u32 s36, s36, s52
	ds_read2_b64 v[4:7], v4 offset1:1
	s_addc_u32 s37, s37, 0
	v_lshl_add_u64 v[8:9], v[160:161], 1, s[36:37]
	s_waitcnt lgkmcnt(1)
	global_store_dwordx4 v[8:9], v[0:3], off
	s_add_i32 s44, s44, s69
	s_andn2_b64 vcc, exec, s[38:39]
	v_add_u32_e32 v0, 0x4000, v160
	v_mov_b32_e32 v1, v161
	v_lshl_add_u64 v[0:1], v[0:1], 1, s[36:37]
	s_waitcnt lgkmcnt(0)
	global_store_dwordx4 v[0:1], v[4:7], off
	v_add_u32_e32 v0, 0x4100, v10
	ds_read2_b64 v[0:3], v0 offset1:1
	v_add_u32_e32 v4, 0x8000, v160
	v_mov_b32_e32 v5, v161
	v_lshl_add_u64 v[8:9], v[4:5], 1, s[36:37]
	v_add_u32_e32 v4, 0x6180, v10
	ds_read2_b64 v[4:7], v4 offset1:1
	s_waitcnt lgkmcnt(1)
	global_store_dwordx4 v[8:9], v[0:3], off
	s_add_i32 s45, s45, s42
	s_nop 0
	v_add_u32_e32 v0, 0xc000, v160
	v_mov_b32_e32 v1, v161
	v_lshl_add_u64 v[0:1], v[0:1], 1, s[36:37]
	s_waitcnt lgkmcnt(0)
	global_store_dwordx4 v[0:1], v[4:7], off
	v_add_u32_e32 v0, 0x8200, v10
	ds_read2_b64 v[0:3], v0 offset1:1
	v_add_u32_e32 v4, 0x10000, v160
	v_mov_b32_e32 v5, v161
	v_lshl_add_u64 v[8:9], v[4:5], 1, s[36:37]
	v_add_u32_e32 v4, 0xa280, v10
	ds_read2_b64 v[4:7], v4 offset1:1
	s_waitcnt lgkmcnt(1)
	global_store_dwordx4 v[8:9], v[0:3], off
	s_nop 1
	v_add_u32_e32 v0, 0x14000, v160
	v_mov_b32_e32 v1, v161
	v_lshl_add_u64 v[0:1], v[0:1], 1, s[36:37]
	s_waitcnt lgkmcnt(0)
	global_store_dwordx4 v[0:1], v[4:7], off
	v_add_u32_e32 v0, 0xc300, v10
	ds_read2_b64 v[0:3], v0 offset1:1
	v_add_u32_e32 v4, 0x18000, v160
	v_mov_b32_e32 v5, v161
	v_lshl_add_u64 v[8:9], v[4:5], 1, s[36:37]
	v_add_u32_e32 v4, 0xe380, v10
	ds_read2_b64 v[4:7], v4 offset1:1
	s_waitcnt lgkmcnt(1)
	global_store_dwordx4 v[8:9], v[0:3], off
	s_nop 1
	v_add_u32_e32 v0, 0x1c000, v160
	v_mov_b32_e32 v1, v161
	v_lshl_add_u64 v[0:1], v[0:1], 1, s[36:37]
	s_waitcnt lgkmcnt(0)
	global_store_dwordx4 v[0:1], v[4:7], off
	v_add_u32_e32 v0, 0x10400, v10
	ds_read2_b64 v[0:3], v0 offset1:1
	v_add_u32_e32 v4, 0x20000, v160
	v_mov_b32_e32 v5, v161
	v_lshl_add_u64 v[8:9], v[4:5], 1, s[36:37]
	v_add_u32_e32 v4, 0x12480, v10
	ds_read2_b64 v[4:7], v4 offset1:1
	s_waitcnt lgkmcnt(1)
	global_store_dwordx4 v[8:9], v[0:3], off
	s_nop 1
	v_add_u32_e32 v0, 0x24000, v160
	v_mov_b32_e32 v1, v161
	v_lshl_add_u64 v[0:1], v[0:1], 1, s[36:37]
	s_waitcnt lgkmcnt(0)
	global_store_dwordx4 v[0:1], v[4:7], off
	v_add_u32_e32 v0, 0x14500, v10
	ds_read2_b64 v[0:3], v0 offset1:1
	v_add_u32_e32 v4, 0x28000, v160
	v_mov_b32_e32 v5, v161
	v_lshl_add_u64 v[8:9], v[4:5], 1, s[36:37]
	v_add_u32_e32 v4, 0x16580, v10
	ds_read2_b64 v[4:7], v4 offset1:1
	s_waitcnt lgkmcnt(1)
	global_store_dwordx4 v[8:9], v[0:3], off
	s_nop 1
	v_add_u32_e32 v0, 0x2c000, v160
	v_mov_b32_e32 v1, v161
	v_lshl_add_u64 v[0:1], v[0:1], 1, s[36:37]
	s_waitcnt lgkmcnt(0)
	global_store_dwordx4 v[0:1], v[4:7], off
	v_add_u32_e32 v0, 0x18600, v10
	ds_read2_b64 v[0:3], v0 offset1:1
	v_add_u32_e32 v4, 0x30000, v160
	v_mov_b32_e32 v5, v161
	v_lshl_add_u64 v[8:9], v[4:5], 1, s[36:37]
	v_add_u32_e32 v4, 0x1a680, v10
	ds_read2_b64 v[4:7], v4 offset1:1
	s_waitcnt lgkmcnt(1)
	global_store_dwordx4 v[8:9], v[0:3], off
	v_add_u32_e32 v8, 0x38000, v160
	v_mov_b32_e32 v9, v161
	v_add_u32_e32 v0, 0x34000, v160
	v_mov_b32_e32 v1, v161
	v_lshl_add_u64 v[0:1], v[0:1], 1, s[36:37]
	s_waitcnt lgkmcnt(0)
	global_store_dwordx4 v[0:1], v[4:7], off
	v_add_u32_e32 v0, 0x1c700, v10
	ds_read2_b64 v[0:3], v0 offset1:1
	v_add_u32_e32 v4, 0x1e780, v10
	ds_read2_b64 v[4:7], v4 offset1:1
	v_lshl_add_u64 v[8:9], v[8:9], 1, s[36:37]
	v_add_u32_e32 v160, 0x3c000, v160
	s_waitcnt lgkmcnt(1)
	global_store_dwordx4 v[8:9], v[0:3], off
	s_nop 1
	v_lshl_add_u64 v[0:1], v[160:161], 1, s[36:37]
	s_waitcnt lgkmcnt(0)
	global_store_dwordx4 v[0:1], v[4:7], off
	s_barrier
	s_cbranch_vccz .LBB0_417

; DI void stg16_nt(void* p, u32x4 v) { __builtin_nontemporal_store(v, (u32x4*)p); }
; DI void epi_seg(const f32x16 (&acc)[4][2], const Seg& sg0, const Seg& sg1, int m0, int n0, const float* rs, const float2* cs64, const float2* cs32, bf16_t* stg) {
;     ...
; #pragma unroll
;   for (int it = 0; it < 16; ++it) {
;     const int idx = tid + NTHR * it, rr = idx >> 5, c = idx & 31;
;     const Seg& fs = (c >> 4) ? sg1 : sg0;
;     const int lcc = n0 + c * 8 - fs.cbase;
;     if (fs.kind != K_NONE && lcc < fs.nvalid) {
;       const int row = m0 + rr;
;       size_t off;
;       if (fs.kind == K_KC2) { const int b = row >> 9, n = (row >> 2) & 127, g = row & 3; off = ((size_t)((b * 4 + g) * 128 + n)) * 64 + lcc; }
;       else off = (size_t)row * fs.ld + lcc;
;       stg16_nt(fs.dst + off, stage_read16(stg, rr, c));
;     }
;   }
.LBB0_423:
	s_or_b64 exec, exec, s[38:39]
	v_and_b32_e32 v1, 31, v160
	v_lshlrev_b32_e32 v0, 3, v1
	v_subrev_u32_e32 v0, s48, v0
	v_subrev_u32_e32 v0, s49, v0
	v_add_u32_e32 v0, s33, v0
	v_cmp_gt_i32_e32 vcc, 2.0, v0
	s_waitcnt lgkmcnt(0)
	s_barrier
	s_and_saveexec_b64 s[38:39], vcc
	s_cbranch_execz .LBB0_418
	v_ashrrev_i32_e32 v4, 5, v160
	v_add_u32_e32 v2, s47, v4
	v_ashrrev_i32_e32 v3, 31, v2
	v_lshlrev_b32_e32 v8, 4, v1
	v_ashrrev_i32_e32 v1, 31, v0
	v_lshlrev_b64 v[2:3], 11, v[2:3]
	v_lshl_add_u64 v[2:3], s[14:15], 0, v[2:3]
	v_lshlrev_b64 v[10:11], 1, v[0:1]
	v_mad_u64_u32 v[0:1], s[48:49], v4, s45, v[8:9]
	v_lshl_add_u64 v[12:13], v[2:3], 0, v[10:11]
	ds_read2_b64 v[0:3], v0 offset1:1
	v_add_u32_e32 v4, 0x200, v160
	v_ashrrev_i32_e32 v9, 5, v4
	v_mad_u64_u32 v[4:5], s[48:49], v9, s45, v[8:9]
	ds_read2_b64 v[4:7], v4 offset1:1
	s_waitcnt lgkmcnt(1)
	global_store_dwordx4 v[12:13], v[0:3], off
	s_nop 1
	v_add_u32_e32 v0, s47, v9
	v_ashrrev_i32_e32 v1, 31, v0
	v_lshlrev_b64 v[0:1], 11, v[0:1]
	v_lshl_add_u64 v[0:1], s[14:15], 0, v[0:1]
	v_lshl_add_u64 v[0:1], v[0:1], 0, v[10:11]
	s_waitcnt lgkmcnt(0)
	global_store_dwordx4 v[0:1], v[4:7], off
	v_add_u32_e32 v0, 0x400, v160
	v_ashrrev_i32_e32 v2, 5, v0
	v_add_u32_e32 v0, s47, v2
	v_ashrrev_i32_e32 v1, 31, v0
	v_lshlrev_b64 v[0:1], 11, v[0:1]
	v_lshl_add_u64 v[0:1], s[14:15], 0, v[0:1]
	v_lshl_add_u64 v[12:13], v[0:1], 0, v[10:11]
	v_mad_u64_u32 v[0:1], s[48:49], v2, s45, v[8:9]
	ds_read2_b64 v[0:3], v0 offset1:1
	v_add_u32_e32 v4, 0x600, v160
	v_ashrrev_i32_e32 v9, 5, v4
	v_mad_u64_u32 v[4:5], s[48:49], v9, s45, v[8:9]
	ds_read2_b64 v[4:7], v4 offset1:1
	s_waitcnt lgkmcnt(1)
	global_store_dwordx4 v[12:13], v[0:3], off
	s_nop 1
	v_add_u32_e32 v0, s47, v9
	v_ashrrev_i32_e32 v1, 31, v0
	v_lshlrev_b64 v[0:1], 11, v[0:1]
	v_lshl_add_u64 v[0:1], s[14:15], 0, v[0:1]
	v_lshl_add_u64 v[0:1], v[0:1], 0, v[10:11]
	s_waitcnt lgkmcnt(0)
	global_store_dwordx4 v[0:1], v[4:7], off
	v_add_u32_e32 v0, 0x800, v160
	v_ashrrev_i32_e32 v2, 5, v0
	v_add_u32_e32 v0, s47, v2
	v_ashrrev_i32_e32 v1, 31, v0
	v_lshlrev_b64 v[0:1], 11, v[0:1]
	v_lshl_add_u64 v[0:1], s[14:15], 0, v[0:1]
	v_lshl_add_u64 v[12:13], v[0:1], 0, v[10:11]
	v_mad_u64_u32 v[0:1], s[48:49], v2, s45, v[8:9]
	ds_read2_b64 v[0:3], v0 offset1:1
	v_add_u32_e32 v4, 0xa00, v160
	v_ashrrev_i32_e32 v9, 5, v4
	v_mad_u64_u32 v[4:5], s[48:49], v9, s45, v[8:9]
	ds_read2_b64 v[4:7], v4 offset1:1
	s_waitcnt lgkmcnt(1)
	global_store_dwordx4 v[12:13], v[0:3], off
	s_nop 1
	v_add_u32_e32 v0, s47, v9
	v_ashrrev_i32_e32 v1, 31, v0
	v_lshlrev_b64 v[0:1], 11, v[0:1]
	v_lshl_add_u64 v[0:1], s[14:15], 0, v[0:1]
	v_lshl_add_u64 v[0:1], v[0:1], 0, v[10:11]
	s_waitcnt lgkmcnt(0)
	global_store_dwordx4 v[0:1], v[4:7], off
	v_add_u32_e32 v0, 0xc00, v160
	v_ashrrev_i32_e32 v2, 5, v0
	v_add_u32_e32 v0, s47, v2
	v_ashrrev_i32_e32 v1, 31, v0
	v_lshlrev_b64 v[0:1], 11, v[0:1]
	v_lshl_add_u64 v[0:1], s[14:15], 0, v[0:1]
	v_lshl_add_u64 v[12:13], v[0:1], 0, v[10:11]
	v_mad_u64_u32 v[0:1], s[48:49], v2, s45, v[8:9]
	ds_read2_b64 v[0:3], v0 offset1:1
	v_add_u32_e32 v4, 0xe00, v160
	v_ashrrev_i32_e32 v9, 5, v4
	v_mad_u64_u32 v[4:5], s[48:49], v9, s45, v[8:9]
	ds_read2_b64 v[4:7], v4 offset1:1
	s_waitcnt lgkmcnt(1)
	global_store_dwordx4 v[12:13], v[0:3], off
	s_nop 1
	v_add_u32_e32 v0, s47, v9
	v_ashrrev_i32_e32 v1, 31, v0
	v_lshlrev_b64 v[0:1], 11, v[0:1]
	v_lshl_add_u64 v[0:1], s[14:15], 0, v[0:1]
	v_lshl_add_u64 v[0:1], v[0:1], 0, v[10:11]
	s_waitcnt lgkmcnt(0)
	global_store_dwordx4 v[0:1], v[4:7], off
	v_add_u32_e32 v0, 0x1000, v160
	v_ashrrev_i32_e32 v2, 5, v0
	v_add_u32_e32 v0, s47, v2
	v_ashrrev_i32_e32 v1, 31, v0
	v_lshlrev_b64 v[0:1], 11, v[0:1]
	v_lshl_add_u64 v[0:1], s[14:15], 0, v[0:1]
	v_lshl_add_u64 v[12:13], v[0:1], 0, v[10:11]
	v_mad_u64_u32 v[0:1], s[48:49], v2, s45, v[8:9]
	ds_read2_b64 v[0:3], v0 offset1:1
	v_add_u32_e32 v4, 0x1200, v160
	v_ashrrev_i32_e32 v9, 5, v4
	v_mad_u64_u32 v[4:5], s[48:49], v9, s45, v[8:9]
	ds_read2_b64 v[4:7], v4 offset1:1
	s_waitcnt lgkmcnt(1)
	global_store_dwordx4 v[12:13], v[0:3], off
	s_nop 1
	v_add_u32_e32 v0, s47, v9
	v_ashrrev_i32_e32 v1, 31, v0
	v_lshlrev_b64 v[0:1], 11, v[0:1]
	v_lshl_add_u64 v[0:1], s[14:15], 0, v[0:1]
	v_lshl_add_u64 v[0:1], v[0:1], 0, v[10:11]
	s_waitcnt lgkmcnt(0)
	global_store_dwordx4 v[0:1], v[4:7], off
	v_add_u32_e32 v0, 0x1400, v160
	v_ashrrev_i32_e32 v2, 5, v0
	v_add_u32_e32 v0, s47, v2
	v_ashrrev_i32_e32 v1, 31, v0
	v_lshlrev_b64 v[0:1], 11, v[0:1]
	v_lshl_add_u64 v[0:1], s[14:15], 0, v[0:1]
	v_lshl_add_u64 v[12:13], v[0:1], 0, v[10:11]
	v_mad_u64_u32 v[0:1], s[48:49], v2, s45, v[8:9]
	ds_read2_b64 v[0:3], v0 offset1:1
	v_add_u32_e32 v4, 0x1600, v160
	v_ashrrev_i32_e32 v9, 5, v4
	v_mad_u64_u32 v[4:5], s[48:49], v9, s45, v[8:9]
	ds_read2_b64 v[4:7], v4 offset1:1
	s_waitcnt lgkmcnt(1)
	global_store_dwordx4 v[12:13], v[0:3], off
	s_nop 1
	v_add_u32_e32 v0, s47, v9
	v_ashrrev_i32_e32 v1, 31, v0
	v_lshlrev_b64 v[0:1], 11, v[0:1]
	v_lshl_add_u64 v[0:1], s[14:15], 0, v[0:1]
	v_lshl_add_u64 v[0:1], v[0:1], 0, v[10:11]
	s_waitcnt lgkmcnt(0)
	global_store_dwordx4 v[0:1], v[4:7], off
	v_add_u32_e32 v0, 0x1800, v160
	v_ashrrev_i32_e32 v2, 5, v0
	v_add_u32_e32 v0, s47, v2
	v_ashrrev_i32_e32 v1, 31, v0
	v_lshlrev_b64 v[0:1], 11, v[0:1]
	v_lshl_add_u64 v[0:1], s[14:15], 0, v[0:1]
	v_lshl_add_u64 v[12:13], v[0:1], 0, v[10:11]
	v_mad_u64_u32 v[0:1], s[48:49], v2, s45, v[8:9]
	ds_read2_b64 v[0:3], v0 offset1:1
	v_add_u32_e32 v4, 0x1a00, v160
	v_ashrrev_i32_e32 v9, 5, v4
	v_mad_u64_u32 v[4:5], s[48:49], v9, s45, v[8:9]
	ds_read2_b64 v[4:7], v4 offset1:1
	s_waitcnt lgkmcnt(1)
	global_store_dwordx4 v[12:13], v[0:3], off
	s_nop 1
	v_add_u32_e32 v0, s47, v9
	v_ashrrev_i32_e32 v1, 31, v0
	v_lshlrev_b64 v[0:1], 11, v[0:1]
	v_lshl_add_u64 v[0:1], s[14:15], 0, v[0:1]
	v_lshl_add_u64 v[0:1], v[0:1], 0, v[10:11]
	s_waitcnt lgkmcnt(0)
	global_store_dwordx4 v[0:1], v[4:7], off
	v_add_u32_e32 v0, 0x1c00, v160
	v_ashrrev_i32_e32 v2, 5, v0
	v_add_u32_e32 v0, s47, v2
	v_ashrrev_i32_e32 v1, 31, v0
	v_lshlrev_b64 v[0:1], 11, v[0:1]
	v_lshl_add_u64 v[0:1], s[14:15], 0, v[0:1]
	v_lshl_add_u64 v[12:13], v[0:1], 0, v[10:11]
	v_mad_u64_u32 v[0:1], s[48:49], v2, s45, v[8:9]
	ds_read2_b64 v[0:3], v0 offset1:1
	v_add_u32_e32 v4, 0x1e00, v160
	v_ashrrev_i32_e32 v9, 5, v4
	v_mad_u64_u32 v[4:5], s[48:49], v9, s45, v[8:9]
	ds_read2_b64 v[4:7], v4 offset1:1
	s_waitcnt lgkmcnt(1)
	global_store_dwordx4 v[12:13], v[0:3], off
	s_nop 1
	v_add_u32_e32 v0, s47, v9
	v_ashrrev_i32_e32 v1, 31, v0
	v_lshlrev_b64 v[0:1], 11, v[0:1]
	v_lshl_add_u64 v[0:1], s[14:15], 0, v[0:1]
	v_lshl_add_u64 v[0:1], v[0:1], 0, v[10:11]
	s_waitcnt lgkmcnt(0)
	global_store_dwordx4 v[0:1], v[4:7], off
	s_branch .LBB0_418

; DI unsigned pack2(float a, float b) { f32x2_t v = {a, b}; bf16x2_t r = __builtin_convertvector(v, bf16x2_t); return __builtin_bit_cast(unsigned, r); }
; DI float sigmoidf_(float x) { return __builtin_amdgcn_rcpf(1.f + __expf(-x)); }
; template <bool LAST>
; DI void phase_gate(const Params& P, int layer, unsigned char* smem, int L, int G) {
;     ...
;     unsigned gq[4][2][8];
; #pragma unroll
;     for (int i = 0; i < 4; ++i)
; #pragma unroll
;       for (int q4 = 0; q4 < 4; ++q4) {
;         const int fl = wm * 128 + i * 32 + 8 * q4 + 4 * h;
;         const f32x4 c1v = *(const f32x4*)(vecL + fl), c2v = *(const f32x4*)(vecL + 256 + fl);
;         const float c1a[4] = {c1v.x, c1v.y, c1v.z, c1v.w}, c2a[4] = {c2v.x, c2v.y, c2v.z, c2v.w};
; #pragma unroll
;         for (int j = 0; j < 2; ++j) {
;           const int lrow = wn * 64 + j * 32 + r;
;           const float mu = rowA[lrow], rstd = rowB[lrow];
;           float sg4[4];
; #pragma unroll
;           for (int e = 0; e < 4; ++e) sg4[e] = sigmoidf_(rstd * (accu[i][j][4 * q4 + e] - mu * c1a[e]) + c2a[e]);
;           gq[i][j][2 * q4] = pack2(sg4[0], sg4[1]); gq[i][j][2 * q4 + 1] = pack2(sg4[2], sg4[3]);
;         }
;         __builtin_amdgcn_sched_barrier(0);
;       }
.LBB0_479:
	v_lshrrev_b32_e32 v160, 1, v163
	v_lshrrev_b32_e32 v163, 3, v163
	v_and_b32_e32 v163, 4, v163
	v_and_or_b32 v160, v160, s43, v163
	v_lshlrev_b32_e32 v160, 2, v160
	v_add_u32_e32 v163, 0x24800, v160
	v_add_u32_e32 v164, 0x24c00, v160
	v_and_b32_e32 v167, 0x37c, v168
	ds_read_b128 v[170:173], v163
	ds_read_b128 v[174:177], v164
	v_or_b32_e32 v164, 0x24000, v167
	v_or_b32_e32 v166, 0x24080, v167
	v_or_b32_e32 v165, 0x24400, v167
	ds_read_b32 v168, v164
	ds_read_b32 v169, v165
	v_or_b32_e32 v167, 0x24480, v167
	ds_read_b32 v178, v166
	ds_read_b32 v179, v167
	s_waitcnt lgkmcnt(3)
	v_fma_f32 v112, -v170, v168, v112
	v_fma_f32 v113, -v171, v168, v113
	s_waitcnt lgkmcnt(1)
	v_fma_f32 v98, -v172, v178, v98
	v_fma_f32 v114, -v172, v168, v114
	v_fma_f32 v115, -v173, v168, v115
	v_fma_f32 v96, -v170, v178, v96
	v_fma_f32 v97, -v171, v178, v97
	s_waitcnt lgkmcnt(0)
	v_fma_f32 v98, v179, v98, v176
	v_fma_f32 v99, -v173, v178, v99
	v_fma_f32 v112, v169, v112, v174
	v_fma_f32 v113, v169, v113, v175
	v_fma_f32 v114, v169, v114, v176
	v_fma_f32 v115, v169, v115, v177
	v_fma_f32 v96, v179, v96, v174
	v_fma_f32 v97, v179, v97, v175
	v_mul_f32_e32 v98, 0xbfb8aa3b, v98
	v_fmac_f32_e32 v177, v179, v99
	v_mul_f32_e32 v112, 0xbfb8aa3b, v112
	v_mul_f32_e32 v113, 0xbfb8aa3b, v113
	v_mul_f32_e32 v114, 0xbfb8aa3b, v114
	v_mul_f32_e32 v115, 0xbfb8aa3b, v115
	v_mul_f32_e32 v96, 0xbfb8aa3b, v96
	v_mul_f32_e32 v97, 0xbfb8aa3b, v97
	v_exp_f32_e32 v98, v98
	v_mul_f32_e32 v99, 0xbfb8aa3b, v177
	v_exp_f32_e32 v112, v112
	v_exp_f32_e32 v113, v113
	v_exp_f32_e32 v114, v114
	v_exp_f32_e32 v115, v115
	v_exp_f32_e32 v96, v96
	v_exp_f32_e32 v97, v97
	v_exp_f32_e32 v99, v99
	v_add_f32_e32 v98, 1.0, v98
	v_add_f32_e32 v112, 1.0, v112
	v_add_f32_e32 v113, 1.0, v113
	v_add_f32_e32 v114, 1.0, v114
	v_add_f32_e32 v115, 1.0, v115
	v_add_f32_e32 v96, 1.0, v96
	v_add_f32_e32 v97, 1.0, v97
	v_rcp_f32_e32 v168, v98
	v_add_f32_e32 v98, 1.0, v99
	v_rcp_f32_e32 v112, v112
	v_rcp_f32_e32 v113, v113
	v_rcp_f32_e32 v114, v114
	v_rcp_f32_e32 v115, v115
	v_rcp_f32_e32 v96, v96
	v_rcp_f32_e32 v97, v97
	v_rcp_f32_e32 v169, v98
	v_cvt_pk_bf16_f32 v99, v112, v113
	v_cvt_pk_bf16_f32 v98, v114, v115
	v_cvt_pk_bf16_f32 v97, v96, v97
	v_cvt_pk_bf16_f32 v96, v168, v169
	v_add_u32_e32 v112, 0x24820, v160
	v_add_u32_e32 v168, 0x24c20, v160
	ds_read_b128 v[112:115], v112
	ds_read_b128 v[168:171], v168
	ds_read_b32 v172, v164
	ds_read_b32 v173, v165
	ds_read_b32 v174, v166
	ds_read_b32 v175, v167
	s_waitcnt lgkmcnt(3)
	v_fma_f32 v116, -v112, v172, v116
	v_fma_f32 v117, -v113, v172, v117
	s_waitcnt lgkmcnt(1)
	v_fma_f32 v102, -v114, v174, v102
	v_fma_f32 v118, -v114, v172, v118
	v_fma_f32 v119, -v115, v172, v119
	v_fma_f32 v100, -v112, v174, v100
	v_fma_f32 v101, -v113, v174, v101
	s_waitcnt lgkmcnt(0)
	v_fma_f32 v102, v175, v102, v170
	v_fma_f32 v103, -v115, v174, v103
	v_fma_f32 v116, v173, v116, v168
	v_fma_f32 v117, v173, v117, v169
	v_fma_f32 v118, v173, v118, v170
	v_fma_f32 v119, v173, v119, v171
	v_fma_f32 v100, v175, v100, v168
	v_fma_f32 v101, v175, v101, v169
	v_mul_f32_e32 v102, 0xbfb8aa3b, v102
	v_fmac_f32_e32 v171, v175, v103
	v_mul_f32_e32 v116, 0xbfb8aa3b, v116
	v_mul_f32_e32 v117, 0xbfb8aa3b, v117
	v_mul_f32_e32 v118, 0xbfb8aa3b, v118
	v_mul_f32_e32 v119, 0xbfb8aa3b, v119
	v_mul_f32_e32 v100, 0xbfb8aa3b, v100
	v_mul_f32_e32 v101, 0xbfb8aa3b, v101
	v_exp_f32_e32 v102, v102
	v_mul_f32_e32 v103, 0xbfb8aa3b, v171
	v_exp_f32_e32 v116, v116
	v_exp_f32_e32 v117, v117
	v_exp_f32_e32 v118, v118
	v_exp_f32_e32 v119, v119
	v_exp_f32_e32 v100, v100
	v_exp_f32_e32 v101, v101
	v_exp_f32_e32 v103, v103
	v_add_f32_e32 v102, 1.0, v102
	v_add_f32_e32 v116, 1.0, v116
	v_add_f32_e32 v117, 1.0, v117
	v_add_f32_e32 v118, 1.0, v118
	v_add_f32_e32 v119, 1.0, v119
	v_add_f32_e32 v100, 1.0, v100
	v_add_f32_e32 v101, 1.0, v101
	v_rcp_f32_e32 v113, v102
	v_add_f32_e32 v102, 1.0, v103
	v_rcp_f32_e32 v116, v116
	v_rcp_f32_e32 v117, v117
	v_rcp_f32_e32 v118, v118
	v_rcp_f32_e32 v112, v119
	v_rcp_f32_e32 v100, v100
	v_rcp_f32_e32 v101, v101
	v_rcp_f32_e32 v114, v102
	v_cvt_pk_bf16_f32 v103, v116, v117
	v_cvt_pk_bf16_f32 v102, v118, v112
	v_cvt_pk_bf16_f32 v101, v100, v101
	v_cvt_pk_bf16_f32 v100, v113, v114
	v_add_u32_e32 v112, 0x24840, v160
	v_add_u32_e32 v116, 0x24c40, v160
	ds_read_b128 v[112:115], v112
	ds_read_b128 v[116:119], v116
	ds_read_b32 v168, v164
	ds_read_b32 v169, v165
	ds_read_b32 v170, v166
	ds_read_b32 v171, v167
	s_waitcnt lgkmcnt(3)
	v_fma_f32 v120, -v112, v168, v120
	v_fma_f32 v121, -v113, v168, v121
	s_waitcnt lgkmcnt(1)
	v_fma_f32 v106, -v114, v170, v106
	v_fma_f32 v122, -v114, v168, v122
	v_fma_f32 v123, -v115, v168, v123
	v_fma_f32 v104, -v112, v170, v104
	v_fma_f32 v105, -v113, v170, v105
	s_waitcnt lgkmcnt(0)
	v_fma_f32 v106, v171, v106, v118
	v_fma_f32 v107, -v115, v170, v107
	v_fma_f32 v120, v169, v120, v116
	v_fma_f32 v121, v169, v121, v117
	v_fma_f32 v122, v169, v122, v118
	v_fma_f32 v123, v169, v123, v119
	v_fma_f32 v104, v171, v104, v116
	v_fma_f32 v105, v171, v105, v117
	v_mul_f32_e32 v106, 0xbfb8aa3b, v106
	v_fmac_f32_e32 v119, v171, v107
	v_mul_f32_e32 v120, 0xbfb8aa3b, v120
	v_mul_f32_e32 v121, 0xbfb8aa3b, v121
	v_mul_f32_e32 v122, 0xbfb8aa3b, v122
	v_mul_f32_e32 v123, 0xbfb8aa3b, v123
	v_mul_f32_e32 v104, 0xbfb8aa3b, v104
	v_mul_f32_e32 v105, 0xbfb8aa3b, v105
	v_exp_f32_e32 v106, v106
	v_mul_f32_e32 v107, 0xbfb8aa3b, v119
	v_exp_f32_e32 v120, v120
	v_exp_f32_e32 v121, v121
	v_exp_f32_e32 v122, v122
	v_exp_f32_e32 v123, v123
	v_exp_f32_e32 v104, v104
	v_exp_f32_e32 v105, v105
	v_exp_f32_e32 v107, v107
	v_add_f32_e32 v106, 1.0, v106
	v_add_f32_e32 v120, 1.0, v120
	v_add_f32_e32 v121, 1.0, v121
	v_add_f32_e32 v122, 1.0, v122
	v_add_f32_e32 v123, 1.0, v123
	v_add_f32_e32 v104, 1.0, v104
	v_add_f32_e32 v105, 1.0, v105
	v_rcp_f32_e32 v113, v106
	v_add_f32_e32 v106, 1.0, v107
	v_rcp_f32_e32 v120, v120
	v_rcp_f32_e32 v121, v121
	v_rcp_f32_e32 v122, v122
	v_rcp_f32_e32 v112, v123
	v_rcp_f32_e32 v104, v104
	v_rcp_f32_e32 v105, v105
	v_rcp_f32_e32 v114, v106
	v_cvt_pk_bf16_f32 v107, v120, v121
	v_cvt_pk_bf16_f32 v106, v122, v112
	v_cvt_pk_bf16_f32 v105, v104, v105
	v_cvt_pk_bf16_f32 v104, v113, v114
	v_add_u32_e32 v112, 0x24860, v160
	v_add_u32_e32 v116, 0x24c60, v160
	ds_read_b128 v[112:115], v112
	ds_read_b128 v[116:119], v116
	ds_read_b32 v120, v164
	ds_read_b32 v121, v165
	ds_read_b32 v122, v166
	ds_read_b32 v123, v167
	s_waitcnt lgkmcnt(3)
; DI unsigned pack2(float a, float b) { f32x2_t v = {a, b}; bf16x2_t r = __builtin_convertvector(v, bf16x2_t); return __builtin_bit_cast(unsigned, r); }
; DI float sigmoidf_(float x) { return __builtin_amdgcn_rcpf(1.f + __expf(-x)); }
; template <bool LAST>
; DI void phase_gate(const Params& P, int layer, unsigned char* smem, int L, int G) {
;     ...
; #pragma unroll
;     for (int i = 0; i < 4; ++i)
; #pragma unroll
;       for (int q4 = 0; q4 < 4; ++q4) {
;         const int fl = wm * 128 + i * 32 + 8 * q4 + 4 * h;
;         const f32x4 c1v = *(const f32x4*)(vecL + fl), c2v = *(const f32x4*)(vecL + 256 + fl);
;         const float c1a[4] = {c1v.x, c1v.y, c1v.z, c1v.w}, c2a[4] = {c2v.x, c2v.y, c2v.z, c2v.w};
; #pragma unroll
;         for (int j = 0; j < 2; ++j) {
;           const int lrow = wn * 64 + j * 32 + r;
;           const float mu = rowA[lrow], rstd = rowB[lrow];
;           float sg4[4];
; #pragma unroll
;           for (int e = 0; e < 4; ++e) sg4[e] = sigmoidf_(rstd * (accu[i][j][4 * q4 + e] - mu * c1a[e]) + c2a[e]);
;           gq[i][j][2 * q4] = pack2(sg4[0], sg4[1]); gq[i][j][2 * q4 + 1] = pack2(sg4[2], sg4[3]);
;         }
;         __builtin_amdgcn_sched_barrier(0);
;       }
	v_fma_f32 v125, -v113, v120, v125
	v_fma_f32 v124, -v112, v120, v124
	s_waitcnt lgkmcnt(1)
	v_fma_f32 v110, -v114, v122, v110
	v_fma_f32 v125, v121, v125, v117
	v_fma_f32 v126, -v114, v120, v126
	v_fma_f32 v120, -v115, v120, v127
	v_fma_f32 v108, -v112, v122, v108
	v_fma_f32 v109, -v113, v122, v109
	s_waitcnt lgkmcnt(0)
	v_fma_f32 v110, v123, v110, v118
	v_fma_f32 v111, -v115, v122, v111
	v_fma_f32 v124, v121, v124, v116
	v_mul_f32_e32 v125, 0xbfb8aa3b, v125
	v_fma_f32 v126, v121, v126, v118
	v_fma_f32 v120, v121, v120, v119
	v_fma_f32 v108, v123, v108, v116
	v_fma_f32 v109, v123, v109, v117
	v_mul_f32_e32 v110, 0xbfb8aa3b, v110
	v_fmac_f32_e32 v119, v123, v111
	v_mul_f32_e32 v124, 0xbfb8aa3b, v124
	v_exp_f32_e32 v125, v125
	v_mul_f32_e32 v126, 0xbfb8aa3b, v126
	v_mul_f32_e32 v120, 0xbfb8aa3b, v120
	v_mul_f32_e32 v108, 0xbfb8aa3b, v108
	v_mul_f32_e32 v109, 0xbfb8aa3b, v109
	v_exp_f32_e32 v110, v110
	v_mul_f32_e32 v111, 0xbfb8aa3b, v119
	v_exp_f32_e32 v124, v124
	v_exp_f32_e32 v126, v126
	v_exp_f32_e32 v120, v120
	v_exp_f32_e32 v108, v108
	v_exp_f32_e32 v109, v109
	v_exp_f32_e32 v111, v111
	v_add_f32_e32 v125, 1.0, v125
	v_add_f32_e32 v110, 1.0, v110
	v_add_f32_e32 v124, 1.0, v124
	v_rcp_f32_e32 v121, v125
	v_add_f32_e32 v125, 1.0, v126
	v_add_f32_e32 v120, 1.0, v120
	v_add_f32_e32 v108, 1.0, v108
	v_add_f32_e32 v109, 1.0, v109
	v_rcp_f32_e32 v113, v110
	v_add_f32_e32 v110, 1.0, v111
	v_rcp_f32_e32 v124, v124
	v_rcp_f32_e32 v125, v125
	v_rcp_f32_e32 v112, v120
	v_rcp_f32_e32 v108, v108
	v_rcp_f32_e32 v109, v109
	v_rcp_f32_e32 v114, v110
	v_cvt_pk_bf16_f32 v111, v124, v121
	v_cvt_pk_bf16_f32 v110, v125, v112
	v_cvt_pk_bf16_f32 v109, v108, v109
	v_cvt_pk_bf16_f32 v108, v113, v114
	v_add_u32_e32 v112, 0x24880, v160
	v_add_u32_e32 v116, 0x24c80, v160
	ds_read_b128 v[112:115], v112
	ds_read_b128 v[116:119], v116
	ds_read_b32 v120, v164
	ds_read_b32 v121, v165
	ds_read_b32 v122, v166
	ds_read_b32 v123, v167
	s_waitcnt lgkmcnt(3)
	v_fma_f32 v80, -v112, v120, v80
	v_fma_f32 v81, -v113, v120, v81
	s_waitcnt lgkmcnt(1)
	v_fma_f32 v66, -v114, v122, v66
	v_fma_f32 v82, -v114, v120, v82
	v_fma_f32 v83, -v115, v120, v83
	v_fma_f32 v64, -v112, v122, v64
	v_fma_f32 v65, -v113, v122, v65
	s_waitcnt lgkmcnt(0)
	v_fma_f32 v66, v123, v66, v118
	v_fma_f32 v67, -v115, v122, v67
	v_fma_f32 v80, v121, v80, v116
	v_fma_f32 v81, v121, v81, v117
	v_fma_f32 v82, v121, v82, v118
	v_fma_f32 v83, v121, v83, v119
	v_fma_f32 v64, v123, v64, v116
	v_fma_f32 v65, v123, v65, v117
	v_mul_f32_e32 v66, 0xbfb8aa3b, v66
	v_fmac_f32_e32 v119, v123, v67
	v_mul_f32_e32 v80, 0xbfb8aa3b, v80
	v_mul_f32_e32 v81, 0xbfb8aa3b, v81
	v_mul_f32_e32 v82, 0xbfb8aa3b, v82
	v_mul_f32_e32 v83, 0xbfb8aa3b, v83
	v_mul_f32_e32 v64, 0xbfb8aa3b, v64
	v_mul_f32_e32 v65, 0xbfb8aa3b, v65
	v_exp_f32_e32 v66, v66
	v_mul_f32_e32 v67, 0xbfb8aa3b, v119
	v_exp_f32_e32 v80, v80
	v_exp_f32_e32 v81, v81
	v_exp_f32_e32 v82, v82
	v_exp_f32_e32 v83, v83
	v_exp_f32_e32 v64, v64
	v_exp_f32_e32 v65, v65
	v_exp_f32_e32 v67, v67
	v_add_f32_e32 v66, 1.0, v66
	v_add_f32_e32 v80, 1.0, v80
	v_add_f32_e32 v81, 1.0, v81
	v_add_f32_e32 v82, 1.0, v82
	v_add_f32_e32 v83, 1.0, v83
	v_add_f32_e32 v64, 1.0, v64
	v_add_f32_e32 v65, 1.0, v65
	v_rcp_f32_e32 v112, v66
	v_add_f32_e32 v66, 1.0, v67
	v_rcp_f32_e32 v80, v80
	v_rcp_f32_e32 v81, v81
	v_rcp_f32_e32 v82, v82
	v_rcp_f32_e32 v83, v83
	v_rcp_f32_e32 v64, v64
	v_rcp_f32_e32 v65, v65
	v_rcp_f32_e32 v113, v66
	v_cvt_pk_bf16_f32 v67, v80, v81
	v_cvt_pk_bf16_f32 v66, v82, v83
	v_cvt_pk_bf16_f32 v65, v64, v65
	v_cvt_pk_bf16_f32 v64, v112, v113
	v_add_u32_e32 v80, 0x248a0, v160
	v_add_u32_e32 v112, 0x24ca0, v160
	ds_read_b128 v[80:83], v80
	ds_read_b128 v[112:115], v112
	ds_read_b32 v116, v164
	ds_read_b32 v117, v165
	ds_read_b32 v118, v166
	ds_read_b32 v119, v167
	s_waitcnt lgkmcnt(3)
	v_fma_f32 v84, -v80, v116, v84
	v_fma_f32 v85, -v81, v116, v85
	s_waitcnt lgkmcnt(1)
	v_fma_f32 v70, -v82, v118, v70
	v_fma_f32 v86, -v82, v116, v86
	v_fma_f32 v87, -v83, v116, v87
	v_fma_f32 v68, -v80, v118, v68
	v_fma_f32 v69, -v81, v118, v69
	s_waitcnt lgkmcnt(0)
	v_fma_f32 v70, v119, v70, v114
	v_fma_f32 v71, -v83, v118, v71
	v_fma_f32 v84, v117, v84, v112
	v_fma_f32 v85, v117, v85, v113
	v_fma_f32 v86, v117, v86, v114
	v_fma_f32 v87, v117, v87, v115
	v_fma_f32 v68, v119, v68, v112
	v_fma_f32 v69, v119, v69, v113
	v_mul_f32_e32 v70, 0xbfb8aa3b, v70
	v_fmac_f32_e32 v115, v119, v71
	v_mul_f32_e32 v84, 0xbfb8aa3b, v84
	v_mul_f32_e32 v85, 0xbfb8aa3b, v85
	v_mul_f32_e32 v86, 0xbfb8aa3b, v86
	v_mul_f32_e32 v87, 0xbfb8aa3b, v87
	v_mul_f32_e32 v68, 0xbfb8aa3b, v68
	v_mul_f32_e32 v69, 0xbfb8aa3b, v69
	v_exp_f32_e32 v70, v70
	v_mul_f32_e32 v71, 0xbfb8aa3b, v115
	v_exp_f32_e32 v84, v84
	v_exp_f32_e32 v85, v85
	v_exp_f32_e32 v86, v86
	v_exp_f32_e32 v87, v87
	v_exp_f32_e32 v68, v68
	v_exp_f32_e32 v69, v69
	v_exp_f32_e32 v71, v71
	v_add_f32_e32 v70, 1.0, v70
	v_add_f32_e32 v84, 1.0, v84
	v_add_f32_e32 v85, 1.0, v85
	v_add_f32_e32 v86, 1.0, v86
	v_add_f32_e32 v87, 1.0, v87
	v_add_f32_e32 v68, 1.0, v68
	v_add_f32_e32 v69, 1.0, v69
	v_rcp_f32_e32 v81, v70
	v_add_f32_e32 v70, 1.0, v71
	v_rcp_f32_e32 v84, v84
	v_rcp_f32_e32 v85, v85
	v_rcp_f32_e32 v86, v86
	v_rcp_f32_e32 v80, v87
	v_rcp_f32_e32 v68, v68
	v_rcp_f32_e32 v69, v69
	v_rcp_f32_e32 v82, v70
	v_cvt_pk_bf16_f32 v71, v84, v85
	v_cvt_pk_bf16_f32 v70, v86, v80
	v_cvt_pk_bf16_f32 v69, v68, v69
	v_cvt_pk_bf16_f32 v68, v81, v82
	v_add_u32_e32 v80, 0x248c0, v160
	v_add_u32_e32 v84, 0x24cc0, v160
	ds_read_b128 v[80:83], v80
	ds_read_b128 v[84:87], v84
	ds_read_b32 v112, v164
	ds_read_b32 v113, v165
	ds_read_b32 v114, v166
	ds_read_b32 v115, v167
	s_waitcnt lgkmcnt(3)
; DI unsigned pack2(float a, float b) { f32x2_t v = {a, b}; bf16x2_t r = __builtin_convertvector(v, bf16x2_t); return __builtin_bit_cast(unsigned, r); }
; DI float sigmoidf_(float x) { return __builtin_amdgcn_rcpf(1.f + __expf(-x)); }
; template <bool LAST>
; DI void phase_gate(const Params& P, int layer, unsigned char* smem, int L, int G) {
;     ...
; #pragma unroll
;     for (int i = 0; i < 4; ++i)
; #pragma unroll
;       for (int q4 = 0; q4 < 4; ++q4) {
;         const int fl = wm * 128 + i * 32 + 8 * q4 + 4 * h;
;         const f32x4 c1v = *(const f32x4*)(vecL + fl), c2v = *(const f32x4*)(vecL + 256 + fl);
;         const float c1a[4] = {c1v.x, c1v.y, c1v.z, c1v.w}, c2a[4] = {c2v.x, c2v.y, c2v.z, c2v.w};
; #pragma unroll
;         for (int j = 0; j < 2; ++j) {
;           const int lrow = wn * 64 + j * 32 + r;
;           const float mu = rowA[lrow], rstd = rowB[lrow];
;           float sg4[4];
; #pragma unroll
;           for (int e = 0; e < 4; ++e) sg4[e] = sigmoidf_(rstd * (accu[i][j][4 * q4 + e] - mu * c1a[e]) + c2a[e]);
;           gq[i][j][2 * q4] = pack2(sg4[0], sg4[1]); gq[i][j][2 * q4 + 1] = pack2(sg4[2], sg4[3]);
;         }
;         __builtin_amdgcn_sched_barrier(0);
;       }
	v_fma_f32 v88, -v80, v112, v88
	v_fma_f32 v89, -v81, v112, v89
	s_waitcnt lgkmcnt(1)
	v_fma_f32 v74, -v82, v114, v74
	v_fma_f32 v90, -v82, v112, v90
	v_fma_f32 v91, -v83, v112, v91
	v_fma_f32 v72, -v80, v114, v72
	v_fma_f32 v73, -v81, v114, v73
	s_waitcnt lgkmcnt(0)
	v_fma_f32 v74, v115, v74, v86
	v_fma_f32 v75, -v83, v114, v75
	v_fma_f32 v88, v113, v88, v84
	v_fma_f32 v89, v113, v89, v85
	v_fma_f32 v90, v113, v90, v86
	v_fma_f32 v91, v113, v91, v87
	v_fma_f32 v72, v115, v72, v84
	v_fma_f32 v73, v115, v73, v85
	v_mul_f32_e32 v74, 0xbfb8aa3b, v74
	v_fmac_f32_e32 v87, v115, v75
	v_mul_f32_e32 v88, 0xbfb8aa3b, v88
	v_mul_f32_e32 v89, 0xbfb8aa3b, v89
	v_mul_f32_e32 v90, 0xbfb8aa3b, v90
	v_mul_f32_e32 v91, 0xbfb8aa3b, v91
	v_mul_f32_e32 v72, 0xbfb8aa3b, v72
	v_mul_f32_e32 v73, 0xbfb8aa3b, v73
	v_exp_f32_e32 v74, v74
	v_mul_f32_e32 v75, 0xbfb8aa3b, v87
	v_exp_f32_e32 v88, v88
	v_exp_f32_e32 v89, v89
	v_exp_f32_e32 v90, v90
	v_exp_f32_e32 v91, v91
	v_exp_f32_e32 v72, v72
	v_exp_f32_e32 v73, v73
	v_exp_f32_e32 v75, v75
	v_add_f32_e32 v74, 1.0, v74
	v_add_f32_e32 v88, 1.0, v88
	v_add_f32_e32 v89, 1.0, v89
	v_add_f32_e32 v90, 1.0, v90
	v_add_f32_e32 v91, 1.0, v91
	v_add_f32_e32 v72, 1.0, v72
	v_add_f32_e32 v73, 1.0, v73
	v_rcp_f32_e32 v81, v74
	v_add_f32_e32 v74, 1.0, v75
	v_rcp_f32_e32 v88, v88
	v_rcp_f32_e32 v89, v89
	v_rcp_f32_e32 v90, v90
	v_rcp_f32_e32 v80, v91
	v_rcp_f32_e32 v72, v72
	v_rcp_f32_e32 v73, v73
	v_rcp_f32_e32 v82, v74
	v_cvt_pk_bf16_f32 v75, v88, v89
	v_cvt_pk_bf16_f32 v74, v90, v80
	v_cvt_pk_bf16_f32 v73, v72, v73
	v_cvt_pk_bf16_f32 v72, v81, v82
	v_add_u32_e32 v80, 0x248e0, v160
	v_add_u32_e32 v84, 0x24ce0, v160
	ds_read_b128 v[80:83], v80
	ds_read_b128 v[84:87], v84
	ds_read_b32 v88, v164
	ds_read_b32 v89, v165
	ds_read_b32 v90, v166
	ds_read_b32 v91, v167
	s_waitcnt lgkmcnt(3)
	v_fma_f32 v93, -v81, v88, v93
	v_fma_f32 v92, -v80, v88, v92
	s_waitcnt lgkmcnt(1)
	v_fma_f32 v78, -v82, v90, v78
	v_fma_f32 v93, v89, v93, v85
	v_fma_f32 v94, -v82, v88, v94
	v_fma_f32 v88, -v83, v88, v95
	v_fma_f32 v76, -v80, v90, v76
	v_fma_f32 v77, -v81, v90, v77
	s_waitcnt lgkmcnt(0)
	v_fma_f32 v78, v91, v78, v86
	v_fma_f32 v79, -v83, v90, v79
	v_fma_f32 v92, v89, v92, v84
	v_mul_f32_e32 v93, 0xbfb8aa3b, v93
	v_fma_f32 v94, v89, v94, v86
	v_fma_f32 v88, v89, v88, v87
	v_fma_f32 v76, v91, v76, v84
	v_fma_f32 v77, v91, v77, v85
	v_mul_f32_e32 v78, 0xbfb8aa3b, v78
	v_fmac_f32_e32 v87, v91, v79
	v_mul_f32_e32 v92, 0xbfb8aa3b, v92
	v_exp_f32_e32 v93, v93
	v_mul_f32_e32 v94, 0xbfb8aa3b, v94
	v_mul_f32_e32 v88, 0xbfb8aa3b, v88
	v_mul_f32_e32 v76, 0xbfb8aa3b, v76
	v_mul_f32_e32 v77, 0xbfb8aa3b, v77
	v_exp_f32_e32 v78, v78
	v_mul_f32_e32 v79, 0xbfb8aa3b, v87
	v_exp_f32_e32 v92, v92
	v_exp_f32_e32 v94, v94
	v_exp_f32_e32 v88, v88
	v_exp_f32_e32 v76, v76
	v_exp_f32_e32 v77, v77
	v_exp_f32_e32 v79, v79
	v_add_f32_e32 v93, 1.0, v93
	v_add_f32_e32 v78, 1.0, v78
	v_add_f32_e32 v92, 1.0, v92
	v_rcp_f32_e32 v89, v93
	v_add_f32_e32 v93, 1.0, v94
	v_add_f32_e32 v88, 1.0, v88
	v_add_f32_e32 v76, 1.0, v76
	v_add_f32_e32 v77, 1.0, v77
	v_rcp_f32_e32 v81, v78
	v_add_f32_e32 v78, 1.0, v79
	v_rcp_f32_e32 v92, v92
	v_rcp_f32_e32 v93, v93
	v_rcp_f32_e32 v80, v88
	v_rcp_f32_e32 v76, v76
	v_rcp_f32_e32 v77, v77
	v_rcp_f32_e32 v82, v78
	v_cvt_pk_bf16_f32 v79, v92, v89
	v_cvt_pk_bf16_f32 v78, v93, v80
	v_cvt_pk_bf16_f32 v77, v76, v77
	v_cvt_pk_bf16_f32 v76, v81, v82
	v_add_u32_e32 v80, 0x24900, v160
	v_add_u32_e32 v84, 0x24d00, v160
	ds_read_b128 v[80:83], v80
	ds_read_b128 v[84:87], v84
	ds_read_b32 v88, v164
	ds_read_b32 v89, v165
	ds_read_b32 v90, v166
	ds_read_b32 v91, v167
	s_waitcnt lgkmcnt(3)
	v_fma_f32 v48, -v80, v88, v48
	v_fma_f32 v49, -v81, v88, v49
	s_waitcnt lgkmcnt(1)
	v_fma_f32 v34, -v82, v90, v34
	v_fma_f32 v50, -v82, v88, v50
	v_fma_f32 v51, -v83, v88, v51
	v_fma_f32 v32, -v80, v90, v32
	v_fma_f32 v33, -v81, v90, v33
	s_waitcnt lgkmcnt(0)
	v_fma_f32 v34, v91, v34, v86
	v_fma_f32 v35, -v83, v90, v35
	v_fma_f32 v48, v89, v48, v84
	v_fma_f32 v49, v89, v49, v85
	v_fma_f32 v50, v89, v50, v86
	v_fma_f32 v51, v89, v51, v87
	v_fma_f32 v32, v91, v32, v84
	v_fma_f32 v33, v91, v33, v85
	v_mul_f32_e32 v34, 0xbfb8aa3b, v34
	v_fmac_f32_e32 v87, v91, v35
	v_mul_f32_e32 v48, 0xbfb8aa3b, v48
	v_mul_f32_e32 v49, 0xbfb8aa3b, v49
	v_mul_f32_e32 v50, 0xbfb8aa3b, v50
	v_mul_f32_e32 v51, 0xbfb8aa3b, v51
	v_mul_f32_e32 v32, 0xbfb8aa3b, v32
	v_mul_f32_e32 v33, 0xbfb8aa3b, v33
	v_exp_f32_e32 v34, v34
	v_mul_f32_e32 v35, 0xbfb8aa3b, v87
	v_exp_f32_e32 v48, v48
	v_exp_f32_e32 v49, v49
	v_exp_f32_e32 v50, v50
	v_exp_f32_e32 v51, v51
	v_exp_f32_e32 v32, v32
	v_exp_f32_e32 v33, v33
	v_exp_f32_e32 v35, v35
	v_add_f32_e32 v34, 1.0, v34
	v_add_f32_e32 v48, 1.0, v48
	v_add_f32_e32 v49, 1.0, v49
	v_add_f32_e32 v50, 1.0, v50
	v_add_f32_e32 v51, 1.0, v51
	v_add_f32_e32 v32, 1.0, v32
	v_add_f32_e32 v33, 1.0, v33
	v_rcp_f32_e32 v80, v34
	v_add_f32_e32 v34, 1.0, v35
	v_rcp_f32_e32 v48, v48
	v_rcp_f32_e32 v49, v49
	v_rcp_f32_e32 v50, v50
	v_rcp_f32_e32 v51, v51
	v_rcp_f32_e32 v32, v32
	v_rcp_f32_e32 v33, v33
	v_rcp_f32_e32 v81, v34
	v_cvt_pk_bf16_f32 v35, v48, v49
	v_cvt_pk_bf16_f32 v34, v50, v51
	v_cvt_pk_bf16_f32 v33, v32, v33
	v_cvt_pk_bf16_f32 v32, v80, v81
	v_add_u32_e32 v48, 0x24920, v160
	v_add_u32_e32 v80, 0x24d20, v160
	ds_read_b128 v[48:51], v48
	ds_read_b128 v[80:83], v80
	ds_read_b32 v84, v164
	ds_read_b32 v85, v165
	ds_read_b32 v86, v166
	ds_read_b32 v87, v167
	s_waitcnt lgkmcnt(3)
	v_fma_f32 v53, -v49, v84, v53
	v_fma_f32 v52, -v48, v84, v52
	s_waitcnt lgkmcnt(1)
	v_fma_f32 v36, -v48, v86, v36
	s_waitcnt lgkmcnt(0)
; DI unsigned pack2(float a, float b) { f32x2_t v = {a, b}; bf16x2_t r = __builtin_convertvector(v, bf16x2_t); return __builtin_bit_cast(unsigned, r); }
; DI float sigmoidf_(float x) { return __builtin_amdgcn_rcpf(1.f + __expf(-x)); }
; template <bool LAST>
; DI void phase_gate(const Params& P, int layer, unsigned char* smem, int L, int G) {
;     ...
; #pragma unroll
;     for (int i = 0; i < 4; ++i)
; #pragma unroll
;       for (int q4 = 0; q4 < 4; ++q4) {
;         const int fl = wm * 128 + i * 32 + 8 * q4 + 4 * h;
;         const f32x4 c1v = *(const f32x4*)(vecL + fl), c2v = *(const f32x4*)(vecL + 256 + fl);
;         const float c1a[4] = {c1v.x, c1v.y, c1v.z, c1v.w}, c2a[4] = {c2v.x, c2v.y, c2v.z, c2v.w};
; #pragma unroll
;         for (int j = 0; j < 2; ++j) {
;           const int lrow = wn * 64 + j * 32 + r;
;           const float mu = rowA[lrow], rstd = rowB[lrow];
;           float sg4[4];
; #pragma unroll
;           for (int e = 0; e < 4; ++e) sg4[e] = sigmoidf_(rstd * (accu[i][j][4 * q4 + e] - mu * c1a[e]) + c2a[e]);
;           gq[i][j][2 * q4] = pack2(sg4[0], sg4[1]); gq[i][j][2 * q4 + 1] = pack2(sg4[2], sg4[3]);
;         }
;         __builtin_amdgcn_sched_barrier(0);
;       }
	v_fma_f32 v36, v87, v36, v80
	v_fma_f32 v37, -v49, v86, v37
	v_mul_f32_e32 v36, 0xbfb8aa3b, v36
	v_fma_f32 v37, v87, v37, v81
	v_exp_f32_e32 v36, v36
	v_mul_f32_e32 v37, 0xbfb8aa3b, v37
	v_exp_f32_e32 v37, v37
	v_fma_f32 v54, -v50, v84, v54
	v_add_f32_e32 v36, 1.0, v36
	v_rcp_f32_e32 v49, v36
	v_add_f32_e32 v36, 1.0, v37
	v_fma_f32 v37, -v50, v86, v38
	v_fma_f32 v55, -v51, v84, v55
	v_fma_f32 v37, v87, v37, v82
	v_fma_f32 v38, -v51, v86, v39
	v_fma_f32 v52, v85, v52, v80
	v_fma_f32 v53, v85, v53, v81
	v_fma_f32 v54, v85, v54, v82
	v_fma_f32 v55, v85, v55, v83
	v_mul_f32_e32 v37, 0xbfb8aa3b, v37
	v_fmac_f32_e32 v83, v87, v38
	v_mul_f32_e32 v52, 0xbfb8aa3b, v52
	v_mul_f32_e32 v53, 0xbfb8aa3b, v53
	v_mul_f32_e32 v54, 0xbfb8aa3b, v54
	v_mul_f32_e32 v55, 0xbfb8aa3b, v55
	v_exp_f32_e32 v37, v37
	v_mul_f32_e32 v38, 0xbfb8aa3b, v83
	v_exp_f32_e32 v52, v52
	v_exp_f32_e32 v53, v53
	v_exp_f32_e32 v54, v54
	v_exp_f32_e32 v55, v55
	v_exp_f32_e32 v38, v38
	v_rcp_f32_e32 v39, v36
	v_add_f32_e32 v36, 1.0, v37
	v_add_f32_e32 v52, 1.0, v52
	v_add_f32_e32 v53, 1.0, v53
	v_add_f32_e32 v54, 1.0, v54
	v_add_f32_e32 v55, 1.0, v55
	v_rcp_f32_e32 v37, v36
	v_add_f32_e32 v36, 1.0, v38
	v_rcp_f32_e32 v52, v52
	v_rcp_f32_e32 v53, v53
	v_rcp_f32_e32 v54, v54
	v_rcp_f32_e32 v48, v55
	v_rcp_f32_e32 v38, v36
	v_cvt_pk_bf16_f32 v80, v52, v53
	v_cvt_pk_bf16_f32 v55, v49, v39
	v_cvt_pk_bf16_f32 v36, v54, v48
	v_cvt_pk_bf16_f32 v53, v37, v38
	v_add_u32_e32 v37, 0x24940, v160
	v_add_u32_e32 v38, 0x24d40, v160
	ds_read_b128 v[48:51], v37
	ds_read_b128 v[82:85], v38
	ds_read_b32 v37, v164
	ds_read_b32 v38, v165
	ds_read_b32 v39, v166
	ds_read_b32 v52, v167
	s_waitcnt lgkmcnt(3)
	v_fma_f32 v54, -v48, v37, v56
	v_fma_f32 v56, -v49, v37, v57
	s_waitcnt lgkmcnt(2)
	v_fma_f32 v56, v38, v56, v83
	v_fma_f32 v57, -v50, v37, v58
	v_fma_f32 v37, -v51, v37, v59
	s_waitcnt lgkmcnt(1)
	v_fma_f32 v40, -v48, v39, v40
	v_fma_f32 v41, -v49, v39, v41
	v_fma_f32 v42, -v50, v39, v42
	v_fma_f32 v39, -v51, v39, v43
	v_fma_f32 v54, v38, v54, v82
	v_mul_f32_e32 v56, 0xbfb8aa3b, v56
	v_fma_f32 v57, v38, v57, v84
	v_fma_f32 v37, v38, v37, v85
	s_waitcnt lgkmcnt(0)
	v_fma_f32 v40, v52, v40, v82
	v_fma_f32 v41, v52, v41, v83
	v_fma_f32 v42, v52, v42, v84
	v_fmac_f32_e32 v85, v52, v39
	v_mul_f32_e32 v54, 0xbfb8aa3b, v54
	v_exp_f32_e32 v56, v56
	v_mul_f32_e32 v57, 0xbfb8aa3b, v57
	v_mul_f32_e32 v37, 0xbfb8aa3b, v37
	v_mul_f32_e32 v40, 0xbfb8aa3b, v40
	v_mul_f32_e32 v41, 0xbfb8aa3b, v41
	v_mul_f32_e32 v42, 0xbfb8aa3b, v42
	v_mul_f32_e32 v39, 0xbfb8aa3b, v85
	v_exp_f32_e32 v54, v54
	v_exp_f32_e32 v57, v57
	v_exp_f32_e32 v37, v37
	v_exp_f32_e32 v40, v40
	v_exp_f32_e32 v41, v41
	v_exp_f32_e32 v42, v42
	v_exp_f32_e32 v39, v39
	v_add_f32_e32 v56, 1.0, v56
	v_add_f32_e32 v54, 1.0, v54
	v_rcp_f32_e32 v38, v56
	v_add_f32_e32 v56, 1.0, v57
	v_add_f32_e32 v37, 1.0, v37
	v_add_f32_e32 v40, 1.0, v40
	v_add_f32_e32 v41, 1.0, v41
	v_add_f32_e32 v42, 1.0, v42
	v_add_f32_e32 v39, 1.0, v39
	v_rcp_f32_e32 v54, v54
	v_rcp_f32_e32 v56, v56
	v_rcp_f32_e32 v37, v37
	v_rcp_f32_e32 v40, v40
	v_rcp_f32_e32 v41, v41
	v_rcp_f32_e32 v42, v42
	v_rcp_f32_e32 v39, v39
	v_cvt_pk_bf16_f32 v83, v54, v38
	v_cvt_pk_bf16_f32 v82, v56, v37
	v_cvt_pk_bf16_f32 v81, v40, v41
	v_cvt_pk_bf16_f32 v59, v42, v39
	v_add_u32_e32 v37, 0x24960, v160
	v_add_u32_e32 v42, 0x24d60, v160
	ds_read_b128 v[38:41], v37
	ds_read_b128 v[48:51], v42
	ds_read_b32 v37, v164
	ds_read_b32 v42, v165
	ds_read_b32 v43, v166
	ds_read_b32 v52, v167
	s_waitcnt lgkmcnt(3)
	v_fma_f32 v56, -v39, v37, v61
	v_fma_f32 v54, -v38, v37, v60
	s_waitcnt lgkmcnt(2)
	v_fma_f32 v56, v42, v56, v49
	v_fma_f32 v57, -v40, v37, v62
	v_fma_f32 v37, -v41, v37, v63
	s_waitcnt lgkmcnt(1)
	v_fma_f32 v38, -v38, v43, v44
	v_fma_f32 v39, -v39, v43, v45
	v_fma_f32 v40, -v40, v43, v46
	v_fma_f32 v41, -v41, v43, v47
	v_fma_f32 v54, v42, v54, v48
	v_mul_f32_e32 v56, 0xbfb8aa3b, v56
	v_fma_f32 v57, v42, v57, v50
	v_fma_f32 v37, v42, v37, v51
	s_waitcnt lgkmcnt(0)
	v_fma_f32 v38, v52, v38, v48
	v_fma_f32 v39, v52, v39, v49
	v_fma_f32 v40, v52, v40, v50
	v_fmac_f32_e32 v51, v52, v41
	v_mul_f32_e32 v54, 0xbfb8aa3b, v54
	v_exp_f32_e32 v56, v56
	v_mul_f32_e32 v57, 0xbfb8aa3b, v57
	v_mul_f32_e32 v37, 0xbfb8aa3b, v37
	v_mul_f32_e32 v38, 0xbfb8aa3b, v38
	v_mul_f32_e32 v39, 0xbfb8aa3b, v39
	v_mul_f32_e32 v40, 0xbfb8aa3b, v40
	v_mul_f32_e32 v41, 0xbfb8aa3b, v51
	v_exp_f32_e32 v54, v54
	v_exp_f32_e32 v57, v57
	v_exp_f32_e32 v37, v37
	v_exp_f32_e32 v38, v38
	v_exp_f32_e32 v39, v39
	v_exp_f32_e32 v40, v40
	v_exp_f32_e32 v41, v41
	v_add_f32_e32 v56, 1.0, v56
	v_add_f32_e32 v54, 1.0, v54
	v_rcp_f32_e32 v42, v56
	v_add_f32_e32 v56, 1.0, v57
	v_add_f32_e32 v37, 1.0, v37
	v_add_f32_e32 v38, 1.0, v38
	v_add_f32_e32 v39, 1.0, v39
	v_add_f32_e32 v40, 1.0, v40
	v_add_f32_e32 v41, 1.0, v41
	v_rcp_f32_e32 v54, v54
	v_rcp_f32_e32 v56, v56
	v_rcp_f32_e32 v37, v37
	v_rcp_f32_e32 v38, v38
	v_rcp_f32_e32 v39, v39
	v_rcp_f32_e32 v40, v40
	v_rcp_f32_e32 v41, v41
	v_cvt_pk_bf16_f32 v91, v54, v42
	v_cvt_pk_bf16_f32 v86, v56, v37
	v_cvt_pk_bf16_f32 v85, v38, v39
	v_cvt_pk_bf16_f32 v84, v40, v41
	v_add_u32_e32 v37, 0x24980, v160
	v_add_u32_e32 v42, 0x24d80, v160
	ds_read_b128 v[38:41], v37
	ds_read_b128 v[42:45], v42
	ds_read_b32 v37, v164
	ds_read_b32 v46, v165
	ds_read_b32 v47, v166
	ds_read_b32 v48, v167
	s_waitcnt lgkmcnt(3)
	v_fma_f32 v16, -v38, v37, v16
	v_fma_f32 v17, -v39, v37, v17
	v_fma_f32 v18, -v40, v37, v18
	v_fma_f32 v19, -v41, v37, v19
	s_waitcnt lgkmcnt(1)
	v_fma_f32 v0, -v38, v47, v0
	v_fma_f32 v1, -v39, v47, v1
	v_fma_f32 v2, -v40, v47, v2
	v_fma_f32 v3, -v41, v47, v3
	v_fma_f32 v16, v46, v16, v42
	v_fma_f32 v17, v46, v17, v43
	v_fma_f32 v18, v46, v18, v44
	v_fma_f32 v19, v46, v19, v45
	s_waitcnt lgkmcnt(0)
; DI unsigned pack2(float a, float b) { f32x2_t v = {a, b}; bf16x2_t r = __builtin_convertvector(v, bf16x2_t); return __builtin_bit_cast(unsigned, r); }
; DI float sigmoidf_(float x) { return __builtin_amdgcn_rcpf(1.f + __expf(-x)); }
; template <bool LAST>
; DI void phase_gate(const Params& P, int layer, unsigned char* smem, int L, int G) {
;     ...
; #pragma unroll
;     for (int i = 0; i < 4; ++i)
; #pragma unroll
;       for (int q4 = 0; q4 < 4; ++q4) {
;         const int fl = wm * 128 + i * 32 + 8 * q4 + 4 * h;
;         const f32x4 c1v = *(const f32x4*)(vecL + fl), c2v = *(const f32x4*)(vecL + 256 + fl);
;         const float c1a[4] = {c1v.x, c1v.y, c1v.z, c1v.w}, c2a[4] = {c2v.x, c2v.y, c2v.z, c2v.w};
; #pragma unroll
;         for (int j = 0; j < 2; ++j) {
;           const int lrow = wn * 64 + j * 32 + r;
;           const float mu = rowA[lrow], rstd = rowB[lrow];
;           float sg4[4];
; #pragma unroll
;           for (int e = 0; e < 4; ++e) sg4[e] = sigmoidf_(rstd * (accu[i][j][4 * q4 + e] - mu * c1a[e]) + c2a[e]);
;           gq[i][j][2 * q4] = pack2(sg4[0], sg4[1]); gq[i][j][2 * q4 + 1] = pack2(sg4[2], sg4[3]);
;         }
;         __builtin_amdgcn_sched_barrier(0);
;       }
	v_fma_f32 v0, v48, v0, v42
	v_fma_f32 v1, v48, v1, v43
	v_fma_f32 v2, v48, v2, v44
	v_fmac_f32_e32 v45, v48, v3
	v_mul_f32_e32 v16, 0xbfb8aa3b, v16
	v_mul_f32_e32 v17, 0xbfb8aa3b, v17
	v_mul_f32_e32 v18, 0xbfb8aa3b, v18
	v_mul_f32_e32 v19, 0xbfb8aa3b, v19
	v_mul_f32_e32 v0, 0xbfb8aa3b, v0
	v_mul_f32_e32 v1, 0xbfb8aa3b, v1
	v_mul_f32_e32 v2, 0xbfb8aa3b, v2
	v_mul_f32_e32 v3, 0xbfb8aa3b, v45
	v_exp_f32_e32 v16, v16
	v_exp_f32_e32 v17, v17
	v_exp_f32_e32 v18, v18
	v_exp_f32_e32 v19, v19
	v_exp_f32_e32 v0, v0
	v_exp_f32_e32 v1, v1
	v_exp_f32_e32 v2, v2
	v_exp_f32_e32 v3, v3
	v_add_f32_e32 v16, 1.0, v16
	v_add_f32_e32 v17, 1.0, v17
	v_add_f32_e32 v18, 1.0, v18
	v_add_f32_e32 v19, 1.0, v19
	v_add_f32_e32 v0, 1.0, v0
	v_add_f32_e32 v1, 1.0, v1
	v_add_f32_e32 v2, 1.0, v2
	v_add_f32_e32 v3, 1.0, v3
	v_rcp_f32_e32 v16, v16
	v_rcp_f32_e32 v17, v17
	v_rcp_f32_e32 v18, v18
	v_rcp_f32_e32 v19, v19
	v_rcp_f32_e32 v0, v0
	v_rcp_f32_e32 v1, v1
	v_rcp_f32_e32 v2, v2
	v_rcp_f32_e32 v37, v3
	v_cvt_pk_bf16_f32 v17, v16, v17
	v_cvt_pk_bf16_f32 v16, v18, v19
	v_cvt_pk_bf16_f32 v3, v0, v1
	v_cvt_pk_bf16_f32 v2, v2, v37
	v_add_u32_e32 v0, 0x249a0, v160
	v_add_u32_e32 v1, 0x24da0, v160
	ds_read_b128 v[38:41], v0
	ds_read_b128 v[42:45], v1
	ds_read_b32 v0, v164
	ds_read_b32 v1, v165
	ds_read_b32 v18, v166
	ds_read_b32 v19, v167
	s_waitcnt lgkmcnt(3)
	v_fma_f32 v21, -v39, v0, v21
	v_fma_f32 v20, -v38, v0, v20
	s_waitcnt lgkmcnt(1)
	v_fma_f32 v6, -v40, v18, v6
	v_fma_f32 v21, v1, v21, v43
	v_fma_f32 v22, -v40, v0, v22
	v_fma_f32 v0, -v41, v0, v23
	v_fma_f32 v4, -v38, v18, v4
	v_fma_f32 v5, -v39, v18, v5
	s_waitcnt lgkmcnt(0)
	v_fma_f32 v6, v19, v6, v44
	v_fma_f32 v7, -v41, v18, v7
	v_fma_f32 v20, v1, v20, v42
	v_mul_f32_e32 v21, 0xbfb8aa3b, v21
	v_fma_f32 v22, v1, v22, v44
	v_fma_f32 v0, v1, v0, v45
	v_fma_f32 v4, v19, v4, v42
	v_fma_f32 v5, v19, v5, v43
	v_mul_f32_e32 v6, 0xbfb8aa3b, v6
	v_fmac_f32_e32 v45, v19, v7
	v_mul_f32_e32 v20, 0xbfb8aa3b, v20
	v_exp_f32_e32 v21, v21
	v_mul_f32_e32 v22, 0xbfb8aa3b, v22
	v_mul_f32_e32 v0, 0xbfb8aa3b, v0
	v_mul_f32_e32 v4, 0xbfb8aa3b, v4
	v_mul_f32_e32 v5, 0xbfb8aa3b, v5
	v_exp_f32_e32 v6, v6
	v_mul_f32_e32 v7, 0xbfb8aa3b, v45
	v_exp_f32_e32 v20, v20
	v_exp_f32_e32 v22, v22
	v_exp_f32_e32 v0, v0
	v_exp_f32_e32 v4, v4
	v_exp_f32_e32 v5, v5
	v_exp_f32_e32 v7, v7
	v_add_f32_e32 v21, 1.0, v21
	v_add_f32_e32 v6, 1.0, v6
	v_add_f32_e32 v20, 1.0, v20
	v_rcp_f32_e32 v1, v21
	v_add_f32_e32 v21, 1.0, v22
	v_add_f32_e32 v0, 1.0, v0
	v_add_f32_e32 v4, 1.0, v4
	v_add_f32_e32 v5, 1.0, v5
	v_rcp_f32_e32 v18, v6
	v_add_f32_e32 v6, 1.0, v7
	v_rcp_f32_e32 v20, v20
	v_rcp_f32_e32 v21, v21
	v_rcp_f32_e32 v0, v0
	v_rcp_f32_e32 v4, v4
	v_rcp_f32_e32 v5, v5
	v_rcp_f32_e32 v19, v6
	v_cvt_pk_bf16_f32 v7, v20, v1
	v_cvt_pk_bf16_f32 v6, v21, v0
	v_cvt_pk_bf16_f32 v5, v4, v5
	v_cvt_pk_bf16_f32 v4, v18, v19
	v_add_u32_e32 v0, 0x249c0, v160
	v_add_u32_e32 v1, 0x24dc0, v160
	ds_read_b128 v[18:21], v0
	ds_read_b128 v[38:41], v1
	ds_read_b32 v0, v164
	ds_read_b32 v1, v165
	ds_read_b32 v22, v166
	ds_read_b32 v23, v167
	s_waitcnt lgkmcnt(3)
	v_fma_f32 v25, -v19, v0, v25
	v_fma_f32 v24, -v18, v0, v24
	s_waitcnt lgkmcnt(1)
	v_fma_f32 v9, -v19, v22, v9
	s_waitcnt lgkmcnt(0)
	v_fma_f32 v9, v23, v9, v39
	v_fma_f32 v10, -v20, v22, v10
	v_fma_f32 v25, v1, v25, v39
	v_fma_f32 v26, -v20, v0, v26
	v_fma_f32 v0, -v21, v0, v27
	v_fma_f32 v8, -v18, v22, v8
	v_mul_f32_e32 v9, 0xbfb8aa3b, v9
	v_fma_f32 v10, v23, v10, v40
	v_fma_f32 v11, -v21, v22, v11
	v_fma_f32 v24, v1, v24, v38
	v_mul_f32_e32 v25, 0xbfb8aa3b, v25
	v_fma_f32 v26, v1, v26, v40
	v_fma_f32 v0, v1, v0, v41
	v_fma_f32 v8, v23, v8, v38
	v_exp_f32_e32 v9, v9
	v_mul_f32_e32 v10, 0xbfb8aa3b, v10
	v_fmac_f32_e32 v41, v23, v11
	v_mul_f32_e32 v24, 0xbfb8aa3b, v24
	v_exp_f32_e32 v25, v25
	v_mul_f32_e32 v26, 0xbfb8aa3b, v26
	v_mul_f32_e32 v0, 0xbfb8aa3b, v0
	v_mul_f32_e32 v8, 0xbfb8aa3b, v8
	v_exp_f32_e32 v10, v10
	v_mul_f32_e32 v11, 0xbfb8aa3b, v41
	v_exp_f32_e32 v24, v24
	v_exp_f32_e32 v26, v26
	v_exp_f32_e32 v0, v0
	v_exp_f32_e32 v8, v8
	v_exp_f32_e32 v11, v11
	v_add_f32_e32 v9, 1.0, v9
	v_add_f32_e32 v25, 1.0, v25
	v_rcp_f32_e32 v18, v9
	v_add_f32_e32 v9, 1.0, v10
	v_add_f32_e32 v24, 1.0, v24
	v_rcp_f32_e32 v1, v25
	v_add_f32_e32 v25, 1.0, v26
	v_add_f32_e32 v0, 1.0, v0
	v_add_f32_e32 v8, 1.0, v8
	v_rcp_f32_e32 v10, v9
	v_add_f32_e32 v9, 1.0, v11
	v_rcp_f32_e32 v24, v24
	v_rcp_f32_e32 v25, v25
	v_rcp_f32_e32 v0, v0
	v_rcp_f32_e32 v8, v8
	v_rcp_f32_e32 v11, v9
	v_cvt_pk_bf16_f32 v27, v24, v1
	v_cvt_pk_bf16_f32 v9, v25, v0
	v_cvt_pk_bf16_f32 v19, v8, v18
	v_cvt_pk_bf16_f32 v8, v10, v11
	v_add_u32_e32 v0, 0x24de0, v160
	ds_read_b128 v[20:23], v163 offset:480
	ds_read_b32 v1, v164
	ds_read_b128 v[38:41], v0
	ds_read_b32 v0, v165
	ds_read_b32 v10, v166
	ds_read_b32 v18, v167
	s_waitcnt lgkmcnt(4)
	v_fma_f32 v24, -v21, v1, v29
	v_fma_f32 v11, -v20, v1, v28
	s_waitcnt lgkmcnt(2)
	v_fma_f32 v24, v0, v24, v39
	v_fma_f32 v25, -v22, v1, v30
	v_fma_f32 v1, -v23, v1, v31
	s_waitcnt lgkmcnt(1)
	v_fma_f32 v12, -v20, v10, v12
	v_fma_f32 v13, -v21, v10, v13
	v_fma_f32 v14, -v22, v10, v14
	v_fma_f32 v10, -v23, v10, v15
	v_fma_f32 v11, v0, v11, v38
	v_mul_f32_e32 v24, 0xbfb8aa3b, v24
	v_fma_f32 v25, v0, v25, v40
	v_fma_f32 v0, v0, v1, v41
	s_waitcnt lgkmcnt(0)
; DI unsigned pack2(float a, float b) { f32x2_t v = {a, b}; bf16x2_t r = __builtin_convertvector(v, bf16x2_t); return __builtin_bit_cast(unsigned, r); }
; DI float sigmoidf_(float x) { return __builtin_amdgcn_rcpf(1.f + __expf(-x)); }
; DI int otid() { int t = threadIdx.x; asm volatile("" : "+v"(t)); return t; }
; template <bool NT>
; DI void stage_load_tile(bf16_t* stg, const bf16_t* tilebase) {
;   const int tid = otid();
;   const int r0 = tid >> 5, c = tid & 31;
;   const unsigned o0 = (unsigned)(r0 * 1024 + c * 8);
;   __builtin_amdgcn_sched_barrier(0);
; #pragma unroll
;   for (int hf = 0; hf < 2; ++hf) {
; #pragma unroll
;     for (int it = 8 * hf; it < 8 * hf + 8; ++it) {
;       const u32x4* gp = (const u32x4*)(tilebase + (o0 + (unsigned)(it * 16 * 1024)));
;       stage_write16(stg, r0 + 16 * it, c, NT ? __builtin_nontemporal_load(gp) : *gp);
;     }
;     __builtin_amdgcn_sched_barrier(0);
;   }
; }
; template <bool LAST>
; DI void phase_gate(const Params& P, int layer, unsigned char* smem, int L, int G) {
;     ...
; #pragma unroll
;     for (int i = 0; i < 4; ++i)
; #pragma unroll
;       for (int q4 = 0; q4 < 4; ++q4) {
;         const int fl = wm * 128 + i * 32 + 8 * q4 + 4 * h;
;         const f32x4 c1v = *(const f32x4*)(vecL + fl), c2v = *(const f32x4*)(vecL + 256 + fl);
;         const float c1a[4] = {c1v.x, c1v.y, c1v.z, c1v.w}, c2a[4] = {c2v.x, c2v.y, c2v.z, c2v.w};
; #pragma unroll
;         for (int j = 0; j < 2; ++j) {
;           const int lrow = wn * 64 + j * 32 + r;
;           const float mu = rowA[lrow], rstd = rowB[lrow];
;           float sg4[4];
; #pragma unroll
;           for (int e = 0; e < 4; ++e) sg4[e] = sigmoidf_(rstd * (accu[i][j][4 * q4 + e] - mu * c1a[e]) + c2a[e]);
;           gq[i][j][2 * q4] = pack2(sg4[0], sg4[1]); gq[i][j][2 * q4 + 1] = pack2(sg4[2], sg4[3]);
;         }
;         __builtin_amdgcn_sched_barrier(0);
;       }
;     stage_load_tile<true>(stg, PPb + (size_t)mt * 256 * 1024 + nt * 256);
	v_fma_f32 v12, v18, v12, v38
	v_fma_f32 v13, v18, v13, v39
	v_fma_f32 v14, v18, v14, v40
	v_fmac_f32_e32 v41, v18, v10
	v_mul_f32_e32 v11, 0xbfb8aa3b, v11
	v_exp_f32_e32 v24, v24
	v_mul_f32_e32 v25, 0xbfb8aa3b, v25
	v_mul_f32_e32 v0, 0xbfb8aa3b, v0
	v_mul_f32_e32 v12, 0xbfb8aa3b, v12
	v_mul_f32_e32 v13, 0xbfb8aa3b, v13
	v_mul_f32_e32 v14, 0xbfb8aa3b, v14
	v_mul_f32_e32 v10, 0xbfb8aa3b, v41
	v_exp_f32_e32 v11, v11
	v_exp_f32_e32 v25, v25
	v_exp_f32_e32 v0, v0
	v_exp_f32_e32 v12, v12
	v_exp_f32_e32 v13, v13
	v_exp_f32_e32 v14, v14
	v_exp_f32_e32 v10, v10
	v_add_f32_e32 v24, 1.0, v24
	v_add_f32_e32 v11, 1.0, v11
	v_rcp_f32_e32 v1, v24
	v_add_f32_e32 v24, 1.0, v25
	v_add_f32_e32 v0, 1.0, v0
	v_add_f32_e32 v12, 1.0, v12
	v_add_f32_e32 v13, 1.0, v13
	v_add_f32_e32 v14, 1.0, v14
	v_add_f32_e32 v10, 1.0, v10
	v_rcp_f32_e32 v11, v11
	v_rcp_f32_e32 v24, v24
	v_rcp_f32_e32 v0, v0
	v_rcp_f32_e32 v12, v12
	v_rcp_f32_e32 v13, v13
	v_rcp_f32_e32 v14, v14
	v_rcp_f32_e32 v10, v10
	v_cvt_pk_bf16_f32 v112, v11, v1
	v_cvt_pk_bf16_f32 v30, v24, v0
	v_cvt_pk_bf16_f32 v29, v12, v13
	v_cvt_pk_bf16_f32 v28, v14, v10
	s_ashr_i32 s25, s24, 31
	s_lshl_b64 s[24:25], s[24:25], 19
	v_mov_b32_e32 v10, v192
	s_add_u32 s30, s66, s24
	v_mov_b32_e32 v163, v161
	s_addc_u32 s31, s67, s25
	v_and_b32_e32 v26, 31, v10
	v_lshlrev_b64 v[0:1], 1, v[162:163]
	v_ashrrev_i32_e32 v18, 5, v10
	v_lshlrev_b32_e32 v10, 3, v26
	v_lshl_add_u64 v[14:15], s[30:31], 0, v[0:1]
	v_lshl_or_b32 v160, v18, 10, v10
	v_add_u32_e32 v12, 0x4000, v160
	v_mov_b32_e32 v13, v161
	v_add_u32_e32 v24, 0x8000, v160
	v_mov_b32_e32 v25, v161
	v_add_u32_e32 v38, 0xc000, v160
	v_mov_b32_e32 v39, v161
	v_lshl_add_u64 v[10:11], v[160:161], 1, v[14:15]
	v_lshl_add_u64 v[20:21], v[12:13], 1, v[14:15]
	v_lshl_add_u64 v[24:25], v[24:25], 1, v[14:15]
	v_lshl_add_u64 v[42:43], v[38:39], 1, v[14:15]
	global_load_dwordx4 v[10:13], v[10:11], off nt
	s_nop 0
	global_load_dwordx4 v[20:23], v[20:21], off nt
	s_nop 0
	global_load_dwordx4 v[38:41], v[24:25], off nt
	s_nop 0
	global_load_dwordx4 v[42:45], v[42:43], off nt
	v_add_u32_e32 v24, 0x10000, v160
	v_mov_b32_e32 v25, v161
	v_lshl_add_u64 v[24:25], v[24:25], 1, v[14:15]
	v_add_u32_e32 v46, 0x14000, v160
	v_mov_b32_e32 v47, v161
	v_lshl_add_u64 v[50:51], v[46:47], 1, v[14:15]
	global_load_dwordx4 v[46:49], v[24:25], off nt
	global_load_dwordx4 v[60:63], v[50:51], off nt
	v_add_u32_e32 v24, 0x18000, v160
	v_mov_b32_e32 v25, v161
	v_lshl_add_u64 v[24:25], v[24:25], 1, v[14:15]
	v_add_u32_e32 v50, 0x1c000, v160
	v_mov_b32_e32 v51, v161
	v_lshl_add_u64 v[50:51], v[50:51], 1, v[14:15]
	global_load_dwordx4 v[92:95], v[24:25], off nt
	global_load_dwordx4 v[114:117], v[50:51], off nt
	v_add_u32_e32 v218, 0x20000, v160
	v_mov_b32_e32 v219, v161
	v_add_u32_e32 v220, 0x24000, v160
	v_mov_b32_e32 v221, v161
	v_add_u32_e32 v252, 0x28000, v160
	v_mov_b32_e32 v253, v161
	v_add_u32_e32 v226, 0x2c000, v160
	v_mov_b32_e32 v227, v161
	v_lshl_add_u64 v[218:219], v[218:219], 1, v[14:15]
	v_lshl_add_u64 v[222:223], v[220:221], 1, v[14:15]
	v_lshl_add_u64 v[252:253], v[252:253], 1, v[14:15]
	v_lshl_add_u64 v[230:231], v[226:227], 1, v[14:15]
	global_load_dwordx4 v[218:221], v[218:219], off nt
	s_nop 0
	global_load_dwordx4 v[222:225], v[222:223], off nt
	s_nop 0
	global_load_dwordx4 v[226:229], v[252:253], off nt
	s_nop 0
	global_load_dwordx4 v[230:233], v[230:231], off nt
	v_add_u32_e32 v252, 0x30000, v160
	v_mov_b32_e32 v253, v161
	v_lshl_add_u64 v[252:253], v[252:253], 1, v[14:15]
	v_add_u32_e32 v234, 0x34000, v160
	v_mov_b32_e32 v235, v161
	v_lshl_add_u64 v[254:255], v[234:235], 1, v[14:15]
	global_load_dwordx4 v[234:237], v[252:253], off nt
	global_load_dwordx4 v[238:241], v[254:255], off nt
	v_add_u32_e32 v252, 0x38000, v160
	v_mov_b32_e32 v253, v161
	v_lshl_add_u64 v[252:253], v[252:253], 1, v[14:15]
	v_add_u32_e32 v160, 0x3c000, v160
	v_lshl_add_u64 v[190:191], v[160:161], 1, v[14:15]
	global_load_dwordx4 v[242:245], v[252:253], off nt
	global_load_dwordx4 v[248:251], v[190:191], off nt
	v_mul_lo_u32 v18, v18, s44
	v_lshl_add_u32 v18, v26, 4, v18
	v_add_u32_e32 v24, 0x2080, v18
	v_add_u32_e32 v25, 0x4100, v18
	v_add_u32_e32 v26, 0x6180, v18
	v_add_u32_e32 v31, 0x8200, v18
	v_add_u32_e32 v37, 0xa280, v18
	v_add_u32_e32 v50, 0xc300, v18
	v_add_u32_e32 v51, 0xe380, v18
	s_waitcnt vmcnt(15)
	ds_write2_b64 v18, v[10:11], v[12:13] offset1:1
	s_waitcnt vmcnt(14)
	ds_write2_b64 v24, v[20:21], v[22:23] offset1:1
	s_waitcnt vmcnt(13)
	ds_write2_b64 v25, v[38:39], v[40:41] offset1:1
	s_waitcnt vmcnt(12)
	ds_write2_b64 v26, v[42:43], v[44:45] offset1:1
	s_waitcnt vmcnt(11)
	ds_write2_b64 v31, v[46:47], v[48:49] offset1:1
	s_waitcnt vmcnt(10)
	ds_write2_b64 v37, v[60:61], v[62:63] offset1:1
	s_waitcnt vmcnt(9)
	ds_write2_b64 v50, v[92:93], v[94:95] offset1:1
	s_waitcnt vmcnt(8)
	ds_write2_b64 v51, v[114:115], v[116:117] offset1:1
	v_add_u32_e32 v14, 0x10400, v18
	v_add_u32_e32 v15, 0x12480, v18
	v_add_u32_e32 v24, 0x14500, v18
	v_add_u32_e32 v25, 0x16580, v18
	v_add_u32_e32 v26, 0x18600, v18
	v_add_u32_e32 v31, 0x1a680, v18
	v_add_u32_e32 v37, 0x1c700, v18
	v_add_u32_e32 v18, 0x1e780, v18
	s_waitcnt vmcnt(7)
	ds_write2_b64 v14, v[218:219], v[220:221] offset1:1
	s_waitcnt vmcnt(6)
	ds_write2_b64 v15, v[222:223], v[224:225] offset1:1
	s_waitcnt vmcnt(5)
	ds_write2_b64 v24, v[226:227], v[228:229] offset1:1
	s_waitcnt vmcnt(4)
	ds_write2_b64 v25, v[230:231], v[232:233] offset1:1
	s_waitcnt vmcnt(3)
	ds_write2_b64 v26, v[234:235], v[236:237] offset1:1
	s_waitcnt vmcnt(2)
	ds_write2_b64 v31, v[238:239], v[240:241] offset1:1
	s_waitcnt vmcnt(1)
	ds_write2_b64 v37, v[242:243], v[244:245] offset1:1
	s_waitcnt vmcnt(0)
	ds_write2_b64 v18, v[248:249], v[250:251] offset1:1
	v_mov_b32_e32 v10, v192
	s_waitcnt lgkmcnt(0)
	s_barrier
; DI unsigned pack2(float a, float b) { f32x2_t v = {a, b}; bf16x2_t r = __builtin_convertvector(v, bf16x2_t); return __builtin_bit_cast(unsigned, r); }
; DI float bflo(unsigned u) { return __uint_as_float(u << 16); }
; DI float bfhi(unsigned u) { return __uint_as_float(u & 0xffff0000u); }
; DI int otid() { int t = threadIdx.x; asm volatile("" : "+v"(t)); return t; }
; template <bool LAST>
; DI void phase_gate(const Params& P, int layer, unsigned char* smem, int L, int G) {
;     ...
;     {
;       const int tid1 = otid();
;       const int lane1 = tid1 & 63, w1 = tid1 >> 6, r1 = lane1 & 31, h1 = lane1 >> 5, wm1 = w1 >> 2, wn1 = w1 & 3;
; #pragma unroll
;       for (int i = 0; i < 4; ++i)
; #pragma unroll
;         for (int q4 = 0; q4 < 4; ++q4) {
; #pragma unroll
;           for (int j = 0; j < 2; ++j) {
;             const uint2 pv = *(const uint2*)(stg + (wn1 * 64 + j * 32 + r1) * STG + wm1 * 128 + i * 32 + 8 * q4 + 4 * h1);
;             const unsigned g0 = gq[i][j][2 * q4], g1 = gq[i][j][2 * q4 + 1];
;             gq[i][j][2 * q4] = pack2(bflo(g0) * bflo(pv.x), bfhi(g0) * bfhi(pv.x));
;             gq[i][j][2 * q4 + 1] = pack2(bflo(g1) * bflo(pv.y), bfhi(g1) * bfhi(pv.y));
;           }
;           __builtin_amdgcn_sched_barrier(0);
;         }
;     }
	v_and_b32_e32 v13, 0xffff0000, v99
	v_lshrrev_b32_e32 v12, 2, v10
	v_and_b32_e32 v12, 8, v12
	v_and_b32_e32 v11, 0xdf, v10
	v_and_or_b32 v10, v10, s42, v12
	v_mad_u32_u24 v113, v11, s44, v10
	ds_read_b64 v[10:11], v113
	ds_read_b64 v[14:15], v113 offset:16640
	v_lshlrev_b32_e32 v12, 16, v99
	s_waitcnt lgkmcnt(1)
	v_lshlrev_b32_e32 v20, 16, v10
	v_and_b32_e32 v21, 0xffff0000, v10
	v_pk_mul_f32 v[12:13], v[12:13], v[20:21]
	v_lshlrev_b32_e32 v10, 16, v11
	v_cvt_pk_bf16_f32 v31, v12, v13
	v_lshlrev_b32_e32 v12, 16, v98
	v_and_b32_e32 v13, 0xffff0000, v98
	v_and_b32_e32 v11, 0xffff0000, v11
	v_pk_mul_f32 v[10:11], v[12:13], v[10:11]
	s_waitcnt lgkmcnt(0)
	v_lshlrev_b32_e32 v12, 16, v14
	v_cvt_pk_bf16_f32 v98, v10, v11
	v_lshlrev_b32_e32 v10, 16, v97
	v_and_b32_e32 v11, 0xffff0000, v97
	v_and_b32_e32 v13, 0xffff0000, v14
	v_pk_mul_f32 v[10:11], v[10:11], v[12:13]
	v_lshlrev_b32_e32 v12, 16, v15
	v_cvt_pk_bf16_f32 v97, v10, v11
	v_lshlrev_b32_e32 v10, 16, v96
	v_and_b32_e32 v11, 0xffff0000, v96
	v_and_b32_e32 v13, 0xffff0000, v15
	v_pk_mul_f32 v[10:11], v[10:11], v[12:13]
	s_nop 0
	v_cvt_pk_bf16_f32 v96, v10, v11
	ds_read_b64 v[10:11], v113 offset:16
	ds_read_b64 v[14:15], v113 offset:16656
	v_lshlrev_b32_e32 v12, 16, v103
	v_and_b32_e32 v13, 0xffff0000, v103
	s_waitcnt lgkmcnt(1)
	v_lshlrev_b32_e32 v20, 16, v10
	v_and_b32_e32 v21, 0xffff0000, v10
	v_pk_mul_f32 v[12:13], v[12:13], v[20:21]
	v_lshlrev_b32_e32 v10, 16, v11
	v_cvt_pk_bf16_f32 v93, v12, v13
	v_lshlrev_b32_e32 v12, 16, v102
	v_and_b32_e32 v13, 0xffff0000, v102
	v_and_b32_e32 v11, 0xffff0000, v11
	v_pk_mul_f32 v[10:11], v[12:13], v[10:11]
	s_waitcnt lgkmcnt(0)
	v_lshlrev_b32_e32 v12, 16, v14
	v_cvt_pk_bf16_f32 v95, v10, v11
	v_lshlrev_b32_e32 v10, 16, v101
	v_and_b32_e32 v11, 0xffff0000, v101
	v_and_b32_e32 v13, 0xffff0000, v14
	v_pk_mul_f32 v[10:11], v[10:11], v[12:13]
	v_lshlrev_b32_e32 v12, 16, v15
	v_cvt_pk_bf16_f32 v92, v10, v11
	v_lshlrev_b32_e32 v10, 16, v100
	v_and_b32_e32 v11, 0xffff0000, v100
	v_and_b32_e32 v13, 0xffff0000, v15
	v_pk_mul_f32 v[10:11], v[10:11], v[12:13]
	s_nop 0
	v_cvt_pk_bf16_f32 v94, v10, v11
	ds_read_b64 v[10:11], v113 offset:32
	ds_read_b64 v[14:15], v113 offset:16672
	v_lshlrev_b32_e32 v12, 16, v107
	v_and_b32_e32 v13, 0xffff0000, v107
	s_waitcnt lgkmcnt(1)
	v_lshlrev_b32_e32 v20, 16, v10
	v_and_b32_e32 v21, 0xffff0000, v10
	v_pk_mul_f32 v[12:13], v[12:13], v[20:21]
	v_lshlrev_b32_e32 v10, 16, v11
	v_cvt_pk_bf16_f32 v88, v12, v13
	v_lshlrev_b32_e32 v12, 16, v106
	v_and_b32_e32 v13, 0xffff0000, v106
	v_and_b32_e32 v11, 0xffff0000, v11
	v_pk_mul_f32 v[10:11], v[12:13], v[10:11]
	s_waitcnt lgkmcnt(0)
	v_lshlrev_b32_e32 v12, 16, v14
	v_cvt_pk_bf16_f32 v90, v10, v11
	v_lshlrev_b32_e32 v10, 16, v105
	v_and_b32_e32 v11, 0xffff0000, v105
	v_and_b32_e32 v13, 0xffff0000, v14
	v_pk_mul_f32 v[10:11], v[10:11], v[12:13]
	v_lshlrev_b32_e32 v12, 16, v15
	v_cvt_pk_bf16_f32 v87, v10, v11
	v_lshlrev_b32_e32 v10, 16, v104
	v_and_b32_e32 v11, 0xffff0000, v104
	v_and_b32_e32 v13, 0xffff0000, v15
	v_pk_mul_f32 v[10:11], v[10:11], v[12:13]
	s_nop 0
	v_cvt_pk_bf16_f32 v89, v10, v11
	ds_read_b64 v[10:11], v113 offset:48
	ds_read_b64 v[14:15], v113 offset:16688
	v_lshlrev_b32_e32 v12, 16, v111
	v_and_b32_e32 v13, 0xffff0000, v111
	s_waitcnt lgkmcnt(1)
	v_lshlrev_b32_e32 v20, 16, v10
	v_and_b32_e32 v21, 0xffff0000, v10
	v_pk_mul_f32 v[12:13], v[12:13], v[20:21]
	v_lshlrev_b32_e32 v10, 16, v11
	v_cvt_pk_bf16_f32 v61, v12, v13
	v_lshlrev_b32_e32 v12, 16, v110
	v_and_b32_e32 v13, 0xffff0000, v110
	v_and_b32_e32 v11, 0xffff0000, v11
	v_pk_mul_f32 v[10:11], v[12:13], v[10:11]
	s_waitcnt lgkmcnt(0)
	v_lshlrev_b32_e32 v12, 16, v14
	v_cvt_pk_bf16_f32 v63, v10, v11
	v_lshlrev_b32_e32 v10, 16, v109
	v_and_b32_e32 v11, 0xffff0000, v109
	v_and_b32_e32 v13, 0xffff0000, v14
	v_pk_mul_f32 v[10:11], v[10:11], v[12:13]
	v_lshlrev_b32_e32 v12, 16, v15
	v_cvt_pk_bf16_f32 v60, v10, v11
	v_lshlrev_b32_e32 v10, 16, v108
	v_and_b32_e32 v11, 0xffff0000, v108
	v_and_b32_e32 v13, 0xffff0000, v15
	v_pk_mul_f32 v[10:11], v[10:11], v[12:13]
	s_nop 0
	v_cvt_pk_bf16_f32 v62, v10, v11
	ds_read_b64 v[10:11], v113 offset:64
	ds_read_b64 v[14:15], v113 offset:16704
	v_lshlrev_b32_e32 v12, 16, v67
	v_and_b32_e32 v13, 0xffff0000, v67
	s_waitcnt lgkmcnt(1)
	v_lshlrev_b32_e32 v20, 16, v10
	v_and_b32_e32 v21, 0xffff0000, v10
	v_pk_mul_f32 v[12:13], v[12:13], v[20:21]
	v_lshlrev_b32_e32 v10, 16, v11
	v_cvt_pk_bf16_f32 v56, v12, v13
	v_lshlrev_b32_e32 v12, 16, v66
	v_and_b32_e32 v13, 0xffff0000, v66
	v_and_b32_e32 v11, 0xffff0000, v11
	v_pk_mul_f32 v[10:11], v[12:13], v[10:11]
	s_waitcnt lgkmcnt(0)
	v_lshlrev_b32_e32 v12, 16, v14
	v_cvt_pk_bf16_f32 v58, v10, v11
	v_lshlrev_b32_e32 v10, 16, v65
	v_and_b32_e32 v11, 0xffff0000, v65
	v_and_b32_e32 v13, 0xffff0000, v14
	v_pk_mul_f32 v[10:11], v[10:11], v[12:13]
	v_lshlrev_b32_e32 v12, 16, v15
	v_cvt_pk_bf16_f32 v54, v10, v11
	v_lshlrev_b32_e32 v10, 16, v64
	v_and_b32_e32 v11, 0xffff0000, v64
	v_and_b32_e32 v13, 0xffff0000, v15
	v_pk_mul_f32 v[10:11], v[10:11], v[12:13]
	s_nop 0
	v_cvt_pk_bf16_f32 v57, v10, v11
	ds_read_b64 v[10:11], v113 offset:80
	ds_read_b64 v[14:15], v113 offset:16720
	v_lshlrev_b32_e32 v12, 16, v71
	v_and_b32_e32 v13, 0xffff0000, v71
	s_waitcnt lgkmcnt(1)
	v_lshlrev_b32_e32 v20, 16, v10
	v_and_b32_e32 v21, 0xffff0000, v10
	v_pk_mul_f32 v[12:13], v[12:13], v[20:21]
	v_lshlrev_b32_e32 v10, 16, v11
	v_cvt_pk_bf16_f32 v50, v12, v13
	v_lshlrev_b32_e32 v12, 16, v70
	v_and_b32_e32 v13, 0xffff0000, v70
	v_and_b32_e32 v11, 0xffff0000, v11
	v_pk_mul_f32 v[10:11], v[12:13], v[10:11]
	s_waitcnt lgkmcnt(0)
; DI unsigned pack2(float a, float b) { f32x2_t v = {a, b}; bf16x2_t r = __builtin_convertvector(v, bf16x2_t); return __builtin_bit_cast(unsigned, r); }
; DI float bflo(unsigned u) { return __uint_as_float(u << 16); }
; DI float bfhi(unsigned u) { return __uint_as_float(u & 0xffff0000u); }
; DI int otid() { int t = threadIdx.x; asm volatile("" : "+v"(t)); return t; }
; template <bool LAST>
; DI void phase_gate(const Params& P, int layer, unsigned char* smem, int L, int G) {
;     ...
;     {
;       const int tid1 = otid();
;       const int lane1 = tid1 & 63, w1 = tid1 >> 6, r1 = lane1 & 31, h1 = lane1 >> 5, wm1 = w1 >> 2, wn1 = w1 & 3;
; #pragma unroll
;       for (int i = 0; i < 4; ++i)
; #pragma unroll
;         for (int q4 = 0; q4 < 4; ++q4) {
; #pragma unroll
;           for (int j = 0; j < 2; ++j) {
;             const uint2 pv = *(const uint2*)(stg + (wn1 * 64 + j * 32 + r1) * STG + wm1 * 128 + i * 32 + 8 * q4 + 4 * h1);
;             const unsigned g0 = gq[i][j][2 * q4], g1 = gq[i][j][2 * q4 + 1];
;             gq[i][j][2 * q4] = pack2(bflo(g0) * bflo(pv.x), bfhi(g0) * bfhi(pv.x));
;             gq[i][j][2 * q4 + 1] = pack2(bflo(g1) * bflo(pv.y), bfhi(g1) * bfhi(pv.y));
;           }
;           __builtin_amdgcn_sched_barrier(0);
;         }
;     }
	v_lshlrev_b32_e32 v12, 16, v14
	v_cvt_pk_bf16_f32 v52, v10, v11
	v_lshlrev_b32_e32 v10, 16, v69
	v_and_b32_e32 v11, 0xffff0000, v69
	v_and_b32_e32 v13, 0xffff0000, v14
	v_pk_mul_f32 v[10:11], v[10:11], v[12:13]
	v_lshlrev_b32_e32 v12, 16, v15
	v_cvt_pk_bf16_f32 v49, v10, v11
	v_lshlrev_b32_e32 v10, 16, v68
	v_and_b32_e32 v11, 0xffff0000, v68
	v_and_b32_e32 v13, 0xffff0000, v15
	v_pk_mul_f32 v[10:11], v[10:11], v[12:13]
	s_nop 0
	v_cvt_pk_bf16_f32 v51, v10, v11
	ds_read_b64 v[10:11], v113 offset:96
	ds_read_b64 v[14:15], v113 offset:16736
	v_lshlrev_b32_e32 v12, 16, v75
	v_and_b32_e32 v13, 0xffff0000, v75
	s_waitcnt lgkmcnt(1)
	v_lshlrev_b32_e32 v20, 16, v10
	v_and_b32_e32 v21, 0xffff0000, v10
	v_pk_mul_f32 v[12:13], v[12:13], v[20:21]
	v_lshlrev_b32_e32 v10, 16, v11
	v_cvt_pk_bf16_f32 v46, v12, v13
	v_lshlrev_b32_e32 v12, 16, v74
	v_and_b32_e32 v13, 0xffff0000, v74
	v_and_b32_e32 v11, 0xffff0000, v11
	v_pk_mul_f32 v[10:11], v[12:13], v[10:11]
	s_waitcnt lgkmcnt(0)
	v_lshlrev_b32_e32 v12, 16, v14
	v_cvt_pk_bf16_f32 v48, v10, v11
	v_lshlrev_b32_e32 v10, 16, v73
	v_and_b32_e32 v11, 0xffff0000, v73
	v_and_b32_e32 v13, 0xffff0000, v14
	v_pk_mul_f32 v[10:11], v[10:11], v[12:13]
	v_lshlrev_b32_e32 v12, 16, v15
	v_cvt_pk_bf16_f32 v45, v10, v11
	v_lshlrev_b32_e32 v10, 16, v72
	v_and_b32_e32 v11, 0xffff0000, v72
	v_and_b32_e32 v13, 0xffff0000, v15
	v_pk_mul_f32 v[10:11], v[10:11], v[12:13]
	s_nop 0
	v_cvt_pk_bf16_f32 v47, v10, v11
	ds_read_b64 v[10:11], v113 offset:112
	ds_read_b64 v[14:15], v113 offset:16752
	v_lshlrev_b32_e32 v12, 16, v79
	v_and_b32_e32 v13, 0xffff0000, v79
	s_waitcnt lgkmcnt(1)
	v_lshlrev_b32_e32 v20, 16, v10
	v_and_b32_e32 v21, 0xffff0000, v10
	v_pk_mul_f32 v[12:13], v[12:13], v[20:21]
	v_lshlrev_b32_e32 v10, 16, v11
	v_cvt_pk_bf16_f32 v42, v12, v13
	v_lshlrev_b32_e32 v12, 16, v78
	v_and_b32_e32 v13, 0xffff0000, v78
	v_and_b32_e32 v11, 0xffff0000, v11
	v_pk_mul_f32 v[10:11], v[12:13], v[10:11]
	s_waitcnt lgkmcnt(0)
	v_lshlrev_b32_e32 v12, 16, v14
	v_cvt_pk_bf16_f32 v44, v10, v11
	v_lshlrev_b32_e32 v10, 16, v77
	v_and_b32_e32 v11, 0xffff0000, v77
	v_and_b32_e32 v13, 0xffff0000, v14
	v_pk_mul_f32 v[10:11], v[10:11], v[12:13]
	v_lshlrev_b32_e32 v12, 16, v15
	v_cvt_pk_bf16_f32 v41, v10, v11
	v_lshlrev_b32_e32 v10, 16, v76
	v_and_b32_e32 v11, 0xffff0000, v76
	v_and_b32_e32 v13, 0xffff0000, v15
	v_pk_mul_f32 v[10:11], v[10:11], v[12:13]
	s_nop 0
	v_cvt_pk_bf16_f32 v43, v10, v11
	ds_read_b64 v[10:11], v113 offset:128
	ds_read_b64 v[14:15], v113 offset:16768
	v_lshlrev_b32_e32 v12, 16, v35
	v_and_b32_e32 v13, 0xffff0000, v35
	s_waitcnt lgkmcnt(1)
	v_lshlrev_b32_e32 v20, 16, v10
	v_and_b32_e32 v21, 0xffff0000, v10
	v_pk_mul_f32 v[12:13], v[12:13], v[20:21]
	v_lshlrev_b32_e32 v10, 16, v11
	v_cvt_pk_bf16_f32 v38, v12, v13
	v_lshlrev_b32_e32 v12, 16, v34
	v_and_b32_e32 v13, 0xffff0000, v34
	v_and_b32_e32 v11, 0xffff0000, v11
	v_pk_mul_f32 v[10:11], v[12:13], v[10:11]
	s_waitcnt lgkmcnt(0)
	v_lshlrev_b32_e32 v12, 16, v14
	v_cvt_pk_bf16_f32 v40, v10, v11
	v_lshlrev_b32_e32 v10, 16, v33
	v_and_b32_e32 v11, 0xffff0000, v33
	v_and_b32_e32 v13, 0xffff0000, v14
	v_pk_mul_f32 v[10:11], v[10:11], v[12:13]
	v_lshlrev_b32_e32 v12, 16, v15
	v_cvt_pk_bf16_f32 v37, v10, v11
	v_lshlrev_b32_e32 v10, 16, v32
	v_and_b32_e32 v11, 0xffff0000, v32
	v_and_b32_e32 v13, 0xffff0000, v15
	v_pk_mul_f32 v[10:11], v[10:11], v[12:13]
	s_nop 0
	v_cvt_pk_bf16_f32 v39, v10, v11
	ds_read_b64 v[10:11], v113 offset:144
	ds_read_b64 v[14:15], v113 offset:16784
	v_lshlrev_b32_e32 v12, 16, v80
	v_and_b32_e32 v13, 0xffff0000, v80
	s_waitcnt lgkmcnt(1)
	v_lshlrev_b32_e32 v20, 16, v10
	v_and_b32_e32 v21, 0xffff0000, v10
	v_pk_mul_f32 v[12:13], v[12:13], v[20:21]
	v_lshlrev_b32_e32 v10, 16, v11
	v_cvt_pk_bf16_f32 v34, v12, v13
	v_lshlrev_b32_e32 v12, 16, v36
	v_and_b32_e32 v13, 0xffff0000, v36
	v_and_b32_e32 v11, 0xffff0000, v11
	v_pk_mul_f32 v[10:11], v[12:13], v[10:11]
	s_waitcnt lgkmcnt(0)
	v_lshlrev_b32_e32 v12, 16, v14
	v_cvt_pk_bf16_f32 v36, v10, v11
	v_lshlrev_b32_e32 v10, 16, v55
	v_and_b32_e32 v11, 0xffff0000, v55
	v_and_b32_e32 v13, 0xffff0000, v14
	v_pk_mul_f32 v[10:11], v[10:11], v[12:13]
	v_lshlrev_b32_e32 v12, 16, v15
	v_cvt_pk_bf16_f32 v32, v10, v11
	v_lshlrev_b32_e32 v10, 16, v53
	v_and_b32_e32 v11, 0xffff0000, v53
	v_and_b32_e32 v13, 0xffff0000, v15
	v_pk_mul_f32 v[10:11], v[10:11], v[12:13]
	s_nop 0
	v_cvt_pk_bf16_f32 v35, v10, v11
	ds_read_b64 v[10:11], v113 offset:160
	ds_read_b64 v[14:15], v113 offset:16800
	v_lshlrev_b32_e32 v12, 16, v83
	v_and_b32_e32 v13, 0xffff0000, v83
	s_waitcnt lgkmcnt(1)
	v_lshlrev_b32_e32 v20, 16, v10
	v_and_b32_e32 v21, 0xffff0000, v10
	v_pk_mul_f32 v[12:13], v[12:13], v[20:21]
	v_lshlrev_b32_e32 v10, 16, v11
	v_cvt_pk_bf16_f32 v24, v12, v13
	v_lshlrev_b32_e32 v12, 16, v82
	v_and_b32_e32 v13, 0xffff0000, v82
	v_and_b32_e32 v11, 0xffff0000, v11
	v_pk_mul_f32 v[10:11], v[12:13], v[10:11]
	s_waitcnt lgkmcnt(0)
	v_lshlrev_b32_e32 v12, 16, v14
	v_cvt_pk_bf16_f32 v26, v10, v11
	v_lshlrev_b32_e32 v10, 16, v81
	v_and_b32_e32 v11, 0xffff0000, v81
	v_and_b32_e32 v13, 0xffff0000, v14
	v_pk_mul_f32 v[10:11], v[10:11], v[12:13]
	v_lshlrev_b32_e32 v12, 16, v15
	v_cvt_pk_bf16_f32 v23, v10, v11
	v_lshlrev_b32_e32 v10, 16, v59
	v_and_b32_e32 v11, 0xffff0000, v59
	v_and_b32_e32 v13, 0xffff0000, v15
	v_pk_mul_f32 v[10:11], v[10:11], v[12:13]
	s_nop 0
	v_cvt_pk_bf16_f32 v25, v10, v11
	ds_read_b64 v[10:11], v113 offset:176
	ds_read_b64 v[14:15], v113 offset:16816
	v_lshlrev_b32_e32 v12, 16, v91
	v_and_b32_e32 v13, 0xffff0000, v91
	s_waitcnt lgkmcnt(1)
; DI unsigned pack2(float a, float b) { f32x2_t v = {a, b}; bf16x2_t r = __builtin_convertvector(v, bf16x2_t); return __builtin_bit_cast(unsigned, r); }
; DI float bflo(unsigned u) { return __uint_as_float(u << 16); }
; DI float bfhi(unsigned u) { return __uint_as_float(u & 0xffff0000u); }
; DI int otid() { int t = threadIdx.x; asm volatile("" : "+v"(t)); return t; }
; template <bool LAST>
; DI void phase_gate(const Params& P, int layer, unsigned char* smem, int L, int G) {
;     ...
;     {
;       const int tid1 = otid();
;       const int lane1 = tid1 & 63, w1 = tid1 >> 6, r1 = lane1 & 31, h1 = lane1 >> 5, wm1 = w1 >> 2, wn1 = w1 & 3;
; #pragma unroll
;       for (int i = 0; i < 4; ++i)
; #pragma unroll
;         for (int q4 = 0; q4 < 4; ++q4) {
; #pragma unroll
;           for (int j = 0; j < 2; ++j) {
;             const uint2 pv = *(const uint2*)(stg + (wn1 * 64 + j * 32 + r1) * STG + wm1 * 128 + i * 32 + 8 * q4 + 4 * h1);
;             const unsigned g0 = gq[i][j][2 * q4], g1 = gq[i][j][2 * q4 + 1];
;             gq[i][j][2 * q4] = pack2(bflo(g0) * bflo(pv.x), bfhi(g0) * bfhi(pv.x));
;             gq[i][j][2 * q4 + 1] = pack2(bflo(g1) * bflo(pv.y), bfhi(g1) * bfhi(pv.y));
;           }
;           __builtin_amdgcn_sched_barrier(0);
;         }
;     }
;     __syncthreads();
	v_lshlrev_b32_e32 v20, 16, v10
	v_and_b32_e32 v21, 0xffff0000, v10
	v_pk_mul_f32 v[12:13], v[12:13], v[20:21]
	v_lshlrev_b32_e32 v10, 16, v11
	v_cvt_pk_bf16_f32 v20, v12, v13
	v_lshlrev_b32_e32 v12, 16, v86
	v_and_b32_e32 v13, 0xffff0000, v86
	v_and_b32_e32 v11, 0xffff0000, v11
	v_pk_mul_f32 v[10:11], v[12:13], v[10:11]
	s_waitcnt lgkmcnt(0)
	v_lshlrev_b32_e32 v12, 16, v14
	v_cvt_pk_bf16_f32 v22, v10, v11
	v_lshlrev_b32_e32 v10, 16, v85
	v_and_b32_e32 v11, 0xffff0000, v85
	v_and_b32_e32 v13, 0xffff0000, v14
	v_pk_mul_f32 v[10:11], v[10:11], v[12:13]
	v_lshlrev_b32_e32 v12, 16, v15
	v_cvt_pk_bf16_f32 v18, v10, v11
	v_lshlrev_b32_e32 v10, 16, v84
	v_and_b32_e32 v11, 0xffff0000, v84
	v_and_b32_e32 v13, 0xffff0000, v15
	v_pk_mul_f32 v[10:11], v[10:11], v[12:13]
	s_nop 0
	v_cvt_pk_bf16_f32 v21, v10, v11
	ds_read_b64 v[10:11], v113 offset:192
	ds_read_b64 v[64:65], v113 offset:16832
	v_lshlrev_b32_e32 v12, 16, v17
	v_and_b32_e32 v13, 0xffff0000, v17
	s_waitcnt lgkmcnt(1)
	v_lshlrev_b32_e32 v14, 16, v10
	v_and_b32_e32 v15, 0xffff0000, v10
	v_pk_mul_f32 v[12:13], v[12:13], v[14:15]
	v_lshlrev_b32_e32 v10, 16, v11
	v_cvt_pk_bf16_f32 v15, v12, v13
	v_lshlrev_b32_e32 v12, 16, v16
	v_and_b32_e32 v13, 0xffff0000, v16
	v_and_b32_e32 v11, 0xffff0000, v11
	v_pk_mul_f32 v[10:11], v[12:13], v[10:11]
	s_waitcnt lgkmcnt(0)
	v_lshlrev_b32_e32 v12, 16, v64
	v_cvt_pk_bf16_f32 v17, v10, v11
	v_lshlrev_b32_e32 v10, 16, v3
	v_and_b32_e32 v11, 0xffff0000, v3
	v_and_b32_e32 v13, 0xffff0000, v64
	v_pk_mul_f32 v[10:11], v[10:11], v[12:13]
	v_lshlrev_b32_e32 v12, 16, v65
	v_cvt_pk_bf16_f32 v14, v10, v11
	v_lshlrev_b32_e32 v10, 16, v2
	v_and_b32_e32 v11, 0xffff0000, v2
	v_and_b32_e32 v13, 0xffff0000, v65
	v_pk_mul_f32 v[2:3], v[10:11], v[12:13]
	s_nop 0
	v_cvt_pk_bf16_f32 v16, v2, v3
	ds_read_b64 v[2:3], v113 offset:208
	ds_read_b64 v[64:65], v113 offset:16848
	v_lshlrev_b32_e32 v10, 16, v7
	v_and_b32_e32 v11, 0xffff0000, v7
	s_waitcnt lgkmcnt(1)
	v_lshlrev_b32_e32 v12, 16, v2
	v_and_b32_e32 v13, 0xffff0000, v2
	v_pk_mul_f32 v[10:11], v[10:11], v[12:13]
	v_lshlrev_b32_e32 v12, 16, v6
	v_lshlrev_b32_e32 v2, 16, v3
	v_and_b32_e32 v13, 0xffff0000, v6
	v_and_b32_e32 v3, 0xffff0000, v3
	v_pk_mul_f32 v[2:3], v[12:13], v[2:3]
	s_waitcnt lgkmcnt(0)
	v_lshlrev_b32_e32 v6, 16, v64
	v_cvt_pk_bf16_f32 v13, v2, v3
	v_lshlrev_b32_e32 v2, 16, v5
	v_and_b32_e32 v3, 0xffff0000, v5
	v_and_b32_e32 v7, 0xffff0000, v64
	v_pk_mul_f32 v[2:3], v[2:3], v[6:7]
	v_cvt_pk_bf16_f32 v11, v10, v11
	v_cvt_pk_bf16_f32 v10, v2, v3
	v_lshlrev_b32_e32 v2, 16, v4
	v_lshlrev_b32_e32 v6, 16, v65
	v_and_b32_e32 v3, 0xffff0000, v4
	v_and_b32_e32 v7, 0xffff0000, v65
	v_pk_mul_f32 v[2:3], v[2:3], v[6:7]
	s_nop 0
	v_cvt_pk_bf16_f32 v12, v2, v3
	ds_read_b64 v[2:3], v113 offset:224
	ds_read_b64 v[64:65], v113 offset:16864
	v_lshlrev_b32_e32 v4, 16, v27
	v_and_b32_e32 v5, 0xffff0000, v27
	s_waitcnt lgkmcnt(1)
	v_lshlrev_b32_e32 v6, 16, v2
	v_and_b32_e32 v7, 0xffff0000, v2
	v_pk_mul_f32 v[4:5], v[4:5], v[6:7]
	v_lshlrev_b32_e32 v2, 16, v3
	v_cvt_pk_bf16_f32 v7, v4, v5
	v_lshlrev_b32_e32 v4, 16, v9
	v_and_b32_e32 v5, 0xffff0000, v9
	v_and_b32_e32 v3, 0xffff0000, v3
	v_pk_mul_f32 v[2:3], v[4:5], v[2:3]
	s_waitcnt lgkmcnt(0)
	v_lshlrev_b32_e32 v4, 16, v64
	v_cvt_pk_bf16_f32 v9, v2, v3
	v_lshlrev_b32_e32 v2, 16, v19
	v_and_b32_e32 v3, 0xffff0000, v19
	v_and_b32_e32 v5, 0xffff0000, v64
	v_pk_mul_f32 v[2:3], v[2:3], v[4:5]
	v_lshlrev_b32_e32 v4, 16, v65
	v_cvt_pk_bf16_f32 v6, v2, v3
	v_lshlrev_b32_e32 v2, 16, v8
	v_and_b32_e32 v3, 0xffff0000, v8
	v_and_b32_e32 v5, 0xffff0000, v65
	v_pk_mul_f32 v[2:3], v[2:3], v[4:5]
	s_nop 0
	v_cvt_pk_bf16_f32 v8, v2, v3
	ds_read_b64 v[2:3], v113 offset:240
	ds_read_b64 v[64:65], v113 offset:16880
	v_lshlrev_b32_e32 v4, 16, v112
	v_and_b32_e32 v5, 0xffff0000, v112
	s_waitcnt lgkmcnt(1)
	v_lshlrev_b32_e32 v66, 16, v2
	v_and_b32_e32 v67, 0xffff0000, v2
	v_pk_mul_f32 v[4:5], v[4:5], v[66:67]
	v_lshlrev_b32_e32 v66, 16, v30
	v_lshlrev_b32_e32 v2, 16, v3
	v_and_b32_e32 v67, 0xffff0000, v30
	v_and_b32_e32 v3, 0xffff0000, v3
	v_pk_mul_f32 v[2:3], v[66:67], v[2:3]
	v_cvt_pk_bf16_f32 v4, v4, v5
	v_cvt_pk_bf16_f32 v5, v2, v3
	v_lshlrev_b32_e32 v2, 16, v29
	s_waitcnt lgkmcnt(0)
	v_lshlrev_b32_e32 v66, 16, v64
	v_and_b32_e32 v3, 0xffff0000, v29
	v_and_b32_e32 v67, 0xffff0000, v64
	v_pk_mul_f32 v[2:3], v[2:3], v[66:67]
	v_lshlrev_b32_e32 v66, 16, v28
	v_lshlrev_b32_e32 v64, 16, v65
	v_and_b32_e32 v67, 0xffff0000, v28
	v_and_b32_e32 v65, 0xffff0000, v65
	v_pk_mul_f32 v[28:29], v[66:67], v[64:65]
	v_cvt_pk_bf16_f32 v2, v2, v3
	v_cvt_pk_bf16_f32 v3, v28, v29
	v_mov_b32_e32 v19, v192
	s_barrier
; DI int otid() { int t = threadIdx.x; asm volatile("" : "+v"(t)); return t; }
; template <bool NT>
; DI void stage_load_tile(bf16_t* stg, const bf16_t* tilebase) {
;   const int tid = otid();
;   const int r0 = tid >> 5, c = tid & 31;
;   const unsigned o0 = (unsigned)(r0 * 1024 + c * 8);
;   __builtin_amdgcn_sched_barrier(0);
; #pragma unroll
;   for (int hf = 0; hf < 2; ++hf) {
; #pragma unroll
;     for (int it = 8 * hf; it < 8 * hf + 8; ++it) {
;       const u32x4* gp = (const u32x4*)(tilebase + (o0 + (unsigned)(it * 16 * 1024)));
;       stage_write16(stg, r0 + 16 * it, c, NT ? __builtin_nontemporal_load(gp) : *gp);
;     }
;     __builtin_amdgcn_sched_barrier(0);
;   }
; }
; template <bool LAST>
; DI void phase_gate(const Params& P, int layer, unsigned char* smem, int L, int G) {
;     ...
;     stage_load_tile<false>(stg, Sb + (size_t)mt * 256 * 1024 + nt * 256);
;     __syncthreads();
	s_add_u32 s30, s76, s24
	v_ashrrev_i32_e32 v27, 5, v19
	v_and_b32_e32 v19, 31, v19
	s_addc_u32 s31, s77, s25
	v_lshlrev_b32_e32 v30, 3, v19
	v_lshl_add_u64 v[28:29], s[30:31], 0, v[0:1]
	v_lshl_or_b32 v160, v27, 10, v30
	v_add_u32_e32 v66, 0x4000, v160
	v_mov_b32_e32 v67, v161
	v_add_u32_e32 v72, 0x8000, v160
	v_mov_b32_e32 v73, v161
	v_add_u32_e32 v74, 0xc000, v160
	v_mov_b32_e32 v75, v161
	v_add_u32_e32 v80, 0x10000, v160
	v_mov_b32_e32 v81, v161
	v_add_u32_e32 v82, 0x14000, v160
	v_mov_b32_e32 v83, v161
	v_lshl_add_u64 v[64:65], v[160:161], 1, v[28:29]
	v_lshl_add_u64 v[68:69], v[66:67], 1, v[28:29]
	v_lshl_add_u64 v[72:73], v[72:73], 1, v[28:29]
	v_lshl_add_u64 v[76:77], v[74:75], 1, v[28:29]
	v_lshl_add_u64 v[80:81], v[80:81], 1, v[28:29]
	v_lshl_add_u64 v[84:85], v[82:83], 1, v[28:29]
	global_load_dwordx4 v[64:67], v[64:65], off
	s_nop 0
	global_load_dwordx4 v[68:71], v[68:69], off
	s_nop 0
	global_load_dwordx4 v[72:75], v[72:73], off
	s_nop 0
	global_load_dwordx4 v[76:79], v[76:77], off
	s_nop 0
	global_load_dwordx4 v[80:83], v[80:81], off
	s_nop 0
	global_load_dwordx4 v[100:103], v[84:85], off
	v_add_u32_e32 v84, 0x18000, v160
	v_mov_b32_e32 v85, v161
	v_add_u32_e32 v104, 0x1c000, v160
	v_mov_b32_e32 v105, v161
	v_lshl_add_u64 v[84:85], v[84:85], 1, v[28:29]
	v_lshl_add_u64 v[108:109], v[104:105], 1, v[28:29]
	global_load_dwordx4 v[104:107], v[84:85], off
	s_nop 0
	global_load_dwordx4 v[108:111], v[108:109], off
	v_add_u32_e32 v218, 0x20000, v160
	v_mov_b32_e32 v219, v161
	v_add_u32_e32 v220, 0x24000, v160
	v_mov_b32_e32 v221, v161
	v_add_u32_e32 v226, 0x28000, v160
	v_mov_b32_e32 v227, v161
	v_add_u32_e32 v228, 0x2c000, v160
	v_mov_b32_e32 v229, v161
	v_add_u32_e32 v234, 0x30000, v160
	v_mov_b32_e32 v235, v161
	v_add_u32_e32 v236, 0x34000, v160
	v_mov_b32_e32 v237, v161
	v_lshl_add_u64 v[218:219], v[218:219], 1, v[28:29]
	v_lshl_add_u64 v[222:223], v[220:221], 1, v[28:29]
	v_lshl_add_u64 v[226:227], v[226:227], 1, v[28:29]
	v_lshl_add_u64 v[230:231], v[228:229], 1, v[28:29]
	v_lshl_add_u64 v[234:235], v[234:235], 1, v[28:29]
	v_lshl_add_u64 v[252:253], v[236:237], 1, v[28:29]
	global_load_dwordx4 v[218:221], v[218:219], off
	s_nop 0
	global_load_dwordx4 v[222:225], v[222:223], off
	s_nop 0
	global_load_dwordx4 v[226:229], v[226:227], off
	s_nop 0
	global_load_dwordx4 v[230:233], v[230:231], off
	s_nop 0
	global_load_dwordx4 v[234:237], v[234:235], off
	s_nop 0
	global_load_dwordx4 v[238:241], v[252:253], off
	v_add_u32_e32 v252, 0x38000, v160
	v_mov_b32_e32 v253, v161
	v_lshl_add_u64 v[252:253], v[252:253], 1, v[28:29]
	v_add_u32_e32 v160, 0x3c000, v160
	v_lshl_add_u64 v[190:191], v[160:161], 1, v[28:29]
	global_load_dwordx4 v[242:245], v[252:253], off
	global_load_dwordx4 v[248:251], v[190:191], off
	v_mul_lo_u32 v27, v27, s44
	v_lshl_add_u32 v19, v19, 4, v27
	v_add_u32_e32 v27, 0x2080, v19
	v_add_u32_e32 v30, 0x4100, v19
	v_add_u32_e32 v33, 0x6180, v19
	v_add_u32_e32 v53, 0x8200, v19
	v_add_u32_e32 v55, 0xa280, v19
	v_add_u32_e32 v59, 0xc300, v19
	v_add_u32_e32 v84, 0xe380, v19
	s_waitcnt vmcnt(15)
	ds_write2_b64 v19, v[64:65], v[66:67] offset1:1
	s_waitcnt vmcnt(14)
	ds_write2_b64 v27, v[68:69], v[70:71] offset1:1
	s_waitcnt vmcnt(13)
	ds_write2_b64 v30, v[72:73], v[74:75] offset1:1
	s_waitcnt vmcnt(12)
	ds_write2_b64 v33, v[76:77], v[78:79] offset1:1
	s_waitcnt vmcnt(11)
	ds_write2_b64 v53, v[80:81], v[82:83] offset1:1
	s_waitcnt vmcnt(10)
	ds_write2_b64 v55, v[100:101], v[102:103] offset1:1
	s_waitcnt vmcnt(9)
	ds_write2_b64 v59, v[104:105], v[106:107] offset1:1
	s_waitcnt vmcnt(8)
	ds_write2_b64 v84, v[108:109], v[110:111] offset1:1
	v_add_u32_e32 v27, 0x10400, v19
	v_add_u32_e32 v28, 0x12480, v19
	v_add_u32_e32 v29, 0x14500, v19
	v_add_u32_e32 v30, 0x16580, v19
	v_add_u32_e32 v33, 0x18600, v19
	v_add_u32_e32 v53, 0x1a680, v19
	v_add_u32_e32 v55, 0x1c700, v19
	v_add_u32_e32 v19, 0x1e780, v19
	s_waitcnt vmcnt(7)
	ds_write2_b64 v27, v[218:219], v[220:221] offset1:1
	s_waitcnt vmcnt(6)
	ds_write2_b64 v28, v[222:223], v[224:225] offset1:1
	s_waitcnt vmcnt(5)
	ds_write2_b64 v29, v[226:227], v[228:229] offset1:1
	s_waitcnt vmcnt(4)
	ds_write2_b64 v30, v[230:231], v[232:233] offset1:1
	s_waitcnt vmcnt(3)
	ds_write2_b64 v33, v[234:235], v[236:237] offset1:1
	s_waitcnt vmcnt(2)
	ds_write2_b64 v53, v[238:239], v[240:241] offset1:1
	s_waitcnt vmcnt(1)
	ds_write2_b64 v55, v[242:243], v[244:245] offset1:1
	s_waitcnt vmcnt(0)
	ds_write2_b64 v19, v[248:249], v[250:251] offset1:1
	v_mov_b32_e32 v19, v192
	s_waitcnt lgkmcnt(0)
	s_barrier
; DI unsigned pack2(float a, float b) { f32x2_t v = {a, b}; bf16x2_t r = __builtin_convertvector(v, bf16x2_t); return __builtin_bit_cast(unsigned, r); }
; DI float bflo(unsigned u) { return __uint_as_float(u << 16); }
; DI float bfhi(unsigned u) { return __uint_as_float(u & 0xffff0000u); }
; DI int otid() { int t = threadIdx.x; asm volatile("" : "+v"(t)); return t; }
; template <bool LAST>
; DI void phase_gate(const Params& P, int layer, unsigned char* smem, int L, int G) {
;     ...
;     const int tid2 = otid();
;     const int lane2 = tid2 & 63, w2 = tid2 >> 6, r2 = lane2 & 31, h2 = lane2 >> 5, wm2 = w2 >> 2, wn2 = w2 & 3;
; #pragma unroll
;     for (int i = 0; i < 4; ++i)
; #pragma unroll
;       for (int q4 = 0; q4 < 4; ++q4) {
;         const int fl = wm2 * 128 + i * 32 + 8 * q4 + 4 * h2;
;         const int f0 = nt * 256 + fl;
;         const f32x4 gv = *(const f32x4*)(vecL + 512 + fl), bv = *(const f32x4*)(vecL + 768 + fl);
;         const float ga[4] = {gv.x, gv.y, gv.z, gv.w}, ba[4] = {bv.x, bv.y, bv.z, bv.w};
; #pragma unroll
;         for (int j = 0; j < 2; ++j) {
;           const int lrow = wn2 * 64 + j * 32 + r2;
;           const float mu = rowA[lrow], rstd = rowB[lrow];
;           uint2* sp = (uint2*)(stg + lrow * STG + fl);
;           const uint2 sv = *sp;
;           const float sa[4] = {bflo(sv.x), bfhi(sv.x), bflo(sv.y), bfhi(sv.y)};
;           float y[4];
;           const float gg[4] = {bflo(gq[i][j][2 * q4]), bfhi(gq[i][j][2 * q4]), bflo(gq[i][j][2 * q4 + 1]), bfhi(gq[i][j][2 * q4 + 1])};
; #pragma unroll
;           for (int e = 0; e < 4; ++e) y[e] = (sa[e] - mu) * rstd * ga[e] + ba[e] + gg[e];
;           if (LAST) { f32x4 o = {y[0], y[1], y[2], y[3]}; *(f32x4*)(P.out + (size_t)(mt * 256 + lrow) * 1024 + f0) = o; }
;           else { uint2 pk; pk.x = pack2(y[0], y[1]); pk.y = pack2(y[2], y[3]); *sp = pk; }
;         }
;         __builtin_amdgcn_sched_barrier(0);
;       }
	v_lshlrev_b32_e32 v82, 16, v31
	v_lshrrev_b32_e32 v28, 3, v19
	v_ashrrev_i32_e32 v27, 1, v19
	v_and_b32_e32 v28, 4, v28
	v_and_or_b32 v30, v27, s45, v28
	v_and_b32_e32 v19, 0xdf, v19
	v_lshlrev_b32_e32 v27, 2, v30
	v_lshlrev_b32_e32 v33, 2, v19
	v_mul_u32_u24_e32 v19, 0x208, v19
	v_add_u32_e32 v28, 0x25000, v27
	v_lshl_add_u32 v19, v30, 1, v19
	v_add_u32_e32 v29, 0x25400, v27
	ds_read_b128 v[64:67], v28
	ds_read_b128 v[68:71], v29
	ds_read_b64 v[72:73], v19
	v_or_b32_e32 v29, 0x24000, v33
	v_or_b32_e32 v30, 0x24400, v33
	ds_read_b32 v74, v29
	ds_read_b32 v76, v30
	ds_read_b64 v[78:79], v19 offset:16640
	v_and_b32_e32 v83, 0xffff0000, v31
	s_waitcnt lgkmcnt(3)
	v_lshlrev_b32_e32 v80, 16, v72
	v_and_b32_e32 v81, 0xffff0000, v72
	v_lshlrev_b32_e32 v72, 16, v73
	v_and_b32_e32 v73, 0xffff0000, v73
	s_waitcnt lgkmcnt(2)
	v_pk_add_f32 v[80:81], v[80:81], v[74:75] op_sel_hi:[1,0] neg_lo:[0,1] neg_hi:[0,1]
	v_pk_add_f32 v[72:73], v[72:73], v[74:75] op_sel_hi:[1,0] neg_lo:[0,1] neg_hi:[0,1]
	s_waitcnt lgkmcnt(1)
	v_pk_mul_f32 v[80:81], v[76:77], v[80:81] op_sel_hi:[0,1]
	v_pk_mul_f32 v[72:73], v[76:77], v[72:73] op_sel_hi:[0,1]
	v_lshlrev_b32_e32 v84, 16, v98
	v_and_b32_e32 v85, 0xffff0000, v98
	v_pk_fma_f32 v[80:81], v[64:65], v[80:81], v[68:69]
	v_pk_fma_f32 v[72:73], v[66:67], v[72:73], v[70:71]
	v_pk_add_f32 v[80:81], v[80:81], v[82:83]
	v_pk_add_f32 v[72:73], v[72:73], v[84:85]
	v_cvt_pk_bf16_f32 v74, v80, v81
	v_cvt_pk_bf16_f32 v75, v72, v73
	ds_write_b64 v19, v[74:75]
	v_or_b32_e32 v31, 0x24080, v33
	v_or_b32_e32 v33, 0x24480, v33
	ds_read_b32 v72, v31
	ds_read_b32 v74, v33
	s_waitcnt lgkmcnt(3)
	v_lshlrev_b32_e32 v76, 16, v78
	v_and_b32_e32 v77, 0xffff0000, v78
	v_lshlrev_b32_e32 v78, 16, v79
	s_waitcnt lgkmcnt(1)
	v_pk_add_f32 v[76:77], v[76:77], v[72:73] op_sel_hi:[1,0] neg_lo:[0,1] neg_hi:[0,1]
	v_and_b32_e32 v79, 0xffff0000, v79
	s_waitcnt lgkmcnt(0)
	v_pk_mul_f32 v[76:77], v[74:75], v[76:77] op_sel_hi:[0,1]
	v_pk_fma_f32 v[64:65], v[64:65], v[76:77], v[68:69]
	v_pk_add_f32 v[68:69], v[78:79], v[72:73] op_sel_hi:[1,0] neg_lo:[0,1] neg_hi:[0,1]
	v_lshlrev_b32_e32 v80, 16, v97
	v_pk_mul_f32 v[68:69], v[74:75], v[68:69] op_sel_hi:[0,1]
	v_and_b32_e32 v81, 0xffff0000, v97
	v_lshlrev_b32_e32 v82, 16, v96
	v_and_b32_e32 v83, 0xffff0000, v96
	v_pk_fma_f32 v[66:67], v[66:67], v[68:69], v[70:71]
	v_pk_add_f32 v[64:65], v[64:65], v[80:81]
	v_pk_add_f32 v[66:67], v[66:67], v[82:83]
	v_cvt_pk_bf16_f32 v64, v64, v65
	v_cvt_pk_bf16_f32 v65, v66, v67
	ds_write_b64 v19, v[64:65] offset:16640
	v_add_u32_e32 v53, 0x25020, v27
	v_add_u32_e32 v55, 0x25420, v27
	ds_read_b64 v[72:73], v19 offset:16
	ds_read_b128 v[64:67], v53
	ds_read_b128 v[68:71], v55
	ds_read_b32 v74, v29
	ds_read_b32 v76, v30
	ds_read_b64 v[78:79], v19 offset:16656
	s_waitcnt lgkmcnt(5)
	v_lshlrev_b32_e32 v80, 16, v72
	v_and_b32_e32 v81, 0xffff0000, v72
	v_lshlrev_b32_e32 v72, 16, v73
	v_and_b32_e32 v73, 0xffff0000, v73
	s_waitcnt lgkmcnt(2)
	v_pk_add_f32 v[80:81], v[80:81], v[74:75] op_sel_hi:[1,0] neg_lo:[0,1] neg_hi:[0,1]
	v_pk_add_f32 v[72:73], v[72:73], v[74:75] op_sel_hi:[1,0] neg_lo:[0,1] neg_hi:[0,1]
	s_waitcnt lgkmcnt(1)
	v_pk_mul_f32 v[80:81], v[76:77], v[80:81] op_sel_hi:[0,1]
	v_pk_mul_f32 v[72:73], v[76:77], v[72:73] op_sel_hi:[0,1]
	v_lshlrev_b32_e32 v82, 16, v93
	v_and_b32_e32 v83, 0xffff0000, v93
	v_lshlrev_b32_e32 v84, 16, v95
	v_and_b32_e32 v85, 0xffff0000, v95
	v_pk_fma_f32 v[80:81], v[64:65], v[80:81], v[68:69]
	v_pk_fma_f32 v[72:73], v[66:67], v[72:73], v[70:71]
	v_pk_add_f32 v[80:81], v[80:81], v[82:83]
	v_pk_add_f32 v[72:73], v[72:73], v[84:85]
	v_cvt_pk_bf16_f32 v74, v80, v81
	v_cvt_pk_bf16_f32 v75, v72, v73
	ds_write_b64 v19, v[74:75] offset:16
	ds_read_b32 v72, v31
	ds_read_b32 v74, v33
	s_waitcnt lgkmcnt(3)
	v_lshlrev_b32_e32 v76, 16, v78
	v_and_b32_e32 v77, 0xffff0000, v78
	v_lshlrev_b32_e32 v78, 16, v79
	s_waitcnt lgkmcnt(1)
	v_pk_add_f32 v[76:77], v[76:77], v[72:73] op_sel_hi:[1,0] neg_lo:[0,1] neg_hi:[0,1]
	v_and_b32_e32 v79, 0xffff0000, v79
	s_waitcnt lgkmcnt(0)
	v_pk_mul_f32 v[76:77], v[74:75], v[76:77] op_sel_hi:[0,1]
	v_pk_fma_f32 v[64:65], v[64:65], v[76:77], v[68:69]
	v_pk_add_f32 v[68:69], v[78:79], v[72:73] op_sel_hi:[1,0] neg_lo:[0,1] neg_hi:[0,1]
	v_lshlrev_b32_e32 v80, 16, v92
	v_pk_mul_f32 v[68:69], v[74:75], v[68:69] op_sel_hi:[0,1]
	v_and_b32_e32 v81, 0xffff0000, v92
	v_lshlrev_b32_e32 v82, 16, v94
	v_and_b32_e32 v83, 0xffff0000, v94
	v_pk_fma_f32 v[66:67], v[66:67], v[68:69], v[70:71]
	v_pk_add_f32 v[64:65], v[64:65], v[80:81]
	v_pk_add_f32 v[66:67], v[66:67], v[82:83]
	v_cvt_pk_bf16_f32 v64, v64, v65
	v_cvt_pk_bf16_f32 v65, v66, v67
	ds_write_b64 v19, v[64:65] offset:16656
	v_add_u32_e32 v53, 0x25040, v27
	v_add_u32_e32 v55, 0x25440, v27
	ds_read_b64 v[72:73], v19 offset:32
	ds_read_b128 v[64:67], v53
	ds_read_b128 v[68:71], v55
	ds_read_b32 v74, v29
	ds_read_b32 v76, v30
	ds_read_b64 v[78:79], v19 offset:16672
	s_waitcnt lgkmcnt(5)
	v_lshlrev_b32_e32 v80, 16, v72
	v_and_b32_e32 v81, 0xffff0000, v72
	v_lshlrev_b32_e32 v72, 16, v73
	v_and_b32_e32 v73, 0xffff0000, v73
	s_waitcnt lgkmcnt(2)
	v_pk_add_f32 v[80:81], v[80:81], v[74:75] op_sel_hi:[1,0] neg_lo:[0,1] neg_hi:[0,1]
	v_pk_add_f32 v[72:73], v[72:73], v[74:75] op_sel_hi:[1,0] neg_lo:[0,1] neg_hi:[0,1]
	s_waitcnt lgkmcnt(1)
	v_pk_mul_f32 v[80:81], v[76:77], v[80:81] op_sel_hi:[0,1]
	v_pk_mul_f32 v[72:73], v[76:77], v[72:73] op_sel_hi:[0,1]
	v_lshlrev_b32_e32 v82, 16, v88
	v_and_b32_e32 v83, 0xffff0000, v88
	v_lshlrev_b32_e32 v84, 16, v90
	v_and_b32_e32 v85, 0xffff0000, v90
	v_pk_fma_f32 v[80:81], v[64:65], v[80:81], v[68:69]
	v_pk_fma_f32 v[72:73], v[66:67], v[72:73], v[70:71]
	v_pk_add_f32 v[80:81], v[80:81], v[82:83]
	v_pk_add_f32 v[72:73], v[72:73], v[84:85]
	v_cvt_pk_bf16_f32 v74, v80, v81
	v_cvt_pk_bf16_f32 v75, v72, v73
	ds_write_b64 v19, v[74:75] offset:32
	ds_read_b32 v72, v31
	ds_read_b32 v74, v33
	s_waitcnt lgkmcnt(3)
; DI unsigned pack2(float a, float b) { f32x2_t v = {a, b}; bf16x2_t r = __builtin_convertvector(v, bf16x2_t); return __builtin_bit_cast(unsigned, r); }
; DI float bflo(unsigned u) { return __uint_as_float(u << 16); }
; DI float bfhi(unsigned u) { return __uint_as_float(u & 0xffff0000u); }
; DI int otid() { int t = threadIdx.x; asm volatile("" : "+v"(t)); return t; }
; template <bool LAST>
; DI void phase_gate(const Params& P, int layer, unsigned char* smem, int L, int G) {
;     ...
;     const int tid2 = otid();
;     const int lane2 = tid2 & 63, w2 = tid2 >> 6, r2 = lane2 & 31, h2 = lane2 >> 5, wm2 = w2 >> 2, wn2 = w2 & 3;
; #pragma unroll
;     for (int i = 0; i < 4; ++i)
; #pragma unroll
;       for (int q4 = 0; q4 < 4; ++q4) {
;         const int fl = wm2 * 128 + i * 32 + 8 * q4 + 4 * h2;
;         const int f0 = nt * 256 + fl;
;         const f32x4 gv = *(const f32x4*)(vecL + 512 + fl), bv = *(const f32x4*)(vecL + 768 + fl);
;         const float ga[4] = {gv.x, gv.y, gv.z, gv.w}, ba[4] = {bv.x, bv.y, bv.z, bv.w};
; #pragma unroll
;         for (int j = 0; j < 2; ++j) {
;           const int lrow = wn2 * 64 + j * 32 + r2;
;           const float mu = rowA[lrow], rstd = rowB[lrow];
;           uint2* sp = (uint2*)(stg + lrow * STG + fl);
;           const uint2 sv = *sp;
;           const float sa[4] = {bflo(sv.x), bfhi(sv.x), bflo(sv.y), bfhi(sv.y)};
;           float y[4];
;           const float gg[4] = {bflo(gq[i][j][2 * q4]), bfhi(gq[i][j][2 * q4]), bflo(gq[i][j][2 * q4 + 1]), bfhi(gq[i][j][2 * q4 + 1])};
; #pragma unroll
;           for (int e = 0; e < 4; ++e) y[e] = (sa[e] - mu) * rstd * ga[e] + ba[e] + gg[e];
;           if (LAST) { f32x4 o = {y[0], y[1], y[2], y[3]}; *(f32x4*)(P.out + (size_t)(mt * 256 + lrow) * 1024 + f0) = o; }
;           else { uint2 pk; pk.x = pack2(y[0], y[1]); pk.y = pack2(y[2], y[3]); *sp = pk; }
;         }
;         __builtin_amdgcn_sched_barrier(0);
;       }
	v_lshlrev_b32_e32 v76, 16, v78
	v_and_b32_e32 v77, 0xffff0000, v78
	v_lshlrev_b32_e32 v78, 16, v79
	s_waitcnt lgkmcnt(1)
	v_pk_add_f32 v[76:77], v[76:77], v[72:73] op_sel_hi:[1,0] neg_lo:[0,1] neg_hi:[0,1]
	v_and_b32_e32 v79, 0xffff0000, v79
	s_waitcnt lgkmcnt(0)
	v_pk_mul_f32 v[76:77], v[74:75], v[76:77] op_sel_hi:[0,1]
	v_pk_fma_f32 v[64:65], v[64:65], v[76:77], v[68:69]
	v_pk_add_f32 v[68:69], v[78:79], v[72:73] op_sel_hi:[1,0] neg_lo:[0,1] neg_hi:[0,1]
	v_lshlrev_b32_e32 v80, 16, v87
	v_pk_mul_f32 v[68:69], v[74:75], v[68:69] op_sel_hi:[0,1]
	v_and_b32_e32 v81, 0xffff0000, v87
	v_lshlrev_b32_e32 v82, 16, v89
	v_and_b32_e32 v83, 0xffff0000, v89
	v_pk_fma_f32 v[66:67], v[66:67], v[68:69], v[70:71]
	v_pk_add_f32 v[64:65], v[64:65], v[80:81]
	v_pk_add_f32 v[66:67], v[66:67], v[82:83]
	v_cvt_pk_bf16_f32 v64, v64, v65
	v_cvt_pk_bf16_f32 v65, v66, v67
	ds_write_b64 v19, v[64:65] offset:16672
	v_add_u32_e32 v53, 0x25060, v27
	v_add_u32_e32 v55, 0x25460, v27
	ds_read_b64 v[72:73], v19 offset:48
	ds_read_b128 v[64:67], v53
	ds_read_b128 v[68:71], v55
	ds_read_b32 v74, v29
	ds_read_b32 v76, v30
	ds_read_b64 v[78:79], v19 offset:16688
	s_waitcnt lgkmcnt(5)
	v_lshlrev_b32_e32 v80, 16, v72
	v_and_b32_e32 v81, 0xffff0000, v72
	v_lshlrev_b32_e32 v72, 16, v73
	v_and_b32_e32 v73, 0xffff0000, v73
	s_waitcnt lgkmcnt(2)
	v_pk_add_f32 v[80:81], v[80:81], v[74:75] op_sel_hi:[1,0] neg_lo:[0,1] neg_hi:[0,1]
	v_pk_add_f32 v[72:73], v[72:73], v[74:75] op_sel_hi:[1,0] neg_lo:[0,1] neg_hi:[0,1]
	s_waitcnt lgkmcnt(1)
	v_pk_mul_f32 v[80:81], v[76:77], v[80:81] op_sel_hi:[0,1]
	v_pk_mul_f32 v[72:73], v[76:77], v[72:73] op_sel_hi:[0,1]
	v_lshlrev_b32_e32 v82, 16, v61
	v_and_b32_e32 v83, 0xffff0000, v61
	v_lshlrev_b32_e32 v84, 16, v63
	v_and_b32_e32 v85, 0xffff0000, v63
	v_pk_fma_f32 v[80:81], v[64:65], v[80:81], v[68:69]
	v_pk_fma_f32 v[72:73], v[66:67], v[72:73], v[70:71]
	v_pk_add_f32 v[80:81], v[80:81], v[82:83]
	v_pk_add_f32 v[72:73], v[72:73], v[84:85]
	v_cvt_pk_bf16_f32 v74, v80, v81
	v_cvt_pk_bf16_f32 v75, v72, v73
	ds_write_b64 v19, v[74:75] offset:48
	ds_read_b32 v72, v31
	ds_read_b32 v74, v33
	s_waitcnt lgkmcnt(3)
	v_lshlrev_b32_e32 v76, 16, v78
	v_and_b32_e32 v77, 0xffff0000, v78
	v_lshlrev_b32_e32 v80, 16, v60
	v_and_b32_e32 v81, 0xffff0000, v60
	v_lshlrev_b32_e32 v60, 16, v62
	v_and_b32_e32 v61, 0xffff0000, v62
	s_waitcnt lgkmcnt(1)
	v_pk_add_f32 v[62:63], v[76:77], v[72:73] op_sel_hi:[1,0] neg_lo:[0,1] neg_hi:[0,1]
	v_lshlrev_b32_e32 v78, 16, v79
	v_and_b32_e32 v79, 0xffff0000, v79
	s_waitcnt lgkmcnt(0)
	v_pk_mul_f32 v[62:63], v[74:75], v[62:63] op_sel_hi:[0,1]
	v_pk_fma_f32 v[62:63], v[64:65], v[62:63], v[68:69]
	v_pk_add_f32 v[64:65], v[78:79], v[72:73] op_sel_hi:[1,0] neg_lo:[0,1] neg_hi:[0,1]
	v_pk_add_f32 v[62:63], v[62:63], v[80:81]
	v_pk_mul_f32 v[64:65], v[74:75], v[64:65] op_sel_hi:[0,1]
	v_pk_fma_f32 v[64:65], v[66:67], v[64:65], v[70:71]
	v_cvt_pk_bf16_f32 v62, v62, v63
	v_pk_add_f32 v[60:61], v[64:65], v[60:61]
	s_nop 0
	v_cvt_pk_bf16_f32 v63, v60, v61
	ds_write_b64 v19, v[62:63] offset:16688
	v_add_u32_e32 v53, 0x25080, v27
	v_add_u32_e32 v55, 0x25480, v27
	ds_read_b64 v[68:69], v19 offset:64
	ds_read_b128 v[60:63], v53
	ds_read_b128 v[64:67], v55
	ds_read_b32 v70, v29
	ds_read_b32 v72, v30
	ds_read_b64 v[74:75], v19 offset:16704
	s_waitcnt lgkmcnt(5)
	v_lshlrev_b32_e32 v76, 16, v68
	v_and_b32_e32 v77, 0xffff0000, v68
	v_lshlrev_b32_e32 v68, 16, v69
	v_and_b32_e32 v69, 0xffff0000, v69
	v_lshlrev_b32_e32 v80, 16, v58
	v_and_b32_e32 v81, 0xffff0000, v58
	s_waitcnt lgkmcnt(2)
	v_pk_add_f32 v[58:59], v[76:77], v[70:71] op_sel_hi:[1,0] neg_lo:[0,1] neg_hi:[0,1]
	v_pk_add_f32 v[68:69], v[68:69], v[70:71] op_sel_hi:[1,0] neg_lo:[0,1] neg_hi:[0,1]
	s_waitcnt lgkmcnt(1)
	v_pk_mul_f32 v[58:59], v[72:73], v[58:59] op_sel_hi:[0,1]
	v_pk_mul_f32 v[68:69], v[72:73], v[68:69] op_sel_hi:[0,1]
	v_lshlrev_b32_e32 v78, 16, v56
	v_and_b32_e32 v79, 0xffff0000, v56
	v_pk_fma_f32 v[58:59], v[60:61], v[58:59], v[64:65]
	v_pk_fma_f32 v[68:69], v[62:63], v[68:69], v[66:67]
	v_pk_add_f32 v[58:59], v[58:59], v[78:79]
	v_pk_add_f32 v[68:69], v[68:69], v[80:81]
	v_cvt_pk_bf16_f32 v58, v58, v59
	v_cvt_pk_bf16_f32 v59, v68, v69
	ds_write_b64 v19, v[58:59] offset:64
	ds_read_b32 v56, v31
	ds_read_b32 v58, v33
	s_waitcnt lgkmcnt(3)
	v_lshlrev_b32_e32 v68, 16, v74
	v_and_b32_e32 v69, 0xffff0000, v74
	v_lshlrev_b32_e32 v70, 16, v75
	v_and_b32_e32 v71, 0xffff0000, v75
	v_lshlrev_b32_e32 v72, 16, v54
	v_and_b32_e32 v73, 0xffff0000, v54
	v_lshlrev_b32_e32 v54, 16, v57
	v_and_b32_e32 v55, 0xffff0000, v57
	s_waitcnt lgkmcnt(1)
	v_pk_add_f32 v[68:69], v[68:69], v[56:57] op_sel_hi:[1,0] neg_lo:[0,1] neg_hi:[0,1]
	v_pk_add_f32 v[56:57], v[70:71], v[56:57] op_sel_hi:[1,0] neg_lo:[0,1] neg_hi:[0,1]
	s_waitcnt lgkmcnt(0)
	v_pk_mul_f32 v[68:69], v[58:59], v[68:69] op_sel_hi:[0,1]
	v_pk_mul_f32 v[56:57], v[58:59], v[56:57] op_sel_hi:[0,1]
	v_pk_fma_f32 v[60:61], v[60:61], v[68:69], v[64:65]
	v_pk_fma_f32 v[56:57], v[62:63], v[56:57], v[66:67]
	v_pk_add_f32 v[60:61], v[60:61], v[72:73]
	v_pk_add_f32 v[54:55], v[56:57], v[54:55]
	v_cvt_pk_bf16_f32 v56, v60, v61
	v_cvt_pk_bf16_f32 v57, v54, v55
	ds_write_b64 v19, v[56:57] offset:16704
	v_add_u32_e32 v58, 0x254a0, v27
	v_add_u32_e32 v53, 0x250a0, v27
	ds_read_b64 v[62:63], v19 offset:80
	ds_read_b128 v[54:57], v53
	ds_read_b128 v[58:61], v58
	ds_read_b32 v64, v29
	ds_read_b32 v66, v30
	ds_read_b64 v[68:69], v19 offset:16720
	s_waitcnt lgkmcnt(5)
	v_lshlrev_b32_e32 v70, 16, v62
	v_and_b32_e32 v71, 0xffff0000, v62
	v_lshlrev_b32_e32 v62, 16, v63
	v_and_b32_e32 v63, 0xffff0000, v63
	v_lshlrev_b32_e32 v74, 16, v52
	v_and_b32_e32 v75, 0xffff0000, v52
	s_waitcnt lgkmcnt(2)
; DI unsigned pack2(float a, float b) { f32x2_t v = {a, b}; bf16x2_t r = __builtin_convertvector(v, bf16x2_t); return __builtin_bit_cast(unsigned, r); }
; DI float bflo(unsigned u) { return __uint_as_float(u << 16); }
; DI float bfhi(unsigned u) { return __uint_as_float(u & 0xffff0000u); }
; DI int otid() { int t = threadIdx.x; asm volatile("" : "+v"(t)); return t; }
; template <bool LAST>
; DI void phase_gate(const Params& P, int layer, unsigned char* smem, int L, int G) {
;     ...
;     const int tid2 = otid();
;     const int lane2 = tid2 & 63, w2 = tid2 >> 6, r2 = lane2 & 31, h2 = lane2 >> 5, wm2 = w2 >> 2, wn2 = w2 & 3;
; #pragma unroll
;     for (int i = 0; i < 4; ++i)
; #pragma unroll
;       for (int q4 = 0; q4 < 4; ++q4) {
;         const int fl = wm2 * 128 + i * 32 + 8 * q4 + 4 * h2;
;         const int f0 = nt * 256 + fl;
;         const f32x4 gv = *(const f32x4*)(vecL + 512 + fl), bv = *(const f32x4*)(vecL + 768 + fl);
;         const float ga[4] = {gv.x, gv.y, gv.z, gv.w}, ba[4] = {bv.x, bv.y, bv.z, bv.w};
; #pragma unroll
;         for (int j = 0; j < 2; ++j) {
;           const int lrow = wn2 * 64 + j * 32 + r2;
;           const float mu = rowA[lrow], rstd = rowB[lrow];
;           uint2* sp = (uint2*)(stg + lrow * STG + fl);
;           const uint2 sv = *sp;
;           const float sa[4] = {bflo(sv.x), bfhi(sv.x), bflo(sv.y), bfhi(sv.y)};
;           float y[4];
;           const float gg[4] = {bflo(gq[i][j][2 * q4]), bfhi(gq[i][j][2 * q4]), bflo(gq[i][j][2 * q4 + 1]), bfhi(gq[i][j][2 * q4 + 1])};
; #pragma unroll
;           for (int e = 0; e < 4; ++e) y[e] = (sa[e] - mu) * rstd * ga[e] + ba[e] + gg[e];
;           if (LAST) { f32x4 o = {y[0], y[1], y[2], y[3]}; *(f32x4*)(P.out + (size_t)(mt * 256 + lrow) * 1024 + f0) = o; }
;           else { uint2 pk; pk.x = pack2(y[0], y[1]); pk.y = pack2(y[2], y[3]); *sp = pk; }
;         }
;         __builtin_amdgcn_sched_barrier(0);
;       }
	v_pk_add_f32 v[52:53], v[70:71], v[64:65] op_sel_hi:[1,0] neg_lo:[0,1] neg_hi:[0,1]
	v_pk_add_f32 v[62:63], v[62:63], v[64:65] op_sel_hi:[1,0] neg_lo:[0,1] neg_hi:[0,1]
	s_waitcnt lgkmcnt(1)
	v_pk_mul_f32 v[52:53], v[66:67], v[52:53] op_sel_hi:[0,1]
	v_pk_mul_f32 v[62:63], v[66:67], v[62:63] op_sel_hi:[0,1]
	v_lshlrev_b32_e32 v72, 16, v50
	v_and_b32_e32 v73, 0xffff0000, v50
	v_pk_fma_f32 v[52:53], v[54:55], v[52:53], v[58:59]
	v_pk_fma_f32 v[62:63], v[56:57], v[62:63], v[60:61]
	v_pk_add_f32 v[52:53], v[52:53], v[72:73]
	v_pk_add_f32 v[62:63], v[62:63], v[74:75]
	v_cvt_pk_bf16_f32 v52, v52, v53
	v_cvt_pk_bf16_f32 v53, v62, v63
	ds_write_b64 v19, v[52:53] offset:80
	ds_read_b32 v50, v31
	ds_read_b32 v52, v33
	s_waitcnt lgkmcnt(3)
	v_lshlrev_b32_e32 v62, 16, v68
	v_and_b32_e32 v63, 0xffff0000, v68
	v_lshlrev_b32_e32 v64, 16, v69
	v_and_b32_e32 v65, 0xffff0000, v69
	v_lshlrev_b32_e32 v68, 16, v51
	v_and_b32_e32 v69, 0xffff0000, v51
	s_waitcnt lgkmcnt(1)
	v_pk_add_f32 v[62:63], v[62:63], v[50:51] op_sel_hi:[1,0] neg_lo:[0,1] neg_hi:[0,1]
	v_pk_add_f32 v[50:51], v[64:65], v[50:51] op_sel_hi:[1,0] neg_lo:[0,1] neg_hi:[0,1]
	s_waitcnt lgkmcnt(0)
	v_pk_mul_f32 v[62:63], v[52:53], v[62:63] op_sel_hi:[0,1]
	v_pk_mul_f32 v[50:51], v[52:53], v[50:51] op_sel_hi:[0,1]
	v_lshlrev_b32_e32 v66, 16, v49
	v_and_b32_e32 v67, 0xffff0000, v49
	v_pk_fma_f32 v[54:55], v[54:55], v[62:63], v[58:59]
	v_pk_fma_f32 v[50:51], v[56:57], v[50:51], v[60:61]
	v_pk_add_f32 v[54:55], v[54:55], v[66:67]
	v_pk_add_f32 v[50:51], v[50:51], v[68:69]
	v_cvt_pk_bf16_f32 v52, v54, v55
	v_cvt_pk_bf16_f32 v53, v50, v51
	ds_write_b64 v19, v[52:53] offset:16720
	v_add_u32_e32 v54, 0x254c0, v27
	v_add_u32_e32 v49, 0x250c0, v27
	ds_read_b64 v[58:59], v19 offset:96
	ds_read_b128 v[50:53], v49
	ds_read_b128 v[54:57], v54
	ds_read_b32 v60, v29
	ds_read_b32 v62, v30
	ds_read_b64 v[64:65], v19 offset:16736
	s_waitcnt lgkmcnt(5)
	v_lshlrev_b32_e32 v66, 16, v58
	v_and_b32_e32 v67, 0xffff0000, v58
	v_lshlrev_b32_e32 v58, 16, v59
	v_and_b32_e32 v59, 0xffff0000, v59
	v_lshlrev_b32_e32 v70, 16, v48
	v_and_b32_e32 v71, 0xffff0000, v48
	s_waitcnt lgkmcnt(2)
	v_pk_add_f32 v[48:49], v[66:67], v[60:61] op_sel_hi:[1,0] neg_lo:[0,1] neg_hi:[0,1]
	v_pk_add_f32 v[58:59], v[58:59], v[60:61] op_sel_hi:[1,0] neg_lo:[0,1] neg_hi:[0,1]
	s_waitcnt lgkmcnt(1)
	v_pk_mul_f32 v[48:49], v[62:63], v[48:49] op_sel_hi:[0,1]
	v_pk_mul_f32 v[58:59], v[62:63], v[58:59] op_sel_hi:[0,1]
	v_lshlrev_b32_e32 v68, 16, v46
	v_and_b32_e32 v69, 0xffff0000, v46
	v_pk_fma_f32 v[48:49], v[50:51], v[48:49], v[54:55]
	v_pk_fma_f32 v[58:59], v[52:53], v[58:59], v[56:57]
	v_pk_add_f32 v[48:49], v[48:49], v[68:69]
	v_pk_add_f32 v[58:59], v[58:59], v[70:71]
	v_cvt_pk_bf16_f32 v48, v48, v49
	v_cvt_pk_bf16_f32 v49, v58, v59
	ds_write_b64 v19, v[48:49] offset:96
	ds_read_b32 v46, v31
	ds_read_b32 v48, v33
	s_waitcnt lgkmcnt(3)
	v_lshlrev_b32_e32 v58, 16, v64
	v_and_b32_e32 v59, 0xffff0000, v64
	v_lshlrev_b32_e32 v60, 16, v65
	v_and_b32_e32 v61, 0xffff0000, v65
	v_lshlrev_b32_e32 v64, 16, v47
	v_and_b32_e32 v65, 0xffff0000, v47
	s_waitcnt lgkmcnt(1)
	v_pk_add_f32 v[58:59], v[58:59], v[46:47] op_sel_hi:[1,0] neg_lo:[0,1] neg_hi:[0,1]
	v_pk_add_f32 v[46:47], v[60:61], v[46:47] op_sel_hi:[1,0] neg_lo:[0,1] neg_hi:[0,1]
	s_waitcnt lgkmcnt(0)
	v_pk_mul_f32 v[58:59], v[48:49], v[58:59] op_sel_hi:[0,1]
	v_pk_mul_f32 v[46:47], v[48:49], v[46:47] op_sel_hi:[0,1]
	v_lshlrev_b32_e32 v62, 16, v45
	v_and_b32_e32 v63, 0xffff0000, v45
	v_pk_fma_f32 v[50:51], v[50:51], v[58:59], v[54:55]
	v_pk_fma_f32 v[46:47], v[52:53], v[46:47], v[56:57]
	v_pk_add_f32 v[50:51], v[50:51], v[62:63]
	v_pk_add_f32 v[46:47], v[46:47], v[64:65]
	v_cvt_pk_bf16_f32 v48, v50, v51
	v_cvt_pk_bf16_f32 v49, v46, v47
	ds_write_b64 v19, v[48:49] offset:16736
	v_add_u32_e32 v50, 0x254e0, v27
	v_add_u32_e32 v45, 0x250e0, v27
	ds_read_b64 v[54:55], v19 offset:112
	ds_read_b128 v[46:49], v45
	ds_read_b128 v[50:53], v50
	ds_read_b32 v56, v29
	ds_read_b32 v58, v30
	ds_read_b64 v[60:61], v19 offset:16752
	s_waitcnt lgkmcnt(5)
	v_lshlrev_b32_e32 v62, 16, v54
	v_and_b32_e32 v63, 0xffff0000, v54
	v_lshlrev_b32_e32 v54, 16, v55
	v_and_b32_e32 v55, 0xffff0000, v55
	v_lshlrev_b32_e32 v66, 16, v44
	v_and_b32_e32 v67, 0xffff0000, v44
	s_waitcnt lgkmcnt(2)
	v_pk_add_f32 v[44:45], v[62:63], v[56:57] op_sel_hi:[1,0] neg_lo:[0,1] neg_hi:[0,1]
	v_pk_add_f32 v[54:55], v[54:55], v[56:57] op_sel_hi:[1,0] neg_lo:[0,1] neg_hi:[0,1]
	s_waitcnt lgkmcnt(1)
	v_pk_mul_f32 v[44:45], v[58:59], v[44:45] op_sel_hi:[0,1]
	v_pk_mul_f32 v[54:55], v[58:59], v[54:55] op_sel_hi:[0,1]
	v_lshlrev_b32_e32 v64, 16, v42
	v_and_b32_e32 v65, 0xffff0000, v42
	v_pk_fma_f32 v[44:45], v[46:47], v[44:45], v[50:51]
	v_pk_fma_f32 v[54:55], v[48:49], v[54:55], v[52:53]
	v_pk_add_f32 v[44:45], v[44:45], v[64:65]
	v_pk_add_f32 v[54:55], v[54:55], v[66:67]
	v_cvt_pk_bf16_f32 v44, v44, v45
	v_cvt_pk_bf16_f32 v45, v54, v55
	ds_write_b64 v19, v[44:45] offset:112
	ds_read_b32 v42, v31
	ds_read_b32 v44, v33
	s_waitcnt lgkmcnt(3)
	v_lshlrev_b32_e32 v54, 16, v60
	v_and_b32_e32 v55, 0xffff0000, v60
	v_lshlrev_b32_e32 v56, 16, v61
	v_and_b32_e32 v57, 0xffff0000, v61
	v_lshlrev_b32_e32 v60, 16, v43
	v_and_b32_e32 v61, 0xffff0000, v43
	s_waitcnt lgkmcnt(1)
	v_pk_add_f32 v[54:55], v[54:55], v[42:43] op_sel_hi:[1,0] neg_lo:[0,1] neg_hi:[0,1]
	v_pk_add_f32 v[42:43], v[56:57], v[42:43] op_sel_hi:[1,0] neg_lo:[0,1] neg_hi:[0,1]
	s_waitcnt lgkmcnt(0)
; DI unsigned pack2(float a, float b) { f32x2_t v = {a, b}; bf16x2_t r = __builtin_convertvector(v, bf16x2_t); return __builtin_bit_cast(unsigned, r); }
; DI float bflo(unsigned u) { return __uint_as_float(u << 16); }
; DI float bfhi(unsigned u) { return __uint_as_float(u & 0xffff0000u); }
; DI int otid() { int t = threadIdx.x; asm volatile("" : "+v"(t)); return t; }
; template <bool LAST>
; DI void phase_gate(const Params& P, int layer, unsigned char* smem, int L, int G) {
;     ...
;     const int tid2 = otid();
;     const int lane2 = tid2 & 63, w2 = tid2 >> 6, r2 = lane2 & 31, h2 = lane2 >> 5, wm2 = w2 >> 2, wn2 = w2 & 3;
; #pragma unroll
;     for (int i = 0; i < 4; ++i)
; #pragma unroll
;       for (int q4 = 0; q4 < 4; ++q4) {
;         const int fl = wm2 * 128 + i * 32 + 8 * q4 + 4 * h2;
;         const int f0 = nt * 256 + fl;
;         const f32x4 gv = *(const f32x4*)(vecL + 512 + fl), bv = *(const f32x4*)(vecL + 768 + fl);
;         const float ga[4] = {gv.x, gv.y, gv.z, gv.w}, ba[4] = {bv.x, bv.y, bv.z, bv.w};
; #pragma unroll
;         for (int j = 0; j < 2; ++j) {
;           const int lrow = wn2 * 64 + j * 32 + r2;
;           const float mu = rowA[lrow], rstd = rowB[lrow];
;           uint2* sp = (uint2*)(stg + lrow * STG + fl);
;           const uint2 sv = *sp;
;           const float sa[4] = {bflo(sv.x), bfhi(sv.x), bflo(sv.y), bfhi(sv.y)};
;           float y[4];
;           const float gg[4] = {bflo(gq[i][j][2 * q4]), bfhi(gq[i][j][2 * q4]), bflo(gq[i][j][2 * q4 + 1]), bfhi(gq[i][j][2 * q4 + 1])};
; #pragma unroll
;           for (int e = 0; e < 4; ++e) y[e] = (sa[e] - mu) * rstd * ga[e] + ba[e] + gg[e];
;           if (LAST) { f32x4 o = {y[0], y[1], y[2], y[3]}; *(f32x4*)(P.out + (size_t)(mt * 256 + lrow) * 1024 + f0) = o; }
;           else { uint2 pk; pk.x = pack2(y[0], y[1]); pk.y = pack2(y[2], y[3]); *sp = pk; }
;         }
;         __builtin_amdgcn_sched_barrier(0);
;       }
	v_pk_mul_f32 v[54:55], v[44:45], v[54:55] op_sel_hi:[0,1]
	v_pk_mul_f32 v[42:43], v[44:45], v[42:43] op_sel_hi:[0,1]
	v_lshlrev_b32_e32 v58, 16, v41
	v_and_b32_e32 v59, 0xffff0000, v41
	v_pk_fma_f32 v[46:47], v[46:47], v[54:55], v[50:51]
	v_pk_fma_f32 v[42:43], v[48:49], v[42:43], v[52:53]
	v_pk_add_f32 v[46:47], v[46:47], v[58:59]
	v_pk_add_f32 v[42:43], v[42:43], v[60:61]
	v_cvt_pk_bf16_f32 v44, v46, v47
	v_cvt_pk_bf16_f32 v45, v42, v43
	ds_write_b64 v19, v[44:45] offset:16752
	v_add_u32_e32 v46, 0x25500, v27
	v_add_u32_e32 v41, 0x25100, v27
	ds_read_b64 v[50:51], v19 offset:128
	ds_read_b128 v[42:45], v41
	ds_read_b128 v[46:49], v46
	ds_read_b32 v52, v29
	ds_read_b32 v54, v30
	ds_read_b64 v[56:57], v19 offset:16768
	s_waitcnt lgkmcnt(5)
	v_lshlrev_b32_e32 v58, 16, v50
	v_and_b32_e32 v59, 0xffff0000, v50
	v_lshlrev_b32_e32 v50, 16, v51
	v_and_b32_e32 v51, 0xffff0000, v51
	v_lshlrev_b32_e32 v62, 16, v40
	v_and_b32_e32 v63, 0xffff0000, v40
	s_waitcnt lgkmcnt(2)
	v_pk_add_f32 v[40:41], v[58:59], v[52:53] op_sel_hi:[1,0] neg_lo:[0,1] neg_hi:[0,1]
	v_pk_add_f32 v[50:51], v[50:51], v[52:53] op_sel_hi:[1,0] neg_lo:[0,1] neg_hi:[0,1]
	s_waitcnt lgkmcnt(1)
	v_pk_mul_f32 v[40:41], v[54:55], v[40:41] op_sel_hi:[0,1]
	v_pk_mul_f32 v[50:51], v[54:55], v[50:51] op_sel_hi:[0,1]
	v_lshlrev_b32_e32 v60, 16, v38
	v_and_b32_e32 v61, 0xffff0000, v38
	v_pk_fma_f32 v[40:41], v[42:43], v[40:41], v[46:47]
	v_pk_fma_f32 v[50:51], v[44:45], v[50:51], v[48:49]
	v_pk_add_f32 v[40:41], v[40:41], v[60:61]
	v_pk_add_f32 v[50:51], v[50:51], v[62:63]
	v_cvt_pk_bf16_f32 v40, v40, v41
	v_cvt_pk_bf16_f32 v41, v50, v51
	ds_write_b64 v19, v[40:41] offset:128
	ds_read_b32 v38, v31
	ds_read_b32 v40, v33
	s_waitcnt lgkmcnt(3)
	v_lshlrev_b32_e32 v50, 16, v56
	v_and_b32_e32 v51, 0xffff0000, v56
	v_lshlrev_b32_e32 v52, 16, v57
	v_and_b32_e32 v53, 0xffff0000, v57
	v_lshlrev_b32_e32 v56, 16, v39
	v_and_b32_e32 v57, 0xffff0000, v39
	s_waitcnt lgkmcnt(1)
	v_pk_add_f32 v[50:51], v[50:51], v[38:39] op_sel_hi:[1,0] neg_lo:[0,1] neg_hi:[0,1]
	v_pk_add_f32 v[38:39], v[52:53], v[38:39] op_sel_hi:[1,0] neg_lo:[0,1] neg_hi:[0,1]
	s_waitcnt lgkmcnt(0)
	v_pk_mul_f32 v[50:51], v[40:41], v[50:51] op_sel_hi:[0,1]
	v_pk_mul_f32 v[38:39], v[40:41], v[38:39] op_sel_hi:[0,1]
	v_lshlrev_b32_e32 v54, 16, v37
	v_and_b32_e32 v55, 0xffff0000, v37
	v_pk_fma_f32 v[42:43], v[42:43], v[50:51], v[46:47]
	v_pk_fma_f32 v[38:39], v[44:45], v[38:39], v[48:49]
	v_pk_add_f32 v[42:43], v[42:43], v[54:55]
	v_pk_add_f32 v[38:39], v[38:39], v[56:57]
	v_cvt_pk_bf16_f32 v40, v42, v43
	v_cvt_pk_bf16_f32 v41, v38, v39
	ds_write_b64 v19, v[40:41] offset:16768
	v_add_u32_e32 v42, 0x25520, v27
	v_add_u32_e32 v37, 0x25120, v27
	ds_read_b64 v[46:47], v19 offset:144
	ds_read_b128 v[38:41], v37
	ds_read_b128 v[42:45], v42
	ds_read_b32 v48, v29
	ds_read_b32 v50, v30
	ds_read_b64 v[52:53], v19 offset:16784
	s_waitcnt lgkmcnt(5)
	v_lshlrev_b32_e32 v54, 16, v46
	v_and_b32_e32 v55, 0xffff0000, v46
	v_lshlrev_b32_e32 v46, 16, v47
	v_and_b32_e32 v47, 0xffff0000, v47
	v_lshlrev_b32_e32 v58, 16, v36
	v_and_b32_e32 v59, 0xffff0000, v36
	s_waitcnt lgkmcnt(2)
	v_pk_add_f32 v[36:37], v[54:55], v[48:49] op_sel_hi:[1,0] neg_lo:[0,1] neg_hi:[0,1]
	v_pk_add_f32 v[46:47], v[46:47], v[48:49] op_sel_hi:[1,0] neg_lo:[0,1] neg_hi:[0,1]
	s_waitcnt lgkmcnt(1)
	v_pk_mul_f32 v[36:37], v[50:51], v[36:37] op_sel_hi:[0,1]
	v_pk_mul_f32 v[46:47], v[50:51], v[46:47] op_sel_hi:[0,1]
	v_lshlrev_b32_e32 v56, 16, v34
	v_and_b32_e32 v57, 0xffff0000, v34
	v_pk_fma_f32 v[36:37], v[38:39], v[36:37], v[42:43]
	v_pk_fma_f32 v[46:47], v[40:41], v[46:47], v[44:45]
	v_pk_add_f32 v[36:37], v[36:37], v[56:57]
	v_pk_add_f32 v[46:47], v[46:47], v[58:59]
	v_cvt_pk_bf16_f32 v36, v36, v37
	v_cvt_pk_bf16_f32 v37, v46, v47
	ds_write_b64 v19, v[36:37] offset:144
	ds_read_b32 v34, v31
	ds_read_b32 v36, v33
	s_waitcnt lgkmcnt(3)
	v_lshlrev_b32_e32 v46, 16, v52
	v_and_b32_e32 v47, 0xffff0000, v52
	v_lshlrev_b32_e32 v48, 16, v53
	v_and_b32_e32 v49, 0xffff0000, v53
	v_lshlrev_b32_e32 v52, 16, v35
	v_and_b32_e32 v53, 0xffff0000, v35
	s_waitcnt lgkmcnt(1)
	v_pk_add_f32 v[46:47], v[46:47], v[34:35] op_sel_hi:[1,0] neg_lo:[0,1] neg_hi:[0,1]
	v_pk_add_f32 v[34:35], v[48:49], v[34:35] op_sel_hi:[1,0] neg_lo:[0,1] neg_hi:[0,1]
	s_waitcnt lgkmcnt(0)
	v_pk_mul_f32 v[46:47], v[36:37], v[46:47] op_sel_hi:[0,1]
	v_pk_mul_f32 v[34:35], v[36:37], v[34:35] op_sel_hi:[0,1]
	v_lshlrev_b32_e32 v50, 16, v32
	v_and_b32_e32 v51, 0xffff0000, v32
	v_pk_fma_f32 v[38:39], v[38:39], v[46:47], v[42:43]
	v_pk_fma_f32 v[34:35], v[40:41], v[34:35], v[44:45]
	v_pk_add_f32 v[38:39], v[38:39], v[50:51]
	v_pk_add_f32 v[34:35], v[34:35], v[52:53]
	v_cvt_pk_bf16_f32 v36, v38, v39
	v_cvt_pk_bf16_f32 v37, v34, v35
	ds_write_b64 v19, v[36:37] offset:16784
	v_add_u32_e32 v32, 0x25140, v27
	v_add_u32_e32 v38, 0x25540, v27
	ds_read_b64 v[42:43], v19 offset:160
	ds_read_b128 v[34:37], v32
	ds_read_b128 v[38:41], v38
	ds_read_b32 v32, v29
	ds_read_b32 v44, v30
	ds_read_b64 v[46:47], v19 offset:16800
	s_waitcnt lgkmcnt(5)
	v_lshlrev_b32_e32 v48, 16, v42
	v_and_b32_e32 v49, 0xffff0000, v42
	v_lshlrev_b32_e32 v42, 16, v43
	v_and_b32_e32 v43, 0xffff0000, v43
	s_waitcnt lgkmcnt(2)
	v_pk_add_f32 v[48:49], v[48:49], v[32:33] op_sel_hi:[1,0] neg_lo:[0,1] neg_hi:[0,1]
	v_pk_add_f32 v[42:43], v[42:43], v[32:33] op_sel_hi:[1,0] neg_lo:[0,1] neg_hi:[0,1]
	s_waitcnt lgkmcnt(1)
; DI unsigned pack2(float a, float b) { f32x2_t v = {a, b}; bf16x2_t r = __builtin_convertvector(v, bf16x2_t); return __builtin_bit_cast(unsigned, r); }
; DI float bflo(unsigned u) { return __uint_as_float(u << 16); }
; DI float bfhi(unsigned u) { return __uint_as_float(u & 0xffff0000u); }
; DI int otid() { int t = threadIdx.x; asm volatile("" : "+v"(t)); return t; }
; template <bool LAST>
; DI void phase_gate(const Params& P, int layer, unsigned char* smem, int L, int G) {
;     ...
;     const int tid2 = otid();
;     const int lane2 = tid2 & 63, w2 = tid2 >> 6, r2 = lane2 & 31, h2 = lane2 >> 5, wm2 = w2 >> 2, wn2 = w2 & 3;
; #pragma unroll
;     for (int i = 0; i < 4; ++i)
; #pragma unroll
;       for (int q4 = 0; q4 < 4; ++q4) {
;         const int fl = wm2 * 128 + i * 32 + 8 * q4 + 4 * h2;
;         const int f0 = nt * 256 + fl;
;         const f32x4 gv = *(const f32x4*)(vecL + 512 + fl), bv = *(const f32x4*)(vecL + 768 + fl);
;         const float ga[4] = {gv.x, gv.y, gv.z, gv.w}, ba[4] = {bv.x, bv.y, bv.z, bv.w};
; #pragma unroll
;         for (int j = 0; j < 2; ++j) {
;           const int lrow = wn2 * 64 + j * 32 + r2;
;           const float mu = rowA[lrow], rstd = rowB[lrow];
;           uint2* sp = (uint2*)(stg + lrow * STG + fl);
;           const uint2 sv = *sp;
;           const float sa[4] = {bflo(sv.x), bfhi(sv.x), bflo(sv.y), bfhi(sv.y)};
;           float y[4];
;           const float gg[4] = {bflo(gq[i][j][2 * q4]), bfhi(gq[i][j][2 * q4]), bflo(gq[i][j][2 * q4 + 1]), bfhi(gq[i][j][2 * q4 + 1])};
; #pragma unroll
;           for (int e = 0; e < 4; ++e) y[e] = (sa[e] - mu) * rstd * ga[e] + ba[e] + gg[e];
;           if (LAST) { f32x4 o = {y[0], y[1], y[2], y[3]}; *(f32x4*)(P.out + (size_t)(mt * 256 + lrow) * 1024 + f0) = o; }
;           else { uint2 pk; pk.x = pack2(y[0], y[1]); pk.y = pack2(y[2], y[3]); *sp = pk; }
;         }
;         __builtin_amdgcn_sched_barrier(0);
;       }
	v_pk_mul_f32 v[48:49], v[44:45], v[48:49] op_sel_hi:[0,1]
	v_pk_mul_f32 v[42:43], v[44:45], v[42:43] op_sel_hi:[0,1]
	v_lshlrev_b32_e32 v50, 16, v24
	v_and_b32_e32 v51, 0xffff0000, v24
	v_lshlrev_b32_e32 v52, 16, v26
	v_and_b32_e32 v53, 0xffff0000, v26
	v_pk_fma_f32 v[48:49], v[34:35], v[48:49], v[38:39]
	v_pk_fma_f32 v[42:43], v[36:37], v[42:43], v[40:41]
	v_pk_add_f32 v[48:49], v[48:49], v[50:51]
	v_pk_add_f32 v[42:43], v[42:43], v[52:53]
	v_cvt_pk_bf16_f32 v44, v48, v49
	v_cvt_pk_bf16_f32 v45, v42, v43
	ds_write_b64 v19, v[44:45] offset:160
	ds_read_b32 v24, v31
	ds_read_b32 v26, v33
	s_waitcnt lgkmcnt(3)
	v_lshlrev_b32_e32 v42, 16, v46
	v_and_b32_e32 v43, 0xffff0000, v46
	v_lshlrev_b32_e32 v44, 16, v47
	v_and_b32_e32 v45, 0xffff0000, v47
	v_lshlrev_b32_e32 v48, 16, v25
	v_and_b32_e32 v49, 0xffff0000, v25
	s_waitcnt lgkmcnt(1)
	v_pk_add_f32 v[42:43], v[42:43], v[24:25] op_sel_hi:[1,0] neg_lo:[0,1] neg_hi:[0,1]
	v_pk_add_f32 v[24:25], v[44:45], v[24:25] op_sel_hi:[1,0] neg_lo:[0,1] neg_hi:[0,1]
	s_waitcnt lgkmcnt(0)
	v_pk_mul_f32 v[42:43], v[26:27], v[42:43] op_sel_hi:[0,1]
	v_pk_mul_f32 v[24:25], v[26:27], v[24:25] op_sel_hi:[0,1]
	v_lshlrev_b32_e32 v46, 16, v23
	v_and_b32_e32 v47, 0xffff0000, v23
	v_pk_fma_f32 v[34:35], v[34:35], v[42:43], v[38:39]
	v_pk_fma_f32 v[24:25], v[36:37], v[24:25], v[40:41]
	v_pk_add_f32 v[34:35], v[34:35], v[46:47]
	v_pk_add_f32 v[24:25], v[24:25], v[48:49]
	v_cvt_pk_bf16_f32 v34, v34, v35
	v_cvt_pk_bf16_f32 v35, v24, v25
	ds_write_b64 v19, v[34:35] offset:16800
	v_add_u32_e32 v26, 0x25560, v27
	v_add_u32_e32 v23, 0x25160, v27
	ds_read_b64 v[24:25], v19 offset:176
	ds_read_b128 v[34:37], v23
	ds_read_b128 v[38:41], v26
	ds_read_b32 v26, v29
	ds_read_b32 v32, v30
	ds_read_b64 v[42:43], v19 offset:16816
	s_waitcnt lgkmcnt(5)
	v_lshlrev_b32_e32 v44, 16, v24
	v_and_b32_e32 v45, 0xffff0000, v24
	v_lshlrev_b32_e32 v24, 16, v25
	v_and_b32_e32 v25, 0xffff0000, v25
	v_lshlrev_b32_e32 v48, 16, v22
	v_and_b32_e32 v49, 0xffff0000, v22
	s_waitcnt lgkmcnt(2)
	v_pk_add_f32 v[22:23], v[44:45], v[26:27] op_sel_hi:[1,0] neg_lo:[0,1] neg_hi:[0,1]
	v_pk_add_f32 v[24:25], v[24:25], v[26:27] op_sel_hi:[1,0] neg_lo:[0,1] neg_hi:[0,1]
	s_waitcnt lgkmcnt(1)
	v_pk_mul_f32 v[22:23], v[32:33], v[22:23] op_sel_hi:[0,1]
	v_pk_mul_f32 v[24:25], v[32:33], v[24:25] op_sel_hi:[0,1]
	v_lshlrev_b32_e32 v46, 16, v20
	v_and_b32_e32 v47, 0xffff0000, v20
	v_pk_fma_f32 v[22:23], v[34:35], v[22:23], v[38:39]
	v_pk_fma_f32 v[24:25], v[36:37], v[24:25], v[40:41]
	v_pk_add_f32 v[22:23], v[22:23], v[46:47]
	v_pk_add_f32 v[24:25], v[24:25], v[48:49]
	v_cvt_pk_bf16_f32 v22, v22, v23
	v_cvt_pk_bf16_f32 v23, v24, v25
	ds_write_b64 v19, v[22:23] offset:176
	ds_read_b32 v20, v31
	ds_read_b32 v22, v33
	s_waitcnt lgkmcnt(3)
	v_lshlrev_b32_e32 v24, 16, v42
	v_and_b32_e32 v25, 0xffff0000, v42
	v_lshlrev_b32_e32 v42, 16, v43
	v_and_b32_e32 v43, 0xffff0000, v43
	v_lshlrev_b32_e32 v46, 16, v21
	v_and_b32_e32 v47, 0xffff0000, v21
	s_waitcnt lgkmcnt(1)
	v_pk_add_f32 v[24:25], v[24:25], v[20:21] op_sel_hi:[1,0] neg_lo:[0,1] neg_hi:[0,1]
	v_pk_add_f32 v[20:21], v[42:43], v[20:21] op_sel_hi:[1,0] neg_lo:[0,1] neg_hi:[0,1]
	s_waitcnt lgkmcnt(0)
	v_pk_mul_f32 v[24:25], v[22:23], v[24:25] op_sel_hi:[0,1]
	v_pk_mul_f32 v[20:21], v[22:23], v[20:21] op_sel_hi:[0,1]
	v_lshlrev_b32_e32 v44, 16, v18
	v_and_b32_e32 v45, 0xffff0000, v18
	v_pk_fma_f32 v[24:25], v[34:35], v[24:25], v[38:39]
	v_pk_fma_f32 v[20:21], v[36:37], v[20:21], v[40:41]
	v_pk_add_f32 v[24:25], v[24:25], v[44:45]
	v_pk_add_f32 v[20:21], v[20:21], v[46:47]
	v_cvt_pk_bf16_f32 v22, v24, v25
	v_cvt_pk_bf16_f32 v23, v20, v21
	ds_write_b64 v19, v[22:23] offset:16816
	v_add_u32_e32 v18, 0x25180, v27
	v_add_u32_e32 v26, 0x25580, v27
	ds_read_b64 v[24:25], v19 offset:192
	ds_read_b128 v[20:23], v18
	ds_read_b128 v[34:37], v26
	ds_read_b32 v18, v29
	ds_read_b32 v26, v30
	ds_read_b64 v[38:39], v19 offset:16832
	s_waitcnt lgkmcnt(5)
	v_lshlrev_b32_e32 v40, 16, v24
	v_and_b32_e32 v41, 0xffff0000, v24
	v_lshlrev_b32_e32 v24, 16, v25
	v_and_b32_e32 v25, 0xffff0000, v25
	s_waitcnt lgkmcnt(2)
	v_pk_add_f32 v[40:41], v[40:41], v[18:19] op_sel_hi:[1,0] neg_lo:[0,1] neg_hi:[0,1]
	v_pk_add_f32 v[24:25], v[24:25], v[18:19] op_sel_hi:[1,0] neg_lo:[0,1] neg_hi:[0,1]
	s_waitcnt lgkmcnt(1)
	v_pk_mul_f32 v[40:41], v[26:27], v[40:41] op_sel_hi:[0,1]
	v_pk_mul_f32 v[24:25], v[26:27], v[24:25] op_sel_hi:[0,1]
	v_lshlrev_b32_e32 v42, 16, v15
	v_and_b32_e32 v43, 0xffff0000, v15
	v_lshlrev_b32_e32 v44, 16, v17
	v_and_b32_e32 v45, 0xffff0000, v17
	v_pk_fma_f32 v[40:41], v[20:21], v[40:41], v[34:35]
	v_pk_fma_f32 v[24:25], v[22:23], v[24:25], v[36:37]
	v_pk_add_f32 v[40:41], v[40:41], v[42:43]
	v_pk_add_f32 v[24:25], v[24:25], v[44:45]
	v_cvt_pk_bf16_f32 v40, v40, v41
	v_cvt_pk_bf16_f32 v41, v24, v25
	ds_write_b64 v19, v[40:41] offset:192
	ds_read_b32 v18, v31
	ds_read_b32 v24, v33
	s_waitcnt lgkmcnt(3)
	v_lshlrev_b32_e32 v40, 16, v38
	v_and_b32_e32 v41, 0xffff0000, v38
	v_lshlrev_b32_e32 v42, 16, v14
	v_and_b32_e32 v43, 0xffff0000, v14
	v_lshlrev_b32_e32 v14, 16, v16
	v_and_b32_e32 v15, 0xffff0000, v16
	s_waitcnt lgkmcnt(1)
	v_pk_add_f32 v[16:17], v[40:41], v[18:19] op_sel_hi:[1,0] neg_lo:[0,1] neg_hi:[0,1]
	v_lshlrev_b32_e32 v38, 16, v39
	v_and_b32_e32 v39, 0xffff0000, v39
	s_waitcnt lgkmcnt(0)
; DI unsigned pack2(float a, float b) { f32x2_t v = {a, b}; bf16x2_t r = __builtin_convertvector(v, bf16x2_t); return __builtin_bit_cast(unsigned, r); }
; DI float bflo(unsigned u) { return __uint_as_float(u << 16); }
; DI float bfhi(unsigned u) { return __uint_as_float(u & 0xffff0000u); }
; DI int otid() { int t = threadIdx.x; asm volatile("" : "+v"(t)); return t; }
; template <bool LAST>
; DI void phase_gate(const Params& P, int layer, unsigned char* smem, int L, int G) {
;     ...
;     const int tid2 = otid();
;     const int lane2 = tid2 & 63, w2 = tid2 >> 6, r2 = lane2 & 31, h2 = lane2 >> 5, wm2 = w2 >> 2, wn2 = w2 & 3;
; #pragma unroll
;     for (int i = 0; i < 4; ++i)
; #pragma unroll
;       for (int q4 = 0; q4 < 4; ++q4) {
;         const int fl = wm2 * 128 + i * 32 + 8 * q4 + 4 * h2;
;         const int f0 = nt * 256 + fl;
;         const f32x4 gv = *(const f32x4*)(vecL + 512 + fl), bv = *(const f32x4*)(vecL + 768 + fl);
;         const float ga[4] = {gv.x, gv.y, gv.z, gv.w}, ba[4] = {bv.x, bv.y, bv.z, bv.w};
; #pragma unroll
;         for (int j = 0; j < 2; ++j) {
;           const int lrow = wn2 * 64 + j * 32 + r2;
;           const float mu = rowA[lrow], rstd = rowB[lrow];
;           uint2* sp = (uint2*)(stg + lrow * STG + fl);
;           const uint2 sv = *sp;
;           const float sa[4] = {bflo(sv.x), bfhi(sv.x), bflo(sv.y), bfhi(sv.y)};
;           float y[4];
;           const float gg[4] = {bflo(gq[i][j][2 * q4]), bfhi(gq[i][j][2 * q4]), bflo(gq[i][j][2 * q4 + 1]), bfhi(gq[i][j][2 * q4 + 1])};
; #pragma unroll
;           for (int e = 0; e < 4; ++e) y[e] = (sa[e] - mu) * rstd * ga[e] + ba[e] + gg[e];
;           if (LAST) { f32x4 o = {y[0], y[1], y[2], y[3]}; *(f32x4*)(P.out + (size_t)(mt * 256 + lrow) * 1024 + f0) = o; }
;           else { uint2 pk; pk.x = pack2(y[0], y[1]); pk.y = pack2(y[2], y[3]); *sp = pk; }
;         }
;         __builtin_amdgcn_sched_barrier(0);
;       }
;     __syncthreads();
	v_pk_mul_f32 v[16:17], v[24:25], v[16:17] op_sel_hi:[0,1]
	v_pk_fma_f32 v[16:17], v[20:21], v[16:17], v[34:35]
	v_pk_add_f32 v[20:21], v[38:39], v[18:19] op_sel_hi:[1,0] neg_lo:[0,1] neg_hi:[0,1]
	v_pk_add_f32 v[16:17], v[16:17], v[42:43]
	v_pk_mul_f32 v[20:21], v[24:25], v[20:21] op_sel_hi:[0,1]
	v_pk_fma_f32 v[20:21], v[22:23], v[20:21], v[36:37]
	v_cvt_pk_bf16_f32 v16, v16, v17
	v_pk_add_f32 v[14:15], v[20:21], v[14:15]
	s_nop 0
	v_cvt_pk_bf16_f32 v17, v14, v15
	ds_write_b64 v19, v[16:17] offset:16832
	v_add_u32_e32 v14, 0x251a0, v27
	v_add_u32_e32 v18, 0x255a0, v27
	ds_read_b64 v[24:25], v19 offset:208
	ds_read_b128 v[14:17], v14
	ds_read_b128 v[20:23], v18
	ds_read_b32 v18, v29
	ds_read_b32 v26, v30
	ds_read_b64 v[34:35], v19 offset:16848
	s_waitcnt lgkmcnt(5)
	v_lshlrev_b32_e32 v36, 16, v24
	v_and_b32_e32 v37, 0xffff0000, v24
	v_lshlrev_b32_e32 v24, 16, v25
	v_and_b32_e32 v25, 0xffff0000, v25
	s_waitcnt lgkmcnt(2)
	v_pk_add_f32 v[36:37], v[36:37], v[18:19] op_sel_hi:[1,0] neg_lo:[0,1] neg_hi:[0,1]
	v_pk_add_f32 v[24:25], v[24:25], v[18:19] op_sel_hi:[1,0] neg_lo:[0,1] neg_hi:[0,1]
	s_waitcnt lgkmcnt(1)
	v_pk_mul_f32 v[36:37], v[26:27], v[36:37] op_sel_hi:[0,1]
	v_pk_mul_f32 v[24:25], v[26:27], v[24:25] op_sel_hi:[0,1]
	v_lshlrev_b32_e32 v38, 16, v11
	v_and_b32_e32 v39, 0xffff0000, v11
	v_lshlrev_b32_e32 v40, 16, v13
	v_and_b32_e32 v41, 0xffff0000, v13
	v_pk_fma_f32 v[36:37], v[14:15], v[36:37], v[20:21]
	v_pk_fma_f32 v[24:25], v[16:17], v[24:25], v[22:23]
	v_pk_add_f32 v[36:37], v[36:37], v[38:39]
	v_pk_add_f32 v[24:25], v[24:25], v[40:41]
	v_cvt_pk_bf16_f32 v36, v36, v37
	v_cvt_pk_bf16_f32 v37, v24, v25
	ds_write_b64 v19, v[36:37] offset:208
	ds_read_b32 v18, v31
	ds_read_b32 v24, v33
	s_waitcnt lgkmcnt(3)
	v_lshlrev_b32_e32 v36, 16, v34
	v_and_b32_e32 v37, 0xffff0000, v34
	v_lshlrev_b32_e32 v38, 16, v10
	v_and_b32_e32 v39, 0xffff0000, v10
	v_lshlrev_b32_e32 v10, 16, v12
	v_and_b32_e32 v11, 0xffff0000, v12
	s_waitcnt lgkmcnt(1)
	v_pk_add_f32 v[12:13], v[36:37], v[18:19] op_sel_hi:[1,0] neg_lo:[0,1] neg_hi:[0,1]
	v_lshlrev_b32_e32 v34, 16, v35
	v_and_b32_e32 v35, 0xffff0000, v35
	s_waitcnt lgkmcnt(0)
	v_pk_mul_f32 v[12:13], v[24:25], v[12:13] op_sel_hi:[0,1]
	v_pk_fma_f32 v[12:13], v[14:15], v[12:13], v[20:21]
	v_pk_add_f32 v[14:15], v[34:35], v[18:19] op_sel_hi:[1,0] neg_lo:[0,1] neg_hi:[0,1]
	v_pk_add_f32 v[12:13], v[12:13], v[38:39]
	v_pk_mul_f32 v[14:15], v[24:25], v[14:15] op_sel_hi:[0,1]
	v_pk_fma_f32 v[14:15], v[16:17], v[14:15], v[22:23]
	v_cvt_pk_bf16_f32 v12, v12, v13
	v_pk_add_f32 v[10:11], v[14:15], v[10:11]
	s_nop 0
	v_cvt_pk_bf16_f32 v13, v10, v11
	ds_write_b64 v19, v[12:13] offset:16848
	v_add_u32_e32 v10, 0x251c0, v27
	v_add_u32_e32 v14, 0x255c0, v27
	ds_read_b64 v[20:21], v19 offset:224
	ds_read_b128 v[10:13], v10
	ds_read_b128 v[14:17], v14
	ds_read_b32 v18, v29
	ds_read_b32 v22, v30
	ds_read_b64 v[24:25], v19 offset:16864
	s_waitcnt lgkmcnt(5)
	v_lshlrev_b32_e32 v34, 16, v20
	v_and_b32_e32 v35, 0xffff0000, v20
	v_lshlrev_b32_e32 v20, 16, v21
	v_and_b32_e32 v21, 0xffff0000, v21
	s_waitcnt lgkmcnt(2)
	v_pk_add_f32 v[34:35], v[34:35], v[18:19] op_sel_hi:[1,0] neg_lo:[0,1] neg_hi:[0,1]
	v_pk_add_f32 v[20:21], v[20:21], v[18:19] op_sel_hi:[1,0] neg_lo:[0,1] neg_hi:[0,1]
	s_waitcnt lgkmcnt(1)
	v_pk_mul_f32 v[34:35], v[22:23], v[34:35] op_sel_hi:[0,1]
	v_pk_mul_f32 v[20:21], v[22:23], v[20:21] op_sel_hi:[0,1]
	v_lshlrev_b32_e32 v36, 16, v7
	v_and_b32_e32 v37, 0xffff0000, v7
	v_lshlrev_b32_e32 v38, 16, v9
	v_and_b32_e32 v39, 0xffff0000, v9
	v_pk_fma_f32 v[34:35], v[10:11], v[34:35], v[14:15]
	v_pk_fma_f32 v[20:21], v[12:13], v[20:21], v[16:17]
	v_pk_add_f32 v[34:35], v[34:35], v[36:37]
	v_pk_add_f32 v[20:21], v[20:21], v[38:39]
	v_cvt_pk_bf16_f32 v22, v34, v35
	v_cvt_pk_bf16_f32 v23, v20, v21
	ds_write_b64 v19, v[22:23] offset:224
	ds_read_b32 v18, v31
	ds_read_b32 v20, v33
	s_waitcnt lgkmcnt(3)
	v_lshlrev_b32_e32 v22, 16, v24
	v_and_b32_e32 v23, 0xffff0000, v24
	v_lshlrev_b32_e32 v34, 16, v6
	v_and_b32_e32 v35, 0xffff0000, v6
	v_lshlrev_b32_e32 v6, 16, v8
	v_and_b32_e32 v7, 0xffff0000, v8
	s_waitcnt lgkmcnt(1)
	v_pk_add_f32 v[8:9], v[22:23], v[18:19] op_sel_hi:[1,0] neg_lo:[0,1] neg_hi:[0,1]
	v_lshlrev_b32_e32 v24, 16, v25
	v_and_b32_e32 v25, 0xffff0000, v25
	s_waitcnt lgkmcnt(0)
	v_pk_mul_f32 v[8:9], v[20:21], v[8:9] op_sel_hi:[0,1]
	v_pk_fma_f32 v[8:9], v[10:11], v[8:9], v[14:15]
	v_pk_add_f32 v[10:11], v[24:25], v[18:19] op_sel_hi:[1,0] neg_lo:[0,1] neg_hi:[0,1]
	v_pk_add_f32 v[8:9], v[8:9], v[34:35]
	v_pk_mul_f32 v[10:11], v[20:21], v[10:11] op_sel_hi:[0,1]
	v_pk_fma_f32 v[10:11], v[12:13], v[10:11], v[16:17]
	v_cvt_pk_bf16_f32 v8, v8, v9
	v_pk_add_f32 v[6:7], v[10:11], v[6:7]
	s_nop 0
	v_cvt_pk_bf16_f32 v9, v6, v7
	ds_write_b64 v19, v[8:9] offset:16864
	ds_read_b128 v[6:9], v28 offset:480
	ds_read_b64 v[14:15], v19 offset:240
	ds_read_b32 v16, v29
	ds_read_b32 v18, v30
	v_add_u32_e32 v10, 0x255e0, v27
	ds_read_b128 v[10:13], v10
	s_waitcnt lgkmcnt(3)
	v_lshlrev_b32_e32 v20, 16, v14
	v_and_b32_e32 v21, 0xffff0000, v14
	v_lshlrev_b32_e32 v14, 16, v15
	v_and_b32_e32 v15, 0xffff0000, v15
	s_waitcnt lgkmcnt(2)
	v_pk_add_f32 v[20:21], v[20:21], v[16:17] op_sel_hi:[1,0] neg_lo:[0,1] neg_hi:[0,1]
	v_pk_add_f32 v[14:15], v[14:15], v[16:17] op_sel_hi:[1,0] neg_lo:[0,1] neg_hi:[0,1]
	s_waitcnt lgkmcnt(1)
	v_pk_mul_f32 v[20:21], v[18:19], v[20:21] op_sel_hi:[0,1]
	v_pk_mul_f32 v[14:15], v[18:19], v[14:15] op_sel_hi:[0,1]
	v_lshlrev_b32_e32 v22, 16, v4
	v_and_b32_e32 v23, 0xffff0000, v4
	v_lshlrev_b32_e32 v4, 16, v5
	v_and_b32_e32 v5, 0xffff0000, v5
	s_waitcnt lgkmcnt(0)
	v_pk_fma_f32 v[20:21], v[6:7], v[20:21], v[10:11]
	v_pk_fma_f32 v[14:15], v[8:9], v[14:15], v[12:13]
	v_pk_add_f32 v[20:21], v[20:21], v[22:23]
	v_pk_add_f32 v[4:5], v[14:15], v[4:5]
	v_cvt_pk_bf16_f32 v14, v20, v21
	v_cvt_pk_bf16_f32 v15, v4, v5
	ds_write_b64 v19, v[14:15] offset:240
	ds_read_b32 v4, v33
	ds_read_b64 v[14:15], v19 offset:16880
	ds_read_b32 v16, v31
	v_lshlrev_b32_e32 v22, 16, v2
	v_and_b32_e32 v23, 0xffff0000, v2
	v_lshlrev_b32_e32 v2, 16, v3
	s_waitcnt lgkmcnt(1)
	v_lshlrev_b32_e32 v20, 16, v14
	v_and_b32_e32 v21, 0xffff0000, v14
	s_waitcnt lgkmcnt(0)
	v_pk_add_f32 v[20:21], v[20:21], v[16:17] op_sel_hi:[1,0] neg_lo:[0,1] neg_hi:[0,1]
	v_lshlrev_b32_e32 v14, 16, v15
	v_and_b32_e32 v15, 0xffff0000, v15
	v_pk_mul_f32 v[20:21], v[4:5], v[20:21] op_sel_hi:[0,1]
	v_pk_fma_f32 v[6:7], v[6:7], v[20:21], v[10:11]
	v_pk_add_f32 v[10:11], v[14:15], v[16:17] op_sel_hi:[1,0] neg_lo:[0,1] neg_hi:[0,1]
	v_and_b32_e32 v3, 0xffff0000, v3
	v_pk_mul_f32 v[4:5], v[4:5], v[10:11] op_sel_hi:[0,1]
	v_pk_fma_f32 v[4:5], v[8:9], v[4:5], v[12:13]
	v_pk_add_f32 v[6:7], v[6:7], v[22:23]
	v_pk_add_f32 v[2:3], v[4:5], v[2:3]
	v_cvt_pk_bf16_f32 v4, v6, v7
	v_cvt_pk_bf16_f32 v5, v2, v3
	ds_write_b64 v19, v[4:5] offset:16880
	s_add_u32 s24, s80, s24
	s_addc_u32 s25, s81, s25
	v_lshl_add_u64 v[8:9], s[24:25], 0, v[0:1]
	v_mov_b32_e32 v0, v192
	s_waitcnt lgkmcnt(0)
	s_barrier
; DI int otid() { int t = threadIdx.x; asm volatile("" : "+v"(t)); return t; }
; DI void stg16_nt(void* p, u32x4 v) { __builtin_nontemporal_store(v, (u32x4*)p); }
; DI void stage_store_tile(const bf16_t* stg, bf16_t* tilebase) {
;   const int tid = otid();
;   const int r0 = tid >> 5, c = tid & 31;
;   const unsigned o0 = (unsigned)(r0 * 1024 + c * 8);
; #pragma unroll
;   for (int it = 0; it < 16; ++it) stg16_nt(tilebase + (o0 + (unsigned)(it * 16 * 1024)), stage_read16(stg, r0 + 16 * it, c));
; }
; template <bool LAST>
; DI void phase_gate(const Params& P, int layer, unsigned char* smem, int L, int G) {
;     ...
;     if (!LAST) stage_store_tile(stg, xb + (size_t)mt * 256 * 1024 + nt * 256);
;     __syncthreads();
	s_add_i32 s36, s36, s74
	v_ashrrev_i32_e32 v4, 5, v0
	v_and_b32_e32 v0, 31, v0
	v_mul_lo_u32 v1, v4, s44
	v_lshl_add_u32 v12, v0, 4, v1
	v_lshlrev_b32_e32 v5, 3, v0
	ds_read2_b64 v[0:3], v12 offset1:1
	v_lshl_or_b32 v160, v4, 10, v5
	v_add_u32_e32 v4, 0x2080, v12
	ds_read2_b64 v[4:7], v4 offset1:1
	v_lshl_add_u64 v[10:11], v[160:161], 1, v[8:9]
	s_waitcnt lgkmcnt(1)
	global_store_dwordx4 v[10:11], v[0:3], off
	s_add_i32 s33, s33, s69
	s_add_i32 s34, s34, s35
	v_add_u32_e32 v0, 0x4000, v160
	v_mov_b32_e32 v1, v161
	v_lshl_add_u64 v[0:1], v[0:1], 1, v[8:9]
	s_waitcnt lgkmcnt(0)
	global_store_dwordx4 v[0:1], v[4:7], off
	v_add_u32_e32 v0, 0x4100, v12
	ds_read2_b64 v[0:3], v0 offset1:1
	v_add_u32_e32 v4, 0x8000, v160
	v_mov_b32_e32 v5, v161
	v_lshl_add_u64 v[10:11], v[4:5], 1, v[8:9]
	v_add_u32_e32 v4, 0x6180, v12
	ds_read2_b64 v[4:7], v4 offset1:1
	s_waitcnt lgkmcnt(1)
	global_store_dwordx4 v[10:11], v[0:3], off
	s_add_i32 s24, s70, s36
	s_cmpk_lt_i32 s24, 0x400
	v_add_u32_e32 v0, 0xc000, v160
	v_mov_b32_e32 v1, v161
	v_lshl_add_u64 v[0:1], v[0:1], 1, v[8:9]
	s_waitcnt lgkmcnt(0)
	global_store_dwordx4 v[0:1], v[4:7], off
	v_add_u32_e32 v0, 0x8200, v12
	ds_read2_b64 v[0:3], v0 offset1:1
	v_add_u32_e32 v4, 0x10000, v160
	v_mov_b32_e32 v5, v161
	v_lshl_add_u64 v[10:11], v[4:5], 1, v[8:9]
	v_add_u32_e32 v4, 0xa280, v12
	ds_read2_b64 v[4:7], v4 offset1:1
	s_waitcnt lgkmcnt(1)
	global_store_dwordx4 v[10:11], v[0:3], off
	s_nop 1
	v_add_u32_e32 v0, 0x14000, v160
	v_mov_b32_e32 v1, v161
	v_lshl_add_u64 v[0:1], v[0:1], 1, v[8:9]
	s_waitcnt lgkmcnt(0)
	global_store_dwordx4 v[0:1], v[4:7], off
	v_add_u32_e32 v0, 0xc300, v12
	ds_read2_b64 v[0:3], v0 offset1:1
	v_add_u32_e32 v4, 0x18000, v160
	v_mov_b32_e32 v5, v161
	v_lshl_add_u64 v[10:11], v[4:5], 1, v[8:9]
	v_add_u32_e32 v4, 0xe380, v12
	ds_read2_b64 v[4:7], v4 offset1:1
	s_waitcnt lgkmcnt(1)
	global_store_dwordx4 v[10:11], v[0:3], off
	s_nop 1
	v_add_u32_e32 v0, 0x1c000, v160
	v_mov_b32_e32 v1, v161
	v_lshl_add_u64 v[0:1], v[0:1], 1, v[8:9]
	s_waitcnt lgkmcnt(0)
	global_store_dwordx4 v[0:1], v[4:7], off
	v_add_u32_e32 v0, 0x10400, v12
	ds_read2_b64 v[0:3], v0 offset1:1
	v_add_u32_e32 v4, 0x20000, v160
	v_mov_b32_e32 v5, v161
	v_lshl_add_u64 v[10:11], v[4:5], 1, v[8:9]
	v_add_u32_e32 v4, 0x12480, v12
	ds_read2_b64 v[4:7], v4 offset1:1
	s_waitcnt lgkmcnt(1)
	global_store_dwordx4 v[10:11], v[0:3], off
	s_nop 1
	v_add_u32_e32 v0, 0x24000, v160
	v_mov_b32_e32 v1, v161
	v_lshl_add_u64 v[0:1], v[0:1], 1, v[8:9]
	s_waitcnt lgkmcnt(0)
	global_store_dwordx4 v[0:1], v[4:7], off
	v_add_u32_e32 v0, 0x14500, v12
	ds_read2_b64 v[0:3], v0 offset1:1
	v_add_u32_e32 v4, 0x28000, v160
	v_mov_b32_e32 v5, v161
	v_lshl_add_u64 v[10:11], v[4:5], 1, v[8:9]
	v_add_u32_e32 v4, 0x16580, v12
	ds_read2_b64 v[4:7], v4 offset1:1
	s_waitcnt lgkmcnt(1)
	global_store_dwordx4 v[10:11], v[0:3], off
	s_nop 1
	v_add_u32_e32 v0, 0x2c000, v160
	v_mov_b32_e32 v1, v161
	v_lshl_add_u64 v[0:1], v[0:1], 1, v[8:9]
	s_waitcnt lgkmcnt(0)
	global_store_dwordx4 v[0:1], v[4:7], off
	v_add_u32_e32 v0, 0x18600, v12
	ds_read2_b64 v[0:3], v0 offset1:1
	v_add_u32_e32 v4, 0x30000, v160
	v_mov_b32_e32 v5, v161
	v_lshl_add_u64 v[10:11], v[4:5], 1, v[8:9]
	v_add_u32_e32 v4, 0x1a680, v12
	ds_read2_b64 v[4:7], v4 offset1:1
	s_waitcnt lgkmcnt(1)
	global_store_dwordx4 v[10:11], v[0:3], off
	v_add_u32_e32 v10, 0x38000, v160
	v_mov_b32_e32 v11, v161
	v_add_u32_e32 v0, 0x34000, v160
	v_mov_b32_e32 v1, v161
	v_lshl_add_u64 v[0:1], v[0:1], 1, v[8:9]
	s_waitcnt lgkmcnt(0)
	global_store_dwordx4 v[0:1], v[4:7], off
	v_add_u32_e32 v0, 0x1c700, v12
	ds_read2_b64 v[0:3], v0 offset1:1
	v_add_u32_e32 v4, 0x1e780, v12
	ds_read2_b64 v[4:7], v4 offset1:1
	v_lshl_add_u64 v[10:11], v[10:11], 1, v[8:9]
	v_add_u32_e32 v160, 0x3c000, v160
	s_waitcnt lgkmcnt(1)
	global_store_dwordx4 v[10:11], v[0:3], off
	s_nop 1
	v_lshl_add_u64 v[0:1], v[160:161], 1, v[8:9]
	s_waitcnt lgkmcnt(0)
	global_store_dwordx4 v[0:1], v[4:7], off
	s_barrier
	s_cbranch_scc0 .LBB0_488

; DI void stg16_nt(void* p, u32x4 v) { __builtin_nontemporal_store(v, (u32x4*)p); }
; DI void epi_seg(const f32x16 (&acc)[4][2], const Seg& sg0, const Seg& sg1, int m0, int n0, const float* rs, const float2* cs64, const float2* cs32, bf16_t* stg) {
;     ...
; #pragma unroll
;   for (int it = 0; it < 16; ++it) {
;     const int idx = tid + NTHR * it, rr = idx >> 5, c = idx & 31;
;     const Seg& fs = (c >> 4) ? sg1 : sg0;
;     const int lcc = n0 + c * 8 - fs.cbase;
;     if (fs.kind != K_NONE && lcc < fs.nvalid) {
;       const int row = m0 + rr;
;       size_t off;
;       if (fs.kind == K_KC2) { const int b = row >> 9, n = (row >> 2) & 127, g = row & 3; off = ((size_t)((b * 4 + g) * 128 + n)) * 64 + lcc; }
;       else off = (size_t)row * fs.ld + lcc;
;       stg16_nt(fs.dst + off, stage_read16(stg, rr, c));
;     }
;   }
.LBB0_578:
	s_or_b64 exec, exec, s[46:47]
	s_waitcnt lgkmcnt(0)
	v_and_b32_e32 v1, 31, v170
	v_mov_b32_e32 v2, s60
	v_mov_b32_e32 v3, s57
	v_cmp_gt_u32_e32 vcc, 16, v1
	v_lshl_or_b32 v0, v1, 3, s62
	s_nop 0
	v_cndmask_b32_e32 v2, v2, v3, vcc
	v_sub_u32_e32 v0, v0, v2
	v_mov_b32_e32 v2, s59
	v_mov_b32_e32 v3, s37
	v_cndmask_b32_e32 v2, v2, v3, vcc
	v_cmp_lt_i32_e64 s[0:1], v0, v2
	s_barrier
	s_and_saveexec_b64 s[2:3], s[0:1]
	s_cbranch_execz .LBB0_544
	v_ashrrev_i32_e32 v4, 5, v170
	v_mov_b32_e32 v2, s34
	v_mov_b32_e32 v3, s36
	v_mov_b32_e32 v5, s39
	v_mov_b32_e32 v6, s31
	v_lshlrev_b32_e32 v8, 4, v1
	v_add_u32_e32 v1, s35, v4
	v_cndmask_b32_e32 v9, v2, v3, vcc
	v_cndmask_b32_e32 v11, v5, v6, vcc
	v_mov_b32_e32 v5, s38
	v_mov_b32_e32 v6, s30
	v_mad_i64_i32 v[2:3], s[0:1], v9, v1, 0
	v_ashrrev_i32_e32 v1, 31, v0
	v_cndmask_b32_e32 v10, v5, v6, vcc
	v_lshl_add_u64 v[2:3], v[2:3], 1, v[10:11]
	v_lshlrev_b64 v[12:13], 1, v[0:1]
	v_mad_u64_u32 v[0:1], s[0:1], v4, s55, v[8:9]
	v_lshl_add_u64 v[14:15], v[2:3], 0, v[12:13]
	ds_read2_b64 v[0:3], v0 offset1:1
	v_add_u32_e32 v4, 0x200, v170
	v_ashrrev_i32_e32 v16, 5, v4
	v_mad_u64_u32 v[4:5], s[0:1], v16, s55, v[8:9]
	ds_read2_b64 v[4:7], v4 offset1:1
	s_waitcnt lgkmcnt(1)
	global_store_dwordx4 v[14:15], v[0:3], off
	s_nop 1
	v_add_u32_e32 v0, s35, v16
	v_mad_i64_i32 v[0:1], s[0:1], v9, v0, 0
	v_lshl_add_u64 v[0:1], v[0:1], 1, v[10:11]
	v_lshl_add_u64 v[0:1], v[0:1], 0, v[12:13]
	s_waitcnt lgkmcnt(0)
	global_store_dwordx4 v[0:1], v[4:7], off
	v_add_u32_e32 v0, 0x400, v170
	v_ashrrev_i32_e32 v2, 5, v0
	v_add_u32_e32 v0, s35, v2
	v_mad_i64_i32 v[0:1], s[0:1], v9, v0, 0
	v_lshl_add_u64 v[0:1], v[0:1], 1, v[10:11]
	v_lshl_add_u64 v[14:15], v[0:1], 0, v[12:13]
	v_mad_u64_u32 v[0:1], s[0:1], v2, s55, v[8:9]
	ds_read2_b64 v[0:3], v0 offset1:1
	v_add_u32_e32 v4, 0x600, v170
	v_ashrrev_i32_e32 v16, 5, v4
	v_mad_u64_u32 v[4:5], s[0:1], v16, s55, v[8:9]
	ds_read2_b64 v[4:7], v4 offset1:1
	s_waitcnt lgkmcnt(1)
	global_store_dwordx4 v[14:15], v[0:3], off
	s_nop 1
	v_add_u32_e32 v0, s35, v16
	v_mad_i64_i32 v[0:1], s[0:1], v9, v0, 0
	v_lshl_add_u64 v[0:1], v[0:1], 1, v[10:11]
	v_lshl_add_u64 v[0:1], v[0:1], 0, v[12:13]
	s_waitcnt lgkmcnt(0)
	global_store_dwordx4 v[0:1], v[4:7], off
	v_add_u32_e32 v0, 0x800, v170
	v_ashrrev_i32_e32 v2, 5, v0
	v_add_u32_e32 v0, s35, v2
	v_mad_i64_i32 v[0:1], s[0:1], v9, v0, 0
	v_lshl_add_u64 v[0:1], v[0:1], 1, v[10:11]
	v_lshl_add_u64 v[14:15], v[0:1], 0, v[12:13]
	v_mad_u64_u32 v[0:1], s[0:1], v2, s55, v[8:9]
	ds_read2_b64 v[0:3], v0 offset1:1
	v_add_u32_e32 v4, 0xa00, v170
	v_ashrrev_i32_e32 v16, 5, v4
	v_mad_u64_u32 v[4:5], s[0:1], v16, s55, v[8:9]
	ds_read2_b64 v[4:7], v4 offset1:1
	s_waitcnt lgkmcnt(1)
	global_store_dwordx4 v[14:15], v[0:3], off
	s_nop 1
	v_add_u32_e32 v0, s35, v16
	v_mad_i64_i32 v[0:1], s[0:1], v9, v0, 0
	v_lshl_add_u64 v[0:1], v[0:1], 1, v[10:11]
	v_lshl_add_u64 v[0:1], v[0:1], 0, v[12:13]
	s_waitcnt lgkmcnt(0)
	global_store_dwordx4 v[0:1], v[4:7], off
	v_add_u32_e32 v0, 0xc00, v170
	v_ashrrev_i32_e32 v2, 5, v0
	v_add_u32_e32 v0, s35, v2
	v_mad_i64_i32 v[0:1], s[0:1], v9, v0, 0
	v_lshl_add_u64 v[0:1], v[0:1], 1, v[10:11]
	v_lshl_add_u64 v[14:15], v[0:1], 0, v[12:13]
	v_mad_u64_u32 v[0:1], s[0:1], v2, s55, v[8:9]
	ds_read2_b64 v[0:3], v0 offset1:1
	v_add_u32_e32 v4, 0xe00, v170
	v_ashrrev_i32_e32 v16, 5, v4
	v_mad_u64_u32 v[4:5], s[0:1], v16, s55, v[8:9]
	ds_read2_b64 v[4:7], v4 offset1:1
	s_waitcnt lgkmcnt(1)
	global_store_dwordx4 v[14:15], v[0:3], off
	s_nop 1
	v_add_u32_e32 v0, s35, v16
	v_mad_i64_i32 v[0:1], s[0:1], v9, v0, 0
	v_lshl_add_u64 v[0:1], v[0:1], 1, v[10:11]
	v_lshl_add_u64 v[0:1], v[0:1], 0, v[12:13]
	s_waitcnt lgkmcnt(0)
	global_store_dwordx4 v[0:1], v[4:7], off
	v_add_u32_e32 v0, 0x1000, v170
	v_ashrrev_i32_e32 v2, 5, v0
	v_add_u32_e32 v0, s35, v2
	v_mad_i64_i32 v[0:1], s[0:1], v9, v0, 0
	v_lshl_add_u64 v[0:1], v[0:1], 1, v[10:11]
	v_lshl_add_u64 v[14:15], v[0:1], 0, v[12:13]
	v_mad_u64_u32 v[0:1], s[0:1], v2, s55, v[8:9]
	ds_read2_b64 v[0:3], v0 offset1:1
	v_add_u32_e32 v4, 0x1200, v170
	v_ashrrev_i32_e32 v16, 5, v4
	v_mad_u64_u32 v[4:5], s[0:1], v16, s55, v[8:9]
	ds_read2_b64 v[4:7], v4 offset1:1
	s_waitcnt lgkmcnt(1)
	global_store_dwordx4 v[14:15], v[0:3], off
	s_nop 1
	v_add_u32_e32 v0, s35, v16
	v_mad_i64_i32 v[0:1], s[0:1], v9, v0, 0
	v_lshl_add_u64 v[0:1], v[0:1], 1, v[10:11]
	v_lshl_add_u64 v[0:1], v[0:1], 0, v[12:13]
	s_waitcnt lgkmcnt(0)
	global_store_dwordx4 v[0:1], v[4:7], off
	v_add_u32_e32 v0, 0x1400, v170
	v_ashrrev_i32_e32 v2, 5, v0
	v_add_u32_e32 v0, s35, v2
	v_mad_i64_i32 v[0:1], s[0:1], v9, v0, 0
	v_lshl_add_u64 v[0:1], v[0:1], 1, v[10:11]
	v_lshl_add_u64 v[14:15], v[0:1], 0, v[12:13]
	v_mad_u64_u32 v[0:1], s[0:1], v2, s55, v[8:9]
	ds_read2_b64 v[0:3], v0 offset1:1
	v_add_u32_e32 v4, 0x1600, v170
	v_ashrrev_i32_e32 v16, 5, v4
	v_mad_u64_u32 v[4:5], s[0:1], v16, s55, v[8:9]
	ds_read2_b64 v[4:7], v4 offset1:1
	s_waitcnt lgkmcnt(1)
	global_store_dwordx4 v[14:15], v[0:3], off
	s_nop 1
	v_add_u32_e32 v0, s35, v16
	v_mad_i64_i32 v[0:1], s[0:1], v9, v0, 0
	v_lshl_add_u64 v[0:1], v[0:1], 1, v[10:11]
	v_lshl_add_u64 v[0:1], v[0:1], 0, v[12:13]
	s_waitcnt lgkmcnt(0)
	global_store_dwordx4 v[0:1], v[4:7], off
	v_add_u32_e32 v0, 0x1800, v170
	v_ashrrev_i32_e32 v2, 5, v0
	v_add_u32_e32 v0, s35, v2
	v_mad_i64_i32 v[0:1], s[0:1], v9, v0, 0
	v_lshl_add_u64 v[0:1], v[0:1], 1, v[10:11]
	v_lshl_add_u64 v[14:15], v[0:1], 0, v[12:13]
	v_mad_u64_u32 v[0:1], s[0:1], v2, s55, v[8:9]
	ds_read2_b64 v[0:3], v0 offset1:1
	v_add_u32_e32 v4, 0x1a00, v170
	v_ashrrev_i32_e32 v16, 5, v4
	v_mad_u64_u32 v[4:5], s[0:1], v16, s55, v[8:9]
	ds_read2_b64 v[4:7], v4 offset1:1
	s_waitcnt lgkmcnt(1)
	global_store_dwordx4 v[14:15], v[0:3], off
	s_nop 1
	v_add_u32_e32 v0, s35, v16
	v_mad_i64_i32 v[0:1], s[0:1], v9, v0, 0
	v_lshl_add_u64 v[0:1], v[0:1], 1, v[10:11]
	v_lshl_add_u64 v[0:1], v[0:1], 0, v[12:13]
	s_waitcnt lgkmcnt(0)
	global_store_dwordx4 v[0:1], v[4:7], off
	v_add_u32_e32 v0, 0x1c00, v170
	v_ashrrev_i32_e32 v2, 5, v0
	v_add_u32_e32 v0, s35, v2
	v_mad_i64_i32 v[0:1], s[0:1], v9, v0, 0
	v_lshl_add_u64 v[0:1], v[0:1], 1, v[10:11]
	v_lshl_add_u64 v[14:15], v[0:1], 0, v[12:13]
	v_mad_u64_u32 v[0:1], s[0:1], v2, s55, v[8:9]
	ds_read2_b64 v[0:3], v0 offset1:1
	v_add_u32_e32 v4, 0x1e00, v170
	v_ashrrev_i32_e32 v16, 5, v4
	v_mad_u64_u32 v[4:5], s[0:1], v16, s55, v[8:9]
	ds_read2_b64 v[4:7], v4 offset1:1
	s_waitcnt lgkmcnt(1)
	global_store_dwordx4 v[14:15], v[0:3], off
	s_nop 1
	v_add_u32_e32 v0, s35, v16
	v_mad_i64_i32 v[0:1], s[0:1], v9, v0, 0
	v_lshl_add_u64 v[0:1], v[0:1], 1, v[10:11]
	v_lshl_add_u64 v[0:1], v[0:1], 0, v[12:13]
	s_waitcnt lgkmcnt(0)
	global_store_dwordx4 v[0:1], v[4:7], off
	s_branch .LBB0_544

; DI unsigned pack2(float a, float b) { f32x2_t v = {a, b}; bf16x2_t r = __builtin_convertvector(v, bf16x2_t); return __builtin_bit_cast(unsigned, r); }
; DI void stg16_nt(void* p, u32x4 v) { __builtin_nontemporal_store(v, (u32x4*)p); }
; DI void epi_seg(const f32x16 (&acc)[4][2], const Seg& sg0, const Seg& sg1, int m0, int n0, const float* rs, const float2* cs64, const float2* cs32, bf16_t* stg) {
;     ...
;   if (kind0 == K_VT) {
; #pragma unroll
;     for (int i = 0; i < 4; ++i)
; #pragma unroll
;       for (int q4 = 0; q4 < 4; ++q4) {
;         const int t0l = wm * 128 + i * 32 + 8 * q4 + 4 * h;
;         float s0 = 1.f, s1 = 1.f, s2 = 1.f, s3 = 1.f;
;         if (rs) { s0 = rs[t0l]; s1 = rs[t0l + 1]; s2 = rs[t0l + 2]; s3 = rs[t0l + 3]; }
; #pragma unroll
;         for (int j = 0; j < 2; ++j)
;           *(uint2*)(stg + (wn * 64 + j * 32 + r) * STG + t0l) =
;               make_uint2(pack2(acc[i][j][4 * q4] * s0, acc[i][j][4 * q4 + 1] * s1), pack2(acc[i][j][4 * q4 + 2] * s2, acc[i][j][4 * q4 + 3] * s3));
;       }
;     __syncthreads();
;     const int b = m0 >> 11, s0 = m0 & (SEQ - 1);
; #pragma unroll
;     for (int it = 0; it < 16; ++it) {
;       const int idx = tid + NTHR * it, rr = idx >> 5, c = idx & 31;
;       const int lc = n0 + rr - sg0.cbase, g = lc >> 6, d = lc & 63;
;       stg16_nt(sg0.dst + ((size_t)((b * sg0.G + g) * 64 + d)) * SEQ + s0 + c * 8, stage_read16(stg, rr, c));
.LBB0_634:
	s_lshl_b32 s0, s22, 3
	s_andn2_b32 s0, s0, 63
	s_waitcnt lgkmcnt(0)
	v_pk_mul_f32 v[4:5], v[28:29], v[0:1]
	v_pk_mul_f32 v[6:7], v[30:31], v[2:3]
	v_pk_mul_f32 v[0:1], v[12:13], v[0:1]
	v_pk_mul_f32 v[2:3], v[14:15], v[2:3]
	s_mul_i32 s0, s61, s0
	s_sub_i32 s10, s37, s60
	v_cvt_pk_bf16_f32 v0, v0, v1
	v_cvt_pk_bf16_f32 v1, v2, v3
	v_ashrrev_i32_e32 v2, 5, v139
	s_add_i32 s0, s0, s10
	ds_write_b64 v112, v[0:1] offset:16880
	v_add_u32_e32 v0, s0, v2
	v_ashrrev_i32_e32 v1, 31, v0
	s_and_b32 s1, s62, 0x700
	v_lshlrev_b64 v[0:1], 12, v[0:1]
	v_lshl_add_u64 v[0:1], s[38:39], 0, v[0:1]
	s_lshl_b32 s22, s1, 1
	v_lshlrev_b32_e32 v136, 4, v181
	v_lshl_add_u64 v[0:1], v[0:1], 0, s[22:23]
	v_cvt_pk_bf16_f32 v4, v4, v5
	v_cvt_pk_bf16_f32 v5, v6, v7
	v_lshl_add_u64 v[8:9], v[0:1], 0, v[136:137]
	v_mad_u64_u32 v[0:1], s[10:11], v2, s58, v[136:137]
	ds_write_b64 v112, v[4:5] offset:240
	s_waitcnt lgkmcnt(0)
	s_barrier
; DI void stg16_nt(void* p, u32x4 v) { __builtin_nontemporal_store(v, (u32x4*)p); }
; DI void epi_seg(const f32x16 (&acc)[4][2], const Seg& sg0, const Seg& sg1, int m0, int n0, const float* rs, const float2* cs64, const float2* cs32, bf16_t* stg) {
;     ...
; #pragma unroll
;     for (int it = 0; it < 16; ++it) {
;       const int idx = tid + NTHR * it, rr = idx >> 5, c = idx & 31;
;       const int lc = n0 + rr - sg0.cbase, g = lc >> 6, d = lc & 63;
;       stg16_nt(sg0.dst + ((size_t)((b * sg0.G + g) * 64 + d)) * SEQ + s0 + c * 8, stage_read16(stg, rr, c));
;     }
;     __syncthreads();
	ds_read2_b64 v[0:3], v0 offset1:1
	v_add_u32_e32 v4, 0x200, v139
	v_ashrrev_i32_e32 v10, 5, v4
	v_mad_u64_u32 v[4:5], s[10:11], v10, s58, v[136:137]
	ds_read2_b64 v[4:7], v4 offset1:1
	s_waitcnt lgkmcnt(1)
	global_store_dwordx4 v[8:9], v[0:3], off
	s_nop 1
	v_add_u32_e32 v0, s0, v10
	v_ashrrev_i32_e32 v1, 31, v0
	v_lshlrev_b64 v[0:1], 12, v[0:1]
	v_lshl_add_u64 v[0:1], s[38:39], 0, v[0:1]
	v_lshl_add_u64 v[0:1], v[0:1], 0, s[22:23]
	v_lshl_add_u64 v[0:1], v[0:1], 0, v[136:137]
	s_waitcnt lgkmcnt(0)
	global_store_dwordx4 v[0:1], v[4:7], off
	v_add_u32_e32 v0, 0x400, v139
	v_ashrrev_i32_e32 v2, 5, v0
	v_add_u32_e32 v0, s0, v2
	v_ashrrev_i32_e32 v1, 31, v0
	v_lshlrev_b64 v[0:1], 12, v[0:1]
	v_lshl_add_u64 v[0:1], s[38:39], 0, v[0:1]
	v_lshl_add_u64 v[0:1], v[0:1], 0, s[22:23]
	v_lshl_add_u64 v[8:9], v[0:1], 0, v[136:137]
	v_mad_u64_u32 v[0:1], s[10:11], v2, s58, v[136:137]
	ds_read2_b64 v[0:3], v0 offset1:1
	v_add_u32_e32 v4, 0x600, v139
	v_ashrrev_i32_e32 v10, 5, v4
	v_mad_u64_u32 v[4:5], s[10:11], v10, s58, v[136:137]
	ds_read2_b64 v[4:7], v4 offset1:1
	s_waitcnt lgkmcnt(1)
	global_store_dwordx4 v[8:9], v[0:3], off
	s_nop 1
	v_add_u32_e32 v0, s0, v10
	v_ashrrev_i32_e32 v1, 31, v0
	v_lshlrev_b64 v[0:1], 12, v[0:1]
	v_lshl_add_u64 v[0:1], s[38:39], 0, v[0:1]
	v_lshl_add_u64 v[0:1], v[0:1], 0, s[22:23]
	v_lshl_add_u64 v[0:1], v[0:1], 0, v[136:137]
	s_waitcnt lgkmcnt(0)
	global_store_dwordx4 v[0:1], v[4:7], off
	v_add_u32_e32 v0, 0x800, v139
	v_ashrrev_i32_e32 v2, 5, v0
	v_add_u32_e32 v0, s0, v2
	v_ashrrev_i32_e32 v1, 31, v0
	v_lshlrev_b64 v[0:1], 12, v[0:1]
	v_lshl_add_u64 v[0:1], s[38:39], 0, v[0:1]
	v_lshl_add_u64 v[0:1], v[0:1], 0, s[22:23]
	v_lshl_add_u64 v[8:9], v[0:1], 0, v[136:137]
	v_mad_u64_u32 v[0:1], s[10:11], v2, s58, v[136:137]
	ds_read2_b64 v[0:3], v0 offset1:1
	v_add_u32_e32 v4, 0xa00, v139
	v_ashrrev_i32_e32 v10, 5, v4
	v_mad_u64_u32 v[4:5], s[10:11], v10, s58, v[136:137]
	ds_read2_b64 v[4:7], v4 offset1:1
	s_waitcnt lgkmcnt(1)
	global_store_dwordx4 v[8:9], v[0:3], off
	s_nop 1
	v_add_u32_e32 v0, s0, v10
	v_ashrrev_i32_e32 v1, 31, v0
	v_lshlrev_b64 v[0:1], 12, v[0:1]
	v_lshl_add_u64 v[0:1], s[38:39], 0, v[0:1]
	v_lshl_add_u64 v[0:1], v[0:1], 0, s[22:23]
	v_lshl_add_u64 v[0:1], v[0:1], 0, v[136:137]
	s_waitcnt lgkmcnt(0)
	global_store_dwordx4 v[0:1], v[4:7], off
	v_add_u32_e32 v0, 0xc00, v139
	v_ashrrev_i32_e32 v2, 5, v0
	v_add_u32_e32 v0, s0, v2
	v_ashrrev_i32_e32 v1, 31, v0
	v_lshlrev_b64 v[0:1], 12, v[0:1]
	v_lshl_add_u64 v[0:1], s[38:39], 0, v[0:1]
	v_lshl_add_u64 v[0:1], v[0:1], 0, s[22:23]
	v_lshl_add_u64 v[8:9], v[0:1], 0, v[136:137]
	v_mad_u64_u32 v[0:1], s[10:11], v2, s58, v[136:137]
	ds_read2_b64 v[0:3], v0 offset1:1
	v_add_u32_e32 v4, 0xe00, v139
	v_ashrrev_i32_e32 v10, 5, v4
	v_mad_u64_u32 v[4:5], s[10:11], v10, s58, v[136:137]
	ds_read2_b64 v[4:7], v4 offset1:1
	s_waitcnt lgkmcnt(1)
	global_store_dwordx4 v[8:9], v[0:3], off
	s_nop 1
	v_add_u32_e32 v0, s0, v10
	v_ashrrev_i32_e32 v1, 31, v0
	v_lshlrev_b64 v[0:1], 12, v[0:1]
	v_lshl_add_u64 v[0:1], s[38:39], 0, v[0:1]
	v_lshl_add_u64 v[0:1], v[0:1], 0, s[22:23]
	v_lshl_add_u64 v[0:1], v[0:1], 0, v[136:137]
	s_waitcnt lgkmcnt(0)
	global_store_dwordx4 v[0:1], v[4:7], off
	v_add_u32_e32 v0, 0x1000, v139
	v_ashrrev_i32_e32 v2, 5, v0
	v_add_u32_e32 v0, s0, v2
	v_ashrrev_i32_e32 v1, 31, v0
	v_lshlrev_b64 v[0:1], 12, v[0:1]
	v_lshl_add_u64 v[0:1], s[38:39], 0, v[0:1]
	v_lshl_add_u64 v[0:1], v[0:1], 0, s[22:23]
	v_lshl_add_u64 v[8:9], v[0:1], 0, v[136:137]
	v_mad_u64_u32 v[0:1], s[10:11], v2, s58, v[136:137]
	ds_read2_b64 v[0:3], v0 offset1:1
	v_add_u32_e32 v4, 0x1200, v139
	v_ashrrev_i32_e32 v10, 5, v4
	v_mad_u64_u32 v[4:5], s[10:11], v10, s58, v[136:137]
	ds_read2_b64 v[4:7], v4 offset1:1
	s_waitcnt lgkmcnt(1)
	global_store_dwordx4 v[8:9], v[0:3], off
	s_nop 1
	v_add_u32_e32 v0, s0, v10
	v_ashrrev_i32_e32 v1, 31, v0
	v_lshlrev_b64 v[0:1], 12, v[0:1]
	v_lshl_add_u64 v[0:1], s[38:39], 0, v[0:1]
	v_lshl_add_u64 v[0:1], v[0:1], 0, s[22:23]
	v_lshl_add_u64 v[0:1], v[0:1], 0, v[136:137]
	s_waitcnt lgkmcnt(0)
	global_store_dwordx4 v[0:1], v[4:7], off
	v_add_u32_e32 v0, 0x1400, v139
	v_ashrrev_i32_e32 v2, 5, v0
	v_add_u32_e32 v0, s0, v2
	v_ashrrev_i32_e32 v1, 31, v0
	v_lshlrev_b64 v[0:1], 12, v[0:1]
	v_lshl_add_u64 v[0:1], s[38:39], 0, v[0:1]
	v_lshl_add_u64 v[0:1], v[0:1], 0, s[22:23]
	v_lshl_add_u64 v[8:9], v[0:1], 0, v[136:137]
	v_mad_u64_u32 v[0:1], s[10:11], v2, s58, v[136:137]
	ds_read2_b64 v[0:3], v0 offset1:1
	v_add_u32_e32 v4, 0x1600, v139
	v_ashrrev_i32_e32 v10, 5, v4
	v_mad_u64_u32 v[4:5], s[10:11], v10, s58, v[136:137]
	ds_read2_b64 v[4:7], v4 offset1:1
	s_waitcnt lgkmcnt(1)
	global_store_dwordx4 v[8:9], v[0:3], off
	s_nop 1
	v_add_u32_e32 v0, s0, v10
	v_ashrrev_i32_e32 v1, 31, v0
	v_lshlrev_b64 v[0:1], 12, v[0:1]
	v_lshl_add_u64 v[0:1], s[38:39], 0, v[0:1]
	v_lshl_add_u64 v[0:1], v[0:1], 0, s[22:23]
	v_lshl_add_u64 v[0:1], v[0:1], 0, v[136:137]
	s_waitcnt lgkmcnt(0)
	global_store_dwordx4 v[0:1], v[4:7], off
	v_add_u32_e32 v0, 0x1800, v139
	v_ashrrev_i32_e32 v2, 5, v0
	v_add_u32_e32 v0, s0, v2
	v_ashrrev_i32_e32 v1, 31, v0
	v_lshlrev_b64 v[0:1], 12, v[0:1]
	v_lshl_add_u64 v[0:1], s[38:39], 0, v[0:1]
	v_lshl_add_u64 v[0:1], v[0:1], 0, s[22:23]
	v_lshl_add_u64 v[8:9], v[0:1], 0, v[136:137]
	v_mad_u64_u32 v[0:1], s[10:11], v2, s58, v[136:137]
	ds_read2_b64 v[0:3], v0 offset1:1
	v_add_u32_e32 v4, 0x1a00, v139
	v_ashrrev_i32_e32 v10, 5, v4
	v_mad_u64_u32 v[4:5], s[10:11], v10, s58, v[136:137]
	ds_read2_b64 v[4:7], v4 offset1:1
	s_waitcnt lgkmcnt(1)
	global_store_dwordx4 v[8:9], v[0:3], off
	s_nop 1
	v_add_u32_e32 v0, s0, v10
	v_ashrrev_i32_e32 v1, 31, v0
	v_lshlrev_b64 v[0:1], 12, v[0:1]
	v_lshl_add_u64 v[0:1], s[38:39], 0, v[0:1]
	v_lshl_add_u64 v[0:1], v[0:1], 0, s[22:23]
	v_lshl_add_u64 v[0:1], v[0:1], 0, v[136:137]
	s_waitcnt lgkmcnt(0)
	global_store_dwordx4 v[0:1], v[4:7], off
	v_add_u32_e32 v0, 0x1c00, v139
	v_ashrrev_i32_e32 v2, 5, v0
	v_add_u32_e32 v0, s0, v2
	v_ashrrev_i32_e32 v1, 31, v0
	v_lshlrev_b64 v[0:1], 12, v[0:1]
	v_lshl_add_u64 v[0:1], s[38:39], 0, v[0:1]
	v_lshl_add_u64 v[0:1], v[0:1], 0, s[22:23]
	v_lshl_add_u64 v[8:9], v[0:1], 0, v[136:137]
	v_mad_u64_u32 v[0:1], s[10:11], v2, s58, v[136:137]
	ds_read2_b64 v[0:3], v0 offset1:1
	v_add_u32_e32 v4, 0x1e00, v139
	v_ashrrev_i32_e32 v10, 5, v4
	v_mad_u64_u32 v[4:5], s[10:11], v10, s58, v[136:137]
	ds_read2_b64 v[4:7], v4 offset1:1
	s_waitcnt lgkmcnt(1)
	global_store_dwordx4 v[8:9], v[0:3], off
	s_nop 1
	v_add_u32_e32 v0, s0, v10
	v_ashrrev_i32_e32 v1, 31, v0
	v_lshlrev_b64 v[0:1], 12, v[0:1]
	v_lshl_add_u64 v[0:1], s[38:39], 0, v[0:1]
	v_lshl_add_u64 v[0:1], v[0:1], 0, s[22:23]
	v_lshl_add_u64 v[0:1], v[0:1], 0, v[136:137]
	s_waitcnt lgkmcnt(0)
	global_store_dwordx4 v[0:1], v[4:7], off
	s_barrier

; DI void stg16_nt(void* p, u32x4 v) { __builtin_nontemporal_store(v, (u32x4*)p); }
; DI void epi_seg(const f32x16 (&acc)[4][2], const Seg& sg0, const Seg& sg1, int m0, int n0, const float* rs, const float2* cs64, const float2* cs32, bf16_t* stg) {
;     ...
; #pragma unroll
;   for (int it = 0; it < 16; ++it) {
;     const int idx = tid + NTHR * it, rr = idx >> 5, c = idx & 31;
;     const Seg& fs = (c >> 4) ? sg1 : sg0;
;     const int lcc = n0 + c * 8 - fs.cbase;
;     if (fs.kind != K_NONE && lcc < fs.nvalid) {
;       const int row = m0 + rr;
;       size_t off;
;       if (fs.kind == K_KC2) { const int b = row >> 9, n = (row >> 2) & 127, g = row & 3; off = ((size_t)((b * 4 + g) * 128 + n)) * 64 + lcc; }
;       else off = (size_t)row * fs.ld + lcc;
;       stg16_nt(fs.dst + off, stage_read16(stg, rr, c));
;     }
;   }
.LBB0_677:
	s_or_b64 exec, exec, s[42:43]
	v_mov_b32_e32 v129, s63
	v_mov_b32_e32 v130, s60
	v_cmp_gt_u32_e32 vcc, 16, v181
	v_lshl_or_b32 v128, v181, 3, s37
	s_waitcnt lgkmcnt(0)
	v_cndmask_b32_e32 v129, v129, v130, vcc
	v_sub_u32_e32 v128, v128, v129
	v_cmp_gt_i32_e64 s[0:1], 2.0, v128
	s_barrier
	s_and_saveexec_b64 s[10:11], s[0:1]
	s_cbranch_execz .LBB0_679
	s_and_b64 s[0:1], s[40:41], exec
	s_cselect_b32 s12, 0x26368800, s48
	s_cselect_b32 s13, 0x400, s49
	s_cselect_b32 s40, s50, 0x22368800
	s_and_b64 s[0:1], s[34:35], exec
	s_cselect_b32 s1, s40, s12
	s_cselect_b32 s0, s13, 0x400
	s_add_u32 s12, s72, s1
	s_addc_u32 s13, s73, 0
	s_waitcnt vmcnt(0)
	v_ashrrev_i32_e32 v132, 5, v139
	v_mov_b32_e32 v130, s0
	v_mov_b32_e32 v131, s36
	v_mov_b32_e32 v133, s13
	v_mov_b32_e32 v134, s39
	v_add_u32_e32 v129, s62, v132
	v_cndmask_b32_e32 v138, v130, v131, vcc
	v_cndmask_b32_e32 v141, v133, v134, vcc
	v_mov_b32_e32 v133, s12
	v_mov_b32_e32 v134, s38
	v_lshlrev_b32_e32 v136, 4, v181
	v_mad_i64_i32 v[130:131], s[0:1], v138, v129, 0
	v_ashrrev_i32_e32 v129, 31, v128
	v_cndmask_b32_e32 v140, v133, v134, vcc
	v_lshl_add_u64 v[130:131], v[130:131], 1, v[140:141]
	v_lshlrev_b64 v[142:143], 1, v[128:129]
	v_mad_u64_u32 v[128:129], s[0:1], v132, s58, v[136:137]
	v_lshl_add_u64 v[144:145], v[130:131], 0, v[142:143]
	ds_read2_b64 v[128:131], v128 offset1:1
	v_add_u32_e32 v132, 0x200, v139
	v_ashrrev_i32_e32 v146, 5, v132
	v_mad_u64_u32 v[132:133], s[0:1], v146, s58, v[136:137]
	ds_read2_b64 v[132:135], v132 offset1:1
	s_waitcnt lgkmcnt(1)
	global_store_dwordx4 v[144:145], v[128:131], off
	s_nop 1
	v_add_u32_e32 v128, s62, v146
	v_mad_i64_i32 v[128:129], s[0:1], v138, v128, 0
	v_lshl_add_u64 v[128:129], v[128:129], 1, v[140:141]
	v_lshl_add_u64 v[128:129], v[128:129], 0, v[142:143]
	s_waitcnt lgkmcnt(0)
	global_store_dwordx4 v[128:129], v[132:135], off
	v_add_u32_e32 v128, 0x400, v139
	v_ashrrev_i32_e32 v130, 5, v128
	v_add_u32_e32 v128, s62, v130
	v_mad_i64_i32 v[128:129], s[0:1], v138, v128, 0
	v_lshl_add_u64 v[128:129], v[128:129], 1, v[140:141]
	v_lshl_add_u64 v[144:145], v[128:129], 0, v[142:143]
	v_mad_u64_u32 v[128:129], s[0:1], v130, s58, v[136:137]
	ds_read2_b64 v[128:131], v128 offset1:1
	v_add_u32_e32 v132, 0x600, v139
	v_ashrrev_i32_e32 v146, 5, v132
	v_mad_u64_u32 v[132:133], s[0:1], v146, s58, v[136:137]
	ds_read2_b64 v[132:135], v132 offset1:1
	s_waitcnt lgkmcnt(1)
	global_store_dwordx4 v[144:145], v[128:131], off
	s_nop 1
	v_add_u32_e32 v128, s62, v146
	v_mad_i64_i32 v[128:129], s[0:1], v138, v128, 0
	v_lshl_add_u64 v[128:129], v[128:129], 1, v[140:141]
	v_lshl_add_u64 v[128:129], v[128:129], 0, v[142:143]
	s_waitcnt lgkmcnt(0)
	global_store_dwordx4 v[128:129], v[132:135], off
	v_add_u32_e32 v128, 0x800, v139
	v_ashrrev_i32_e32 v130, 5, v128
	v_add_u32_e32 v128, s62, v130
	v_mad_i64_i32 v[128:129], s[0:1], v138, v128, 0
	v_lshl_add_u64 v[128:129], v[128:129], 1, v[140:141]
	v_lshl_add_u64 v[144:145], v[128:129], 0, v[142:143]
	v_mad_u64_u32 v[128:129], s[0:1], v130, s58, v[136:137]
	ds_read2_b64 v[128:131], v128 offset1:1
	v_add_u32_e32 v132, 0xa00, v139
	v_ashrrev_i32_e32 v146, 5, v132
	v_mad_u64_u32 v[132:133], s[0:1], v146, s58, v[136:137]
	ds_read2_b64 v[132:135], v132 offset1:1
	s_waitcnt lgkmcnt(1)
	global_store_dwordx4 v[144:145], v[128:131], off
	s_nop 1
	v_add_u32_e32 v128, s62, v146
	v_mad_i64_i32 v[128:129], s[0:1], v138, v128, 0
	v_lshl_add_u64 v[128:129], v[128:129], 1, v[140:141]
	v_lshl_add_u64 v[128:129], v[128:129], 0, v[142:143]
	s_waitcnt lgkmcnt(0)
	global_store_dwordx4 v[128:129], v[132:135], off
	v_add_u32_e32 v128, 0xc00, v139
	v_ashrrev_i32_e32 v130, 5, v128
	v_add_u32_e32 v128, s62, v130
	v_mad_i64_i32 v[128:129], s[0:1], v138, v128, 0
	v_lshl_add_u64 v[128:129], v[128:129], 1, v[140:141]
	v_lshl_add_u64 v[144:145], v[128:129], 0, v[142:143]
	v_mad_u64_u32 v[128:129], s[0:1], v130, s58, v[136:137]
	ds_read2_b64 v[128:131], v128 offset1:1
	v_add_u32_e32 v132, 0xe00, v139
	v_ashrrev_i32_e32 v146, 5, v132
	v_mad_u64_u32 v[132:133], s[0:1], v146, s58, v[136:137]
	ds_read2_b64 v[132:135], v132 offset1:1
	s_waitcnt lgkmcnt(1)
; DI void stg16_nt(void* p, u32x4 v) { __builtin_nontemporal_store(v, (u32x4*)p); }
; DI void epi_seg(const f32x16 (&acc)[4][2], const Seg& sg0, const Seg& sg1, int m0, int n0, const float* rs, const float2* cs64, const float2* cs32, bf16_t* stg) {
;     ...
; #pragma unroll
;   for (int it = 0; it < 16; ++it) {
;     const int idx = tid + NTHR * it, rr = idx >> 5, c = idx & 31;
;     const Seg& fs = (c >> 4) ? sg1 : sg0;
;     const int lcc = n0 + c * 8 - fs.cbase;
;     if (fs.kind != K_NONE && lcc < fs.nvalid) {
;       const int row = m0 + rr;
;       size_t off;
;       if (fs.kind == K_KC2) { const int b = row >> 9, n = (row >> 2) & 127, g = row & 3; off = ((size_t)((b * 4 + g) * 128 + n)) * 64 + lcc; }
;       else off = (size_t)row * fs.ld + lcc;
;       stg16_nt(fs.dst + off, stage_read16(stg, rr, c));
;     }
;   }
	global_store_dwordx4 v[144:145], v[128:131], off
	s_nop 1
	v_add_u32_e32 v128, s62, v146
	v_mad_i64_i32 v[128:129], s[0:1], v138, v128, 0
	v_lshl_add_u64 v[128:129], v[128:129], 1, v[140:141]
	v_lshl_add_u64 v[128:129], v[128:129], 0, v[142:143]
	s_waitcnt lgkmcnt(0)
	global_store_dwordx4 v[128:129], v[132:135], off
	v_add_u32_e32 v128, 0x1000, v139
	v_ashrrev_i32_e32 v130, 5, v128
	v_add_u32_e32 v128, s62, v130
	v_mad_i64_i32 v[128:129], s[0:1], v138, v128, 0
	v_lshl_add_u64 v[128:129], v[128:129], 1, v[140:141]
	v_lshl_add_u64 v[144:145], v[128:129], 0, v[142:143]
	v_mad_u64_u32 v[128:129], s[0:1], v130, s58, v[136:137]
	ds_read2_b64 v[128:131], v128 offset1:1
	v_add_u32_e32 v132, 0x1200, v139
	v_ashrrev_i32_e32 v146, 5, v132
	v_mad_u64_u32 v[132:133], s[0:1], v146, s58, v[136:137]
	ds_read2_b64 v[132:135], v132 offset1:1
	s_waitcnt lgkmcnt(1)
	global_store_dwordx4 v[144:145], v[128:131], off
	s_nop 1
	v_add_u32_e32 v128, s62, v146
	v_mad_i64_i32 v[128:129], s[0:1], v138, v128, 0
	v_lshl_add_u64 v[128:129], v[128:129], 1, v[140:141]
	v_lshl_add_u64 v[128:129], v[128:129], 0, v[142:143]
	s_waitcnt lgkmcnt(0)
	global_store_dwordx4 v[128:129], v[132:135], off
	v_add_u32_e32 v128, 0x1400, v139
	v_ashrrev_i32_e32 v130, 5, v128
	v_add_u32_e32 v128, s62, v130
	v_mad_i64_i32 v[128:129], s[0:1], v138, v128, 0
	v_lshl_add_u64 v[128:129], v[128:129], 1, v[140:141]
	v_lshl_add_u64 v[144:145], v[128:129], 0, v[142:143]
	v_mad_u64_u32 v[128:129], s[0:1], v130, s58, v[136:137]
	ds_read2_b64 v[128:131], v128 offset1:1
	v_add_u32_e32 v132, 0x1600, v139
	v_ashrrev_i32_e32 v146, 5, v132
	v_mad_u64_u32 v[132:133], s[0:1], v146, s58, v[136:137]
	ds_read2_b64 v[132:135], v132 offset1:1
	s_waitcnt lgkmcnt(1)
	global_store_dwordx4 v[144:145], v[128:131], off
	s_nop 1
	v_add_u32_e32 v128, s62, v146
	v_mad_i64_i32 v[128:129], s[0:1], v138, v128, 0
	v_lshl_add_u64 v[128:129], v[128:129], 1, v[140:141]
	v_lshl_add_u64 v[128:129], v[128:129], 0, v[142:143]
	s_waitcnt lgkmcnt(0)
	global_store_dwordx4 v[128:129], v[132:135], off
	v_add_u32_e32 v128, 0x1800, v139
	v_ashrrev_i32_e32 v130, 5, v128
	v_add_u32_e32 v128, s62, v130
	v_mad_i64_i32 v[128:129], s[0:1], v138, v128, 0
	v_lshl_add_u64 v[128:129], v[128:129], 1, v[140:141]
	v_lshl_add_u64 v[144:145], v[128:129], 0, v[142:143]
	v_mad_u64_u32 v[128:129], s[0:1], v130, s58, v[136:137]
	ds_read2_b64 v[128:131], v128 offset1:1
	v_add_u32_e32 v132, 0x1a00, v139
	v_ashrrev_i32_e32 v146, 5, v132
	v_mad_u64_u32 v[132:133], s[0:1], v146, s58, v[136:137]
	ds_read2_b64 v[132:135], v132 offset1:1
	s_waitcnt lgkmcnt(1)
	global_store_dwordx4 v[144:145], v[128:131], off
	s_nop 1
	v_add_u32_e32 v128, s62, v146
	v_mad_i64_i32 v[128:129], s[0:1], v138, v128, 0
	v_lshl_add_u64 v[128:129], v[128:129], 1, v[140:141]
	v_lshl_add_u64 v[128:129], v[128:129], 0, v[142:143]
	s_waitcnt lgkmcnt(0)
	global_store_dwordx4 v[128:129], v[132:135], off
	v_add_u32_e32 v128, 0x1c00, v139
	v_ashrrev_i32_e32 v130, 5, v128
	v_add_u32_e32 v128, s62, v130
	v_mad_i64_i32 v[128:129], s[0:1], v138, v128, 0
	v_lshl_add_u64 v[128:129], v[128:129], 1, v[140:141]
	v_lshl_add_u64 v[144:145], v[128:129], 0, v[142:143]
	v_mad_u64_u32 v[128:129], s[0:1], v130, s58, v[136:137]
	ds_read2_b64 v[128:131], v128 offset1:1
	v_add_u32_e32 v132, 0x1e00, v139
	v_ashrrev_i32_e32 v146, 5, v132
	v_mad_u64_u32 v[132:133], s[0:1], v146, s58, v[136:137]
	ds_read2_b64 v[132:135], v132 offset1:1
	s_waitcnt lgkmcnt(1)
	global_store_dwordx4 v[144:145], v[128:131], off
	s_nop 1
	v_add_u32_e32 v128, s62, v146
	v_mad_i64_i32 v[128:129], s[0:1], v138, v128, 0
	v_lshl_add_u64 v[128:129], v[128:129], 1, v[140:141]
	v_lshl_add_u64 v[128:129], v[128:129], 0, v[142:143]
	s_waitcnt lgkmcnt(0)
	global_store_dwordx4 v[128:129], v[132:135], off

; DI int otid() { int t = threadIdx.x; asm volatile("" : "+v"(t)); return t; }
; DI void stg16_nt(void* p, u32x4 v) { __builtin_nontemporal_store(v, (u32x4*)p); }
; DI void stage_store_tile(const bf16_t* stg, bf16_t* tilebase) {
;   const int tid = otid();
;   const int r0 = tid >> 5, c = tid & 31;
;   const unsigned o0 = (unsigned)(r0 * 1024 + c * 8);
; #pragma unroll
;   for (int it = 0; it < 16; ++it) stg16_nt(tilebase + (o0 + (unsigned)(it * 16 * 1024)), stage_read16(stg, r0 + 16 * it, c));
; }
; template <bool XF32>
; DI void phase_outproj(const Params& P, int layer, const void* xres, const bf16_t* og, unsigned char* smem, int L, int G) {
;     ...
;     __syncthreads();
;     stage_store_tile(stg, Sb + (size_t)mt * 256 * 1024 + nt * 256);
;     __syncthreads();
.LBB0_847:
	s_or_b64 exec, exec, s[20:21]
	v_mov_b32_e32 v0, v192
	s_waitcnt lgkmcnt(0)
	s_barrier
	s_lshl_b64 s[14:15], s[14:15], 18
	v_ashrrev_i32_e32 v4, 5, v0
	v_and_b32_e32 v0, 31, v0
	v_mul_lo_u32 v1, v4, s29
	s_lshl_b64 s[14:15], s[14:15], 1
	v_lshl_add_u32 v10, v0, 4, v1
	s_add_u32 s14, s76, s14
	v_lshlrev_b32_e32 v5, 3, v0
	ds_read2_b64 v[0:3], v10 offset1:1
	s_addc_u32 s15, s77, s15
	v_lshl_or_b32 v160, v4, 10, v5
	v_add_u32_e32 v4, 0x2080, v10
	s_add_u32 s14, s14, s34
	ds_read2_b64 v[4:7], v4 offset1:1
	s_addc_u32 s15, s15, 0
	v_lshl_add_u64 v[8:9], v[160:161], 1, s[14:15]
	s_waitcnt lgkmcnt(1)
	global_store_dwordx4 v[8:9], v[0:3], off
	s_add_i32 s25, s25, s69
	s_andn2_b64 vcc, exec, s[18:19]
	v_add_u32_e32 v0, 0x4000, v160
	v_mov_b32_e32 v1, v161
	v_lshl_add_u64 v[0:1], v[0:1], 1, s[14:15]
	s_waitcnt lgkmcnt(0)
	global_store_dwordx4 v[0:1], v[4:7], off
	v_add_u32_e32 v0, 0x4100, v10
	ds_read2_b64 v[0:3], v0 offset1:1
	v_add_u32_e32 v4, 0x8000, v160
	v_mov_b32_e32 v5, v161
	v_lshl_add_u64 v[8:9], v[4:5], 1, s[14:15]
	v_add_u32_e32 v4, 0x6180, v10
	ds_read2_b64 v[4:7], v4 offset1:1
	s_waitcnt lgkmcnt(1)
	global_store_dwordx4 v[8:9], v[0:3], off
	s_add_i32 s26, s26, s23
	s_nop 0
	v_add_u32_e32 v0, 0xc000, v160
	v_mov_b32_e32 v1, v161
	v_lshl_add_u64 v[0:1], v[0:1], 1, s[14:15]
	s_waitcnt lgkmcnt(0)
	global_store_dwordx4 v[0:1], v[4:7], off
	v_add_u32_e32 v0, 0x8200, v10
	ds_read2_b64 v[0:3], v0 offset1:1
	v_add_u32_e32 v4, 0x10000, v160
	v_mov_b32_e32 v5, v161
	v_lshl_add_u64 v[8:9], v[4:5], 1, s[14:15]
	v_add_u32_e32 v4, 0xa280, v10
	ds_read2_b64 v[4:7], v4 offset1:1
	s_waitcnt lgkmcnt(1)
	global_store_dwordx4 v[8:9], v[0:3], off
	s_nop 1
	v_add_u32_e32 v0, 0x14000, v160
	v_mov_b32_e32 v1, v161
	v_lshl_add_u64 v[0:1], v[0:1], 1, s[14:15]
	s_waitcnt lgkmcnt(0)
	global_store_dwordx4 v[0:1], v[4:7], off
	v_add_u32_e32 v0, 0xc300, v10
	ds_read2_b64 v[0:3], v0 offset1:1
	v_add_u32_e32 v4, 0x18000, v160
	v_mov_b32_e32 v5, v161
	v_lshl_add_u64 v[8:9], v[4:5], 1, s[14:15]
	v_add_u32_e32 v4, 0xe380, v10
	ds_read2_b64 v[4:7], v4 offset1:1
	s_waitcnt lgkmcnt(1)
	global_store_dwordx4 v[8:9], v[0:3], off
	s_nop 1
	v_add_u32_e32 v0, 0x1c000, v160
	v_mov_b32_e32 v1, v161
	v_lshl_add_u64 v[0:1], v[0:1], 1, s[14:15]
	s_waitcnt lgkmcnt(0)
	global_store_dwordx4 v[0:1], v[4:7], off
	v_add_u32_e32 v0, 0x10400, v10
	ds_read2_b64 v[0:3], v0 offset1:1
	v_add_u32_e32 v4, 0x20000, v160
	v_mov_b32_e32 v5, v161
	v_lshl_add_u64 v[8:9], v[4:5], 1, s[14:15]
	v_add_u32_e32 v4, 0x12480, v10
	ds_read2_b64 v[4:7], v4 offset1:1
	s_waitcnt lgkmcnt(1)
	global_store_dwordx4 v[8:9], v[0:3], off
	s_nop 1
	v_add_u32_e32 v0, 0x24000, v160
	v_mov_b32_e32 v1, v161
	v_lshl_add_u64 v[0:1], v[0:1], 1, s[14:15]
	s_waitcnt lgkmcnt(0)
	global_store_dwordx4 v[0:1], v[4:7], off
	v_add_u32_e32 v0, 0x14500, v10
	ds_read2_b64 v[0:3], v0 offset1:1
	v_add_u32_e32 v4, 0x28000, v160
	v_mov_b32_e32 v5, v161
	v_lshl_add_u64 v[8:9], v[4:5], 1, s[14:15]
	v_add_u32_e32 v4, 0x16580, v10
	ds_read2_b64 v[4:7], v4 offset1:1
	s_waitcnt lgkmcnt(1)
	global_store_dwordx4 v[8:9], v[0:3], off
	s_nop 1
	v_add_u32_e32 v0, 0x2c000, v160
	v_mov_b32_e32 v1, v161
	v_lshl_add_u64 v[0:1], v[0:1], 1, s[14:15]
	s_waitcnt lgkmcnt(0)
	global_store_dwordx4 v[0:1], v[4:7], off
	v_add_u32_e32 v0, 0x18600, v10
	ds_read2_b64 v[0:3], v0 offset1:1
	v_add_u32_e32 v4, 0x30000, v160
	v_mov_b32_e32 v5, v161
	v_lshl_add_u64 v[8:9], v[4:5], 1, s[14:15]
	v_add_u32_e32 v4, 0x1a680, v10
	ds_read2_b64 v[4:7], v4 offset1:1
	s_waitcnt lgkmcnt(1)
	global_store_dwordx4 v[8:9], v[0:3], off
	v_add_u32_e32 v8, 0x38000, v160
	v_mov_b32_e32 v9, v161
	v_add_u32_e32 v0, 0x34000, v160
	v_mov_b32_e32 v1, v161
	v_lshl_add_u64 v[0:1], v[0:1], 1, s[14:15]
	s_waitcnt lgkmcnt(0)
	global_store_dwordx4 v[0:1], v[4:7], off
	v_add_u32_e32 v0, 0x1c700, v10
	ds_read2_b64 v[0:3], v0 offset1:1
	v_add_u32_e32 v4, 0x1e780, v10
	ds_read2_b64 v[4:7], v4 offset1:1
	v_lshl_add_u64 v[8:9], v[8:9], 1, s[14:15]
	v_add_u32_e32 v160, 0x3c000, v160
	s_waitcnt lgkmcnt(1)
	global_store_dwordx4 v[8:9], v[0:3], off
	s_nop 1
	v_lshl_add_u64 v[0:1], v[160:161], 1, s[14:15]
	s_waitcnt lgkmcnt(0)
	global_store_dwordx4 v[0:1], v[4:7], off
	s_barrier
	s_cbranch_vccz .LBB0_858

; DI void stg16_nt(void* p, u32x4 v) { __builtin_nontemporal_store(v, (u32x4*)p); }
; DI void epi_seg(const f32x16 (&acc)[4][2], const Seg& sg0, const Seg& sg1, int m0, int n0, const float* rs, const float2* cs64, const float2* cs32, bf16_t* stg) {
;     ...
; #pragma unroll
;   for (int it = 0; it < 16; ++it) {
;     const int idx = tid + NTHR * it, rr = idx >> 5, c = idx & 31;
;     const Seg& fs = (c >> 4) ? sg1 : sg0;
;     const int lcc = n0 + c * 8 - fs.cbase;
;     if (fs.kind != K_NONE && lcc < fs.nvalid) {
;       const int row = m0 + rr;
;       size_t off;
;       if (fs.kind == K_KC2) { const int b = row >> 9, n = (row >> 2) & 127, g = row & 3; off = ((size_t)((b * 4 + g) * 128 + n)) * 64 + lcc; }
;       else off = (size_t)row * fs.ld + lcc;
;       stg16_nt(fs.dst + off, stage_read16(stg, rr, c));
;     }
;   }
;   __syncthreads();
.LBB0_864:
	s_or_b64 exec, exec, s[18:19]
	v_and_b32_e32 v1, 31, v160
	v_lshlrev_b32_e32 v0, 3, v1
	v_subrev_u32_e32 v0, s29, v0
	v_subrev_u32_e32 v0, s30, v0
	v_add_u32_e32 v0, s22, v0
	v_cmp_gt_i32_e32 vcc, 2.0, v0
	s_waitcnt lgkmcnt(0)
	s_barrier
	s_and_saveexec_b64 s[18:19], vcc
	s_cbranch_execz .LBB0_859
	v_ashrrev_i32_e32 v4, 5, v160
	v_add_u32_e32 v2, s28, v4
	v_ashrrev_i32_e32 v3, 31, v2
	v_lshlrev_b32_e32 v8, 4, v1
	v_ashrrev_i32_e32 v1, 31, v0
	v_lshlrev_b64 v[2:3], 11, v[2:3]
	v_lshl_add_u64 v[2:3], s[66:67], 0, v[2:3]
	v_lshlrev_b64 v[10:11], 1, v[0:1]
	v_mad_u64_u32 v[0:1], s[30:31], v4, s26, v[8:9]
	v_lshl_add_u64 v[12:13], v[2:3], 0, v[10:11]
	ds_read2_b64 v[0:3], v0 offset1:1
	v_add_u32_e32 v4, 0x200, v160
	v_ashrrev_i32_e32 v9, 5, v4
	v_mad_u64_u32 v[4:5], s[30:31], v9, s26, v[8:9]
	ds_read2_b64 v[4:7], v4 offset1:1
	s_waitcnt lgkmcnt(1)
	global_store_dwordx4 v[12:13], v[0:3], off
	s_nop 1
	v_add_u32_e32 v0, s28, v9
	v_ashrrev_i32_e32 v1, 31, v0
	v_lshlrev_b64 v[0:1], 11, v[0:1]
	v_lshl_add_u64 v[0:1], s[66:67], 0, v[0:1]
	v_lshl_add_u64 v[0:1], v[0:1], 0, v[10:11]
	s_waitcnt lgkmcnt(0)
	global_store_dwordx4 v[0:1], v[4:7], off
	v_add_u32_e32 v0, 0x400, v160
	v_ashrrev_i32_e32 v2, 5, v0
	v_add_u32_e32 v0, s28, v2
	v_ashrrev_i32_e32 v1, 31, v0
	v_lshlrev_b64 v[0:1], 11, v[0:1]
	v_lshl_add_u64 v[0:1], s[66:67], 0, v[0:1]
	v_lshl_add_u64 v[12:13], v[0:1], 0, v[10:11]
	v_mad_u64_u32 v[0:1], s[30:31], v2, s26, v[8:9]
	ds_read2_b64 v[0:3], v0 offset1:1
	v_add_u32_e32 v4, 0x600, v160
	v_ashrrev_i32_e32 v9, 5, v4
	v_mad_u64_u32 v[4:5], s[30:31], v9, s26, v[8:9]
	ds_read2_b64 v[4:7], v4 offset1:1
	s_waitcnt lgkmcnt(1)
	global_store_dwordx4 v[12:13], v[0:3], off
	s_nop 1
	v_add_u32_e32 v0, s28, v9
	v_ashrrev_i32_e32 v1, 31, v0
	v_lshlrev_b64 v[0:1], 11, v[0:1]
	v_lshl_add_u64 v[0:1], s[66:67], 0, v[0:1]
	v_lshl_add_u64 v[0:1], v[0:1], 0, v[10:11]
	s_waitcnt lgkmcnt(0)
	global_store_dwordx4 v[0:1], v[4:7], off
	v_add_u32_e32 v0, 0x800, v160
	v_ashrrev_i32_e32 v2, 5, v0
	v_add_u32_e32 v0, s28, v2
	v_ashrrev_i32_e32 v1, 31, v0
	v_lshlrev_b64 v[0:1], 11, v[0:1]
	v_lshl_add_u64 v[0:1], s[66:67], 0, v[0:1]
	v_lshl_add_u64 v[12:13], v[0:1], 0, v[10:11]
	v_mad_u64_u32 v[0:1], s[30:31], v2, s26, v[8:9]
	ds_read2_b64 v[0:3], v0 offset1:1
	v_add_u32_e32 v4, 0xa00, v160
	v_ashrrev_i32_e32 v9, 5, v4
	v_mad_u64_u32 v[4:5], s[30:31], v9, s26, v[8:9]
	ds_read2_b64 v[4:7], v4 offset1:1
	s_waitcnt lgkmcnt(1)
	global_store_dwordx4 v[12:13], v[0:3], off
	s_nop 1
	v_add_u32_e32 v0, s28, v9
	v_ashrrev_i32_e32 v1, 31, v0
	v_lshlrev_b64 v[0:1], 11, v[0:1]
	v_lshl_add_u64 v[0:1], s[66:67], 0, v[0:1]
	v_lshl_add_u64 v[0:1], v[0:1], 0, v[10:11]
	s_waitcnt lgkmcnt(0)
	global_store_dwordx4 v[0:1], v[4:7], off
	v_add_u32_e32 v0, 0xc00, v160
	v_ashrrev_i32_e32 v2, 5, v0
	v_add_u32_e32 v0, s28, v2
	v_ashrrev_i32_e32 v1, 31, v0
	v_lshlrev_b64 v[0:1], 11, v[0:1]
	v_lshl_add_u64 v[0:1], s[66:67], 0, v[0:1]
	v_lshl_add_u64 v[12:13], v[0:1], 0, v[10:11]
	v_mad_u64_u32 v[0:1], s[30:31], v2, s26, v[8:9]
	ds_read2_b64 v[0:3], v0 offset1:1
	v_add_u32_e32 v4, 0xe00, v160
	v_ashrrev_i32_e32 v9, 5, v4
	v_mad_u64_u32 v[4:5], s[30:31], v9, s26, v[8:9]
	ds_read2_b64 v[4:7], v4 offset1:1
	s_waitcnt lgkmcnt(1)
	global_store_dwordx4 v[12:13], v[0:3], off
	s_nop 1
	v_add_u32_e32 v0, s28, v9
	v_ashrrev_i32_e32 v1, 31, v0
	v_lshlrev_b64 v[0:1], 11, v[0:1]
	v_lshl_add_u64 v[0:1], s[66:67], 0, v[0:1]
	v_lshl_add_u64 v[0:1], v[0:1], 0, v[10:11]
	s_waitcnt lgkmcnt(0)
	global_store_dwordx4 v[0:1], v[4:7], off
	v_add_u32_e32 v0, 0x1000, v160
	v_ashrrev_i32_e32 v2, 5, v0
	v_add_u32_e32 v0, s28, v2
	v_ashrrev_i32_e32 v1, 31, v0
	v_lshlrev_b64 v[0:1], 11, v[0:1]
	v_lshl_add_u64 v[0:1], s[66:67], 0, v[0:1]
	v_lshl_add_u64 v[12:13], v[0:1], 0, v[10:11]
	v_mad_u64_u32 v[0:1], s[30:31], v2, s26, v[8:9]
	ds_read2_b64 v[0:3], v0 offset1:1
	v_add_u32_e32 v4, 0x1200, v160
	v_ashrrev_i32_e32 v9, 5, v4
	v_mad_u64_u32 v[4:5], s[30:31], v9, s26, v[8:9]
	ds_read2_b64 v[4:7], v4 offset1:1
	s_waitcnt lgkmcnt(1)
	global_store_dwordx4 v[12:13], v[0:3], off
	s_nop 1
	v_add_u32_e32 v0, s28, v9
	v_ashrrev_i32_e32 v1, 31, v0
	v_lshlrev_b64 v[0:1], 11, v[0:1]
	v_lshl_add_u64 v[0:1], s[66:67], 0, v[0:1]
	v_lshl_add_u64 v[0:1], v[0:1], 0, v[10:11]
	s_waitcnt lgkmcnt(0)
	global_store_dwordx4 v[0:1], v[4:7], off
	v_add_u32_e32 v0, 0x1400, v160
	v_ashrrev_i32_e32 v2, 5, v0
	v_add_u32_e32 v0, s28, v2
	v_ashrrev_i32_e32 v1, 31, v0
	v_lshlrev_b64 v[0:1], 11, v[0:1]
	v_lshl_add_u64 v[0:1], s[66:67], 0, v[0:1]
	v_lshl_add_u64 v[12:13], v[0:1], 0, v[10:11]
	v_mad_u64_u32 v[0:1], s[30:31], v2, s26, v[8:9]
	ds_read2_b64 v[0:3], v0 offset1:1
	v_add_u32_e32 v4, 0x1600, v160
	v_ashrrev_i32_e32 v9, 5, v4
	v_mad_u64_u32 v[4:5], s[30:31], v9, s26, v[8:9]
	ds_read2_b64 v[4:7], v4 offset1:1
	s_waitcnt lgkmcnt(1)
	global_store_dwordx4 v[12:13], v[0:3], off
	s_nop 1
	v_add_u32_e32 v0, s28, v9
	v_ashrrev_i32_e32 v1, 31, v0
	v_lshlrev_b64 v[0:1], 11, v[0:1]
	v_lshl_add_u64 v[0:1], s[66:67], 0, v[0:1]
	v_lshl_add_u64 v[0:1], v[0:1], 0, v[10:11]
	s_waitcnt lgkmcnt(0)
	global_store_dwordx4 v[0:1], v[4:7], off
	v_add_u32_e32 v0, 0x1800, v160
	v_ashrrev_i32_e32 v2, 5, v0
	v_add_u32_e32 v0, s28, v2
	v_ashrrev_i32_e32 v1, 31, v0
	v_lshlrev_b64 v[0:1], 11, v[0:1]
	v_lshl_add_u64 v[0:1], s[66:67], 0, v[0:1]
	v_lshl_add_u64 v[12:13], v[0:1], 0, v[10:11]
	v_mad_u64_u32 v[0:1], s[30:31], v2, s26, v[8:9]
	ds_read2_b64 v[0:3], v0 offset1:1
	v_add_u32_e32 v4, 0x1a00, v160
	v_ashrrev_i32_e32 v9, 5, v4
	v_mad_u64_u32 v[4:5], s[30:31], v9, s26, v[8:9]
	ds_read2_b64 v[4:7], v4 offset1:1
	s_waitcnt lgkmcnt(1)
	global_store_dwordx4 v[12:13], v[0:3], off
	s_nop 1
	v_add_u32_e32 v0, s28, v9
	v_ashrrev_i32_e32 v1, 31, v0
	v_lshlrev_b64 v[0:1], 11, v[0:1]
	v_lshl_add_u64 v[0:1], s[66:67], 0, v[0:1]
	v_lshl_add_u64 v[0:1], v[0:1], 0, v[10:11]
	s_waitcnt lgkmcnt(0)
	global_store_dwordx4 v[0:1], v[4:7], off
	v_add_u32_e32 v0, 0x1c00, v160
	v_ashrrev_i32_e32 v2, 5, v0
	v_add_u32_e32 v0, s28, v2
	v_ashrrev_i32_e32 v1, 31, v0
	v_lshlrev_b64 v[0:1], 11, v[0:1]
	v_lshl_add_u64 v[0:1], s[66:67], 0, v[0:1]
	v_lshl_add_u64 v[12:13], v[0:1], 0, v[10:11]
	v_mad_u64_u32 v[0:1], s[30:31], v2, s26, v[8:9]
	ds_read2_b64 v[0:3], v0 offset1:1
	v_add_u32_e32 v4, 0x1e00, v160
	v_ashrrev_i32_e32 v9, 5, v4
	v_mad_u64_u32 v[4:5], s[30:31], v9, s26, v[8:9]
	ds_read2_b64 v[4:7], v4 offset1:1
	s_waitcnt lgkmcnt(1)
	global_store_dwordx4 v[12:13], v[0:3], off
	s_nop 1
	v_add_u32_e32 v0, s28, v9
	v_ashrrev_i32_e32 v1, 31, v0
	v_lshlrev_b64 v[0:1], 11, v[0:1]
	v_lshl_add_u64 v[0:1], s[66:67], 0, v[0:1]
	v_lshl_add_u64 v[0:1], v[0:1], 0, v[10:11]
	s_waitcnt lgkmcnt(0)
	global_store_dwordx4 v[0:1], v[4:7], off
	s_branch .LBB0_859

; DI unsigned pack2(float a, float b) { f32x2_t v = {a, b}; bf16x2_t r = __builtin_convertvector(v, bf16x2_t); return __builtin_bit_cast(unsigned, r); }
; DI float sigmoidf_(float x) { return __builtin_amdgcn_rcpf(1.f + __expf(-x)); }
; template <bool LAST>
; DI void phase_gate(const Params& P, int layer, unsigned char* smem, int L, int G) {
;     ...
;     unsigned gq[4][2][8];
; #pragma unroll
;     for (int i = 0; i < 4; ++i)
; #pragma unroll
;       for (int q4 = 0; q4 < 4; ++q4) {
;         const int fl = wm * 128 + i * 32 + 8 * q4 + 4 * h;
;         const f32x4 c1v = *(const f32x4*)(vecL + fl), c2v = *(const f32x4*)(vecL + 256 + fl);
;         const float c1a[4] = {c1v.x, c1v.y, c1v.z, c1v.w}, c2a[4] = {c2v.x, c2v.y, c2v.z, c2v.w};
; #pragma unroll
;         for (int j = 0; j < 2; ++j) {
;           const int lrow = wn * 64 + j * 32 + r;
;           const float mu = rowA[lrow], rstd = rowB[lrow];
;           float sg4[4];
; #pragma unroll
;           for (int e = 0; e < 4; ++e) sg4[e] = sigmoidf_(rstd * (accu[i][j][4 * q4 + e] - mu * c1a[e]) + c2a[e]);
;           gq[i][j][2 * q4] = pack2(sg4[0], sg4[1]); gq[i][j][2 * q4 + 1] = pack2(sg4[2], sg4[3]);
;         }
;         __builtin_amdgcn_sched_barrier(0);
;       }
.LBB0_920:
	v_lshrrev_b32_e32 v160, 1, v163
	v_lshrrev_b32_e32 v163, 3, v163
	v_and_b32_e32 v163, 4, v163
	v_and_or_b32 v160, v160, s39, v163
	v_lshlrev_b32_e32 v160, 2, v160
	v_add_u32_e32 v163, 0x24800, v160
	v_add_u32_e32 v164, 0x24c00, v160
	v_and_b32_e32 v167, 0x37c, v168
	ds_read_b128 v[170:173], v163
	ds_read_b128 v[174:177], v164
	v_or_b32_e32 v164, 0x24000, v167
	v_or_b32_e32 v166, 0x24080, v167
	v_or_b32_e32 v165, 0x24400, v167
	ds_read_b32 v168, v164
	ds_read_b32 v169, v165
	v_or_b32_e32 v167, 0x24480, v167
	ds_read_b32 v178, v166
	ds_read_b32 v179, v167
	s_waitcnt lgkmcnt(3)
	v_fma_f32 v112, -v170, v168, v112
	v_fma_f32 v113, -v171, v168, v113
	s_waitcnt lgkmcnt(1)
	v_fma_f32 v98, -v172, v178, v98
	v_fma_f32 v114, -v172, v168, v114
	v_fma_f32 v115, -v173, v168, v115
	v_fma_f32 v96, -v170, v178, v96
	v_fma_f32 v97, -v171, v178, v97
	s_waitcnt lgkmcnt(0)
	v_fma_f32 v98, v179, v98, v176
	v_fma_f32 v99, -v173, v178, v99
	v_fma_f32 v112, v169, v112, v174
	v_fma_f32 v113, v169, v113, v175
	v_fma_f32 v114, v169, v114, v176
	v_fma_f32 v115, v169, v115, v177
	v_fma_f32 v96, v179, v96, v174
	v_fma_f32 v97, v179, v97, v175
	v_mul_f32_e32 v98, 0xbfb8aa3b, v98
	v_fmac_f32_e32 v177, v179, v99
	v_mul_f32_e32 v112, 0xbfb8aa3b, v112
	v_mul_f32_e32 v113, 0xbfb8aa3b, v113
	v_mul_f32_e32 v114, 0xbfb8aa3b, v114
	v_mul_f32_e32 v115, 0xbfb8aa3b, v115
	v_mul_f32_e32 v96, 0xbfb8aa3b, v96
	v_mul_f32_e32 v97, 0xbfb8aa3b, v97
	v_exp_f32_e32 v98, v98
	v_mul_f32_e32 v99, 0xbfb8aa3b, v177
	v_exp_f32_e32 v112, v112
	v_exp_f32_e32 v113, v113
	v_exp_f32_e32 v114, v114
	v_exp_f32_e32 v115, v115
	v_exp_f32_e32 v96, v96
	v_exp_f32_e32 v97, v97
	v_exp_f32_e32 v99, v99
	v_add_f32_e32 v98, 1.0, v98
	v_add_f32_e32 v112, 1.0, v112
	v_add_f32_e32 v113, 1.0, v113
	v_add_f32_e32 v114, 1.0, v114
	v_add_f32_e32 v115, 1.0, v115
	v_add_f32_e32 v96, 1.0, v96
	v_add_f32_e32 v97, 1.0, v97
	v_rcp_f32_e32 v168, v98
	v_add_f32_e32 v98, 1.0, v99
	v_rcp_f32_e32 v112, v112
	v_rcp_f32_e32 v113, v113
	v_rcp_f32_e32 v114, v114
	v_rcp_f32_e32 v115, v115
	v_rcp_f32_e32 v96, v96
	v_rcp_f32_e32 v97, v97
	v_rcp_f32_e32 v169, v98
	v_cvt_pk_bf16_f32 v99, v112, v113
	v_cvt_pk_bf16_f32 v98, v114, v115
	v_cvt_pk_bf16_f32 v97, v96, v97
	v_cvt_pk_bf16_f32 v96, v168, v169
	v_add_u32_e32 v112, 0x24820, v160
	v_add_u32_e32 v168, 0x24c20, v160
	ds_read_b128 v[112:115], v112
	ds_read_b128 v[168:171], v168
	ds_read_b32 v172, v164
	ds_read_b32 v173, v165
	ds_read_b32 v174, v166
	ds_read_b32 v175, v167
	s_waitcnt lgkmcnt(3)
	v_fma_f32 v116, -v112, v172, v116
	v_fma_f32 v117, -v113, v172, v117
	s_waitcnt lgkmcnt(1)
	v_fma_f32 v102, -v114, v174, v102
	v_fma_f32 v118, -v114, v172, v118
	v_fma_f32 v119, -v115, v172, v119
	v_fma_f32 v100, -v112, v174, v100
	v_fma_f32 v101, -v113, v174, v101
	s_waitcnt lgkmcnt(0)
	v_fma_f32 v102, v175, v102, v170
	v_fma_f32 v103, -v115, v174, v103
	v_fma_f32 v116, v173, v116, v168
	v_fma_f32 v117, v173, v117, v169
	v_fma_f32 v118, v173, v118, v170
	v_fma_f32 v119, v173, v119, v171
	v_fma_f32 v100, v175, v100, v168
	v_fma_f32 v101, v175, v101, v169
	v_mul_f32_e32 v102, 0xbfb8aa3b, v102
	v_fmac_f32_e32 v171, v175, v103
	v_mul_f32_e32 v116, 0xbfb8aa3b, v116
	v_mul_f32_e32 v117, 0xbfb8aa3b, v117
	v_mul_f32_e32 v118, 0xbfb8aa3b, v118
	v_mul_f32_e32 v119, 0xbfb8aa3b, v119
	v_mul_f32_e32 v100, 0xbfb8aa3b, v100
	v_mul_f32_e32 v101, 0xbfb8aa3b, v101
	v_exp_f32_e32 v102, v102
	v_mul_f32_e32 v103, 0xbfb8aa3b, v171
	v_exp_f32_e32 v116, v116
	v_exp_f32_e32 v117, v117
	v_exp_f32_e32 v118, v118
	v_exp_f32_e32 v119, v119
	v_exp_f32_e32 v100, v100
	v_exp_f32_e32 v101, v101
	v_exp_f32_e32 v103, v103
	v_add_f32_e32 v102, 1.0, v102
	v_add_f32_e32 v116, 1.0, v116
	v_add_f32_e32 v117, 1.0, v117
	v_add_f32_e32 v118, 1.0, v118
	v_add_f32_e32 v119, 1.0, v119
	v_add_f32_e32 v100, 1.0, v100
	v_add_f32_e32 v101, 1.0, v101
	v_rcp_f32_e32 v113, v102
	v_add_f32_e32 v102, 1.0, v103
	v_rcp_f32_e32 v116, v116
	v_rcp_f32_e32 v117, v117
	v_rcp_f32_e32 v118, v118
	v_rcp_f32_e32 v112, v119
	v_rcp_f32_e32 v100, v100
	v_rcp_f32_e32 v101, v101
	v_rcp_f32_e32 v114, v102
	v_cvt_pk_bf16_f32 v103, v116, v117
	v_cvt_pk_bf16_f32 v102, v118, v112
	v_cvt_pk_bf16_f32 v101, v100, v101
	v_cvt_pk_bf16_f32 v100, v113, v114
	v_add_u32_e32 v112, 0x24840, v160
	v_add_u32_e32 v116, 0x24c40, v160
	ds_read_b128 v[112:115], v112
	ds_read_b128 v[116:119], v116
	ds_read_b32 v168, v164
	ds_read_b32 v169, v165
	ds_read_b32 v170, v166
	ds_read_b32 v171, v167
	s_waitcnt lgkmcnt(3)
	v_fma_f32 v120, -v112, v168, v120
	v_fma_f32 v121, -v113, v168, v121
	s_waitcnt lgkmcnt(1)
	v_fma_f32 v106, -v114, v170, v106
	v_fma_f32 v122, -v114, v168, v122
	v_fma_f32 v123, -v115, v168, v123
	v_fma_f32 v104, -v112, v170, v104
	v_fma_f32 v105, -v113, v170, v105
	s_waitcnt lgkmcnt(0)
	v_fma_f32 v106, v171, v106, v118
	v_fma_f32 v107, -v115, v170, v107
	v_fma_f32 v120, v169, v120, v116
	v_fma_f32 v121, v169, v121, v117
	v_fma_f32 v122, v169, v122, v118
	v_fma_f32 v123, v169, v123, v119
	v_fma_f32 v104, v171, v104, v116
	v_fma_f32 v105, v171, v105, v117
	v_mul_f32_e32 v106, 0xbfb8aa3b, v106
	v_fmac_f32_e32 v119, v171, v107
	v_mul_f32_e32 v120, 0xbfb8aa3b, v120
	v_mul_f32_e32 v121, 0xbfb8aa3b, v121
	v_mul_f32_e32 v122, 0xbfb8aa3b, v122
	v_mul_f32_e32 v123, 0xbfb8aa3b, v123
	v_mul_f32_e32 v104, 0xbfb8aa3b, v104
	v_mul_f32_e32 v105, 0xbfb8aa3b, v105
	v_exp_f32_e32 v106, v106
	v_mul_f32_e32 v107, 0xbfb8aa3b, v119
	v_exp_f32_e32 v120, v120
	v_exp_f32_e32 v121, v121
	v_exp_f32_e32 v122, v122
	v_exp_f32_e32 v123, v123
	v_exp_f32_e32 v104, v104
	v_exp_f32_e32 v105, v105
	v_exp_f32_e32 v107, v107
	v_add_f32_e32 v106, 1.0, v106
	v_add_f32_e32 v120, 1.0, v120
	v_add_f32_e32 v121, 1.0, v121
	v_add_f32_e32 v122, 1.0, v122
	v_add_f32_e32 v123, 1.0, v123
	v_add_f32_e32 v104, 1.0, v104
	v_add_f32_e32 v105, 1.0, v105
	v_rcp_f32_e32 v113, v106
	v_add_f32_e32 v106, 1.0, v107
	v_rcp_f32_e32 v120, v120
	v_rcp_f32_e32 v121, v121
	v_rcp_f32_e32 v122, v122
	v_rcp_f32_e32 v112, v123
	v_rcp_f32_e32 v104, v104
	v_rcp_f32_e32 v105, v105
	v_rcp_f32_e32 v114, v106
	v_cvt_pk_bf16_f32 v107, v120, v121
	v_cvt_pk_bf16_f32 v106, v122, v112
	v_cvt_pk_bf16_f32 v105, v104, v105
	v_cvt_pk_bf16_f32 v104, v113, v114
	v_add_u32_e32 v112, 0x24860, v160
	v_add_u32_e32 v116, 0x24c60, v160
	ds_read_b128 v[112:115], v112
	ds_read_b128 v[116:119], v116
	ds_read_b32 v120, v164
	ds_read_b32 v121, v165
	ds_read_b32 v122, v166
	ds_read_b32 v123, v167
	s_waitcnt lgkmcnt(3)
; DI unsigned pack2(float a, float b) { f32x2_t v = {a, b}; bf16x2_t r = __builtin_convertvector(v, bf16x2_t); return __builtin_bit_cast(unsigned, r); }
; DI float sigmoidf_(float x) { return __builtin_amdgcn_rcpf(1.f + __expf(-x)); }
; template <bool LAST>
; DI void phase_gate(const Params& P, int layer, unsigned char* smem, int L, int G) {
;     ...
;     unsigned gq[4][2][8];
; #pragma unroll
;     for (int i = 0; i < 4; ++i)
; #pragma unroll
;       for (int q4 = 0; q4 < 4; ++q4) {
;         const int fl = wm * 128 + i * 32 + 8 * q4 + 4 * h;
;         const f32x4 c1v = *(const f32x4*)(vecL + fl), c2v = *(const f32x4*)(vecL + 256 + fl);
;         const float c1a[4] = {c1v.x, c1v.y, c1v.z, c1v.w}, c2a[4] = {c2v.x, c2v.y, c2v.z, c2v.w};
; #pragma unroll
;         for (int j = 0; j < 2; ++j) {
;           const int lrow = wn * 64 + j * 32 + r;
;           const float mu = rowA[lrow], rstd = rowB[lrow];
;           float sg4[4];
; #pragma unroll
;           for (int e = 0; e < 4; ++e) sg4[e] = sigmoidf_(rstd * (accu[i][j][4 * q4 + e] - mu * c1a[e]) + c2a[e]);
;           gq[i][j][2 * q4] = pack2(sg4[0], sg4[1]); gq[i][j][2 * q4 + 1] = pack2(sg4[2], sg4[3]);
;         }
;         __builtin_amdgcn_sched_barrier(0);
;       }
	v_fma_f32 v125, -v113, v120, v125
	v_fma_f32 v124, -v112, v120, v124
	s_waitcnt lgkmcnt(1)
	v_fma_f32 v110, -v114, v122, v110
	v_fma_f32 v125, v121, v125, v117
	v_fma_f32 v126, -v114, v120, v126
	v_fma_f32 v120, -v115, v120, v127
	v_fma_f32 v108, -v112, v122, v108
	v_fma_f32 v109, -v113, v122, v109
	s_waitcnt lgkmcnt(0)
	v_fma_f32 v110, v123, v110, v118
	v_fma_f32 v111, -v115, v122, v111
	v_fma_f32 v124, v121, v124, v116
	v_mul_f32_e32 v125, 0xbfb8aa3b, v125
	v_fma_f32 v126, v121, v126, v118
	v_fma_f32 v120, v121, v120, v119
	v_fma_f32 v108, v123, v108, v116
	v_fma_f32 v109, v123, v109, v117
	v_mul_f32_e32 v110, 0xbfb8aa3b, v110
	v_fmac_f32_e32 v119, v123, v111
	v_mul_f32_e32 v124, 0xbfb8aa3b, v124
	v_exp_f32_e32 v125, v125
	v_mul_f32_e32 v126, 0xbfb8aa3b, v126
	v_mul_f32_e32 v120, 0xbfb8aa3b, v120
	v_mul_f32_e32 v108, 0xbfb8aa3b, v108
	v_mul_f32_e32 v109, 0xbfb8aa3b, v109
	v_exp_f32_e32 v110, v110
	v_mul_f32_e32 v111, 0xbfb8aa3b, v119
	v_exp_f32_e32 v124, v124
	v_exp_f32_e32 v126, v126
	v_exp_f32_e32 v120, v120
	v_exp_f32_e32 v108, v108
	v_exp_f32_e32 v109, v109
	v_exp_f32_e32 v111, v111
	v_add_f32_e32 v125, 1.0, v125
	v_add_f32_e32 v110, 1.0, v110
	v_add_f32_e32 v124, 1.0, v124
	v_rcp_f32_e32 v121, v125
	v_add_f32_e32 v125, 1.0, v126
	v_add_f32_e32 v120, 1.0, v120
	v_add_f32_e32 v108, 1.0, v108
	v_add_f32_e32 v109, 1.0, v109
	v_rcp_f32_e32 v113, v110
	v_add_f32_e32 v110, 1.0, v111
	v_rcp_f32_e32 v124, v124
	v_rcp_f32_e32 v125, v125
	v_rcp_f32_e32 v112, v120
	v_rcp_f32_e32 v108, v108
	v_rcp_f32_e32 v109, v109
	v_rcp_f32_e32 v114, v110
	v_cvt_pk_bf16_f32 v111, v124, v121
	v_cvt_pk_bf16_f32 v110, v125, v112
	v_cvt_pk_bf16_f32 v109, v108, v109
	v_cvt_pk_bf16_f32 v108, v113, v114
	v_add_u32_e32 v112, 0x24880, v160
	v_add_u32_e32 v116, 0x24c80, v160
	ds_read_b128 v[112:115], v112
	ds_read_b128 v[116:119], v116
	ds_read_b32 v120, v164
	ds_read_b32 v121, v165
	ds_read_b32 v122, v166
	ds_read_b32 v123, v167
	s_waitcnt lgkmcnt(3)
	v_fma_f32 v80, -v112, v120, v80
	v_fma_f32 v81, -v113, v120, v81
	s_waitcnt lgkmcnt(1)
	v_fma_f32 v66, -v114, v122, v66
	v_fma_f32 v82, -v114, v120, v82
	v_fma_f32 v83, -v115, v120, v83
	v_fma_f32 v64, -v112, v122, v64
	v_fma_f32 v65, -v113, v122, v65
	s_waitcnt lgkmcnt(0)
	v_fma_f32 v66, v123, v66, v118
	v_fma_f32 v67, -v115, v122, v67
	v_fma_f32 v80, v121, v80, v116
	v_fma_f32 v81, v121, v81, v117
	v_fma_f32 v82, v121, v82, v118
	v_fma_f32 v83, v121, v83, v119
	v_fma_f32 v64, v123, v64, v116
	v_fma_f32 v65, v123, v65, v117
	v_mul_f32_e32 v66, 0xbfb8aa3b, v66
	v_fmac_f32_e32 v119, v123, v67
	v_mul_f32_e32 v80, 0xbfb8aa3b, v80
	v_mul_f32_e32 v81, 0xbfb8aa3b, v81
	v_mul_f32_e32 v82, 0xbfb8aa3b, v82
	v_mul_f32_e32 v83, 0xbfb8aa3b, v83
	v_mul_f32_e32 v64, 0xbfb8aa3b, v64
	v_mul_f32_e32 v65, 0xbfb8aa3b, v65
	v_exp_f32_e32 v66, v66
	v_mul_f32_e32 v67, 0xbfb8aa3b, v119
	v_exp_f32_e32 v80, v80
	v_exp_f32_e32 v81, v81
	v_exp_f32_e32 v82, v82
	v_exp_f32_e32 v83, v83
	v_exp_f32_e32 v64, v64
	v_exp_f32_e32 v65, v65
	v_exp_f32_e32 v67, v67
	v_add_f32_e32 v66, 1.0, v66
	v_add_f32_e32 v80, 1.0, v80
	v_add_f32_e32 v81, 1.0, v81
	v_add_f32_e32 v82, 1.0, v82
	v_add_f32_e32 v83, 1.0, v83
	v_add_f32_e32 v64, 1.0, v64
	v_add_f32_e32 v65, 1.0, v65
	v_rcp_f32_e32 v112, v66
	v_add_f32_e32 v66, 1.0, v67
	v_rcp_f32_e32 v80, v80
	v_rcp_f32_e32 v81, v81
	v_rcp_f32_e32 v82, v82
	v_rcp_f32_e32 v83, v83
	v_rcp_f32_e32 v64, v64
	v_rcp_f32_e32 v65, v65
	v_rcp_f32_e32 v113, v66
	v_cvt_pk_bf16_f32 v67, v80, v81
	v_cvt_pk_bf16_f32 v66, v82, v83
	v_cvt_pk_bf16_f32 v65, v64, v65
	v_cvt_pk_bf16_f32 v64, v112, v113
	v_add_u32_e32 v80, 0x248a0, v160
	v_add_u32_e32 v112, 0x24ca0, v160
	ds_read_b128 v[80:83], v80
	ds_read_b128 v[112:115], v112
	ds_read_b32 v116, v164
	ds_read_b32 v117, v165
	ds_read_b32 v118, v166
	ds_read_b32 v119, v167
	s_waitcnt lgkmcnt(3)
	v_fma_f32 v84, -v80, v116, v84
	v_fma_f32 v85, -v81, v116, v85
	s_waitcnt lgkmcnt(1)
	v_fma_f32 v70, -v82, v118, v70
	v_fma_f32 v86, -v82, v116, v86
	v_fma_f32 v87, -v83, v116, v87
	v_fma_f32 v68, -v80, v118, v68
	v_fma_f32 v69, -v81, v118, v69
	s_waitcnt lgkmcnt(0)
	v_fma_f32 v70, v119, v70, v114
	v_fma_f32 v71, -v83, v118, v71
	v_fma_f32 v84, v117, v84, v112
	v_fma_f32 v85, v117, v85, v113
	v_fma_f32 v86, v117, v86, v114
	v_fma_f32 v87, v117, v87, v115
	v_fma_f32 v68, v119, v68, v112
	v_fma_f32 v69, v119, v69, v113
	v_mul_f32_e32 v70, 0xbfb8aa3b, v70
	v_fmac_f32_e32 v115, v119, v71
	v_mul_f32_e32 v84, 0xbfb8aa3b, v84
	v_mul_f32_e32 v85, 0xbfb8aa3b, v85
	v_mul_f32_e32 v86, 0xbfb8aa3b, v86
	v_mul_f32_e32 v87, 0xbfb8aa3b, v87
	v_mul_f32_e32 v68, 0xbfb8aa3b, v68
	v_mul_f32_e32 v69, 0xbfb8aa3b, v69
	v_exp_f32_e32 v70, v70
	v_mul_f32_e32 v71, 0xbfb8aa3b, v115
	v_exp_f32_e32 v84, v84
	v_exp_f32_e32 v85, v85
	v_exp_f32_e32 v86, v86
	v_exp_f32_e32 v87, v87
	v_exp_f32_e32 v68, v68
	v_exp_f32_e32 v69, v69
	v_exp_f32_e32 v71, v71
	v_add_f32_e32 v70, 1.0, v70
	v_add_f32_e32 v84, 1.0, v84
	v_add_f32_e32 v85, 1.0, v85
	v_add_f32_e32 v86, 1.0, v86
	v_add_f32_e32 v87, 1.0, v87
	v_add_f32_e32 v68, 1.0, v68
	v_add_f32_e32 v69, 1.0, v69
	v_rcp_f32_e32 v81, v70
	v_add_f32_e32 v70, 1.0, v71
	v_rcp_f32_e32 v84, v84
	v_rcp_f32_e32 v85, v85
	v_rcp_f32_e32 v86, v86
	v_rcp_f32_e32 v80, v87
	v_rcp_f32_e32 v68, v68
	v_rcp_f32_e32 v69, v69
	v_rcp_f32_e32 v82, v70
	v_cvt_pk_bf16_f32 v71, v84, v85
	v_cvt_pk_bf16_f32 v70, v86, v80
	v_cvt_pk_bf16_f32 v69, v68, v69
	v_cvt_pk_bf16_f32 v68, v81, v82
	v_add_u32_e32 v80, 0x248c0, v160
	v_add_u32_e32 v84, 0x24cc0, v160
	ds_read_b128 v[80:83], v80
	ds_read_b128 v[84:87], v84
	ds_read_b32 v112, v164
	ds_read_b32 v113, v165
	ds_read_b32 v114, v166
	ds_read_b32 v115, v167
	s_waitcnt lgkmcnt(3)
; DI unsigned pack2(float a, float b) { f32x2_t v = {a, b}; bf16x2_t r = __builtin_convertvector(v, bf16x2_t); return __builtin_bit_cast(unsigned, r); }
; DI float sigmoidf_(float x) { return __builtin_amdgcn_rcpf(1.f + __expf(-x)); }
; template <bool LAST>
; DI void phase_gate(const Params& P, int layer, unsigned char* smem, int L, int G) {
;     ...
;     unsigned gq[4][2][8];
; #pragma unroll
;     for (int i = 0; i < 4; ++i)
; #pragma unroll
;       for (int q4 = 0; q4 < 4; ++q4) {
;         const int fl = wm * 128 + i * 32 + 8 * q4 + 4 * h;
;         const f32x4 c1v = *(const f32x4*)(vecL + fl), c2v = *(const f32x4*)(vecL + 256 + fl);
;         const float c1a[4] = {c1v.x, c1v.y, c1v.z, c1v.w}, c2a[4] = {c2v.x, c2v.y, c2v.z, c2v.w};
; #pragma unroll
;         for (int j = 0; j < 2; ++j) {
;           const int lrow = wn * 64 + j * 32 + r;
;           const float mu = rowA[lrow], rstd = rowB[lrow];
;           float sg4[4];
; #pragma unroll
;           for (int e = 0; e < 4; ++e) sg4[e] = sigmoidf_(rstd * (accu[i][j][4 * q4 + e] - mu * c1a[e]) + c2a[e]);
;           gq[i][j][2 * q4] = pack2(sg4[0], sg4[1]); gq[i][j][2 * q4 + 1] = pack2(sg4[2], sg4[3]);
;         }
;         __builtin_amdgcn_sched_barrier(0);
;       }
	v_fma_f32 v88, -v80, v112, v88
	v_fma_f32 v89, -v81, v112, v89
	s_waitcnt lgkmcnt(1)
	v_fma_f32 v74, -v82, v114, v74
	v_fma_f32 v90, -v82, v112, v90
	v_fma_f32 v91, -v83, v112, v91
	v_fma_f32 v72, -v80, v114, v72
	v_fma_f32 v73, -v81, v114, v73
	s_waitcnt lgkmcnt(0)
	v_fma_f32 v74, v115, v74, v86
	v_fma_f32 v75, -v83, v114, v75
	v_fma_f32 v88, v113, v88, v84
	v_fma_f32 v89, v113, v89, v85
	v_fma_f32 v90, v113, v90, v86
	v_fma_f32 v91, v113, v91, v87
	v_fma_f32 v72, v115, v72, v84
	v_fma_f32 v73, v115, v73, v85
	v_mul_f32_e32 v74, 0xbfb8aa3b, v74
	v_fmac_f32_e32 v87, v115, v75
	v_mul_f32_e32 v88, 0xbfb8aa3b, v88
	v_mul_f32_e32 v89, 0xbfb8aa3b, v89
	v_mul_f32_e32 v90, 0xbfb8aa3b, v90
	v_mul_f32_e32 v91, 0xbfb8aa3b, v91
	v_mul_f32_e32 v72, 0xbfb8aa3b, v72
	v_mul_f32_e32 v73, 0xbfb8aa3b, v73
	v_exp_f32_e32 v74, v74
	v_mul_f32_e32 v75, 0xbfb8aa3b, v87
	v_exp_f32_e32 v88, v88
	v_exp_f32_e32 v89, v89
	v_exp_f32_e32 v90, v90
	v_exp_f32_e32 v91, v91
	v_exp_f32_e32 v72, v72
	v_exp_f32_e32 v73, v73
	v_exp_f32_e32 v75, v75
	v_add_f32_e32 v74, 1.0, v74
	v_add_f32_e32 v88, 1.0, v88
	v_add_f32_e32 v89, 1.0, v89
	v_add_f32_e32 v90, 1.0, v90
	v_add_f32_e32 v91, 1.0, v91
	v_add_f32_e32 v72, 1.0, v72
	v_add_f32_e32 v73, 1.0, v73
	v_rcp_f32_e32 v81, v74
	v_add_f32_e32 v74, 1.0, v75
	v_rcp_f32_e32 v88, v88
	v_rcp_f32_e32 v89, v89
	v_rcp_f32_e32 v90, v90
	v_rcp_f32_e32 v80, v91
	v_rcp_f32_e32 v72, v72
	v_rcp_f32_e32 v73, v73
	v_rcp_f32_e32 v82, v74
	v_cvt_pk_bf16_f32 v75, v88, v89
	v_cvt_pk_bf16_f32 v74, v90, v80
	v_cvt_pk_bf16_f32 v73, v72, v73
	v_cvt_pk_bf16_f32 v72, v81, v82
	v_add_u32_e32 v80, 0x248e0, v160
	v_add_u32_e32 v84, 0x24ce0, v160
	ds_read_b128 v[80:83], v80
	ds_read_b128 v[84:87], v84
	ds_read_b32 v88, v164
	ds_read_b32 v89, v165
	ds_read_b32 v90, v166
	ds_read_b32 v91, v167
	s_waitcnt lgkmcnt(3)
	v_fma_f32 v93, -v81, v88, v93
	v_fma_f32 v92, -v80, v88, v92
	s_waitcnt lgkmcnt(1)
	v_fma_f32 v78, -v82, v90, v78
	v_fma_f32 v93, v89, v93, v85
	v_fma_f32 v94, -v82, v88, v94
	v_fma_f32 v88, -v83, v88, v95
	v_fma_f32 v76, -v80, v90, v76
	v_fma_f32 v77, -v81, v90, v77
	s_waitcnt lgkmcnt(0)
	v_fma_f32 v78, v91, v78, v86
	v_fma_f32 v79, -v83, v90, v79
	v_fma_f32 v92, v89, v92, v84
	v_mul_f32_e32 v93, 0xbfb8aa3b, v93
	v_fma_f32 v94, v89, v94, v86
	v_fma_f32 v88, v89, v88, v87
	v_fma_f32 v76, v91, v76, v84
	v_fma_f32 v77, v91, v77, v85
	v_mul_f32_e32 v78, 0xbfb8aa3b, v78
	v_fmac_f32_e32 v87, v91, v79
	v_mul_f32_e32 v92, 0xbfb8aa3b, v92
	v_exp_f32_e32 v93, v93
	v_mul_f32_e32 v94, 0xbfb8aa3b, v94
	v_mul_f32_e32 v88, 0xbfb8aa3b, v88
	v_mul_f32_e32 v76, 0xbfb8aa3b, v76
	v_mul_f32_e32 v77, 0xbfb8aa3b, v77
	v_exp_f32_e32 v78, v78
	v_mul_f32_e32 v79, 0xbfb8aa3b, v87
	v_exp_f32_e32 v92, v92
	v_exp_f32_e32 v94, v94
	v_exp_f32_e32 v88, v88
	v_exp_f32_e32 v76, v76
	v_exp_f32_e32 v77, v77
	v_exp_f32_e32 v79, v79
	v_add_f32_e32 v93, 1.0, v93
	v_add_f32_e32 v78, 1.0, v78
	v_add_f32_e32 v92, 1.0, v92
	v_rcp_f32_e32 v89, v93
	v_add_f32_e32 v93, 1.0, v94
	v_add_f32_e32 v88, 1.0, v88
	v_add_f32_e32 v76, 1.0, v76
	v_add_f32_e32 v77, 1.0, v77
	v_rcp_f32_e32 v81, v78
	v_add_f32_e32 v78, 1.0, v79
	v_rcp_f32_e32 v92, v92
	v_rcp_f32_e32 v93, v93
	v_rcp_f32_e32 v80, v88
	v_rcp_f32_e32 v76, v76
	v_rcp_f32_e32 v77, v77
	v_rcp_f32_e32 v82, v78
	v_cvt_pk_bf16_f32 v79, v92, v89
	v_cvt_pk_bf16_f32 v78, v93, v80
	v_cvt_pk_bf16_f32 v77, v76, v77
	v_cvt_pk_bf16_f32 v76, v81, v82
	v_add_u32_e32 v80, 0x24900, v160
	v_add_u32_e32 v84, 0x24d00, v160
	ds_read_b128 v[80:83], v80
	ds_read_b128 v[84:87], v84
	ds_read_b32 v88, v164
	ds_read_b32 v89, v165
	ds_read_b32 v90, v166
	ds_read_b32 v91, v167
	s_waitcnt lgkmcnt(3)
	v_fma_f32 v48, -v80, v88, v48
	v_fma_f32 v49, -v81, v88, v49
	s_waitcnt lgkmcnt(1)
	v_fma_f32 v34, -v82, v90, v34
	v_fma_f32 v50, -v82, v88, v50
	v_fma_f32 v51, -v83, v88, v51
	v_fma_f32 v32, -v80, v90, v32
	v_fma_f32 v33, -v81, v90, v33
	s_waitcnt lgkmcnt(0)
	v_fma_f32 v34, v91, v34, v86
	v_fma_f32 v35, -v83, v90, v35
	v_fma_f32 v48, v89, v48, v84
	v_fma_f32 v49, v89, v49, v85
	v_fma_f32 v50, v89, v50, v86
	v_fma_f32 v51, v89, v51, v87
	v_fma_f32 v32, v91, v32, v84
	v_fma_f32 v33, v91, v33, v85
	v_mul_f32_e32 v34, 0xbfb8aa3b, v34
	v_fmac_f32_e32 v87, v91, v35
	v_mul_f32_e32 v48, 0xbfb8aa3b, v48
	v_mul_f32_e32 v49, 0xbfb8aa3b, v49
	v_mul_f32_e32 v50, 0xbfb8aa3b, v50
	v_mul_f32_e32 v51, 0xbfb8aa3b, v51
	v_mul_f32_e32 v32, 0xbfb8aa3b, v32
	v_mul_f32_e32 v33, 0xbfb8aa3b, v33
	v_exp_f32_e32 v34, v34
	v_mul_f32_e32 v35, 0xbfb8aa3b, v87
	v_exp_f32_e32 v48, v48
	v_exp_f32_e32 v49, v49
	v_exp_f32_e32 v50, v50
	v_exp_f32_e32 v51, v51
	v_exp_f32_e32 v32, v32
	v_exp_f32_e32 v33, v33
	v_exp_f32_e32 v35, v35
	v_add_f32_e32 v34, 1.0, v34
	v_add_f32_e32 v48, 1.0, v48
	v_add_f32_e32 v49, 1.0, v49
	v_add_f32_e32 v50, 1.0, v50
	v_add_f32_e32 v51, 1.0, v51
	v_add_f32_e32 v32, 1.0, v32
	v_add_f32_e32 v33, 1.0, v33
	v_rcp_f32_e32 v80, v34
	v_add_f32_e32 v34, 1.0, v35
	v_rcp_f32_e32 v48, v48
	v_rcp_f32_e32 v49, v49
	v_rcp_f32_e32 v50, v50
	v_rcp_f32_e32 v51, v51
	v_rcp_f32_e32 v32, v32
	v_rcp_f32_e32 v33, v33
	v_rcp_f32_e32 v81, v34
	v_cvt_pk_bf16_f32 v35, v48, v49
	v_cvt_pk_bf16_f32 v34, v50, v51
	v_cvt_pk_bf16_f32 v33, v32, v33
	v_cvt_pk_bf16_f32 v32, v80, v81
	v_add_u32_e32 v48, 0x24920, v160
	v_add_u32_e32 v80, 0x24d20, v160
	ds_read_b128 v[48:51], v48
	ds_read_b128 v[80:83], v80
	ds_read_b32 v84, v164
	ds_read_b32 v85, v165
	ds_read_b32 v86, v166
	ds_read_b32 v87, v167
	s_waitcnt lgkmcnt(3)
	v_fma_f32 v53, -v49, v84, v53
	v_fma_f32 v52, -v48, v84, v52
	s_waitcnt lgkmcnt(1)
	v_fma_f32 v36, -v48, v86, v36
	s_waitcnt lgkmcnt(0)
; DI unsigned pack2(float a, float b) { f32x2_t v = {a, b}; bf16x2_t r = __builtin_convertvector(v, bf16x2_t); return __builtin_bit_cast(unsigned, r); }
; DI float sigmoidf_(float x) { return __builtin_amdgcn_rcpf(1.f + __expf(-x)); }
; template <bool LAST>
; DI void phase_gate(const Params& P, int layer, unsigned char* smem, int L, int G) {
;     ...
;     unsigned gq[4][2][8];
; #pragma unroll
;     for (int i = 0; i < 4; ++i)
; #pragma unroll
;       for (int q4 = 0; q4 < 4; ++q4) {
;         const int fl = wm * 128 + i * 32 + 8 * q4 + 4 * h;
;         const f32x4 c1v = *(const f32x4*)(vecL + fl), c2v = *(const f32x4*)(vecL + 256 + fl);
;         const float c1a[4] = {c1v.x, c1v.y, c1v.z, c1v.w}, c2a[4] = {c2v.x, c2v.y, c2v.z, c2v.w};
; #pragma unroll
;         for (int j = 0; j < 2; ++j) {
;           const int lrow = wn * 64 + j * 32 + r;
;           const float mu = rowA[lrow], rstd = rowB[lrow];
;           float sg4[4];
; #pragma unroll
;           for (int e = 0; e < 4; ++e) sg4[e] = sigmoidf_(rstd * (accu[i][j][4 * q4 + e] - mu * c1a[e]) + c2a[e]);
;           gq[i][j][2 * q4] = pack2(sg4[0], sg4[1]); gq[i][j][2 * q4 + 1] = pack2(sg4[2], sg4[3]);
;         }
;         __builtin_amdgcn_sched_barrier(0);
;       }
	v_fma_f32 v36, v87, v36, v80
	v_fma_f32 v37, -v49, v86, v37
	v_mul_f32_e32 v36, 0xbfb8aa3b, v36
	v_fma_f32 v37, v87, v37, v81
	v_exp_f32_e32 v36, v36
	v_mul_f32_e32 v37, 0xbfb8aa3b, v37
	v_exp_f32_e32 v37, v37
	v_fma_f32 v54, -v50, v84, v54
	v_add_f32_e32 v36, 1.0, v36
	v_rcp_f32_e32 v49, v36
	v_add_f32_e32 v36, 1.0, v37
	v_fma_f32 v37, -v50, v86, v38
	v_fma_f32 v55, -v51, v84, v55
	v_fma_f32 v37, v87, v37, v82
	v_fma_f32 v38, -v51, v86, v39
	v_fma_f32 v52, v85, v52, v80
	v_fma_f32 v53, v85, v53, v81
	v_fma_f32 v54, v85, v54, v82
	v_fma_f32 v55, v85, v55, v83
	v_mul_f32_e32 v37, 0xbfb8aa3b, v37
	v_fmac_f32_e32 v83, v87, v38
	v_mul_f32_e32 v52, 0xbfb8aa3b, v52
	v_mul_f32_e32 v53, 0xbfb8aa3b, v53
	v_mul_f32_e32 v54, 0xbfb8aa3b, v54
	v_mul_f32_e32 v55, 0xbfb8aa3b, v55
	v_exp_f32_e32 v37, v37
	v_mul_f32_e32 v38, 0xbfb8aa3b, v83
	v_exp_f32_e32 v52, v52
	v_exp_f32_e32 v53, v53
	v_exp_f32_e32 v54, v54
	v_exp_f32_e32 v55, v55
	v_exp_f32_e32 v38, v38
	v_rcp_f32_e32 v39, v36
	v_add_f32_e32 v36, 1.0, v37
	v_add_f32_e32 v52, 1.0, v52
	v_add_f32_e32 v53, 1.0, v53
	v_add_f32_e32 v54, 1.0, v54
	v_add_f32_e32 v55, 1.0, v55
	v_rcp_f32_e32 v37, v36
	v_add_f32_e32 v36, 1.0, v38
	v_rcp_f32_e32 v52, v52
	v_rcp_f32_e32 v53, v53
	v_rcp_f32_e32 v54, v54
	v_rcp_f32_e32 v48, v55
	v_rcp_f32_e32 v38, v36
	v_cvt_pk_bf16_f32 v80, v52, v53
	v_cvt_pk_bf16_f32 v55, v49, v39
	v_cvt_pk_bf16_f32 v36, v54, v48
	v_cvt_pk_bf16_f32 v53, v37, v38
	v_add_u32_e32 v37, 0x24940, v160
	v_add_u32_e32 v38, 0x24d40, v160
	ds_read_b128 v[48:51], v37
	ds_read_b128 v[82:85], v38
	ds_read_b32 v37, v164
	ds_read_b32 v38, v165
	ds_read_b32 v39, v166
	ds_read_b32 v52, v167
	s_waitcnt lgkmcnt(3)
	v_fma_f32 v54, -v48, v37, v56
	v_fma_f32 v56, -v49, v37, v57
	s_waitcnt lgkmcnt(2)
	v_fma_f32 v56, v38, v56, v83
	v_fma_f32 v57, -v50, v37, v58
	v_fma_f32 v37, -v51, v37, v59
	s_waitcnt lgkmcnt(1)
	v_fma_f32 v40, -v48, v39, v40
	v_fma_f32 v41, -v49, v39, v41
	v_fma_f32 v42, -v50, v39, v42
	v_fma_f32 v39, -v51, v39, v43
	v_fma_f32 v54, v38, v54, v82
	v_mul_f32_e32 v56, 0xbfb8aa3b, v56
	v_fma_f32 v57, v38, v57, v84
	v_fma_f32 v37, v38, v37, v85
	s_waitcnt lgkmcnt(0)
	v_fma_f32 v40, v52, v40, v82
	v_fma_f32 v41, v52, v41, v83
	v_fma_f32 v42, v52, v42, v84
	v_fmac_f32_e32 v85, v52, v39
	v_mul_f32_e32 v54, 0xbfb8aa3b, v54
	v_exp_f32_e32 v56, v56
	v_mul_f32_e32 v57, 0xbfb8aa3b, v57
	v_mul_f32_e32 v37, 0xbfb8aa3b, v37
	v_mul_f32_e32 v40, 0xbfb8aa3b, v40
	v_mul_f32_e32 v41, 0xbfb8aa3b, v41
	v_mul_f32_e32 v42, 0xbfb8aa3b, v42
	v_mul_f32_e32 v39, 0xbfb8aa3b, v85
	v_exp_f32_e32 v54, v54
	v_exp_f32_e32 v57, v57
	v_exp_f32_e32 v37, v37
	v_exp_f32_e32 v40, v40
	v_exp_f32_e32 v41, v41
	v_exp_f32_e32 v42, v42
	v_exp_f32_e32 v39, v39
	v_add_f32_e32 v56, 1.0, v56
	v_add_f32_e32 v54, 1.0, v54
	v_rcp_f32_e32 v38, v56
	v_add_f32_e32 v56, 1.0, v57
	v_add_f32_e32 v37, 1.0, v37
	v_add_f32_e32 v40, 1.0, v40
	v_add_f32_e32 v41, 1.0, v41
	v_add_f32_e32 v42, 1.0, v42
	v_add_f32_e32 v39, 1.0, v39
	v_rcp_f32_e32 v54, v54
	v_rcp_f32_e32 v56, v56
	v_rcp_f32_e32 v37, v37
	v_rcp_f32_e32 v40, v40
	v_rcp_f32_e32 v41, v41
	v_rcp_f32_e32 v42, v42
	v_rcp_f32_e32 v39, v39
	v_cvt_pk_bf16_f32 v83, v54, v38
	v_cvt_pk_bf16_f32 v82, v56, v37
	v_cvt_pk_bf16_f32 v81, v40, v41
	v_cvt_pk_bf16_f32 v59, v42, v39
	v_add_u32_e32 v37, 0x24960, v160
	v_add_u32_e32 v42, 0x24d60, v160
	ds_read_b128 v[38:41], v37
	ds_read_b128 v[48:51], v42
	ds_read_b32 v37, v164
	ds_read_b32 v42, v165
	ds_read_b32 v43, v166
	ds_read_b32 v52, v167
	s_waitcnt lgkmcnt(3)
	v_fma_f32 v56, -v39, v37, v61
	v_fma_f32 v54, -v38, v37, v60
	s_waitcnt lgkmcnt(2)
	v_fma_f32 v56, v42, v56, v49
	v_fma_f32 v57, -v40, v37, v62
	v_fma_f32 v37, -v41, v37, v63
	s_waitcnt lgkmcnt(1)
	v_fma_f32 v38, -v38, v43, v44
	v_fma_f32 v39, -v39, v43, v45
	v_fma_f32 v40, -v40, v43, v46
	v_fma_f32 v41, -v41, v43, v47
	v_fma_f32 v54, v42, v54, v48
	v_mul_f32_e32 v56, 0xbfb8aa3b, v56
	v_fma_f32 v57, v42, v57, v50
	v_fma_f32 v37, v42, v37, v51
	s_waitcnt lgkmcnt(0)
	v_fma_f32 v38, v52, v38, v48
	v_fma_f32 v39, v52, v39, v49
	v_fma_f32 v40, v52, v40, v50
	v_fmac_f32_e32 v51, v52, v41
	v_mul_f32_e32 v54, 0xbfb8aa3b, v54
	v_exp_f32_e32 v56, v56
	v_mul_f32_e32 v57, 0xbfb8aa3b, v57
	v_mul_f32_e32 v37, 0xbfb8aa3b, v37
	v_mul_f32_e32 v38, 0xbfb8aa3b, v38
	v_mul_f32_e32 v39, 0xbfb8aa3b, v39
	v_mul_f32_e32 v40, 0xbfb8aa3b, v40
	v_mul_f32_e32 v41, 0xbfb8aa3b, v51
	v_exp_f32_e32 v54, v54
	v_exp_f32_e32 v57, v57
	v_exp_f32_e32 v37, v37
	v_exp_f32_e32 v38, v38
	v_exp_f32_e32 v39, v39
	v_exp_f32_e32 v40, v40
	v_exp_f32_e32 v41, v41
	v_add_f32_e32 v56, 1.0, v56
	v_add_f32_e32 v54, 1.0, v54
	v_rcp_f32_e32 v42, v56
	v_add_f32_e32 v56, 1.0, v57
	v_add_f32_e32 v37, 1.0, v37
	v_add_f32_e32 v38, 1.0, v38
	v_add_f32_e32 v39, 1.0, v39
	v_add_f32_e32 v40, 1.0, v40
	v_add_f32_e32 v41, 1.0, v41
	v_rcp_f32_e32 v54, v54
	v_rcp_f32_e32 v56, v56
	v_rcp_f32_e32 v37, v37
	v_rcp_f32_e32 v38, v38
	v_rcp_f32_e32 v39, v39
	v_rcp_f32_e32 v40, v40
	v_rcp_f32_e32 v41, v41
	v_cvt_pk_bf16_f32 v91, v54, v42
	v_cvt_pk_bf16_f32 v86, v56, v37
	v_cvt_pk_bf16_f32 v85, v38, v39
	v_cvt_pk_bf16_f32 v84, v40, v41
	v_add_u32_e32 v37, 0x24980, v160
	v_add_u32_e32 v42, 0x24d80, v160
	ds_read_b128 v[38:41], v37
	ds_read_b128 v[42:45], v42
	ds_read_b32 v37, v164
	ds_read_b32 v46, v165
	ds_read_b32 v47, v166
	ds_read_b32 v48, v167
	s_waitcnt lgkmcnt(3)
	v_fma_f32 v16, -v38, v37, v16
	v_fma_f32 v17, -v39, v37, v17
	v_fma_f32 v18, -v40, v37, v18
	v_fma_f32 v19, -v41, v37, v19
	s_waitcnt lgkmcnt(1)
	v_fma_f32 v0, -v38, v47, v0
	v_fma_f32 v1, -v39, v47, v1
	v_fma_f32 v2, -v40, v47, v2
	v_fma_f32 v3, -v41, v47, v3
	v_fma_f32 v16, v46, v16, v42
	v_fma_f32 v17, v46, v17, v43
	v_fma_f32 v18, v46, v18, v44
	v_fma_f32 v19, v46, v19, v45
	s_waitcnt lgkmcnt(0)
; DI unsigned pack2(float a, float b) { f32x2_t v = {a, b}; bf16x2_t r = __builtin_convertvector(v, bf16x2_t); return __builtin_bit_cast(unsigned, r); }
; DI float sigmoidf_(float x) { return __builtin_amdgcn_rcpf(1.f + __expf(-x)); }
; template <bool LAST>
; DI void phase_gate(const Params& P, int layer, unsigned char* smem, int L, int G) {
;     ...
;     unsigned gq[4][2][8];
; #pragma unroll
;     for (int i = 0; i < 4; ++i)
; #pragma unroll
;       for (int q4 = 0; q4 < 4; ++q4) {
;         const int fl = wm * 128 + i * 32 + 8 * q4 + 4 * h;
;         const f32x4 c1v = *(const f32x4*)(vecL + fl), c2v = *(const f32x4*)(vecL + 256 + fl);
;         const float c1a[4] = {c1v.x, c1v.y, c1v.z, c1v.w}, c2a[4] = {c2v.x, c2v.y, c2v.z, c2v.w};
; #pragma unroll
;         for (int j = 0; j < 2; ++j) {
;           const int lrow = wn * 64 + j * 32 + r;
;           const float mu = rowA[lrow], rstd = rowB[lrow];
;           float sg4[4];
; #pragma unroll
;           for (int e = 0; e < 4; ++e) sg4[e] = sigmoidf_(rstd * (accu[i][j][4 * q4 + e] - mu * c1a[e]) + c2a[e]);
;           gq[i][j][2 * q4] = pack2(sg4[0], sg4[1]); gq[i][j][2 * q4 + 1] = pack2(sg4[2], sg4[3]);
;         }
;         __builtin_amdgcn_sched_barrier(0);
;       }
	v_fma_f32 v0, v48, v0, v42
	v_fma_f32 v1, v48, v1, v43
	v_fma_f32 v2, v48, v2, v44
	v_fmac_f32_e32 v45, v48, v3
	v_mul_f32_e32 v16, 0xbfb8aa3b, v16
	v_mul_f32_e32 v17, 0xbfb8aa3b, v17
	v_mul_f32_e32 v18, 0xbfb8aa3b, v18
	v_mul_f32_e32 v19, 0xbfb8aa3b, v19
	v_mul_f32_e32 v0, 0xbfb8aa3b, v0
	v_mul_f32_e32 v1, 0xbfb8aa3b, v1
	v_mul_f32_e32 v2, 0xbfb8aa3b, v2
	v_mul_f32_e32 v3, 0xbfb8aa3b, v45
	v_exp_f32_e32 v16, v16
	v_exp_f32_e32 v17, v17
	v_exp_f32_e32 v18, v18
	v_exp_f32_e32 v19, v19
	v_exp_f32_e32 v0, v0
	v_exp_f32_e32 v1, v1
	v_exp_f32_e32 v2, v2
	v_exp_f32_e32 v3, v3
	v_add_f32_e32 v16, 1.0, v16
	v_add_f32_e32 v17, 1.0, v17
	v_add_f32_e32 v18, 1.0, v18
	v_add_f32_e32 v19, 1.0, v19
	v_add_f32_e32 v0, 1.0, v0
	v_add_f32_e32 v1, 1.0, v1
	v_add_f32_e32 v2, 1.0, v2
	v_add_f32_e32 v3, 1.0, v3
	v_rcp_f32_e32 v16, v16
	v_rcp_f32_e32 v17, v17
	v_rcp_f32_e32 v18, v18
	v_rcp_f32_e32 v19, v19
	v_rcp_f32_e32 v0, v0
	v_rcp_f32_e32 v1, v1
	v_rcp_f32_e32 v2, v2
	v_rcp_f32_e32 v37, v3
	v_cvt_pk_bf16_f32 v17, v16, v17
	v_cvt_pk_bf16_f32 v16, v18, v19
	v_cvt_pk_bf16_f32 v3, v0, v1
	v_cvt_pk_bf16_f32 v2, v2, v37
	v_add_u32_e32 v0, 0x249a0, v160
	v_add_u32_e32 v1, 0x24da0, v160
	ds_read_b128 v[38:41], v0
	ds_read_b128 v[42:45], v1
	ds_read_b32 v0, v164
	ds_read_b32 v1, v165
	ds_read_b32 v18, v166
	ds_read_b32 v19, v167
	s_waitcnt lgkmcnt(3)
	v_fma_f32 v21, -v39, v0, v21
	v_fma_f32 v20, -v38, v0, v20
	s_waitcnt lgkmcnt(1)
	v_fma_f32 v6, -v40, v18, v6
	v_fma_f32 v21, v1, v21, v43
	v_fma_f32 v22, -v40, v0, v22
	v_fma_f32 v0, -v41, v0, v23
	v_fma_f32 v4, -v38, v18, v4
	v_fma_f32 v5, -v39, v18, v5
	s_waitcnt lgkmcnt(0)
	v_fma_f32 v6, v19, v6, v44
	v_fma_f32 v7, -v41, v18, v7
	v_fma_f32 v20, v1, v20, v42
	v_mul_f32_e32 v21, 0xbfb8aa3b, v21
	v_fma_f32 v22, v1, v22, v44
	v_fma_f32 v0, v1, v0, v45
	v_fma_f32 v4, v19, v4, v42
	v_fma_f32 v5, v19, v5, v43
	v_mul_f32_e32 v6, 0xbfb8aa3b, v6
	v_fmac_f32_e32 v45, v19, v7
	v_mul_f32_e32 v20, 0xbfb8aa3b, v20
	v_exp_f32_e32 v21, v21
	v_mul_f32_e32 v22, 0xbfb8aa3b, v22
	v_mul_f32_e32 v0, 0xbfb8aa3b, v0
	v_mul_f32_e32 v4, 0xbfb8aa3b, v4
	v_mul_f32_e32 v5, 0xbfb8aa3b, v5
	v_exp_f32_e32 v6, v6
	v_mul_f32_e32 v7, 0xbfb8aa3b, v45
	v_exp_f32_e32 v20, v20
	v_exp_f32_e32 v22, v22
	v_exp_f32_e32 v0, v0
	v_exp_f32_e32 v4, v4
	v_exp_f32_e32 v5, v5
	v_exp_f32_e32 v7, v7
	v_add_f32_e32 v21, 1.0, v21
	v_add_f32_e32 v6, 1.0, v6
	v_add_f32_e32 v20, 1.0, v20
	v_rcp_f32_e32 v1, v21
	v_add_f32_e32 v21, 1.0, v22
	v_add_f32_e32 v0, 1.0, v0
	v_add_f32_e32 v4, 1.0, v4
	v_add_f32_e32 v5, 1.0, v5
	v_rcp_f32_e32 v18, v6
	v_add_f32_e32 v6, 1.0, v7
	v_rcp_f32_e32 v20, v20
	v_rcp_f32_e32 v21, v21
	v_rcp_f32_e32 v0, v0
	v_rcp_f32_e32 v4, v4
	v_rcp_f32_e32 v5, v5
	v_rcp_f32_e32 v19, v6
	v_cvt_pk_bf16_f32 v7, v20, v1
	v_cvt_pk_bf16_f32 v6, v21, v0
	v_cvt_pk_bf16_f32 v5, v4, v5
	v_cvt_pk_bf16_f32 v4, v18, v19
	v_add_u32_e32 v0, 0x249c0, v160
	v_add_u32_e32 v1, 0x24dc0, v160
	ds_read_b128 v[18:21], v0
	ds_read_b128 v[38:41], v1
	ds_read_b32 v0, v164
	ds_read_b32 v1, v165
	ds_read_b32 v22, v166
	ds_read_b32 v23, v167
	s_waitcnt lgkmcnt(3)
	v_fma_f32 v25, -v19, v0, v25
	v_fma_f32 v24, -v18, v0, v24
	s_waitcnt lgkmcnt(1)
	v_fma_f32 v9, -v19, v22, v9
	s_waitcnt lgkmcnt(0)
	v_fma_f32 v9, v23, v9, v39
	v_fma_f32 v10, -v20, v22, v10
	v_fma_f32 v25, v1, v25, v39
	v_fma_f32 v26, -v20, v0, v26
	v_fma_f32 v0, -v21, v0, v27
	v_fma_f32 v8, -v18, v22, v8
	v_mul_f32_e32 v9, 0xbfb8aa3b, v9
	v_fma_f32 v10, v23, v10, v40
	v_fma_f32 v11, -v21, v22, v11
	v_fma_f32 v24, v1, v24, v38
	v_mul_f32_e32 v25, 0xbfb8aa3b, v25
	v_fma_f32 v26, v1, v26, v40
	v_fma_f32 v0, v1, v0, v41
	v_fma_f32 v8, v23, v8, v38
	v_exp_f32_e32 v9, v9
	v_mul_f32_e32 v10, 0xbfb8aa3b, v10
	v_fmac_f32_e32 v41, v23, v11
	v_mul_f32_e32 v24, 0xbfb8aa3b, v24
	v_exp_f32_e32 v25, v25
	v_mul_f32_e32 v26, 0xbfb8aa3b, v26
	v_mul_f32_e32 v0, 0xbfb8aa3b, v0
	v_mul_f32_e32 v8, 0xbfb8aa3b, v8
	v_exp_f32_e32 v10, v10
	v_mul_f32_e32 v11, 0xbfb8aa3b, v41
	v_exp_f32_e32 v24, v24
	v_exp_f32_e32 v26, v26
	v_exp_f32_e32 v0, v0
	v_exp_f32_e32 v8, v8
	v_exp_f32_e32 v11, v11
	v_add_f32_e32 v9, 1.0, v9
	v_add_f32_e32 v25, 1.0, v25
	v_rcp_f32_e32 v18, v9
	v_add_f32_e32 v9, 1.0, v10
	v_add_f32_e32 v24, 1.0, v24
	v_rcp_f32_e32 v1, v25
	v_add_f32_e32 v25, 1.0, v26
	v_add_f32_e32 v0, 1.0, v0
	v_add_f32_e32 v8, 1.0, v8
	v_rcp_f32_e32 v10, v9
	v_add_f32_e32 v9, 1.0, v11
	v_rcp_f32_e32 v24, v24
	v_rcp_f32_e32 v25, v25
	v_rcp_f32_e32 v0, v0
	v_rcp_f32_e32 v8, v8
	v_rcp_f32_e32 v11, v9
	v_cvt_pk_bf16_f32 v27, v24, v1
	v_cvt_pk_bf16_f32 v9, v25, v0
	v_cvt_pk_bf16_f32 v19, v8, v18
	v_cvt_pk_bf16_f32 v8, v10, v11
	v_add_u32_e32 v0, 0x24de0, v160
	ds_read_b128 v[20:23], v163 offset:480
	ds_read_b32 v1, v164
	ds_read_b128 v[38:41], v0
	ds_read_b32 v0, v165
	ds_read_b32 v10, v166
	ds_read_b32 v18, v167
	s_waitcnt lgkmcnt(4)
	v_fma_f32 v24, -v21, v1, v29
	v_fma_f32 v11, -v20, v1, v28
	s_waitcnt lgkmcnt(2)
	v_fma_f32 v24, v0, v24, v39
	v_fma_f32 v25, -v22, v1, v30
	v_fma_f32 v1, -v23, v1, v31
	s_waitcnt lgkmcnt(1)
	v_fma_f32 v12, -v20, v10, v12
	v_fma_f32 v13, -v21, v10, v13
	v_fma_f32 v14, -v22, v10, v14
	v_fma_f32 v10, -v23, v10, v15
	v_fma_f32 v11, v0, v11, v38
	v_mul_f32_e32 v24, 0xbfb8aa3b, v24
	v_fma_f32 v25, v0, v25, v40
	v_fma_f32 v0, v0, v1, v41
	s_waitcnt lgkmcnt(0)
; DI int otid() { int t = threadIdx.x; asm volatile("" : "+v"(t)); return t; }
; template <bool NT>
; DI void stage_load_tile(bf16_t* stg, const bf16_t* tilebase) {
;   const int tid = otid();
;   const int r0 = tid >> 5, c = tid & 31;
;   const unsigned o0 = (unsigned)(r0 * 1024 + c * 8);
;   __builtin_amdgcn_sched_barrier(0);
; #pragma unroll
;   for (int hf = 0; hf < 2; ++hf) {
; #pragma unroll
;     for (int it = 8 * hf; it < 8 * hf + 8; ++it) {
;       const u32x4* gp = (const u32x4*)(tilebase + (o0 + (unsigned)(it * 16 * 1024)));
;       stage_write16(stg, r0 + 16 * it, c, NT ? __builtin_nontemporal_load(gp) : *gp);
;     }
;     __builtin_amdgcn_sched_barrier(0);
;   }
; }
; template <bool LAST>
; DI void phase_gate(const Params& P, int layer, unsigned char* smem, int L, int G) {
;     ...
;     stage_load_tile<true>(stg, PPb + (size_t)mt * 256 * 1024 + nt * 256);
;     __syncthreads();
	v_fma_f32 v12, v18, v12, v38
	v_fma_f32 v13, v18, v13, v39
	v_fma_f32 v14, v18, v14, v40
	v_fmac_f32_e32 v41, v18, v10
	v_mul_f32_e32 v11, 0xbfb8aa3b, v11
	v_exp_f32_e32 v24, v24
	v_mul_f32_e32 v25, 0xbfb8aa3b, v25
	v_mul_f32_e32 v0, 0xbfb8aa3b, v0
	v_mul_f32_e32 v12, 0xbfb8aa3b, v12
	v_mul_f32_e32 v13, 0xbfb8aa3b, v13
	v_mul_f32_e32 v14, 0xbfb8aa3b, v14
	v_mul_f32_e32 v10, 0xbfb8aa3b, v41
	v_exp_f32_e32 v11, v11
	v_exp_f32_e32 v25, v25
	v_exp_f32_e32 v0, v0
	v_exp_f32_e32 v12, v12
	v_exp_f32_e32 v13, v13
	v_exp_f32_e32 v14, v14
	v_exp_f32_e32 v10, v10
	v_add_f32_e32 v24, 1.0, v24
	v_add_f32_e32 v11, 1.0, v11
	v_rcp_f32_e32 v1, v24
	v_add_f32_e32 v24, 1.0, v25
	v_add_f32_e32 v0, 1.0, v0
	v_add_f32_e32 v12, 1.0, v12
	v_add_f32_e32 v13, 1.0, v13
	v_add_f32_e32 v14, 1.0, v14
	v_add_f32_e32 v10, 1.0, v10
	v_rcp_f32_e32 v11, v11
	v_rcp_f32_e32 v24, v24
	v_rcp_f32_e32 v0, v0
	v_rcp_f32_e32 v12, v12
	v_rcp_f32_e32 v13, v13
	v_rcp_f32_e32 v14, v14
	v_rcp_f32_e32 v10, v10
	v_cvt_pk_bf16_f32 v112, v11, v1
	v_cvt_pk_bf16_f32 v30, v24, v0
	v_cvt_pk_bf16_f32 v29, v12, v13
	v_cvt_pk_bf16_f32 v28, v14, v10
	s_ashr_i32 s25, s24, 31
	s_lshl_b64 s[24:25], s[24:25], 19
	v_mov_b32_e32 v10, v192
	s_add_u32 s26, s66, s24
	v_mov_b32_e32 v163, v161
	s_addc_u32 s27, s67, s25
	v_and_b32_e32 v26, 31, v10
	v_lshlrev_b64 v[0:1], 1, v[162:163]
	v_ashrrev_i32_e32 v18, 5, v10
	v_lshlrev_b32_e32 v10, 3, v26
	v_lshl_add_u64 v[14:15], s[26:27], 0, v[0:1]
	v_lshl_or_b32 v160, v18, 10, v10
	v_add_u32_e32 v12, 0x4000, v160
	v_mov_b32_e32 v13, v161
	v_add_u32_e32 v24, 0x8000, v160
	v_mov_b32_e32 v25, v161
	v_add_u32_e32 v38, 0xc000, v160
	v_mov_b32_e32 v39, v161
	v_lshl_add_u64 v[10:11], v[160:161], 1, v[14:15]
	v_lshl_add_u64 v[20:21], v[12:13], 1, v[14:15]
	v_lshl_add_u64 v[24:25], v[24:25], 1, v[14:15]
	v_lshl_add_u64 v[42:43], v[38:39], 1, v[14:15]
	global_load_dwordx4 v[10:13], v[10:11], off nt
	s_nop 0
	global_load_dwordx4 v[20:23], v[20:21], off nt
	s_nop 0
	global_load_dwordx4 v[38:41], v[24:25], off nt
	s_nop 0
	global_load_dwordx4 v[42:45], v[42:43], off nt
	v_add_u32_e32 v24, 0x10000, v160
	v_mov_b32_e32 v25, v161
	v_lshl_add_u64 v[24:25], v[24:25], 1, v[14:15]
	v_add_u32_e32 v46, 0x14000, v160
	v_mov_b32_e32 v47, v161
	v_lshl_add_u64 v[50:51], v[46:47], 1, v[14:15]
	global_load_dwordx4 v[46:49], v[24:25], off nt
	global_load_dwordx4 v[60:63], v[50:51], off nt
	v_add_u32_e32 v24, 0x18000, v160
	v_mov_b32_e32 v25, v161
	v_lshl_add_u64 v[24:25], v[24:25], 1, v[14:15]
	v_add_u32_e32 v50, 0x1c000, v160
	v_mov_b32_e32 v51, v161
	v_lshl_add_u64 v[50:51], v[50:51], 1, v[14:15]
	global_load_dwordx4 v[92:95], v[24:25], off nt
	global_load_dwordx4 v[114:117], v[50:51], off nt
	v_add_u32_e32 v218, 0x20000, v160
	v_mov_b32_e32 v219, v161
	v_add_u32_e32 v220, 0x24000, v160
	v_mov_b32_e32 v221, v161
	v_add_u32_e32 v252, 0x28000, v160
	v_mov_b32_e32 v253, v161
	v_add_u32_e32 v226, 0x2c000, v160
	v_mov_b32_e32 v227, v161
	v_lshl_add_u64 v[218:219], v[218:219], 1, v[14:15]
	v_lshl_add_u64 v[222:223], v[220:221], 1, v[14:15]
	v_lshl_add_u64 v[252:253], v[252:253], 1, v[14:15]
	v_lshl_add_u64 v[230:231], v[226:227], 1, v[14:15]
	global_load_dwordx4 v[218:221], v[218:219], off nt
	s_nop 0
	global_load_dwordx4 v[222:225], v[222:223], off nt
	s_nop 0
	global_load_dwordx4 v[226:229], v[252:253], off nt
	s_nop 0
	global_load_dwordx4 v[230:233], v[230:231], off nt
	v_add_u32_e32 v252, 0x30000, v160
	v_mov_b32_e32 v253, v161
	v_lshl_add_u64 v[252:253], v[252:253], 1, v[14:15]
	v_add_u32_e32 v234, 0x34000, v160
	v_mov_b32_e32 v235, v161
	v_lshl_add_u64 v[254:255], v[234:235], 1, v[14:15]
	global_load_dwordx4 v[234:237], v[252:253], off nt
	global_load_dwordx4 v[238:241], v[254:255], off nt
	v_add_u32_e32 v252, 0x38000, v160
	v_mov_b32_e32 v253, v161
	v_lshl_add_u64 v[252:253], v[252:253], 1, v[14:15]
	v_add_u32_e32 v160, 0x3c000, v160
	v_lshl_add_u64 v[190:191], v[160:161], 1, v[14:15]
	global_load_dwordx4 v[242:245], v[252:253], off nt
	global_load_dwordx4 v[248:251], v[190:191], off nt
	v_mul_lo_u32 v18, v18, s40
	v_lshl_add_u32 v18, v26, 4, v18
	v_add_u32_e32 v24, 0x2080, v18
	v_add_u32_e32 v25, 0x4100, v18
	v_add_u32_e32 v26, 0x6180, v18
	v_add_u32_e32 v31, 0x8200, v18
	v_add_u32_e32 v37, 0xa280, v18
	v_add_u32_e32 v50, 0xc300, v18
	v_add_u32_e32 v51, 0xe380, v18
	s_waitcnt vmcnt(15)
	ds_write2_b64 v18, v[10:11], v[12:13] offset1:1
	s_waitcnt vmcnt(14)
	ds_write2_b64 v24, v[20:21], v[22:23] offset1:1
	s_waitcnt vmcnt(13)
	ds_write2_b64 v25, v[38:39], v[40:41] offset1:1
	s_waitcnt vmcnt(12)
	ds_write2_b64 v26, v[42:43], v[44:45] offset1:1
	s_waitcnt vmcnt(11)
	ds_write2_b64 v31, v[46:47], v[48:49] offset1:1
	s_waitcnt vmcnt(10)
	ds_write2_b64 v37, v[60:61], v[62:63] offset1:1
	s_waitcnt vmcnt(9)
	ds_write2_b64 v50, v[92:93], v[94:95] offset1:1
	s_waitcnt vmcnt(8)
	ds_write2_b64 v51, v[114:115], v[116:117] offset1:1
	v_add_u32_e32 v14, 0x10400, v18
	v_add_u32_e32 v15, 0x12480, v18
	v_add_u32_e32 v24, 0x14500, v18
	v_add_u32_e32 v25, 0x16580, v18
	v_add_u32_e32 v26, 0x18600, v18
	v_add_u32_e32 v31, 0x1a680, v18
	v_add_u32_e32 v37, 0x1c700, v18
	v_add_u32_e32 v18, 0x1e780, v18
	s_waitcnt vmcnt(7)
	ds_write2_b64 v14, v[218:219], v[220:221] offset1:1
	s_waitcnt vmcnt(6)
	ds_write2_b64 v15, v[222:223], v[224:225] offset1:1
	s_waitcnt vmcnt(5)
	ds_write2_b64 v24, v[226:227], v[228:229] offset1:1
	s_waitcnt vmcnt(4)
	ds_write2_b64 v25, v[230:231], v[232:233] offset1:1
	s_waitcnt vmcnt(3)
	ds_write2_b64 v26, v[234:235], v[236:237] offset1:1
	s_waitcnt vmcnt(2)
	ds_write2_b64 v31, v[238:239], v[240:241] offset1:1
	s_waitcnt vmcnt(1)
	ds_write2_b64 v37, v[242:243], v[244:245] offset1:1
	s_waitcnt vmcnt(0)
	ds_write2_b64 v18, v[248:249], v[250:251] offset1:1
	v_mov_b32_e32 v10, v192
	s_waitcnt lgkmcnt(0)
	s_barrier
; DI unsigned pack2(float a, float b) { f32x2_t v = {a, b}; bf16x2_t r = __builtin_convertvector(v, bf16x2_t); return __builtin_bit_cast(unsigned, r); }
; DI float bflo(unsigned u) { return __uint_as_float(u << 16); }
; DI float bfhi(unsigned u) { return __uint_as_float(u & 0xffff0000u); }
; DI int otid() { int t = threadIdx.x; asm volatile("" : "+v"(t)); return t; }
; template <bool LAST>
; DI void phase_gate(const Params& P, int layer, unsigned char* smem, int L, int G) {
;     ...
;     {
;       const int tid1 = otid();
;       const int lane1 = tid1 & 63, w1 = tid1 >> 6, r1 = lane1 & 31, h1 = lane1 >> 5, wm1 = w1 >> 2, wn1 = w1 & 3;
; #pragma unroll
;       for (int i = 0; i < 4; ++i)
; #pragma unroll
;         for (int q4 = 0; q4 < 4; ++q4) {
; #pragma unroll
;           for (int j = 0; j < 2; ++j) {
;             const uint2 pv = *(const uint2*)(stg + (wn1 * 64 + j * 32 + r1) * STG + wm1 * 128 + i * 32 + 8 * q4 + 4 * h1);
;             const unsigned g0 = gq[i][j][2 * q4], g1 = gq[i][j][2 * q4 + 1];
;             gq[i][j][2 * q4] = pack2(bflo(g0) * bflo(pv.x), bfhi(g0) * bfhi(pv.x));
;             gq[i][j][2 * q4 + 1] = pack2(bflo(g1) * bflo(pv.y), bfhi(g1) * bfhi(pv.y));
;           }
;           __builtin_amdgcn_sched_barrier(0);
;         }
	v_and_b32_e32 v13, 0xffff0000, v99
	v_lshrrev_b32_e32 v12, 2, v10
	v_and_b32_e32 v12, 8, v12
	v_and_b32_e32 v11, 0xdf, v10
	v_and_or_b32 v10, v10, s38, v12
	v_mad_u32_u24 v113, v11, s40, v10
	ds_read_b64 v[10:11], v113
	ds_read_b64 v[14:15], v113 offset:16640
	v_lshlrev_b32_e32 v12, 16, v99
	s_waitcnt lgkmcnt(1)
	v_lshlrev_b32_e32 v20, 16, v10
	v_and_b32_e32 v21, 0xffff0000, v10
	v_pk_mul_f32 v[12:13], v[12:13], v[20:21]
	v_lshlrev_b32_e32 v10, 16, v11
	v_cvt_pk_bf16_f32 v31, v12, v13
	v_lshlrev_b32_e32 v12, 16, v98
	v_and_b32_e32 v13, 0xffff0000, v98
	v_and_b32_e32 v11, 0xffff0000, v11
	v_pk_mul_f32 v[10:11], v[12:13], v[10:11]
	s_waitcnt lgkmcnt(0)
	v_lshlrev_b32_e32 v12, 16, v14
	v_cvt_pk_bf16_f32 v98, v10, v11
	v_lshlrev_b32_e32 v10, 16, v97
	v_and_b32_e32 v11, 0xffff0000, v97
	v_and_b32_e32 v13, 0xffff0000, v14
	v_pk_mul_f32 v[10:11], v[10:11], v[12:13]
	v_lshlrev_b32_e32 v12, 16, v15
	v_cvt_pk_bf16_f32 v97, v10, v11
	v_lshlrev_b32_e32 v10, 16, v96
	v_and_b32_e32 v11, 0xffff0000, v96
	v_and_b32_e32 v13, 0xffff0000, v15
	v_pk_mul_f32 v[10:11], v[10:11], v[12:13]
	s_nop 0
	v_cvt_pk_bf16_f32 v96, v10, v11
	ds_read_b64 v[10:11], v113 offset:16
	ds_read_b64 v[14:15], v113 offset:16656
	v_lshlrev_b32_e32 v12, 16, v103
	v_and_b32_e32 v13, 0xffff0000, v103
	s_waitcnt lgkmcnt(1)
	v_lshlrev_b32_e32 v20, 16, v10
	v_and_b32_e32 v21, 0xffff0000, v10
	v_pk_mul_f32 v[12:13], v[12:13], v[20:21]
	v_lshlrev_b32_e32 v10, 16, v11
	v_cvt_pk_bf16_f32 v93, v12, v13
	v_lshlrev_b32_e32 v12, 16, v102
	v_and_b32_e32 v13, 0xffff0000, v102
	v_and_b32_e32 v11, 0xffff0000, v11
	v_pk_mul_f32 v[10:11], v[12:13], v[10:11]
	s_waitcnt lgkmcnt(0)
	v_lshlrev_b32_e32 v12, 16, v14
	v_cvt_pk_bf16_f32 v95, v10, v11
	v_lshlrev_b32_e32 v10, 16, v101
	v_and_b32_e32 v11, 0xffff0000, v101
	v_and_b32_e32 v13, 0xffff0000, v14
	v_pk_mul_f32 v[10:11], v[10:11], v[12:13]
	v_lshlrev_b32_e32 v12, 16, v15
	v_cvt_pk_bf16_f32 v92, v10, v11
	v_lshlrev_b32_e32 v10, 16, v100
	v_and_b32_e32 v11, 0xffff0000, v100
	v_and_b32_e32 v13, 0xffff0000, v15
	v_pk_mul_f32 v[10:11], v[10:11], v[12:13]
	s_nop 0
	v_cvt_pk_bf16_f32 v94, v10, v11
	ds_read_b64 v[10:11], v113 offset:32
	ds_read_b64 v[14:15], v113 offset:16672
	v_lshlrev_b32_e32 v12, 16, v107
	v_and_b32_e32 v13, 0xffff0000, v107
	s_waitcnt lgkmcnt(1)
	v_lshlrev_b32_e32 v20, 16, v10
	v_and_b32_e32 v21, 0xffff0000, v10
	v_pk_mul_f32 v[12:13], v[12:13], v[20:21]
	v_lshlrev_b32_e32 v10, 16, v11
	v_cvt_pk_bf16_f32 v88, v12, v13
	v_lshlrev_b32_e32 v12, 16, v106
	v_and_b32_e32 v13, 0xffff0000, v106
	v_and_b32_e32 v11, 0xffff0000, v11
	v_pk_mul_f32 v[10:11], v[12:13], v[10:11]
	s_waitcnt lgkmcnt(0)
	v_lshlrev_b32_e32 v12, 16, v14
	v_cvt_pk_bf16_f32 v90, v10, v11
	v_lshlrev_b32_e32 v10, 16, v105
	v_and_b32_e32 v11, 0xffff0000, v105
	v_and_b32_e32 v13, 0xffff0000, v14
	v_pk_mul_f32 v[10:11], v[10:11], v[12:13]
	v_lshlrev_b32_e32 v12, 16, v15
	v_cvt_pk_bf16_f32 v87, v10, v11
	v_lshlrev_b32_e32 v10, 16, v104
	v_and_b32_e32 v11, 0xffff0000, v104
	v_and_b32_e32 v13, 0xffff0000, v15
	v_pk_mul_f32 v[10:11], v[10:11], v[12:13]
	s_nop 0
	v_cvt_pk_bf16_f32 v89, v10, v11
	ds_read_b64 v[10:11], v113 offset:48
	ds_read_b64 v[14:15], v113 offset:16688
	v_lshlrev_b32_e32 v12, 16, v111
	v_and_b32_e32 v13, 0xffff0000, v111
	s_waitcnt lgkmcnt(1)
	v_lshlrev_b32_e32 v20, 16, v10
	v_and_b32_e32 v21, 0xffff0000, v10
	v_pk_mul_f32 v[12:13], v[12:13], v[20:21]
	v_lshlrev_b32_e32 v10, 16, v11
	v_cvt_pk_bf16_f32 v61, v12, v13
	v_lshlrev_b32_e32 v12, 16, v110
	v_and_b32_e32 v13, 0xffff0000, v110
	v_and_b32_e32 v11, 0xffff0000, v11
	v_pk_mul_f32 v[10:11], v[12:13], v[10:11]
	s_waitcnt lgkmcnt(0)
	v_lshlrev_b32_e32 v12, 16, v14
	v_cvt_pk_bf16_f32 v63, v10, v11
	v_lshlrev_b32_e32 v10, 16, v109
	v_and_b32_e32 v11, 0xffff0000, v109
	v_and_b32_e32 v13, 0xffff0000, v14
	v_pk_mul_f32 v[10:11], v[10:11], v[12:13]
	v_lshlrev_b32_e32 v12, 16, v15
	v_cvt_pk_bf16_f32 v60, v10, v11
	v_lshlrev_b32_e32 v10, 16, v108
	v_and_b32_e32 v11, 0xffff0000, v108
	v_and_b32_e32 v13, 0xffff0000, v15
	v_pk_mul_f32 v[10:11], v[10:11], v[12:13]
	s_nop 0
	v_cvt_pk_bf16_f32 v62, v10, v11
	ds_read_b64 v[10:11], v113 offset:64
	ds_read_b64 v[14:15], v113 offset:16704
	v_lshlrev_b32_e32 v12, 16, v67
	v_and_b32_e32 v13, 0xffff0000, v67
	s_waitcnt lgkmcnt(1)
	v_lshlrev_b32_e32 v20, 16, v10
	v_and_b32_e32 v21, 0xffff0000, v10
	v_pk_mul_f32 v[12:13], v[12:13], v[20:21]
	v_lshlrev_b32_e32 v10, 16, v11
	v_cvt_pk_bf16_f32 v56, v12, v13
	v_lshlrev_b32_e32 v12, 16, v66
	v_and_b32_e32 v13, 0xffff0000, v66
	v_and_b32_e32 v11, 0xffff0000, v11
	v_pk_mul_f32 v[10:11], v[12:13], v[10:11]
	s_waitcnt lgkmcnt(0)
	v_lshlrev_b32_e32 v12, 16, v14
	v_cvt_pk_bf16_f32 v58, v10, v11
	v_lshlrev_b32_e32 v10, 16, v65
	v_and_b32_e32 v11, 0xffff0000, v65
	v_and_b32_e32 v13, 0xffff0000, v14
	v_pk_mul_f32 v[10:11], v[10:11], v[12:13]
	v_lshlrev_b32_e32 v12, 16, v15
	v_cvt_pk_bf16_f32 v54, v10, v11
	v_lshlrev_b32_e32 v10, 16, v64
	v_and_b32_e32 v11, 0xffff0000, v64
	v_and_b32_e32 v13, 0xffff0000, v15
	v_pk_mul_f32 v[10:11], v[10:11], v[12:13]
	s_nop 0
	v_cvt_pk_bf16_f32 v57, v10, v11
	ds_read_b64 v[10:11], v113 offset:80
	ds_read_b64 v[14:15], v113 offset:16720
	v_lshlrev_b32_e32 v12, 16, v71
	v_and_b32_e32 v13, 0xffff0000, v71
	s_waitcnt lgkmcnt(1)
	v_lshlrev_b32_e32 v20, 16, v10
	v_and_b32_e32 v21, 0xffff0000, v10
	v_pk_mul_f32 v[12:13], v[12:13], v[20:21]
	v_lshlrev_b32_e32 v10, 16, v11
	v_cvt_pk_bf16_f32 v50, v12, v13
	v_lshlrev_b32_e32 v12, 16, v70
	v_and_b32_e32 v13, 0xffff0000, v70
	v_and_b32_e32 v11, 0xffff0000, v11
	v_pk_mul_f32 v[10:11], v[12:13], v[10:11]
	s_waitcnt lgkmcnt(0)
; DI unsigned pack2(float a, float b) { f32x2_t v = {a, b}; bf16x2_t r = __builtin_convertvector(v, bf16x2_t); return __builtin_bit_cast(unsigned, r); }
; DI float bflo(unsigned u) { return __uint_as_float(u << 16); }
; DI float bfhi(unsigned u) { return __uint_as_float(u & 0xffff0000u); }
; template <bool LAST>
; DI void phase_gate(const Params& P, int layer, unsigned char* smem, int L, int G) {
;     ...
; #pragma unroll
;       for (int i = 0; i < 4; ++i)
; #pragma unroll
;         for (int q4 = 0; q4 < 4; ++q4) {
; #pragma unroll
;           for (int j = 0; j < 2; ++j) {
;             const uint2 pv = *(const uint2*)(stg + (wn1 * 64 + j * 32 + r1) * STG + wm1 * 128 + i * 32 + 8 * q4 + 4 * h1);
;             const unsigned g0 = gq[i][j][2 * q4], g1 = gq[i][j][2 * q4 + 1];
;             gq[i][j][2 * q4] = pack2(bflo(g0) * bflo(pv.x), bfhi(g0) * bfhi(pv.x));
;             gq[i][j][2 * q4 + 1] = pack2(bflo(g1) * bflo(pv.y), bfhi(g1) * bfhi(pv.y));
;           }
;           __builtin_amdgcn_sched_barrier(0);
;         }
	v_lshlrev_b32_e32 v12, 16, v14
	v_cvt_pk_bf16_f32 v52, v10, v11
	v_lshlrev_b32_e32 v10, 16, v69
	v_and_b32_e32 v11, 0xffff0000, v69
	v_and_b32_e32 v13, 0xffff0000, v14
	v_pk_mul_f32 v[10:11], v[10:11], v[12:13]
	v_lshlrev_b32_e32 v12, 16, v15
	v_cvt_pk_bf16_f32 v49, v10, v11
	v_lshlrev_b32_e32 v10, 16, v68
	v_and_b32_e32 v11, 0xffff0000, v68
	v_and_b32_e32 v13, 0xffff0000, v15
	v_pk_mul_f32 v[10:11], v[10:11], v[12:13]
	s_nop 0
	v_cvt_pk_bf16_f32 v51, v10, v11
	ds_read_b64 v[10:11], v113 offset:96
	ds_read_b64 v[14:15], v113 offset:16736
	v_lshlrev_b32_e32 v12, 16, v75
	v_and_b32_e32 v13, 0xffff0000, v75
	s_waitcnt lgkmcnt(1)
	v_lshlrev_b32_e32 v20, 16, v10
	v_and_b32_e32 v21, 0xffff0000, v10
	v_pk_mul_f32 v[12:13], v[12:13], v[20:21]
	v_lshlrev_b32_e32 v10, 16, v11
	v_cvt_pk_bf16_f32 v46, v12, v13
	v_lshlrev_b32_e32 v12, 16, v74
	v_and_b32_e32 v13, 0xffff0000, v74
	v_and_b32_e32 v11, 0xffff0000, v11
	v_pk_mul_f32 v[10:11], v[12:13], v[10:11]
	s_waitcnt lgkmcnt(0)
	v_lshlrev_b32_e32 v12, 16, v14
	v_cvt_pk_bf16_f32 v48, v10, v11
	v_lshlrev_b32_e32 v10, 16, v73
	v_and_b32_e32 v11, 0xffff0000, v73
	v_and_b32_e32 v13, 0xffff0000, v14
	v_pk_mul_f32 v[10:11], v[10:11], v[12:13]
	v_lshlrev_b32_e32 v12, 16, v15
	v_cvt_pk_bf16_f32 v45, v10, v11
	v_lshlrev_b32_e32 v10, 16, v72
	v_and_b32_e32 v11, 0xffff0000, v72
	v_and_b32_e32 v13, 0xffff0000, v15
	v_pk_mul_f32 v[10:11], v[10:11], v[12:13]
	s_nop 0
	v_cvt_pk_bf16_f32 v47, v10, v11
	ds_read_b64 v[10:11], v113 offset:112
	ds_read_b64 v[14:15], v113 offset:16752
	v_lshlrev_b32_e32 v12, 16, v79
	v_and_b32_e32 v13, 0xffff0000, v79
	s_waitcnt lgkmcnt(1)
	v_lshlrev_b32_e32 v20, 16, v10
	v_and_b32_e32 v21, 0xffff0000, v10
	v_pk_mul_f32 v[12:13], v[12:13], v[20:21]
	v_lshlrev_b32_e32 v10, 16, v11
	v_cvt_pk_bf16_f32 v42, v12, v13
	v_lshlrev_b32_e32 v12, 16, v78
	v_and_b32_e32 v13, 0xffff0000, v78
	v_and_b32_e32 v11, 0xffff0000, v11
	v_pk_mul_f32 v[10:11], v[12:13], v[10:11]
	s_waitcnt lgkmcnt(0)
	v_lshlrev_b32_e32 v12, 16, v14
	v_cvt_pk_bf16_f32 v44, v10, v11
	v_lshlrev_b32_e32 v10, 16, v77
	v_and_b32_e32 v11, 0xffff0000, v77
	v_and_b32_e32 v13, 0xffff0000, v14
	v_pk_mul_f32 v[10:11], v[10:11], v[12:13]
	v_lshlrev_b32_e32 v12, 16, v15
	v_cvt_pk_bf16_f32 v41, v10, v11
	v_lshlrev_b32_e32 v10, 16, v76
	v_and_b32_e32 v11, 0xffff0000, v76
	v_and_b32_e32 v13, 0xffff0000, v15
	v_pk_mul_f32 v[10:11], v[10:11], v[12:13]
	s_nop 0
	v_cvt_pk_bf16_f32 v43, v10, v11
	ds_read_b64 v[10:11], v113 offset:128
	ds_read_b64 v[14:15], v113 offset:16768
	v_lshlrev_b32_e32 v12, 16, v35
	v_and_b32_e32 v13, 0xffff0000, v35
	s_waitcnt lgkmcnt(1)
	v_lshlrev_b32_e32 v20, 16, v10
	v_and_b32_e32 v21, 0xffff0000, v10
	v_pk_mul_f32 v[12:13], v[12:13], v[20:21]
	v_lshlrev_b32_e32 v10, 16, v11
	v_cvt_pk_bf16_f32 v38, v12, v13
	v_lshlrev_b32_e32 v12, 16, v34
	v_and_b32_e32 v13, 0xffff0000, v34
	v_and_b32_e32 v11, 0xffff0000, v11
	v_pk_mul_f32 v[10:11], v[12:13], v[10:11]
	s_waitcnt lgkmcnt(0)
	v_lshlrev_b32_e32 v12, 16, v14
	v_cvt_pk_bf16_f32 v40, v10, v11
	v_lshlrev_b32_e32 v10, 16, v33
	v_and_b32_e32 v11, 0xffff0000, v33
	v_and_b32_e32 v13, 0xffff0000, v14
	v_pk_mul_f32 v[10:11], v[10:11], v[12:13]
	v_lshlrev_b32_e32 v12, 16, v15
	v_cvt_pk_bf16_f32 v37, v10, v11
	v_lshlrev_b32_e32 v10, 16, v32
	v_and_b32_e32 v11, 0xffff0000, v32
	v_and_b32_e32 v13, 0xffff0000, v15
	v_pk_mul_f32 v[10:11], v[10:11], v[12:13]
	s_nop 0
	v_cvt_pk_bf16_f32 v39, v10, v11
	ds_read_b64 v[10:11], v113 offset:144
	ds_read_b64 v[14:15], v113 offset:16784
	v_lshlrev_b32_e32 v12, 16, v80
	v_and_b32_e32 v13, 0xffff0000, v80
	s_waitcnt lgkmcnt(1)
	v_lshlrev_b32_e32 v20, 16, v10
	v_and_b32_e32 v21, 0xffff0000, v10
	v_pk_mul_f32 v[12:13], v[12:13], v[20:21]
	v_lshlrev_b32_e32 v10, 16, v11
	v_cvt_pk_bf16_f32 v34, v12, v13
	v_lshlrev_b32_e32 v12, 16, v36
	v_and_b32_e32 v13, 0xffff0000, v36
	v_and_b32_e32 v11, 0xffff0000, v11
	v_pk_mul_f32 v[10:11], v[12:13], v[10:11]
	s_waitcnt lgkmcnt(0)
	v_lshlrev_b32_e32 v12, 16, v14
	v_cvt_pk_bf16_f32 v36, v10, v11
	v_lshlrev_b32_e32 v10, 16, v55
	v_and_b32_e32 v11, 0xffff0000, v55
	v_and_b32_e32 v13, 0xffff0000, v14
	v_pk_mul_f32 v[10:11], v[10:11], v[12:13]
	v_lshlrev_b32_e32 v12, 16, v15
	v_cvt_pk_bf16_f32 v32, v10, v11
	v_lshlrev_b32_e32 v10, 16, v53
	v_and_b32_e32 v11, 0xffff0000, v53
	v_and_b32_e32 v13, 0xffff0000, v15
	v_pk_mul_f32 v[10:11], v[10:11], v[12:13]
	s_nop 0
	v_cvt_pk_bf16_f32 v35, v10, v11
	ds_read_b64 v[10:11], v113 offset:160
	ds_read_b64 v[14:15], v113 offset:16800
	v_lshlrev_b32_e32 v12, 16, v83
	v_and_b32_e32 v13, 0xffff0000, v83
	s_waitcnt lgkmcnt(1)
	v_lshlrev_b32_e32 v20, 16, v10
	v_and_b32_e32 v21, 0xffff0000, v10
	v_pk_mul_f32 v[12:13], v[12:13], v[20:21]
	v_lshlrev_b32_e32 v10, 16, v11
	v_cvt_pk_bf16_f32 v24, v12, v13
	v_lshlrev_b32_e32 v12, 16, v82
	v_and_b32_e32 v13, 0xffff0000, v82
	v_and_b32_e32 v11, 0xffff0000, v11
	v_pk_mul_f32 v[10:11], v[12:13], v[10:11]
	s_waitcnt lgkmcnt(0)
	v_lshlrev_b32_e32 v12, 16, v14
	v_cvt_pk_bf16_f32 v26, v10, v11
	v_lshlrev_b32_e32 v10, 16, v81
	v_and_b32_e32 v11, 0xffff0000, v81
	v_and_b32_e32 v13, 0xffff0000, v14
	v_pk_mul_f32 v[10:11], v[10:11], v[12:13]
	v_lshlrev_b32_e32 v12, 16, v15
	v_cvt_pk_bf16_f32 v23, v10, v11
	v_lshlrev_b32_e32 v10, 16, v59
	v_and_b32_e32 v11, 0xffff0000, v59
	v_and_b32_e32 v13, 0xffff0000, v15
	v_pk_mul_f32 v[10:11], v[10:11], v[12:13]
	s_nop 0
	v_cvt_pk_bf16_f32 v25, v10, v11
	ds_read_b64 v[10:11], v113 offset:176
	ds_read_b64 v[14:15], v113 offset:16816
	v_lshlrev_b32_e32 v12, 16, v91
	v_and_b32_e32 v13, 0xffff0000, v91
	s_waitcnt lgkmcnt(1)
; DI unsigned pack2(float a, float b) { f32x2_t v = {a, b}; bf16x2_t r = __builtin_convertvector(v, bf16x2_t); return __builtin_bit_cast(unsigned, r); }
; DI float bflo(unsigned u) { return __uint_as_float(u << 16); }
; DI float bfhi(unsigned u) { return __uint_as_float(u & 0xffff0000u); }
; template <bool LAST>
; DI void phase_gate(const Params& P, int layer, unsigned char* smem, int L, int G) {
;     ...
; #pragma unroll
;       for (int i = 0; i < 4; ++i)
; #pragma unroll
;         for (int q4 = 0; q4 < 4; ++q4) {
; #pragma unroll
;           for (int j = 0; j < 2; ++j) {
;             const uint2 pv = *(const uint2*)(stg + (wn1 * 64 + j * 32 + r1) * STG + wm1 * 128 + i * 32 + 8 * q4 + 4 * h1);
;             const unsigned g0 = gq[i][j][2 * q4], g1 = gq[i][j][2 * q4 + 1];
;             gq[i][j][2 * q4] = pack2(bflo(g0) * bflo(pv.x), bfhi(g0) * bfhi(pv.x));
;             gq[i][j][2 * q4 + 1] = pack2(bflo(g1) * bflo(pv.y), bfhi(g1) * bfhi(pv.y));
;           }
;           __builtin_amdgcn_sched_barrier(0);
;         }
;     }
;     __syncthreads();
	v_lshlrev_b32_e32 v20, 16, v10
	v_and_b32_e32 v21, 0xffff0000, v10
	v_pk_mul_f32 v[12:13], v[12:13], v[20:21]
	v_lshlrev_b32_e32 v10, 16, v11
	v_cvt_pk_bf16_f32 v20, v12, v13
	v_lshlrev_b32_e32 v12, 16, v86
	v_and_b32_e32 v13, 0xffff0000, v86
	v_and_b32_e32 v11, 0xffff0000, v11
	v_pk_mul_f32 v[10:11], v[12:13], v[10:11]
	s_waitcnt lgkmcnt(0)
	v_lshlrev_b32_e32 v12, 16, v14
	v_cvt_pk_bf16_f32 v22, v10, v11
	v_lshlrev_b32_e32 v10, 16, v85
	v_and_b32_e32 v11, 0xffff0000, v85
	v_and_b32_e32 v13, 0xffff0000, v14
	v_pk_mul_f32 v[10:11], v[10:11], v[12:13]
	v_lshlrev_b32_e32 v12, 16, v15
	v_cvt_pk_bf16_f32 v18, v10, v11
	v_lshlrev_b32_e32 v10, 16, v84
	v_and_b32_e32 v11, 0xffff0000, v84
	v_and_b32_e32 v13, 0xffff0000, v15
	v_pk_mul_f32 v[10:11], v[10:11], v[12:13]
	s_nop 0
	v_cvt_pk_bf16_f32 v21, v10, v11
	ds_read_b64 v[10:11], v113 offset:192
	ds_read_b64 v[64:65], v113 offset:16832
	v_lshlrev_b32_e32 v12, 16, v17
	v_and_b32_e32 v13, 0xffff0000, v17
	s_waitcnt lgkmcnt(1)
	v_lshlrev_b32_e32 v14, 16, v10
	v_and_b32_e32 v15, 0xffff0000, v10
	v_pk_mul_f32 v[12:13], v[12:13], v[14:15]
	v_lshlrev_b32_e32 v10, 16, v11
	v_cvt_pk_bf16_f32 v15, v12, v13
	v_lshlrev_b32_e32 v12, 16, v16
	v_and_b32_e32 v13, 0xffff0000, v16
	v_and_b32_e32 v11, 0xffff0000, v11
	v_pk_mul_f32 v[10:11], v[12:13], v[10:11]
	s_waitcnt lgkmcnt(0)
	v_lshlrev_b32_e32 v12, 16, v64
	v_cvt_pk_bf16_f32 v17, v10, v11
	v_lshlrev_b32_e32 v10, 16, v3
	v_and_b32_e32 v11, 0xffff0000, v3
	v_and_b32_e32 v13, 0xffff0000, v64
	v_pk_mul_f32 v[10:11], v[10:11], v[12:13]
	v_lshlrev_b32_e32 v12, 16, v65
	v_cvt_pk_bf16_f32 v14, v10, v11
	v_lshlrev_b32_e32 v10, 16, v2
	v_and_b32_e32 v11, 0xffff0000, v2
	v_and_b32_e32 v13, 0xffff0000, v65
	v_pk_mul_f32 v[2:3], v[10:11], v[12:13]
	s_nop 0
	v_cvt_pk_bf16_f32 v16, v2, v3
	ds_read_b64 v[2:3], v113 offset:208
	ds_read_b64 v[64:65], v113 offset:16848
	v_lshlrev_b32_e32 v10, 16, v7
	v_and_b32_e32 v11, 0xffff0000, v7
	s_waitcnt lgkmcnt(1)
	v_lshlrev_b32_e32 v12, 16, v2
	v_and_b32_e32 v13, 0xffff0000, v2
	v_pk_mul_f32 v[10:11], v[10:11], v[12:13]
	v_lshlrev_b32_e32 v12, 16, v6
	v_lshlrev_b32_e32 v2, 16, v3
	v_and_b32_e32 v13, 0xffff0000, v6
	v_and_b32_e32 v3, 0xffff0000, v3
	v_pk_mul_f32 v[2:3], v[12:13], v[2:3]
	s_waitcnt lgkmcnt(0)
	v_lshlrev_b32_e32 v6, 16, v64
	v_cvt_pk_bf16_f32 v13, v2, v3
	v_lshlrev_b32_e32 v2, 16, v5
	v_and_b32_e32 v3, 0xffff0000, v5
	v_and_b32_e32 v7, 0xffff0000, v64
	v_pk_mul_f32 v[2:3], v[2:3], v[6:7]
	v_cvt_pk_bf16_f32 v11, v10, v11
	v_cvt_pk_bf16_f32 v10, v2, v3
	v_lshlrev_b32_e32 v2, 16, v4
	v_lshlrev_b32_e32 v6, 16, v65
	v_and_b32_e32 v3, 0xffff0000, v4
	v_and_b32_e32 v7, 0xffff0000, v65
	v_pk_mul_f32 v[2:3], v[2:3], v[6:7]
	s_nop 0
	v_cvt_pk_bf16_f32 v12, v2, v3
	ds_read_b64 v[2:3], v113 offset:224
	ds_read_b64 v[64:65], v113 offset:16864
	v_lshlrev_b32_e32 v4, 16, v27
	v_and_b32_e32 v5, 0xffff0000, v27
	s_waitcnt lgkmcnt(1)
	v_lshlrev_b32_e32 v6, 16, v2
	v_and_b32_e32 v7, 0xffff0000, v2
	v_pk_mul_f32 v[4:5], v[4:5], v[6:7]
	v_lshlrev_b32_e32 v2, 16, v3
	v_cvt_pk_bf16_f32 v7, v4, v5
	v_lshlrev_b32_e32 v4, 16, v9
	v_and_b32_e32 v5, 0xffff0000, v9
	v_and_b32_e32 v3, 0xffff0000, v3
	v_pk_mul_f32 v[2:3], v[4:5], v[2:3]
	s_waitcnt lgkmcnt(0)
	v_lshlrev_b32_e32 v4, 16, v64
	v_cvt_pk_bf16_f32 v9, v2, v3
	v_lshlrev_b32_e32 v2, 16, v19
	v_and_b32_e32 v3, 0xffff0000, v19
	v_and_b32_e32 v5, 0xffff0000, v64
	v_pk_mul_f32 v[2:3], v[2:3], v[4:5]
	v_lshlrev_b32_e32 v4, 16, v65
	v_cvt_pk_bf16_f32 v6, v2, v3
	v_lshlrev_b32_e32 v2, 16, v8
	v_and_b32_e32 v3, 0xffff0000, v8
	v_and_b32_e32 v5, 0xffff0000, v65
	v_pk_mul_f32 v[2:3], v[2:3], v[4:5]
	s_nop 0
	v_cvt_pk_bf16_f32 v8, v2, v3
	ds_read_b64 v[2:3], v113 offset:240
	ds_read_b64 v[64:65], v113 offset:16880
	v_lshlrev_b32_e32 v4, 16, v112
	v_and_b32_e32 v5, 0xffff0000, v112
	s_waitcnt lgkmcnt(1)
	v_lshlrev_b32_e32 v66, 16, v2
	v_and_b32_e32 v67, 0xffff0000, v2
	v_pk_mul_f32 v[4:5], v[4:5], v[66:67]
	v_lshlrev_b32_e32 v66, 16, v30
	v_lshlrev_b32_e32 v2, 16, v3
	v_and_b32_e32 v67, 0xffff0000, v30
	v_and_b32_e32 v3, 0xffff0000, v3
	v_pk_mul_f32 v[2:3], v[66:67], v[2:3]
	v_cvt_pk_bf16_f32 v4, v4, v5
	v_cvt_pk_bf16_f32 v5, v2, v3
	v_lshlrev_b32_e32 v2, 16, v29
	s_waitcnt lgkmcnt(0)
	v_lshlrev_b32_e32 v66, 16, v64
	v_and_b32_e32 v3, 0xffff0000, v29
	v_and_b32_e32 v67, 0xffff0000, v64
	v_pk_mul_f32 v[2:3], v[2:3], v[66:67]
	v_lshlrev_b32_e32 v66, 16, v28
	v_lshlrev_b32_e32 v64, 16, v65
	v_and_b32_e32 v67, 0xffff0000, v28
	v_and_b32_e32 v65, 0xffff0000, v65
	v_pk_mul_f32 v[28:29], v[66:67], v[64:65]
	v_cvt_pk_bf16_f32 v2, v2, v3
	v_cvt_pk_bf16_f32 v3, v28, v29
	v_mov_b32_e32 v19, v192
	s_barrier
; DI int otid() { int t = threadIdx.x; asm volatile("" : "+v"(t)); return t; }
; template <bool NT>
; DI void stage_load_tile(bf16_t* stg, const bf16_t* tilebase) {
;   const int tid = otid();
;   const int r0 = tid >> 5, c = tid & 31;
;   const unsigned o0 = (unsigned)(r0 * 1024 + c * 8);
;   __builtin_amdgcn_sched_barrier(0);
; #pragma unroll
;   for (int hf = 0; hf < 2; ++hf) {
; #pragma unroll
;     for (int it = 8 * hf; it < 8 * hf + 8; ++it) {
;       const u32x4* gp = (const u32x4*)(tilebase + (o0 + (unsigned)(it * 16 * 1024)));
;       stage_write16(stg, r0 + 16 * it, c, NT ? __builtin_nontemporal_load(gp) : *gp);
;     }
;     __builtin_amdgcn_sched_barrier(0);
;   }
; }
; template <bool LAST>
; DI void phase_gate(const Params& P, int layer, unsigned char* smem, int L, int G) {
;     ...
;     stage_load_tile<false>(stg, Sb + (size_t)mt * 256 * 1024 + nt * 256);
;     __syncthreads();
	s_add_u32 s26, s76, s24
	v_ashrrev_i32_e32 v27, 5, v19
	v_and_b32_e32 v19, 31, v19
	s_addc_u32 s27, s77, s25
	v_lshlrev_b32_e32 v30, 3, v19
	v_lshl_add_u64 v[28:29], s[26:27], 0, v[0:1]
	v_lshl_or_b32 v160, v27, 10, v30
	v_add_u32_e32 v66, 0x4000, v160
	v_mov_b32_e32 v67, v161
	v_add_u32_e32 v72, 0x8000, v160
	v_mov_b32_e32 v73, v161
	v_add_u32_e32 v74, 0xc000, v160
	v_mov_b32_e32 v75, v161
	v_add_u32_e32 v80, 0x10000, v160
	v_mov_b32_e32 v81, v161
	v_add_u32_e32 v82, 0x14000, v160
	v_mov_b32_e32 v83, v161
	v_lshl_add_u64 v[64:65], v[160:161], 1, v[28:29]
	v_lshl_add_u64 v[68:69], v[66:67], 1, v[28:29]
	v_lshl_add_u64 v[72:73], v[72:73], 1, v[28:29]
	v_lshl_add_u64 v[76:77], v[74:75], 1, v[28:29]
	v_lshl_add_u64 v[80:81], v[80:81], 1, v[28:29]
	v_lshl_add_u64 v[84:85], v[82:83], 1, v[28:29]
	global_load_dwordx4 v[64:67], v[64:65], off
	s_nop 0
	global_load_dwordx4 v[68:71], v[68:69], off
	s_nop 0
	global_load_dwordx4 v[72:75], v[72:73], off
	s_nop 0
	global_load_dwordx4 v[76:79], v[76:77], off
	s_nop 0
	global_load_dwordx4 v[80:83], v[80:81], off
	s_nop 0
	global_load_dwordx4 v[100:103], v[84:85], off
	v_add_u32_e32 v84, 0x18000, v160
	v_mov_b32_e32 v85, v161
	v_add_u32_e32 v104, 0x1c000, v160
	v_mov_b32_e32 v105, v161
	v_lshl_add_u64 v[84:85], v[84:85], 1, v[28:29]
	v_lshl_add_u64 v[108:109], v[104:105], 1, v[28:29]
	global_load_dwordx4 v[104:107], v[84:85], off
	s_nop 0
	global_load_dwordx4 v[108:111], v[108:109], off
	v_add_u32_e32 v218, 0x20000, v160
	v_mov_b32_e32 v219, v161
	v_add_u32_e32 v220, 0x24000, v160
	v_mov_b32_e32 v221, v161
	v_add_u32_e32 v226, 0x28000, v160
	v_mov_b32_e32 v227, v161
	v_add_u32_e32 v228, 0x2c000, v160
	v_mov_b32_e32 v229, v161
	v_add_u32_e32 v234, 0x30000, v160
	v_mov_b32_e32 v235, v161
	v_add_u32_e32 v236, 0x34000, v160
	v_mov_b32_e32 v237, v161
	v_lshl_add_u64 v[218:219], v[218:219], 1, v[28:29]
	v_lshl_add_u64 v[222:223], v[220:221], 1, v[28:29]
	v_lshl_add_u64 v[226:227], v[226:227], 1, v[28:29]
	v_lshl_add_u64 v[230:231], v[228:229], 1, v[28:29]
	v_lshl_add_u64 v[234:235], v[234:235], 1, v[28:29]
	v_lshl_add_u64 v[252:253], v[236:237], 1, v[28:29]
	global_load_dwordx4 v[218:221], v[218:219], off
	s_nop 0
	global_load_dwordx4 v[222:225], v[222:223], off
	s_nop 0
	global_load_dwordx4 v[226:229], v[226:227], off
	s_nop 0
	global_load_dwordx4 v[230:233], v[230:231], off
	s_nop 0
	global_load_dwordx4 v[234:237], v[234:235], off
	s_nop 0
	global_load_dwordx4 v[238:241], v[252:253], off
	v_add_u32_e32 v252, 0x38000, v160
	v_mov_b32_e32 v253, v161
	v_lshl_add_u64 v[252:253], v[252:253], 1, v[28:29]
	v_add_u32_e32 v160, 0x3c000, v160
	v_lshl_add_u64 v[190:191], v[160:161], 1, v[28:29]
	global_load_dwordx4 v[242:245], v[252:253], off
	global_load_dwordx4 v[248:251], v[190:191], off
	v_mul_lo_u32 v27, v27, s40
	v_lshl_add_u32 v19, v19, 4, v27
	v_add_u32_e32 v27, 0x2080, v19
	v_add_u32_e32 v30, 0x4100, v19
	v_add_u32_e32 v33, 0x6180, v19
	v_add_u32_e32 v53, 0x8200, v19
	v_add_u32_e32 v55, 0xa280, v19
	v_add_u32_e32 v59, 0xc300, v19
	v_add_u32_e32 v84, 0xe380, v19
	s_waitcnt vmcnt(15)
	ds_write2_b64 v19, v[64:65], v[66:67] offset1:1
	s_waitcnt vmcnt(14)
	ds_write2_b64 v27, v[68:69], v[70:71] offset1:1
	s_waitcnt vmcnt(13)
	ds_write2_b64 v30, v[72:73], v[74:75] offset1:1
	s_waitcnt vmcnt(12)
	ds_write2_b64 v33, v[76:77], v[78:79] offset1:1
	s_waitcnt vmcnt(11)
	ds_write2_b64 v53, v[80:81], v[82:83] offset1:1
	s_waitcnt vmcnt(10)
	ds_write2_b64 v55, v[100:101], v[102:103] offset1:1
	s_waitcnt vmcnt(9)
	ds_write2_b64 v59, v[104:105], v[106:107] offset1:1
	s_waitcnt vmcnt(8)
	ds_write2_b64 v84, v[108:109], v[110:111] offset1:1
	v_add_u32_e32 v27, 0x10400, v19
	v_add_u32_e32 v28, 0x12480, v19
	v_add_u32_e32 v29, 0x14500, v19
	v_add_u32_e32 v30, 0x16580, v19
	v_add_u32_e32 v33, 0x18600, v19
	v_add_u32_e32 v53, 0x1a680, v19
	v_add_u32_e32 v55, 0x1c700, v19
	v_add_u32_e32 v19, 0x1e780, v19
	s_waitcnt vmcnt(7)
	ds_write2_b64 v27, v[218:219], v[220:221] offset1:1
	s_waitcnt vmcnt(6)
	ds_write2_b64 v28, v[222:223], v[224:225] offset1:1
	s_waitcnt vmcnt(5)
	ds_write2_b64 v29, v[226:227], v[228:229] offset1:1
	s_waitcnt vmcnt(4)
	ds_write2_b64 v30, v[230:231], v[232:233] offset1:1
	s_waitcnt vmcnt(3)
	ds_write2_b64 v33, v[234:235], v[236:237] offset1:1
	s_waitcnt vmcnt(2)
	ds_write2_b64 v53, v[238:239], v[240:241] offset1:1
	s_waitcnt vmcnt(1)
	ds_write2_b64 v55, v[242:243], v[244:245] offset1:1
	s_waitcnt vmcnt(0)
	ds_write2_b64 v19, v[248:249], v[250:251] offset1:1
	v_mov_b32_e32 v19, v192
	s_waitcnt lgkmcnt(0)
	s_barrier
; DI unsigned pack2(float a, float b) { f32x2_t v = {a, b}; bf16x2_t r = __builtin_convertvector(v, bf16x2_t); return __builtin_bit_cast(unsigned, r); }
; DI float bflo(unsigned u) { return __uint_as_float(u << 16); }
; DI float bfhi(unsigned u) { return __uint_as_float(u & 0xffff0000u); }
; DI int otid() { int t = threadIdx.x; asm volatile("" : "+v"(t)); return t; }
; template <bool LAST>
; DI void phase_gate(const Params& P, int layer, unsigned char* smem, int L, int G) {
;     ...
;     const int tid2 = otid();
;     const int lane2 = tid2 & 63, w2 = tid2 >> 6, r2 = lane2 & 31, h2 = lane2 >> 5, wm2 = w2 >> 2, wn2 = w2 & 3;
; #pragma unroll
;     for (int i = 0; i < 4; ++i)
; #pragma unroll
;       for (int q4 = 0; q4 < 4; ++q4) {
;         const int fl = wm2 * 128 + i * 32 + 8 * q4 + 4 * h2;
;         const int f0 = nt * 256 + fl;
;         const f32x4 gv = *(const f32x4*)(vecL + 512 + fl), bv = *(const f32x4*)(vecL + 768 + fl);
;         const float ga[4] = {gv.x, gv.y, gv.z, gv.w}, ba[4] = {bv.x, bv.y, bv.z, bv.w};
; #pragma unroll
;         for (int j = 0; j < 2; ++j) {
;           const int lrow = wn2 * 64 + j * 32 + r2;
;           const float mu = rowA[lrow], rstd = rowB[lrow];
;           uint2* sp = (uint2*)(stg + lrow * STG + fl);
;           const uint2 sv = *sp;
;           const float sa[4] = {bflo(sv.x), bfhi(sv.x), bflo(sv.y), bfhi(sv.y)};
;           float y[4];
;           const float gg[4] = {bflo(gq[i][j][2 * q4]), bfhi(gq[i][j][2 * q4]), bflo(gq[i][j][2 * q4 + 1]), bfhi(gq[i][j][2 * q4 + 1])};
; #pragma unroll
;           for (int e = 0; e < 4; ++e) y[e] = (sa[e] - mu) * rstd * ga[e] + ba[e] + gg[e];
;           if (LAST) { f32x4 o = {y[0], y[1], y[2], y[3]}; *(f32x4*)(P.out + (size_t)(mt * 256 + lrow) * 1024 + f0) = o; }
;           else { uint2 pk; pk.x = pack2(y[0], y[1]); pk.y = pack2(y[2], y[3]); *sp = pk; }
;         }
	v_lshlrev_b32_e32 v82, 16, v31
	v_lshrrev_b32_e32 v28, 3, v19
	v_ashrrev_i32_e32 v27, 1, v19
	v_and_b32_e32 v28, 4, v28
	v_and_or_b32 v30, v27, s41, v28
	v_and_b32_e32 v19, 0xdf, v19
	v_lshlrev_b32_e32 v27, 2, v30
	v_lshlrev_b32_e32 v33, 2, v19
	v_mul_u32_u24_e32 v19, 0x208, v19
	v_add_u32_e32 v28, 0x25000, v27
	v_lshl_add_u32 v19, v30, 1, v19
	v_add_u32_e32 v29, 0x25400, v27
	ds_read_b128 v[64:67], v28
	ds_read_b128 v[68:71], v29
	ds_read_b64 v[72:73], v19
	v_or_b32_e32 v29, 0x24000, v33
	v_or_b32_e32 v30, 0x24400, v33
	ds_read_b32 v74, v29
	ds_read_b32 v76, v30
	ds_read_b64 v[78:79], v19 offset:16640
	v_and_b32_e32 v83, 0xffff0000, v31
	s_waitcnt lgkmcnt(3)
	v_lshlrev_b32_e32 v80, 16, v72
	v_and_b32_e32 v81, 0xffff0000, v72
	v_lshlrev_b32_e32 v72, 16, v73
	v_and_b32_e32 v73, 0xffff0000, v73
	s_waitcnt lgkmcnt(2)
	v_pk_add_f32 v[80:81], v[80:81], v[74:75] op_sel_hi:[1,0] neg_lo:[0,1] neg_hi:[0,1]
	v_pk_add_f32 v[72:73], v[72:73], v[74:75] op_sel_hi:[1,0] neg_lo:[0,1] neg_hi:[0,1]
	s_waitcnt lgkmcnt(1)
	v_pk_mul_f32 v[80:81], v[76:77], v[80:81] op_sel_hi:[0,1]
	v_pk_mul_f32 v[72:73], v[76:77], v[72:73] op_sel_hi:[0,1]
	v_lshlrev_b32_e32 v84, 16, v98
	v_and_b32_e32 v85, 0xffff0000, v98
	v_pk_fma_f32 v[80:81], v[64:65], v[80:81], v[68:69]
	v_pk_fma_f32 v[72:73], v[66:67], v[72:73], v[70:71]
	v_pk_add_f32 v[80:81], v[80:81], v[82:83]
	v_pk_add_f32 v[72:73], v[72:73], v[84:85]
	v_cvt_pk_bf16_f32 v74, v80, v81
	v_cvt_pk_bf16_f32 v75, v72, v73
	ds_write_b64 v19, v[74:75]
	v_or_b32_e32 v31, 0x24080, v33
	v_or_b32_e32 v33, 0x24480, v33
	ds_read_b32 v72, v31
	ds_read_b32 v74, v33
	s_waitcnt lgkmcnt(3)
	v_lshlrev_b32_e32 v76, 16, v78
	v_and_b32_e32 v77, 0xffff0000, v78
	v_lshlrev_b32_e32 v78, 16, v79
	s_waitcnt lgkmcnt(1)
	v_pk_add_f32 v[76:77], v[76:77], v[72:73] op_sel_hi:[1,0] neg_lo:[0,1] neg_hi:[0,1]
	v_and_b32_e32 v79, 0xffff0000, v79
	s_waitcnt lgkmcnt(0)
	v_pk_mul_f32 v[76:77], v[74:75], v[76:77] op_sel_hi:[0,1]
	v_pk_fma_f32 v[64:65], v[64:65], v[76:77], v[68:69]
	v_pk_add_f32 v[68:69], v[78:79], v[72:73] op_sel_hi:[1,0] neg_lo:[0,1] neg_hi:[0,1]
	v_lshlrev_b32_e32 v80, 16, v97
	v_pk_mul_f32 v[68:69], v[74:75], v[68:69] op_sel_hi:[0,1]
	v_and_b32_e32 v81, 0xffff0000, v97
	v_lshlrev_b32_e32 v82, 16, v96
	v_and_b32_e32 v83, 0xffff0000, v96
	v_pk_fma_f32 v[66:67], v[66:67], v[68:69], v[70:71]
	v_pk_add_f32 v[64:65], v[64:65], v[80:81]
	v_pk_add_f32 v[66:67], v[66:67], v[82:83]
	v_cvt_pk_bf16_f32 v64, v64, v65
	v_cvt_pk_bf16_f32 v65, v66, v67
	ds_write_b64 v19, v[64:65] offset:16640
	v_add_u32_e32 v53, 0x25020, v27
	v_add_u32_e32 v55, 0x25420, v27
	ds_read_b64 v[72:73], v19 offset:16
	ds_read_b128 v[64:67], v53
	ds_read_b128 v[68:71], v55
	ds_read_b32 v74, v29
	ds_read_b32 v76, v30
	ds_read_b64 v[78:79], v19 offset:16656
	s_waitcnt lgkmcnt(5)
	v_lshlrev_b32_e32 v80, 16, v72
	v_and_b32_e32 v81, 0xffff0000, v72
	v_lshlrev_b32_e32 v72, 16, v73
	v_and_b32_e32 v73, 0xffff0000, v73
	s_waitcnt lgkmcnt(2)
	v_pk_add_f32 v[80:81], v[80:81], v[74:75] op_sel_hi:[1,0] neg_lo:[0,1] neg_hi:[0,1]
	v_pk_add_f32 v[72:73], v[72:73], v[74:75] op_sel_hi:[1,0] neg_lo:[0,1] neg_hi:[0,1]
	s_waitcnt lgkmcnt(1)
	v_pk_mul_f32 v[80:81], v[76:77], v[80:81] op_sel_hi:[0,1]
	v_pk_mul_f32 v[72:73], v[76:77], v[72:73] op_sel_hi:[0,1]
	v_lshlrev_b32_e32 v82, 16, v93
	v_and_b32_e32 v83, 0xffff0000, v93
	v_lshlrev_b32_e32 v84, 16, v95
	v_and_b32_e32 v85, 0xffff0000, v95
	v_pk_fma_f32 v[80:81], v[64:65], v[80:81], v[68:69]
	v_pk_fma_f32 v[72:73], v[66:67], v[72:73], v[70:71]
	v_pk_add_f32 v[80:81], v[80:81], v[82:83]
	v_pk_add_f32 v[72:73], v[72:73], v[84:85]
	v_cvt_pk_bf16_f32 v74, v80, v81
	v_cvt_pk_bf16_f32 v75, v72, v73
	ds_write_b64 v19, v[74:75] offset:16
	ds_read_b32 v72, v31
	ds_read_b32 v74, v33
	s_waitcnt lgkmcnt(3)
	v_lshlrev_b32_e32 v76, 16, v78
	v_and_b32_e32 v77, 0xffff0000, v78
	v_lshlrev_b32_e32 v78, 16, v79
	s_waitcnt lgkmcnt(1)
	v_pk_add_f32 v[76:77], v[76:77], v[72:73] op_sel_hi:[1,0] neg_lo:[0,1] neg_hi:[0,1]
	v_and_b32_e32 v79, 0xffff0000, v79
	s_waitcnt lgkmcnt(0)
	v_pk_mul_f32 v[76:77], v[74:75], v[76:77] op_sel_hi:[0,1]
	v_pk_fma_f32 v[64:65], v[64:65], v[76:77], v[68:69]
	v_pk_add_f32 v[68:69], v[78:79], v[72:73] op_sel_hi:[1,0] neg_lo:[0,1] neg_hi:[0,1]
	v_lshlrev_b32_e32 v80, 16, v92
	v_pk_mul_f32 v[68:69], v[74:75], v[68:69] op_sel_hi:[0,1]
	v_and_b32_e32 v81, 0xffff0000, v92
	v_lshlrev_b32_e32 v82, 16, v94
	v_and_b32_e32 v83, 0xffff0000, v94
	v_pk_fma_f32 v[66:67], v[66:67], v[68:69], v[70:71]
	v_pk_add_f32 v[64:65], v[64:65], v[80:81]
	v_pk_add_f32 v[66:67], v[66:67], v[82:83]
	v_cvt_pk_bf16_f32 v64, v64, v65
	v_cvt_pk_bf16_f32 v65, v66, v67
	ds_write_b64 v19, v[64:65] offset:16656
	v_add_u32_e32 v53, 0x25040, v27
	v_add_u32_e32 v55, 0x25440, v27
	ds_read_b64 v[72:73], v19 offset:32
	ds_read_b128 v[64:67], v53
	ds_read_b128 v[68:71], v55
	ds_read_b32 v74, v29
	ds_read_b32 v76, v30
	ds_read_b64 v[78:79], v19 offset:16672
	s_waitcnt lgkmcnt(5)
	v_lshlrev_b32_e32 v80, 16, v72
	v_and_b32_e32 v81, 0xffff0000, v72
	v_lshlrev_b32_e32 v72, 16, v73
	v_and_b32_e32 v73, 0xffff0000, v73
	s_waitcnt lgkmcnt(2)
	v_pk_add_f32 v[80:81], v[80:81], v[74:75] op_sel_hi:[1,0] neg_lo:[0,1] neg_hi:[0,1]
	v_pk_add_f32 v[72:73], v[72:73], v[74:75] op_sel_hi:[1,0] neg_lo:[0,1] neg_hi:[0,1]
	s_waitcnt lgkmcnt(1)
	v_pk_mul_f32 v[80:81], v[76:77], v[80:81] op_sel_hi:[0,1]
	v_pk_mul_f32 v[72:73], v[76:77], v[72:73] op_sel_hi:[0,1]
	v_lshlrev_b32_e32 v82, 16, v88
	v_and_b32_e32 v83, 0xffff0000, v88
	v_lshlrev_b32_e32 v84, 16, v90
	v_and_b32_e32 v85, 0xffff0000, v90
	v_pk_fma_f32 v[80:81], v[64:65], v[80:81], v[68:69]
	v_pk_fma_f32 v[72:73], v[66:67], v[72:73], v[70:71]
	v_pk_add_f32 v[80:81], v[80:81], v[82:83]
	v_pk_add_f32 v[72:73], v[72:73], v[84:85]
	v_cvt_pk_bf16_f32 v74, v80, v81
	v_cvt_pk_bf16_f32 v75, v72, v73
	ds_write_b64 v19, v[74:75] offset:32
	ds_read_b32 v72, v31
	ds_read_b32 v74, v33
	s_waitcnt lgkmcnt(3)
; DI unsigned pack2(float a, float b) { f32x2_t v = {a, b}; bf16x2_t r = __builtin_convertvector(v, bf16x2_t); return __builtin_bit_cast(unsigned, r); }
; DI float bflo(unsigned u) { return __uint_as_float(u << 16); }
; DI float bfhi(unsigned u) { return __uint_as_float(u & 0xffff0000u); }
; DI int otid() { int t = threadIdx.x; asm volatile("" : "+v"(t)); return t; }
; template <bool LAST>
; DI void phase_gate(const Params& P, int layer, unsigned char* smem, int L, int G) {
;     ...
;     const int tid2 = otid();
;     const int lane2 = tid2 & 63, w2 = tid2 >> 6, r2 = lane2 & 31, h2 = lane2 >> 5, wm2 = w2 >> 2, wn2 = w2 & 3;
; #pragma unroll
;     for (int i = 0; i < 4; ++i)
; #pragma unroll
;       for (int q4 = 0; q4 < 4; ++q4) {
;         const int fl = wm2 * 128 + i * 32 + 8 * q4 + 4 * h2;
;         const int f0 = nt * 256 + fl;
;         const f32x4 gv = *(const f32x4*)(vecL + 512 + fl), bv = *(const f32x4*)(vecL + 768 + fl);
;         const float ga[4] = {gv.x, gv.y, gv.z, gv.w}, ba[4] = {bv.x, bv.y, bv.z, bv.w};
; #pragma unroll
;         for (int j = 0; j < 2; ++j) {
;           const int lrow = wn2 * 64 + j * 32 + r2;
;           const float mu = rowA[lrow], rstd = rowB[lrow];
;           uint2* sp = (uint2*)(stg + lrow * STG + fl);
;           const uint2 sv = *sp;
;           const float sa[4] = {bflo(sv.x), bfhi(sv.x), bflo(sv.y), bfhi(sv.y)};
;           float y[4];
;           const float gg[4] = {bflo(gq[i][j][2 * q4]), bfhi(gq[i][j][2 * q4]), bflo(gq[i][j][2 * q4 + 1]), bfhi(gq[i][j][2 * q4 + 1])};
; #pragma unroll
;           for (int e = 0; e < 4; ++e) y[e] = (sa[e] - mu) * rstd * ga[e] + ba[e] + gg[e];
;           if (LAST) { f32x4 o = {y[0], y[1], y[2], y[3]}; *(f32x4*)(P.out + (size_t)(mt * 256 + lrow) * 1024 + f0) = o; }
;           else { uint2 pk; pk.x = pack2(y[0], y[1]); pk.y = pack2(y[2], y[3]); *sp = pk; }
;         }
	v_lshlrev_b32_e32 v76, 16, v78
	v_and_b32_e32 v77, 0xffff0000, v78
	v_lshlrev_b32_e32 v78, 16, v79
	s_waitcnt lgkmcnt(1)
	v_pk_add_f32 v[76:77], v[76:77], v[72:73] op_sel_hi:[1,0] neg_lo:[0,1] neg_hi:[0,1]
	v_and_b32_e32 v79, 0xffff0000, v79
	s_waitcnt lgkmcnt(0)
	v_pk_mul_f32 v[76:77], v[74:75], v[76:77] op_sel_hi:[0,1]
	v_pk_fma_f32 v[64:65], v[64:65], v[76:77], v[68:69]
	v_pk_add_f32 v[68:69], v[78:79], v[72:73] op_sel_hi:[1,0] neg_lo:[0,1] neg_hi:[0,1]
	v_lshlrev_b32_e32 v80, 16, v87
	v_pk_mul_f32 v[68:69], v[74:75], v[68:69] op_sel_hi:[0,1]
	v_and_b32_e32 v81, 0xffff0000, v87
	v_lshlrev_b32_e32 v82, 16, v89
	v_and_b32_e32 v83, 0xffff0000, v89
	v_pk_fma_f32 v[66:67], v[66:67], v[68:69], v[70:71]
	v_pk_add_f32 v[64:65], v[64:65], v[80:81]
	v_pk_add_f32 v[66:67], v[66:67], v[82:83]
	v_cvt_pk_bf16_f32 v64, v64, v65
	v_cvt_pk_bf16_f32 v65, v66, v67
	ds_write_b64 v19, v[64:65] offset:16672
	v_add_u32_e32 v53, 0x25060, v27
	v_add_u32_e32 v55, 0x25460, v27
	ds_read_b64 v[72:73], v19 offset:48
	ds_read_b128 v[64:67], v53
	ds_read_b128 v[68:71], v55
	ds_read_b32 v74, v29
	ds_read_b32 v76, v30
	ds_read_b64 v[78:79], v19 offset:16688
	s_waitcnt lgkmcnt(5)
	v_lshlrev_b32_e32 v80, 16, v72
	v_and_b32_e32 v81, 0xffff0000, v72
	v_lshlrev_b32_e32 v72, 16, v73
	v_and_b32_e32 v73, 0xffff0000, v73
	s_waitcnt lgkmcnt(2)
	v_pk_add_f32 v[80:81], v[80:81], v[74:75] op_sel_hi:[1,0] neg_lo:[0,1] neg_hi:[0,1]
	v_pk_add_f32 v[72:73], v[72:73], v[74:75] op_sel_hi:[1,0] neg_lo:[0,1] neg_hi:[0,1]
	s_waitcnt lgkmcnt(1)
	v_pk_mul_f32 v[80:81], v[76:77], v[80:81] op_sel_hi:[0,1]
	v_pk_mul_f32 v[72:73], v[76:77], v[72:73] op_sel_hi:[0,1]
	v_lshlrev_b32_e32 v82, 16, v61
	v_and_b32_e32 v83, 0xffff0000, v61
	v_lshlrev_b32_e32 v84, 16, v63
	v_and_b32_e32 v85, 0xffff0000, v63
	v_pk_fma_f32 v[80:81], v[64:65], v[80:81], v[68:69]
	v_pk_fma_f32 v[72:73], v[66:67], v[72:73], v[70:71]
	v_pk_add_f32 v[80:81], v[80:81], v[82:83]
	v_pk_add_f32 v[72:73], v[72:73], v[84:85]
	v_cvt_pk_bf16_f32 v74, v80, v81
	v_cvt_pk_bf16_f32 v75, v72, v73
	ds_write_b64 v19, v[74:75] offset:48
	ds_read_b32 v72, v31
	ds_read_b32 v74, v33
	s_waitcnt lgkmcnt(3)
	v_lshlrev_b32_e32 v76, 16, v78
	v_and_b32_e32 v77, 0xffff0000, v78
	v_lshlrev_b32_e32 v80, 16, v60
	v_and_b32_e32 v81, 0xffff0000, v60
	v_lshlrev_b32_e32 v60, 16, v62
	v_and_b32_e32 v61, 0xffff0000, v62
	s_waitcnt lgkmcnt(1)
	v_pk_add_f32 v[62:63], v[76:77], v[72:73] op_sel_hi:[1,0] neg_lo:[0,1] neg_hi:[0,1]
	v_lshlrev_b32_e32 v78, 16, v79
	v_and_b32_e32 v79, 0xffff0000, v79
	s_waitcnt lgkmcnt(0)
	v_pk_mul_f32 v[62:63], v[74:75], v[62:63] op_sel_hi:[0,1]
	v_pk_fma_f32 v[62:63], v[64:65], v[62:63], v[68:69]
	v_pk_add_f32 v[64:65], v[78:79], v[72:73] op_sel_hi:[1,0] neg_lo:[0,1] neg_hi:[0,1]
	v_pk_add_f32 v[62:63], v[62:63], v[80:81]
	v_pk_mul_f32 v[64:65], v[74:75], v[64:65] op_sel_hi:[0,1]
	v_pk_fma_f32 v[64:65], v[66:67], v[64:65], v[70:71]
	v_cvt_pk_bf16_f32 v62, v62, v63
	v_pk_add_f32 v[60:61], v[64:65], v[60:61]
	s_nop 0
	v_cvt_pk_bf16_f32 v63, v60, v61
	ds_write_b64 v19, v[62:63] offset:16688
	v_add_u32_e32 v53, 0x25080, v27
	v_add_u32_e32 v55, 0x25480, v27
	ds_read_b64 v[68:69], v19 offset:64
	ds_read_b128 v[60:63], v53
	ds_read_b128 v[64:67], v55
	ds_read_b32 v70, v29
	ds_read_b32 v72, v30
	ds_read_b64 v[74:75], v19 offset:16704
	s_waitcnt lgkmcnt(5)
	v_lshlrev_b32_e32 v76, 16, v68
	v_and_b32_e32 v77, 0xffff0000, v68
	v_lshlrev_b32_e32 v68, 16, v69
	v_and_b32_e32 v69, 0xffff0000, v69
	v_lshlrev_b32_e32 v80, 16, v58
	v_and_b32_e32 v81, 0xffff0000, v58
	s_waitcnt lgkmcnt(2)
	v_pk_add_f32 v[58:59], v[76:77], v[70:71] op_sel_hi:[1,0] neg_lo:[0,1] neg_hi:[0,1]
	v_pk_add_f32 v[68:69], v[68:69], v[70:71] op_sel_hi:[1,0] neg_lo:[0,1] neg_hi:[0,1]
	s_waitcnt lgkmcnt(1)
	v_pk_mul_f32 v[58:59], v[72:73], v[58:59] op_sel_hi:[0,1]
	v_pk_mul_f32 v[68:69], v[72:73], v[68:69] op_sel_hi:[0,1]
	v_lshlrev_b32_e32 v78, 16, v56
	v_and_b32_e32 v79, 0xffff0000, v56
	v_pk_fma_f32 v[58:59], v[60:61], v[58:59], v[64:65]
	v_pk_fma_f32 v[68:69], v[62:63], v[68:69], v[66:67]
	v_pk_add_f32 v[58:59], v[58:59], v[78:79]
	v_pk_add_f32 v[68:69], v[68:69], v[80:81]
	v_cvt_pk_bf16_f32 v58, v58, v59
	v_cvt_pk_bf16_f32 v59, v68, v69
	ds_write_b64 v19, v[58:59] offset:64
	ds_read_b32 v56, v31
	ds_read_b32 v58, v33
	s_waitcnt lgkmcnt(3)
	v_lshlrev_b32_e32 v68, 16, v74
	v_and_b32_e32 v69, 0xffff0000, v74
	v_lshlrev_b32_e32 v70, 16, v75
	v_and_b32_e32 v71, 0xffff0000, v75
	v_lshlrev_b32_e32 v72, 16, v54
	v_and_b32_e32 v73, 0xffff0000, v54
	v_lshlrev_b32_e32 v54, 16, v57
	v_and_b32_e32 v55, 0xffff0000, v57
	s_waitcnt lgkmcnt(1)
	v_pk_add_f32 v[68:69], v[68:69], v[56:57] op_sel_hi:[1,0] neg_lo:[0,1] neg_hi:[0,1]
	v_pk_add_f32 v[56:57], v[70:71], v[56:57] op_sel_hi:[1,0] neg_lo:[0,1] neg_hi:[0,1]
	s_waitcnt lgkmcnt(0)
	v_pk_mul_f32 v[68:69], v[58:59], v[68:69] op_sel_hi:[0,1]
	v_pk_mul_f32 v[56:57], v[58:59], v[56:57] op_sel_hi:[0,1]
	v_pk_fma_f32 v[60:61], v[60:61], v[68:69], v[64:65]
	v_pk_fma_f32 v[56:57], v[62:63], v[56:57], v[66:67]
	v_pk_add_f32 v[60:61], v[60:61], v[72:73]
	v_pk_add_f32 v[54:55], v[56:57], v[54:55]
	v_cvt_pk_bf16_f32 v56, v60, v61
	v_cvt_pk_bf16_f32 v57, v54, v55
	ds_write_b64 v19, v[56:57] offset:16704
	v_add_u32_e32 v58, 0x254a0, v27
	v_add_u32_e32 v53, 0x250a0, v27
	ds_read_b64 v[62:63], v19 offset:80
	ds_read_b128 v[54:57], v53
	ds_read_b128 v[58:61], v58
	ds_read_b32 v64, v29
	ds_read_b32 v66, v30
	ds_read_b64 v[68:69], v19 offset:16720
	s_waitcnt lgkmcnt(5)
	v_lshlrev_b32_e32 v70, 16, v62
	v_and_b32_e32 v71, 0xffff0000, v62
	v_lshlrev_b32_e32 v62, 16, v63
	v_and_b32_e32 v63, 0xffff0000, v63
	v_lshlrev_b32_e32 v74, 16, v52
	v_and_b32_e32 v75, 0xffff0000, v52
	s_waitcnt lgkmcnt(2)
; DI unsigned pack2(float a, float b) { f32x2_t v = {a, b}; bf16x2_t r = __builtin_convertvector(v, bf16x2_t); return __builtin_bit_cast(unsigned, r); }
; DI float bflo(unsigned u) { return __uint_as_float(u << 16); }
; DI float bfhi(unsigned u) { return __uint_as_float(u & 0xffff0000u); }
; DI int otid() { int t = threadIdx.x; asm volatile("" : "+v"(t)); return t; }
; template <bool LAST>
; DI void phase_gate(const Params& P, int layer, unsigned char* smem, int L, int G) {
;     ...
;     const int tid2 = otid();
;     const int lane2 = tid2 & 63, w2 = tid2 >> 6, r2 = lane2 & 31, h2 = lane2 >> 5, wm2 = w2 >> 2, wn2 = w2 & 3;
; #pragma unroll
;     for (int i = 0; i < 4; ++i)
; #pragma unroll
;       for (int q4 = 0; q4 < 4; ++q4) {
;         const int fl = wm2 * 128 + i * 32 + 8 * q4 + 4 * h2;
;         const int f0 = nt * 256 + fl;
;         const f32x4 gv = *(const f32x4*)(vecL + 512 + fl), bv = *(const f32x4*)(vecL + 768 + fl);
;         const float ga[4] = {gv.x, gv.y, gv.z, gv.w}, ba[4] = {bv.x, bv.y, bv.z, bv.w};
; #pragma unroll
;         for (int j = 0; j < 2; ++j) {
;           const int lrow = wn2 * 64 + j * 32 + r2;
;           const float mu = rowA[lrow], rstd = rowB[lrow];
;           uint2* sp = (uint2*)(stg + lrow * STG + fl);
;           const uint2 sv = *sp;
;           const float sa[4] = {bflo(sv.x), bfhi(sv.x), bflo(sv.y), bfhi(sv.y)};
;           float y[4];
;           const float gg[4] = {bflo(gq[i][j][2 * q4]), bfhi(gq[i][j][2 * q4]), bflo(gq[i][j][2 * q4 + 1]), bfhi(gq[i][j][2 * q4 + 1])};
; #pragma unroll
;           for (int e = 0; e < 4; ++e) y[e] = (sa[e] - mu) * rstd * ga[e] + ba[e] + gg[e];
;           if (LAST) { f32x4 o = {y[0], y[1], y[2], y[3]}; *(f32x4*)(P.out + (size_t)(mt * 256 + lrow) * 1024 + f0) = o; }
;           else { uint2 pk; pk.x = pack2(y[0], y[1]); pk.y = pack2(y[2], y[3]); *sp = pk; }
;         }
	v_pk_add_f32 v[52:53], v[70:71], v[64:65] op_sel_hi:[1,0] neg_lo:[0,1] neg_hi:[0,1]
	v_pk_add_f32 v[62:63], v[62:63], v[64:65] op_sel_hi:[1,0] neg_lo:[0,1] neg_hi:[0,1]
	s_waitcnt lgkmcnt(1)
	v_pk_mul_f32 v[52:53], v[66:67], v[52:53] op_sel_hi:[0,1]
	v_pk_mul_f32 v[62:63], v[66:67], v[62:63] op_sel_hi:[0,1]
	v_lshlrev_b32_e32 v72, 16, v50
	v_and_b32_e32 v73, 0xffff0000, v50
	v_pk_fma_f32 v[52:53], v[54:55], v[52:53], v[58:59]
	v_pk_fma_f32 v[62:63], v[56:57], v[62:63], v[60:61]
	v_pk_add_f32 v[52:53], v[52:53], v[72:73]
	v_pk_add_f32 v[62:63], v[62:63], v[74:75]
	v_cvt_pk_bf16_f32 v52, v52, v53
	v_cvt_pk_bf16_f32 v53, v62, v63
	ds_write_b64 v19, v[52:53] offset:80
	ds_read_b32 v50, v31
	ds_read_b32 v52, v33
	s_waitcnt lgkmcnt(3)
	v_lshlrev_b32_e32 v62, 16, v68
	v_and_b32_e32 v63, 0xffff0000, v68
	v_lshlrev_b32_e32 v64, 16, v69
	v_and_b32_e32 v65, 0xffff0000, v69
	v_lshlrev_b32_e32 v68, 16, v51
	v_and_b32_e32 v69, 0xffff0000, v51
	s_waitcnt lgkmcnt(1)
	v_pk_add_f32 v[62:63], v[62:63], v[50:51] op_sel_hi:[1,0] neg_lo:[0,1] neg_hi:[0,1]
	v_pk_add_f32 v[50:51], v[64:65], v[50:51] op_sel_hi:[1,0] neg_lo:[0,1] neg_hi:[0,1]
	s_waitcnt lgkmcnt(0)
	v_pk_mul_f32 v[62:63], v[52:53], v[62:63] op_sel_hi:[0,1]
	v_pk_mul_f32 v[50:51], v[52:53], v[50:51] op_sel_hi:[0,1]
	v_lshlrev_b32_e32 v66, 16, v49
	v_and_b32_e32 v67, 0xffff0000, v49
	v_pk_fma_f32 v[54:55], v[54:55], v[62:63], v[58:59]
	v_pk_fma_f32 v[50:51], v[56:57], v[50:51], v[60:61]
	v_pk_add_f32 v[54:55], v[54:55], v[66:67]
	v_pk_add_f32 v[50:51], v[50:51], v[68:69]
	v_cvt_pk_bf16_f32 v52, v54, v55
	v_cvt_pk_bf16_f32 v53, v50, v51
	ds_write_b64 v19, v[52:53] offset:16720
	v_add_u32_e32 v54, 0x254c0, v27
	v_add_u32_e32 v49, 0x250c0, v27
	ds_read_b64 v[58:59], v19 offset:96
	ds_read_b128 v[50:53], v49
	ds_read_b128 v[54:57], v54
	ds_read_b32 v60, v29
	ds_read_b32 v62, v30
	ds_read_b64 v[64:65], v19 offset:16736
	s_waitcnt lgkmcnt(5)
	v_lshlrev_b32_e32 v66, 16, v58
	v_and_b32_e32 v67, 0xffff0000, v58
	v_lshlrev_b32_e32 v58, 16, v59
	v_and_b32_e32 v59, 0xffff0000, v59
	v_lshlrev_b32_e32 v70, 16, v48
	v_and_b32_e32 v71, 0xffff0000, v48
	s_waitcnt lgkmcnt(2)
	v_pk_add_f32 v[48:49], v[66:67], v[60:61] op_sel_hi:[1,0] neg_lo:[0,1] neg_hi:[0,1]
	v_pk_add_f32 v[58:59], v[58:59], v[60:61] op_sel_hi:[1,0] neg_lo:[0,1] neg_hi:[0,1]
	s_waitcnt lgkmcnt(1)
	v_pk_mul_f32 v[48:49], v[62:63], v[48:49] op_sel_hi:[0,1]
	v_pk_mul_f32 v[58:59], v[62:63], v[58:59] op_sel_hi:[0,1]
	v_lshlrev_b32_e32 v68, 16, v46
	v_and_b32_e32 v69, 0xffff0000, v46
	v_pk_fma_f32 v[48:49], v[50:51], v[48:49], v[54:55]
	v_pk_fma_f32 v[58:59], v[52:53], v[58:59], v[56:57]
	v_pk_add_f32 v[48:49], v[48:49], v[68:69]
	v_pk_add_f32 v[58:59], v[58:59], v[70:71]
	v_cvt_pk_bf16_f32 v48, v48, v49
	v_cvt_pk_bf16_f32 v49, v58, v59
	ds_write_b64 v19, v[48:49] offset:96
	ds_read_b32 v46, v31
	ds_read_b32 v48, v33
	s_waitcnt lgkmcnt(3)
	v_lshlrev_b32_e32 v58, 16, v64
	v_and_b32_e32 v59, 0xffff0000, v64
	v_lshlrev_b32_e32 v60, 16, v65
	v_and_b32_e32 v61, 0xffff0000, v65
	v_lshlrev_b32_e32 v64, 16, v47
	v_and_b32_e32 v65, 0xffff0000, v47
	s_waitcnt lgkmcnt(1)
	v_pk_add_f32 v[58:59], v[58:59], v[46:47] op_sel_hi:[1,0] neg_lo:[0,1] neg_hi:[0,1]
	v_pk_add_f32 v[46:47], v[60:61], v[46:47] op_sel_hi:[1,0] neg_lo:[0,1] neg_hi:[0,1]
	s_waitcnt lgkmcnt(0)
	v_pk_mul_f32 v[58:59], v[48:49], v[58:59] op_sel_hi:[0,1]
	v_pk_mul_f32 v[46:47], v[48:49], v[46:47] op_sel_hi:[0,1]
	v_lshlrev_b32_e32 v62, 16, v45
	v_and_b32_e32 v63, 0xffff0000, v45
	v_pk_fma_f32 v[50:51], v[50:51], v[58:59], v[54:55]
	v_pk_fma_f32 v[46:47], v[52:53], v[46:47], v[56:57]
	v_pk_add_f32 v[50:51], v[50:51], v[62:63]
	v_pk_add_f32 v[46:47], v[46:47], v[64:65]
	v_cvt_pk_bf16_f32 v48, v50, v51
	v_cvt_pk_bf16_f32 v49, v46, v47
	ds_write_b64 v19, v[48:49] offset:16736
	v_add_u32_e32 v50, 0x254e0, v27
	v_add_u32_e32 v45, 0x250e0, v27
	ds_read_b64 v[54:55], v19 offset:112
	ds_read_b128 v[46:49], v45
	ds_read_b128 v[50:53], v50
	ds_read_b32 v56, v29
	ds_read_b32 v58, v30
	ds_read_b64 v[60:61], v19 offset:16752
	s_waitcnt lgkmcnt(5)
	v_lshlrev_b32_e32 v62, 16, v54
	v_and_b32_e32 v63, 0xffff0000, v54
	v_lshlrev_b32_e32 v54, 16, v55
	v_and_b32_e32 v55, 0xffff0000, v55
	v_lshlrev_b32_e32 v66, 16, v44
	v_and_b32_e32 v67, 0xffff0000, v44
	s_waitcnt lgkmcnt(2)
	v_pk_add_f32 v[44:45], v[62:63], v[56:57] op_sel_hi:[1,0] neg_lo:[0,1] neg_hi:[0,1]
	v_pk_add_f32 v[54:55], v[54:55], v[56:57] op_sel_hi:[1,0] neg_lo:[0,1] neg_hi:[0,1]
	s_waitcnt lgkmcnt(1)
	v_pk_mul_f32 v[44:45], v[58:59], v[44:45] op_sel_hi:[0,1]
	v_pk_mul_f32 v[54:55], v[58:59], v[54:55] op_sel_hi:[0,1]
	v_lshlrev_b32_e32 v64, 16, v42
	v_and_b32_e32 v65, 0xffff0000, v42
	v_pk_fma_f32 v[44:45], v[46:47], v[44:45], v[50:51]
	v_pk_fma_f32 v[54:55], v[48:49], v[54:55], v[52:53]
	v_pk_add_f32 v[44:45], v[44:45], v[64:65]
	v_pk_add_f32 v[54:55], v[54:55], v[66:67]
	v_cvt_pk_bf16_f32 v44, v44, v45
	v_cvt_pk_bf16_f32 v45, v54, v55
	ds_write_b64 v19, v[44:45] offset:112
	ds_read_b32 v42, v31
	ds_read_b32 v44, v33
	s_waitcnt lgkmcnt(3)
	v_lshlrev_b32_e32 v54, 16, v60
	v_and_b32_e32 v55, 0xffff0000, v60
	v_lshlrev_b32_e32 v56, 16, v61
	v_and_b32_e32 v57, 0xffff0000, v61
	v_lshlrev_b32_e32 v60, 16, v43
	v_and_b32_e32 v61, 0xffff0000, v43
	s_waitcnt lgkmcnt(1)
	v_pk_add_f32 v[54:55], v[54:55], v[42:43] op_sel_hi:[1,0] neg_lo:[0,1] neg_hi:[0,1]
	v_pk_add_f32 v[42:43], v[56:57], v[42:43] op_sel_hi:[1,0] neg_lo:[0,1] neg_hi:[0,1]
	s_waitcnt lgkmcnt(0)
; DI unsigned pack2(float a, float b) { f32x2_t v = {a, b}; bf16x2_t r = __builtin_convertvector(v, bf16x2_t); return __builtin_bit_cast(unsigned, r); }
; DI float bflo(unsigned u) { return __uint_as_float(u << 16); }
; DI float bfhi(unsigned u) { return __uint_as_float(u & 0xffff0000u); }
; DI int otid() { int t = threadIdx.x; asm volatile("" : "+v"(t)); return t; }
; template <bool LAST>
; DI void phase_gate(const Params& P, int layer, unsigned char* smem, int L, int G) {
;     ...
;     const int tid2 = otid();
;     const int lane2 = tid2 & 63, w2 = tid2 >> 6, r2 = lane2 & 31, h2 = lane2 >> 5, wm2 = w2 >> 2, wn2 = w2 & 3;
; #pragma unroll
;     for (int i = 0; i < 4; ++i)
; #pragma unroll
;       for (int q4 = 0; q4 < 4; ++q4) {
;         const int fl = wm2 * 128 + i * 32 + 8 * q4 + 4 * h2;
;         const int f0 = nt * 256 + fl;
;         const f32x4 gv = *(const f32x4*)(vecL + 512 + fl), bv = *(const f32x4*)(vecL + 768 + fl);
;         const float ga[4] = {gv.x, gv.y, gv.z, gv.w}, ba[4] = {bv.x, bv.y, bv.z, bv.w};
; #pragma unroll
;         for (int j = 0; j < 2; ++j) {
;           const int lrow = wn2 * 64 + j * 32 + r2;
;           const float mu = rowA[lrow], rstd = rowB[lrow];
;           uint2* sp = (uint2*)(stg + lrow * STG + fl);
;           const uint2 sv = *sp;
;           const float sa[4] = {bflo(sv.x), bfhi(sv.x), bflo(sv.y), bfhi(sv.y)};
;           float y[4];
;           const float gg[4] = {bflo(gq[i][j][2 * q4]), bfhi(gq[i][j][2 * q4]), bflo(gq[i][j][2 * q4 + 1]), bfhi(gq[i][j][2 * q4 + 1])};
; #pragma unroll
;           for (int e = 0; e < 4; ++e) y[e] = (sa[e] - mu) * rstd * ga[e] + ba[e] + gg[e];
;           if (LAST) { f32x4 o = {y[0], y[1], y[2], y[3]}; *(f32x4*)(P.out + (size_t)(mt * 256 + lrow) * 1024 + f0) = o; }
;           else { uint2 pk; pk.x = pack2(y[0], y[1]); pk.y = pack2(y[2], y[3]); *sp = pk; }
;         }
	v_pk_mul_f32 v[54:55], v[44:45], v[54:55] op_sel_hi:[0,1]
	v_pk_mul_f32 v[42:43], v[44:45], v[42:43] op_sel_hi:[0,1]
	v_lshlrev_b32_e32 v58, 16, v41
	v_and_b32_e32 v59, 0xffff0000, v41
	v_pk_fma_f32 v[46:47], v[46:47], v[54:55], v[50:51]
	v_pk_fma_f32 v[42:43], v[48:49], v[42:43], v[52:53]
	v_pk_add_f32 v[46:47], v[46:47], v[58:59]
	v_pk_add_f32 v[42:43], v[42:43], v[60:61]
	v_cvt_pk_bf16_f32 v44, v46, v47
	v_cvt_pk_bf16_f32 v45, v42, v43
	ds_write_b64 v19, v[44:45] offset:16752
	v_add_u32_e32 v46, 0x25500, v27
	v_add_u32_e32 v41, 0x25100, v27
	ds_read_b64 v[50:51], v19 offset:128
	ds_read_b128 v[42:45], v41
	ds_read_b128 v[46:49], v46
	ds_read_b32 v52, v29
	ds_read_b32 v54, v30
	ds_read_b64 v[56:57], v19 offset:16768
	s_waitcnt lgkmcnt(5)
	v_lshlrev_b32_e32 v58, 16, v50
	v_and_b32_e32 v59, 0xffff0000, v50
	v_lshlrev_b32_e32 v50, 16, v51
	v_and_b32_e32 v51, 0xffff0000, v51
	v_lshlrev_b32_e32 v62, 16, v40
	v_and_b32_e32 v63, 0xffff0000, v40
	s_waitcnt lgkmcnt(2)
	v_pk_add_f32 v[40:41], v[58:59], v[52:53] op_sel_hi:[1,0] neg_lo:[0,1] neg_hi:[0,1]
	v_pk_add_f32 v[50:51], v[50:51], v[52:53] op_sel_hi:[1,0] neg_lo:[0,1] neg_hi:[0,1]
	s_waitcnt lgkmcnt(1)
	v_pk_mul_f32 v[40:41], v[54:55], v[40:41] op_sel_hi:[0,1]
	v_pk_mul_f32 v[50:51], v[54:55], v[50:51] op_sel_hi:[0,1]
	v_lshlrev_b32_e32 v60, 16, v38
	v_and_b32_e32 v61, 0xffff0000, v38
	v_pk_fma_f32 v[40:41], v[42:43], v[40:41], v[46:47]
	v_pk_fma_f32 v[50:51], v[44:45], v[50:51], v[48:49]
	v_pk_add_f32 v[40:41], v[40:41], v[60:61]
	v_pk_add_f32 v[50:51], v[50:51], v[62:63]
	v_cvt_pk_bf16_f32 v40, v40, v41
	v_cvt_pk_bf16_f32 v41, v50, v51
	ds_write_b64 v19, v[40:41] offset:128
	ds_read_b32 v38, v31
	ds_read_b32 v40, v33
	s_waitcnt lgkmcnt(3)
	v_lshlrev_b32_e32 v50, 16, v56
	v_and_b32_e32 v51, 0xffff0000, v56
	v_lshlrev_b32_e32 v52, 16, v57
	v_and_b32_e32 v53, 0xffff0000, v57
	v_lshlrev_b32_e32 v56, 16, v39
	v_and_b32_e32 v57, 0xffff0000, v39
	s_waitcnt lgkmcnt(1)
	v_pk_add_f32 v[50:51], v[50:51], v[38:39] op_sel_hi:[1,0] neg_lo:[0,1] neg_hi:[0,1]
	v_pk_add_f32 v[38:39], v[52:53], v[38:39] op_sel_hi:[1,0] neg_lo:[0,1] neg_hi:[0,1]
	s_waitcnt lgkmcnt(0)
	v_pk_mul_f32 v[50:51], v[40:41], v[50:51] op_sel_hi:[0,1]
	v_pk_mul_f32 v[38:39], v[40:41], v[38:39] op_sel_hi:[0,1]
	v_lshlrev_b32_e32 v54, 16, v37
	v_and_b32_e32 v55, 0xffff0000, v37
	v_pk_fma_f32 v[42:43], v[42:43], v[50:51], v[46:47]
	v_pk_fma_f32 v[38:39], v[44:45], v[38:39], v[48:49]
	v_pk_add_f32 v[42:43], v[42:43], v[54:55]
	v_pk_add_f32 v[38:39], v[38:39], v[56:57]
	v_cvt_pk_bf16_f32 v40, v42, v43
	v_cvt_pk_bf16_f32 v41, v38, v39
	ds_write_b64 v19, v[40:41] offset:16768
	v_add_u32_e32 v42, 0x25520, v27
	v_add_u32_e32 v37, 0x25120, v27
	ds_read_b64 v[46:47], v19 offset:144
	ds_read_b128 v[38:41], v37
	ds_read_b128 v[42:45], v42
	ds_read_b32 v48, v29
	ds_read_b32 v50, v30
	ds_read_b64 v[52:53], v19 offset:16784
	s_waitcnt lgkmcnt(5)
	v_lshlrev_b32_e32 v54, 16, v46
	v_and_b32_e32 v55, 0xffff0000, v46
	v_lshlrev_b32_e32 v46, 16, v47
	v_and_b32_e32 v47, 0xffff0000, v47
	v_lshlrev_b32_e32 v58, 16, v36
	v_and_b32_e32 v59, 0xffff0000, v36
	s_waitcnt lgkmcnt(2)
	v_pk_add_f32 v[36:37], v[54:55], v[48:49] op_sel_hi:[1,0] neg_lo:[0,1] neg_hi:[0,1]
	v_pk_add_f32 v[46:47], v[46:47], v[48:49] op_sel_hi:[1,0] neg_lo:[0,1] neg_hi:[0,1]
	s_waitcnt lgkmcnt(1)
	v_pk_mul_f32 v[36:37], v[50:51], v[36:37] op_sel_hi:[0,1]
	v_pk_mul_f32 v[46:47], v[50:51], v[46:47] op_sel_hi:[0,1]
	v_lshlrev_b32_e32 v56, 16, v34
	v_and_b32_e32 v57, 0xffff0000, v34
	v_pk_fma_f32 v[36:37], v[38:39], v[36:37], v[42:43]
	v_pk_fma_f32 v[46:47], v[40:41], v[46:47], v[44:45]
	v_pk_add_f32 v[36:37], v[36:37], v[56:57]
	v_pk_add_f32 v[46:47], v[46:47], v[58:59]
	v_cvt_pk_bf16_f32 v36, v36, v37
	v_cvt_pk_bf16_f32 v37, v46, v47
	ds_write_b64 v19, v[36:37] offset:144
	ds_read_b32 v34, v31
	ds_read_b32 v36, v33
	s_waitcnt lgkmcnt(3)
	v_lshlrev_b32_e32 v46, 16, v52
	v_and_b32_e32 v47, 0xffff0000, v52
	v_lshlrev_b32_e32 v48, 16, v53
	v_and_b32_e32 v49, 0xffff0000, v53
	v_lshlrev_b32_e32 v52, 16, v35
	v_and_b32_e32 v53, 0xffff0000, v35
	s_waitcnt lgkmcnt(1)
	v_pk_add_f32 v[46:47], v[46:47], v[34:35] op_sel_hi:[1,0] neg_lo:[0,1] neg_hi:[0,1]
	v_pk_add_f32 v[34:35], v[48:49], v[34:35] op_sel_hi:[1,0] neg_lo:[0,1] neg_hi:[0,1]
	s_waitcnt lgkmcnt(0)
	v_pk_mul_f32 v[46:47], v[36:37], v[46:47] op_sel_hi:[0,1]
	v_pk_mul_f32 v[34:35], v[36:37], v[34:35] op_sel_hi:[0,1]
	v_lshlrev_b32_e32 v50, 16, v32
	v_and_b32_e32 v51, 0xffff0000, v32
	v_pk_fma_f32 v[38:39], v[38:39], v[46:47], v[42:43]
	v_pk_fma_f32 v[34:35], v[40:41], v[34:35], v[44:45]
	v_pk_add_f32 v[38:39], v[38:39], v[50:51]
	v_pk_add_f32 v[34:35], v[34:35], v[52:53]
	v_cvt_pk_bf16_f32 v36, v38, v39
	v_cvt_pk_bf16_f32 v37, v34, v35
	ds_write_b64 v19, v[36:37] offset:16784
	v_add_u32_e32 v32, 0x25140, v27
	v_add_u32_e32 v38, 0x25540, v27
	ds_read_b64 v[42:43], v19 offset:160
	ds_read_b128 v[34:37], v32
	ds_read_b128 v[38:41], v38
	ds_read_b32 v32, v29
	ds_read_b32 v44, v30
	ds_read_b64 v[46:47], v19 offset:16800
	s_waitcnt lgkmcnt(5)
	v_lshlrev_b32_e32 v48, 16, v42
	v_and_b32_e32 v49, 0xffff0000, v42
	v_lshlrev_b32_e32 v42, 16, v43
	v_and_b32_e32 v43, 0xffff0000, v43
	s_waitcnt lgkmcnt(2)
	v_pk_add_f32 v[48:49], v[48:49], v[32:33] op_sel_hi:[1,0] neg_lo:[0,1] neg_hi:[0,1]
	v_pk_add_f32 v[42:43], v[42:43], v[32:33] op_sel_hi:[1,0] neg_lo:[0,1] neg_hi:[0,1]
	s_waitcnt lgkmcnt(1)
; DI unsigned pack2(float a, float b) { f32x2_t v = {a, b}; bf16x2_t r = __builtin_convertvector(v, bf16x2_t); return __builtin_bit_cast(unsigned, r); }
; DI float bflo(unsigned u) { return __uint_as_float(u << 16); }
; DI float bfhi(unsigned u) { return __uint_as_float(u & 0xffff0000u); }
; DI int otid() { int t = threadIdx.x; asm volatile("" : "+v"(t)); return t; }
; template <bool LAST>
; DI void phase_gate(const Params& P, int layer, unsigned char* smem, int L, int G) {
;     ...
;     const int tid2 = otid();
;     const int lane2 = tid2 & 63, w2 = tid2 >> 6, r2 = lane2 & 31, h2 = lane2 >> 5, wm2 = w2 >> 2, wn2 = w2 & 3;
; #pragma unroll
;     for (int i = 0; i < 4; ++i)
; #pragma unroll
;       for (int q4 = 0; q4 < 4; ++q4) {
;         const int fl = wm2 * 128 + i * 32 + 8 * q4 + 4 * h2;
;         const int f0 = nt * 256 + fl;
;         const f32x4 gv = *(const f32x4*)(vecL + 512 + fl), bv = *(const f32x4*)(vecL + 768 + fl);
;         const float ga[4] = {gv.x, gv.y, gv.z, gv.w}, ba[4] = {bv.x, bv.y, bv.z, bv.w};
; #pragma unroll
;         for (int j = 0; j < 2; ++j) {
;           const int lrow = wn2 * 64 + j * 32 + r2;
;           const float mu = rowA[lrow], rstd = rowB[lrow];
;           uint2* sp = (uint2*)(stg + lrow * STG + fl);
;           const uint2 sv = *sp;
;           const float sa[4] = {bflo(sv.x), bfhi(sv.x), bflo(sv.y), bfhi(sv.y)};
;           float y[4];
;           const float gg[4] = {bflo(gq[i][j][2 * q4]), bfhi(gq[i][j][2 * q4]), bflo(gq[i][j][2 * q4 + 1]), bfhi(gq[i][j][2 * q4 + 1])};
; #pragma unroll
;           for (int e = 0; e < 4; ++e) y[e] = (sa[e] - mu) * rstd * ga[e] + ba[e] + gg[e];
;           if (LAST) { f32x4 o = {y[0], y[1], y[2], y[3]}; *(f32x4*)(P.out + (size_t)(mt * 256 + lrow) * 1024 + f0) = o; }
;           else { uint2 pk; pk.x = pack2(y[0], y[1]); pk.y = pack2(y[2], y[3]); *sp = pk; }
;         }
	v_pk_mul_f32 v[48:49], v[44:45], v[48:49] op_sel_hi:[0,1]
	v_pk_mul_f32 v[42:43], v[44:45], v[42:43] op_sel_hi:[0,1]
	v_lshlrev_b32_e32 v50, 16, v24
	v_and_b32_e32 v51, 0xffff0000, v24
	v_lshlrev_b32_e32 v52, 16, v26
	v_and_b32_e32 v53, 0xffff0000, v26
	v_pk_fma_f32 v[48:49], v[34:35], v[48:49], v[38:39]
	v_pk_fma_f32 v[42:43], v[36:37], v[42:43], v[40:41]
	v_pk_add_f32 v[48:49], v[48:49], v[50:51]
	v_pk_add_f32 v[42:43], v[42:43], v[52:53]
	v_cvt_pk_bf16_f32 v44, v48, v49
	v_cvt_pk_bf16_f32 v45, v42, v43
	ds_write_b64 v19, v[44:45] offset:160
	ds_read_b32 v24, v31
	ds_read_b32 v26, v33
	s_waitcnt lgkmcnt(3)
	v_lshlrev_b32_e32 v42, 16, v46
	v_and_b32_e32 v43, 0xffff0000, v46
	v_lshlrev_b32_e32 v44, 16, v47
	v_and_b32_e32 v45, 0xffff0000, v47
	v_lshlrev_b32_e32 v48, 16, v25
	v_and_b32_e32 v49, 0xffff0000, v25
	s_waitcnt lgkmcnt(1)
	v_pk_add_f32 v[42:43], v[42:43], v[24:25] op_sel_hi:[1,0] neg_lo:[0,1] neg_hi:[0,1]
	v_pk_add_f32 v[24:25], v[44:45], v[24:25] op_sel_hi:[1,0] neg_lo:[0,1] neg_hi:[0,1]
	s_waitcnt lgkmcnt(0)
	v_pk_mul_f32 v[42:43], v[26:27], v[42:43] op_sel_hi:[0,1]
	v_pk_mul_f32 v[24:25], v[26:27], v[24:25] op_sel_hi:[0,1]
	v_lshlrev_b32_e32 v46, 16, v23
	v_and_b32_e32 v47, 0xffff0000, v23
	v_pk_fma_f32 v[34:35], v[34:35], v[42:43], v[38:39]
	v_pk_fma_f32 v[24:25], v[36:37], v[24:25], v[40:41]
	v_pk_add_f32 v[34:35], v[34:35], v[46:47]
	v_pk_add_f32 v[24:25], v[24:25], v[48:49]
	v_cvt_pk_bf16_f32 v34, v34, v35
	v_cvt_pk_bf16_f32 v35, v24, v25
	ds_write_b64 v19, v[34:35] offset:16800
	v_add_u32_e32 v26, 0x25560, v27
	v_add_u32_e32 v23, 0x25160, v27
	ds_read_b64 v[24:25], v19 offset:176
	ds_read_b128 v[34:37], v23
	ds_read_b128 v[38:41], v26
	ds_read_b32 v26, v29
	ds_read_b32 v32, v30
	ds_read_b64 v[42:43], v19 offset:16816
	s_waitcnt lgkmcnt(5)
	v_lshlrev_b32_e32 v44, 16, v24
	v_and_b32_e32 v45, 0xffff0000, v24
	v_lshlrev_b32_e32 v24, 16, v25
	v_and_b32_e32 v25, 0xffff0000, v25
	v_lshlrev_b32_e32 v48, 16, v22
	v_and_b32_e32 v49, 0xffff0000, v22
	s_waitcnt lgkmcnt(2)
	v_pk_add_f32 v[22:23], v[44:45], v[26:27] op_sel_hi:[1,0] neg_lo:[0,1] neg_hi:[0,1]
	v_pk_add_f32 v[24:25], v[24:25], v[26:27] op_sel_hi:[1,0] neg_lo:[0,1] neg_hi:[0,1]
	s_waitcnt lgkmcnt(1)
	v_pk_mul_f32 v[22:23], v[32:33], v[22:23] op_sel_hi:[0,1]
	v_pk_mul_f32 v[24:25], v[32:33], v[24:25] op_sel_hi:[0,1]
	v_lshlrev_b32_e32 v46, 16, v20
	v_and_b32_e32 v47, 0xffff0000, v20
	v_pk_fma_f32 v[22:23], v[34:35], v[22:23], v[38:39]
	v_pk_fma_f32 v[24:25], v[36:37], v[24:25], v[40:41]
	v_pk_add_f32 v[22:23], v[22:23], v[46:47]
	v_pk_add_f32 v[24:25], v[24:25], v[48:49]
	v_cvt_pk_bf16_f32 v22, v22, v23
	v_cvt_pk_bf16_f32 v23, v24, v25
	ds_write_b64 v19, v[22:23] offset:176
	ds_read_b32 v20, v31
	ds_read_b32 v22, v33
	s_waitcnt lgkmcnt(3)
	v_lshlrev_b32_e32 v24, 16, v42
	v_and_b32_e32 v25, 0xffff0000, v42
	v_lshlrev_b32_e32 v42, 16, v43
	v_and_b32_e32 v43, 0xffff0000, v43
	v_lshlrev_b32_e32 v46, 16, v21
	v_and_b32_e32 v47, 0xffff0000, v21
	s_waitcnt lgkmcnt(1)
	v_pk_add_f32 v[24:25], v[24:25], v[20:21] op_sel_hi:[1,0] neg_lo:[0,1] neg_hi:[0,1]
	v_pk_add_f32 v[20:21], v[42:43], v[20:21] op_sel_hi:[1,0] neg_lo:[0,1] neg_hi:[0,1]
	s_waitcnt lgkmcnt(0)
	v_pk_mul_f32 v[24:25], v[22:23], v[24:25] op_sel_hi:[0,1]
	v_pk_mul_f32 v[20:21], v[22:23], v[20:21] op_sel_hi:[0,1]
	v_lshlrev_b32_e32 v44, 16, v18
	v_and_b32_e32 v45, 0xffff0000, v18
	v_pk_fma_f32 v[24:25], v[34:35], v[24:25], v[38:39]
	v_pk_fma_f32 v[20:21], v[36:37], v[20:21], v[40:41]
	v_pk_add_f32 v[24:25], v[24:25], v[44:45]
	v_pk_add_f32 v[20:21], v[20:21], v[46:47]
	v_cvt_pk_bf16_f32 v22, v24, v25
	v_cvt_pk_bf16_f32 v23, v20, v21
	ds_write_b64 v19, v[22:23] offset:16816
	v_add_u32_e32 v18, 0x25180, v27
	v_add_u32_e32 v26, 0x25580, v27
	ds_read_b64 v[24:25], v19 offset:192
	ds_read_b128 v[20:23], v18
	ds_read_b128 v[34:37], v26
	ds_read_b32 v18, v29
	ds_read_b32 v26, v30
	ds_read_b64 v[38:39], v19 offset:16832
	s_waitcnt lgkmcnt(5)
	v_lshlrev_b32_e32 v40, 16, v24
	v_and_b32_e32 v41, 0xffff0000, v24
	v_lshlrev_b32_e32 v24, 16, v25
	v_and_b32_e32 v25, 0xffff0000, v25
	s_waitcnt lgkmcnt(2)
	v_pk_add_f32 v[40:41], v[40:41], v[18:19] op_sel_hi:[1,0] neg_lo:[0,1] neg_hi:[0,1]
	v_pk_add_f32 v[24:25], v[24:25], v[18:19] op_sel_hi:[1,0] neg_lo:[0,1] neg_hi:[0,1]
	s_waitcnt lgkmcnt(1)
	v_pk_mul_f32 v[40:41], v[26:27], v[40:41] op_sel_hi:[0,1]
	v_pk_mul_f32 v[24:25], v[26:27], v[24:25] op_sel_hi:[0,1]
	v_lshlrev_b32_e32 v42, 16, v15
	v_and_b32_e32 v43, 0xffff0000, v15
	v_lshlrev_b32_e32 v44, 16, v17
	v_and_b32_e32 v45, 0xffff0000, v17
	v_pk_fma_f32 v[40:41], v[20:21], v[40:41], v[34:35]
	v_pk_fma_f32 v[24:25], v[22:23], v[24:25], v[36:37]
	v_pk_add_f32 v[40:41], v[40:41], v[42:43]
	v_pk_add_f32 v[24:25], v[24:25], v[44:45]
	v_cvt_pk_bf16_f32 v40, v40, v41
	v_cvt_pk_bf16_f32 v41, v24, v25
	ds_write_b64 v19, v[40:41] offset:192
	ds_read_b32 v18, v31
	ds_read_b32 v24, v33
	s_waitcnt lgkmcnt(3)
	v_lshlrev_b32_e32 v40, 16, v38
	v_and_b32_e32 v41, 0xffff0000, v38
	v_lshlrev_b32_e32 v42, 16, v14
	v_and_b32_e32 v43, 0xffff0000, v14
	v_lshlrev_b32_e32 v14, 16, v16
	v_and_b32_e32 v15, 0xffff0000, v16
	s_waitcnt lgkmcnt(1)
	v_pk_add_f32 v[16:17], v[40:41], v[18:19] op_sel_hi:[1,0] neg_lo:[0,1] neg_hi:[0,1]
	v_lshlrev_b32_e32 v38, 16, v39
	v_and_b32_e32 v39, 0xffff0000, v39
	s_waitcnt lgkmcnt(0)
; DI unsigned pack2(float a, float b) { f32x2_t v = {a, b}; bf16x2_t r = __builtin_convertvector(v, bf16x2_t); return __builtin_bit_cast(unsigned, r); }
; DI float bflo(unsigned u) { return __uint_as_float(u << 16); }
; DI float bfhi(unsigned u) { return __uint_as_float(u & 0xffff0000u); }
; DI int otid() { int t = threadIdx.x; asm volatile("" : "+v"(t)); return t; }
; template <bool LAST>
; DI void phase_gate(const Params& P, int layer, unsigned char* smem, int L, int G) {
;     ...
;     const int tid2 = otid();
;     const int lane2 = tid2 & 63, w2 = tid2 >> 6, r2 = lane2 & 31, h2 = lane2 >> 5, wm2 = w2 >> 2, wn2 = w2 & 3;
; #pragma unroll
;     for (int i = 0; i < 4; ++i)
; #pragma unroll
;       for (int q4 = 0; q4 < 4; ++q4) {
;         const int fl = wm2 * 128 + i * 32 + 8 * q4 + 4 * h2;
;         const int f0 = nt * 256 + fl;
;         const f32x4 gv = *(const f32x4*)(vecL + 512 + fl), bv = *(const f32x4*)(vecL + 768 + fl);
;         const float ga[4] = {gv.x, gv.y, gv.z, gv.w}, ba[4] = {bv.x, bv.y, bv.z, bv.w};
; #pragma unroll
;         for (int j = 0; j < 2; ++j) {
;           const int lrow = wn2 * 64 + j * 32 + r2;
;           const float mu = rowA[lrow], rstd = rowB[lrow];
;           uint2* sp = (uint2*)(stg + lrow * STG + fl);
;           const uint2 sv = *sp;
;           const float sa[4] = {bflo(sv.x), bfhi(sv.x), bflo(sv.y), bfhi(sv.y)};
;           float y[4];
;           const float gg[4] = {bflo(gq[i][j][2 * q4]), bfhi(gq[i][j][2 * q4]), bflo(gq[i][j][2 * q4 + 1]), bfhi(gq[i][j][2 * q4 + 1])};
; #pragma unroll
;           for (int e = 0; e < 4; ++e) y[e] = (sa[e] - mu) * rstd * ga[e] + ba[e] + gg[e];
;           if (LAST) { f32x4 o = {y[0], y[1], y[2], y[3]}; *(f32x4*)(P.out + (size_t)(mt * 256 + lrow) * 1024 + f0) = o; }
;           else { uint2 pk; pk.x = pack2(y[0], y[1]); pk.y = pack2(y[2], y[3]); *sp = pk; }
;         }
;         __builtin_amdgcn_sched_barrier(0);
;       }
;     __syncthreads();
	v_pk_mul_f32 v[16:17], v[24:25], v[16:17] op_sel_hi:[0,1]
	v_pk_fma_f32 v[16:17], v[20:21], v[16:17], v[34:35]
	v_pk_add_f32 v[20:21], v[38:39], v[18:19] op_sel_hi:[1,0] neg_lo:[0,1] neg_hi:[0,1]
	v_pk_add_f32 v[16:17], v[16:17], v[42:43]
	v_pk_mul_f32 v[20:21], v[24:25], v[20:21] op_sel_hi:[0,1]
	v_pk_fma_f32 v[20:21], v[22:23], v[20:21], v[36:37]
	v_cvt_pk_bf16_f32 v16, v16, v17
	v_pk_add_f32 v[14:15], v[20:21], v[14:15]
	s_nop 0
	v_cvt_pk_bf16_f32 v17, v14, v15
	ds_write_b64 v19, v[16:17] offset:16832
	v_add_u32_e32 v14, 0x251a0, v27
	v_add_u32_e32 v18, 0x255a0, v27
	ds_read_b64 v[24:25], v19 offset:208
	ds_read_b128 v[14:17], v14
	ds_read_b128 v[20:23], v18
	ds_read_b32 v18, v29
	ds_read_b32 v26, v30
	ds_read_b64 v[34:35], v19 offset:16848
	s_waitcnt lgkmcnt(5)
	v_lshlrev_b32_e32 v36, 16, v24
	v_and_b32_e32 v37, 0xffff0000, v24
	v_lshlrev_b32_e32 v24, 16, v25
	v_and_b32_e32 v25, 0xffff0000, v25
	s_waitcnt lgkmcnt(2)
	v_pk_add_f32 v[36:37], v[36:37], v[18:19] op_sel_hi:[1,0] neg_lo:[0,1] neg_hi:[0,1]
	v_pk_add_f32 v[24:25], v[24:25], v[18:19] op_sel_hi:[1,0] neg_lo:[0,1] neg_hi:[0,1]
	s_waitcnt lgkmcnt(1)
	v_pk_mul_f32 v[36:37], v[26:27], v[36:37] op_sel_hi:[0,1]
	v_pk_mul_f32 v[24:25], v[26:27], v[24:25] op_sel_hi:[0,1]
	v_lshlrev_b32_e32 v38, 16, v11
	v_and_b32_e32 v39, 0xffff0000, v11
	v_lshlrev_b32_e32 v40, 16, v13
	v_and_b32_e32 v41, 0xffff0000, v13
	v_pk_fma_f32 v[36:37], v[14:15], v[36:37], v[20:21]
	v_pk_fma_f32 v[24:25], v[16:17], v[24:25], v[22:23]
	v_pk_add_f32 v[36:37], v[36:37], v[38:39]
	v_pk_add_f32 v[24:25], v[24:25], v[40:41]
	v_cvt_pk_bf16_f32 v36, v36, v37
	v_cvt_pk_bf16_f32 v37, v24, v25
	ds_write_b64 v19, v[36:37] offset:208
	ds_read_b32 v18, v31
	ds_read_b32 v24, v33
	s_waitcnt lgkmcnt(3)
	v_lshlrev_b32_e32 v36, 16, v34
	v_and_b32_e32 v37, 0xffff0000, v34
	v_lshlrev_b32_e32 v38, 16, v10
	v_and_b32_e32 v39, 0xffff0000, v10
	v_lshlrev_b32_e32 v10, 16, v12
	v_and_b32_e32 v11, 0xffff0000, v12
	s_waitcnt lgkmcnt(1)
	v_pk_add_f32 v[12:13], v[36:37], v[18:19] op_sel_hi:[1,0] neg_lo:[0,1] neg_hi:[0,1]
	v_lshlrev_b32_e32 v34, 16, v35
	v_and_b32_e32 v35, 0xffff0000, v35
	s_waitcnt lgkmcnt(0)
	v_pk_mul_f32 v[12:13], v[24:25], v[12:13] op_sel_hi:[0,1]
	v_pk_fma_f32 v[12:13], v[14:15], v[12:13], v[20:21]
	v_pk_add_f32 v[14:15], v[34:35], v[18:19] op_sel_hi:[1,0] neg_lo:[0,1] neg_hi:[0,1]
	v_pk_add_f32 v[12:13], v[12:13], v[38:39]
	v_pk_mul_f32 v[14:15], v[24:25], v[14:15] op_sel_hi:[0,1]
	v_pk_fma_f32 v[14:15], v[16:17], v[14:15], v[22:23]
	v_cvt_pk_bf16_f32 v12, v12, v13
	v_pk_add_f32 v[10:11], v[14:15], v[10:11]
	s_nop 0
	v_cvt_pk_bf16_f32 v13, v10, v11
	ds_write_b64 v19, v[12:13] offset:16848
	v_add_u32_e32 v10, 0x251c0, v27
	v_add_u32_e32 v14, 0x255c0, v27
	ds_read_b64 v[20:21], v19 offset:224
	ds_read_b128 v[10:13], v10
	ds_read_b128 v[14:17], v14
	ds_read_b32 v18, v29
	ds_read_b32 v22, v30
	ds_read_b64 v[24:25], v19 offset:16864
	s_waitcnt lgkmcnt(5)
	v_lshlrev_b32_e32 v34, 16, v20
	v_and_b32_e32 v35, 0xffff0000, v20
	v_lshlrev_b32_e32 v20, 16, v21
	v_and_b32_e32 v21, 0xffff0000, v21
	s_waitcnt lgkmcnt(2)
	v_pk_add_f32 v[34:35], v[34:35], v[18:19] op_sel_hi:[1,0] neg_lo:[0,1] neg_hi:[0,1]
	v_pk_add_f32 v[20:21], v[20:21], v[18:19] op_sel_hi:[1,0] neg_lo:[0,1] neg_hi:[0,1]
	s_waitcnt lgkmcnt(1)
	v_pk_mul_f32 v[34:35], v[22:23], v[34:35] op_sel_hi:[0,1]
	v_pk_mul_f32 v[20:21], v[22:23], v[20:21] op_sel_hi:[0,1]
	v_lshlrev_b32_e32 v36, 16, v7
	v_and_b32_e32 v37, 0xffff0000, v7
	v_lshlrev_b32_e32 v38, 16, v9
	v_and_b32_e32 v39, 0xffff0000, v9
	v_pk_fma_f32 v[34:35], v[10:11], v[34:35], v[14:15]
	v_pk_fma_f32 v[20:21], v[12:13], v[20:21], v[16:17]
	v_pk_add_f32 v[34:35], v[34:35], v[36:37]
	v_pk_add_f32 v[20:21], v[20:21], v[38:39]
	v_cvt_pk_bf16_f32 v22, v34, v35
	v_cvt_pk_bf16_f32 v23, v20, v21
	ds_write_b64 v19, v[22:23] offset:224
	ds_read_b32 v18, v31
	ds_read_b32 v20, v33
	s_waitcnt lgkmcnt(3)
	v_lshlrev_b32_e32 v22, 16, v24
	v_and_b32_e32 v23, 0xffff0000, v24
	v_lshlrev_b32_e32 v34, 16, v6
	v_and_b32_e32 v35, 0xffff0000, v6
	v_lshlrev_b32_e32 v6, 16, v8
	v_and_b32_e32 v7, 0xffff0000, v8
	s_waitcnt lgkmcnt(1)
	v_pk_add_f32 v[8:9], v[22:23], v[18:19] op_sel_hi:[1,0] neg_lo:[0,1] neg_hi:[0,1]
	v_lshlrev_b32_e32 v24, 16, v25
	v_and_b32_e32 v25, 0xffff0000, v25
	s_waitcnt lgkmcnt(0)
	v_pk_mul_f32 v[8:9], v[20:21], v[8:9] op_sel_hi:[0,1]
	v_pk_fma_f32 v[8:9], v[10:11], v[8:9], v[14:15]
	v_pk_add_f32 v[10:11], v[24:25], v[18:19] op_sel_hi:[1,0] neg_lo:[0,1] neg_hi:[0,1]
	v_pk_add_f32 v[8:9], v[8:9], v[34:35]
	v_pk_mul_f32 v[10:11], v[20:21], v[10:11] op_sel_hi:[0,1]
	v_pk_fma_f32 v[10:11], v[12:13], v[10:11], v[16:17]
	v_cvt_pk_bf16_f32 v8, v8, v9
	v_pk_add_f32 v[6:7], v[10:11], v[6:7]
	s_nop 0
	v_cvt_pk_bf16_f32 v9, v6, v7
	ds_write_b64 v19, v[8:9] offset:16864
	ds_read_b128 v[6:9], v28 offset:480
	ds_read_b64 v[14:15], v19 offset:240
	ds_read_b32 v16, v29
	ds_read_b32 v18, v30
	v_add_u32_e32 v10, 0x255e0, v27
	ds_read_b128 v[10:13], v10
	s_waitcnt lgkmcnt(3)
	v_lshlrev_b32_e32 v20, 16, v14
	v_and_b32_e32 v21, 0xffff0000, v14
	v_lshlrev_b32_e32 v14, 16, v15
	v_and_b32_e32 v15, 0xffff0000, v15
	s_waitcnt lgkmcnt(2)
	v_pk_add_f32 v[20:21], v[20:21], v[16:17] op_sel_hi:[1,0] neg_lo:[0,1] neg_hi:[0,1]
	v_pk_add_f32 v[14:15], v[14:15], v[16:17] op_sel_hi:[1,0] neg_lo:[0,1] neg_hi:[0,1]
	s_waitcnt lgkmcnt(1)
	v_pk_mul_f32 v[20:21], v[18:19], v[20:21] op_sel_hi:[0,1]
	v_pk_mul_f32 v[14:15], v[18:19], v[14:15] op_sel_hi:[0,1]
	v_lshlrev_b32_e32 v22, 16, v4
	v_and_b32_e32 v23, 0xffff0000, v4
	v_lshlrev_b32_e32 v4, 16, v5
	v_and_b32_e32 v5, 0xffff0000, v5
	s_waitcnt lgkmcnt(0)
	v_pk_fma_f32 v[20:21], v[6:7], v[20:21], v[10:11]
	v_pk_fma_f32 v[14:15], v[8:9], v[14:15], v[12:13]
	v_pk_add_f32 v[20:21], v[20:21], v[22:23]
	v_pk_add_f32 v[4:5], v[14:15], v[4:5]
	v_cvt_pk_bf16_f32 v14, v20, v21
	v_cvt_pk_bf16_f32 v15, v4, v5
	ds_write_b64 v19, v[14:15] offset:240
	ds_read_b32 v4, v33
	ds_read_b64 v[14:15], v19 offset:16880
	ds_read_b32 v16, v31
	v_lshlrev_b32_e32 v22, 16, v2
	v_and_b32_e32 v23, 0xffff0000, v2
	v_lshlrev_b32_e32 v2, 16, v3
	s_waitcnt lgkmcnt(1)
	v_lshlrev_b32_e32 v20, 16, v14
	v_and_b32_e32 v21, 0xffff0000, v14
	s_waitcnt lgkmcnt(0)
	v_pk_add_f32 v[20:21], v[20:21], v[16:17] op_sel_hi:[1,0] neg_lo:[0,1] neg_hi:[0,1]
	v_lshlrev_b32_e32 v14, 16, v15
	v_and_b32_e32 v15, 0xffff0000, v15
	v_pk_mul_f32 v[20:21], v[4:5], v[20:21] op_sel_hi:[0,1]
	v_pk_fma_f32 v[6:7], v[6:7], v[20:21], v[10:11]
	v_pk_add_f32 v[10:11], v[14:15], v[16:17] op_sel_hi:[1,0] neg_lo:[0,1] neg_hi:[0,1]
	v_and_b32_e32 v3, 0xffff0000, v3
	v_pk_mul_f32 v[4:5], v[4:5], v[10:11] op_sel_hi:[0,1]
	v_pk_fma_f32 v[4:5], v[8:9], v[4:5], v[12:13]
	v_pk_add_f32 v[6:7], v[6:7], v[22:23]
	v_pk_add_f32 v[2:3], v[4:5], v[2:3]
	v_cvt_pk_bf16_f32 v4, v6, v7
	v_cvt_pk_bf16_f32 v5, v2, v3
	ds_write_b64 v19, v[4:5] offset:16880
	s_add_u32 s24, s80, s24
	s_addc_u32 s25, s81, s25
	v_lshl_add_u64 v[8:9], s[24:25], 0, v[0:1]
	v_mov_b32_e32 v0, v192
	s_waitcnt lgkmcnt(0)
	s_barrier
; DI int otid() { int t = threadIdx.x; asm volatile("" : "+v"(t)); return t; }
; DI void stg16_nt(void* p, u32x4 v) { __builtin_nontemporal_store(v, (u32x4*)p); }
; DI void stage_store_tile(const bf16_t* stg, bf16_t* tilebase) {
;   const int tid = otid();
;   const int r0 = tid >> 5, c = tid & 31;
;   const unsigned o0 = (unsigned)(r0 * 1024 + c * 8);
; #pragma unroll
;   for (int it = 0; it < 16; ++it) stg16_nt(tilebase + (o0 + (unsigned)(it * 16 * 1024)), stage_read16(stg, r0 + 16 * it, c));
; }
; template <bool LAST>
; DI void phase_gate(const Params& P, int layer, unsigned char* smem, int L, int G) {
;     ...
;   for (int t = L; t < 256 * 4; t += G) {
;     ...
;     if (!LAST) stage_store_tile(stg, xb + (size_t)mt * 256 * 1024 + nt * 256);
;     __syncthreads();
	s_add_i32 s31, s31, s74
	v_ashrrev_i32_e32 v4, 5, v0
	v_and_b32_e32 v0, 31, v0
	v_mul_lo_u32 v1, v4, s40
	v_lshl_add_u32 v12, v0, 4, v1
	v_lshlrev_b32_e32 v5, 3, v0
	ds_read2_b64 v[0:3], v12 offset1:1
	v_lshl_or_b32 v160, v4, 10, v5
	v_add_u32_e32 v4, 0x2080, v12
	ds_read2_b64 v[4:7], v4 offset1:1
	v_lshl_add_u64 v[10:11], v[160:161], 1, v[8:9]
	s_waitcnt lgkmcnt(1)
	global_store_dwordx4 v[10:11], v[0:3], off
	s_add_i32 s28, s28, s69
	s_add_i32 s29, s29, s30
	v_add_u32_e32 v0, 0x4000, v160
	v_mov_b32_e32 v1, v161
	v_lshl_add_u64 v[0:1], v[0:1], 1, v[8:9]
	s_waitcnt lgkmcnt(0)
	global_store_dwordx4 v[0:1], v[4:7], off
	v_add_u32_e32 v0, 0x4100, v12
	ds_read2_b64 v[0:3], v0 offset1:1
	v_add_u32_e32 v4, 0x8000, v160
	v_mov_b32_e32 v5, v161
	v_lshl_add_u64 v[10:11], v[4:5], 1, v[8:9]
	v_add_u32_e32 v4, 0x6180, v12
	ds_read2_b64 v[4:7], v4 offset1:1
	s_waitcnt lgkmcnt(1)
	global_store_dwordx4 v[10:11], v[0:3], off
	s_add_i32 s24, s70, s31
	s_cmpk_lt_i32 s24, 0x400
	v_add_u32_e32 v0, 0xc000, v160
	v_mov_b32_e32 v1, v161
	v_lshl_add_u64 v[0:1], v[0:1], 1, v[8:9]
	s_waitcnt lgkmcnt(0)
	global_store_dwordx4 v[0:1], v[4:7], off
	v_add_u32_e32 v0, 0x8200, v12
	ds_read2_b64 v[0:3], v0 offset1:1
	v_add_u32_e32 v4, 0x10000, v160
	v_mov_b32_e32 v5, v161
	v_lshl_add_u64 v[10:11], v[4:5], 1, v[8:9]
	v_add_u32_e32 v4, 0xa280, v12
	ds_read2_b64 v[4:7], v4 offset1:1
	s_waitcnt lgkmcnt(1)
	global_store_dwordx4 v[10:11], v[0:3], off
	s_nop 1
	v_add_u32_e32 v0, 0x14000, v160
	v_mov_b32_e32 v1, v161
	v_lshl_add_u64 v[0:1], v[0:1], 1, v[8:9]
	s_waitcnt lgkmcnt(0)
	global_store_dwordx4 v[0:1], v[4:7], off
	v_add_u32_e32 v0, 0xc300, v12
	ds_read2_b64 v[0:3], v0 offset1:1
	v_add_u32_e32 v4, 0x18000, v160
	v_mov_b32_e32 v5, v161
	v_lshl_add_u64 v[10:11], v[4:5], 1, v[8:9]
	v_add_u32_e32 v4, 0xe380, v12
	ds_read2_b64 v[4:7], v4 offset1:1
	s_waitcnt lgkmcnt(1)
	global_store_dwordx4 v[10:11], v[0:3], off
	s_nop 1
	v_add_u32_e32 v0, 0x1c000, v160
	v_mov_b32_e32 v1, v161
	v_lshl_add_u64 v[0:1], v[0:1], 1, v[8:9]
	s_waitcnt lgkmcnt(0)
	global_store_dwordx4 v[0:1], v[4:7], off
	v_add_u32_e32 v0, 0x10400, v12
	ds_read2_b64 v[0:3], v0 offset1:1
	v_add_u32_e32 v4, 0x20000, v160
	v_mov_b32_e32 v5, v161
	v_lshl_add_u64 v[10:11], v[4:5], 1, v[8:9]
	v_add_u32_e32 v4, 0x12480, v12
	ds_read2_b64 v[4:7], v4 offset1:1
	s_waitcnt lgkmcnt(1)
	global_store_dwordx4 v[10:11], v[0:3], off
	s_nop 1
	v_add_u32_e32 v0, 0x24000, v160
	v_mov_b32_e32 v1, v161
	v_lshl_add_u64 v[0:1], v[0:1], 1, v[8:9]
	s_waitcnt lgkmcnt(0)
	global_store_dwordx4 v[0:1], v[4:7], off
	v_add_u32_e32 v0, 0x14500, v12
	ds_read2_b64 v[0:3], v0 offset1:1
	v_add_u32_e32 v4, 0x28000, v160
	v_mov_b32_e32 v5, v161
	v_lshl_add_u64 v[10:11], v[4:5], 1, v[8:9]
	v_add_u32_e32 v4, 0x16580, v12
	ds_read2_b64 v[4:7], v4 offset1:1
	s_waitcnt lgkmcnt(1)
	global_store_dwordx4 v[10:11], v[0:3], off
	s_nop 1
	v_add_u32_e32 v0, 0x2c000, v160
	v_mov_b32_e32 v1, v161
	v_lshl_add_u64 v[0:1], v[0:1], 1, v[8:9]
	s_waitcnt lgkmcnt(0)
	global_store_dwordx4 v[0:1], v[4:7], off
	v_add_u32_e32 v0, 0x18600, v12
	ds_read2_b64 v[0:3], v0 offset1:1
	v_add_u32_e32 v4, 0x30000, v160
	v_mov_b32_e32 v5, v161
	v_lshl_add_u64 v[10:11], v[4:5], 1, v[8:9]
	v_add_u32_e32 v4, 0x1a680, v12
	ds_read2_b64 v[4:7], v4 offset1:1
	s_waitcnt lgkmcnt(1)
	global_store_dwordx4 v[10:11], v[0:3], off
	v_add_u32_e32 v10, 0x38000, v160
	v_mov_b32_e32 v11, v161
	v_add_u32_e32 v0, 0x34000, v160
	v_mov_b32_e32 v1, v161
	v_lshl_add_u64 v[0:1], v[0:1], 1, v[8:9]
	s_waitcnt lgkmcnt(0)
	global_store_dwordx4 v[0:1], v[4:7], off
	v_add_u32_e32 v0, 0x1c700, v12
	ds_read2_b64 v[0:3], v0 offset1:1
	v_add_u32_e32 v4, 0x1e780, v12
	ds_read2_b64 v[4:7], v4 offset1:1
	v_lshl_add_u64 v[10:11], v[10:11], 1, v[8:9]
	v_add_u32_e32 v160, 0x3c000, v160
	s_waitcnt lgkmcnt(1)
	global_store_dwordx4 v[10:11], v[0:3], off
	s_nop 1
	v_lshl_add_u64 v[0:1], v[160:161], 1, v[8:9]
	s_waitcnt lgkmcnt(0)
	global_store_dwordx4 v[0:1], v[4:7], off
	s_barrier
	s_cbranch_scc0 .LBB0_929

; DI void stg16_nt(void* p, u32x4 v) { __builtin_nontemporal_store(v, (u32x4*)p); }
; DI void epi_seg(const f32x16 (&acc)[4][2], const Seg& sg0, const Seg& sg1, int m0, int n0, const float* rs, const float2* cs64, const float2* cs32, bf16_t* stg) {
;     ...
; #pragma unroll
;   for (int it = 0; it < 16; ++it) {
;     const int idx = tid + NTHR * it, rr = idx >> 5, c = idx & 31;
;     const Seg& fs = (c >> 4) ? sg1 : sg0;
;     const int lcc = n0 + c * 8 - fs.cbase;
;     if (fs.kind != K_NONE && lcc < fs.nvalid) {
;       const int row = m0 + rr;
;       size_t off;
;       if (fs.kind == K_KC2) { const int b = row >> 9, n = (row >> 2) & 127, g = row & 3; off = ((size_t)((b * 4 + g) * 128 + n)) * 64 + lcc; }
;       else off = (size_t)row * fs.ld + lcc;
;       stg16_nt(fs.dst + off, stage_read16(stg, rr, c));
;     }
;   }
;   __syncthreads();
.LBB0_1052:
	s_or_b64 exec, exec, s[2:3]
	v_mov_b32_e32 v161, s62
	v_mov_b32_e32 v162, s58
	v_cmp_gt_u32_e32 vcc, 16, v195
	v_lshl_or_b32 v160, v195, 3, s37
	s_waitcnt lgkmcnt(0)
	v_cndmask_b32_e32 v161, v161, v162, vcc
	v_sub_u32_e32 v164, v160, v161
	v_mov_b32_e32 v160, s59
	v_mov_b32_e32 v161, s60
	v_cndmask_b32_e32 v160, v160, v161, vcc
	v_cmp_ne_u32_e64 s[0:1], 7, v160
	v_mov_b32_e32 v160, s61
	v_cndmask_b32_e32 v160, 2.0, v160, vcc
	v_cmp_lt_i32_e64 s[2:3], v164, v160
	s_and_b64 s[2:3], s[0:1], s[2:3]
	s_barrier
	s_and_saveexec_b64 s[0:1], s[2:3]
	s_cbranch_execz .LBB0_1054
	v_ashrrev_i32_e32 v161, 5, v194
	v_mov_b32_e32 v163, s38
	v_mov_b32_e32 v165, s36
	v_add_u32_e32 v162, s39, v161
	v_cndmask_b32_e32 v176, v163, v165, vcc
	v_mad_i64_i32 v[166:167], s[2:3], v176, v162, 0
	v_mov_b32_e32 v162, s41
	v_mov_b32_e32 v163, s35
	v_cndmask_b32_e32 v163, v162, v163, vcc
	v_mov_b32_e32 v162, s40
	v_mov_b32_e32 v168, s34
	v_ashrrev_i32_e32 v165, 31, v164
	v_cndmask_b32_e32 v162, v162, v168, vcc
	v_lshlrev_b32_e32 v160, 4, v195
	v_lshl_add_u64 v[166:167], v[166:167], 1, v[162:163]
	v_lshlrev_b64 v[164:165], 1, v[164:165]
	v_lshl_add_u64 v[174:175], v[166:167], 0, v[164:165]
	v_mad_u64_u32 v[166:167], s[2:3], v161, s56, v[160:161]
	ds_read2_b64 v[166:169], v166 offset1:1
	v_add_u32_e32 v161, 0x200, v194
	v_ashrrev_i32_e32 v161, 5, v161
	v_mad_u64_u32 v[170:171], s[2:3], v161, s56, v[160:161]
	ds_read2_b64 v[170:173], v170 offset1:1
	v_add_u32_e32 v161, s39, v161
	s_waitcnt lgkmcnt(1)
	global_store_dwordx4 v[174:175], v[166:169], off
	s_nop 1
	v_mad_i64_i32 v[166:167], s[2:3], v176, v161, 0
	v_lshl_add_u64 v[166:167], v[166:167], 1, v[162:163]
	v_add_u32_e32 v161, 0x400, v194
	v_lshl_add_u64 v[166:167], v[166:167], 0, v[164:165]
	v_ashrrev_i32_e32 v161, 5, v161
	s_waitcnt lgkmcnt(0)
	global_store_dwordx4 v[166:167], v[170:173], off
	v_add_u32_e32 v166, s39, v161
	v_mad_i64_i32 v[166:167], s[2:3], v176, v166, 0
	v_lshl_add_u64 v[166:167], v[166:167], 1, v[162:163]
	v_lshl_add_u64 v[174:175], v[166:167], 0, v[164:165]
	v_mad_u64_u32 v[166:167], s[2:3], v161, s56, v[160:161]
	ds_read2_b64 v[166:169], v166 offset1:1
	v_add_u32_e32 v161, 0x600, v194
	v_ashrrev_i32_e32 v161, 5, v161
	v_mad_u64_u32 v[170:171], s[2:3], v161, s56, v[160:161]
	ds_read2_b64 v[170:173], v170 offset1:1
	v_add_u32_e32 v161, s39, v161
	s_waitcnt lgkmcnt(1)
	global_store_dwordx4 v[174:175], v[166:169], off
	s_nop 1
	v_mad_i64_i32 v[166:167], s[2:3], v176, v161, 0
	v_lshl_add_u64 v[166:167], v[166:167], 1, v[162:163]
	v_add_u32_e32 v161, 0x800, v194
	v_lshl_add_u64 v[166:167], v[166:167], 0, v[164:165]
	v_ashrrev_i32_e32 v161, 5, v161
	s_waitcnt lgkmcnt(0)
	global_store_dwordx4 v[166:167], v[170:173], off
	v_add_u32_e32 v166, s39, v161
	v_mad_i64_i32 v[166:167], s[2:3], v176, v166, 0
	v_lshl_add_u64 v[166:167], v[166:167], 1, v[162:163]
	v_lshl_add_u64 v[174:175], v[166:167], 0, v[164:165]
	v_mad_u64_u32 v[166:167], s[2:3], v161, s56, v[160:161]
	ds_read2_b64 v[166:169], v166 offset1:1
	v_add_u32_e32 v161, 0xa00, v194
	v_ashrrev_i32_e32 v161, 5, v161
	v_mad_u64_u32 v[170:171], s[2:3], v161, s56, v[160:161]
	ds_read2_b64 v[170:173], v170 offset1:1
	v_add_u32_e32 v161, s39, v161
	s_waitcnt lgkmcnt(1)
	global_store_dwordx4 v[174:175], v[166:169], off
	s_nop 1
	v_mad_i64_i32 v[166:167], s[2:3], v176, v161, 0
	v_lshl_add_u64 v[166:167], v[166:167], 1, v[162:163]
	v_add_u32_e32 v161, 0xc00, v194
	v_lshl_add_u64 v[166:167], v[166:167], 0, v[164:165]
	v_ashrrev_i32_e32 v161, 5, v161
	s_waitcnt lgkmcnt(0)
	global_store_dwordx4 v[166:167], v[170:173], off
	v_add_u32_e32 v166, s39, v161
	v_mad_i64_i32 v[166:167], s[2:3], v176, v166, 0
	v_lshl_add_u64 v[166:167], v[166:167], 1, v[162:163]
	v_lshl_add_u64 v[174:175], v[166:167], 0, v[164:165]
	v_mad_u64_u32 v[166:167], s[2:3], v161, s56, v[160:161]
	ds_read2_b64 v[166:169], v166 offset1:1
	v_add_u32_e32 v161, 0xe00, v194
	v_ashrrev_i32_e32 v161, 5, v161
	v_mad_u64_u32 v[170:171], s[2:3], v161, s56, v[160:161]
	ds_read2_b64 v[170:173], v170 offset1:1
	v_add_u32_e32 v161, s39, v161
	s_waitcnt lgkmcnt(1)
; DI void stg16_nt(void* p, u32x4 v) { __builtin_nontemporal_store(v, (u32x4*)p); }
; DI void epi_seg(const f32x16 (&acc)[4][2], const Seg& sg0, const Seg& sg1, int m0, int n0, const float* rs, const float2* cs64, const float2* cs32, bf16_t* stg) {
;     ...
; #pragma unroll
;   for (int it = 0; it < 16; ++it) {
;     const int idx = tid + NTHR * it, rr = idx >> 5, c = idx & 31;
;     const Seg& fs = (c >> 4) ? sg1 : sg0;
;     const int lcc = n0 + c * 8 - fs.cbase;
;     if (fs.kind != K_NONE && lcc < fs.nvalid) {
;       const int row = m0 + rr;
;       size_t off;
;       if (fs.kind == K_KC2) { const int b = row >> 9, n = (row >> 2) & 127, g = row & 3; off = ((size_t)((b * 4 + g) * 128 + n)) * 64 + lcc; }
;       else off = (size_t)row * fs.ld + lcc;
;       stg16_nt(fs.dst + off, stage_read16(stg, rr, c));
;     }
;   }
;   __syncthreads();
	global_store_dwordx4 v[174:175], v[166:169], off
	s_nop 1
	v_mad_i64_i32 v[166:167], s[2:3], v176, v161, 0
	v_lshl_add_u64 v[166:167], v[166:167], 1, v[162:163]
	v_add_u32_e32 v161, 0x1000, v194
	v_lshl_add_u64 v[166:167], v[166:167], 0, v[164:165]
	v_ashrrev_i32_e32 v161, 5, v161
	s_waitcnt lgkmcnt(0)
	global_store_dwordx4 v[166:167], v[170:173], off
	v_add_u32_e32 v166, s39, v161
	v_mad_i64_i32 v[166:167], s[2:3], v176, v166, 0
	v_lshl_add_u64 v[166:167], v[166:167], 1, v[162:163]
	v_lshl_add_u64 v[174:175], v[166:167], 0, v[164:165]
	v_mad_u64_u32 v[166:167], s[2:3], v161, s56, v[160:161]
	ds_read2_b64 v[166:169], v166 offset1:1
	v_add_u32_e32 v161, 0x1200, v194
	v_ashrrev_i32_e32 v161, 5, v161
	v_mad_u64_u32 v[170:171], s[2:3], v161, s56, v[160:161]
	ds_read2_b64 v[170:173], v170 offset1:1
	v_add_u32_e32 v161, s39, v161
	s_waitcnt lgkmcnt(1)
	global_store_dwordx4 v[174:175], v[166:169], off
	s_nop 1
	v_mad_i64_i32 v[166:167], s[2:3], v176, v161, 0
	v_lshl_add_u64 v[166:167], v[166:167], 1, v[162:163]
	v_add_u32_e32 v161, 0x1400, v194
	v_lshl_add_u64 v[166:167], v[166:167], 0, v[164:165]
	v_ashrrev_i32_e32 v161, 5, v161
	s_waitcnt lgkmcnt(0)
	global_store_dwordx4 v[166:167], v[170:173], off
	v_add_u32_e32 v166, s39, v161
	v_mad_i64_i32 v[166:167], s[2:3], v176, v166, 0
	v_lshl_add_u64 v[166:167], v[166:167], 1, v[162:163]
	v_lshl_add_u64 v[174:175], v[166:167], 0, v[164:165]
	v_mad_u64_u32 v[166:167], s[2:3], v161, s56, v[160:161]
	ds_read2_b64 v[166:169], v166 offset1:1
	v_add_u32_e32 v161, 0x1600, v194
	v_ashrrev_i32_e32 v161, 5, v161
	v_mad_u64_u32 v[170:171], s[2:3], v161, s56, v[160:161]
	ds_read2_b64 v[170:173], v170 offset1:1
	v_add_u32_e32 v161, s39, v161
	s_waitcnt lgkmcnt(1)
	global_store_dwordx4 v[174:175], v[166:169], off
	s_nop 1
	v_mad_i64_i32 v[166:167], s[2:3], v176, v161, 0
	v_lshl_add_u64 v[166:167], v[166:167], 1, v[162:163]
	v_add_u32_e32 v161, 0x1800, v194
	v_lshl_add_u64 v[166:167], v[166:167], 0, v[164:165]
	v_ashrrev_i32_e32 v161, 5, v161
	s_waitcnt lgkmcnt(0)
	global_store_dwordx4 v[166:167], v[170:173], off
	v_add_u32_e32 v166, s39, v161
	v_mad_i64_i32 v[166:167], s[2:3], v176, v166, 0
	v_lshl_add_u64 v[166:167], v[166:167], 1, v[162:163]
	v_lshl_add_u64 v[174:175], v[166:167], 0, v[164:165]
	v_mad_u64_u32 v[166:167], s[2:3], v161, s56, v[160:161]
	ds_read2_b64 v[166:169], v166 offset1:1
	v_add_u32_e32 v161, 0x1a00, v194
	v_ashrrev_i32_e32 v161, 5, v161
	v_mad_u64_u32 v[170:171], s[2:3], v161, s56, v[160:161]
	ds_read2_b64 v[170:173], v170 offset1:1
	v_add_u32_e32 v161, s39, v161
	s_waitcnt lgkmcnt(1)
	global_store_dwordx4 v[174:175], v[166:169], off
	s_nop 1
	v_mad_i64_i32 v[166:167], s[2:3], v176, v161, 0
	v_lshl_add_u64 v[166:167], v[166:167], 1, v[162:163]
	v_add_u32_e32 v161, 0x1c00, v194
	v_lshl_add_u64 v[166:167], v[166:167], 0, v[164:165]
	v_ashrrev_i32_e32 v161, 5, v161
	s_waitcnt lgkmcnt(0)
	global_store_dwordx4 v[166:167], v[170:173], off
	v_add_u32_e32 v166, s39, v161
	v_mad_i64_i32 v[166:167], s[2:3], v176, v166, 0
	v_lshl_add_u64 v[166:167], v[166:167], 1, v[162:163]
	v_lshl_add_u64 v[174:175], v[166:167], 0, v[164:165]
	v_mad_u64_u32 v[166:167], s[2:3], v161, s56, v[160:161]
	v_add_u32_e32 v161, 0x1e00, v194
	v_ashrrev_i32_e32 v177, 5, v161
	v_mad_u64_u32 v[160:161], s[2:3], v177, s56, v[160:161]
	ds_read2_b64 v[166:169], v166 offset1:1
	ds_read2_b64 v[170:173], v160 offset1:1
	v_add_u32_e32 v160, s39, v177
	v_mad_i64_i32 v[160:161], s[2:3], v176, v160, 0
	v_lshl_add_u64 v[160:161], v[160:161], 1, v[162:163]
	v_lshl_add_u64 v[160:161], v[160:161], 0, v[164:165]
	s_waitcnt lgkmcnt(1)
	global_store_dwordx4 v[174:175], v[166:169], off
	s_waitcnt lgkmcnt(0)
	global_store_dwordx4 v[160:161], v[170:173], off

; DI unsigned pack2(float a, float b) { f32x2_t v = {a, b}; bf16x2_t r = __builtin_convertvector(v, bf16x2_t); return __builtin_bit_cast(unsigned, r); }
; DI void stg16_nt(void* p, u32x4 v) { __builtin_nontemporal_store(v, (u32x4*)p); }
; DI void epi_seg(const f32x16 (&acc)[4][2], const Seg& sg0, const Seg& sg1, int m0, int n0, const float* rs, const float2* cs64, const float2* cs32, bf16_t* stg) {
;     ...
;   if (kind0 == K_VT) {
; #pragma unroll
;     for (int i = 0; i < 4; ++i)
; #pragma unroll
;       for (int q4 = 0; q4 < 4; ++q4) {
;         const int t0l = wm * 128 + i * 32 + 8 * q4 + 4 * h;
;         float s0 = 1.f, s1 = 1.f, s2 = 1.f, s3 = 1.f;
;         if (rs) { s0 = rs[t0l]; s1 = rs[t0l + 1]; s2 = rs[t0l + 2]; s3 = rs[t0l + 3]; }
; #pragma unroll
;         for (int j = 0; j < 2; ++j)
;           *(uint2*)(stg + (wn * 64 + j * 32 + r) * STG + t0l) =
;               make_uint2(pack2(acc[i][j][4 * q4] * s0, acc[i][j][4 * q4 + 1] * s1), pack2(acc[i][j][4 * q4 + 2] * s2, acc[i][j][4 * q4 + 3] * s3));
;       }
;     __syncthreads();
;     const int b = m0 >> 11, s0 = m0 & (SEQ - 1);
;     ...
;       const int lc = n0 + rr - sg0.cbase, g = lc >> 6, d = lc & 63;
;       stg16_nt(sg0.dst + ((size_t)((b * sg0.G + g) * 64 + d)) * SEQ + s0 + c * 8, stage_read16(stg, rr, c));
.LBB0_1055:
	v_and_b32_e32 v161, 0xffffff00, v194
	v_lshl_or_b32 v160, v197, 6, v195
	v_lshl_or_b32 v161, v196, 3, v161
	v_cvt_pk_bf16_f32 v0, v0, v1
	v_cvt_pk_bf16_f32 v1, v2, v3
	v_mad_u32_u24 v160, v160, s56, v161
	v_cvt_pk_bf16_f32 v4, v4, v5
	v_cvt_pk_bf16_f32 v5, v6, v7
	v_cvt_pk_bf16_f32 v2, v112, v113
	v_cvt_pk_bf16_f32 v3, v114, v115
	ds_write2_b64 v160, v[0:1], v[4:5] offset1:2
	v_cvt_pk_bf16_f32 v0, v116, v117
	v_cvt_pk_bf16_f32 v1, v118, v119
	v_add_u32_e32 v6, 0x4000, v160
	ds_write2_b64 v6, v[2:3], v[0:1] offset0:32 offset1:34
	v_cvt_pk_bf16_f32 v0, v8, v9
	v_cvt_pk_bf16_f32 v1, v10, v11
	v_cvt_pk_bf16_f32 v4, v12, v13
	v_cvt_pk_bf16_f32 v5, v14, v15
	v_cvt_pk_bf16_f32 v2, v120, v121
	v_cvt_pk_bf16_f32 v3, v122, v123
	ds_write2_b64 v160, v[0:1], v[4:5] offset0:4 offset1:6
	v_cvt_pk_bf16_f32 v0, v124, v125
	v_cvt_pk_bf16_f32 v1, v126, v127
	ds_write2_b64 v6, v[2:3], v[0:1] offset0:36 offset1:38
	v_cvt_pk_bf16_f32 v0, v48, v49
	v_cvt_pk_bf16_f32 v1, v50, v51
	v_cvt_pk_bf16_f32 v4, v52, v53
	v_cvt_pk_bf16_f32 v5, v54, v55
	v_cvt_pk_bf16_f32 v2, v96, v97
	v_cvt_pk_bf16_f32 v3, v98, v99
	ds_write2_b64 v160, v[0:1], v[4:5] offset0:8 offset1:10
	v_cvt_pk_bf16_f32 v0, v100, v101
	v_cvt_pk_bf16_f32 v1, v102, v103
	ds_write2_b64 v6, v[2:3], v[0:1] offset0:40 offset1:42
	v_cvt_pk_bf16_f32 v0, v56, v57
	v_cvt_pk_bf16_f32 v1, v58, v59
	v_cvt_pk_bf16_f32 v4, v60, v61
	v_cvt_pk_bf16_f32 v5, v62, v63
	v_cvt_pk_bf16_f32 v2, v104, v105
	v_cvt_pk_bf16_f32 v3, v106, v107
	ds_write2_b64 v160, v[0:1], v[4:5] offset0:12 offset1:14
	v_cvt_pk_bf16_f32 v0, v108, v109
	v_cvt_pk_bf16_f32 v1, v110, v111
	ds_write2_b64 v6, v[2:3], v[0:1] offset0:44 offset1:46
	v_cvt_pk_bf16_f32 v0, v32, v33
	v_cvt_pk_bf16_f32 v1, v34, v35
	v_cvt_pk_bf16_f32 v4, v36, v37
	v_cvt_pk_bf16_f32 v5, v38, v39
	v_cvt_pk_bf16_f32 v2, v80, v81
	v_cvt_pk_bf16_f32 v3, v82, v83
	ds_write2_b64 v160, v[0:1], v[4:5] offset0:16 offset1:18
	v_cvt_pk_bf16_f32 v0, v84, v85
	v_cvt_pk_bf16_f32 v1, v86, v87
	ds_write2_b64 v6, v[2:3], v[0:1] offset0:48 offset1:50
	v_cvt_pk_bf16_f32 v0, v40, v41
	v_cvt_pk_bf16_f32 v1, v42, v43
	v_cvt_pk_bf16_f32 v4, v44, v45
	v_cvt_pk_bf16_f32 v5, v46, v47
	v_cvt_pk_bf16_f32 v2, v88, v89
	v_cvt_pk_bf16_f32 v3, v90, v91
	ds_write2_b64 v160, v[0:1], v[4:5] offset0:20 offset1:22
	v_cvt_pk_bf16_f32 v0, v92, v93
	v_cvt_pk_bf16_f32 v1, v94, v95
	ds_write2_b64 v6, v[2:3], v[0:1] offset0:52 offset1:54
	v_cvt_pk_bf16_f32 v0, v16, v17
	v_cvt_pk_bf16_f32 v1, v18, v19
	v_cvt_pk_bf16_f32 v4, v20, v21
	v_cvt_pk_bf16_f32 v5, v22, v23
	v_cvt_pk_bf16_f32 v2, v64, v65
	v_cvt_pk_bf16_f32 v3, v66, v67
	ds_write2_b64 v160, v[0:1], v[4:5] offset0:24 offset1:26
	v_cvt_pk_bf16_f32 v0, v68, v69
	v_cvt_pk_bf16_f32 v1, v70, v71
	ds_write2_b64 v6, v[2:3], v[0:1] offset0:56 offset1:58
	v_cvt_pk_bf16_f32 v0, v24, v25
	v_cvt_pk_bf16_f32 v1, v26, v27
	v_cvt_pk_bf16_f32 v4, v28, v29
	v_cvt_pk_bf16_f32 v5, v30, v31
	s_lshl_b32 s0, s30, 5
	v_cvt_pk_bf16_f32 v2, v72, v73
	v_cvt_pk_bf16_f32 v3, v74, v75
	ds_write2_b64 v160, v[0:1], v[4:5] offset0:28 offset1:30
	v_cvt_pk_bf16_f32 v0, v76, v77
	v_cvt_pk_bf16_f32 v1, v78, v79
	s_and_b32 s0, s0, 0xffffff00
	s_sub_i32 s2, s37, s58
	ds_write2_b64 v6, v[2:3], v[0:1] offset0:60 offset1:62
	v_ashrrev_i32_e32 v2, 5, v194
	s_add_i32 s0, s2, s0
	v_add_u32_e32 v0, s0, v2
	v_ashrrev_i32_e32 v1, 31, v0
	s_and_b32 s1, s39, 0x700
	v_lshlrev_b64 v[0:1], 12, v[0:1]
	v_lshl_add_u64 v[0:1], s[34:35], 0, v[0:1]
	s_lshl_b32 s30, s1, 1
	v_lshlrev_b32_e32 v184, 4, v195
	v_lshl_add_u64 v[0:1], v[0:1], 0, s[30:31]
	v_lshl_add_u64 v[8:9], v[0:1], 0, v[184:185]
	v_mad_u64_u32 v[0:1], s[2:3], v2, s56, v[184:185]
	s_waitcnt lgkmcnt(0)
	s_barrier
; DI void stg16_nt(void* p, u32x4 v) { __builtin_nontemporal_store(v, (u32x4*)p); }
; DI void epi_seg(const f32x16 (&acc)[4][2], const Seg& sg0, const Seg& sg1, int m0, int n0, const float* rs, const float2* cs64, const float2* cs32, bf16_t* stg) {
;     ...
; #pragma unroll
;     for (int it = 0; it < 16; ++it) {
;       const int idx = tid + NTHR * it, rr = idx >> 5, c = idx & 31;
;       const int lc = n0 + rr - sg0.cbase, g = lc >> 6, d = lc & 63;
;       stg16_nt(sg0.dst + ((size_t)((b * sg0.G + g) * 64 + d)) * SEQ + s0 + c * 8, stage_read16(stg, rr, c));
;     }
;     __syncthreads();
;     return;
	ds_read2_b64 v[0:3], v0 offset1:1
	v_add_u32_e32 v4, 0x200, v194
	v_ashrrev_i32_e32 v10, 5, v4
	v_mad_u64_u32 v[4:5], s[2:3], v10, s56, v[184:185]
	ds_read2_b64 v[4:7], v4 offset1:1
	s_waitcnt lgkmcnt(1)
	global_store_dwordx4 v[8:9], v[0:3], off
	s_nop 1
	v_add_u32_e32 v0, s0, v10
	v_ashrrev_i32_e32 v1, 31, v0
	v_lshlrev_b64 v[0:1], 12, v[0:1]
	v_lshl_add_u64 v[0:1], s[34:35], 0, v[0:1]
	v_lshl_add_u64 v[0:1], v[0:1], 0, s[30:31]
	v_lshl_add_u64 v[0:1], v[0:1], 0, v[184:185]
	s_waitcnt lgkmcnt(0)
	global_store_dwordx4 v[0:1], v[4:7], off
	v_add_u32_e32 v0, 0x400, v194
	v_ashrrev_i32_e32 v2, 5, v0
	v_add_u32_e32 v0, s0, v2
	v_ashrrev_i32_e32 v1, 31, v0
	v_lshlrev_b64 v[0:1], 12, v[0:1]
	v_lshl_add_u64 v[0:1], s[34:35], 0, v[0:1]
	v_lshl_add_u64 v[0:1], v[0:1], 0, s[30:31]
	v_lshl_add_u64 v[8:9], v[0:1], 0, v[184:185]
	v_mad_u64_u32 v[0:1], s[2:3], v2, s56, v[184:185]
	ds_read2_b64 v[0:3], v0 offset1:1
	v_add_u32_e32 v4, 0x600, v194
	v_ashrrev_i32_e32 v10, 5, v4
	v_mad_u64_u32 v[4:5], s[2:3], v10, s56, v[184:185]
	ds_read2_b64 v[4:7], v4 offset1:1
	s_waitcnt lgkmcnt(1)
	global_store_dwordx4 v[8:9], v[0:3], off
	s_nop 1
	v_add_u32_e32 v0, s0, v10
	v_ashrrev_i32_e32 v1, 31, v0
	v_lshlrev_b64 v[0:1], 12, v[0:1]
	v_lshl_add_u64 v[0:1], s[34:35], 0, v[0:1]
	v_lshl_add_u64 v[0:1], v[0:1], 0, s[30:31]
	v_lshl_add_u64 v[0:1], v[0:1], 0, v[184:185]
	s_waitcnt lgkmcnt(0)
	global_store_dwordx4 v[0:1], v[4:7], off
	v_add_u32_e32 v0, 0x800, v194
	v_ashrrev_i32_e32 v2, 5, v0
	v_add_u32_e32 v0, s0, v2
	v_ashrrev_i32_e32 v1, 31, v0
	v_lshlrev_b64 v[0:1], 12, v[0:1]
	v_lshl_add_u64 v[0:1], s[34:35], 0, v[0:1]
	v_lshl_add_u64 v[0:1], v[0:1], 0, s[30:31]
	v_lshl_add_u64 v[8:9], v[0:1], 0, v[184:185]
	v_mad_u64_u32 v[0:1], s[2:3], v2, s56, v[184:185]
	ds_read2_b64 v[0:3], v0 offset1:1
	v_add_u32_e32 v4, 0xa00, v194
	v_ashrrev_i32_e32 v10, 5, v4
	v_mad_u64_u32 v[4:5], s[2:3], v10, s56, v[184:185]
	ds_read2_b64 v[4:7], v4 offset1:1
	s_waitcnt lgkmcnt(1)
	global_store_dwordx4 v[8:9], v[0:3], off
	s_nop 1
	v_add_u32_e32 v0, s0, v10
	v_ashrrev_i32_e32 v1, 31, v0
	v_lshlrev_b64 v[0:1], 12, v[0:1]
	v_lshl_add_u64 v[0:1], s[34:35], 0, v[0:1]
	v_lshl_add_u64 v[0:1], v[0:1], 0, s[30:31]
	v_lshl_add_u64 v[0:1], v[0:1], 0, v[184:185]
	s_waitcnt lgkmcnt(0)
	global_store_dwordx4 v[0:1], v[4:7], off
	v_add_u32_e32 v0, 0xc00, v194
	v_ashrrev_i32_e32 v2, 5, v0
	v_add_u32_e32 v0, s0, v2
	v_ashrrev_i32_e32 v1, 31, v0
	v_lshlrev_b64 v[0:1], 12, v[0:1]
	v_lshl_add_u64 v[0:1], s[34:35], 0, v[0:1]
	v_lshl_add_u64 v[0:1], v[0:1], 0, s[30:31]
	v_lshl_add_u64 v[8:9], v[0:1], 0, v[184:185]
	v_mad_u64_u32 v[0:1], s[2:3], v2, s56, v[184:185]
	ds_read2_b64 v[0:3], v0 offset1:1
	v_add_u32_e32 v4, 0xe00, v194
	v_ashrrev_i32_e32 v10, 5, v4
	v_mad_u64_u32 v[4:5], s[2:3], v10, s56, v[184:185]
	ds_read2_b64 v[4:7], v4 offset1:1
	s_waitcnt lgkmcnt(1)
	global_store_dwordx4 v[8:9], v[0:3], off
	s_nop 1
	v_add_u32_e32 v0, s0, v10
	v_ashrrev_i32_e32 v1, 31, v0
	v_lshlrev_b64 v[0:1], 12, v[0:1]
	v_lshl_add_u64 v[0:1], s[34:35], 0, v[0:1]
	v_lshl_add_u64 v[0:1], v[0:1], 0, s[30:31]
	v_lshl_add_u64 v[0:1], v[0:1], 0, v[184:185]
	s_waitcnt lgkmcnt(0)
	global_store_dwordx4 v[0:1], v[4:7], off
	v_add_u32_e32 v0, 0x1000, v194
	v_ashrrev_i32_e32 v2, 5, v0
	v_add_u32_e32 v0, s0, v2
	v_ashrrev_i32_e32 v1, 31, v0
	v_lshlrev_b64 v[0:1], 12, v[0:1]
	v_lshl_add_u64 v[0:1], s[34:35], 0, v[0:1]
	v_lshl_add_u64 v[0:1], v[0:1], 0, s[30:31]
	v_lshl_add_u64 v[8:9], v[0:1], 0, v[184:185]
	v_mad_u64_u32 v[0:1], s[2:3], v2, s56, v[184:185]
	ds_read2_b64 v[0:3], v0 offset1:1
	v_add_u32_e32 v4, 0x1200, v194
	v_ashrrev_i32_e32 v10, 5, v4
	v_mad_u64_u32 v[4:5], s[2:3], v10, s56, v[184:185]
	ds_read2_b64 v[4:7], v4 offset1:1
	s_waitcnt lgkmcnt(1)
	global_store_dwordx4 v[8:9], v[0:3], off
	s_nop 1
	v_add_u32_e32 v0, s0, v10
	v_ashrrev_i32_e32 v1, 31, v0
	v_lshlrev_b64 v[0:1], 12, v[0:1]
	v_lshl_add_u64 v[0:1], s[34:35], 0, v[0:1]
	v_lshl_add_u64 v[0:1], v[0:1], 0, s[30:31]
	v_lshl_add_u64 v[0:1], v[0:1], 0, v[184:185]
	s_waitcnt lgkmcnt(0)
	global_store_dwordx4 v[0:1], v[4:7], off
	v_add_u32_e32 v0, 0x1400, v194
	v_ashrrev_i32_e32 v2, 5, v0
	v_add_u32_e32 v0, s0, v2
	v_ashrrev_i32_e32 v1, 31, v0
	v_lshlrev_b64 v[0:1], 12, v[0:1]
	v_lshl_add_u64 v[0:1], s[34:35], 0, v[0:1]
	v_lshl_add_u64 v[0:1], v[0:1], 0, s[30:31]
	v_lshl_add_u64 v[8:9], v[0:1], 0, v[184:185]
	v_mad_u64_u32 v[0:1], s[2:3], v2, s56, v[184:185]
	ds_read2_b64 v[0:3], v0 offset1:1
	v_add_u32_e32 v4, 0x1600, v194
	v_ashrrev_i32_e32 v10, 5, v4
	v_mad_u64_u32 v[4:5], s[2:3], v10, s56, v[184:185]
	ds_read2_b64 v[4:7], v4 offset1:1
	s_waitcnt lgkmcnt(1)
	global_store_dwordx4 v[8:9], v[0:3], off
	s_nop 1
	v_add_u32_e32 v0, s0, v10
	v_ashrrev_i32_e32 v1, 31, v0
	v_lshlrev_b64 v[0:1], 12, v[0:1]
	v_lshl_add_u64 v[0:1], s[34:35], 0, v[0:1]
	v_lshl_add_u64 v[0:1], v[0:1], 0, s[30:31]
	v_lshl_add_u64 v[0:1], v[0:1], 0, v[184:185]
	s_waitcnt lgkmcnt(0)
	global_store_dwordx4 v[0:1], v[4:7], off
	v_add_u32_e32 v0, 0x1800, v194
	v_ashrrev_i32_e32 v2, 5, v0
	v_add_u32_e32 v0, s0, v2
	v_ashrrev_i32_e32 v1, 31, v0
	v_lshlrev_b64 v[0:1], 12, v[0:1]
	v_lshl_add_u64 v[0:1], s[34:35], 0, v[0:1]
	v_lshl_add_u64 v[0:1], v[0:1], 0, s[30:31]
	v_lshl_add_u64 v[8:9], v[0:1], 0, v[184:185]
	v_mad_u64_u32 v[0:1], s[2:3], v2, s56, v[184:185]
	ds_read2_b64 v[0:3], v0 offset1:1
	v_add_u32_e32 v4, 0x1a00, v194
	v_ashrrev_i32_e32 v10, 5, v4
	v_mad_u64_u32 v[4:5], s[2:3], v10, s56, v[184:185]
	ds_read2_b64 v[4:7], v4 offset1:1
	s_waitcnt lgkmcnt(1)
	global_store_dwordx4 v[8:9], v[0:3], off
	s_nop 1
	v_add_u32_e32 v0, s0, v10
	v_ashrrev_i32_e32 v1, 31, v0
	v_lshlrev_b64 v[0:1], 12, v[0:1]
	v_lshl_add_u64 v[0:1], s[34:35], 0, v[0:1]
	v_lshl_add_u64 v[0:1], v[0:1], 0, s[30:31]
	v_lshl_add_u64 v[0:1], v[0:1], 0, v[184:185]
	s_waitcnt lgkmcnt(0)
	global_store_dwordx4 v[0:1], v[4:7], off
	v_add_u32_e32 v0, 0x1c00, v194
	v_ashrrev_i32_e32 v2, 5, v0
	v_add_u32_e32 v0, s0, v2
	v_ashrrev_i32_e32 v1, 31, v0
	v_lshlrev_b64 v[0:1], 12, v[0:1]
	v_lshl_add_u64 v[0:1], s[34:35], 0, v[0:1]
	v_lshl_add_u64 v[0:1], v[0:1], 0, s[30:31]
	v_lshl_add_u64 v[8:9], v[0:1], 0, v[184:185]
	v_mad_u64_u32 v[0:1], s[2:3], v2, s56, v[184:185]
	ds_read2_b64 v[0:3], v0 offset1:1
	v_add_u32_e32 v4, 0x1e00, v194
	v_ashrrev_i32_e32 v10, 5, v4
	v_mad_u64_u32 v[4:5], s[2:3], v10, s56, v[184:185]
	ds_read2_b64 v[4:7], v4 offset1:1
	s_waitcnt lgkmcnt(1)
	global_store_dwordx4 v[8:9], v[0:3], off
	s_nop 1
	v_add_u32_e32 v0, s0, v10
	v_ashrrev_i32_e32 v1, 31, v0
	v_lshlrev_b64 v[0:1], 12, v[0:1]
	v_lshl_add_u64 v[0:1], s[34:35], 0, v[0:1]
	v_lshl_add_u64 v[0:1], v[0:1], 0, s[30:31]
	v_lshl_add_u64 v[0:1], v[0:1], 0, v[184:185]
	s_waitcnt lgkmcnt(0)
	global_store_dwordx4 v[0:1], v[4:7], off
	s_waitcnt vmcnt(63) expcnt(7) lgkmcnt(15)
	s_barrier
	s_branch .LBB0_985

; #define K_STEP(ks) { bf16x8 xa0, xa1, xa2, xa3, xb0, xb1; FR_LOAD(ks, x) FR_MMA(x) \
;                      if (wr) GL_STORE(ks) if (ld) GL_LOADA(ks, kt + 2) }
; template <bool AF32, class AR>
; DI void gemm_loop(f32x16 (&acc)[4][2], GR& R, const AR& ar, const bf16_t* __restrict__ Bt, int ldb, int m0, int n0, int nk, bf16_t* lds, bool swp) {
;     ...
;   for (int kt = 0; kt < nk; ++kt) {
;     const bool wr = kt + 1 < nk, ld = kt + 2 < nk;
;     bf16_t* sA = lds + ((kt + 1) & 1) * LDS_TILE;
;     bf16_t* sB = lds + 2 * LDS_TILE + ((kt + 1) & 1) * LDS_TILE;
;     const bf16_t* cA = lds + (kt & 1) * LDS_TILE;
;     const bf16_t* cB = lds + 2 * LDS_TILE + (kt & 1) * LDS_TILE;
;     const bf16_t* pa = (swp ? cB : cA) + (wm * 128 + r) * 72 + 8 * h;
;     const bf16_t* pb = (swp ? cA : cB) + (wn * 64 + r) * 72 + 8 * h;
;     ...
;     K_STEP(0) K_STEP(1) K_STEP(2) K_STEP(3)
;     ...
;     __syncthreads();
;   }
.LBB0_1122:
	s_add_i32 s12, s2, 1
	s_bitcmp1_b32 s12, 0
	s_cselect_b32 s13, 0x9000, 0
	s_bitcmp1_b32 s2, 0
	s_cselect_b32 s14, 0x9000, 0
	v_add_u32_e32 v163, s14, v168
	v_add_u32_e32 v173, s14, v169
	ds_read_b128 v[174:177], v163
	ds_read_b128 v[178:181], v173
	ds_read_b128 v[182:185], v163 offset:4608
	ds_read_b128 v[186:189], v173 offset:4608
	s_waitcnt lgkmcnt(2)
	v_mfma_f32_32x32x16_bf16 v[112:127], v[174:177], v[178:181], v[112:127]
	v_add_u32_e32 v195, s13, v170
	v_add_u32_e32 v194, s13, v172
	s_cmp_lg_u32 s12, 30
	s_waitcnt lgkmcnt(0)
	v_mfma_f32_32x32x16_bf16 v[48:63], v[174:177], v[186:189], v[48:63]
	v_mfma_f32_32x32x16_bf16 v[96:111], v[182:185], v[178:181], v[96:111]
	v_mfma_f32_32x32x16_bf16 v[32:47], v[182:185], v[186:189], v[32:47]
	ds_read_b128 v[174:177], v163 offset:9216
	ds_read_b128 v[182:185], v163 offset:13824
	s_waitcnt vmcnt(7)
	ds_write_b128 v195, v[156:159]
	s_waitcnt vmcnt(6)
	ds_write_b128 v194, v[152:155]
	s_waitcnt lgkmcnt(3)
	v_mfma_f32_32x32x16_bf16 v[80:95], v[174:177], v[178:181], v[80:95]
	v_mfma_f32_32x32x16_bf16 v[16:31], v[174:177], v[186:189], v[16:31]
	s_waitcnt lgkmcnt(2)
	v_mfma_f32_32x32x16_bf16 v[64:79], v[182:185], v[178:181], v[64:79]
	ds_read_b128 v[152:155], v163 offset:32
	ds_read_b128 v[156:159], v173 offset:32
	ds_read_b128 v[174:177], v163 offset:4640
	ds_read_b128 v[178:181], v173 offset:4640
	s_waitcnt lgkmcnt(2)
	v_mfma_f32_32x32x16_bf16 v[112:127], v[152:155], v[156:159], v[112:127]
	s_waitcnt lgkmcnt(0)
	v_mfma_f32_32x32x16_bf16 v[48:63], v[152:155], v[178:181], v[48:63]
	v_mfma_f32_32x32x16_bf16 v[96:111], v[174:177], v[156:159], v[96:111]
	v_mfma_f32_32x32x16_bf16 v[32:47], v[174:177], v[178:181], v[32:47]
	ds_read_b128 v[152:155], v163 offset:9248
	ds_read_b128 v[174:177], v163 offset:13856
	s_waitcnt vmcnt(5)
	ds_write_b128 v195, v[144:147] offset:9216
	s_waitcnt vmcnt(4)
	ds_write_b128 v194, v[148:151] offset:9216
	v_mfma_f32_32x32x16_bf16 v[0:15], v[182:185], v[186:189], v[0:15]
	s_waitcnt lgkmcnt(3)
	v_mfma_f32_32x32x16_bf16 v[80:95], v[152:155], v[156:159], v[80:95]
	v_mfma_f32_32x32x16_bf16 v[16:31], v[152:155], v[178:181], v[16:31]
	s_waitcnt lgkmcnt(2)
	v_mfma_f32_32x32x16_bf16 v[64:79], v[174:177], v[156:159], v[64:79]
	ds_read_b128 v[144:147], v163 offset:64
	ds_read_b128 v[148:151], v173 offset:64
	ds_read_b128 v[152:155], v163 offset:4672
	ds_read_b128 v[156:159], v173 offset:4672
	s_waitcnt lgkmcnt(2)
	v_mfma_f32_32x32x16_bf16 v[112:127], v[144:147], v[148:151], v[112:127]
	s_waitcnt lgkmcnt(0)
	v_mfma_f32_32x32x16_bf16 v[48:63], v[144:147], v[156:159], v[48:63]
	v_mfma_f32_32x32x16_bf16 v[0:15], v[174:177], v[178:181], v[0:15]
	v_mfma_f32_32x32x16_bf16 v[96:111], v[152:155], v[148:151], v[96:111]
	v_mfma_f32_32x32x16_bf16 v[32:47], v[152:155], v[156:159], v[32:47]
	ds_read_b128 v[144:147], v163 offset:9280
	ds_read_b128 v[152:155], v163 offset:13888
	s_waitcnt vmcnt(3)
	ds_write_b128 v195, v[136:139] offset:18432
	s_waitcnt vmcnt(2)
	ds_write_b128 v194, v[140:143] offset:18432
	ds_read_b128 v[136:139], v163 offset:96
	ds_read_b128 v[174:177], v173 offset:96
	ds_read_b128 v[140:143], v163 offset:4704
	ds_read_b128 v[178:181], v173 offset:4704
	s_waitcnt lgkmcnt(7)
	v_mfma_f32_32x32x16_bf16 v[80:95], v[144:147], v[148:151], v[80:95]
	v_mfma_f32_32x32x16_bf16 v[16:31], v[144:147], v[156:159], v[16:31]
	v_add_u32_e32 v147, s2, v160
	v_add_co_u32_e32 v144, vcc, s27, v166
	v_add_u32_e32 v146, 0x202, v147
	s_nop 0
	v_addc_co_u32_e32 v145, vcc, -1, v167, vcc
	s_mov_b32 s2, s12
	s_waitcnt lgkmcnt(2)
	v_mfma_f32_32x32x16_bf16 v[112:127], v[136:139], v[174:177], v[112:127]
	s_waitcnt lgkmcnt(0)
	v_mfma_f32_32x32x16_bf16 v[48:63], v[136:139], v[178:181], v[48:63]
	v_add_u32_e32 v136, 2, v147
	v_add_u32_e32 v138, 0x102, v147
	v_ashrrev_i32_e32 v137, 31, v136
	v_ashrrev_i32_e32 v139, 31, v138
	v_mfma_f32_32x32x16_bf16 v[64:79], v[152:155], v[148:151], v[64:79]
	v_add_u32_e32 v150, 0x302, v147
	v_add_co_u32_e32 v148, vcc, s28, v166
	v_ashrrev_i32_e32 v147, 31, v146
	v_ashrrev_i32_e32 v151, 31, v150
	v_addc_co_u32_e32 v149, vcc, -1, v167, vcc
	v_mfma_f32_32x32x16_bf16 v[0:15], v[152:155], v[156:159], v[0:15]
	v_lshlrev_b64 v[152:153], 9, v[136:137]
	v_lshlrev_b64 v[154:155], 9, v[138:139]
	ds_read_b128 v[136:139], v163 offset:9312
	ds_read_b128 v[182:185], v163 offset:13920
	v_lshlrev_b64 v[146:147], 9, v[146:147]
	v_add_co_u32_e32 v186, vcc, s20, v166
	v_lshl_add_u64 v[188:189], v[164:165], 0, v[146:147]
	v_mfma_f32_32x32x16_bf16 v[96:111], v[140:143], v[174:177], v[96:111]
	v_addc_co_u32_e32 v187, vcc, 0, v167, vcc
	v_mfma_f32_32x32x16_bf16 v[32:47], v[140:143], v[178:181], v[32:47]
	v_lshlrev_b64 v[140:141], 9, v[150:151]
	v_lshl_add_u64 v[142:143], v[164:165], 0, v[152:153]
	v_lshl_add_u64 v[150:151], v[164:165], 0, v[154:155]
	v_lshl_add_u64 v[190:191], v[164:165], 0, v[140:141]
	global_load_dwordx4 v[156:159], v[142:143], off
	global_load_dwordx4 v[152:155], v[144:145], off
	s_waitcnt lgkmcnt(1)
	v_mfma_f32_32x32x16_bf16 v[80:95], v[136:139], v[174:177], v[80:95]
	v_mfma_f32_32x32x16_bf16 v[16:31], v[136:139], v[178:181], v[16:31]
	global_load_dwordx4 v[144:147], v[150:151], off
	s_nop 0
	global_load_dwordx4 v[148:151], v[148:149], off
	s_nop 0
	global_load_dwordx4 v[136:139], v[188:189], off
	global_load_dwordx4 v[140:143], v[166:167], off
	s_waitcnt vmcnt(7)
	ds_write_b128 v195, v[128:131] offset:27648
	s_waitcnt vmcnt(6)
	ds_write_b128 v194, v[132:135] offset:27648
	global_load_dwordx4 v[128:131], v[190:191], off
	global_load_dwordx4 v[132:135], v[186:187], off
	v_lshl_add_u64 v[166:167], v[166:167], 0, s[4:5]
	s_waitcnt lgkmcnt(0)
	s_barrier
; #define K_STEP(ks) { bf16x8 xa0, xa1, xa2, xa3, xb0, xb1; FR_LOAD(ks, x) FR_MMA(x) \
;                      if (wr) GL_STORE(ks) if (ld) GL_LOADA(ks, kt + 2) }
; template <bool AF32, class AR>
; DI void gemm_loop(f32x16 (&acc)[4][2], GR& R, const AR& ar, const bf16_t* __restrict__ Bt, int ldb, int m0, int n0, int nk, bf16_t* lds, bool swp) {
;     ...
;   for (int kt = 0; kt < nk; ++kt) {
;     const bool wr = kt + 1 < nk, ld = kt + 2 < nk;
;     bf16_t* sA = lds + ((kt + 1) & 1) * LDS_TILE;
;     bf16_t* sB = lds + 2 * LDS_TILE + ((kt + 1) & 1) * LDS_TILE;
;     const bf16_t* cA = lds + (kt & 1) * LDS_TILE;
;     const bf16_t* cB = lds + 2 * LDS_TILE + (kt & 1) * LDS_TILE;
;     const bf16_t* pa = (swp ? cB : cA) + (wm * 128 + r) * 72 + 8 * h;
;     const bf16_t* pb = (swp ? cA : cB) + (wn * 64 + r) * 72 + 8 * h;
;     ...
;     K_STEP(0) K_STEP(1) K_STEP(2) K_STEP(3)
;     ...
;     __syncthreads();
;   }
	v_mfma_f32_32x32x16_bf16 v[64:79], v[182:185], v[174:177], v[64:79]
	v_mfma_f32_32x32x16_bf16 v[0:15], v[182:185], v[178:181], v[0:15]
	s_cbranch_scc1 .LBB0_1122
	ds_read_b128 v[164:167], v168
	ds_read_b128 v[172:175], v168 offset:4608
	ds_read_b128 v[176:179], v168 offset:9216
	ds_read_b128 v[180:183], v168 offset:13824
	ds_read_b128 v[184:187], v169
	ds_read_b128 v[188:191], v169 offset:4608
	v_lshlrev_b32_e32 v160, 1, v171
	v_add3_u32 v160, v160, v162, s29
	s_waitcnt vmcnt(7)
	ds_write_b128 v170, v[156:159] offset:36864
	s_waitcnt vmcnt(6)
	ds_write_b128 v160, v[152:155]
	s_waitcnt lgkmcnt(3)
	v_mfma_f32_32x32x16_bf16 v[112:127], v[164:167], v[184:187], v[112:127]
	s_and_b64 s[10:11], s[10:11], exec
	s_cselect_b32 s2, s30, 0x1d000000
	s_add_u32 s10, s76, s2
	s_addc_u32 s11, s77, 0
	s_lshl_b32 s2, s33, 2
	s_and_b32 s12, s2, 0xffffff00
	s_ashr_i32 s13, s12, 31
	s_waitcnt lgkmcnt(2)
	v_mfma_f32_32x32x16_bf16 v[48:63], v[164:167], v[188:191], v[48:63]
	s_lshl_b64 s[12:13], s[12:13], 2
	s_add_u32 s12, s6, s12
	s_addc_u32 s13, s7, s13
	s_add_i32 s33, s33, s74
	s_add_i32 s16, s16, s17
	s_cmpk_lt_i32 s33, 0x80
	v_mfma_f32_32x32x16_bf16 v[32:47], v[172:175], v[188:191], v[32:47]
	v_mfma_f32_32x32x16_bf16 v[16:31], v[176:179], v[188:191], v[16:31]
	v_mfma_f32_32x32x16_bf16 v[0:15], v[180:183], v[188:191], v[0:15]
	v_mfma_f32_32x32x16_bf16 v[96:111], v[172:175], v[184:187], v[96:111]
	v_mfma_f32_32x32x16_bf16 v[80:95], v[176:179], v[184:187], v[80:95]
	v_mfma_f32_32x32x16_bf16 v[64:79], v[180:183], v[184:187], v[64:79]
	ds_read_b128 v[152:155], v168 offset:32
	ds_read_b128 v[156:159], v168 offset:4640
	ds_read_b128 v[162:165], v168 offset:9248
	ds_read_b128 v[172:175], v168 offset:13856
	ds_read_b128 v[176:179], v169 offset:32
	ds_read_b128 v[180:183], v169 offset:4640
	s_waitcnt vmcnt(5)
	ds_write_b128 v170, v[144:147] offset:46080
	s_waitcnt vmcnt(4)
	ds_write_b128 v160, v[148:151] offset:9216
	s_waitcnt lgkmcnt(2)
	v_mfma_f32_32x32x16_bf16 v[48:63], v[152:155], v[180:183], v[48:63]
	v_mfma_f32_32x32x16_bf16 v[32:47], v[156:159], v[180:183], v[32:47]
	v_mfma_f32_32x32x16_bf16 v[16:31], v[162:165], v[180:183], v[16:31]
	v_mfma_f32_32x32x16_bf16 v[0:15], v[172:175], v[180:183], v[0:15]
	v_mfma_f32_32x32x16_bf16 v[112:127], v[152:155], v[176:179], v[112:127]
	v_mfma_f32_32x32x16_bf16 v[96:111], v[156:159], v[176:179], v[96:111]
	v_mfma_f32_32x32x16_bf16 v[80:95], v[162:165], v[176:179], v[80:95]
	v_mfma_f32_32x32x16_bf16 v[64:79], v[172:175], v[176:179], v[64:79]
	ds_read_b128 v[144:147], v168 offset:64
	ds_read_b128 v[148:151], v168 offset:4672
	ds_read_b128 v[152:155], v168 offset:9280
	ds_read_b128 v[156:159], v168 offset:13888
	ds_read_b128 v[162:165], v169 offset:64
	ds_read_b128 v[172:175], v169 offset:4672
	s_waitcnt vmcnt(3)
	ds_write_b128 v170, v[136:139] offset:55296
	s_waitcnt vmcnt(2)
	ds_write_b128 v160, v[140:143] offset:18432
	s_waitcnt lgkmcnt(2)
	v_mfma_f32_32x32x16_bf16 v[48:63], v[144:147], v[172:175], v[48:63]
	v_mfma_f32_32x32x16_bf16 v[32:47], v[148:151], v[172:175], v[32:47]
	v_mfma_f32_32x32x16_bf16 v[16:31], v[152:155], v[172:175], v[16:31]
	v_mfma_f32_32x32x16_bf16 v[0:15], v[156:159], v[172:175], v[0:15]
	v_mfma_f32_32x32x16_bf16 v[112:127], v[144:147], v[162:165], v[112:127]
	v_mfma_f32_32x32x16_bf16 v[96:111], v[148:151], v[162:165], v[96:111]
	v_mfma_f32_32x32x16_bf16 v[80:95], v[152:155], v[162:165], v[80:95]
	v_mfma_f32_32x32x16_bf16 v[64:79], v[156:159], v[162:165], v[64:79]
	ds_read_b128 v[136:139], v168 offset:96
	ds_read_b128 v[140:143], v168 offset:4704
	ds_read_b128 v[144:147], v168 offset:9312
	ds_read_b128 v[148:151], v168 offset:13920
	ds_read_b128 v[152:155], v169 offset:96
	ds_read_b128 v[156:159], v169 offset:4704
	s_waitcnt vmcnt(1)
	ds_write_b128 v170, v[128:131] offset:64512
	s_waitcnt vmcnt(0)
	ds_write_b128 v160, v[132:135] offset:27648
	s_waitcnt lgkmcnt(0)
	s_barrier
	v_mfma_f32_32x32x16_bf16 v[48:63], v[136:139], v[156:159], v[48:63]
	v_mfma_f32_32x32x16_bf16 v[32:47], v[140:143], v[156:159], v[32:47]
	v_mfma_f32_32x32x16_bf16 v[16:31], v[144:147], v[156:159], v[16:31]
	v_mfma_f32_32x32x16_bf16 v[0:15], v[148:151], v[156:159], v[0:15]
	v_mfma_f32_32x32x16_bf16 v[112:127], v[136:139], v[152:155], v[112:127]
	v_mfma_f32_32x32x16_bf16 v[96:111], v[140:143], v[152:155], v[96:111]
	v_mfma_f32_32x32x16_bf16 v[80:95], v[144:147], v[152:155], v[80:95]
	v_mfma_f32_32x32x16_bf16 v[64:79], v[148:151], v[152:155], v[64:79]
	ds_read_b128 v[128:131], v168 offset:41472
	ds_read_b128 v[132:135], v168 offset:46080
	ds_read_b128 v[136:139], v168 offset:50688
	ds_read_b128 v[140:143], v169 offset:41472
	ds_read_b128 v[144:147], v169 offset:36864
	ds_read_b128 v[148:151], v169 offset:36896
	ds_read_b128 v[152:155], v168 offset:36864
	ds_read_b128 v[156:159], v168 offset:36896
	s_waitcnt lgkmcnt(1)
	v_mfma_f32_32x32x16_bf16 v[48:63], v[152:155], v[140:143], v[48:63]
	v_mfma_f32_32x32x16_bf16 v[32:47], v[128:131], v[140:143], v[32:47]
	v_mfma_f32_32x32x16_bf16 v[16:31], v[132:135], v[140:143], v[16:31]
	v_mfma_f32_32x32x16_bf16 v[0:15], v[136:139], v[140:143], v[0:15]
	v_mfma_f32_32x32x16_bf16 v[112:127], v[152:155], v[144:147], v[112:127]
	v_mfma_f32_32x32x16_bf16 v[96:111], v[128:131], v[144:147], v[96:111]
	v_mfma_f32_32x32x16_bf16 v[80:95], v[132:135], v[144:147], v[80:95]
	v_mfma_f32_32x32x16_bf16 v[64:79], v[136:139], v[144:147], v[64:79]
	ds_read_b128 v[128:131], v169 offset:41504
	ds_read_b128 v[132:135], v168 offset:50720
	ds_read_b128 v[136:139], v168 offset:46112
	ds_read_b128 v[140:143], v168 offset:41504
	s_waitcnt lgkmcnt(3)
	v_mfma_f32_32x32x16_bf16 v[48:63], v[156:159], v[128:131], v[48:63]
	s_waitcnt lgkmcnt(0)
; DI unsigned pack2(float a, float b) { f32x2_t v = {a, b}; bf16x2_t r = __builtin_convertvector(v, bf16x2_t); return __builtin_bit_cast(unsigned, r); }
; DI float bflo(unsigned u) { return __uint_as_float(u << 16); }
; DI float bfhi(unsigned u) { return __uint_as_float(u & 0xffff0000u); }
; DI float siluf_(float x) { return x * __builtin_amdgcn_rcpf(1.f + __expf(-x)); }
; DI void epi_seg(const f32x16 (&acc)[4][2], const Seg& sg0, const Seg& sg1, int m0, int n0, const float* rs, const float2* cs64, const float2* cs32, bf16_t* stg) {
;     ...
;       } else {
; #pragma unroll
;         for (int ch = 0; ch < 2; ++ch) {
;           float ss = 0.f;
; #pragma unroll
;           for (int i = 2 * ch; i < 2 * ch + 2; ++i)
; #pragma unroll
;             for (int q4 = 0; q4 < 4; ++q4) {
;               float v[4] = {acc[i][j][4 * q4] * sc, acc[i][j][4 * q4 + 1] * sc, acc[i][j][4 * q4 + 2] * sc, acc[i][j][4 * q4 + 3] * sc};
;               if (kind == K_SILU) {
;                 const f32x4 bv = *(const f32x4*)(sg.bias + lcw + i * 32 + 8 * q4 + 4 * h);
;                 v[0] = siluf_(v[0] + bv.x); v[1] = siluf_(v[1] + bv.y); v[2] = siluf_(v[2] + bv.z); v[3] = siluf_(v[3] + bv.w);
;               }
;               const uint2 pk = make_uint2(pack2(v[0], v[1]), pack2(v[2], v[3]));
;               *(uint2*)(srow + i * 32 + 8 * q4) = pk;
;               const float f0 = bflo(pk.x), f1 = bfhi(pk.x), f2 = bflo(pk.y), f3 = bfhi(pk.y);
;               ss += (f0 * f0 + f1 * f1) + (f2 * f2 + f3 * f3);
;             }
	v_mfma_f32_32x32x16_bf16 v[32:47], v[140:143], v[128:131], v[32:47]
	v_mfma_f32_32x32x16_bf16 v[16:31], v[136:139], v[128:131], v[16:31]
	v_mfma_f32_32x32x16_bf16 v[0:15], v[132:135], v[128:131], v[0:15]
	v_mfma_f32_32x32x16_bf16 v[112:127], v[156:159], v[148:151], v[112:127]
	v_mfma_f32_32x32x16_bf16 v[96:111], v[140:143], v[148:151], v[96:111]
	v_mfma_f32_32x32x16_bf16 v[80:95], v[136:139], v[148:151], v[80:95]
	v_mfma_f32_32x32x16_bf16 v[64:79], v[132:135], v[148:151], v[64:79]
	ds_read_b128 v[128:131], v169 offset:41536
	ds_read_b128 v[132:135], v169 offset:36928
	ds_read_b128 v[136:139], v168 offset:50752
	ds_read_b128 v[140:143], v168 offset:46144
	ds_read_b128 v[144:147], v168 offset:41536
	ds_read_b128 v[148:151], v168 offset:36928
	s_waitcnt lgkmcnt(0)
	v_mfma_f32_32x32x16_bf16 v[48:63], v[148:151], v[128:131], v[48:63]
	v_mfma_f32_32x32x16_bf16 v[32:47], v[144:147], v[128:131], v[32:47]
	v_mfma_f32_32x32x16_bf16 v[16:31], v[140:143], v[128:131], v[16:31]
	v_mfma_f32_32x32x16_bf16 v[0:15], v[136:139], v[128:131], v[0:15]
	v_mfma_f32_32x32x16_bf16 v[112:127], v[148:151], v[132:135], v[112:127]
	v_mfma_f32_32x32x16_bf16 v[96:111], v[144:147], v[132:135], v[96:111]
	v_mfma_f32_32x32x16_bf16 v[80:95], v[140:143], v[132:135], v[80:95]
	v_mfma_f32_32x32x16_bf16 v[64:79], v[136:139], v[132:135], v[64:79]
	ds_read_b128 v[128:131], v169 offset:41568
	ds_read_b128 v[132:135], v169 offset:36960
	ds_read_b128 v[136:139], v168 offset:50784
	ds_read_b128 v[140:143], v168 offset:46176
	ds_read_b128 v[144:147], v168 offset:41568
	ds_read_b128 v[148:151], v168 offset:36960
	s_waitcnt lgkmcnt(0)
	s_barrier
	v_mfma_f32_32x32x16_bf16 v[48:63], v[148:151], v[128:131], v[48:63]
	v_mfma_f32_32x32x16_bf16 v[32:47], v[144:147], v[128:131], v[32:47]
	v_mfma_f32_32x32x16_bf16 v[16:31], v[140:143], v[128:131], v[16:31]
	v_mfma_f32_32x32x16_bf16 v[0:15], v[136:139], v[128:131], v[0:15]
	v_mov_b32_e32 v130, v192
	s_nop 0
	v_ashrrev_i32_e32 v128, 1, v130
	v_and_b32_e32 v128, 0xffffff80, v128
	v_lshrrev_b32_e32 v129, 3, v130
	v_and_b32_e32 v131, 0xdf, v130
	v_mfma_f32_32x32x16_bf16 v[112:127], v[148:151], v[132:135], v[112:127]
	v_mul_u32_u24_e32 v131, 0x208, v131
	v_mfma_f32_32x32x16_bf16 v[96:111], v[144:147], v[132:135], v[96:111]
	v_mfma_f32_32x32x16_bf16 v[80:95], v[140:143], v[132:135], v[80:95]
	v_mfma_f32_32x32x16_bf16 v[64:79], v[136:139], v[132:135], v[64:79]
	v_and_b32_e32 v132, 4, v129
	v_ashrrev_i32_e32 v129, 31, v128
	v_or_b32_e32 v133, v128, v132
	v_lshl_add_u64 v[128:129], v[128:129], 2, s[12:13]
	v_lshlrev_b32_e32 v160, 2, v132
	v_lshl_add_u64 v[128:129], v[128:129], 0, v[160:161]
	v_lshl_add_u32 v131, v133, 1, v131
	global_load_dwordx4 v[132:135], v[128:129], off
	s_waitcnt vmcnt(0)
	v_pk_add_f32 v[112:113], v[112:113], v[132:133]
	s_nop 0
	v_mul_f32_e32 v132, 0xbfb8aa3b, v112
	v_mul_f32_e32 v133, 0xbfb8aa3b, v113
	v_exp_f32_e32 v132, v132
	v_exp_f32_e32 v133, v133
	v_pk_add_f32 v[114:115], v[114:115], v[134:135]
	v_add_f32_e32 v132, 1.0, v132
	v_add_f32_e32 v133, 1.0, v133
	v_rcp_f32_e32 v132, v132
	v_rcp_f32_e32 v133, v133
	s_nop 0
	v_pk_mul_f32 v[112:113], v[112:113], v[132:133]
	v_mul_f32_e32 v132, 0xbfb8aa3b, v114
	v_mul_f32_e32 v133, 0xbfb8aa3b, v115
	v_exp_f32_e32 v132, v132
	v_exp_f32_e32 v133, v133
	v_add_f32_e32 v132, 1.0, v132
	v_add_f32_e32 v133, 1.0, v133
	v_rcp_f32_e32 v132, v132
	v_rcp_f32_e32 v133, v133
	s_nop 0
	v_pk_mul_f32 v[114:115], v[114:115], v[132:133]
	v_cvt_pk_bf16_f32 v132, v112, v113
	v_cvt_pk_bf16_f32 v133, v114, v115
	global_load_dwordx4 v[112:115], v[128:129], off offset:32
	s_waitcnt vmcnt(0)
	v_pk_add_f32 v[112:113], v[116:117], v[112:113]
	s_nop 0
	v_mul_f32_e32 v116, 0xbfb8aa3b, v112
	v_mul_f32_e32 v117, 0xbfb8aa3b, v113
	v_exp_f32_e32 v116, v116
	v_exp_f32_e32 v117, v117
	v_pk_add_f32 v[114:115], v[118:119], v[114:115]
	v_add_f32_e32 v116, 1.0, v116
	v_add_f32_e32 v117, 1.0, v117
	v_rcp_f32_e32 v116, v116
	v_rcp_f32_e32 v117, v117
	s_nop 0
	v_pk_mul_f32 v[112:113], v[112:113], v[116:117]
	v_mul_f32_e32 v116, 0xbfb8aa3b, v114
	v_mul_f32_e32 v117, 0xbfb8aa3b, v115
	v_exp_f32_e32 v116, v116
	v_exp_f32_e32 v117, v117
	v_cvt_pk_bf16_f32 v112, v112, v113
	v_add_f32_e32 v116, 1.0, v116
	v_add_f32_e32 v117, 1.0, v117
	v_rcp_f32_e32 v116, v116
	v_rcp_f32_e32 v117, v117
	s_nop 0
	v_pk_mul_f32 v[114:115], v[114:115], v[116:117]
	s_nop 0
	v_cvt_pk_bf16_f32 v113, v114, v115
	ds_write2_b64 v131, v[132:133], v[112:113] offset1:2
	global_load_dwordx4 v[112:115], v[128:129], off offset:64
	s_waitcnt vmcnt(0)
	v_pk_add_f32 v[112:113], v[120:121], v[112:113]
	s_nop 0
	v_mul_f32_e32 v116, 0xbfb8aa3b, v112
	v_mul_f32_e32 v117, 0xbfb8aa3b, v113
	v_exp_f32_e32 v116, v116
	v_exp_f32_e32 v117, v117
	v_pk_add_f32 v[114:115], v[122:123], v[114:115]
	v_add_f32_e32 v116, 1.0, v116
	v_add_f32_e32 v117, 1.0, v117
	v_rcp_f32_e32 v116, v116
	v_rcp_f32_e32 v117, v117
	s_nop 0
	v_pk_mul_f32 v[112:113], v[112:113], v[116:117]
	v_mul_f32_e32 v116, 0xbfb8aa3b, v114
	v_mul_f32_e32 v117, 0xbfb8aa3b, v115
	v_exp_f32_e32 v116, v116
	v_exp_f32_e32 v117, v117
	v_add_f32_e32 v116, 1.0, v116
	v_add_f32_e32 v117, 1.0, v117
	v_rcp_f32_e32 v116, v116
	v_rcp_f32_e32 v117, v117
	s_nop 0
	v_pk_mul_f32 v[114:115], v[114:115], v[116:117]
	v_cvt_pk_bf16_f32 v116, v112, v113
	v_cvt_pk_bf16_f32 v117, v114, v115
	global_load_dwordx4 v[112:115], v[128:129], off offset:96
	s_waitcnt vmcnt(0)
; DI unsigned pack2(float a, float b) { f32x2_t v = {a, b}; bf16x2_t r = __builtin_convertvector(v, bf16x2_t); return __builtin_bit_cast(unsigned, r); }
; DI float bflo(unsigned u) { return __uint_as_float(u << 16); }
; DI float bfhi(unsigned u) { return __uint_as_float(u & 0xffff0000u); }
; DI float siluf_(float x) { return x * __builtin_amdgcn_rcpf(1.f + __expf(-x)); }
; DI void epi_seg(const f32x16 (&acc)[4][2], const Seg& sg0, const Seg& sg1, int m0, int n0, const float* rs, const float2* cs64, const float2* cs32, bf16_t* stg) {
;     ...
;       } else {
; #pragma unroll
;         for (int ch = 0; ch < 2; ++ch) {
;           float ss = 0.f;
; #pragma unroll
;           for (int i = 2 * ch; i < 2 * ch + 2; ++i)
; #pragma unroll
;             for (int q4 = 0; q4 < 4; ++q4) {
;               float v[4] = {acc[i][j][4 * q4] * sc, acc[i][j][4 * q4 + 1] * sc, acc[i][j][4 * q4 + 2] * sc, acc[i][j][4 * q4 + 3] * sc};
;               if (kind == K_SILU) {
;                 const f32x4 bv = *(const f32x4*)(sg.bias + lcw + i * 32 + 8 * q4 + 4 * h);
;                 v[0] = siluf_(v[0] + bv.x); v[1] = siluf_(v[1] + bv.y); v[2] = siluf_(v[2] + bv.z); v[3] = siluf_(v[3] + bv.w);
;               }
;               const uint2 pk = make_uint2(pack2(v[0], v[1]), pack2(v[2], v[3]));
;               *(uint2*)(srow + i * 32 + 8 * q4) = pk;
;               const float f0 = bflo(pk.x), f1 = bfhi(pk.x), f2 = bflo(pk.y), f3 = bfhi(pk.y);
;               ss += (f0 * f0 + f1 * f1) + (f2 * f2 + f3 * f3);
;             }
	v_pk_add_f32 v[112:113], v[124:125], v[112:113]
	s_nop 0
	v_mul_f32_e32 v118, 0xbfb8aa3b, v112
	v_mul_f32_e32 v119, 0xbfb8aa3b, v113
	v_exp_f32_e32 v118, v118
	v_exp_f32_e32 v119, v119
	v_pk_add_f32 v[114:115], v[126:127], v[114:115]
	v_add_f32_e32 v118, 1.0, v118
	v_add_f32_e32 v119, 1.0, v119
	v_rcp_f32_e32 v118, v118
	v_rcp_f32_e32 v119, v119
	s_nop 0
	v_pk_mul_f32 v[112:113], v[112:113], v[118:119]
	v_mul_f32_e32 v118, 0xbfb8aa3b, v114
	v_mul_f32_e32 v119, 0xbfb8aa3b, v115
	v_exp_f32_e32 v118, v118
	v_exp_f32_e32 v119, v119
	v_cvt_pk_bf16_f32 v112, v112, v113
	v_add_f32_e32 v118, 1.0, v118
	v_add_f32_e32 v119, 1.0, v119
	v_rcp_f32_e32 v118, v118
	v_rcp_f32_e32 v119, v119
	s_nop 0
	v_pk_mul_f32 v[114:115], v[114:115], v[118:119]
	s_nop 0
	v_cvt_pk_bf16_f32 v113, v114, v115
	ds_write2_b64 v131, v[116:117], v[112:113] offset0:4 offset1:6
	global_load_dwordx4 v[112:115], v[128:129], off offset:128
	s_waitcnt vmcnt(0)
	v_pk_add_f32 v[96:97], v[96:97], v[112:113]
	s_nop 0
	v_mul_f32_e32 v112, 0xbfb8aa3b, v96
	v_mul_f32_e32 v113, 0xbfb8aa3b, v97
	v_exp_f32_e32 v112, v112
	v_exp_f32_e32 v113, v113
	v_pk_add_f32 v[98:99], v[98:99], v[114:115]
	v_add_f32_e32 v112, 1.0, v112
	v_add_f32_e32 v113, 1.0, v113
	v_rcp_f32_e32 v112, v112
	v_rcp_f32_e32 v113, v113
	s_nop 0
	v_pk_mul_f32 v[96:97], v[96:97], v[112:113]
	v_mul_f32_e32 v112, 0xbfb8aa3b, v98
	v_mul_f32_e32 v113, 0xbfb8aa3b, v99
	v_exp_f32_e32 v112, v112
	v_exp_f32_e32 v113, v113
	v_add_f32_e32 v112, 1.0, v112
	v_add_f32_e32 v113, 1.0, v113
	v_rcp_f32_e32 v112, v112
	v_rcp_f32_e32 v113, v113
	s_nop 0
	v_pk_mul_f32 v[98:99], v[98:99], v[112:113]
	v_cvt_pk_bf16_f32 v112, v96, v97
	v_cvt_pk_bf16_f32 v113, v98, v99
	global_load_dwordx4 v[96:99], v[128:129], off offset:160
	s_waitcnt vmcnt(0)
	v_pk_add_f32 v[96:97], v[100:101], v[96:97]
	s_nop 0
	v_mul_f32_e32 v100, 0xbfb8aa3b, v96
	v_mul_f32_e32 v101, 0xbfb8aa3b, v97
	v_exp_f32_e32 v100, v100
	v_exp_f32_e32 v101, v101
	v_pk_add_f32 v[98:99], v[102:103], v[98:99]
	v_add_f32_e32 v100, 1.0, v100
	v_add_f32_e32 v101, 1.0, v101
	v_rcp_f32_e32 v100, v100
	v_rcp_f32_e32 v101, v101
	s_nop 0
	v_pk_mul_f32 v[96:97], v[96:97], v[100:101]
	v_mul_f32_e32 v100, 0xbfb8aa3b, v98
	v_mul_f32_e32 v101, 0xbfb8aa3b, v99
	v_exp_f32_e32 v100, v100
	v_exp_f32_e32 v101, v101
	v_cvt_pk_bf16_f32 v96, v96, v97
	v_add_f32_e32 v100, 1.0, v100
	v_add_f32_e32 v101, 1.0, v101
	v_rcp_f32_e32 v100, v100
	v_rcp_f32_e32 v101, v101
	s_nop 0
	v_pk_mul_f32 v[98:99], v[98:99], v[100:101]
	s_nop 0
	v_cvt_pk_bf16_f32 v97, v98, v99
	ds_write2_b64 v131, v[112:113], v[96:97] offset0:8 offset1:10
	global_load_dwordx4 v[96:99], v[128:129], off offset:192
	s_waitcnt vmcnt(0)
	v_pk_add_f32 v[96:97], v[104:105], v[96:97]
	s_nop 0
	v_mul_f32_e32 v100, 0xbfb8aa3b, v96
	v_mul_f32_e32 v101, 0xbfb8aa3b, v97
	v_exp_f32_e32 v100, v100
	v_exp_f32_e32 v101, v101
	v_pk_add_f32 v[98:99], v[106:107], v[98:99]
	v_add_f32_e32 v100, 1.0, v100
	v_add_f32_e32 v101, 1.0, v101
	v_rcp_f32_e32 v100, v100
	v_rcp_f32_e32 v101, v101
	s_nop 0
	v_pk_mul_f32 v[96:97], v[96:97], v[100:101]
	v_mul_f32_e32 v100, 0xbfb8aa3b, v98
	v_mul_f32_e32 v101, 0xbfb8aa3b, v99
	v_exp_f32_e32 v100, v100
	v_exp_f32_e32 v101, v101
	v_add_f32_e32 v100, 1.0, v100
	v_add_f32_e32 v101, 1.0, v101
	v_rcp_f32_e32 v100, v100
	v_rcp_f32_e32 v101, v101
	s_nop 0
	v_pk_mul_f32 v[98:99], v[98:99], v[100:101]
	v_cvt_pk_bf16_f32 v100, v96, v97
	v_cvt_pk_bf16_f32 v101, v98, v99
	global_load_dwordx4 v[96:99], v[128:129], off offset:224
	s_waitcnt vmcnt(0)
	v_pk_add_f32 v[96:97], v[108:109], v[96:97]
	s_nop 0
	v_mul_f32_e32 v102, 0xbfb8aa3b, v96
	v_mul_f32_e32 v103, 0xbfb8aa3b, v97
	v_exp_f32_e32 v102, v102
	v_exp_f32_e32 v103, v103
	v_pk_add_f32 v[98:99], v[110:111], v[98:99]
	v_add_f32_e32 v102, 1.0, v102
	v_add_f32_e32 v103, 1.0, v103
	v_rcp_f32_e32 v102, v102
	v_rcp_f32_e32 v103, v103
	s_nop 0
	v_pk_mul_f32 v[96:97], v[96:97], v[102:103]
	v_mul_f32_e32 v102, 0xbfb8aa3b, v98
	v_mul_f32_e32 v103, 0xbfb8aa3b, v99
	v_exp_f32_e32 v102, v102
	v_exp_f32_e32 v103, v103
	v_cvt_pk_bf16_f32 v96, v96, v97
	v_add_f32_e32 v102, 1.0, v102
	v_add_f32_e32 v103, 1.0, v103
	v_rcp_f32_e32 v102, v102
	v_rcp_f32_e32 v103, v103
	s_nop 0
	v_pk_mul_f32 v[98:99], v[98:99], v[102:103]
	s_nop 0
	v_cvt_pk_bf16_f32 v97, v98, v99
	ds_write2_b64 v131, v[100:101], v[96:97] offset0:12 offset1:14
	global_load_dwordx4 v[96:99], v[128:129], off offset:256
	s_waitcnt vmcnt(0)
	v_pk_add_f32 v[80:81], v[80:81], v[96:97]
	s_nop 0
	v_mul_f32_e32 v96, 0xbfb8aa3b, v80
	v_mul_f32_e32 v97, 0xbfb8aa3b, v81
	v_exp_f32_e32 v96, v96
	v_exp_f32_e32 v97, v97
	v_pk_add_f32 v[82:83], v[82:83], v[98:99]
	v_add_f32_e32 v96, 1.0, v96
	v_add_f32_e32 v97, 1.0, v97
	v_rcp_f32_e32 v96, v96
	v_rcp_f32_e32 v97, v97
	s_nop 0
	v_pk_mul_f32 v[80:81], v[80:81], v[96:97]
	v_mul_f32_e32 v96, 0xbfb8aa3b, v82
	v_mul_f32_e32 v97, 0xbfb8aa3b, v83
	v_exp_f32_e32 v96, v96
	v_exp_f32_e32 v97, v97
	v_add_f32_e32 v96, 1.0, v96
	v_add_f32_e32 v97, 1.0, v97
	v_rcp_f32_e32 v96, v96
	v_rcp_f32_e32 v97, v97
	s_nop 0
	v_pk_mul_f32 v[82:83], v[82:83], v[96:97]
	v_cvt_pk_bf16_f32 v96, v80, v81
	v_cvt_pk_bf16_f32 v97, v82, v83
	global_load_dwordx4 v[80:83], v[128:129], off offset:288
	s_waitcnt vmcnt(0)
	v_pk_add_f32 v[80:81], v[84:85], v[80:81]
	s_nop 0
	v_mul_f32_e32 v84, 0xbfb8aa3b, v80
	v_mul_f32_e32 v85, 0xbfb8aa3b, v81
	v_exp_f32_e32 v84, v84
	v_exp_f32_e32 v85, v85
	v_pk_add_f32 v[82:83], v[86:87], v[82:83]
	v_add_f32_e32 v84, 1.0, v84
	v_add_f32_e32 v85, 1.0, v85
	v_rcp_f32_e32 v84, v84
	v_rcp_f32_e32 v85, v85
	s_nop 0
	v_pk_mul_f32 v[80:81], v[80:81], v[84:85]
	v_mul_f32_e32 v84, 0xbfb8aa3b, v82
	v_mul_f32_e32 v85, 0xbfb8aa3b, v83
	v_exp_f32_e32 v84, v84
	v_exp_f32_e32 v85, v85
	v_cvt_pk_bf16_f32 v80, v80, v81
	v_add_f32_e32 v84, 1.0, v84
	v_add_f32_e32 v85, 1.0, v85
	v_rcp_f32_e32 v84, v84
	v_rcp_f32_e32 v85, v85
	s_nop 0
	v_pk_mul_f32 v[82:83], v[82:83], v[84:85]
	s_nop 0
	v_cvt_pk_bf16_f32 v81, v82, v83
	ds_write2_b64 v131, v[96:97], v[80:81] offset0:16 offset1:18
	global_load_dwordx4 v[80:83], v[128:129], off offset:320
	s_waitcnt vmcnt(0)
; DI unsigned pack2(float a, float b) { f32x2_t v = {a, b}; bf16x2_t r = __builtin_convertvector(v, bf16x2_t); return __builtin_bit_cast(unsigned, r); }
; DI float bflo(unsigned u) { return __uint_as_float(u << 16); }
; DI float bfhi(unsigned u) { return __uint_as_float(u & 0xffff0000u); }
; DI float siluf_(float x) { return x * __builtin_amdgcn_rcpf(1.f + __expf(-x)); }
; DI void epi_seg(const f32x16 (&acc)[4][2], const Seg& sg0, const Seg& sg1, int m0, int n0, const float* rs, const float2* cs64, const float2* cs32, bf16_t* stg) {
;     ...
;       } else {
; #pragma unroll
;         for (int ch = 0; ch < 2; ++ch) {
;           float ss = 0.f;
; #pragma unroll
;           for (int i = 2 * ch; i < 2 * ch + 2; ++i)
; #pragma unroll
;             for (int q4 = 0; q4 < 4; ++q4) {
;               float v[4] = {acc[i][j][4 * q4] * sc, acc[i][j][4 * q4 + 1] * sc, acc[i][j][4 * q4 + 2] * sc, acc[i][j][4 * q4 + 3] * sc};
;               if (kind == K_SILU) {
;                 const f32x4 bv = *(const f32x4*)(sg.bias + lcw + i * 32 + 8 * q4 + 4 * h);
;                 v[0] = siluf_(v[0] + bv.x); v[1] = siluf_(v[1] + bv.y); v[2] = siluf_(v[2] + bv.z); v[3] = siluf_(v[3] + bv.w);
;               }
;               const uint2 pk = make_uint2(pack2(v[0], v[1]), pack2(v[2], v[3]));
;               *(uint2*)(srow + i * 32 + 8 * q4) = pk;
;               const float f0 = bflo(pk.x), f1 = bfhi(pk.x), f2 = bflo(pk.y), f3 = bfhi(pk.y);
;               ss += (f0 * f0 + f1 * f1) + (f2 * f2 + f3 * f3);
;             }
	v_pk_add_f32 v[80:81], v[88:89], v[80:81]
	s_nop 0
	v_mul_f32_e32 v84, 0xbfb8aa3b, v80
	v_mul_f32_e32 v85, 0xbfb8aa3b, v81
	v_exp_f32_e32 v84, v84
	v_exp_f32_e32 v85, v85
	v_pk_add_f32 v[82:83], v[90:91], v[82:83]
	v_add_f32_e32 v84, 1.0, v84
	v_add_f32_e32 v85, 1.0, v85
	v_rcp_f32_e32 v84, v84
	v_rcp_f32_e32 v85, v85
	s_nop 0
	v_pk_mul_f32 v[80:81], v[80:81], v[84:85]
	v_mul_f32_e32 v84, 0xbfb8aa3b, v82
	v_mul_f32_e32 v85, 0xbfb8aa3b, v83
	v_exp_f32_e32 v84, v84
	v_exp_f32_e32 v85, v85
	v_add_f32_e32 v84, 1.0, v84
	v_add_f32_e32 v85, 1.0, v85
	v_rcp_f32_e32 v84, v84
	v_rcp_f32_e32 v85, v85
	s_nop 0
	v_pk_mul_f32 v[82:83], v[82:83], v[84:85]
	v_cvt_pk_bf16_f32 v84, v80, v81
	v_cvt_pk_bf16_f32 v85, v82, v83
	global_load_dwordx4 v[80:83], v[128:129], off offset:352
	s_waitcnt vmcnt(0)
	v_pk_add_f32 v[80:81], v[92:93], v[80:81]
	s_nop 0
	v_mul_f32_e32 v86, 0xbfb8aa3b, v80
	v_mul_f32_e32 v87, 0xbfb8aa3b, v81
	v_exp_f32_e32 v86, v86
	v_exp_f32_e32 v87, v87
	v_pk_add_f32 v[82:83], v[94:95], v[82:83]
	v_add_f32_e32 v86, 1.0, v86
	v_add_f32_e32 v87, 1.0, v87
	v_rcp_f32_e32 v86, v86
	v_rcp_f32_e32 v87, v87
	s_nop 0
	v_pk_mul_f32 v[80:81], v[80:81], v[86:87]
	v_mul_f32_e32 v86, 0xbfb8aa3b, v82
	v_mul_f32_e32 v87, 0xbfb8aa3b, v83
	v_exp_f32_e32 v86, v86
	v_exp_f32_e32 v87, v87
	v_cvt_pk_bf16_f32 v80, v80, v81
	v_add_f32_e32 v86, 1.0, v86
	v_add_f32_e32 v87, 1.0, v87
	v_rcp_f32_e32 v86, v86
	v_rcp_f32_e32 v87, v87
	s_nop 0
	v_pk_mul_f32 v[82:83], v[82:83], v[86:87]
	s_nop 0
	v_cvt_pk_bf16_f32 v81, v82, v83
	ds_write2_b64 v131, v[84:85], v[80:81] offset0:20 offset1:22
	global_load_dwordx4 v[80:83], v[128:129], off offset:384
	s_waitcnt vmcnt(0)
	v_pk_add_f32 v[64:65], v[64:65], v[80:81]
	s_nop 0
	v_mul_f32_e32 v80, 0xbfb8aa3b, v64
	v_mul_f32_e32 v81, 0xbfb8aa3b, v65
	v_exp_f32_e32 v80, v80
	v_exp_f32_e32 v81, v81
	v_pk_add_f32 v[66:67], v[66:67], v[82:83]
	v_add_f32_e32 v80, 1.0, v80
	v_add_f32_e32 v81, 1.0, v81
	v_rcp_f32_e32 v80, v80
	v_rcp_f32_e32 v81, v81
	s_nop 0
	v_pk_mul_f32 v[64:65], v[64:65], v[80:81]
	v_mul_f32_e32 v80, 0xbfb8aa3b, v66
	v_mul_f32_e32 v81, 0xbfb8aa3b, v67
	v_exp_f32_e32 v80, v80
	v_exp_f32_e32 v81, v81
	v_add_f32_e32 v80, 1.0, v80
	v_add_f32_e32 v81, 1.0, v81
	v_rcp_f32_e32 v80, v80
	v_rcp_f32_e32 v81, v81
	s_nop 0
	v_pk_mul_f32 v[66:67], v[66:67], v[80:81]
	v_cvt_pk_bf16_f32 v80, v64, v65
	v_cvt_pk_bf16_f32 v81, v66, v67
	global_load_dwordx4 v[64:67], v[128:129], off offset:416
	s_waitcnt vmcnt(0)
	v_pk_add_f32 v[64:65], v[68:69], v[64:65]
	s_nop 0
	v_mul_f32_e32 v68, 0xbfb8aa3b, v64
	v_mul_f32_e32 v69, 0xbfb8aa3b, v65
	v_exp_f32_e32 v68, v68
	v_exp_f32_e32 v69, v69
	v_pk_add_f32 v[66:67], v[70:71], v[66:67]
	v_add_f32_e32 v68, 1.0, v68
	v_add_f32_e32 v69, 1.0, v69
	v_rcp_f32_e32 v68, v68
	v_rcp_f32_e32 v69, v69
	s_nop 0
	v_pk_mul_f32 v[64:65], v[64:65], v[68:69]
	v_mul_f32_e32 v68, 0xbfb8aa3b, v66
	v_mul_f32_e32 v69, 0xbfb8aa3b, v67
	v_exp_f32_e32 v68, v68
	v_exp_f32_e32 v69, v69
	v_cvt_pk_bf16_f32 v64, v64, v65
	v_add_f32_e32 v68, 1.0, v68
	v_add_f32_e32 v69, 1.0, v69
	v_rcp_f32_e32 v68, v68
	v_rcp_f32_e32 v69, v69
	s_nop 0
	v_pk_mul_f32 v[66:67], v[66:67], v[68:69]
	s_nop 0
	v_cvt_pk_bf16_f32 v65, v66, v67
	ds_write2_b64 v131, v[80:81], v[64:65] offset0:24 offset1:26
	global_load_dwordx4 v[64:67], v[128:129], off offset:448
	s_waitcnt vmcnt(0)
	v_pk_add_f32 v[64:65], v[72:73], v[64:65]
	s_nop 0
	v_mul_f32_e32 v68, 0xbfb8aa3b, v64
	v_mul_f32_e32 v69, 0xbfb8aa3b, v65
	v_exp_f32_e32 v68, v68
	v_exp_f32_e32 v69, v69
	v_pk_add_f32 v[66:67], v[74:75], v[66:67]
	v_add_f32_e32 v68, 1.0, v68
	v_add_f32_e32 v69, 1.0, v69
	v_rcp_f32_e32 v68, v68
	v_rcp_f32_e32 v69, v69
	s_nop 0
	v_pk_mul_f32 v[64:65], v[64:65], v[68:69]
	v_mul_f32_e32 v68, 0xbfb8aa3b, v66
	v_mul_f32_e32 v69, 0xbfb8aa3b, v67
	v_exp_f32_e32 v68, v68
	v_exp_f32_e32 v69, v69
	v_add_f32_e32 v68, 1.0, v68
	v_add_f32_e32 v69, 1.0, v69
	v_rcp_f32_e32 v68, v68
	v_rcp_f32_e32 v69, v69
	s_nop 0
	v_pk_mul_f32 v[66:67], v[66:67], v[68:69]
	v_cvt_pk_bf16_f32 v68, v64, v65
	v_cvt_pk_bf16_f32 v69, v66, v67
	global_load_dwordx4 v[64:67], v[128:129], off offset:480
	s_waitcnt vmcnt(0)
	v_pk_add_f32 v[64:65], v[76:77], v[64:65]
	s_nop 0
	v_mul_f32_e32 v70, 0xbfb8aa3b, v64
	v_mul_f32_e32 v71, 0xbfb8aa3b, v65
	v_exp_f32_e32 v70, v70
	v_exp_f32_e32 v71, v71
	v_pk_add_f32 v[66:67], v[78:79], v[66:67]
	v_add_f32_e32 v70, 1.0, v70
	v_add_f32_e32 v71, 1.0, v71
	v_rcp_f32_e32 v70, v70
	v_rcp_f32_e32 v71, v71
	s_nop 0
	v_pk_mul_f32 v[64:65], v[64:65], v[70:71]
	v_mul_f32_e32 v70, 0xbfb8aa3b, v66
	v_mul_f32_e32 v71, 0xbfb8aa3b, v67
	v_exp_f32_e32 v70, v70
	v_exp_f32_e32 v71, v71
	v_cvt_pk_bf16_f32 v64, v64, v65
	v_add_f32_e32 v70, 1.0, v70
	v_add_f32_e32 v71, 1.0, v71
	v_rcp_f32_e32 v70, v70
	v_rcp_f32_e32 v71, v71
	s_nop 0
	v_pk_mul_f32 v[66:67], v[66:67], v[70:71]
	s_nop 0
	v_cvt_pk_bf16_f32 v65, v66, v67
	ds_write2_b64 v131, v[68:69], v[64:65] offset0:28 offset1:30
	global_load_dwordx4 v[64:67], v[128:129], off
	s_waitcnt vmcnt(0)
	v_pk_add_f32 v[48:49], v[48:49], v[64:65]
	s_nop 0
	v_mul_f32_e32 v64, 0xbfb8aa3b, v48
	v_mul_f32_e32 v65, 0xbfb8aa3b, v49
	v_exp_f32_e32 v64, v64
	v_exp_f32_e32 v65, v65
	v_pk_add_f32 v[50:51], v[50:51], v[66:67]
	v_add_f32_e32 v64, 1.0, v64
	v_add_f32_e32 v65, 1.0, v65
	v_rcp_f32_e32 v64, v64
	v_rcp_f32_e32 v65, v65
	s_nop 0
	v_pk_mul_f32 v[48:49], v[48:49], v[64:65]
	v_mul_f32_e32 v64, 0xbfb8aa3b, v50
	v_mul_f32_e32 v65, 0xbfb8aa3b, v51
	v_exp_f32_e32 v64, v64
	v_exp_f32_e32 v65, v65
	v_add_f32_e32 v64, 1.0, v64
	v_add_f32_e32 v65, 1.0, v65
	v_rcp_f32_e32 v64, v64
	v_rcp_f32_e32 v65, v65
	s_nop 0
	v_pk_mul_f32 v[50:51], v[50:51], v[64:65]
	v_cvt_pk_bf16_f32 v64, v48, v49
	v_cvt_pk_bf16_f32 v65, v50, v51
	global_load_dwordx4 v[48:51], v[128:129], off offset:32
	s_waitcnt vmcnt(0)
; DI unsigned pack2(float a, float b) { f32x2_t v = {a, b}; bf16x2_t r = __builtin_convertvector(v, bf16x2_t); return __builtin_bit_cast(unsigned, r); }
; DI float bflo(unsigned u) { return __uint_as_float(u << 16); }
; DI float bfhi(unsigned u) { return __uint_as_float(u & 0xffff0000u); }
; DI float siluf_(float x) { return x * __builtin_amdgcn_rcpf(1.f + __expf(-x)); }
; DI void epi_seg(const f32x16 (&acc)[4][2], const Seg& sg0, const Seg& sg1, int m0, int n0, const float* rs, const float2* cs64, const float2* cs32, bf16_t* stg) {
;     ...
;       } else {
; #pragma unroll
;         for (int ch = 0; ch < 2; ++ch) {
;           float ss = 0.f;
; #pragma unroll
;           for (int i = 2 * ch; i < 2 * ch + 2; ++i)
; #pragma unroll
;             for (int q4 = 0; q4 < 4; ++q4) {
;               float v[4] = {acc[i][j][4 * q4] * sc, acc[i][j][4 * q4 + 1] * sc, acc[i][j][4 * q4 + 2] * sc, acc[i][j][4 * q4 + 3] * sc};
;               if (kind == K_SILU) {
;                 const f32x4 bv = *(const f32x4*)(sg.bias + lcw + i * 32 + 8 * q4 + 4 * h);
;                 v[0] = siluf_(v[0] + bv.x); v[1] = siluf_(v[1] + bv.y); v[2] = siluf_(v[2] + bv.z); v[3] = siluf_(v[3] + bv.w);
;               }
;               const uint2 pk = make_uint2(pack2(v[0], v[1]), pack2(v[2], v[3]));
;               *(uint2*)(srow + i * 32 + 8 * q4) = pk;
;               const float f0 = bflo(pk.x), f1 = bfhi(pk.x), f2 = bflo(pk.y), f3 = bfhi(pk.y);
;               ss += (f0 * f0 + f1 * f1) + (f2 * f2 + f3 * f3);
;             }
	v_pk_add_f32 v[48:49], v[52:53], v[48:49]
	s_nop 0
	v_mul_f32_e32 v52, 0xbfb8aa3b, v48
	v_mul_f32_e32 v53, 0xbfb8aa3b, v49
	v_exp_f32_e32 v52, v52
	v_exp_f32_e32 v53, v53
	v_pk_add_f32 v[50:51], v[54:55], v[50:51]
	v_add_f32_e32 v52, 1.0, v52
	v_add_f32_e32 v53, 1.0, v53
	v_rcp_f32_e32 v52, v52
	v_rcp_f32_e32 v53, v53
	s_nop 0
	v_pk_mul_f32 v[48:49], v[48:49], v[52:53]
	v_mul_f32_e32 v52, 0xbfb8aa3b, v50
	v_mul_f32_e32 v53, 0xbfb8aa3b, v51
	v_exp_f32_e32 v52, v52
	v_exp_f32_e32 v53, v53
	v_add_f32_e32 v52, 1.0, v52
	v_add_f32_e32 v53, 1.0, v53
	v_rcp_f32_e32 v52, v52
	v_rcp_f32_e32 v53, v53
	s_nop 0
	v_pk_mul_f32 v[50:51], v[50:51], v[52:53]
	v_cvt_pk_bf16_f32 v52, v48, v49
	v_cvt_pk_bf16_f32 v53, v50, v51
	v_add_u32_e32 v48, 0x4000, v131
	ds_write2_b64 v48, v[64:65], v[52:53] offset0:32 offset1:34
	global_load_dwordx4 v[50:53], v[128:129], off offset:64
	s_waitcnt vmcnt(0)
	v_pk_add_f32 v[50:51], v[56:57], v[50:51]
	s_nop 0
	v_mul_f32_e32 v49, 0xbfb8aa3b, v50
	v_exp_f32_e32 v49, v49
	v_pk_add_f32 v[52:53], v[58:59], v[52:53]
	v_add_f32_e32 v49, 1.0, v49
	v_rcp_f32_e32 v54, v49
	v_mul_f32_e32 v49, 0xbfb8aa3b, v51
	v_exp_f32_e32 v49, v49
	s_nop 0
	v_add_f32_e32 v49, 1.0, v49
	v_rcp_f32_e32 v55, v49
	v_mul_f32_e32 v49, 0xbfb8aa3b, v52
	v_exp_f32_e32 v49, v49
	v_pk_mul_f32 v[50:51], v[50:51], v[54:55]
	v_add_f32_e32 v49, 1.0, v49
	v_rcp_f32_e32 v54, v49
	v_mul_f32_e32 v49, 0xbfb8aa3b, v53
	v_exp_f32_e32 v49, v49
	s_nop 0
	v_add_f32_e32 v49, 1.0, v49
	v_rcp_f32_e32 v55, v49
	s_nop 0
	v_pk_mul_f32 v[52:53], v[52:53], v[54:55]
	v_cvt_pk_bf16_f32 v54, v50, v51
	v_cvt_pk_bf16_f32 v55, v52, v53
	global_load_dwordx4 v[50:53], v[128:129], off offset:96
	s_waitcnt vmcnt(0)
	v_pk_add_f32 v[50:51], v[60:61], v[50:51]
	s_nop 0
	v_mul_f32_e32 v49, 0xbfb8aa3b, v50
	v_exp_f32_e32 v49, v49
	v_pk_add_f32 v[52:53], v[62:63], v[52:53]
	v_add_f32_e32 v49, 1.0, v49
	v_rcp_f32_e32 v56, v49
	v_mul_f32_e32 v49, 0xbfb8aa3b, v51
	v_exp_f32_e32 v49, v49
	s_nop 0
	v_add_f32_e32 v49, 1.0, v49
	v_rcp_f32_e32 v57, v49
	v_mul_f32_e32 v49, 0xbfb8aa3b, v52
	v_exp_f32_e32 v49, v49
	v_pk_mul_f32 v[50:51], v[50:51], v[56:57]
	s_nop 0
	v_cvt_pk_bf16_f32 v50, v50, v51
	v_add_f32_e32 v49, 1.0, v49
	v_rcp_f32_e32 v56, v49
	v_mul_f32_e32 v49, 0xbfb8aa3b, v53
	v_exp_f32_e32 v49, v49
	s_nop 0
	v_add_f32_e32 v49, 1.0, v49
	v_rcp_f32_e32 v57, v49
	s_nop 0
	v_pk_mul_f32 v[52:53], v[52:53], v[56:57]
	s_nop 0
	v_cvt_pk_bf16_f32 v51, v52, v53
	ds_write2_b64 v48, v[54:55], v[50:51] offset0:36 offset1:38
	global_load_dwordx4 v[50:53], v[128:129], off offset:128
	s_waitcnt vmcnt(0)
	v_pk_add_f32 v[32:33], v[32:33], v[50:51]
	s_nop 0
	v_mul_f32_e32 v49, 0xbfb8aa3b, v32
	v_exp_f32_e32 v49, v49
	v_pk_add_f32 v[34:35], v[34:35], v[52:53]
	v_add_f32_e32 v49, 1.0, v49
	v_rcp_f32_e32 v50, v49
	v_mul_f32_e32 v49, 0xbfb8aa3b, v33
	v_exp_f32_e32 v49, v49
	s_nop 0
	v_add_f32_e32 v49, 1.0, v49
	v_rcp_f32_e32 v51, v49
	v_mul_f32_e32 v49, 0xbfb8aa3b, v34
	v_exp_f32_e32 v49, v49
	v_pk_mul_f32 v[32:33], v[32:33], v[50:51]
	v_add_f32_e32 v49, 1.0, v49
	v_rcp_f32_e32 v50, v49
	v_mul_f32_e32 v49, 0xbfb8aa3b, v35
	v_exp_f32_e32 v49, v49
	s_nop 0
	v_add_f32_e32 v49, 1.0, v49
	v_rcp_f32_e32 v51, v49
	s_nop 0
	v_pk_mul_f32 v[34:35], v[34:35], v[50:51]
	v_cvt_pk_bf16_f32 v50, v32, v33
	v_cvt_pk_bf16_f32 v51, v34, v35
	global_load_dwordx4 v[32:35], v[128:129], off offset:160
	s_waitcnt vmcnt(0)
	v_pk_add_f32 v[32:33], v[36:37], v[32:33]
	s_nop 0
	v_mul_f32_e32 v36, 0xbfb8aa3b, v32
	v_mul_f32_e32 v37, 0xbfb8aa3b, v33
	v_exp_f32_e32 v36, v36
	v_exp_f32_e32 v37, v37
	v_pk_add_f32 v[34:35], v[38:39], v[34:35]
	v_add_f32_e32 v36, 1.0, v36
	v_add_f32_e32 v37, 1.0, v37
	v_rcp_f32_e32 v36, v36
	v_rcp_f32_e32 v37, v37
	s_nop 0
	v_pk_mul_f32 v[32:33], v[32:33], v[36:37]
	v_mul_f32_e32 v36, 0xbfb8aa3b, v34
	v_mul_f32_e32 v37, 0xbfb8aa3b, v35
	v_exp_f32_e32 v36, v36
	v_exp_f32_e32 v37, v37
	v_cvt_pk_bf16_f32 v32, v32, v33
	v_add_f32_e32 v36, 1.0, v36
	v_add_f32_e32 v37, 1.0, v37
	v_rcp_f32_e32 v36, v36
	v_rcp_f32_e32 v37, v37
	s_nop 0
	v_pk_mul_f32 v[34:35], v[34:35], v[36:37]
	s_nop 0
	v_cvt_pk_bf16_f32 v33, v34, v35
	ds_write2_b64 v48, v[50:51], v[32:33] offset0:40 offset1:42
	global_load_dwordx4 v[32:35], v[128:129], off offset:192
	s_waitcnt vmcnt(0)
	v_pk_add_f32 v[32:33], v[40:41], v[32:33]
	s_nop 0
	v_mul_f32_e32 v36, 0xbfb8aa3b, v32
	v_mul_f32_e32 v37, 0xbfb8aa3b, v33
	v_exp_f32_e32 v36, v36
	v_exp_f32_e32 v37, v37
	v_pk_add_f32 v[34:35], v[42:43], v[34:35]
	v_add_f32_e32 v36, 1.0, v36
	v_add_f32_e32 v37, 1.0, v37
	v_rcp_f32_e32 v36, v36
	v_rcp_f32_e32 v37, v37
	s_nop 0
	v_pk_mul_f32 v[32:33], v[32:33], v[36:37]
	v_mul_f32_e32 v36, 0xbfb8aa3b, v34
	v_mul_f32_e32 v37, 0xbfb8aa3b, v35
	v_exp_f32_e32 v36, v36
	v_exp_f32_e32 v37, v37
	v_add_f32_e32 v36, 1.0, v36
	v_add_f32_e32 v37, 1.0, v37
	v_rcp_f32_e32 v36, v36
	v_rcp_f32_e32 v37, v37
	s_nop 0
	v_pk_mul_f32 v[34:35], v[34:35], v[36:37]
	v_cvt_pk_bf16_f32 v36, v32, v33
	v_cvt_pk_bf16_f32 v37, v34, v35
	global_load_dwordx4 v[32:35], v[128:129], off offset:224
	s_waitcnt vmcnt(0)
	v_pk_add_f32 v[32:33], v[44:45], v[32:33]
	s_nop 0
	v_mul_f32_e32 v38, 0xbfb8aa3b, v32
	v_mul_f32_e32 v39, 0xbfb8aa3b, v33
	v_exp_f32_e32 v38, v38
	v_exp_f32_e32 v39, v39
	v_pk_add_f32 v[34:35], v[46:47], v[34:35]
	v_add_f32_e32 v38, 1.0, v38
	v_add_f32_e32 v39, 1.0, v39
	v_rcp_f32_e32 v38, v38
	v_rcp_f32_e32 v39, v39
	s_nop 0
	v_pk_mul_f32 v[32:33], v[32:33], v[38:39]
	v_mul_f32_e32 v38, 0xbfb8aa3b, v34
	v_mul_f32_e32 v39, 0xbfb8aa3b, v35
	v_exp_f32_e32 v38, v38
	v_exp_f32_e32 v39, v39
	v_cvt_pk_bf16_f32 v32, v32, v33
	v_add_f32_e32 v38, 1.0, v38
	v_add_f32_e32 v39, 1.0, v39
	v_rcp_f32_e32 v38, v38
	v_rcp_f32_e32 v39, v39
	s_nop 0
	v_pk_mul_f32 v[34:35], v[34:35], v[38:39]
	s_nop 0
	v_cvt_pk_bf16_f32 v33, v34, v35
	ds_write2_b64 v48, v[36:37], v[32:33] offset0:44 offset1:46
	global_load_dwordx4 v[32:35], v[128:129], off offset:256
	s_waitcnt vmcnt(0)
; DI unsigned pack2(float a, float b) { f32x2_t v = {a, b}; bf16x2_t r = __builtin_convertvector(v, bf16x2_t); return __builtin_bit_cast(unsigned, r); }
; DI float bflo(unsigned u) { return __uint_as_float(u << 16); }
; DI float bfhi(unsigned u) { return __uint_as_float(u & 0xffff0000u); }
; DI float siluf_(float x) { return x * __builtin_amdgcn_rcpf(1.f + __expf(-x)); }
; DI void epi_seg(const f32x16 (&acc)[4][2], const Seg& sg0, const Seg& sg1, int m0, int n0, const float* rs, const float2* cs64, const float2* cs32, bf16_t* stg) {
;     ...
;       } else {
; #pragma unroll
;         for (int ch = 0; ch < 2; ++ch) {
;           float ss = 0.f;
; #pragma unroll
;           for (int i = 2 * ch; i < 2 * ch + 2; ++i)
; #pragma unroll
;             for (int q4 = 0; q4 < 4; ++q4) {
;               float v[4] = {acc[i][j][4 * q4] * sc, acc[i][j][4 * q4 + 1] * sc, acc[i][j][4 * q4 + 2] * sc, acc[i][j][4 * q4 + 3] * sc};
;               if (kind == K_SILU) {
;                 const f32x4 bv = *(const f32x4*)(sg.bias + lcw + i * 32 + 8 * q4 + 4 * h);
;                 v[0] = siluf_(v[0] + bv.x); v[1] = siluf_(v[1] + bv.y); v[2] = siluf_(v[2] + bv.z); v[3] = siluf_(v[3] + bv.w);
;               }
;               const uint2 pk = make_uint2(pack2(v[0], v[1]), pack2(v[2], v[3]));
;               *(uint2*)(srow + i * 32 + 8 * q4) = pk;
;               const float f0 = bflo(pk.x), f1 = bfhi(pk.x), f2 = bflo(pk.y), f3 = bfhi(pk.y);
;               ss += (f0 * f0 + f1 * f1) + (f2 * f2 + f3 * f3);
;             }
;     ...
; #pragma unroll
;   for (int it = 0; it < 16; ++it) {
;     const int idx = tid + NTHR * it, rr = idx >> 5, c = idx & 31;
;     const Seg& fs = (c >> 4) ? sg1 : sg0;
;     const int lcc = n0 + c * 8 - fs.cbase;
	v_pk_add_f32 v[16:17], v[16:17], v[32:33]
	s_nop 0
	v_mul_f32_e32 v32, 0xbfb8aa3b, v16
	v_mul_f32_e32 v33, 0xbfb8aa3b, v17
	v_exp_f32_e32 v32, v32
	v_exp_f32_e32 v33, v33
	v_pk_add_f32 v[18:19], v[18:19], v[34:35]
	v_add_f32_e32 v32, 1.0, v32
	v_add_f32_e32 v33, 1.0, v33
	v_rcp_f32_e32 v32, v32
	v_rcp_f32_e32 v33, v33
	s_nop 0
	v_pk_mul_f32 v[16:17], v[16:17], v[32:33]
	v_mul_f32_e32 v32, 0xbfb8aa3b, v18
	v_mul_f32_e32 v33, 0xbfb8aa3b, v19
	v_exp_f32_e32 v32, v32
	v_exp_f32_e32 v33, v33
	v_add_f32_e32 v32, 1.0, v32
	v_add_f32_e32 v33, 1.0, v33
	v_rcp_f32_e32 v32, v32
	v_rcp_f32_e32 v33, v33
	s_nop 0
	v_pk_mul_f32 v[18:19], v[18:19], v[32:33]
	v_cvt_pk_bf16_f32 v32, v16, v17
	v_cvt_pk_bf16_f32 v33, v18, v19
	global_load_dwordx4 v[16:19], v[128:129], off offset:288
	s_waitcnt vmcnt(0)
	v_pk_add_f32 v[16:17], v[20:21], v[16:17]
	s_nop 0
	v_mul_f32_e32 v20, 0xbfb8aa3b, v16
	v_mul_f32_e32 v21, 0xbfb8aa3b, v17
	v_exp_f32_e32 v20, v20
	v_exp_f32_e32 v21, v21
	v_pk_add_f32 v[18:19], v[22:23], v[18:19]
	v_add_f32_e32 v20, 1.0, v20
	v_add_f32_e32 v21, 1.0, v21
	v_rcp_f32_e32 v20, v20
	v_rcp_f32_e32 v21, v21
	s_nop 0
	v_pk_mul_f32 v[16:17], v[16:17], v[20:21]
	v_mul_f32_e32 v20, 0xbfb8aa3b, v18
	v_mul_f32_e32 v21, 0xbfb8aa3b, v19
	v_exp_f32_e32 v20, v20
	v_exp_f32_e32 v21, v21
	v_cvt_pk_bf16_f32 v16, v16, v17
	v_add_f32_e32 v20, 1.0, v20
	v_add_f32_e32 v21, 1.0, v21
	v_rcp_f32_e32 v20, v20
	v_rcp_f32_e32 v21, v21
	s_nop 0
	v_pk_mul_f32 v[18:19], v[18:19], v[20:21]
	s_nop 0
	v_cvt_pk_bf16_f32 v17, v18, v19
	ds_write2_b64 v48, v[32:33], v[16:17] offset0:48 offset1:50
	global_load_dwordx4 v[16:19], v[128:129], off offset:320
	s_waitcnt vmcnt(0)
	v_pk_add_f32 v[16:17], v[24:25], v[16:17]
	s_nop 0
	v_mul_f32_e32 v20, 0xbfb8aa3b, v16
	v_mul_f32_e32 v21, 0xbfb8aa3b, v17
	v_exp_f32_e32 v20, v20
	v_exp_f32_e32 v21, v21
	v_pk_add_f32 v[18:19], v[26:27], v[18:19]
	v_add_f32_e32 v20, 1.0, v20
	v_add_f32_e32 v21, 1.0, v21
	v_rcp_f32_e32 v20, v20
	v_rcp_f32_e32 v21, v21
	s_nop 0
	v_pk_mul_f32 v[16:17], v[16:17], v[20:21]
	v_mul_f32_e32 v20, 0xbfb8aa3b, v18
	v_mul_f32_e32 v21, 0xbfb8aa3b, v19
	v_exp_f32_e32 v20, v20
	v_exp_f32_e32 v21, v21
	v_add_f32_e32 v20, 1.0, v20
	v_add_f32_e32 v21, 1.0, v21
	v_rcp_f32_e32 v20, v20
	v_rcp_f32_e32 v21, v21
	s_nop 0
	v_pk_mul_f32 v[18:19], v[18:19], v[20:21]
	v_cvt_pk_bf16_f32 v20, v16, v17
	v_cvt_pk_bf16_f32 v21, v18, v19
	global_load_dwordx4 v[16:19], v[128:129], off offset:352
	s_waitcnt vmcnt(0)
	v_pk_add_f32 v[16:17], v[28:29], v[16:17]
	s_nop 0
	v_mul_f32_e32 v22, 0xbfb8aa3b, v16
	v_mul_f32_e32 v23, 0xbfb8aa3b, v17
	v_exp_f32_e32 v22, v22
	v_exp_f32_e32 v23, v23
	v_pk_add_f32 v[18:19], v[30:31], v[18:19]
	v_add_f32_e32 v22, 1.0, v22
	v_add_f32_e32 v23, 1.0, v23
	v_rcp_f32_e32 v22, v22
	v_rcp_f32_e32 v23, v23
	s_nop 0
	v_pk_mul_f32 v[16:17], v[16:17], v[22:23]
	v_mul_f32_e32 v22, 0xbfb8aa3b, v18
	v_mul_f32_e32 v23, 0xbfb8aa3b, v19
	v_exp_f32_e32 v22, v22
	v_exp_f32_e32 v23, v23
	v_cvt_pk_bf16_f32 v16, v16, v17
	v_add_f32_e32 v22, 1.0, v22
	v_add_f32_e32 v23, 1.0, v23
	v_rcp_f32_e32 v22, v22
	v_rcp_f32_e32 v23, v23
	s_nop 0
	v_pk_mul_f32 v[18:19], v[18:19], v[22:23]
	s_nop 0
	v_cvt_pk_bf16_f32 v17, v18, v19
	ds_write2_b64 v48, v[20:21], v[16:17] offset0:52 offset1:54
	global_load_dwordx4 v[16:19], v[128:129], off offset:384
	s_waitcnt vmcnt(0)
	v_pk_add_f32 v[0:1], v[0:1], v[16:17]
	s_nop 0
	v_mul_f32_e32 v16, 0xbfb8aa3b, v0
	v_mul_f32_e32 v17, 0xbfb8aa3b, v1
	v_exp_f32_e32 v16, v16
	v_exp_f32_e32 v17, v17
	v_pk_add_f32 v[2:3], v[2:3], v[18:19]
	v_add_f32_e32 v16, 1.0, v16
	v_add_f32_e32 v17, 1.0, v17
	v_rcp_f32_e32 v16, v16
	v_rcp_f32_e32 v17, v17
	s_nop 0
	v_pk_mul_f32 v[0:1], v[0:1], v[16:17]
	v_mul_f32_e32 v16, 0xbfb8aa3b, v2
	v_mul_f32_e32 v17, 0xbfb8aa3b, v3
	v_exp_f32_e32 v16, v16
	v_exp_f32_e32 v17, v17
	v_add_f32_e32 v16, 1.0, v16
	v_add_f32_e32 v17, 1.0, v17
	v_rcp_f32_e32 v16, v16
	v_rcp_f32_e32 v17, v17
	s_nop 0
	v_pk_mul_f32 v[2:3], v[2:3], v[16:17]
	v_cvt_pk_bf16_f32 v16, v0, v1
	v_cvt_pk_bf16_f32 v17, v2, v3
	global_load_dwordx4 v[0:3], v[128:129], off offset:416
	s_waitcnt vmcnt(0)
	v_pk_add_f32 v[0:1], v[4:5], v[0:1]
	s_nop 0
	v_mul_f32_e32 v4, 0xbfb8aa3b, v0
	v_mul_f32_e32 v5, 0xbfb8aa3b, v1
	v_exp_f32_e32 v4, v4
	v_exp_f32_e32 v5, v5
	v_pk_add_f32 v[2:3], v[6:7], v[2:3]
	v_add_f32_e32 v4, 1.0, v4
	v_add_f32_e32 v5, 1.0, v5
	v_rcp_f32_e32 v4, v4
	v_rcp_f32_e32 v5, v5
	s_nop 0
	v_pk_mul_f32 v[0:1], v[0:1], v[4:5]
	v_mul_f32_e32 v4, 0xbfb8aa3b, v2
	v_mul_f32_e32 v5, 0xbfb8aa3b, v3
	v_exp_f32_e32 v4, v4
	v_exp_f32_e32 v5, v5
	v_cvt_pk_bf16_f32 v0, v0, v1
	v_add_f32_e32 v4, 1.0, v4
	v_add_f32_e32 v5, 1.0, v5
	v_rcp_f32_e32 v4, v4
	v_rcp_f32_e32 v5, v5
	s_nop 0
	v_pk_mul_f32 v[2:3], v[2:3], v[4:5]
	s_nop 0
	v_cvt_pk_bf16_f32 v1, v2, v3
	ds_write2_b64 v48, v[16:17], v[0:1] offset0:56 offset1:58
	global_load_dwordx4 v[0:3], v[128:129], off offset:448
	s_waitcnt vmcnt(0)
	v_pk_add_f32 v[0:1], v[8:9], v[0:1]
	s_nop 0
	v_mul_f32_e32 v4, 0xbfb8aa3b, v0
	v_mul_f32_e32 v5, 0xbfb8aa3b, v1
	v_exp_f32_e32 v4, v4
	v_exp_f32_e32 v5, v5
	v_pk_add_f32 v[2:3], v[10:11], v[2:3]
	v_add_f32_e32 v4, 1.0, v4
	v_add_f32_e32 v5, 1.0, v5
	v_rcp_f32_e32 v4, v4
	v_rcp_f32_e32 v5, v5
	s_nop 0
	v_pk_mul_f32 v[0:1], v[0:1], v[4:5]
	v_mul_f32_e32 v4, 0xbfb8aa3b, v2
	v_mul_f32_e32 v5, 0xbfb8aa3b, v3
	v_exp_f32_e32 v4, v4
	v_exp_f32_e32 v5, v5
	v_add_f32_e32 v4, 1.0, v4
	v_add_f32_e32 v5, 1.0, v5
	v_rcp_f32_e32 v4, v4
	v_rcp_f32_e32 v5, v5
	s_nop 0
	v_pk_mul_f32 v[2:3], v[2:3], v[4:5]
	v_cvt_pk_bf16_f32 v4, v0, v1
	v_cvt_pk_bf16_f32 v5, v2, v3
	global_load_dwordx4 v[0:3], v[128:129], off offset:480
	s_waitcnt vmcnt(0)
	v_pk_add_f32 v[0:1], v[12:13], v[0:1]
	s_nop 0
	v_mul_f32_e32 v6, 0xbfb8aa3b, v0
	v_mul_f32_e32 v7, 0xbfb8aa3b, v1
	v_exp_f32_e32 v6, v6
	v_exp_f32_e32 v7, v7
	v_pk_add_f32 v[2:3], v[14:15], v[2:3]
	v_add_f32_e32 v6, 1.0, v6
	v_add_f32_e32 v7, 1.0, v7
	v_rcp_f32_e32 v6, v6
	v_rcp_f32_e32 v7, v7
	s_nop 0
	v_pk_mul_f32 v[0:1], v[0:1], v[6:7]
	v_mul_f32_e32 v6, 0xbfb8aa3b, v2
	v_mul_f32_e32 v7, 0xbfb8aa3b, v3
	v_exp_f32_e32 v6, v6
	v_exp_f32_e32 v7, v7
	v_cvt_pk_bf16_f32 v0, v0, v1
	v_add_f32_e32 v6, 1.0, v6
	v_add_f32_e32 v7, 1.0, v7
	v_rcp_f32_e32 v6, v6
	v_rcp_f32_e32 v7, v7
	s_nop 0
	v_pk_mul_f32 v[2:3], v[2:3], v[6:7]
	s_nop 0
	v_cvt_pk_bf16_f32 v1, v2, v3
	ds_write2_b64 v48, v[4:5], v[0:1] offset0:60 offset1:62
	v_lshlrev_b32_e32 v0, 4, v130
	v_ashrrev_i32_e32 v2, 5, v130
	v_and_b32_e32 v160, 0x1f0, v0
	v_add_u32_e32 v0, s34, v2
	v_ashrrev_i32_e32 v1, 31, v0
	v_lshlrev_b64 v[0:1], 9, v[0:1]
	v_lshl_add_u64 v[0:1], s[10:11], 0, v[0:1]
	v_lshl_add_u64 v[4:5], v[0:1], 0, v[160:161]
	v_mad_u64_u32 v[0:1], s[12:13], v2, s31, v[160:161]
	s_waitcnt lgkmcnt(0)
	s_barrier
; DI void stg16_nt(void* p, u32x4 v) { __builtin_nontemporal_store(v, (u32x4*)p); }
; DI void epi_seg(const f32x16 (&acc)[4][2], const Seg& sg0, const Seg& sg1, int m0, int n0, const float* rs, const float2* cs64, const float2* cs32, bf16_t* stg) {
;     ...
; #pragma unroll
;   for (int it = 0; it < 16; ++it) {
;     const int idx = tid + NTHR * it, rr = idx >> 5, c = idx & 31;
;     const Seg& fs = (c >> 4) ? sg1 : sg0;
;     const int lcc = n0 + c * 8 - fs.cbase;
;     if (fs.kind != K_NONE && lcc < fs.nvalid) {
;       const int row = m0 + rr;
;       size_t off;
;       if (fs.kind == K_KC2) { const int b = row >> 9, n = (row >> 2) & 127, g = row & 3; off = ((size_t)((b * 4 + g) * 128 + n)) * 64 + lcc; }
;       else off = (size_t)row * fs.ld + lcc;
;       stg16_nt(fs.dst + off, stage_read16(stg, rr, c));
;     }
;   }
	ds_read2_b64 v[0:3], v0 offset1:1
	s_waitcnt lgkmcnt(0)
	global_store_dwordx4 v[4:5], v[0:3], off
	s_nop 1
	v_add_u32_e32 v0, 0x200, v130
	v_ashrrev_i32_e32 v2, 5, v0
	v_add_u32_e32 v0, s34, v2
	v_ashrrev_i32_e32 v1, 31, v0
	v_lshlrev_b64 v[0:1], 9, v[0:1]
	v_lshl_add_u64 v[0:1], s[10:11], 0, v[0:1]
	v_lshl_add_u64 v[4:5], v[0:1], 0, v[160:161]
	v_mad_u64_u32 v[0:1], s[12:13], v2, s31, v[160:161]
	ds_read2_b64 v[0:3], v0 offset1:1
	s_waitcnt lgkmcnt(0)
	global_store_dwordx4 v[4:5], v[0:3], off
	s_nop 1
	v_add_u32_e32 v0, 0x400, v130
	v_ashrrev_i32_e32 v2, 5, v0
	v_add_u32_e32 v0, s34, v2
	v_ashrrev_i32_e32 v1, 31, v0
	v_lshlrev_b64 v[0:1], 9, v[0:1]
	v_lshl_add_u64 v[0:1], s[10:11], 0, v[0:1]
	v_lshl_add_u64 v[4:5], v[0:1], 0, v[160:161]
	v_mad_u64_u32 v[0:1], s[12:13], v2, s31, v[160:161]
	ds_read2_b64 v[0:3], v0 offset1:1
	s_waitcnt lgkmcnt(0)
	global_store_dwordx4 v[4:5], v[0:3], off
	s_nop 1
	v_add_u32_e32 v0, 0x600, v130
	v_ashrrev_i32_e32 v2, 5, v0
	v_add_u32_e32 v0, s34, v2
	v_ashrrev_i32_e32 v1, 31, v0
	v_lshlrev_b64 v[0:1], 9, v[0:1]
	v_lshl_add_u64 v[0:1], s[10:11], 0, v[0:1]
	v_lshl_add_u64 v[4:5], v[0:1], 0, v[160:161]
	v_mad_u64_u32 v[0:1], s[12:13], v2, s31, v[160:161]
	ds_read2_b64 v[0:3], v0 offset1:1
	s_waitcnt lgkmcnt(0)
	global_store_dwordx4 v[4:5], v[0:3], off
	s_nop 1
	v_add_u32_e32 v0, 0x800, v130
	v_ashrrev_i32_e32 v2, 5, v0
	v_add_u32_e32 v0, s34, v2
	v_ashrrev_i32_e32 v1, 31, v0
	v_lshlrev_b64 v[0:1], 9, v[0:1]
	v_lshl_add_u64 v[0:1], s[10:11], 0, v[0:1]
	v_lshl_add_u64 v[4:5], v[0:1], 0, v[160:161]
	v_mad_u64_u32 v[0:1], s[12:13], v2, s31, v[160:161]
	ds_read2_b64 v[0:3], v0 offset1:1
	s_waitcnt lgkmcnt(0)
	global_store_dwordx4 v[4:5], v[0:3], off
	s_nop 1
	v_add_u32_e32 v0, 0xa00, v130
	v_ashrrev_i32_e32 v2, 5, v0
	v_add_u32_e32 v0, s34, v2
	v_ashrrev_i32_e32 v1, 31, v0
	v_lshlrev_b64 v[0:1], 9, v[0:1]
	v_lshl_add_u64 v[0:1], s[10:11], 0, v[0:1]
	v_lshl_add_u64 v[4:5], v[0:1], 0, v[160:161]
	v_mad_u64_u32 v[0:1], s[12:13], v2, s31, v[160:161]
	ds_read2_b64 v[0:3], v0 offset1:1
	s_waitcnt lgkmcnt(0)
	global_store_dwordx4 v[4:5], v[0:3], off
	s_nop 1
	v_add_u32_e32 v0, 0xc00, v130
	v_ashrrev_i32_e32 v2, 5, v0
	v_add_u32_e32 v0, s34, v2
	v_ashrrev_i32_e32 v1, 31, v0
	v_lshlrev_b64 v[0:1], 9, v[0:1]
	v_lshl_add_u64 v[0:1], s[10:11], 0, v[0:1]
	v_lshl_add_u64 v[4:5], v[0:1], 0, v[160:161]
	v_mad_u64_u32 v[0:1], s[12:13], v2, s31, v[160:161]
	ds_read2_b64 v[0:3], v0 offset1:1
	s_waitcnt lgkmcnt(0)
	global_store_dwordx4 v[4:5], v[0:3], off
	s_nop 1
	v_add_u32_e32 v0, 0xe00, v130
	v_ashrrev_i32_e32 v2, 5, v0
	v_add_u32_e32 v0, s34, v2
	v_ashrrev_i32_e32 v1, 31, v0
	v_lshlrev_b64 v[0:1], 9, v[0:1]
	v_lshl_add_u64 v[0:1], s[10:11], 0, v[0:1]
	v_lshl_add_u64 v[4:5], v[0:1], 0, v[160:161]
	v_mad_u64_u32 v[0:1], s[12:13], v2, s31, v[160:161]
	ds_read2_b64 v[0:3], v0 offset1:1
	s_waitcnt lgkmcnt(0)
	global_store_dwordx4 v[4:5], v[0:3], off
	s_nop 1
	v_add_u32_e32 v0, 0x1000, v130
	v_ashrrev_i32_e32 v2, 5, v0
	v_add_u32_e32 v0, s34, v2
	v_ashrrev_i32_e32 v1, 31, v0
	v_lshlrev_b64 v[0:1], 9, v[0:1]
	v_lshl_add_u64 v[0:1], s[10:11], 0, v[0:1]
	v_lshl_add_u64 v[4:5], v[0:1], 0, v[160:161]
	v_mad_u64_u32 v[0:1], s[12:13], v2, s31, v[160:161]
	ds_read2_b64 v[0:3], v0 offset1:1
	s_waitcnt lgkmcnt(0)
	global_store_dwordx4 v[4:5], v[0:3], off
	s_nop 1
	v_add_u32_e32 v0, 0x1200, v130
	v_ashrrev_i32_e32 v2, 5, v0
	v_add_u32_e32 v0, s34, v2
	v_ashrrev_i32_e32 v1, 31, v0
	v_lshlrev_b64 v[0:1], 9, v[0:1]
	v_lshl_add_u64 v[0:1], s[10:11], 0, v[0:1]
	v_lshl_add_u64 v[4:5], v[0:1], 0, v[160:161]
	v_mad_u64_u32 v[0:1], s[12:13], v2, s31, v[160:161]
	ds_read2_b64 v[0:3], v0 offset1:1
	s_waitcnt lgkmcnt(0)
	global_store_dwordx4 v[4:5], v[0:3], off
	s_nop 1
	v_add_u32_e32 v0, 0x1400, v130
	v_ashrrev_i32_e32 v2, 5, v0
	v_add_u32_e32 v0, s34, v2
	v_ashrrev_i32_e32 v1, 31, v0
	v_lshlrev_b64 v[0:1], 9, v[0:1]
	v_lshl_add_u64 v[0:1], s[10:11], 0, v[0:1]
	v_lshl_add_u64 v[4:5], v[0:1], 0, v[160:161]
	v_mad_u64_u32 v[0:1], s[12:13], v2, s31, v[160:161]
	ds_read2_b64 v[0:3], v0 offset1:1
	s_waitcnt lgkmcnt(0)
	global_store_dwordx4 v[4:5], v[0:3], off
	s_nop 1
	v_add_u32_e32 v0, 0x1600, v130
	v_ashrrev_i32_e32 v2, 5, v0
	v_add_u32_e32 v0, s34, v2
	v_ashrrev_i32_e32 v1, 31, v0
	v_lshlrev_b64 v[0:1], 9, v[0:1]
	v_lshl_add_u64 v[0:1], s[10:11], 0, v[0:1]
	v_lshl_add_u64 v[4:5], v[0:1], 0, v[160:161]
	v_mad_u64_u32 v[0:1], s[12:13], v2, s31, v[160:161]
	ds_read2_b64 v[0:3], v0 offset1:1
	s_waitcnt lgkmcnt(0)
	global_store_dwordx4 v[4:5], v[0:3], off
	s_nop 1
	v_add_u32_e32 v0, 0x1800, v130
	v_ashrrev_i32_e32 v2, 5, v0
	v_add_u32_e32 v0, s34, v2
	v_ashrrev_i32_e32 v1, 31, v0
	v_lshlrev_b64 v[0:1], 9, v[0:1]
	v_lshl_add_u64 v[0:1], s[10:11], 0, v[0:1]
	v_lshl_add_u64 v[4:5], v[0:1], 0, v[160:161]
	v_mad_u64_u32 v[0:1], s[12:13], v2, s31, v[160:161]
	ds_read2_b64 v[0:3], v0 offset1:1
	s_waitcnt lgkmcnt(0)
	global_store_dwordx4 v[4:5], v[0:3], off
	s_nop 1
	v_add_u32_e32 v0, 0x1a00, v130
	v_ashrrev_i32_e32 v2, 5, v0
	v_add_u32_e32 v0, s34, v2
	v_ashrrev_i32_e32 v1, 31, v0
	v_lshlrev_b64 v[0:1], 9, v[0:1]
	v_lshl_add_u64 v[0:1], s[10:11], 0, v[0:1]
	v_lshl_add_u64 v[4:5], v[0:1], 0, v[160:161]
	v_mad_u64_u32 v[0:1], s[12:13], v2, s31, v[160:161]
	ds_read2_b64 v[0:3], v0 offset1:1
	s_waitcnt lgkmcnt(0)
	global_store_dwordx4 v[4:5], v[0:3], off
	s_nop 1
	v_add_u32_e32 v0, 0x1c00, v130
	v_ashrrev_i32_e32 v2, 5, v0
	v_add_u32_e32 v0, s34, v2
	v_ashrrev_i32_e32 v1, 31, v0
	v_lshlrev_b64 v[0:1], 9, v[0:1]
	v_lshl_add_u64 v[0:1], s[10:11], 0, v[0:1]
	v_lshl_add_u64 v[4:5], v[0:1], 0, v[160:161]
	v_mad_u64_u32 v[0:1], s[12:13], v2, s31, v[160:161]
	ds_read2_b64 v[0:3], v0 offset1:1
	s_waitcnt lgkmcnt(0)
	global_store_dwordx4 v[4:5], v[0:3], off
	s_nop 1
	v_add_u32_e32 v0, 0x1e00, v130
	v_ashrrev_i32_e32 v2, 5, v0
	v_add_u32_e32 v0, s34, v2
	v_ashrrev_i32_e32 v1, 31, v0
	v_lshlrev_b64 v[0:1], 9, v[0:1]
	v_lshl_add_u64 v[0:1], s[10:11], 0, v[0:1]
	v_lshl_add_u64 v[4:5], v[0:1], 0, v[160:161]
	v_mad_u64_u32 v[0:1], s[10:11], v2, s31, v[160:161]
	ds_read2_b64 v[0:3], v0 offset1:1
	s_waitcnt lgkmcnt(0)
	global_store_dwordx4 v[4:5], v[0:3], off
	s_barrier
	s_cbranch_scc1 .LBB0_1121

; DI void stg16_nt(void* p, u32x4 v) { __builtin_nontemporal_store(v, (u32x4*)p); }
; DI void epi_seg(const f32x16 (&acc)[4][2], const Seg& sg0, const Seg& sg1, int m0, int n0, const float* rs, const float2* cs64, const float2* cs32, bf16_t* stg) {
;     ...
; #pragma unroll
;   for (int it = 0; it < 16; ++it) {
;     const int idx = tid + NTHR * it, rr = idx >> 5, c = idx & 31;
;     const Seg& fs = (c >> 4) ? sg1 : sg0;
;     const int lcc = n0 + c * 8 - fs.cbase;
;     if (fs.kind != K_NONE && lcc < fs.nvalid) {
;       const int row = m0 + rr;
;       size_t off;
;       if (fs.kind == K_KC2) { const int b = row >> 9, n = (row >> 2) & 127, g = row & 3; off = ((size_t)((b * 4 + g) * 128 + n)) * 64 + lcc; }
;       else off = (size_t)row * fs.ld + lcc;
;       stg16_nt(fs.dst + off, stage_read16(stg, rr, c));
;     }
;   }
.LBB0_1183:
	s_or_b64 exec, exec, s[0:1]
	v_cmp_gt_u32_e32 vcc, 16, v166
	v_lshlrev_b32_e32 v130, 3, v166
	v_and_b32_e32 v131, 24, v169
	v_cndmask_b32_e64 v129, 7, 5, vcc
	v_lshlrev_b32_e32 v128, 4, v166
	v_cmp_eq_u32_e32 vcc, 0, v131
	v_lshlrev_b32_e32 v160, 1, v130
	v_mov_b32_e32 v130, v129
	s_waitcnt lgkmcnt(0)
	s_barrier
	s_and_saveexec_b64 s[0:1], vcc
	s_cbranch_execz .LBB0_1185
	v_ashrrev_i32_e32 v131, 5, v169
	v_add_u32_e32 v132, s30, v131
	v_lshlrev_b32_e32 v134, 7, v131
	v_bfe_u32 v133, v132, 2, 7
	v_and_b32_e32 v134, 0x180, v134
	v_and_b32_e32 v132, 0xfffffe00, v132
	v_or3_b32 v136, v134, v132, v133
	v_mad_u64_u32 v[132:133], s[10:11], v131, s26, v[128:129]
	ds_read2_b64 v[132:135], v132 offset1:1
	v_ashrrev_i32_e32 v137, 31, v136
	v_lshlrev_b64 v[136:137], 7, v[136:137]
	v_lshl_add_u64 v[136:137], s[8:9], 0, v[136:137]
	v_mov_b32_e32 v130, 5
	v_lshl_add_u64 v[136:137], v[136:137], 0, v[160:161]
	s_waitcnt lgkmcnt(0)
	global_store_dwordx4 v[136:137], v[132:135], off
.LBB0_1185:
	s_or_b64 exec, exec, s[0:1]
	v_cmp_gt_u32_e32 vcc, 8, v166
	v_cmp_ne_u32_e64 s[0:1], 7, v130
	s_and_b64 s[0:1], s[0:1], vcc
	s_and_saveexec_b64 s[10:11], s[0:1]
	s_cbranch_execz .LBB0_1187
	v_add_u32_e32 v131, 0x200, v169
	v_ashrrev_i32_e32 v131, 5, v131
	v_add_u32_e32 v132, s30, v131
	v_lshlrev_b32_e32 v134, 7, v131
	v_bfe_u32 v133, v132, 2, 7
	v_and_b32_e32 v134, 0x180, v134
	v_and_b32_e32 v135, 0xfffffe00, v132
	v_or3_b32 v133, v134, v135, v133
	v_cmp_eq_u32_e64 s[0:1], 5, v130
	s_nop 1
	v_cndmask_b32_e64 v134, v132, v133, s[0:1]
	v_mad_u64_u32 v[130:131], s[0:1], v131, s26, v[128:129]
	ds_read2_b64 v[130:133], v130 offset1:1
	v_ashrrev_i32_e32 v135, 31, v134
	v_lshlrev_b64 v[134:135], 7, v[134:135]
	v_lshl_add_u64 v[134:135], s[8:9], 0, v[134:135]
	v_lshl_add_u64 v[134:135], v[134:135], 0, v[160:161]
	s_waitcnt lgkmcnt(0)
	global_store_dwordx4 v[134:135], v[130:133], off
	s_nop 1
	v_mov_b32_e32 v130, v129
.LBB0_1187:
	s_or_b64 exec, exec, s[10:11]
	v_cmp_ne_u32_e64 s[0:1], 7, v130
	s_and_b64 s[0:1], s[0:1], vcc
	s_and_saveexec_b64 s[10:11], s[0:1]
	s_cbranch_execz .LBB0_1189
	v_add_u32_e32 v131, 0x400, v169
	v_ashrrev_i32_e32 v131, 5, v131
	v_add_u32_e32 v132, s30, v131
	v_lshlrev_b32_e32 v134, 7, v131
	v_bfe_u32 v133, v132, 2, 7
	v_and_b32_e32 v134, 0x180, v134
	v_and_b32_e32 v135, 0xfffffe00, v132
	v_or3_b32 v133, v134, v135, v133
	v_cmp_eq_u32_e64 s[0:1], 5, v130
	s_nop 1
	v_cndmask_b32_e64 v134, v132, v133, s[0:1]
	v_mad_u64_u32 v[130:131], s[0:1], v131, s26, v[128:129]
	ds_read2_b64 v[130:133], v130 offset1:1
	v_ashrrev_i32_e32 v135, 31, v134
	v_lshlrev_b64 v[134:135], 7, v[134:135]
	v_lshl_add_u64 v[134:135], s[8:9], 0, v[134:135]
	v_lshl_add_u64 v[134:135], v[134:135], 0, v[160:161]
	s_waitcnt lgkmcnt(0)
	global_store_dwordx4 v[134:135], v[130:133], off
	s_nop 1
	v_mov_b32_e32 v130, v129
.LBB0_1189:
	s_or_b64 exec, exec, s[10:11]
	v_cmp_ne_u32_e64 s[0:1], 7, v130
	s_and_b64 s[0:1], s[0:1], vcc
	s_and_saveexec_b64 s[10:11], s[0:1]
	s_cbranch_execz .LBB0_1191
	v_add_u32_e32 v131, 0x600, v169
	v_ashrrev_i32_e32 v131, 5, v131
	v_add_u32_e32 v132, s30, v131
	v_lshlrev_b32_e32 v134, 7, v131
	v_bfe_u32 v133, v132, 2, 7
	v_and_b32_e32 v134, 0x180, v134
	v_and_b32_e32 v135, 0xfffffe00, v132
	v_or3_b32 v133, v134, v135, v133
	v_cmp_eq_u32_e64 s[0:1], 5, v130
	s_nop 1
	v_cndmask_b32_e64 v134, v132, v133, s[0:1]
	v_mad_u64_u32 v[130:131], s[0:1], v131, s26, v[128:129]
	ds_read2_b64 v[130:133], v130 offset1:1
	v_ashrrev_i32_e32 v135, 31, v134
	v_lshlrev_b64 v[134:135], 7, v[134:135]
	v_lshl_add_u64 v[134:135], s[8:9], 0, v[134:135]
	v_lshl_add_u64 v[134:135], v[134:135], 0, v[160:161]
	s_waitcnt lgkmcnt(0)
	global_store_dwordx4 v[134:135], v[130:133], off
	s_nop 1
	v_mov_b32_e32 v130, v129
.LBB0_1191:
	s_or_b64 exec, exec, s[10:11]
	v_cmp_ne_u32_e64 s[0:1], 7, v130
	s_and_b64 s[0:1], s[0:1], vcc
	s_and_saveexec_b64 s[10:11], s[0:1]
	s_cbranch_execz .LBB0_1193
	v_add_u32_e32 v131, 0x800, v169
	v_ashrrev_i32_e32 v131, 5, v131
	v_add_u32_e32 v132, s30, v131
	v_lshlrev_b32_e32 v134, 7, v131
	v_bfe_u32 v133, v132, 2, 7
	v_and_b32_e32 v134, 0x180, v134
	v_and_b32_e32 v135, 0xfffffe00, v132
	v_or3_b32 v133, v134, v135, v133
	v_cmp_eq_u32_e64 s[0:1], 5, v130
	s_nop 1
	v_cndmask_b32_e64 v134, v132, v133, s[0:1]
	v_mad_u64_u32 v[130:131], s[0:1], v131, s26, v[128:129]
	ds_read2_b64 v[130:133], v130 offset1:1
	v_ashrrev_i32_e32 v135, 31, v134
	v_lshlrev_b64 v[134:135], 7, v[134:135]
	v_lshl_add_u64 v[134:135], s[8:9], 0, v[134:135]
	v_lshl_add_u64 v[134:135], v[134:135], 0, v[160:161]
	s_waitcnt lgkmcnt(0)
	global_store_dwordx4 v[134:135], v[130:133], off
	s_nop 1
	v_mov_b32_e32 v130, v129
.LBB0_1193:
	s_or_b64 exec, exec, s[10:11]
	v_cmp_ne_u32_e64 s[0:1], 7, v130
	s_and_b64 s[0:1], s[0:1], vcc
	s_and_saveexec_b64 s[10:11], s[0:1]
	s_cbranch_execz .LBB0_1195
	v_add_u32_e32 v131, 0xa00, v169
	v_ashrrev_i32_e32 v131, 5, v131
	v_add_u32_e32 v132, s30, v131
	v_lshlrev_b32_e32 v134, 7, v131
	v_bfe_u32 v133, v132, 2, 7
	v_and_b32_e32 v134, 0x180, v134
	v_and_b32_e32 v135, 0xfffffe00, v132
	v_or3_b32 v133, v134, v135, v133
	v_cmp_eq_u32_e64 s[0:1], 5, v130
	s_nop 1
	v_cndmask_b32_e64 v134, v132, v133, s[0:1]
	v_mad_u64_u32 v[130:131], s[0:1], v131, s26, v[128:129]
	ds_read2_b64 v[130:133], v130 offset1:1
	v_ashrrev_i32_e32 v135, 31, v134
	v_lshlrev_b64 v[134:135], 7, v[134:135]
	v_lshl_add_u64 v[134:135], s[8:9], 0, v[134:135]
	v_lshl_add_u64 v[134:135], v[134:135], 0, v[160:161]
	s_waitcnt lgkmcnt(0)
	global_store_dwordx4 v[134:135], v[130:133], off
	s_nop 1
	v_mov_b32_e32 v130, v129
; DI void stg16_nt(void* p, u32x4 v) { __builtin_nontemporal_store(v, (u32x4*)p); }
; DI void epi_seg(const f32x16 (&acc)[4][2], const Seg& sg0, const Seg& sg1, int m0, int n0, const float* rs, const float2* cs64, const float2* cs32, bf16_t* stg) {
;     ...
; #pragma unroll
;   for (int it = 0; it < 16; ++it) {
;     const int idx = tid + NTHR * it, rr = idx >> 5, c = idx & 31;
;     const Seg& fs = (c >> 4) ? sg1 : sg0;
;     const int lcc = n0 + c * 8 - fs.cbase;
;     if (fs.kind != K_NONE && lcc < fs.nvalid) {
;       const int row = m0 + rr;
;       size_t off;
;       if (fs.kind == K_KC2) { const int b = row >> 9, n = (row >> 2) & 127, g = row & 3; off = ((size_t)((b * 4 + g) * 128 + n)) * 64 + lcc; }
;       else off = (size_t)row * fs.ld + lcc;
;       stg16_nt(fs.dst + off, stage_read16(stg, rr, c));
;     }
;   }
.LBB0_1195:
	s_or_b64 exec, exec, s[10:11]
	v_cmp_ne_u32_e64 s[0:1], 7, v130
	s_and_b64 s[0:1], s[0:1], vcc
	s_and_saveexec_b64 s[10:11], s[0:1]
	s_cbranch_execz .LBB0_1197
	v_add_u32_e32 v131, 0xc00, v169
	v_ashrrev_i32_e32 v131, 5, v131
	v_add_u32_e32 v132, s30, v131
	v_lshlrev_b32_e32 v134, 7, v131
	v_bfe_u32 v133, v132, 2, 7
	v_and_b32_e32 v134, 0x180, v134
	v_and_b32_e32 v135, 0xfffffe00, v132
	v_or3_b32 v133, v134, v135, v133
	v_cmp_eq_u32_e64 s[0:1], 5, v130
	s_nop 1
	v_cndmask_b32_e64 v134, v132, v133, s[0:1]
	v_mad_u64_u32 v[130:131], s[0:1], v131, s26, v[128:129]
	ds_read2_b64 v[130:133], v130 offset1:1
	v_ashrrev_i32_e32 v135, 31, v134
	v_lshlrev_b64 v[134:135], 7, v[134:135]
	v_lshl_add_u64 v[134:135], s[8:9], 0, v[134:135]
	v_lshl_add_u64 v[134:135], v[134:135], 0, v[160:161]
	s_waitcnt lgkmcnt(0)
	global_store_dwordx4 v[134:135], v[130:133], off
	s_nop 1
	v_mov_b32_e32 v130, v129
.LBB0_1197:
	s_or_b64 exec, exec, s[10:11]
	v_cmp_ne_u32_e64 s[0:1], 7, v130
	s_and_b64 s[0:1], s[0:1], vcc
	s_and_saveexec_b64 s[10:11], s[0:1]
	s_cbranch_execz .LBB0_1199
	v_add_u32_e32 v131, 0xe00, v169
	v_ashrrev_i32_e32 v131, 5, v131
	v_add_u32_e32 v132, s30, v131
	v_lshlrev_b32_e32 v134, 7, v131
	v_bfe_u32 v133, v132, 2, 7
	v_and_b32_e32 v134, 0x180, v134
	v_and_b32_e32 v135, 0xfffffe00, v132
	v_or3_b32 v133, v134, v135, v133
	v_cmp_eq_u32_e64 s[0:1], 5, v130
	s_nop 1
	v_cndmask_b32_e64 v134, v132, v133, s[0:1]
	v_mad_u64_u32 v[130:131], s[0:1], v131, s26, v[128:129]
	ds_read2_b64 v[130:133], v130 offset1:1
	v_ashrrev_i32_e32 v135, 31, v134
	v_lshlrev_b64 v[134:135], 7, v[134:135]
	v_lshl_add_u64 v[134:135], s[8:9], 0, v[134:135]
	v_lshl_add_u64 v[134:135], v[134:135], 0, v[160:161]
	s_waitcnt lgkmcnt(0)
	global_store_dwordx4 v[134:135], v[130:133], off
	s_nop 1
	v_mov_b32_e32 v130, v129
.LBB0_1199:
	s_or_b64 exec, exec, s[10:11]
	v_cmp_ne_u32_e64 s[0:1], 7, v130
	s_and_b64 s[0:1], s[0:1], vcc
	s_and_saveexec_b64 s[10:11], s[0:1]
	s_cbranch_execz .LBB0_1201
	v_add_u32_e32 v131, 0x1000, v169
	v_ashrrev_i32_e32 v131, 5, v131
	v_add_u32_e32 v132, s30, v131
	v_lshlrev_b32_e32 v134, 7, v131
	v_bfe_u32 v133, v132, 2, 7
	v_and_b32_e32 v134, 0x180, v134
	v_and_b32_e32 v135, 0xfffffe00, v132
	v_or3_b32 v133, v134, v135, v133
	v_cmp_eq_u32_e64 s[0:1], 5, v130
	s_nop 1
	v_cndmask_b32_e64 v134, v132, v133, s[0:1]
	v_mad_u64_u32 v[130:131], s[0:1], v131, s26, v[128:129]
	ds_read2_b64 v[130:133], v130 offset1:1
	v_ashrrev_i32_e32 v135, 31, v134
	v_lshlrev_b64 v[134:135], 7, v[134:135]
	v_lshl_add_u64 v[134:135], s[8:9], 0, v[134:135]
	v_lshl_add_u64 v[134:135], v[134:135], 0, v[160:161]
	s_waitcnt lgkmcnt(0)
	global_store_dwordx4 v[134:135], v[130:133], off
	s_nop 1
	v_mov_b32_e32 v130, v129
.LBB0_1201:
	s_or_b64 exec, exec, s[10:11]
	v_cmp_ne_u32_e64 s[0:1], 7, v130
	s_and_b64 s[0:1], s[0:1], vcc
	s_and_saveexec_b64 s[10:11], s[0:1]
	s_cbranch_execz .LBB0_1203
	v_add_u32_e32 v131, 0x1200, v169
	v_ashrrev_i32_e32 v131, 5, v131
	v_add_u32_e32 v132, s30, v131
	v_lshlrev_b32_e32 v134, 7, v131
	v_bfe_u32 v133, v132, 2, 7
	v_and_b32_e32 v134, 0x180, v134
	v_and_b32_e32 v135, 0xfffffe00, v132
	v_or3_b32 v133, v134, v135, v133
	v_cmp_eq_u32_e64 s[0:1], 5, v130
	s_nop 1
	v_cndmask_b32_e64 v134, v132, v133, s[0:1]
	v_mad_u64_u32 v[130:131], s[0:1], v131, s26, v[128:129]
	ds_read2_b64 v[130:133], v130 offset1:1
	v_ashrrev_i32_e32 v135, 31, v134
	v_lshlrev_b64 v[134:135], 7, v[134:135]
	v_lshl_add_u64 v[134:135], s[8:9], 0, v[134:135]
	v_lshl_add_u64 v[134:135], v[134:135], 0, v[160:161]
	s_waitcnt lgkmcnt(0)
	global_store_dwordx4 v[134:135], v[130:133], off
	s_nop 1
	v_mov_b32_e32 v130, v129
.LBB0_1203:
	s_or_b64 exec, exec, s[10:11]
	v_cmp_ne_u32_e64 s[0:1], 7, v130
	s_and_b64 s[0:1], s[0:1], vcc
	s_and_saveexec_b64 s[10:11], s[0:1]
	s_cbranch_execz .LBB0_1205
	v_add_u32_e32 v131, 0x1400, v169
	v_ashrrev_i32_e32 v131, 5, v131
	v_add_u32_e32 v132, s30, v131
	v_lshlrev_b32_e32 v134, 7, v131
	v_bfe_u32 v133, v132, 2, 7
	v_and_b32_e32 v134, 0x180, v134
	v_and_b32_e32 v135, 0xfffffe00, v132
	v_or3_b32 v133, v134, v135, v133
	v_cmp_eq_u32_e64 s[0:1], 5, v130
	s_nop 1
	v_cndmask_b32_e64 v134, v132, v133, s[0:1]
	v_mad_u64_u32 v[130:131], s[0:1], v131, s26, v[128:129]
	ds_read2_b64 v[130:133], v130 offset1:1
	v_ashrrev_i32_e32 v135, 31, v134
	v_lshlrev_b64 v[134:135], 7, v[134:135]
	v_lshl_add_u64 v[134:135], s[8:9], 0, v[134:135]
	v_lshl_add_u64 v[134:135], v[134:135], 0, v[160:161]
	s_waitcnt lgkmcnt(0)
	global_store_dwordx4 v[134:135], v[130:133], off
	s_nop 1
	v_mov_b32_e32 v130, v129
; DI void stg16_nt(void* p, u32x4 v) { __builtin_nontemporal_store(v, (u32x4*)p); }
; DI void epi_seg(const f32x16 (&acc)[4][2], const Seg& sg0, const Seg& sg1, int m0, int n0, const float* rs, const float2* cs64, const float2* cs32, bf16_t* stg) {
;     ...
; #pragma unroll
;   for (int it = 0; it < 16; ++it) {
;     const int idx = tid + NTHR * it, rr = idx >> 5, c = idx & 31;
;     const Seg& fs = (c >> 4) ? sg1 : sg0;
;     const int lcc = n0 + c * 8 - fs.cbase;
;     if (fs.kind != K_NONE && lcc < fs.nvalid) {
;       const int row = m0 + rr;
;       size_t off;
;       if (fs.kind == K_KC2) { const int b = row >> 9, n = (row >> 2) & 127, g = row & 3; off = ((size_t)((b * 4 + g) * 128 + n)) * 64 + lcc; }
;       else off = (size_t)row * fs.ld + lcc;
;       stg16_nt(fs.dst + off, stage_read16(stg, rr, c));
;     }
;   }
.LBB0_1205:
	s_or_b64 exec, exec, s[10:11]
	v_cmp_ne_u32_e64 s[0:1], 7, v130
	s_and_b64 s[0:1], s[0:1], vcc
	s_and_saveexec_b64 s[10:11], s[0:1]
	s_cbranch_execz .LBB0_1207
	v_add_u32_e32 v131, 0x1600, v169
	v_ashrrev_i32_e32 v131, 5, v131
	v_add_u32_e32 v132, s30, v131
	v_lshlrev_b32_e32 v134, 7, v131
	v_bfe_u32 v133, v132, 2, 7
	v_and_b32_e32 v134, 0x180, v134
	v_and_b32_e32 v135, 0xfffffe00, v132
	v_or3_b32 v133, v134, v135, v133
	v_cmp_eq_u32_e64 s[0:1], 5, v130
	s_nop 1
	v_cndmask_b32_e64 v134, v132, v133, s[0:1]
	v_mad_u64_u32 v[130:131], s[0:1], v131, s26, v[128:129]
	ds_read2_b64 v[130:133], v130 offset1:1
	v_ashrrev_i32_e32 v135, 31, v134
	v_lshlrev_b64 v[134:135], 7, v[134:135]
	v_lshl_add_u64 v[134:135], s[8:9], 0, v[134:135]
	v_lshl_add_u64 v[134:135], v[134:135], 0, v[160:161]
	s_waitcnt lgkmcnt(0)
	global_store_dwordx4 v[134:135], v[130:133], off
	s_nop 1
	v_mov_b32_e32 v130, v129
.LBB0_1207:
	s_or_b64 exec, exec, s[10:11]
	v_cmp_ne_u32_e64 s[0:1], 7, v130
	s_and_b64 s[0:1], s[0:1], vcc
	s_and_saveexec_b64 s[10:11], s[0:1]
	s_cbranch_execz .LBB0_1209
	v_add_u32_e32 v131, 0x1800, v169
	v_ashrrev_i32_e32 v131, 5, v131
	v_add_u32_e32 v132, s30, v131
	v_lshlrev_b32_e32 v134, 7, v131
	v_bfe_u32 v133, v132, 2, 7
	v_and_b32_e32 v134, 0x180, v134
	v_and_b32_e32 v135, 0xfffffe00, v132
	v_or3_b32 v133, v134, v135, v133
	v_cmp_eq_u32_e64 s[0:1], 5, v130
	s_nop 1
	v_cndmask_b32_e64 v134, v132, v133, s[0:1]
	v_mad_u64_u32 v[130:131], s[0:1], v131, s26, v[128:129]
	ds_read2_b64 v[130:133], v130 offset1:1
	v_ashrrev_i32_e32 v135, 31, v134
	v_lshlrev_b64 v[134:135], 7, v[134:135]
	v_lshl_add_u64 v[134:135], s[8:9], 0, v[134:135]
	v_lshl_add_u64 v[134:135], v[134:135], 0, v[160:161]
	s_waitcnt lgkmcnt(0)
	global_store_dwordx4 v[134:135], v[130:133], off
	s_nop 1
	v_mov_b32_e32 v130, v129
.LBB0_1209:
	s_or_b64 exec, exec, s[10:11]
	v_cmp_ne_u32_e64 s[0:1], 7, v130
	s_and_b64 s[0:1], s[0:1], vcc
	s_and_saveexec_b64 s[10:11], s[0:1]
	s_cbranch_execz .LBB0_1211
	v_add_u32_e32 v131, 0x1a00, v169
	v_ashrrev_i32_e32 v131, 5, v131
	v_add_u32_e32 v132, s30, v131
	v_lshlrev_b32_e32 v134, 7, v131
	v_bfe_u32 v133, v132, 2, 7
	v_and_b32_e32 v134, 0x180, v134
	v_and_b32_e32 v135, 0xfffffe00, v132
	v_or3_b32 v133, v134, v135, v133
	v_cmp_eq_u32_e64 s[0:1], 5, v130
	s_nop 1
	v_cndmask_b32_e64 v134, v132, v133, s[0:1]
	v_mad_u64_u32 v[130:131], s[0:1], v131, s26, v[128:129]
	ds_read2_b64 v[130:133], v130 offset1:1
	v_ashrrev_i32_e32 v135, 31, v134
	v_lshlrev_b64 v[134:135], 7, v[134:135]
	v_lshl_add_u64 v[134:135], s[8:9], 0, v[134:135]
	v_lshl_add_u64 v[134:135], v[134:135], 0, v[160:161]
	s_waitcnt lgkmcnt(0)
	global_store_dwordx4 v[134:135], v[130:133], off
	s_nop 1
	v_mov_b32_e32 v130, v129
.LBB0_1211:
	s_or_b64 exec, exec, s[10:11]
	v_cmp_ne_u32_e64 s[0:1], 7, v130
	s_and_b64 s[0:1], s[0:1], vcc
	s_and_saveexec_b64 s[10:11], s[0:1]
	s_cbranch_execz .LBB0_1213
	v_add_u32_e32 v131, 0x1c00, v169
	v_ashrrev_i32_e32 v131, 5, v131
	v_add_u32_e32 v132, s30, v131
	v_lshlrev_b32_e32 v134, 7, v131
	v_bfe_u32 v133, v132, 2, 7
	v_and_b32_e32 v134, 0x180, v134
	v_and_b32_e32 v135, 0xfffffe00, v132
	v_or3_b32 v133, v134, v135, v133
	v_cmp_eq_u32_e64 s[0:1], 5, v130
	s_nop 1
	v_cndmask_b32_e64 v134, v132, v133, s[0:1]
	v_mad_u64_u32 v[130:131], s[0:1], v131, s26, v[128:129]
	ds_read2_b64 v[130:133], v130 offset1:1
	v_ashrrev_i32_e32 v135, 31, v134
	v_lshlrev_b64 v[134:135], 7, v[134:135]
	v_lshl_add_u64 v[134:135], s[8:9], 0, v[134:135]
	v_lshl_add_u64 v[134:135], v[134:135], 0, v[160:161]
	s_waitcnt lgkmcnt(0)
	global_store_dwordx4 v[134:135], v[130:133], off
	s_nop 1
	v_mov_b32_e32 v130, v129
.LBB0_1213:
	s_or_b64 exec, exec, s[10:11]
	v_cmp_ne_u32_e64 s[0:1], 7, v130
	s_and_b64 s[10:11], s[0:1], vcc
	s_and_saveexec_b64 s[0:1], s[10:11]
	s_cbranch_execz .LBB0_1215
	v_add_u32_e32 v129, 0x1e00, v169
	v_ashrrev_i32_e32 v129, 5, v129
	v_add_u32_e32 v131, s30, v129
	v_lshlrev_b32_e32 v133, 7, v129
	v_bfe_u32 v132, v131, 2, 7
	v_and_b32_e32 v133, 0x180, v133
	v_and_b32_e32 v134, 0xfffffe00, v131
	v_or3_b32 v132, v133, v134, v132
	v_cmp_eq_u32_e32 vcc, 5, v130
	v_mad_u64_u32 v[128:129], s[10:11], v129, s26, v[128:129]
	s_nop 0
	v_cndmask_b32_e32 v132, v131, v132, vcc
	ds_read2_b64 v[128:131], v128 offset1:1
	v_ashrrev_i32_e32 v133, 31, v132
	v_lshlrev_b64 v[132:133], 7, v[132:133]
	v_lshl_add_u64 v[132:133], s[8:9], 0, v[132:133]
	v_lshl_add_u64 v[132:133], v[132:133], 0, v[160:161]
	s_waitcnt lgkmcnt(0)
	global_store_dwordx4 v[132:133], v[128:131], off

; DI int otid() { int t = threadIdx.x; asm volatile("" : "+v"(t)); return t; }
; DI void stg16_nt(void* p, u32x4 v) { __builtin_nontemporal_store(v, (u32x4*)p); }
; DI void stage_store_tile(const bf16_t* stg, bf16_t* tilebase) {
;   const int tid = otid();
;   const int r0 = tid >> 5, c = tid & 31;
;   const unsigned o0 = (unsigned)(r0 * 1024 + c * 8);
; #pragma unroll
;   for (int it = 0; it < 16; ++it) stg16_nt(tilebase + (o0 + (unsigned)(it * 16 * 1024)), stage_read16(stg, r0 + 16 * it, c));
; }
.LBB0_1425:
	s_or_b64 exec, exec, s[14:15]
	v_mov_b32_e32 v0, v192
	s_waitcnt lgkmcnt(0)
	s_barrier
	s_lshl_b64 s[10:11], s[10:11], 18
	v_ashrrev_i32_e32 v4, 5, v0
	v_and_b32_e32 v0, 31, v0
	v_mul_lo_u32 v1, v4, s23
	s_lshl_b64 s[10:11], s[10:11], 1
	v_lshl_add_u32 v10, v0, 4, v1
	s_add_u32 s10, s76, s10
	v_lshlrev_b32_e32 v5, 3, v0
	ds_read2_b64 v[0:3], v10 offset1:1
	s_addc_u32 s11, s77, s11
	v_lshl_or_b32 v160, v4, 10, v5
	v_add_u32_e32 v4, 0x2080, v10
	s_add_u32 s10, s10, s27
	ds_read2_b64 v[4:7], v4 offset1:1
	s_addc_u32 s11, s11, 0
	v_lshl_add_u64 v[8:9], v[160:161], 1, s[10:11]
	s_waitcnt lgkmcnt(1)
	global_store_dwordx4 v[8:9], v[0:3], off
	s_add_i32 s19, s19, s69
	s_andn2_b64 vcc, exec, s[12:13]
	v_add_u32_e32 v0, 0x4000, v160
	v_mov_b32_e32 v1, v161
	v_lshl_add_u64 v[0:1], v[0:1], 1, s[10:11]
	s_waitcnt lgkmcnt(0)
	global_store_dwordx4 v[0:1], v[4:7], off
	v_add_u32_e32 v0, 0x4100, v10
	ds_read2_b64 v[0:3], v0 offset1:1
	v_add_u32_e32 v4, 0x8000, v160
	v_mov_b32_e32 v5, v161
	v_lshl_add_u64 v[8:9], v[4:5], 1, s[10:11]
	v_add_u32_e32 v4, 0x6180, v10
	ds_read2_b64 v[4:7], v4 offset1:1
	s_waitcnt lgkmcnt(1)
	global_store_dwordx4 v[8:9], v[0:3], off
	s_add_i32 s20, s20, s17
	s_nop 0
	v_add_u32_e32 v0, 0xc000, v160
	v_mov_b32_e32 v1, v161
	v_lshl_add_u64 v[0:1], v[0:1], 1, s[10:11]
	s_waitcnt lgkmcnt(0)
	global_store_dwordx4 v[0:1], v[4:7], off
	v_add_u32_e32 v0, 0x8200, v10
	ds_read2_b64 v[0:3], v0 offset1:1
	v_add_u32_e32 v4, 0x10000, v160
	v_mov_b32_e32 v5, v161
	v_lshl_add_u64 v[8:9], v[4:5], 1, s[10:11]
	v_add_u32_e32 v4, 0xa280, v10
	ds_read2_b64 v[4:7], v4 offset1:1
	s_waitcnt lgkmcnt(1)
	global_store_dwordx4 v[8:9], v[0:3], off
	s_nop 1
	v_add_u32_e32 v0, 0x14000, v160
	v_mov_b32_e32 v1, v161
	v_lshl_add_u64 v[0:1], v[0:1], 1, s[10:11]
	s_waitcnt lgkmcnt(0)
	global_store_dwordx4 v[0:1], v[4:7], off
	v_add_u32_e32 v0, 0xc300, v10
	ds_read2_b64 v[0:3], v0 offset1:1
	v_add_u32_e32 v4, 0x18000, v160
	v_mov_b32_e32 v5, v161
	v_lshl_add_u64 v[8:9], v[4:5], 1, s[10:11]
	v_add_u32_e32 v4, 0xe380, v10
	ds_read2_b64 v[4:7], v4 offset1:1
	s_waitcnt lgkmcnt(1)
	global_store_dwordx4 v[8:9], v[0:3], off
	s_nop 1
	v_add_u32_e32 v0, 0x1c000, v160
	v_mov_b32_e32 v1, v161
	v_lshl_add_u64 v[0:1], v[0:1], 1, s[10:11]
	s_waitcnt lgkmcnt(0)
	global_store_dwordx4 v[0:1], v[4:7], off
	v_add_u32_e32 v0, 0x10400, v10
	ds_read2_b64 v[0:3], v0 offset1:1
	v_add_u32_e32 v4, 0x20000, v160
	v_mov_b32_e32 v5, v161
	v_lshl_add_u64 v[8:9], v[4:5], 1, s[10:11]
	v_add_u32_e32 v4, 0x12480, v10
	ds_read2_b64 v[4:7], v4 offset1:1
	s_waitcnt lgkmcnt(1)
	global_store_dwordx4 v[8:9], v[0:3], off
	s_nop 1
	v_add_u32_e32 v0, 0x24000, v160
	v_mov_b32_e32 v1, v161
	v_lshl_add_u64 v[0:1], v[0:1], 1, s[10:11]
	s_waitcnt lgkmcnt(0)
	global_store_dwordx4 v[0:1], v[4:7], off
	v_add_u32_e32 v0, 0x14500, v10
	ds_read2_b64 v[0:3], v0 offset1:1
	v_add_u32_e32 v4, 0x28000, v160
	v_mov_b32_e32 v5, v161
	v_lshl_add_u64 v[8:9], v[4:5], 1, s[10:11]
	v_add_u32_e32 v4, 0x16580, v10
	ds_read2_b64 v[4:7], v4 offset1:1
	s_waitcnt lgkmcnt(1)
	global_store_dwordx4 v[8:9], v[0:3], off
	s_nop 1
	v_add_u32_e32 v0, 0x2c000, v160
	v_mov_b32_e32 v1, v161
	v_lshl_add_u64 v[0:1], v[0:1], 1, s[10:11]
	s_waitcnt lgkmcnt(0)
	global_store_dwordx4 v[0:1], v[4:7], off
	v_add_u32_e32 v0, 0x18600, v10
	ds_read2_b64 v[0:3], v0 offset1:1
	v_add_u32_e32 v4, 0x30000, v160
	v_mov_b32_e32 v5, v161
	v_lshl_add_u64 v[8:9], v[4:5], 1, s[10:11]
	v_add_u32_e32 v4, 0x1a680, v10
	ds_read2_b64 v[4:7], v4 offset1:1
	s_waitcnt lgkmcnt(1)
	global_store_dwordx4 v[8:9], v[0:3], off
	v_add_u32_e32 v8, 0x38000, v160
	v_mov_b32_e32 v9, v161
	v_add_u32_e32 v0, 0x34000, v160
	v_mov_b32_e32 v1, v161
	v_lshl_add_u64 v[0:1], v[0:1], 1, s[10:11]
	s_waitcnt lgkmcnt(0)
	global_store_dwordx4 v[0:1], v[4:7], off
	v_add_u32_e32 v0, 0x1c700, v10
	ds_read2_b64 v[0:3], v0 offset1:1
	v_add_u32_e32 v4, 0x1e780, v10
	ds_read2_b64 v[4:7], v4 offset1:1
	v_lshl_add_u64 v[8:9], v[8:9], 1, s[10:11]
	v_add_u32_e32 v160, 0x3c000, v160
	s_waitcnt lgkmcnt(1)
	global_store_dwordx4 v[8:9], v[0:3], off
	s_nop 1
	v_lshl_add_u64 v[0:1], v[160:161], 1, s[10:11]
	s_waitcnt lgkmcnt(0)
	global_store_dwordx4 v[0:1], v[4:7], off
	s_barrier
	s_cbranch_vccz .LBB0_1436

; DI void stg16_nt(void* p, u32x4 v) { __builtin_nontemporal_store(v, (u32x4*)p); }
; DI void epi_seg(const f32x16 (&acc)[4][2], const Seg& sg0, const Seg& sg1, int m0, int n0, const float* rs, const float2* cs64, const float2* cs32, bf16_t* stg) {
;     ...
; #pragma unroll
;   for (int it = 0; it < 16; ++it) {
;     const int idx = tid + NTHR * it, rr = idx >> 5, c = idx & 31;
;     const Seg& fs = (c >> 4) ? sg1 : sg0;
;     const int lcc = n0 + c * 8 - fs.cbase;
;     if (fs.kind != K_NONE && lcc < fs.nvalid) {
;       const int row = m0 + rr;
;       size_t off;
;       if (fs.kind == K_KC2) { const int b = row >> 9, n = (row >> 2) & 127, g = row & 3; off = ((size_t)((b * 4 + g) * 128 + n)) * 64 + lcc; }
;       else off = (size_t)row * fs.ld + lcc;
;       stg16_nt(fs.dst + off, stage_read16(stg, rr, c));
;     }
;   }
.LBB0_1442:
	s_or_b64 exec, exec, s[12:13]
	v_and_b32_e32 v1, 31, v160
	v_lshlrev_b32_e32 v0, 3, v1
	v_subrev_u32_e32 v0, s23, v0
	v_subrev_u32_e32 v0, s24, v0
	v_add_u32_e32 v0, s16, v0
	v_cmp_gt_i32_e32 vcc, 2.0, v0
	s_waitcnt lgkmcnt(0)
	s_barrier
	s_and_saveexec_b64 s[12:13], vcc
	s_cbranch_execz .LBB0_1437
	v_ashrrev_i32_e32 v4, 5, v160
	v_add_u32_e32 v2, s22, v4
	v_ashrrev_i32_e32 v3, 31, v2
	v_lshlrev_b32_e32 v8, 4, v1
	v_ashrrev_i32_e32 v1, 31, v0
	v_lshlrev_b64 v[2:3], 11, v[2:3]
	v_lshl_add_u64 v[2:3], s[66:67], 0, v[2:3]
	v_lshlrev_b64 v[10:11], 1, v[0:1]
	v_mad_u64_u32 v[0:1], s[24:25], v4, s20, v[8:9]
	v_lshl_add_u64 v[12:13], v[2:3], 0, v[10:11]
	ds_read2_b64 v[0:3], v0 offset1:1
	v_add_u32_e32 v4, 0x200, v160
	v_ashrrev_i32_e32 v9, 5, v4
	v_mad_u64_u32 v[4:5], s[24:25], v9, s20, v[8:9]
	ds_read2_b64 v[4:7], v4 offset1:1
	s_waitcnt lgkmcnt(1)
	global_store_dwordx4 v[12:13], v[0:3], off
	s_nop 1
	v_add_u32_e32 v0, s22, v9
	v_ashrrev_i32_e32 v1, 31, v0
	v_lshlrev_b64 v[0:1], 11, v[0:1]
	v_lshl_add_u64 v[0:1], s[66:67], 0, v[0:1]
	v_lshl_add_u64 v[0:1], v[0:1], 0, v[10:11]
	s_waitcnt lgkmcnt(0)
	global_store_dwordx4 v[0:1], v[4:7], off
	v_add_u32_e32 v0, 0x400, v160
	v_ashrrev_i32_e32 v2, 5, v0
	v_add_u32_e32 v0, s22, v2
	v_ashrrev_i32_e32 v1, 31, v0
	v_lshlrev_b64 v[0:1], 11, v[0:1]
	v_lshl_add_u64 v[0:1], s[66:67], 0, v[0:1]
	v_lshl_add_u64 v[12:13], v[0:1], 0, v[10:11]
	v_mad_u64_u32 v[0:1], s[24:25], v2, s20, v[8:9]
	ds_read2_b64 v[0:3], v0 offset1:1
	v_add_u32_e32 v4, 0x600, v160
	v_ashrrev_i32_e32 v9, 5, v4
	v_mad_u64_u32 v[4:5], s[24:25], v9, s20, v[8:9]
	ds_read2_b64 v[4:7], v4 offset1:1
	s_waitcnt lgkmcnt(1)
	global_store_dwordx4 v[12:13], v[0:3], off
	s_nop 1
	v_add_u32_e32 v0, s22, v9
	v_ashrrev_i32_e32 v1, 31, v0
	v_lshlrev_b64 v[0:1], 11, v[0:1]
	v_lshl_add_u64 v[0:1], s[66:67], 0, v[0:1]
	v_lshl_add_u64 v[0:1], v[0:1], 0, v[10:11]
	s_waitcnt lgkmcnt(0)
	global_store_dwordx4 v[0:1], v[4:7], off
	v_add_u32_e32 v0, 0x800, v160
	v_ashrrev_i32_e32 v2, 5, v0
	v_add_u32_e32 v0, s22, v2
	v_ashrrev_i32_e32 v1, 31, v0
	v_lshlrev_b64 v[0:1], 11, v[0:1]
	v_lshl_add_u64 v[0:1], s[66:67], 0, v[0:1]
	v_lshl_add_u64 v[12:13], v[0:1], 0, v[10:11]
	v_mad_u64_u32 v[0:1], s[24:25], v2, s20, v[8:9]
	ds_read2_b64 v[0:3], v0 offset1:1
	v_add_u32_e32 v4, 0xa00, v160
	v_ashrrev_i32_e32 v9, 5, v4
	v_mad_u64_u32 v[4:5], s[24:25], v9, s20, v[8:9]
	ds_read2_b64 v[4:7], v4 offset1:1
	s_waitcnt lgkmcnt(1)
	global_store_dwordx4 v[12:13], v[0:3], off
	s_nop 1
	v_add_u32_e32 v0, s22, v9
	v_ashrrev_i32_e32 v1, 31, v0
	v_lshlrev_b64 v[0:1], 11, v[0:1]
	v_lshl_add_u64 v[0:1], s[66:67], 0, v[0:1]
	v_lshl_add_u64 v[0:1], v[0:1], 0, v[10:11]
	s_waitcnt lgkmcnt(0)
	global_store_dwordx4 v[0:1], v[4:7], off
	v_add_u32_e32 v0, 0xc00, v160
	v_ashrrev_i32_e32 v2, 5, v0
	v_add_u32_e32 v0, s22, v2
	v_ashrrev_i32_e32 v1, 31, v0
	v_lshlrev_b64 v[0:1], 11, v[0:1]
	v_lshl_add_u64 v[0:1], s[66:67], 0, v[0:1]
	v_lshl_add_u64 v[12:13], v[0:1], 0, v[10:11]
	v_mad_u64_u32 v[0:1], s[24:25], v2, s20, v[8:9]
	ds_read2_b64 v[0:3], v0 offset1:1
	v_add_u32_e32 v4, 0xe00, v160
	v_ashrrev_i32_e32 v9, 5, v4
	v_mad_u64_u32 v[4:5], s[24:25], v9, s20, v[8:9]
	ds_read2_b64 v[4:7], v4 offset1:1
	s_waitcnt lgkmcnt(1)
	global_store_dwordx4 v[12:13], v[0:3], off
	s_nop 1
	v_add_u32_e32 v0, s22, v9
	v_ashrrev_i32_e32 v1, 31, v0
	v_lshlrev_b64 v[0:1], 11, v[0:1]
	v_lshl_add_u64 v[0:1], s[66:67], 0, v[0:1]
	v_lshl_add_u64 v[0:1], v[0:1], 0, v[10:11]
	s_waitcnt lgkmcnt(0)
	global_store_dwordx4 v[0:1], v[4:7], off
	v_add_u32_e32 v0, 0x1000, v160
	v_ashrrev_i32_e32 v2, 5, v0
	v_add_u32_e32 v0, s22, v2
	v_ashrrev_i32_e32 v1, 31, v0
	v_lshlrev_b64 v[0:1], 11, v[0:1]
	v_lshl_add_u64 v[0:1], s[66:67], 0, v[0:1]
	v_lshl_add_u64 v[12:13], v[0:1], 0, v[10:11]
	v_mad_u64_u32 v[0:1], s[24:25], v2, s20, v[8:9]
	ds_read2_b64 v[0:3], v0 offset1:1
	v_add_u32_e32 v4, 0x1200, v160
	v_ashrrev_i32_e32 v9, 5, v4
	v_mad_u64_u32 v[4:5], s[24:25], v9, s20, v[8:9]
	ds_read2_b64 v[4:7], v4 offset1:1
	s_waitcnt lgkmcnt(1)
	global_store_dwordx4 v[12:13], v[0:3], off
	s_nop 1
	v_add_u32_e32 v0, s22, v9
	v_ashrrev_i32_e32 v1, 31, v0
	v_lshlrev_b64 v[0:1], 11, v[0:1]
	v_lshl_add_u64 v[0:1], s[66:67], 0, v[0:1]
	v_lshl_add_u64 v[0:1], v[0:1], 0, v[10:11]
	s_waitcnt lgkmcnt(0)
	global_store_dwordx4 v[0:1], v[4:7], off
	v_add_u32_e32 v0, 0x1400, v160
	v_ashrrev_i32_e32 v2, 5, v0
	v_add_u32_e32 v0, s22, v2
	v_ashrrev_i32_e32 v1, 31, v0
	v_lshlrev_b64 v[0:1], 11, v[0:1]
	v_lshl_add_u64 v[0:1], s[66:67], 0, v[0:1]
	v_lshl_add_u64 v[12:13], v[0:1], 0, v[10:11]
	v_mad_u64_u32 v[0:1], s[24:25], v2, s20, v[8:9]
	ds_read2_b64 v[0:3], v0 offset1:1
	v_add_u32_e32 v4, 0x1600, v160
	v_ashrrev_i32_e32 v9, 5, v4
	v_mad_u64_u32 v[4:5], s[24:25], v9, s20, v[8:9]
	ds_read2_b64 v[4:7], v4 offset1:1
	s_waitcnt lgkmcnt(1)
	global_store_dwordx4 v[12:13], v[0:3], off
	s_nop 1
	v_add_u32_e32 v0, s22, v9
	v_ashrrev_i32_e32 v1, 31, v0
	v_lshlrev_b64 v[0:1], 11, v[0:1]
	v_lshl_add_u64 v[0:1], s[66:67], 0, v[0:1]
	v_lshl_add_u64 v[0:1], v[0:1], 0, v[10:11]
	s_waitcnt lgkmcnt(0)
	global_store_dwordx4 v[0:1], v[4:7], off
	v_add_u32_e32 v0, 0x1800, v160
	v_ashrrev_i32_e32 v2, 5, v0
	v_add_u32_e32 v0, s22, v2
	v_ashrrev_i32_e32 v1, 31, v0
	v_lshlrev_b64 v[0:1], 11, v[0:1]
	v_lshl_add_u64 v[0:1], s[66:67], 0, v[0:1]
	v_lshl_add_u64 v[12:13], v[0:1], 0, v[10:11]
	v_mad_u64_u32 v[0:1], s[24:25], v2, s20, v[8:9]
	ds_read2_b64 v[0:3], v0 offset1:1
	v_add_u32_e32 v4, 0x1a00, v160
	v_ashrrev_i32_e32 v9, 5, v4
	v_mad_u64_u32 v[4:5], s[24:25], v9, s20, v[8:9]
	ds_read2_b64 v[4:7], v4 offset1:1
	s_waitcnt lgkmcnt(1)
	global_store_dwordx4 v[12:13], v[0:3], off
	s_nop 1
	v_add_u32_e32 v0, s22, v9
	v_ashrrev_i32_e32 v1, 31, v0
	v_lshlrev_b64 v[0:1], 11, v[0:1]
	v_lshl_add_u64 v[0:1], s[66:67], 0, v[0:1]
	v_lshl_add_u64 v[0:1], v[0:1], 0, v[10:11]
	s_waitcnt lgkmcnt(0)
	global_store_dwordx4 v[0:1], v[4:7], off
	v_add_u32_e32 v0, 0x1c00, v160
	v_ashrrev_i32_e32 v2, 5, v0
	v_add_u32_e32 v0, s22, v2
	v_ashrrev_i32_e32 v1, 31, v0
	v_lshlrev_b64 v[0:1], 11, v[0:1]
	v_lshl_add_u64 v[0:1], s[66:67], 0, v[0:1]
	v_lshl_add_u64 v[12:13], v[0:1], 0, v[10:11]
	v_mad_u64_u32 v[0:1], s[24:25], v2, s20, v[8:9]
	ds_read2_b64 v[0:3], v0 offset1:1
	v_add_u32_e32 v4, 0x1e00, v160
	v_ashrrev_i32_e32 v9, 5, v4
	v_mad_u64_u32 v[4:5], s[24:25], v9, s20, v[8:9]
	ds_read2_b64 v[4:7], v4 offset1:1
	s_waitcnt lgkmcnt(1)
	global_store_dwordx4 v[12:13], v[0:3], off
	s_nop 1
	v_add_u32_e32 v0, s22, v9
	v_ashrrev_i32_e32 v1, 31, v0
	v_lshlrev_b64 v[0:1], 11, v[0:1]
	v_lshl_add_u64 v[0:1], s[66:67], 0, v[0:1]
	v_lshl_add_u64 v[0:1], v[0:1], 0, v[10:11]
	s_waitcnt lgkmcnt(0)
	global_store_dwordx4 v[0:1], v[4:7], off
	s_branch .LBB0_1437

; DI unsigned pack2(float a, float b) { f32x2_t v = {a, b}; bf16x2_t r = __builtin_convertvector(v, bf16x2_t); return __builtin_bit_cast(unsigned, r); }
; DI float sigmoidf_(float x) { return __builtin_amdgcn_rcpf(1.f + __expf(-x)); }
; template <bool LAST>
; DI void phase_gate(const Params& P, int layer, unsigned char* smem, int L, int G) {
;     ...
;     unsigned gq[4][2][8];
; #pragma unroll
;     for (int i = 0; i < 4; ++i)
; #pragma unroll
;       for (int q4 = 0; q4 < 4; ++q4) {
;         const int fl = wm * 128 + i * 32 + 8 * q4 + 4 * h;
;         const f32x4 c1v = *(const f32x4*)(vecL + fl), c2v = *(const f32x4*)(vecL + 256 + fl);
;         const float c1a[4] = {c1v.x, c1v.y, c1v.z, c1v.w}, c2a[4] = {c2v.x, c2v.y, c2v.z, c2v.w};
; #pragma unroll
;         for (int j = 0; j < 2; ++j) {
;           const int lrow = wn * 64 + j * 32 + r;
;           const float mu = rowA[lrow], rstd = rowB[lrow];
;           float sg4[4];
; #pragma unroll
;           for (int e = 0; e < 4; ++e) sg4[e] = sigmoidf_(rstd * (accu[i][j][4 * q4 + e] - mu * c1a[e]) + c2a[e]);
;           gq[i][j][2 * q4] = pack2(sg4[0], sg4[1]); gq[i][j][2 * q4 + 1] = pack2(sg4[2], sg4[3]);
;         }
;         __builtin_amdgcn_sched_barrier(0);
;       }
.LBB0_1498:
	v_lshrrev_b32_e32 v160, 1, v163
	v_lshrrev_b32_e32 v163, 3, v163
	v_and_b32_e32 v163, 4, v163
	v_and_or_b32 v160, v160, s33, v163
	v_lshlrev_b32_e32 v160, 2, v160
	v_add_u32_e32 v163, 0x24800, v160
	v_add_u32_e32 v164, 0x24c00, v160
	v_and_b32_e32 v167, 0x37c, v168
	ds_read_b128 v[170:173], v163
	ds_read_b128 v[174:177], v164
	v_or_b32_e32 v164, 0x24000, v167
	v_or_b32_e32 v166, 0x24080, v167
	v_or_b32_e32 v165, 0x24400, v167
	ds_read_b32 v168, v164
	ds_read_b32 v169, v165
	v_or_b32_e32 v167, 0x24480, v167
	ds_read_b32 v178, v166
	ds_read_b32 v179, v167
	s_waitcnt lgkmcnt(3)
	v_fma_f32 v112, -v170, v168, v112
	v_fma_f32 v113, -v171, v168, v113
	s_waitcnt lgkmcnt(1)
	v_fma_f32 v98, -v172, v178, v98
	v_fma_f32 v114, -v172, v168, v114
	v_fma_f32 v115, -v173, v168, v115
	v_fma_f32 v96, -v170, v178, v96
	v_fma_f32 v97, -v171, v178, v97
	s_waitcnt lgkmcnt(0)
	v_fma_f32 v98, v179, v98, v176
	v_fma_f32 v99, -v173, v178, v99
	v_fma_f32 v112, v169, v112, v174
	v_fma_f32 v113, v169, v113, v175
	v_fma_f32 v114, v169, v114, v176
	v_fma_f32 v115, v169, v115, v177
	v_fma_f32 v96, v179, v96, v174
	v_fma_f32 v97, v179, v97, v175
	v_mul_f32_e32 v98, 0xbfb8aa3b, v98
	v_fmac_f32_e32 v177, v179, v99
	v_mul_f32_e32 v112, 0xbfb8aa3b, v112
	v_mul_f32_e32 v113, 0xbfb8aa3b, v113
	v_mul_f32_e32 v114, 0xbfb8aa3b, v114
	v_mul_f32_e32 v115, 0xbfb8aa3b, v115
	v_mul_f32_e32 v96, 0xbfb8aa3b, v96
	v_mul_f32_e32 v97, 0xbfb8aa3b, v97
	v_exp_f32_e32 v98, v98
	v_mul_f32_e32 v99, 0xbfb8aa3b, v177
	v_exp_f32_e32 v112, v112
	v_exp_f32_e32 v113, v113
	v_exp_f32_e32 v114, v114
	v_exp_f32_e32 v115, v115
	v_exp_f32_e32 v96, v96
	v_exp_f32_e32 v97, v97
	v_exp_f32_e32 v99, v99
	v_add_f32_e32 v98, 1.0, v98
	v_add_f32_e32 v112, 1.0, v112
	v_add_f32_e32 v113, 1.0, v113
	v_add_f32_e32 v114, 1.0, v114
	v_add_f32_e32 v115, 1.0, v115
	v_add_f32_e32 v96, 1.0, v96
	v_add_f32_e32 v97, 1.0, v97
	v_rcp_f32_e32 v168, v98
	v_add_f32_e32 v98, 1.0, v99
	v_rcp_f32_e32 v112, v112
	v_rcp_f32_e32 v113, v113
	v_rcp_f32_e32 v114, v114
	v_rcp_f32_e32 v115, v115
	v_rcp_f32_e32 v96, v96
	v_rcp_f32_e32 v97, v97
	v_rcp_f32_e32 v169, v98
	v_cvt_pk_bf16_f32 v99, v112, v113
	v_cvt_pk_bf16_f32 v98, v114, v115
	v_cvt_pk_bf16_f32 v97, v96, v97
	v_cvt_pk_bf16_f32 v96, v168, v169
	v_add_u32_e32 v112, 0x24820, v160
	v_add_u32_e32 v168, 0x24c20, v160
	ds_read_b128 v[112:115], v112
	ds_read_b128 v[168:171], v168
	ds_read_b32 v172, v164
	ds_read_b32 v173, v165
	ds_read_b32 v174, v166
	ds_read_b32 v175, v167
	s_waitcnt lgkmcnt(3)
	v_fma_f32 v116, -v112, v172, v116
	v_fma_f32 v117, -v113, v172, v117
	s_waitcnt lgkmcnt(1)
	v_fma_f32 v102, -v114, v174, v102
	v_fma_f32 v118, -v114, v172, v118
	v_fma_f32 v119, -v115, v172, v119
	v_fma_f32 v100, -v112, v174, v100
	v_fma_f32 v101, -v113, v174, v101
	s_waitcnt lgkmcnt(0)
	v_fma_f32 v102, v175, v102, v170
	v_fma_f32 v103, -v115, v174, v103
	v_fma_f32 v116, v173, v116, v168
	v_fma_f32 v117, v173, v117, v169
	v_fma_f32 v118, v173, v118, v170
	v_fma_f32 v119, v173, v119, v171
	v_fma_f32 v100, v175, v100, v168
	v_fma_f32 v101, v175, v101, v169
	v_mul_f32_e32 v102, 0xbfb8aa3b, v102
	v_fmac_f32_e32 v171, v175, v103
	v_mul_f32_e32 v116, 0xbfb8aa3b, v116
	v_mul_f32_e32 v117, 0xbfb8aa3b, v117
	v_mul_f32_e32 v118, 0xbfb8aa3b, v118
	v_mul_f32_e32 v119, 0xbfb8aa3b, v119
	v_mul_f32_e32 v100, 0xbfb8aa3b, v100
	v_mul_f32_e32 v101, 0xbfb8aa3b, v101
	v_exp_f32_e32 v102, v102
	v_mul_f32_e32 v103, 0xbfb8aa3b, v171
	v_exp_f32_e32 v116, v116
	v_exp_f32_e32 v117, v117
	v_exp_f32_e32 v118, v118
	v_exp_f32_e32 v119, v119
	v_exp_f32_e32 v100, v100
	v_exp_f32_e32 v101, v101
	v_exp_f32_e32 v103, v103
	v_add_f32_e32 v102, 1.0, v102
	v_add_f32_e32 v116, 1.0, v116
	v_add_f32_e32 v117, 1.0, v117
	v_add_f32_e32 v118, 1.0, v118
	v_add_f32_e32 v119, 1.0, v119
	v_add_f32_e32 v100, 1.0, v100
	v_add_f32_e32 v101, 1.0, v101
	v_rcp_f32_e32 v113, v102
	v_add_f32_e32 v102, 1.0, v103
	v_rcp_f32_e32 v116, v116
	v_rcp_f32_e32 v117, v117
	v_rcp_f32_e32 v118, v118
	v_rcp_f32_e32 v112, v119
	v_rcp_f32_e32 v100, v100
	v_rcp_f32_e32 v101, v101
	v_rcp_f32_e32 v114, v102
	v_cvt_pk_bf16_f32 v103, v116, v117
	v_cvt_pk_bf16_f32 v102, v118, v112
	v_cvt_pk_bf16_f32 v101, v100, v101
	v_cvt_pk_bf16_f32 v100, v113, v114
	v_add_u32_e32 v112, 0x24840, v160
	v_add_u32_e32 v116, 0x24c40, v160
	ds_read_b128 v[112:115], v112
	ds_read_b128 v[116:119], v116
	ds_read_b32 v168, v164
	ds_read_b32 v169, v165
	ds_read_b32 v170, v166
	ds_read_b32 v171, v167
	s_waitcnt lgkmcnt(3)
	v_fma_f32 v120, -v112, v168, v120
	v_fma_f32 v121, -v113, v168, v121
	s_waitcnt lgkmcnt(1)
	v_fma_f32 v106, -v114, v170, v106
	v_fma_f32 v122, -v114, v168, v122
	v_fma_f32 v123, -v115, v168, v123
	v_fma_f32 v104, -v112, v170, v104
	v_fma_f32 v105, -v113, v170, v105
	s_waitcnt lgkmcnt(0)
	v_fma_f32 v106, v171, v106, v118
	v_fma_f32 v107, -v115, v170, v107
	v_fma_f32 v120, v169, v120, v116
	v_fma_f32 v121, v169, v121, v117
	v_fma_f32 v122, v169, v122, v118
	v_fma_f32 v123, v169, v123, v119
	v_fma_f32 v104, v171, v104, v116
	v_fma_f32 v105, v171, v105, v117
	v_mul_f32_e32 v106, 0xbfb8aa3b, v106
	v_fmac_f32_e32 v119, v171, v107
	v_mul_f32_e32 v120, 0xbfb8aa3b, v120
	v_mul_f32_e32 v121, 0xbfb8aa3b, v121
	v_mul_f32_e32 v122, 0xbfb8aa3b, v122
	v_mul_f32_e32 v123, 0xbfb8aa3b, v123
	v_mul_f32_e32 v104, 0xbfb8aa3b, v104
	v_mul_f32_e32 v105, 0xbfb8aa3b, v105
	v_exp_f32_e32 v106, v106
	v_mul_f32_e32 v107, 0xbfb8aa3b, v119
	v_exp_f32_e32 v120, v120
	v_exp_f32_e32 v121, v121
	v_exp_f32_e32 v122, v122
	v_exp_f32_e32 v123, v123
	v_exp_f32_e32 v104, v104
	v_exp_f32_e32 v105, v105
	v_exp_f32_e32 v107, v107
	v_add_f32_e32 v106, 1.0, v106
	v_add_f32_e32 v120, 1.0, v120
	v_add_f32_e32 v121, 1.0, v121
	v_add_f32_e32 v122, 1.0, v122
	v_add_f32_e32 v123, 1.0, v123
	v_add_f32_e32 v104, 1.0, v104
	v_add_f32_e32 v105, 1.0, v105
	v_rcp_f32_e32 v113, v106
	v_add_f32_e32 v106, 1.0, v107
	v_rcp_f32_e32 v120, v120
	v_rcp_f32_e32 v121, v121
	v_rcp_f32_e32 v122, v122
	v_rcp_f32_e32 v112, v123
	v_rcp_f32_e32 v104, v104
	v_rcp_f32_e32 v105, v105
	v_rcp_f32_e32 v114, v106
	v_cvt_pk_bf16_f32 v107, v120, v121
	v_cvt_pk_bf16_f32 v106, v122, v112
	v_cvt_pk_bf16_f32 v105, v104, v105
	v_cvt_pk_bf16_f32 v104, v113, v114
	v_add_u32_e32 v112, 0x24860, v160
	v_add_u32_e32 v116, 0x24c60, v160
	ds_read_b128 v[112:115], v112
	ds_read_b128 v[116:119], v116
	ds_read_b32 v120, v164
	ds_read_b32 v121, v165
	ds_read_b32 v122, v166
	ds_read_b32 v123, v167
	s_waitcnt lgkmcnt(3)
; DI unsigned pack2(float a, float b) { f32x2_t v = {a, b}; bf16x2_t r = __builtin_convertvector(v, bf16x2_t); return __builtin_bit_cast(unsigned, r); }
; DI float sigmoidf_(float x) { return __builtin_amdgcn_rcpf(1.f + __expf(-x)); }
; template <bool LAST>
; DI void phase_gate(const Params& P, int layer, unsigned char* smem, int L, int G) {
;     ...
;     unsigned gq[4][2][8];
; #pragma unroll
;     for (int i = 0; i < 4; ++i)
; #pragma unroll
;       for (int q4 = 0; q4 < 4; ++q4) {
;         const int fl = wm * 128 + i * 32 + 8 * q4 + 4 * h;
;         const f32x4 c1v = *(const f32x4*)(vecL + fl), c2v = *(const f32x4*)(vecL + 256 + fl);
;         const float c1a[4] = {c1v.x, c1v.y, c1v.z, c1v.w}, c2a[4] = {c2v.x, c2v.y, c2v.z, c2v.w};
; #pragma unroll
;         for (int j = 0; j < 2; ++j) {
;           const int lrow = wn * 64 + j * 32 + r;
;           const float mu = rowA[lrow], rstd = rowB[lrow];
;           float sg4[4];
; #pragma unroll
;           for (int e = 0; e < 4; ++e) sg4[e] = sigmoidf_(rstd * (accu[i][j][4 * q4 + e] - mu * c1a[e]) + c2a[e]);
;           gq[i][j][2 * q4] = pack2(sg4[0], sg4[1]); gq[i][j][2 * q4 + 1] = pack2(sg4[2], sg4[3]);
;         }
;         __builtin_amdgcn_sched_barrier(0);
;       }
	v_fma_f32 v125, -v113, v120, v125
	v_fma_f32 v124, -v112, v120, v124
	s_waitcnt lgkmcnt(1)
	v_fma_f32 v110, -v114, v122, v110
	v_fma_f32 v125, v121, v125, v117
	v_fma_f32 v126, -v114, v120, v126
	v_fma_f32 v120, -v115, v120, v127
	v_fma_f32 v108, -v112, v122, v108
	v_fma_f32 v109, -v113, v122, v109
	s_waitcnt lgkmcnt(0)
	v_fma_f32 v110, v123, v110, v118
	v_fma_f32 v111, -v115, v122, v111
	v_fma_f32 v124, v121, v124, v116
	v_mul_f32_e32 v125, 0xbfb8aa3b, v125
	v_fma_f32 v126, v121, v126, v118
	v_fma_f32 v120, v121, v120, v119
	v_fma_f32 v108, v123, v108, v116
	v_fma_f32 v109, v123, v109, v117
	v_mul_f32_e32 v110, 0xbfb8aa3b, v110
	v_fmac_f32_e32 v119, v123, v111
	v_mul_f32_e32 v124, 0xbfb8aa3b, v124
	v_exp_f32_e32 v125, v125
	v_mul_f32_e32 v126, 0xbfb8aa3b, v126
	v_mul_f32_e32 v120, 0xbfb8aa3b, v120
	v_mul_f32_e32 v108, 0xbfb8aa3b, v108
	v_mul_f32_e32 v109, 0xbfb8aa3b, v109
	v_exp_f32_e32 v110, v110
	v_mul_f32_e32 v111, 0xbfb8aa3b, v119
	v_exp_f32_e32 v124, v124
	v_exp_f32_e32 v126, v126
	v_exp_f32_e32 v120, v120
	v_exp_f32_e32 v108, v108
	v_exp_f32_e32 v109, v109
	v_exp_f32_e32 v111, v111
	v_add_f32_e32 v125, 1.0, v125
	v_add_f32_e32 v110, 1.0, v110
	v_add_f32_e32 v124, 1.0, v124
	v_rcp_f32_e32 v121, v125
	v_add_f32_e32 v125, 1.0, v126
	v_add_f32_e32 v120, 1.0, v120
	v_add_f32_e32 v108, 1.0, v108
	v_add_f32_e32 v109, 1.0, v109
	v_rcp_f32_e32 v113, v110
	v_add_f32_e32 v110, 1.0, v111
	v_rcp_f32_e32 v124, v124
	v_rcp_f32_e32 v125, v125
	v_rcp_f32_e32 v112, v120
	v_rcp_f32_e32 v108, v108
	v_rcp_f32_e32 v109, v109
	v_rcp_f32_e32 v114, v110
	v_cvt_pk_bf16_f32 v111, v124, v121
	v_cvt_pk_bf16_f32 v110, v125, v112
	v_cvt_pk_bf16_f32 v109, v108, v109
	v_cvt_pk_bf16_f32 v108, v113, v114
	v_add_u32_e32 v112, 0x24880, v160
	v_add_u32_e32 v116, 0x24c80, v160
	ds_read_b128 v[112:115], v112
	ds_read_b128 v[116:119], v116
	ds_read_b32 v120, v164
	ds_read_b32 v121, v165
	ds_read_b32 v122, v166
	ds_read_b32 v123, v167
	s_waitcnt lgkmcnt(3)
	v_fma_f32 v80, -v112, v120, v80
	v_fma_f32 v81, -v113, v120, v81
	s_waitcnt lgkmcnt(1)
	v_fma_f32 v66, -v114, v122, v66
	v_fma_f32 v82, -v114, v120, v82
	v_fma_f32 v83, -v115, v120, v83
	v_fma_f32 v64, -v112, v122, v64
	v_fma_f32 v65, -v113, v122, v65
	s_waitcnt lgkmcnt(0)
	v_fma_f32 v66, v123, v66, v118
	v_fma_f32 v67, -v115, v122, v67
	v_fma_f32 v80, v121, v80, v116
	v_fma_f32 v81, v121, v81, v117
	v_fma_f32 v82, v121, v82, v118
	v_fma_f32 v83, v121, v83, v119
	v_fma_f32 v64, v123, v64, v116
	v_fma_f32 v65, v123, v65, v117
	v_mul_f32_e32 v66, 0xbfb8aa3b, v66
	v_fmac_f32_e32 v119, v123, v67
	v_mul_f32_e32 v80, 0xbfb8aa3b, v80
	v_mul_f32_e32 v81, 0xbfb8aa3b, v81
	v_mul_f32_e32 v82, 0xbfb8aa3b, v82
	v_mul_f32_e32 v83, 0xbfb8aa3b, v83
	v_mul_f32_e32 v64, 0xbfb8aa3b, v64
	v_mul_f32_e32 v65, 0xbfb8aa3b, v65
	v_exp_f32_e32 v66, v66
	v_mul_f32_e32 v67, 0xbfb8aa3b, v119
	v_exp_f32_e32 v80, v80
	v_exp_f32_e32 v81, v81
	v_exp_f32_e32 v82, v82
	v_exp_f32_e32 v83, v83
	v_exp_f32_e32 v64, v64
	v_exp_f32_e32 v65, v65
	v_exp_f32_e32 v67, v67
	v_add_f32_e32 v66, 1.0, v66
	v_add_f32_e32 v80, 1.0, v80
	v_add_f32_e32 v81, 1.0, v81
	v_add_f32_e32 v82, 1.0, v82
	v_add_f32_e32 v83, 1.0, v83
	v_add_f32_e32 v64, 1.0, v64
	v_add_f32_e32 v65, 1.0, v65
	v_rcp_f32_e32 v112, v66
	v_add_f32_e32 v66, 1.0, v67
	v_rcp_f32_e32 v80, v80
	v_rcp_f32_e32 v81, v81
	v_rcp_f32_e32 v82, v82
	v_rcp_f32_e32 v83, v83
	v_rcp_f32_e32 v64, v64
	v_rcp_f32_e32 v65, v65
	v_rcp_f32_e32 v113, v66
	v_cvt_pk_bf16_f32 v67, v80, v81
	v_cvt_pk_bf16_f32 v66, v82, v83
	v_cvt_pk_bf16_f32 v65, v64, v65
	v_cvt_pk_bf16_f32 v64, v112, v113
	v_add_u32_e32 v80, 0x248a0, v160
	v_add_u32_e32 v112, 0x24ca0, v160
	ds_read_b128 v[80:83], v80
	ds_read_b128 v[112:115], v112
	ds_read_b32 v116, v164
	ds_read_b32 v117, v165
	ds_read_b32 v118, v166
	ds_read_b32 v119, v167
	s_waitcnt lgkmcnt(3)
	v_fma_f32 v84, -v80, v116, v84
	v_fma_f32 v85, -v81, v116, v85
	s_waitcnt lgkmcnt(1)
	v_fma_f32 v70, -v82, v118, v70
	v_fma_f32 v86, -v82, v116, v86
	v_fma_f32 v87, -v83, v116, v87
	v_fma_f32 v68, -v80, v118, v68
	v_fma_f32 v69, -v81, v118, v69
	s_waitcnt lgkmcnt(0)
	v_fma_f32 v70, v119, v70, v114
	v_fma_f32 v71, -v83, v118, v71
	v_fma_f32 v84, v117, v84, v112
	v_fma_f32 v85, v117, v85, v113
	v_fma_f32 v86, v117, v86, v114
	v_fma_f32 v87, v117, v87, v115
	v_fma_f32 v68, v119, v68, v112
	v_fma_f32 v69, v119, v69, v113
	v_mul_f32_e32 v70, 0xbfb8aa3b, v70
	v_fmac_f32_e32 v115, v119, v71
	v_mul_f32_e32 v84, 0xbfb8aa3b, v84
	v_mul_f32_e32 v85, 0xbfb8aa3b, v85
	v_mul_f32_e32 v86, 0xbfb8aa3b, v86
	v_mul_f32_e32 v87, 0xbfb8aa3b, v87
	v_mul_f32_e32 v68, 0xbfb8aa3b, v68
	v_mul_f32_e32 v69, 0xbfb8aa3b, v69
	v_exp_f32_e32 v70, v70
	v_mul_f32_e32 v71, 0xbfb8aa3b, v115
	v_exp_f32_e32 v84, v84
	v_exp_f32_e32 v85, v85
	v_exp_f32_e32 v86, v86
	v_exp_f32_e32 v87, v87
	v_exp_f32_e32 v68, v68
	v_exp_f32_e32 v69, v69
	v_exp_f32_e32 v71, v71
	v_add_f32_e32 v70, 1.0, v70
	v_add_f32_e32 v84, 1.0, v84
	v_add_f32_e32 v85, 1.0, v85
	v_add_f32_e32 v86, 1.0, v86
	v_add_f32_e32 v87, 1.0, v87
	v_add_f32_e32 v68, 1.0, v68
	v_add_f32_e32 v69, 1.0, v69
	v_rcp_f32_e32 v81, v70
	v_add_f32_e32 v70, 1.0, v71
	v_rcp_f32_e32 v84, v84
	v_rcp_f32_e32 v85, v85
	v_rcp_f32_e32 v86, v86
	v_rcp_f32_e32 v80, v87
	v_rcp_f32_e32 v68, v68
	v_rcp_f32_e32 v69, v69
	v_rcp_f32_e32 v82, v70
	v_cvt_pk_bf16_f32 v71, v84, v85
	v_cvt_pk_bf16_f32 v70, v86, v80
	v_cvt_pk_bf16_f32 v69, v68, v69
	v_cvt_pk_bf16_f32 v68, v81, v82
	v_add_u32_e32 v80, 0x248c0, v160
	v_add_u32_e32 v84, 0x24cc0, v160
	ds_read_b128 v[80:83], v80
	ds_read_b128 v[84:87], v84
	ds_read_b32 v112, v164
	ds_read_b32 v113, v165
	ds_read_b32 v114, v166
	ds_read_b32 v115, v167
	s_waitcnt lgkmcnt(3)
; DI unsigned pack2(float a, float b) { f32x2_t v = {a, b}; bf16x2_t r = __builtin_convertvector(v, bf16x2_t); return __builtin_bit_cast(unsigned, r); }
; DI float sigmoidf_(float x) { return __builtin_amdgcn_rcpf(1.f + __expf(-x)); }
; template <bool LAST>
; DI void phase_gate(const Params& P, int layer, unsigned char* smem, int L, int G) {
;     ...
;     unsigned gq[4][2][8];
; #pragma unroll
;     for (int i = 0; i < 4; ++i)
; #pragma unroll
;       for (int q4 = 0; q4 < 4; ++q4) {
;         const int fl = wm * 128 + i * 32 + 8 * q4 + 4 * h;
;         const f32x4 c1v = *(const f32x4*)(vecL + fl), c2v = *(const f32x4*)(vecL + 256 + fl);
;         const float c1a[4] = {c1v.x, c1v.y, c1v.z, c1v.w}, c2a[4] = {c2v.x, c2v.y, c2v.z, c2v.w};
; #pragma unroll
;         for (int j = 0; j < 2; ++j) {
;           const int lrow = wn * 64 + j * 32 + r;
;           const float mu = rowA[lrow], rstd = rowB[lrow];
;           float sg4[4];
; #pragma unroll
;           for (int e = 0; e < 4; ++e) sg4[e] = sigmoidf_(rstd * (accu[i][j][4 * q4 + e] - mu * c1a[e]) + c2a[e]);
;           gq[i][j][2 * q4] = pack2(sg4[0], sg4[1]); gq[i][j][2 * q4 + 1] = pack2(sg4[2], sg4[3]);
;         }
;         __builtin_amdgcn_sched_barrier(0);
;       }
	v_fma_f32 v88, -v80, v112, v88
	v_fma_f32 v89, -v81, v112, v89
	s_waitcnt lgkmcnt(1)
	v_fma_f32 v74, -v82, v114, v74
	v_fma_f32 v90, -v82, v112, v90
	v_fma_f32 v91, -v83, v112, v91
	v_fma_f32 v72, -v80, v114, v72
	v_fma_f32 v73, -v81, v114, v73
	s_waitcnt lgkmcnt(0)
	v_fma_f32 v74, v115, v74, v86
	v_fma_f32 v75, -v83, v114, v75
	v_fma_f32 v88, v113, v88, v84
	v_fma_f32 v89, v113, v89, v85
	v_fma_f32 v90, v113, v90, v86
	v_fma_f32 v91, v113, v91, v87
	v_fma_f32 v72, v115, v72, v84
	v_fma_f32 v73, v115, v73, v85
	v_mul_f32_e32 v74, 0xbfb8aa3b, v74
	v_fmac_f32_e32 v87, v115, v75
	v_mul_f32_e32 v88, 0xbfb8aa3b, v88
	v_mul_f32_e32 v89, 0xbfb8aa3b, v89
	v_mul_f32_e32 v90, 0xbfb8aa3b, v90
	v_mul_f32_e32 v91, 0xbfb8aa3b, v91
	v_mul_f32_e32 v72, 0xbfb8aa3b, v72
	v_mul_f32_e32 v73, 0xbfb8aa3b, v73
	v_exp_f32_e32 v74, v74
	v_mul_f32_e32 v75, 0xbfb8aa3b, v87
	v_exp_f32_e32 v88, v88
	v_exp_f32_e32 v89, v89
	v_exp_f32_e32 v90, v90
	v_exp_f32_e32 v91, v91
	v_exp_f32_e32 v72, v72
	v_exp_f32_e32 v73, v73
	v_exp_f32_e32 v75, v75
	v_add_f32_e32 v74, 1.0, v74
	v_add_f32_e32 v88, 1.0, v88
	v_add_f32_e32 v89, 1.0, v89
	v_add_f32_e32 v90, 1.0, v90
	v_add_f32_e32 v91, 1.0, v91
	v_add_f32_e32 v72, 1.0, v72
	v_add_f32_e32 v73, 1.0, v73
	v_rcp_f32_e32 v81, v74
	v_add_f32_e32 v74, 1.0, v75
	v_rcp_f32_e32 v88, v88
	v_rcp_f32_e32 v89, v89
	v_rcp_f32_e32 v90, v90
	v_rcp_f32_e32 v80, v91
	v_rcp_f32_e32 v72, v72
	v_rcp_f32_e32 v73, v73
	v_rcp_f32_e32 v82, v74
	v_cvt_pk_bf16_f32 v75, v88, v89
	v_cvt_pk_bf16_f32 v74, v90, v80
	v_cvt_pk_bf16_f32 v73, v72, v73
	v_cvt_pk_bf16_f32 v72, v81, v82
	v_add_u32_e32 v80, 0x248e0, v160
	v_add_u32_e32 v84, 0x24ce0, v160
	ds_read_b128 v[80:83], v80
	ds_read_b128 v[84:87], v84
	ds_read_b32 v88, v164
	ds_read_b32 v89, v165
	ds_read_b32 v90, v166
	ds_read_b32 v91, v167
	s_waitcnt lgkmcnt(3)
	v_fma_f32 v93, -v81, v88, v93
	v_fma_f32 v92, -v80, v88, v92
	s_waitcnt lgkmcnt(1)
	v_fma_f32 v78, -v82, v90, v78
	v_fma_f32 v93, v89, v93, v85
	v_fma_f32 v94, -v82, v88, v94
	v_fma_f32 v88, -v83, v88, v95
	v_fma_f32 v76, -v80, v90, v76
	v_fma_f32 v77, -v81, v90, v77
	s_waitcnt lgkmcnt(0)
	v_fma_f32 v78, v91, v78, v86
	v_fma_f32 v79, -v83, v90, v79
	v_fma_f32 v92, v89, v92, v84
	v_mul_f32_e32 v93, 0xbfb8aa3b, v93
	v_fma_f32 v94, v89, v94, v86
	v_fma_f32 v88, v89, v88, v87
	v_fma_f32 v76, v91, v76, v84
	v_fma_f32 v77, v91, v77, v85
	v_mul_f32_e32 v78, 0xbfb8aa3b, v78
	v_fmac_f32_e32 v87, v91, v79
	v_mul_f32_e32 v92, 0xbfb8aa3b, v92
	v_exp_f32_e32 v93, v93
	v_mul_f32_e32 v94, 0xbfb8aa3b, v94
	v_mul_f32_e32 v88, 0xbfb8aa3b, v88
	v_mul_f32_e32 v76, 0xbfb8aa3b, v76
	v_mul_f32_e32 v77, 0xbfb8aa3b, v77
	v_exp_f32_e32 v78, v78
	v_mul_f32_e32 v79, 0xbfb8aa3b, v87
	v_exp_f32_e32 v92, v92
	v_exp_f32_e32 v94, v94
	v_exp_f32_e32 v88, v88
	v_exp_f32_e32 v76, v76
	v_exp_f32_e32 v77, v77
	v_exp_f32_e32 v79, v79
	v_add_f32_e32 v93, 1.0, v93
	v_add_f32_e32 v78, 1.0, v78
	v_add_f32_e32 v92, 1.0, v92
	v_rcp_f32_e32 v89, v93
	v_add_f32_e32 v93, 1.0, v94
	v_add_f32_e32 v88, 1.0, v88
	v_add_f32_e32 v76, 1.0, v76
	v_add_f32_e32 v77, 1.0, v77
	v_rcp_f32_e32 v81, v78
	v_add_f32_e32 v78, 1.0, v79
	v_rcp_f32_e32 v92, v92
	v_rcp_f32_e32 v93, v93
	v_rcp_f32_e32 v80, v88
	v_rcp_f32_e32 v76, v76
	v_rcp_f32_e32 v77, v77
	v_rcp_f32_e32 v82, v78
	v_cvt_pk_bf16_f32 v79, v92, v89
	v_cvt_pk_bf16_f32 v78, v93, v80
	v_cvt_pk_bf16_f32 v77, v76, v77
	v_cvt_pk_bf16_f32 v76, v81, v82
	v_add_u32_e32 v80, 0x24900, v160
	v_add_u32_e32 v84, 0x24d00, v160
	ds_read_b128 v[80:83], v80
	ds_read_b128 v[84:87], v84
	ds_read_b32 v88, v164
	ds_read_b32 v89, v165
	ds_read_b32 v90, v166
	ds_read_b32 v91, v167
	s_waitcnt lgkmcnt(3)
	v_fma_f32 v48, -v80, v88, v48
	v_fma_f32 v49, -v81, v88, v49
	s_waitcnt lgkmcnt(1)
	v_fma_f32 v34, -v82, v90, v34
	v_fma_f32 v50, -v82, v88, v50
	v_fma_f32 v51, -v83, v88, v51
	v_fma_f32 v32, -v80, v90, v32
	v_fma_f32 v33, -v81, v90, v33
	s_waitcnt lgkmcnt(0)
	v_fma_f32 v34, v91, v34, v86
	v_fma_f32 v35, -v83, v90, v35
	v_fma_f32 v48, v89, v48, v84
	v_fma_f32 v49, v89, v49, v85
	v_fma_f32 v50, v89, v50, v86
	v_fma_f32 v51, v89, v51, v87
	v_fma_f32 v32, v91, v32, v84
	v_fma_f32 v33, v91, v33, v85
	v_mul_f32_e32 v34, 0xbfb8aa3b, v34
	v_fmac_f32_e32 v87, v91, v35
	v_mul_f32_e32 v48, 0xbfb8aa3b, v48
	v_mul_f32_e32 v49, 0xbfb8aa3b, v49
	v_mul_f32_e32 v50, 0xbfb8aa3b, v50
	v_mul_f32_e32 v51, 0xbfb8aa3b, v51
	v_mul_f32_e32 v32, 0xbfb8aa3b, v32
	v_mul_f32_e32 v33, 0xbfb8aa3b, v33
	v_exp_f32_e32 v34, v34
	v_mul_f32_e32 v35, 0xbfb8aa3b, v87
	v_exp_f32_e32 v48, v48
	v_exp_f32_e32 v49, v49
	v_exp_f32_e32 v50, v50
	v_exp_f32_e32 v51, v51
	v_exp_f32_e32 v32, v32
	v_exp_f32_e32 v33, v33
	v_exp_f32_e32 v35, v35
	v_add_f32_e32 v34, 1.0, v34
	v_add_f32_e32 v48, 1.0, v48
	v_add_f32_e32 v49, 1.0, v49
	v_add_f32_e32 v50, 1.0, v50
	v_add_f32_e32 v51, 1.0, v51
	v_add_f32_e32 v32, 1.0, v32
	v_add_f32_e32 v33, 1.0, v33
	v_rcp_f32_e32 v80, v34
	v_add_f32_e32 v34, 1.0, v35
	v_rcp_f32_e32 v48, v48
	v_rcp_f32_e32 v49, v49
	v_rcp_f32_e32 v50, v50
	v_rcp_f32_e32 v51, v51
	v_rcp_f32_e32 v32, v32
	v_rcp_f32_e32 v33, v33
	v_rcp_f32_e32 v81, v34
	v_cvt_pk_bf16_f32 v35, v48, v49
	v_cvt_pk_bf16_f32 v34, v50, v51
	v_cvt_pk_bf16_f32 v33, v32, v33
	v_cvt_pk_bf16_f32 v32, v80, v81
	v_add_u32_e32 v48, 0x24920, v160
	v_add_u32_e32 v80, 0x24d20, v160
	ds_read_b128 v[48:51], v48
	ds_read_b128 v[80:83], v80
	ds_read_b32 v84, v164
	ds_read_b32 v85, v165
	ds_read_b32 v86, v166
	ds_read_b32 v87, v167
	s_waitcnt lgkmcnt(3)
	v_fma_f32 v53, -v49, v84, v53
	v_fma_f32 v52, -v48, v84, v52
	s_waitcnt lgkmcnt(1)
	v_fma_f32 v36, -v48, v86, v36
	s_waitcnt lgkmcnt(0)
; DI unsigned pack2(float a, float b) { f32x2_t v = {a, b}; bf16x2_t r = __builtin_convertvector(v, bf16x2_t); return __builtin_bit_cast(unsigned, r); }
; DI float sigmoidf_(float x) { return __builtin_amdgcn_rcpf(1.f + __expf(-x)); }
; template <bool LAST>
; DI void phase_gate(const Params& P, int layer, unsigned char* smem, int L, int G) {
;     ...
;     unsigned gq[4][2][8];
; #pragma unroll
;     for (int i = 0; i < 4; ++i)
; #pragma unroll
;       for (int q4 = 0; q4 < 4; ++q4) {
;         const int fl = wm * 128 + i * 32 + 8 * q4 + 4 * h;
;         const f32x4 c1v = *(const f32x4*)(vecL + fl), c2v = *(const f32x4*)(vecL + 256 + fl);
;         const float c1a[4] = {c1v.x, c1v.y, c1v.z, c1v.w}, c2a[4] = {c2v.x, c2v.y, c2v.z, c2v.w};
; #pragma unroll
;         for (int j = 0; j < 2; ++j) {
;           const int lrow = wn * 64 + j * 32 + r;
;           const float mu = rowA[lrow], rstd = rowB[lrow];
;           float sg4[4];
; #pragma unroll
;           for (int e = 0; e < 4; ++e) sg4[e] = sigmoidf_(rstd * (accu[i][j][4 * q4 + e] - mu * c1a[e]) + c2a[e]);
;           gq[i][j][2 * q4] = pack2(sg4[0], sg4[1]); gq[i][j][2 * q4 + 1] = pack2(sg4[2], sg4[3]);
;         }
;         __builtin_amdgcn_sched_barrier(0);
;       }
	v_fma_f32 v36, v87, v36, v80
	v_fma_f32 v37, -v49, v86, v37
	v_mul_f32_e32 v36, 0xbfb8aa3b, v36
	v_fma_f32 v37, v87, v37, v81
	v_exp_f32_e32 v36, v36
	v_mul_f32_e32 v37, 0xbfb8aa3b, v37
	v_exp_f32_e32 v37, v37
	v_fma_f32 v54, -v50, v84, v54
	v_add_f32_e32 v36, 1.0, v36
	v_rcp_f32_e32 v49, v36
	v_add_f32_e32 v36, 1.0, v37
	v_fma_f32 v37, -v50, v86, v38
	v_fma_f32 v55, -v51, v84, v55
	v_fma_f32 v37, v87, v37, v82
	v_fma_f32 v38, -v51, v86, v39
	v_fma_f32 v52, v85, v52, v80
	v_fma_f32 v53, v85, v53, v81
	v_fma_f32 v54, v85, v54, v82
	v_fma_f32 v55, v85, v55, v83
	v_mul_f32_e32 v37, 0xbfb8aa3b, v37
	v_fmac_f32_e32 v83, v87, v38
	v_mul_f32_e32 v52, 0xbfb8aa3b, v52
	v_mul_f32_e32 v53, 0xbfb8aa3b, v53
	v_mul_f32_e32 v54, 0xbfb8aa3b, v54
	v_mul_f32_e32 v55, 0xbfb8aa3b, v55
	v_exp_f32_e32 v37, v37
	v_mul_f32_e32 v38, 0xbfb8aa3b, v83
	v_exp_f32_e32 v52, v52
	v_exp_f32_e32 v53, v53
	v_exp_f32_e32 v54, v54
	v_exp_f32_e32 v55, v55
	v_exp_f32_e32 v38, v38
	v_rcp_f32_e32 v39, v36
	v_add_f32_e32 v36, 1.0, v37
	v_add_f32_e32 v52, 1.0, v52
	v_add_f32_e32 v53, 1.0, v53
	v_add_f32_e32 v54, 1.0, v54
	v_add_f32_e32 v55, 1.0, v55
	v_rcp_f32_e32 v37, v36
	v_add_f32_e32 v36, 1.0, v38
	v_rcp_f32_e32 v52, v52
	v_rcp_f32_e32 v53, v53
	v_rcp_f32_e32 v54, v54
	v_rcp_f32_e32 v48, v55
	v_rcp_f32_e32 v38, v36
	v_cvt_pk_bf16_f32 v80, v52, v53
	v_cvt_pk_bf16_f32 v55, v49, v39
	v_cvt_pk_bf16_f32 v36, v54, v48
	v_cvt_pk_bf16_f32 v53, v37, v38
	v_add_u32_e32 v37, 0x24940, v160
	v_add_u32_e32 v38, 0x24d40, v160
	ds_read_b128 v[48:51], v37
	ds_read_b128 v[82:85], v38
	ds_read_b32 v37, v164
	ds_read_b32 v38, v165
	ds_read_b32 v39, v166
	ds_read_b32 v52, v167
	s_waitcnt lgkmcnt(3)
	v_fma_f32 v54, -v48, v37, v56
	v_fma_f32 v56, -v49, v37, v57
	s_waitcnt lgkmcnt(2)
	v_fma_f32 v56, v38, v56, v83
	v_fma_f32 v57, -v50, v37, v58
	v_fma_f32 v37, -v51, v37, v59
	s_waitcnt lgkmcnt(1)
	v_fma_f32 v40, -v48, v39, v40
	v_fma_f32 v41, -v49, v39, v41
	v_fma_f32 v42, -v50, v39, v42
	v_fma_f32 v39, -v51, v39, v43
	v_fma_f32 v54, v38, v54, v82
	v_mul_f32_e32 v56, 0xbfb8aa3b, v56
	v_fma_f32 v57, v38, v57, v84
	v_fma_f32 v37, v38, v37, v85
	s_waitcnt lgkmcnt(0)
	v_fma_f32 v40, v52, v40, v82
	v_fma_f32 v41, v52, v41, v83
	v_fma_f32 v42, v52, v42, v84
	v_fmac_f32_e32 v85, v52, v39
	v_mul_f32_e32 v54, 0xbfb8aa3b, v54
	v_exp_f32_e32 v56, v56
	v_mul_f32_e32 v57, 0xbfb8aa3b, v57
	v_mul_f32_e32 v37, 0xbfb8aa3b, v37
	v_mul_f32_e32 v40, 0xbfb8aa3b, v40
	v_mul_f32_e32 v41, 0xbfb8aa3b, v41
	v_mul_f32_e32 v42, 0xbfb8aa3b, v42
	v_mul_f32_e32 v39, 0xbfb8aa3b, v85
	v_exp_f32_e32 v54, v54
	v_exp_f32_e32 v57, v57
	v_exp_f32_e32 v37, v37
	v_exp_f32_e32 v40, v40
	v_exp_f32_e32 v41, v41
	v_exp_f32_e32 v42, v42
	v_exp_f32_e32 v39, v39
	v_add_f32_e32 v56, 1.0, v56
	v_add_f32_e32 v54, 1.0, v54
	v_rcp_f32_e32 v38, v56
	v_add_f32_e32 v56, 1.0, v57
	v_add_f32_e32 v37, 1.0, v37
	v_add_f32_e32 v40, 1.0, v40
	v_add_f32_e32 v41, 1.0, v41
	v_add_f32_e32 v42, 1.0, v42
	v_add_f32_e32 v39, 1.0, v39
	v_rcp_f32_e32 v54, v54
	v_rcp_f32_e32 v56, v56
	v_rcp_f32_e32 v37, v37
	v_rcp_f32_e32 v40, v40
	v_rcp_f32_e32 v41, v41
	v_rcp_f32_e32 v42, v42
	v_rcp_f32_e32 v39, v39
	v_cvt_pk_bf16_f32 v83, v54, v38
	v_cvt_pk_bf16_f32 v82, v56, v37
	v_cvt_pk_bf16_f32 v81, v40, v41
	v_cvt_pk_bf16_f32 v59, v42, v39
	v_add_u32_e32 v37, 0x24960, v160
	v_add_u32_e32 v42, 0x24d60, v160
	ds_read_b128 v[38:41], v37
	ds_read_b128 v[48:51], v42
	ds_read_b32 v37, v164
	ds_read_b32 v42, v165
	ds_read_b32 v43, v166
	ds_read_b32 v52, v167
	s_waitcnt lgkmcnt(3)
	v_fma_f32 v56, -v39, v37, v61
	v_fma_f32 v54, -v38, v37, v60
	s_waitcnt lgkmcnt(2)
	v_fma_f32 v56, v42, v56, v49
	v_fma_f32 v57, -v40, v37, v62
	v_fma_f32 v37, -v41, v37, v63
	s_waitcnt lgkmcnt(1)
	v_fma_f32 v38, -v38, v43, v44
	v_fma_f32 v39, -v39, v43, v45
	v_fma_f32 v40, -v40, v43, v46
	v_fma_f32 v41, -v41, v43, v47
	v_fma_f32 v54, v42, v54, v48
	v_mul_f32_e32 v56, 0xbfb8aa3b, v56
	v_fma_f32 v57, v42, v57, v50
	v_fma_f32 v37, v42, v37, v51
	s_waitcnt lgkmcnt(0)
	v_fma_f32 v38, v52, v38, v48
	v_fma_f32 v39, v52, v39, v49
	v_fma_f32 v40, v52, v40, v50
	v_fmac_f32_e32 v51, v52, v41
	v_mul_f32_e32 v54, 0xbfb8aa3b, v54
	v_exp_f32_e32 v56, v56
	v_mul_f32_e32 v57, 0xbfb8aa3b, v57
	v_mul_f32_e32 v37, 0xbfb8aa3b, v37
	v_mul_f32_e32 v38, 0xbfb8aa3b, v38
	v_mul_f32_e32 v39, 0xbfb8aa3b, v39
	v_mul_f32_e32 v40, 0xbfb8aa3b, v40
	v_mul_f32_e32 v41, 0xbfb8aa3b, v51
	v_exp_f32_e32 v54, v54
	v_exp_f32_e32 v57, v57
	v_exp_f32_e32 v37, v37
	v_exp_f32_e32 v38, v38
	v_exp_f32_e32 v39, v39
	v_exp_f32_e32 v40, v40
	v_exp_f32_e32 v41, v41
	v_add_f32_e32 v56, 1.0, v56
	v_add_f32_e32 v54, 1.0, v54
	v_rcp_f32_e32 v42, v56
	v_add_f32_e32 v56, 1.0, v57
	v_add_f32_e32 v37, 1.0, v37
	v_add_f32_e32 v38, 1.0, v38
	v_add_f32_e32 v39, 1.0, v39
	v_add_f32_e32 v40, 1.0, v40
	v_add_f32_e32 v41, 1.0, v41
	v_rcp_f32_e32 v54, v54
	v_rcp_f32_e32 v56, v56
	v_rcp_f32_e32 v37, v37
	v_rcp_f32_e32 v38, v38
	v_rcp_f32_e32 v39, v39
	v_rcp_f32_e32 v40, v40
	v_rcp_f32_e32 v41, v41
	v_cvt_pk_bf16_f32 v91, v54, v42
	v_cvt_pk_bf16_f32 v86, v56, v37
	v_cvt_pk_bf16_f32 v85, v38, v39
	v_cvt_pk_bf16_f32 v84, v40, v41
	v_add_u32_e32 v37, 0x24980, v160
	v_add_u32_e32 v42, 0x24d80, v160
	ds_read_b128 v[38:41], v37
	ds_read_b128 v[42:45], v42
	ds_read_b32 v37, v164
	ds_read_b32 v46, v165
	ds_read_b32 v47, v166
	ds_read_b32 v48, v167
	s_waitcnt lgkmcnt(3)
	v_fma_f32 v16, -v38, v37, v16
	v_fma_f32 v17, -v39, v37, v17
	v_fma_f32 v18, -v40, v37, v18
	v_fma_f32 v19, -v41, v37, v19
	s_waitcnt lgkmcnt(1)
	v_fma_f32 v0, -v38, v47, v0
	v_fma_f32 v1, -v39, v47, v1
	v_fma_f32 v2, -v40, v47, v2
	v_fma_f32 v3, -v41, v47, v3
	v_fma_f32 v16, v46, v16, v42
	v_fma_f32 v17, v46, v17, v43
	v_fma_f32 v18, v46, v18, v44
	v_fma_f32 v19, v46, v19, v45
	s_waitcnt lgkmcnt(0)
; DI unsigned pack2(float a, float b) { f32x2_t v = {a, b}; bf16x2_t r = __builtin_convertvector(v, bf16x2_t); return __builtin_bit_cast(unsigned, r); }
; DI float sigmoidf_(float x) { return __builtin_amdgcn_rcpf(1.f + __expf(-x)); }
; template <bool LAST>
; DI void phase_gate(const Params& P, int layer, unsigned char* smem, int L, int G) {
;     ...
;     unsigned gq[4][2][8];
; #pragma unroll
;     for (int i = 0; i < 4; ++i)
; #pragma unroll
;       for (int q4 = 0; q4 < 4; ++q4) {
;         const int fl = wm * 128 + i * 32 + 8 * q4 + 4 * h;
;         const f32x4 c1v = *(const f32x4*)(vecL + fl), c2v = *(const f32x4*)(vecL + 256 + fl);
;         const float c1a[4] = {c1v.x, c1v.y, c1v.z, c1v.w}, c2a[4] = {c2v.x, c2v.y, c2v.z, c2v.w};
; #pragma unroll
;         for (int j = 0; j < 2; ++j) {
;           const int lrow = wn * 64 + j * 32 + r;
;           const float mu = rowA[lrow], rstd = rowB[lrow];
;           float sg4[4];
; #pragma unroll
;           for (int e = 0; e < 4; ++e) sg4[e] = sigmoidf_(rstd * (accu[i][j][4 * q4 + e] - mu * c1a[e]) + c2a[e]);
;           gq[i][j][2 * q4] = pack2(sg4[0], sg4[1]); gq[i][j][2 * q4 + 1] = pack2(sg4[2], sg4[3]);
;         }
;         __builtin_amdgcn_sched_barrier(0);
;       }
	v_fma_f32 v0, v48, v0, v42
	v_fma_f32 v1, v48, v1, v43
	v_fma_f32 v2, v48, v2, v44
	v_fmac_f32_e32 v45, v48, v3
	v_mul_f32_e32 v16, 0xbfb8aa3b, v16
	v_mul_f32_e32 v17, 0xbfb8aa3b, v17
	v_mul_f32_e32 v18, 0xbfb8aa3b, v18
	v_mul_f32_e32 v19, 0xbfb8aa3b, v19
	v_mul_f32_e32 v0, 0xbfb8aa3b, v0
	v_mul_f32_e32 v1, 0xbfb8aa3b, v1
	v_mul_f32_e32 v2, 0xbfb8aa3b, v2
	v_mul_f32_e32 v3, 0xbfb8aa3b, v45
	v_exp_f32_e32 v16, v16
	v_exp_f32_e32 v17, v17
	v_exp_f32_e32 v18, v18
	v_exp_f32_e32 v19, v19
	v_exp_f32_e32 v0, v0
	v_exp_f32_e32 v1, v1
	v_exp_f32_e32 v2, v2
	v_exp_f32_e32 v3, v3
	v_add_f32_e32 v16, 1.0, v16
	v_add_f32_e32 v17, 1.0, v17
	v_add_f32_e32 v18, 1.0, v18
	v_add_f32_e32 v19, 1.0, v19
	v_add_f32_e32 v0, 1.0, v0
	v_add_f32_e32 v1, 1.0, v1
	v_add_f32_e32 v2, 1.0, v2
	v_add_f32_e32 v3, 1.0, v3
	v_rcp_f32_e32 v16, v16
	v_rcp_f32_e32 v17, v17
	v_rcp_f32_e32 v18, v18
	v_rcp_f32_e32 v19, v19
	v_rcp_f32_e32 v0, v0
	v_rcp_f32_e32 v1, v1
	v_rcp_f32_e32 v2, v2
	v_rcp_f32_e32 v37, v3
	v_cvt_pk_bf16_f32 v17, v16, v17
	v_cvt_pk_bf16_f32 v16, v18, v19
	v_cvt_pk_bf16_f32 v3, v0, v1
	v_cvt_pk_bf16_f32 v2, v2, v37
	v_add_u32_e32 v0, 0x249a0, v160
	v_add_u32_e32 v1, 0x24da0, v160
	ds_read_b128 v[38:41], v0
	ds_read_b128 v[42:45], v1
	ds_read_b32 v0, v164
	ds_read_b32 v1, v165
	ds_read_b32 v18, v166
	ds_read_b32 v19, v167
	s_waitcnt lgkmcnt(3)
	v_fma_f32 v21, -v39, v0, v21
	v_fma_f32 v20, -v38, v0, v20
	s_waitcnt lgkmcnt(1)
	v_fma_f32 v6, -v40, v18, v6
	v_fma_f32 v21, v1, v21, v43
	v_fma_f32 v22, -v40, v0, v22
	v_fma_f32 v0, -v41, v0, v23
	v_fma_f32 v4, -v38, v18, v4
	v_fma_f32 v5, -v39, v18, v5
	s_waitcnt lgkmcnt(0)
	v_fma_f32 v6, v19, v6, v44
	v_fma_f32 v7, -v41, v18, v7
	v_fma_f32 v20, v1, v20, v42
	v_mul_f32_e32 v21, 0xbfb8aa3b, v21
	v_fma_f32 v22, v1, v22, v44
	v_fma_f32 v0, v1, v0, v45
	v_fma_f32 v4, v19, v4, v42
	v_fma_f32 v5, v19, v5, v43
	v_mul_f32_e32 v6, 0xbfb8aa3b, v6
	v_fmac_f32_e32 v45, v19, v7
	v_mul_f32_e32 v20, 0xbfb8aa3b, v20
	v_exp_f32_e32 v21, v21
	v_mul_f32_e32 v22, 0xbfb8aa3b, v22
	v_mul_f32_e32 v0, 0xbfb8aa3b, v0
	v_mul_f32_e32 v4, 0xbfb8aa3b, v4
	v_mul_f32_e32 v5, 0xbfb8aa3b, v5
	v_exp_f32_e32 v6, v6
	v_mul_f32_e32 v7, 0xbfb8aa3b, v45
	v_exp_f32_e32 v20, v20
	v_exp_f32_e32 v22, v22
	v_exp_f32_e32 v0, v0
	v_exp_f32_e32 v4, v4
	v_exp_f32_e32 v5, v5
	v_exp_f32_e32 v7, v7
	v_add_f32_e32 v21, 1.0, v21
	v_add_f32_e32 v6, 1.0, v6
	v_add_f32_e32 v20, 1.0, v20
	v_rcp_f32_e32 v1, v21
	v_add_f32_e32 v21, 1.0, v22
	v_add_f32_e32 v0, 1.0, v0
	v_add_f32_e32 v4, 1.0, v4
	v_add_f32_e32 v5, 1.0, v5
	v_rcp_f32_e32 v18, v6
	v_add_f32_e32 v6, 1.0, v7
	v_rcp_f32_e32 v20, v20
	v_rcp_f32_e32 v21, v21
	v_rcp_f32_e32 v0, v0
	v_rcp_f32_e32 v4, v4
	v_rcp_f32_e32 v5, v5
	v_rcp_f32_e32 v19, v6
	v_cvt_pk_bf16_f32 v7, v20, v1
	v_cvt_pk_bf16_f32 v6, v21, v0
	v_cvt_pk_bf16_f32 v5, v4, v5
	v_cvt_pk_bf16_f32 v4, v18, v19
	v_add_u32_e32 v0, 0x249c0, v160
	v_add_u32_e32 v1, 0x24dc0, v160
	ds_read_b128 v[18:21], v0
	ds_read_b128 v[38:41], v1
	ds_read_b32 v0, v164
	ds_read_b32 v1, v165
	ds_read_b32 v22, v166
	ds_read_b32 v23, v167
	s_waitcnt lgkmcnt(3)
	v_fma_f32 v25, -v19, v0, v25
	v_fma_f32 v24, -v18, v0, v24
	s_waitcnt lgkmcnt(1)
	v_fma_f32 v9, -v19, v22, v9
	s_waitcnt lgkmcnt(0)
	v_fma_f32 v9, v23, v9, v39
	v_fma_f32 v10, -v20, v22, v10
	v_fma_f32 v25, v1, v25, v39
	v_fma_f32 v26, -v20, v0, v26
	v_fma_f32 v0, -v21, v0, v27
	v_fma_f32 v8, -v18, v22, v8
	v_mul_f32_e32 v9, 0xbfb8aa3b, v9
	v_fma_f32 v10, v23, v10, v40
	v_fma_f32 v11, -v21, v22, v11
	v_fma_f32 v24, v1, v24, v38
	v_mul_f32_e32 v25, 0xbfb8aa3b, v25
	v_fma_f32 v26, v1, v26, v40
	v_fma_f32 v0, v1, v0, v41
	v_fma_f32 v8, v23, v8, v38
	v_exp_f32_e32 v9, v9
	v_mul_f32_e32 v10, 0xbfb8aa3b, v10
	v_fmac_f32_e32 v41, v23, v11
	v_mul_f32_e32 v24, 0xbfb8aa3b, v24
	v_exp_f32_e32 v25, v25
	v_mul_f32_e32 v26, 0xbfb8aa3b, v26
	v_mul_f32_e32 v0, 0xbfb8aa3b, v0
	v_mul_f32_e32 v8, 0xbfb8aa3b, v8
	v_exp_f32_e32 v10, v10
	v_mul_f32_e32 v11, 0xbfb8aa3b, v41
	v_exp_f32_e32 v24, v24
	v_exp_f32_e32 v26, v26
	v_exp_f32_e32 v0, v0
	v_exp_f32_e32 v8, v8
	v_exp_f32_e32 v11, v11
	v_add_f32_e32 v9, 1.0, v9
	v_add_f32_e32 v25, 1.0, v25
	v_rcp_f32_e32 v18, v9
	v_add_f32_e32 v9, 1.0, v10
	v_add_f32_e32 v24, 1.0, v24
	v_rcp_f32_e32 v1, v25
	v_add_f32_e32 v25, 1.0, v26
	v_add_f32_e32 v0, 1.0, v0
	v_add_f32_e32 v8, 1.0, v8
	v_rcp_f32_e32 v10, v9
	v_add_f32_e32 v9, 1.0, v11
	v_rcp_f32_e32 v24, v24
	v_rcp_f32_e32 v25, v25
	v_rcp_f32_e32 v0, v0
	v_rcp_f32_e32 v8, v8
	v_rcp_f32_e32 v11, v9
	v_cvt_pk_bf16_f32 v27, v24, v1
	v_cvt_pk_bf16_f32 v9, v25, v0
	v_cvt_pk_bf16_f32 v19, v8, v18
	v_cvt_pk_bf16_f32 v8, v10, v11
	v_add_u32_e32 v0, 0x24de0, v160
	ds_read_b128 v[20:23], v163 offset:480
	ds_read_b32 v1, v164
	ds_read_b128 v[38:41], v0
	ds_read_b32 v0, v165
	ds_read_b32 v10, v166
	ds_read_b32 v18, v167
	s_waitcnt lgkmcnt(4)
	v_fma_f32 v24, -v21, v1, v29
	v_fma_f32 v11, -v20, v1, v28
	s_waitcnt lgkmcnt(2)
	v_fma_f32 v24, v0, v24, v39
	v_fma_f32 v25, -v22, v1, v30
	v_fma_f32 v1, -v23, v1, v31
	s_waitcnt lgkmcnt(1)
	v_fma_f32 v12, -v20, v10, v12
	v_fma_f32 v13, -v21, v10, v13
	v_fma_f32 v14, -v22, v10, v14
	v_fma_f32 v10, -v23, v10, v15
	v_fma_f32 v11, v0, v11, v38
	v_mul_f32_e32 v24, 0xbfb8aa3b, v24
	v_fma_f32 v25, v0, v25, v40
	v_fma_f32 v0, v0, v1, v41
	s_waitcnt lgkmcnt(0)
; DI unsigned pack2(float a, float b) { f32x2_t v = {a, b}; bf16x2_t r = __builtin_convertvector(v, bf16x2_t); return __builtin_bit_cast(unsigned, r); }
; DI float sigmoidf_(float x) { return __builtin_amdgcn_rcpf(1.f + __expf(-x)); }
; DI int otid() { int t = threadIdx.x; asm volatile("" : "+v"(t)); return t; }
; template <bool NT>
; DI void stage_load_tile(bf16_t* stg, const bf16_t* tilebase) {
;   const int tid = otid();
;   const int r0 = tid >> 5, c = tid & 31;
;   const unsigned o0 = (unsigned)(r0 * 1024 + c * 8);
;   __builtin_amdgcn_sched_barrier(0);
; #pragma unroll
;   for (int hf = 0; hf < 2; ++hf) {
; #pragma unroll
;     for (int it = 8 * hf; it < 8 * hf + 8; ++it) {
;       const u32x4* gp = (const u32x4*)(tilebase + (o0 + (unsigned)(it * 16 * 1024)));
;       stage_write16(stg, r0 + 16 * it, c, NT ? __builtin_nontemporal_load(gp) : *gp);
;     }
;     __builtin_amdgcn_sched_barrier(0);
;   }
; }
; template <bool LAST>
; DI void phase_gate(const Params& P, int layer, unsigned char* smem, int L, int G) {
;     ...
;     unsigned gq[4][2][8];
; #pragma unroll
;     for (int i = 0; i < 4; ++i)
; #pragma unroll
;       for (int q4 = 0; q4 < 4; ++q4) {
;         const int fl = wm * 128 + i * 32 + 8 * q4 + 4 * h;
;         const f32x4 c1v = *(const f32x4*)(vecL + fl), c2v = *(const f32x4*)(vecL + 256 + fl);
;         const float c1a[4] = {c1v.x, c1v.y, c1v.z, c1v.w}, c2a[4] = {c2v.x, c2v.y, c2v.z, c2v.w};
; #pragma unroll
;         for (int j = 0; j < 2; ++j) {
;           const int lrow = wn * 64 + j * 32 + r;
;           const float mu = rowA[lrow], rstd = rowB[lrow];
;           float sg4[4];
; #pragma unroll
;           for (int e = 0; e < 4; ++e) sg4[e] = sigmoidf_(rstd * (accu[i][j][4 * q4 + e] - mu * c1a[e]) + c2a[e]);
;           gq[i][j][2 * q4] = pack2(sg4[0], sg4[1]); gq[i][j][2 * q4 + 1] = pack2(sg4[2], sg4[3]);
;         }
;         __builtin_amdgcn_sched_barrier(0);
;       }
	v_fma_f32 v12, v18, v12, v38
	v_fma_f32 v13, v18, v13, v39
	v_fma_f32 v14, v18, v14, v40
	v_fmac_f32_e32 v41, v18, v10
	v_mul_f32_e32 v11, 0xbfb8aa3b, v11
	v_exp_f32_e32 v24, v24
	v_mul_f32_e32 v25, 0xbfb8aa3b, v25
	v_mul_f32_e32 v0, 0xbfb8aa3b, v0
	v_mul_f32_e32 v12, 0xbfb8aa3b, v12
	v_mul_f32_e32 v13, 0xbfb8aa3b, v13
	v_mul_f32_e32 v14, 0xbfb8aa3b, v14
	v_mul_f32_e32 v10, 0xbfb8aa3b, v41
	v_exp_f32_e32 v11, v11
	v_exp_f32_e32 v25, v25
	v_exp_f32_e32 v0, v0
	v_exp_f32_e32 v12, v12
	v_exp_f32_e32 v13, v13
	v_exp_f32_e32 v14, v14
	v_exp_f32_e32 v10, v10
	v_add_f32_e32 v24, 1.0, v24
	v_add_f32_e32 v11, 1.0, v11
	v_rcp_f32_e32 v1, v24
	v_add_f32_e32 v24, 1.0, v25
	v_add_f32_e32 v0, 1.0, v0
	v_add_f32_e32 v12, 1.0, v12
	v_add_f32_e32 v13, 1.0, v13
	v_add_f32_e32 v14, 1.0, v14
	v_add_f32_e32 v10, 1.0, v10
	v_rcp_f32_e32 v11, v11
	v_rcp_f32_e32 v24, v24
	v_rcp_f32_e32 v0, v0
	v_rcp_f32_e32 v12, v12
	v_rcp_f32_e32 v13, v13
	v_rcp_f32_e32 v14, v14
	v_rcp_f32_e32 v10, v10
	v_cvt_pk_bf16_f32 v112, v11, v1
	v_cvt_pk_bf16_f32 v30, v24, v0
	v_cvt_pk_bf16_f32 v29, v12, v13
	v_cvt_pk_bf16_f32 v28, v14, v10
	s_ashr_i32 s19, s18, 31
	s_lshl_b64 s[18:19], s[18:19], 19
	v_mov_b32_e32 v10, v192
	s_add_u32 s20, s66, s18
	v_mov_b32_e32 v163, v161
	s_addc_u32 s21, s67, s19
	v_and_b32_e32 v26, 31, v10
	v_lshlrev_b64 v[0:1], 1, v[162:163]
	v_ashrrev_i32_e32 v18, 5, v10
	v_lshlrev_b32_e32 v10, 3, v26
	v_lshl_add_u64 v[14:15], s[20:21], 0, v[0:1]
	v_lshl_or_b32 v160, v18, 10, v10
	v_add_u32_e32 v12, 0x4000, v160
	v_mov_b32_e32 v13, v161
	v_add_u32_e32 v24, 0x8000, v160
	v_mov_b32_e32 v25, v161
	v_add_u32_e32 v38, 0xc000, v160
	v_mov_b32_e32 v39, v161
	v_lshl_add_u64 v[10:11], v[160:161], 1, v[14:15]
	v_lshl_add_u64 v[20:21], v[12:13], 1, v[14:15]
	v_lshl_add_u64 v[24:25], v[24:25], 1, v[14:15]
	v_lshl_add_u64 v[42:43], v[38:39], 1, v[14:15]
	global_load_dwordx4 v[10:13], v[10:11], off nt
	s_nop 0
	global_load_dwordx4 v[20:23], v[20:21], off nt
	s_nop 0
	global_load_dwordx4 v[38:41], v[24:25], off nt
	s_nop 0
	global_load_dwordx4 v[42:45], v[42:43], off nt
	v_add_u32_e32 v24, 0x10000, v160
	v_mov_b32_e32 v25, v161
	v_lshl_add_u64 v[24:25], v[24:25], 1, v[14:15]
	v_add_u32_e32 v46, 0x14000, v160
	v_mov_b32_e32 v47, v161
	v_lshl_add_u64 v[50:51], v[46:47], 1, v[14:15]
	global_load_dwordx4 v[46:49], v[24:25], off nt
	global_load_dwordx4 v[60:63], v[50:51], off nt
	v_add_u32_e32 v24, 0x18000, v160
	v_mov_b32_e32 v25, v161
	v_lshl_add_u64 v[24:25], v[24:25], 1, v[14:15]
	v_add_u32_e32 v50, 0x1c000, v160
	v_mov_b32_e32 v51, v161
	v_lshl_add_u64 v[50:51], v[50:51], 1, v[14:15]
	global_load_dwordx4 v[92:95], v[24:25], off nt
	global_load_dwordx4 v[114:117], v[50:51], off nt
	v_add_u32_e32 v218, 0x20000, v160
	v_mov_b32_e32 v219, v161
	v_add_u32_e32 v220, 0x24000, v160
	v_mov_b32_e32 v221, v161
	v_add_u32_e32 v252, 0x28000, v160
	v_mov_b32_e32 v253, v161
	v_add_u32_e32 v226, 0x2c000, v160
	v_mov_b32_e32 v227, v161
	v_lshl_add_u64 v[218:219], v[218:219], 1, v[14:15]
	v_lshl_add_u64 v[222:223], v[220:221], 1, v[14:15]
	v_lshl_add_u64 v[252:253], v[252:253], 1, v[14:15]
	v_lshl_add_u64 v[230:231], v[226:227], 1, v[14:15]
	global_load_dwordx4 v[218:221], v[218:219], off nt
	s_nop 0
	global_load_dwordx4 v[222:225], v[222:223], off nt
	s_nop 0
	global_load_dwordx4 v[226:229], v[252:253], off nt
	s_nop 0
	global_load_dwordx4 v[230:233], v[230:231], off nt
	v_add_u32_e32 v252, 0x30000, v160
	v_mov_b32_e32 v253, v161
	v_lshl_add_u64 v[252:253], v[252:253], 1, v[14:15]
	v_add_u32_e32 v234, 0x34000, v160
	v_mov_b32_e32 v235, v161
	v_lshl_add_u64 v[254:255], v[234:235], 1, v[14:15]
	global_load_dwordx4 v[234:237], v[252:253], off nt
	global_load_dwordx4 v[238:241], v[254:255], off nt
	v_add_u32_e32 v252, 0x38000, v160
	v_mov_b32_e32 v253, v161
	v_lshl_add_u64 v[252:253], v[252:253], 1, v[14:15]
	v_add_u32_e32 v160, 0x3c000, v160
	v_lshl_add_u64 v[190:191], v[160:161], 1, v[14:15]
	global_load_dwordx4 v[242:245], v[252:253], off nt
	global_load_dwordx4 v[248:251], v[190:191], off nt
	v_mul_lo_u32 v18, v18, s34
	v_lshl_add_u32 v18, v26, 4, v18
	v_add_u32_e32 v24, 0x2080, v18
	v_add_u32_e32 v25, 0x4100, v18
	v_add_u32_e32 v26, 0x6180, v18
	v_add_u32_e32 v31, 0x8200, v18
	v_add_u32_e32 v37, 0xa280, v18
	v_add_u32_e32 v50, 0xc300, v18
	v_add_u32_e32 v51, 0xe380, v18
	s_waitcnt vmcnt(15)
	ds_write2_b64 v18, v[10:11], v[12:13] offset1:1
	s_waitcnt vmcnt(14)
	ds_write2_b64 v24, v[20:21], v[22:23] offset1:1
	s_waitcnt vmcnt(13)
	ds_write2_b64 v25, v[38:39], v[40:41] offset1:1
	s_waitcnt vmcnt(12)
	ds_write2_b64 v26, v[42:43], v[44:45] offset1:1
	s_waitcnt vmcnt(11)
	ds_write2_b64 v31, v[46:47], v[48:49] offset1:1
	s_waitcnt vmcnt(10)
	ds_write2_b64 v37, v[60:61], v[62:63] offset1:1
	s_waitcnt vmcnt(9)
	ds_write2_b64 v50, v[92:93], v[94:95] offset1:1
	s_waitcnt vmcnt(8)
	ds_write2_b64 v51, v[114:115], v[116:117] offset1:1
	v_add_u32_e32 v14, 0x10400, v18
	v_add_u32_e32 v15, 0x12480, v18
	v_add_u32_e32 v24, 0x14500, v18
	v_add_u32_e32 v25, 0x16580, v18
	v_add_u32_e32 v26, 0x18600, v18
	v_add_u32_e32 v31, 0x1a680, v18
	v_add_u32_e32 v37, 0x1c700, v18
	v_add_u32_e32 v18, 0x1e780, v18
	s_waitcnt vmcnt(7)
	ds_write2_b64 v14, v[218:219], v[220:221] offset1:1
	s_waitcnt vmcnt(6)
	ds_write2_b64 v15, v[222:223], v[224:225] offset1:1
	s_waitcnt vmcnt(5)
	ds_write2_b64 v24, v[226:227], v[228:229] offset1:1
	s_waitcnt vmcnt(4)
	ds_write2_b64 v25, v[230:231], v[232:233] offset1:1
	s_waitcnt vmcnt(3)
	ds_write2_b64 v26, v[234:235], v[236:237] offset1:1
	s_waitcnt vmcnt(2)
	ds_write2_b64 v31, v[238:239], v[240:241] offset1:1
	s_waitcnt vmcnt(1)
	ds_write2_b64 v37, v[242:243], v[244:245] offset1:1
	s_waitcnt vmcnt(0)
	ds_write2_b64 v18, v[248:249], v[250:251] offset1:1
	v_mov_b32_e32 v10, v192
	s_waitcnt lgkmcnt(0)
	s_barrier
; DI unsigned pack2(float a, float b) { f32x2_t v = {a, b}; bf16x2_t r = __builtin_convertvector(v, bf16x2_t); return __builtin_bit_cast(unsigned, r); }
; DI float bflo(unsigned u) { return __uint_as_float(u << 16); }
; DI float bfhi(unsigned u) { return __uint_as_float(u & 0xffff0000u); }
; DI int otid() { int t = threadIdx.x; asm volatile("" : "+v"(t)); return t; }
; template <bool LAST>
; DI void phase_gate(const Params& P, int layer, unsigned char* smem, int L, int G) {
;     ...
;     {
;       const int tid1 = otid();
;       const int lane1 = tid1 & 63, w1 = tid1 >> 6, r1 = lane1 & 31, h1 = lane1 >> 5, wm1 = w1 >> 2, wn1 = w1 & 3;
; #pragma unroll
;       for (int i = 0; i < 4; ++i)
; #pragma unroll
;         for (int q4 = 0; q4 < 4; ++q4) {
; #pragma unroll
;           for (int j = 0; j < 2; ++j) {
;             const uint2 pv = *(const uint2*)(stg + (wn1 * 64 + j * 32 + r1) * STG + wm1 * 128 + i * 32 + 8 * q4 + 4 * h1);
;             const unsigned g0 = gq[i][j][2 * q4], g1 = gq[i][j][2 * q4 + 1];
;             gq[i][j][2 * q4] = pack2(bflo(g0) * bflo(pv.x), bfhi(g0) * bfhi(pv.x));
;             gq[i][j][2 * q4 + 1] = pack2(bflo(g1) * bflo(pv.y), bfhi(g1) * bfhi(pv.y));
;           }
;           __builtin_amdgcn_sched_barrier(0);
;         }
;     }
	v_and_b32_e32 v13, 0xffff0000, v99
	v_lshrrev_b32_e32 v12, 2, v10
	v_and_b32_e32 v12, 8, v12
	v_and_b32_e32 v11, 0xdf, v10
	v_and_or_b32 v10, v10, s31, v12
	v_mad_u32_u24 v113, v11, s34, v10
	ds_read_b64 v[10:11], v113
	ds_read_b64 v[14:15], v113 offset:16640
	v_lshlrev_b32_e32 v12, 16, v99
	s_waitcnt lgkmcnt(1)
	v_lshlrev_b32_e32 v20, 16, v10
	v_and_b32_e32 v21, 0xffff0000, v10
	v_pk_mul_f32 v[12:13], v[12:13], v[20:21]
	v_lshlrev_b32_e32 v10, 16, v11
	v_cvt_pk_bf16_f32 v31, v12, v13
	v_lshlrev_b32_e32 v12, 16, v98
	v_and_b32_e32 v13, 0xffff0000, v98
	v_and_b32_e32 v11, 0xffff0000, v11
	v_pk_mul_f32 v[10:11], v[12:13], v[10:11]
	s_waitcnt lgkmcnt(0)
	v_lshlrev_b32_e32 v12, 16, v14
	v_cvt_pk_bf16_f32 v98, v10, v11
	v_lshlrev_b32_e32 v10, 16, v97
	v_and_b32_e32 v11, 0xffff0000, v97
	v_and_b32_e32 v13, 0xffff0000, v14
	v_pk_mul_f32 v[10:11], v[10:11], v[12:13]
	v_lshlrev_b32_e32 v12, 16, v15
	v_cvt_pk_bf16_f32 v97, v10, v11
	v_lshlrev_b32_e32 v10, 16, v96
	v_and_b32_e32 v11, 0xffff0000, v96
	v_and_b32_e32 v13, 0xffff0000, v15
	v_pk_mul_f32 v[10:11], v[10:11], v[12:13]
	s_nop 0
	v_cvt_pk_bf16_f32 v96, v10, v11
	ds_read_b64 v[10:11], v113 offset:16
	ds_read_b64 v[14:15], v113 offset:16656
	v_lshlrev_b32_e32 v12, 16, v103
	v_and_b32_e32 v13, 0xffff0000, v103
	s_waitcnt lgkmcnt(1)
	v_lshlrev_b32_e32 v20, 16, v10
	v_and_b32_e32 v21, 0xffff0000, v10
	v_pk_mul_f32 v[12:13], v[12:13], v[20:21]
	v_lshlrev_b32_e32 v10, 16, v11
	v_cvt_pk_bf16_f32 v93, v12, v13
	v_lshlrev_b32_e32 v12, 16, v102
	v_and_b32_e32 v13, 0xffff0000, v102
	v_and_b32_e32 v11, 0xffff0000, v11
	v_pk_mul_f32 v[10:11], v[12:13], v[10:11]
	s_waitcnt lgkmcnt(0)
	v_lshlrev_b32_e32 v12, 16, v14
	v_cvt_pk_bf16_f32 v95, v10, v11
	v_lshlrev_b32_e32 v10, 16, v101
	v_and_b32_e32 v11, 0xffff0000, v101
	v_and_b32_e32 v13, 0xffff0000, v14
	v_pk_mul_f32 v[10:11], v[10:11], v[12:13]
	v_lshlrev_b32_e32 v12, 16, v15
	v_cvt_pk_bf16_f32 v92, v10, v11
	v_lshlrev_b32_e32 v10, 16, v100
	v_and_b32_e32 v11, 0xffff0000, v100
	v_and_b32_e32 v13, 0xffff0000, v15
	v_pk_mul_f32 v[10:11], v[10:11], v[12:13]
	s_nop 0
	v_cvt_pk_bf16_f32 v94, v10, v11
	ds_read_b64 v[10:11], v113 offset:32
	ds_read_b64 v[14:15], v113 offset:16672
	v_lshlrev_b32_e32 v12, 16, v107
	v_and_b32_e32 v13, 0xffff0000, v107
	s_waitcnt lgkmcnt(1)
	v_lshlrev_b32_e32 v20, 16, v10
	v_and_b32_e32 v21, 0xffff0000, v10
	v_pk_mul_f32 v[12:13], v[12:13], v[20:21]
	v_lshlrev_b32_e32 v10, 16, v11
	v_cvt_pk_bf16_f32 v88, v12, v13
	v_lshlrev_b32_e32 v12, 16, v106
	v_and_b32_e32 v13, 0xffff0000, v106
	v_and_b32_e32 v11, 0xffff0000, v11
	v_pk_mul_f32 v[10:11], v[12:13], v[10:11]
	s_waitcnt lgkmcnt(0)
	v_lshlrev_b32_e32 v12, 16, v14
	v_cvt_pk_bf16_f32 v90, v10, v11
	v_lshlrev_b32_e32 v10, 16, v105
	v_and_b32_e32 v11, 0xffff0000, v105
	v_and_b32_e32 v13, 0xffff0000, v14
	v_pk_mul_f32 v[10:11], v[10:11], v[12:13]
	v_lshlrev_b32_e32 v12, 16, v15
	v_cvt_pk_bf16_f32 v87, v10, v11
	v_lshlrev_b32_e32 v10, 16, v104
	v_and_b32_e32 v11, 0xffff0000, v104
	v_and_b32_e32 v13, 0xffff0000, v15
	v_pk_mul_f32 v[10:11], v[10:11], v[12:13]
	s_nop 0
	v_cvt_pk_bf16_f32 v89, v10, v11
	ds_read_b64 v[10:11], v113 offset:48
	ds_read_b64 v[14:15], v113 offset:16688
	v_lshlrev_b32_e32 v12, 16, v111
	v_and_b32_e32 v13, 0xffff0000, v111
	s_waitcnt lgkmcnt(1)
	v_lshlrev_b32_e32 v20, 16, v10
	v_and_b32_e32 v21, 0xffff0000, v10
	v_pk_mul_f32 v[12:13], v[12:13], v[20:21]
	v_lshlrev_b32_e32 v10, 16, v11
	v_cvt_pk_bf16_f32 v61, v12, v13
	v_lshlrev_b32_e32 v12, 16, v110
	v_and_b32_e32 v13, 0xffff0000, v110
	v_and_b32_e32 v11, 0xffff0000, v11
	v_pk_mul_f32 v[10:11], v[12:13], v[10:11]
	s_waitcnt lgkmcnt(0)
	v_lshlrev_b32_e32 v12, 16, v14
	v_cvt_pk_bf16_f32 v63, v10, v11
	v_lshlrev_b32_e32 v10, 16, v109
	v_and_b32_e32 v11, 0xffff0000, v109
	v_and_b32_e32 v13, 0xffff0000, v14
	v_pk_mul_f32 v[10:11], v[10:11], v[12:13]
	v_lshlrev_b32_e32 v12, 16, v15
	v_cvt_pk_bf16_f32 v60, v10, v11
	v_lshlrev_b32_e32 v10, 16, v108
	v_and_b32_e32 v11, 0xffff0000, v108
	v_and_b32_e32 v13, 0xffff0000, v15
	v_pk_mul_f32 v[10:11], v[10:11], v[12:13]
	s_nop 0
	v_cvt_pk_bf16_f32 v62, v10, v11
	ds_read_b64 v[10:11], v113 offset:64
	ds_read_b64 v[14:15], v113 offset:16704
	v_lshlrev_b32_e32 v12, 16, v67
	v_and_b32_e32 v13, 0xffff0000, v67
	s_waitcnt lgkmcnt(1)
	v_lshlrev_b32_e32 v20, 16, v10
	v_and_b32_e32 v21, 0xffff0000, v10
	v_pk_mul_f32 v[12:13], v[12:13], v[20:21]
	v_lshlrev_b32_e32 v10, 16, v11
	v_cvt_pk_bf16_f32 v56, v12, v13
	v_lshlrev_b32_e32 v12, 16, v66
	v_and_b32_e32 v13, 0xffff0000, v66
	v_and_b32_e32 v11, 0xffff0000, v11
	v_pk_mul_f32 v[10:11], v[12:13], v[10:11]
	s_waitcnt lgkmcnt(0)
	v_lshlrev_b32_e32 v12, 16, v14
	v_cvt_pk_bf16_f32 v58, v10, v11
	v_lshlrev_b32_e32 v10, 16, v65
	v_and_b32_e32 v11, 0xffff0000, v65
	v_and_b32_e32 v13, 0xffff0000, v14
	v_pk_mul_f32 v[10:11], v[10:11], v[12:13]
	v_lshlrev_b32_e32 v12, 16, v15
	v_cvt_pk_bf16_f32 v54, v10, v11
	v_lshlrev_b32_e32 v10, 16, v64
	v_and_b32_e32 v11, 0xffff0000, v64
	v_and_b32_e32 v13, 0xffff0000, v15
	v_pk_mul_f32 v[10:11], v[10:11], v[12:13]
	s_nop 0
	v_cvt_pk_bf16_f32 v57, v10, v11
	ds_read_b64 v[10:11], v113 offset:80
	ds_read_b64 v[14:15], v113 offset:16720
	v_lshlrev_b32_e32 v12, 16, v71
	v_and_b32_e32 v13, 0xffff0000, v71
	s_waitcnt lgkmcnt(1)
	v_lshlrev_b32_e32 v20, 16, v10
	v_and_b32_e32 v21, 0xffff0000, v10
	v_pk_mul_f32 v[12:13], v[12:13], v[20:21]
	v_lshlrev_b32_e32 v10, 16, v11
	v_cvt_pk_bf16_f32 v50, v12, v13
	v_lshlrev_b32_e32 v12, 16, v70
	v_and_b32_e32 v13, 0xffff0000, v70
	v_and_b32_e32 v11, 0xffff0000, v11
	v_pk_mul_f32 v[10:11], v[12:13], v[10:11]
	s_waitcnt lgkmcnt(0)
; DI unsigned pack2(float a, float b) { f32x2_t v = {a, b}; bf16x2_t r = __builtin_convertvector(v, bf16x2_t); return __builtin_bit_cast(unsigned, r); }
; DI float bflo(unsigned u) { return __uint_as_float(u << 16); }
; DI float bfhi(unsigned u) { return __uint_as_float(u & 0xffff0000u); }
; DI int otid() { int t = threadIdx.x; asm volatile("" : "+v"(t)); return t; }
; template <bool LAST>
; DI void phase_gate(const Params& P, int layer, unsigned char* smem, int L, int G) {
;     ...
;     {
;       const int tid1 = otid();
;       const int lane1 = tid1 & 63, w1 = tid1 >> 6, r1 = lane1 & 31, h1 = lane1 >> 5, wm1 = w1 >> 2, wn1 = w1 & 3;
; #pragma unroll
;       for (int i = 0; i < 4; ++i)
; #pragma unroll
;         for (int q4 = 0; q4 < 4; ++q4) {
; #pragma unroll
;           for (int j = 0; j < 2; ++j) {
;             const uint2 pv = *(const uint2*)(stg + (wn1 * 64 + j * 32 + r1) * STG + wm1 * 128 + i * 32 + 8 * q4 + 4 * h1);
;             const unsigned g0 = gq[i][j][2 * q4], g1 = gq[i][j][2 * q4 + 1];
;             gq[i][j][2 * q4] = pack2(bflo(g0) * bflo(pv.x), bfhi(g0) * bfhi(pv.x));
;             gq[i][j][2 * q4 + 1] = pack2(bflo(g1) * bflo(pv.y), bfhi(g1) * bfhi(pv.y));
;           }
;           __builtin_amdgcn_sched_barrier(0);
;         }
;     }
	v_lshlrev_b32_e32 v12, 16, v14
	v_cvt_pk_bf16_f32 v52, v10, v11
	v_lshlrev_b32_e32 v10, 16, v69
	v_and_b32_e32 v11, 0xffff0000, v69
	v_and_b32_e32 v13, 0xffff0000, v14
	v_pk_mul_f32 v[10:11], v[10:11], v[12:13]
	v_lshlrev_b32_e32 v12, 16, v15
	v_cvt_pk_bf16_f32 v49, v10, v11
	v_lshlrev_b32_e32 v10, 16, v68
	v_and_b32_e32 v11, 0xffff0000, v68
	v_and_b32_e32 v13, 0xffff0000, v15
	v_pk_mul_f32 v[10:11], v[10:11], v[12:13]
	s_nop 0
	v_cvt_pk_bf16_f32 v51, v10, v11
	ds_read_b64 v[10:11], v113 offset:96
	ds_read_b64 v[14:15], v113 offset:16736
	v_lshlrev_b32_e32 v12, 16, v75
	v_and_b32_e32 v13, 0xffff0000, v75
	s_waitcnt lgkmcnt(1)
	v_lshlrev_b32_e32 v20, 16, v10
	v_and_b32_e32 v21, 0xffff0000, v10
	v_pk_mul_f32 v[12:13], v[12:13], v[20:21]
	v_lshlrev_b32_e32 v10, 16, v11
	v_cvt_pk_bf16_f32 v46, v12, v13
	v_lshlrev_b32_e32 v12, 16, v74
	v_and_b32_e32 v13, 0xffff0000, v74
	v_and_b32_e32 v11, 0xffff0000, v11
	v_pk_mul_f32 v[10:11], v[12:13], v[10:11]
	s_waitcnt lgkmcnt(0)
	v_lshlrev_b32_e32 v12, 16, v14
	v_cvt_pk_bf16_f32 v48, v10, v11
	v_lshlrev_b32_e32 v10, 16, v73
	v_and_b32_e32 v11, 0xffff0000, v73
	v_and_b32_e32 v13, 0xffff0000, v14
	v_pk_mul_f32 v[10:11], v[10:11], v[12:13]
	v_lshlrev_b32_e32 v12, 16, v15
	v_cvt_pk_bf16_f32 v45, v10, v11
	v_lshlrev_b32_e32 v10, 16, v72
	v_and_b32_e32 v11, 0xffff0000, v72
	v_and_b32_e32 v13, 0xffff0000, v15
	v_pk_mul_f32 v[10:11], v[10:11], v[12:13]
	s_nop 0
	v_cvt_pk_bf16_f32 v47, v10, v11
	ds_read_b64 v[10:11], v113 offset:112
	ds_read_b64 v[14:15], v113 offset:16752
	v_lshlrev_b32_e32 v12, 16, v79
	v_and_b32_e32 v13, 0xffff0000, v79
	s_waitcnt lgkmcnt(1)
	v_lshlrev_b32_e32 v20, 16, v10
	v_and_b32_e32 v21, 0xffff0000, v10
	v_pk_mul_f32 v[12:13], v[12:13], v[20:21]
	v_lshlrev_b32_e32 v10, 16, v11
	v_cvt_pk_bf16_f32 v42, v12, v13
	v_lshlrev_b32_e32 v12, 16, v78
	v_and_b32_e32 v13, 0xffff0000, v78
	v_and_b32_e32 v11, 0xffff0000, v11
	v_pk_mul_f32 v[10:11], v[12:13], v[10:11]
	s_waitcnt lgkmcnt(0)
	v_lshlrev_b32_e32 v12, 16, v14
	v_cvt_pk_bf16_f32 v44, v10, v11
	v_lshlrev_b32_e32 v10, 16, v77
	v_and_b32_e32 v11, 0xffff0000, v77
	v_and_b32_e32 v13, 0xffff0000, v14
	v_pk_mul_f32 v[10:11], v[10:11], v[12:13]
	v_lshlrev_b32_e32 v12, 16, v15
	v_cvt_pk_bf16_f32 v41, v10, v11
	v_lshlrev_b32_e32 v10, 16, v76
	v_and_b32_e32 v11, 0xffff0000, v76
	v_and_b32_e32 v13, 0xffff0000, v15
	v_pk_mul_f32 v[10:11], v[10:11], v[12:13]
	s_nop 0
	v_cvt_pk_bf16_f32 v43, v10, v11
	ds_read_b64 v[10:11], v113 offset:128
	ds_read_b64 v[14:15], v113 offset:16768
	v_lshlrev_b32_e32 v12, 16, v35
	v_and_b32_e32 v13, 0xffff0000, v35
	s_waitcnt lgkmcnt(1)
	v_lshlrev_b32_e32 v20, 16, v10
	v_and_b32_e32 v21, 0xffff0000, v10
	v_pk_mul_f32 v[12:13], v[12:13], v[20:21]
	v_lshlrev_b32_e32 v10, 16, v11
	v_cvt_pk_bf16_f32 v38, v12, v13
	v_lshlrev_b32_e32 v12, 16, v34
	v_and_b32_e32 v13, 0xffff0000, v34
	v_and_b32_e32 v11, 0xffff0000, v11
	v_pk_mul_f32 v[10:11], v[12:13], v[10:11]
	s_waitcnt lgkmcnt(0)
	v_lshlrev_b32_e32 v12, 16, v14
	v_cvt_pk_bf16_f32 v40, v10, v11
	v_lshlrev_b32_e32 v10, 16, v33
	v_and_b32_e32 v11, 0xffff0000, v33
	v_and_b32_e32 v13, 0xffff0000, v14
	v_pk_mul_f32 v[10:11], v[10:11], v[12:13]
	v_lshlrev_b32_e32 v12, 16, v15
	v_cvt_pk_bf16_f32 v37, v10, v11
	v_lshlrev_b32_e32 v10, 16, v32
	v_and_b32_e32 v11, 0xffff0000, v32
	v_and_b32_e32 v13, 0xffff0000, v15
	v_pk_mul_f32 v[10:11], v[10:11], v[12:13]
	s_nop 0
	v_cvt_pk_bf16_f32 v39, v10, v11
	ds_read_b64 v[10:11], v113 offset:144
	ds_read_b64 v[14:15], v113 offset:16784
	v_lshlrev_b32_e32 v12, 16, v80
	v_and_b32_e32 v13, 0xffff0000, v80
	s_waitcnt lgkmcnt(1)
	v_lshlrev_b32_e32 v20, 16, v10
	v_and_b32_e32 v21, 0xffff0000, v10
	v_pk_mul_f32 v[12:13], v[12:13], v[20:21]
	v_lshlrev_b32_e32 v10, 16, v11
	v_cvt_pk_bf16_f32 v34, v12, v13
	v_lshlrev_b32_e32 v12, 16, v36
	v_and_b32_e32 v13, 0xffff0000, v36
	v_and_b32_e32 v11, 0xffff0000, v11
	v_pk_mul_f32 v[10:11], v[12:13], v[10:11]
	s_waitcnt lgkmcnt(0)
	v_lshlrev_b32_e32 v12, 16, v14
	v_cvt_pk_bf16_f32 v36, v10, v11
	v_lshlrev_b32_e32 v10, 16, v55
	v_and_b32_e32 v11, 0xffff0000, v55
	v_and_b32_e32 v13, 0xffff0000, v14
	v_pk_mul_f32 v[10:11], v[10:11], v[12:13]
	v_lshlrev_b32_e32 v12, 16, v15
	v_cvt_pk_bf16_f32 v32, v10, v11
	v_lshlrev_b32_e32 v10, 16, v53
	v_and_b32_e32 v11, 0xffff0000, v53
	v_and_b32_e32 v13, 0xffff0000, v15
	v_pk_mul_f32 v[10:11], v[10:11], v[12:13]
	s_nop 0
	v_cvt_pk_bf16_f32 v35, v10, v11
	ds_read_b64 v[10:11], v113 offset:160
	ds_read_b64 v[14:15], v113 offset:16800
	v_lshlrev_b32_e32 v12, 16, v83
	v_and_b32_e32 v13, 0xffff0000, v83
	s_waitcnt lgkmcnt(1)
	v_lshlrev_b32_e32 v20, 16, v10
	v_and_b32_e32 v21, 0xffff0000, v10
	v_pk_mul_f32 v[12:13], v[12:13], v[20:21]
	v_lshlrev_b32_e32 v10, 16, v11
	v_cvt_pk_bf16_f32 v24, v12, v13
	v_lshlrev_b32_e32 v12, 16, v82
	v_and_b32_e32 v13, 0xffff0000, v82
	v_and_b32_e32 v11, 0xffff0000, v11
	v_pk_mul_f32 v[10:11], v[12:13], v[10:11]
	s_waitcnt lgkmcnt(0)
	v_lshlrev_b32_e32 v12, 16, v14
	v_cvt_pk_bf16_f32 v26, v10, v11
	v_lshlrev_b32_e32 v10, 16, v81
	v_and_b32_e32 v11, 0xffff0000, v81
	v_and_b32_e32 v13, 0xffff0000, v14
	v_pk_mul_f32 v[10:11], v[10:11], v[12:13]
	v_lshlrev_b32_e32 v12, 16, v15
	v_cvt_pk_bf16_f32 v23, v10, v11
	v_lshlrev_b32_e32 v10, 16, v59
	v_and_b32_e32 v11, 0xffff0000, v59
	v_and_b32_e32 v13, 0xffff0000, v15
	v_pk_mul_f32 v[10:11], v[10:11], v[12:13]
	s_nop 0
	v_cvt_pk_bf16_f32 v25, v10, v11
	ds_read_b64 v[10:11], v113 offset:176
	ds_read_b64 v[14:15], v113 offset:16816
	v_lshlrev_b32_e32 v12, 16, v91
	v_and_b32_e32 v13, 0xffff0000, v91
	s_waitcnt lgkmcnt(1)
; DI unsigned pack2(float a, float b) { f32x2_t v = {a, b}; bf16x2_t r = __builtin_convertvector(v, bf16x2_t); return __builtin_bit_cast(unsigned, r); }
; DI float bflo(unsigned u) { return __uint_as_float(u << 16); }
; DI float bfhi(unsigned u) { return __uint_as_float(u & 0xffff0000u); }
; template <bool LAST>
; DI void phase_gate(const Params& P, int layer, unsigned char* smem, int L, int G) {
;     ...
; #pragma unroll
;       for (int i = 0; i < 4; ++i)
; #pragma unroll
;         for (int q4 = 0; q4 < 4; ++q4) {
; #pragma unroll
;           for (int j = 0; j < 2; ++j) {
;             const uint2 pv = *(const uint2*)(stg + (wn1 * 64 + j * 32 + r1) * STG + wm1 * 128 + i * 32 + 8 * q4 + 4 * h1);
;             const unsigned g0 = gq[i][j][2 * q4], g1 = gq[i][j][2 * q4 + 1];
;             gq[i][j][2 * q4] = pack2(bflo(g0) * bflo(pv.x), bfhi(g0) * bfhi(pv.x));
;             gq[i][j][2 * q4 + 1] = pack2(bflo(g1) * bflo(pv.y), bfhi(g1) * bfhi(pv.y));
;           }
;           __builtin_amdgcn_sched_barrier(0);
;         }
;     }
;     __syncthreads();
	v_lshlrev_b32_e32 v20, 16, v10
	v_and_b32_e32 v21, 0xffff0000, v10
	v_pk_mul_f32 v[12:13], v[12:13], v[20:21]
	v_lshlrev_b32_e32 v10, 16, v11
	v_cvt_pk_bf16_f32 v20, v12, v13
	v_lshlrev_b32_e32 v12, 16, v86
	v_and_b32_e32 v13, 0xffff0000, v86
	v_and_b32_e32 v11, 0xffff0000, v11
	v_pk_mul_f32 v[10:11], v[12:13], v[10:11]
	s_waitcnt lgkmcnt(0)
	v_lshlrev_b32_e32 v12, 16, v14
	v_cvt_pk_bf16_f32 v22, v10, v11
	v_lshlrev_b32_e32 v10, 16, v85
	v_and_b32_e32 v11, 0xffff0000, v85
	v_and_b32_e32 v13, 0xffff0000, v14
	v_pk_mul_f32 v[10:11], v[10:11], v[12:13]
	v_lshlrev_b32_e32 v12, 16, v15
	v_cvt_pk_bf16_f32 v18, v10, v11
	v_lshlrev_b32_e32 v10, 16, v84
	v_and_b32_e32 v11, 0xffff0000, v84
	v_and_b32_e32 v13, 0xffff0000, v15
	v_pk_mul_f32 v[10:11], v[10:11], v[12:13]
	s_nop 0
	v_cvt_pk_bf16_f32 v21, v10, v11
	ds_read_b64 v[10:11], v113 offset:192
	ds_read_b64 v[64:65], v113 offset:16832
	v_lshlrev_b32_e32 v12, 16, v17
	v_and_b32_e32 v13, 0xffff0000, v17
	s_waitcnt lgkmcnt(1)
	v_lshlrev_b32_e32 v14, 16, v10
	v_and_b32_e32 v15, 0xffff0000, v10
	v_pk_mul_f32 v[12:13], v[12:13], v[14:15]
	v_lshlrev_b32_e32 v10, 16, v11
	v_cvt_pk_bf16_f32 v15, v12, v13
	v_lshlrev_b32_e32 v12, 16, v16
	v_and_b32_e32 v13, 0xffff0000, v16
	v_and_b32_e32 v11, 0xffff0000, v11
	v_pk_mul_f32 v[10:11], v[12:13], v[10:11]
	s_waitcnt lgkmcnt(0)
	v_lshlrev_b32_e32 v12, 16, v64
	v_cvt_pk_bf16_f32 v17, v10, v11
	v_lshlrev_b32_e32 v10, 16, v3
	v_and_b32_e32 v11, 0xffff0000, v3
	v_and_b32_e32 v13, 0xffff0000, v64
	v_pk_mul_f32 v[10:11], v[10:11], v[12:13]
	v_lshlrev_b32_e32 v12, 16, v65
	v_cvt_pk_bf16_f32 v14, v10, v11
	v_lshlrev_b32_e32 v10, 16, v2
	v_and_b32_e32 v11, 0xffff0000, v2
	v_and_b32_e32 v13, 0xffff0000, v65
	v_pk_mul_f32 v[2:3], v[10:11], v[12:13]
	s_nop 0
	v_cvt_pk_bf16_f32 v16, v2, v3
	ds_read_b64 v[2:3], v113 offset:208
	ds_read_b64 v[64:65], v113 offset:16848
	v_lshlrev_b32_e32 v10, 16, v7
	v_and_b32_e32 v11, 0xffff0000, v7
	s_waitcnt lgkmcnt(1)
	v_lshlrev_b32_e32 v12, 16, v2
	v_and_b32_e32 v13, 0xffff0000, v2
	v_pk_mul_f32 v[10:11], v[10:11], v[12:13]
	v_lshlrev_b32_e32 v12, 16, v6
	v_lshlrev_b32_e32 v2, 16, v3
	v_and_b32_e32 v13, 0xffff0000, v6
	v_and_b32_e32 v3, 0xffff0000, v3
	v_pk_mul_f32 v[2:3], v[12:13], v[2:3]
	s_waitcnt lgkmcnt(0)
	v_lshlrev_b32_e32 v6, 16, v64
	v_cvt_pk_bf16_f32 v13, v2, v3
	v_lshlrev_b32_e32 v2, 16, v5
	v_and_b32_e32 v3, 0xffff0000, v5
	v_and_b32_e32 v7, 0xffff0000, v64
	v_pk_mul_f32 v[2:3], v[2:3], v[6:7]
	v_cvt_pk_bf16_f32 v11, v10, v11
	v_cvt_pk_bf16_f32 v10, v2, v3
	v_lshlrev_b32_e32 v2, 16, v4
	v_lshlrev_b32_e32 v6, 16, v65
	v_and_b32_e32 v3, 0xffff0000, v4
	v_and_b32_e32 v7, 0xffff0000, v65
	v_pk_mul_f32 v[2:3], v[2:3], v[6:7]
	s_nop 0
	v_cvt_pk_bf16_f32 v12, v2, v3
	ds_read_b64 v[2:3], v113 offset:224
	ds_read_b64 v[64:65], v113 offset:16864
	v_lshlrev_b32_e32 v4, 16, v27
	v_and_b32_e32 v5, 0xffff0000, v27
	s_waitcnt lgkmcnt(1)
	v_lshlrev_b32_e32 v6, 16, v2
	v_and_b32_e32 v7, 0xffff0000, v2
	v_pk_mul_f32 v[4:5], v[4:5], v[6:7]
	v_lshlrev_b32_e32 v2, 16, v3
	v_cvt_pk_bf16_f32 v7, v4, v5
	v_lshlrev_b32_e32 v4, 16, v9
	v_and_b32_e32 v5, 0xffff0000, v9
	v_and_b32_e32 v3, 0xffff0000, v3
	v_pk_mul_f32 v[2:3], v[4:5], v[2:3]
	s_waitcnt lgkmcnt(0)
	v_lshlrev_b32_e32 v4, 16, v64
	v_cvt_pk_bf16_f32 v9, v2, v3
	v_lshlrev_b32_e32 v2, 16, v19
	v_and_b32_e32 v3, 0xffff0000, v19
	v_and_b32_e32 v5, 0xffff0000, v64
	v_pk_mul_f32 v[2:3], v[2:3], v[4:5]
	v_lshlrev_b32_e32 v4, 16, v65
	v_cvt_pk_bf16_f32 v6, v2, v3
	v_lshlrev_b32_e32 v2, 16, v8
	v_and_b32_e32 v3, 0xffff0000, v8
	v_and_b32_e32 v5, 0xffff0000, v65
	v_pk_mul_f32 v[2:3], v[2:3], v[4:5]
	s_nop 0
	v_cvt_pk_bf16_f32 v8, v2, v3
	ds_read_b64 v[2:3], v113 offset:240
	ds_read_b64 v[64:65], v113 offset:16880
	v_lshlrev_b32_e32 v4, 16, v112
	v_and_b32_e32 v5, 0xffff0000, v112
	s_waitcnt lgkmcnt(1)
	v_lshlrev_b32_e32 v66, 16, v2
	v_and_b32_e32 v67, 0xffff0000, v2
	v_pk_mul_f32 v[4:5], v[4:5], v[66:67]
	v_lshlrev_b32_e32 v66, 16, v30
	v_lshlrev_b32_e32 v2, 16, v3
	v_and_b32_e32 v67, 0xffff0000, v30
	v_and_b32_e32 v3, 0xffff0000, v3
	v_pk_mul_f32 v[2:3], v[66:67], v[2:3]
	v_cvt_pk_bf16_f32 v4, v4, v5
	v_cvt_pk_bf16_f32 v5, v2, v3
	v_lshlrev_b32_e32 v2, 16, v29
	s_waitcnt lgkmcnt(0)
	v_lshlrev_b32_e32 v66, 16, v64
	v_and_b32_e32 v3, 0xffff0000, v29
	v_and_b32_e32 v67, 0xffff0000, v64
	v_pk_mul_f32 v[2:3], v[2:3], v[66:67]
	v_lshlrev_b32_e32 v66, 16, v28
	v_lshlrev_b32_e32 v64, 16, v65
	v_and_b32_e32 v67, 0xffff0000, v28
	v_and_b32_e32 v65, 0xffff0000, v65
	v_pk_mul_f32 v[28:29], v[66:67], v[64:65]
	v_cvt_pk_bf16_f32 v2, v2, v3
	v_cvt_pk_bf16_f32 v3, v28, v29
	v_mov_b32_e32 v19, v192
	s_barrier
; DI int otid() { int t = threadIdx.x; asm volatile("" : "+v"(t)); return t; }
; template <bool NT>
; DI void stage_load_tile(bf16_t* stg, const bf16_t* tilebase) {
;   const int tid = otid();
;   const int r0 = tid >> 5, c = tid & 31;
;   const unsigned o0 = (unsigned)(r0 * 1024 + c * 8);
;   __builtin_amdgcn_sched_barrier(0);
; #pragma unroll
;   for (int hf = 0; hf < 2; ++hf) {
; #pragma unroll
;     for (int it = 8 * hf; it < 8 * hf + 8; ++it) {
;       const u32x4* gp = (const u32x4*)(tilebase + (o0 + (unsigned)(it * 16 * 1024)));
;       stage_write16(stg, r0 + 16 * it, c, NT ? __builtin_nontemporal_load(gp) : *gp);
;     }
;     __builtin_amdgcn_sched_barrier(0);
;   }
; }
; template <bool LAST>
; DI void phase_gate(const Params& P, int layer, unsigned char* smem, int L, int G) {
;     ...
;     stage_load_tile<false>(stg, Sb + (size_t)mt * 256 * 1024 + nt * 256);
;     __syncthreads();
	s_add_u32 s20, s76, s18
	v_ashrrev_i32_e32 v27, 5, v19
	v_and_b32_e32 v19, 31, v19
	s_addc_u32 s21, s77, s19
	v_lshlrev_b32_e32 v30, 3, v19
	v_lshl_add_u64 v[28:29], s[20:21], 0, v[0:1]
	v_lshl_or_b32 v160, v27, 10, v30
	v_add_u32_e32 v66, 0x4000, v160
	v_mov_b32_e32 v67, v161
	v_add_u32_e32 v72, 0x8000, v160
	v_mov_b32_e32 v73, v161
	v_add_u32_e32 v74, 0xc000, v160
	v_mov_b32_e32 v75, v161
	v_add_u32_e32 v80, 0x10000, v160
	v_mov_b32_e32 v81, v161
	v_add_u32_e32 v82, 0x14000, v160
	v_mov_b32_e32 v83, v161
	v_lshl_add_u64 v[64:65], v[160:161], 1, v[28:29]
	v_lshl_add_u64 v[68:69], v[66:67], 1, v[28:29]
	v_lshl_add_u64 v[72:73], v[72:73], 1, v[28:29]
	v_lshl_add_u64 v[76:77], v[74:75], 1, v[28:29]
	v_lshl_add_u64 v[80:81], v[80:81], 1, v[28:29]
	v_lshl_add_u64 v[84:85], v[82:83], 1, v[28:29]
	global_load_dwordx4 v[64:67], v[64:65], off
	s_nop 0
	global_load_dwordx4 v[68:71], v[68:69], off
	s_nop 0
	global_load_dwordx4 v[72:75], v[72:73], off
	s_nop 0
	global_load_dwordx4 v[76:79], v[76:77], off
	s_nop 0
	global_load_dwordx4 v[80:83], v[80:81], off
	s_nop 0
	global_load_dwordx4 v[100:103], v[84:85], off
	v_add_u32_e32 v84, 0x18000, v160
	v_mov_b32_e32 v85, v161
	v_add_u32_e32 v104, 0x1c000, v160
	v_mov_b32_e32 v105, v161
	v_lshl_add_u64 v[84:85], v[84:85], 1, v[28:29]
	v_lshl_add_u64 v[108:109], v[104:105], 1, v[28:29]
	global_load_dwordx4 v[104:107], v[84:85], off
	s_nop 0
	global_load_dwordx4 v[108:111], v[108:109], off
	v_add_u32_e32 v218, 0x20000, v160
	v_mov_b32_e32 v219, v161
	v_add_u32_e32 v220, 0x24000, v160
	v_mov_b32_e32 v221, v161
	v_add_u32_e32 v226, 0x28000, v160
	v_mov_b32_e32 v227, v161
	v_add_u32_e32 v228, 0x2c000, v160
	v_mov_b32_e32 v229, v161
	v_add_u32_e32 v234, 0x30000, v160
	v_mov_b32_e32 v235, v161
	v_add_u32_e32 v236, 0x34000, v160
	v_mov_b32_e32 v237, v161
	v_lshl_add_u64 v[218:219], v[218:219], 1, v[28:29]
	v_lshl_add_u64 v[222:223], v[220:221], 1, v[28:29]
	v_lshl_add_u64 v[226:227], v[226:227], 1, v[28:29]
	v_lshl_add_u64 v[230:231], v[228:229], 1, v[28:29]
	v_lshl_add_u64 v[234:235], v[234:235], 1, v[28:29]
	v_lshl_add_u64 v[252:253], v[236:237], 1, v[28:29]
	global_load_dwordx4 v[218:221], v[218:219], off
	s_nop 0
	global_load_dwordx4 v[222:225], v[222:223], off
	s_nop 0
	global_load_dwordx4 v[226:229], v[226:227], off
	s_nop 0
	global_load_dwordx4 v[230:233], v[230:231], off
	s_nop 0
	global_load_dwordx4 v[234:237], v[234:235], off
	s_nop 0
	global_load_dwordx4 v[238:241], v[252:253], off
	v_add_u32_e32 v252, 0x38000, v160
	v_mov_b32_e32 v253, v161
	v_lshl_add_u64 v[252:253], v[252:253], 1, v[28:29]
	v_add_u32_e32 v160, 0x3c000, v160
	v_lshl_add_u64 v[190:191], v[160:161], 1, v[28:29]
	global_load_dwordx4 v[242:245], v[252:253], off
	global_load_dwordx4 v[248:251], v[190:191], off
	v_mul_lo_u32 v27, v27, s34
	v_lshl_add_u32 v19, v19, 4, v27
	v_add_u32_e32 v27, 0x2080, v19
	v_add_u32_e32 v30, 0x4100, v19
	v_add_u32_e32 v33, 0x6180, v19
	v_add_u32_e32 v53, 0x8200, v19
	v_add_u32_e32 v55, 0xa280, v19
	v_add_u32_e32 v59, 0xc300, v19
	v_add_u32_e32 v84, 0xe380, v19
	s_waitcnt vmcnt(15)
	ds_write2_b64 v19, v[64:65], v[66:67] offset1:1
	s_waitcnt vmcnt(14)
	ds_write2_b64 v27, v[68:69], v[70:71] offset1:1
	s_waitcnt vmcnt(13)
	ds_write2_b64 v30, v[72:73], v[74:75] offset1:1
	s_waitcnt vmcnt(12)
	ds_write2_b64 v33, v[76:77], v[78:79] offset1:1
	s_waitcnt vmcnt(11)
	ds_write2_b64 v53, v[80:81], v[82:83] offset1:1
	s_waitcnt vmcnt(10)
	ds_write2_b64 v55, v[100:101], v[102:103] offset1:1
	s_waitcnt vmcnt(9)
	ds_write2_b64 v59, v[104:105], v[106:107] offset1:1
	s_waitcnt vmcnt(8)
	ds_write2_b64 v84, v[108:109], v[110:111] offset1:1
	v_add_u32_e32 v27, 0x10400, v19
	v_add_u32_e32 v28, 0x12480, v19
	v_add_u32_e32 v29, 0x14500, v19
	v_add_u32_e32 v30, 0x16580, v19
	v_add_u32_e32 v33, 0x18600, v19
	v_add_u32_e32 v53, 0x1a680, v19
	v_add_u32_e32 v55, 0x1c700, v19
	v_add_u32_e32 v19, 0x1e780, v19
	s_waitcnt vmcnt(7)
	ds_write2_b64 v27, v[218:219], v[220:221] offset1:1
	s_waitcnt vmcnt(6)
	ds_write2_b64 v28, v[222:223], v[224:225] offset1:1
	s_waitcnt vmcnt(5)
	ds_write2_b64 v29, v[226:227], v[228:229] offset1:1
	s_waitcnt vmcnt(4)
	ds_write2_b64 v30, v[230:231], v[232:233] offset1:1
	s_waitcnt vmcnt(3)
	ds_write2_b64 v33, v[234:235], v[236:237] offset1:1
	s_waitcnt vmcnt(2)
	ds_write2_b64 v53, v[238:239], v[240:241] offset1:1
	s_waitcnt vmcnt(1)
	ds_write2_b64 v55, v[242:243], v[244:245] offset1:1
	s_waitcnt vmcnt(0)
	ds_write2_b64 v19, v[248:249], v[250:251] offset1:1
	v_mov_b32_e32 v19, v192
	s_waitcnt lgkmcnt(0)
	s_barrier
; DI unsigned pack2(float a, float b) { f32x2_t v = {a, b}; bf16x2_t r = __builtin_convertvector(v, bf16x2_t); return __builtin_bit_cast(unsigned, r); }
; DI float bflo(unsigned u) { return __uint_as_float(u << 16); }
; DI float bfhi(unsigned u) { return __uint_as_float(u & 0xffff0000u); }
; template <bool LAST>
; DI void phase_gate(const Params& P, int layer, unsigned char* smem, int L, int G) {
;     ...
; #pragma unroll
;     for (int i = 0; i < 4; ++i)
; #pragma unroll
;       for (int q4 = 0; q4 < 4; ++q4) {
;         const int fl = wm2 * 128 + i * 32 + 8 * q4 + 4 * h2;
;         const int f0 = nt * 256 + fl;
;         const f32x4 gv = *(const f32x4*)(vecL + 512 + fl), bv = *(const f32x4*)(vecL + 768 + fl);
;         const float ga[4] = {gv.x, gv.y, gv.z, gv.w}, ba[4] = {bv.x, bv.y, bv.z, bv.w};
; #pragma unroll
;         for (int j = 0; j < 2; ++j) {
;           const int lrow = wn2 * 64 + j * 32 + r2;
;           const float mu = rowA[lrow], rstd = rowB[lrow];
;           uint2* sp = (uint2*)(stg + lrow * STG + fl);
;           const uint2 sv = *sp;
;           const float sa[4] = {bflo(sv.x), bfhi(sv.x), bflo(sv.y), bfhi(sv.y)};
;           float y[4];
;           const float gg[4] = {bflo(gq[i][j][2 * q4]), bfhi(gq[i][j][2 * q4]), bflo(gq[i][j][2 * q4 + 1]), bfhi(gq[i][j][2 * q4 + 1])};
; #pragma unroll
;           for (int e = 0; e < 4; ++e) y[e] = (sa[e] - mu) * rstd * ga[e] + ba[e] + gg[e];
;           if (LAST) { f32x4 o = {y[0], y[1], y[2], y[3]}; *(f32x4*)(P.out + (size_t)(mt * 256 + lrow) * 1024 + f0) = o; }
;           else { uint2 pk; pk.x = pack2(y[0], y[1]); pk.y = pack2(y[2], y[3]); *sp = pk; }
;         }
;         __builtin_amdgcn_sched_barrier(0);
;       }
	v_lshlrev_b32_e32 v82, 16, v31
	v_lshrrev_b32_e32 v28, 3, v19
	v_ashrrev_i32_e32 v27, 1, v19
	v_and_b32_e32 v28, 4, v28
	v_and_or_b32 v30, v27, s35, v28
	v_and_b32_e32 v19, 0xdf, v19
	v_lshlrev_b32_e32 v27, 2, v30
	v_lshlrev_b32_e32 v33, 2, v19
	v_mul_u32_u24_e32 v19, 0x208, v19
	v_add_u32_e32 v28, 0x25000, v27
	v_lshl_add_u32 v19, v30, 1, v19
	v_add_u32_e32 v29, 0x25400, v27
	ds_read_b128 v[64:67], v28
	ds_read_b128 v[68:71], v29
	ds_read_b64 v[72:73], v19
	v_or_b32_e32 v29, 0x24000, v33
	v_or_b32_e32 v30, 0x24400, v33
	ds_read_b32 v74, v29
	ds_read_b32 v76, v30
	ds_read_b64 v[78:79], v19 offset:16640
	v_and_b32_e32 v83, 0xffff0000, v31
	s_waitcnt lgkmcnt(3)
	v_lshlrev_b32_e32 v80, 16, v72
	v_and_b32_e32 v81, 0xffff0000, v72
	v_lshlrev_b32_e32 v72, 16, v73
	v_and_b32_e32 v73, 0xffff0000, v73
	s_waitcnt lgkmcnt(2)
	v_pk_add_f32 v[80:81], v[80:81], v[74:75] op_sel_hi:[1,0] neg_lo:[0,1] neg_hi:[0,1]
	v_pk_add_f32 v[72:73], v[72:73], v[74:75] op_sel_hi:[1,0] neg_lo:[0,1] neg_hi:[0,1]
	s_waitcnt lgkmcnt(1)
	v_pk_mul_f32 v[80:81], v[76:77], v[80:81] op_sel_hi:[0,1]
	v_pk_mul_f32 v[72:73], v[76:77], v[72:73] op_sel_hi:[0,1]
	v_lshlrev_b32_e32 v84, 16, v98
	v_and_b32_e32 v85, 0xffff0000, v98
	v_pk_fma_f32 v[80:81], v[64:65], v[80:81], v[68:69]
	v_pk_fma_f32 v[72:73], v[66:67], v[72:73], v[70:71]
	v_pk_add_f32 v[80:81], v[80:81], v[82:83]
	v_pk_add_f32 v[72:73], v[72:73], v[84:85]
	v_cvt_pk_bf16_f32 v74, v80, v81
	v_cvt_pk_bf16_f32 v75, v72, v73
	ds_write_b64 v19, v[74:75]
	v_or_b32_e32 v31, 0x24080, v33
	v_or_b32_e32 v33, 0x24480, v33
	ds_read_b32 v72, v31
	ds_read_b32 v74, v33
	s_waitcnt lgkmcnt(3)
	v_lshlrev_b32_e32 v76, 16, v78
	v_and_b32_e32 v77, 0xffff0000, v78
	v_lshlrev_b32_e32 v78, 16, v79
	s_waitcnt lgkmcnt(1)
	v_pk_add_f32 v[76:77], v[76:77], v[72:73] op_sel_hi:[1,0] neg_lo:[0,1] neg_hi:[0,1]
	v_and_b32_e32 v79, 0xffff0000, v79
	s_waitcnt lgkmcnt(0)
	v_pk_mul_f32 v[76:77], v[74:75], v[76:77] op_sel_hi:[0,1]
	v_pk_fma_f32 v[64:65], v[64:65], v[76:77], v[68:69]
	v_pk_add_f32 v[68:69], v[78:79], v[72:73] op_sel_hi:[1,0] neg_lo:[0,1] neg_hi:[0,1]
	v_lshlrev_b32_e32 v80, 16, v97
	v_pk_mul_f32 v[68:69], v[74:75], v[68:69] op_sel_hi:[0,1]
	v_and_b32_e32 v81, 0xffff0000, v97
	v_lshlrev_b32_e32 v82, 16, v96
	v_and_b32_e32 v83, 0xffff0000, v96
	v_pk_fma_f32 v[66:67], v[66:67], v[68:69], v[70:71]
	v_pk_add_f32 v[64:65], v[64:65], v[80:81]
	v_pk_add_f32 v[66:67], v[66:67], v[82:83]
	v_cvt_pk_bf16_f32 v64, v64, v65
	v_cvt_pk_bf16_f32 v65, v66, v67
	ds_write_b64 v19, v[64:65] offset:16640
	v_add_u32_e32 v53, 0x25020, v27
	v_add_u32_e32 v55, 0x25420, v27
	ds_read_b64 v[72:73], v19 offset:16
	ds_read_b128 v[64:67], v53
	ds_read_b128 v[68:71], v55
	ds_read_b32 v74, v29
	ds_read_b32 v76, v30
	ds_read_b64 v[78:79], v19 offset:16656
	s_waitcnt lgkmcnt(5)
	v_lshlrev_b32_e32 v80, 16, v72
	v_and_b32_e32 v81, 0xffff0000, v72
	v_lshlrev_b32_e32 v72, 16, v73
	v_and_b32_e32 v73, 0xffff0000, v73
	s_waitcnt lgkmcnt(2)
	v_pk_add_f32 v[80:81], v[80:81], v[74:75] op_sel_hi:[1,0] neg_lo:[0,1] neg_hi:[0,1]
	v_pk_add_f32 v[72:73], v[72:73], v[74:75] op_sel_hi:[1,0] neg_lo:[0,1] neg_hi:[0,1]
	s_waitcnt lgkmcnt(1)
	v_pk_mul_f32 v[80:81], v[76:77], v[80:81] op_sel_hi:[0,1]
	v_pk_mul_f32 v[72:73], v[76:77], v[72:73] op_sel_hi:[0,1]
	v_lshlrev_b32_e32 v82, 16, v93
	v_and_b32_e32 v83, 0xffff0000, v93
	v_lshlrev_b32_e32 v84, 16, v95
	v_and_b32_e32 v85, 0xffff0000, v95
	v_pk_fma_f32 v[80:81], v[64:65], v[80:81], v[68:69]
	v_pk_fma_f32 v[72:73], v[66:67], v[72:73], v[70:71]
	v_pk_add_f32 v[80:81], v[80:81], v[82:83]
	v_pk_add_f32 v[72:73], v[72:73], v[84:85]
	v_cvt_pk_bf16_f32 v74, v80, v81
	v_cvt_pk_bf16_f32 v75, v72, v73
	ds_write_b64 v19, v[74:75] offset:16
	ds_read_b32 v72, v31
	ds_read_b32 v74, v33
	s_waitcnt lgkmcnt(3)
	v_lshlrev_b32_e32 v76, 16, v78
	v_and_b32_e32 v77, 0xffff0000, v78
	v_lshlrev_b32_e32 v78, 16, v79
	s_waitcnt lgkmcnt(1)
	v_pk_add_f32 v[76:77], v[76:77], v[72:73] op_sel_hi:[1,0] neg_lo:[0,1] neg_hi:[0,1]
	v_and_b32_e32 v79, 0xffff0000, v79
	s_waitcnt lgkmcnt(0)
	v_pk_mul_f32 v[76:77], v[74:75], v[76:77] op_sel_hi:[0,1]
	v_pk_fma_f32 v[64:65], v[64:65], v[76:77], v[68:69]
	v_pk_add_f32 v[68:69], v[78:79], v[72:73] op_sel_hi:[1,0] neg_lo:[0,1] neg_hi:[0,1]
	v_lshlrev_b32_e32 v80, 16, v92
	v_pk_mul_f32 v[68:69], v[74:75], v[68:69] op_sel_hi:[0,1]
	v_and_b32_e32 v81, 0xffff0000, v92
	v_lshlrev_b32_e32 v82, 16, v94
	v_and_b32_e32 v83, 0xffff0000, v94
	v_pk_fma_f32 v[66:67], v[66:67], v[68:69], v[70:71]
	v_pk_add_f32 v[64:65], v[64:65], v[80:81]
	v_pk_add_f32 v[66:67], v[66:67], v[82:83]
	v_cvt_pk_bf16_f32 v64, v64, v65
	v_cvt_pk_bf16_f32 v65, v66, v67
	ds_write_b64 v19, v[64:65] offset:16656
	v_add_u32_e32 v53, 0x25040, v27
	v_add_u32_e32 v55, 0x25440, v27
	ds_read_b64 v[72:73], v19 offset:32
	ds_read_b128 v[64:67], v53
	ds_read_b128 v[68:71], v55
	ds_read_b32 v74, v29
	ds_read_b32 v76, v30
	ds_read_b64 v[78:79], v19 offset:16672
	s_waitcnt lgkmcnt(5)
	v_lshlrev_b32_e32 v80, 16, v72
	v_and_b32_e32 v81, 0xffff0000, v72
	v_lshlrev_b32_e32 v72, 16, v73
	v_and_b32_e32 v73, 0xffff0000, v73
	s_waitcnt lgkmcnt(2)
	v_pk_add_f32 v[80:81], v[80:81], v[74:75] op_sel_hi:[1,0] neg_lo:[0,1] neg_hi:[0,1]
	v_pk_add_f32 v[72:73], v[72:73], v[74:75] op_sel_hi:[1,0] neg_lo:[0,1] neg_hi:[0,1]
	s_waitcnt lgkmcnt(1)
	v_pk_mul_f32 v[80:81], v[76:77], v[80:81] op_sel_hi:[0,1]
	v_pk_mul_f32 v[72:73], v[76:77], v[72:73] op_sel_hi:[0,1]
	v_lshlrev_b32_e32 v82, 16, v88
	v_and_b32_e32 v83, 0xffff0000, v88
	v_lshlrev_b32_e32 v84, 16, v90
	v_and_b32_e32 v85, 0xffff0000, v90
	v_pk_fma_f32 v[80:81], v[64:65], v[80:81], v[68:69]
	v_pk_fma_f32 v[72:73], v[66:67], v[72:73], v[70:71]
	v_pk_add_f32 v[80:81], v[80:81], v[82:83]
	v_pk_add_f32 v[72:73], v[72:73], v[84:85]
	v_cvt_pk_bf16_f32 v74, v80, v81
	v_cvt_pk_bf16_f32 v75, v72, v73
	ds_write_b64 v19, v[74:75] offset:32
	ds_read_b32 v72, v31
	ds_read_b32 v74, v33
	s_waitcnt lgkmcnt(3)
; DI unsigned pack2(float a, float b) { f32x2_t v = {a, b}; bf16x2_t r = __builtin_convertvector(v, bf16x2_t); return __builtin_bit_cast(unsigned, r); }
; DI float bflo(unsigned u) { return __uint_as_float(u << 16); }
; DI float bfhi(unsigned u) { return __uint_as_float(u & 0xffff0000u); }
; template <bool LAST>
; DI void phase_gate(const Params& P, int layer, unsigned char* smem, int L, int G) {
;     ...
; #pragma unroll
;     for (int i = 0; i < 4; ++i)
; #pragma unroll
;       for (int q4 = 0; q4 < 4; ++q4) {
;         const int fl = wm2 * 128 + i * 32 + 8 * q4 + 4 * h2;
;         const int f0 = nt * 256 + fl;
;         const f32x4 gv = *(const f32x4*)(vecL + 512 + fl), bv = *(const f32x4*)(vecL + 768 + fl);
;         const float ga[4] = {gv.x, gv.y, gv.z, gv.w}, ba[4] = {bv.x, bv.y, bv.z, bv.w};
; #pragma unroll
;         for (int j = 0; j < 2; ++j) {
;           const int lrow = wn2 * 64 + j * 32 + r2;
;           const float mu = rowA[lrow], rstd = rowB[lrow];
;           uint2* sp = (uint2*)(stg + lrow * STG + fl);
;           const uint2 sv = *sp;
;           const float sa[4] = {bflo(sv.x), bfhi(sv.x), bflo(sv.y), bfhi(sv.y)};
;           float y[4];
;           const float gg[4] = {bflo(gq[i][j][2 * q4]), bfhi(gq[i][j][2 * q4]), bflo(gq[i][j][2 * q4 + 1]), bfhi(gq[i][j][2 * q4 + 1])};
; #pragma unroll
;           for (int e = 0; e < 4; ++e) y[e] = (sa[e] - mu) * rstd * ga[e] + ba[e] + gg[e];
;           if (LAST) { f32x4 o = {y[0], y[1], y[2], y[3]}; *(f32x4*)(P.out + (size_t)(mt * 256 + lrow) * 1024 + f0) = o; }
;           else { uint2 pk; pk.x = pack2(y[0], y[1]); pk.y = pack2(y[2], y[3]); *sp = pk; }
;         }
;         __builtin_amdgcn_sched_barrier(0);
;       }
	v_lshlrev_b32_e32 v76, 16, v78
	v_and_b32_e32 v77, 0xffff0000, v78
	v_lshlrev_b32_e32 v78, 16, v79
	s_waitcnt lgkmcnt(1)
	v_pk_add_f32 v[76:77], v[76:77], v[72:73] op_sel_hi:[1,0] neg_lo:[0,1] neg_hi:[0,1]
	v_and_b32_e32 v79, 0xffff0000, v79
	s_waitcnt lgkmcnt(0)
	v_pk_mul_f32 v[76:77], v[74:75], v[76:77] op_sel_hi:[0,1]
	v_pk_fma_f32 v[64:65], v[64:65], v[76:77], v[68:69]
	v_pk_add_f32 v[68:69], v[78:79], v[72:73] op_sel_hi:[1,0] neg_lo:[0,1] neg_hi:[0,1]
	v_lshlrev_b32_e32 v80, 16, v87
	v_pk_mul_f32 v[68:69], v[74:75], v[68:69] op_sel_hi:[0,1]
	v_and_b32_e32 v81, 0xffff0000, v87
	v_lshlrev_b32_e32 v82, 16, v89
	v_and_b32_e32 v83, 0xffff0000, v89
	v_pk_fma_f32 v[66:67], v[66:67], v[68:69], v[70:71]
	v_pk_add_f32 v[64:65], v[64:65], v[80:81]
	v_pk_add_f32 v[66:67], v[66:67], v[82:83]
	v_cvt_pk_bf16_f32 v64, v64, v65
	v_cvt_pk_bf16_f32 v65, v66, v67
	ds_write_b64 v19, v[64:65] offset:16672
	v_add_u32_e32 v53, 0x25060, v27
	v_add_u32_e32 v55, 0x25460, v27
	ds_read_b64 v[72:73], v19 offset:48
	ds_read_b128 v[64:67], v53
	ds_read_b128 v[68:71], v55
	ds_read_b32 v74, v29
	ds_read_b32 v76, v30
	ds_read_b64 v[78:79], v19 offset:16688
	s_waitcnt lgkmcnt(5)
	v_lshlrev_b32_e32 v80, 16, v72
	v_and_b32_e32 v81, 0xffff0000, v72
	v_lshlrev_b32_e32 v72, 16, v73
	v_and_b32_e32 v73, 0xffff0000, v73
	s_waitcnt lgkmcnt(2)
	v_pk_add_f32 v[80:81], v[80:81], v[74:75] op_sel_hi:[1,0] neg_lo:[0,1] neg_hi:[0,1]
	v_pk_add_f32 v[72:73], v[72:73], v[74:75] op_sel_hi:[1,0] neg_lo:[0,1] neg_hi:[0,1]
	s_waitcnt lgkmcnt(1)
	v_pk_mul_f32 v[80:81], v[76:77], v[80:81] op_sel_hi:[0,1]
	v_pk_mul_f32 v[72:73], v[76:77], v[72:73] op_sel_hi:[0,1]
	v_lshlrev_b32_e32 v82, 16, v61
	v_and_b32_e32 v83, 0xffff0000, v61
	v_lshlrev_b32_e32 v84, 16, v63
	v_and_b32_e32 v85, 0xffff0000, v63
	v_pk_fma_f32 v[80:81], v[64:65], v[80:81], v[68:69]
	v_pk_fma_f32 v[72:73], v[66:67], v[72:73], v[70:71]
	v_pk_add_f32 v[80:81], v[80:81], v[82:83]
	v_pk_add_f32 v[72:73], v[72:73], v[84:85]
	v_cvt_pk_bf16_f32 v74, v80, v81
	v_cvt_pk_bf16_f32 v75, v72, v73
	ds_write_b64 v19, v[74:75] offset:48
	ds_read_b32 v72, v31
	ds_read_b32 v74, v33
	s_waitcnt lgkmcnt(3)
	v_lshlrev_b32_e32 v76, 16, v78
	v_and_b32_e32 v77, 0xffff0000, v78
	v_lshlrev_b32_e32 v80, 16, v60
	v_and_b32_e32 v81, 0xffff0000, v60
	v_lshlrev_b32_e32 v60, 16, v62
	v_and_b32_e32 v61, 0xffff0000, v62
	s_waitcnt lgkmcnt(1)
	v_pk_add_f32 v[62:63], v[76:77], v[72:73] op_sel_hi:[1,0] neg_lo:[0,1] neg_hi:[0,1]
	v_lshlrev_b32_e32 v78, 16, v79
	v_and_b32_e32 v79, 0xffff0000, v79
	s_waitcnt lgkmcnt(0)
	v_pk_mul_f32 v[62:63], v[74:75], v[62:63] op_sel_hi:[0,1]
	v_pk_fma_f32 v[62:63], v[64:65], v[62:63], v[68:69]
	v_pk_add_f32 v[64:65], v[78:79], v[72:73] op_sel_hi:[1,0] neg_lo:[0,1] neg_hi:[0,1]
	v_pk_add_f32 v[62:63], v[62:63], v[80:81]
	v_pk_mul_f32 v[64:65], v[74:75], v[64:65] op_sel_hi:[0,1]
	v_pk_fma_f32 v[64:65], v[66:67], v[64:65], v[70:71]
	v_cvt_pk_bf16_f32 v62, v62, v63
	v_pk_add_f32 v[60:61], v[64:65], v[60:61]
	s_nop 0
	v_cvt_pk_bf16_f32 v63, v60, v61
	ds_write_b64 v19, v[62:63] offset:16688
	v_add_u32_e32 v53, 0x25080, v27
	v_add_u32_e32 v55, 0x25480, v27
	ds_read_b64 v[68:69], v19 offset:64
	ds_read_b128 v[60:63], v53
	ds_read_b128 v[64:67], v55
	ds_read_b32 v70, v29
	ds_read_b32 v72, v30
	ds_read_b64 v[74:75], v19 offset:16704
	s_waitcnt lgkmcnt(5)
	v_lshlrev_b32_e32 v76, 16, v68
	v_and_b32_e32 v77, 0xffff0000, v68
	v_lshlrev_b32_e32 v68, 16, v69
	v_and_b32_e32 v69, 0xffff0000, v69
	v_lshlrev_b32_e32 v80, 16, v58
	v_and_b32_e32 v81, 0xffff0000, v58
	s_waitcnt lgkmcnt(2)
	v_pk_add_f32 v[58:59], v[76:77], v[70:71] op_sel_hi:[1,0] neg_lo:[0,1] neg_hi:[0,1]
	v_pk_add_f32 v[68:69], v[68:69], v[70:71] op_sel_hi:[1,0] neg_lo:[0,1] neg_hi:[0,1]
	s_waitcnt lgkmcnt(1)
	v_pk_mul_f32 v[58:59], v[72:73], v[58:59] op_sel_hi:[0,1]
	v_pk_mul_f32 v[68:69], v[72:73], v[68:69] op_sel_hi:[0,1]
	v_lshlrev_b32_e32 v78, 16, v56
	v_and_b32_e32 v79, 0xffff0000, v56
	v_pk_fma_f32 v[58:59], v[60:61], v[58:59], v[64:65]
	v_pk_fma_f32 v[68:69], v[62:63], v[68:69], v[66:67]
	v_pk_add_f32 v[58:59], v[58:59], v[78:79]
	v_pk_add_f32 v[68:69], v[68:69], v[80:81]
	v_cvt_pk_bf16_f32 v58, v58, v59
	v_cvt_pk_bf16_f32 v59, v68, v69
	ds_write_b64 v19, v[58:59] offset:64
	ds_read_b32 v56, v31
	ds_read_b32 v58, v33
	s_waitcnt lgkmcnt(3)
	v_lshlrev_b32_e32 v68, 16, v74
	v_and_b32_e32 v69, 0xffff0000, v74
	v_lshlrev_b32_e32 v70, 16, v75
	v_and_b32_e32 v71, 0xffff0000, v75
	v_lshlrev_b32_e32 v72, 16, v54
	v_and_b32_e32 v73, 0xffff0000, v54
	v_lshlrev_b32_e32 v54, 16, v57
	v_and_b32_e32 v55, 0xffff0000, v57
	s_waitcnt lgkmcnt(1)
	v_pk_add_f32 v[68:69], v[68:69], v[56:57] op_sel_hi:[1,0] neg_lo:[0,1] neg_hi:[0,1]
	v_pk_add_f32 v[56:57], v[70:71], v[56:57] op_sel_hi:[1,0] neg_lo:[0,1] neg_hi:[0,1]
	s_waitcnt lgkmcnt(0)
	v_pk_mul_f32 v[68:69], v[58:59], v[68:69] op_sel_hi:[0,1]
	v_pk_mul_f32 v[56:57], v[58:59], v[56:57] op_sel_hi:[0,1]
	v_pk_fma_f32 v[60:61], v[60:61], v[68:69], v[64:65]
	v_pk_fma_f32 v[56:57], v[62:63], v[56:57], v[66:67]
	v_pk_add_f32 v[60:61], v[60:61], v[72:73]
	v_pk_add_f32 v[54:55], v[56:57], v[54:55]
	v_cvt_pk_bf16_f32 v56, v60, v61
	v_cvt_pk_bf16_f32 v57, v54, v55
	ds_write_b64 v19, v[56:57] offset:16704
	v_add_u32_e32 v58, 0x254a0, v27
	v_add_u32_e32 v53, 0x250a0, v27
	ds_read_b64 v[62:63], v19 offset:80
	ds_read_b128 v[54:57], v53
	ds_read_b128 v[58:61], v58
	ds_read_b32 v64, v29
	ds_read_b32 v66, v30
	ds_read_b64 v[68:69], v19 offset:16720
	s_waitcnt lgkmcnt(5)
	v_lshlrev_b32_e32 v70, 16, v62
	v_and_b32_e32 v71, 0xffff0000, v62
	v_lshlrev_b32_e32 v62, 16, v63
	v_and_b32_e32 v63, 0xffff0000, v63
	v_lshlrev_b32_e32 v74, 16, v52
	v_and_b32_e32 v75, 0xffff0000, v52
	s_waitcnt lgkmcnt(2)
; DI unsigned pack2(float a, float b) { f32x2_t v = {a, b}; bf16x2_t r = __builtin_convertvector(v, bf16x2_t); return __builtin_bit_cast(unsigned, r); }
; DI float bflo(unsigned u) { return __uint_as_float(u << 16); }
; DI float bfhi(unsigned u) { return __uint_as_float(u & 0xffff0000u); }
; template <bool LAST>
; DI void phase_gate(const Params& P, int layer, unsigned char* smem, int L, int G) {
;     ...
; #pragma unroll
;     for (int i = 0; i < 4; ++i)
; #pragma unroll
;       for (int q4 = 0; q4 < 4; ++q4) {
;         const int fl = wm2 * 128 + i * 32 + 8 * q4 + 4 * h2;
;         const int f0 = nt * 256 + fl;
;         const f32x4 gv = *(const f32x4*)(vecL + 512 + fl), bv = *(const f32x4*)(vecL + 768 + fl);
;         const float ga[4] = {gv.x, gv.y, gv.z, gv.w}, ba[4] = {bv.x, bv.y, bv.z, bv.w};
; #pragma unroll
;         for (int j = 0; j < 2; ++j) {
;           const int lrow = wn2 * 64 + j * 32 + r2;
;           const float mu = rowA[lrow], rstd = rowB[lrow];
;           uint2* sp = (uint2*)(stg + lrow * STG + fl);
;           const uint2 sv = *sp;
;           const float sa[4] = {bflo(sv.x), bfhi(sv.x), bflo(sv.y), bfhi(sv.y)};
;           float y[4];
;           const float gg[4] = {bflo(gq[i][j][2 * q4]), bfhi(gq[i][j][2 * q4]), bflo(gq[i][j][2 * q4 + 1]), bfhi(gq[i][j][2 * q4 + 1])};
; #pragma unroll
;           for (int e = 0; e < 4; ++e) y[e] = (sa[e] - mu) * rstd * ga[e] + ba[e] + gg[e];
;           if (LAST) { f32x4 o = {y[0], y[1], y[2], y[3]}; *(f32x4*)(P.out + (size_t)(mt * 256 + lrow) * 1024 + f0) = o; }
;           else { uint2 pk; pk.x = pack2(y[0], y[1]); pk.y = pack2(y[2], y[3]); *sp = pk; }
;         }
;         __builtin_amdgcn_sched_barrier(0);
;       }
	v_pk_add_f32 v[52:53], v[70:71], v[64:65] op_sel_hi:[1,0] neg_lo:[0,1] neg_hi:[0,1]
	v_pk_add_f32 v[62:63], v[62:63], v[64:65] op_sel_hi:[1,0] neg_lo:[0,1] neg_hi:[0,1]
	s_waitcnt lgkmcnt(1)
	v_pk_mul_f32 v[52:53], v[66:67], v[52:53] op_sel_hi:[0,1]
	v_pk_mul_f32 v[62:63], v[66:67], v[62:63] op_sel_hi:[0,1]
	v_lshlrev_b32_e32 v72, 16, v50
	v_and_b32_e32 v73, 0xffff0000, v50
	v_pk_fma_f32 v[52:53], v[54:55], v[52:53], v[58:59]
	v_pk_fma_f32 v[62:63], v[56:57], v[62:63], v[60:61]
	v_pk_add_f32 v[52:53], v[52:53], v[72:73]
	v_pk_add_f32 v[62:63], v[62:63], v[74:75]
	v_cvt_pk_bf16_f32 v52, v52, v53
	v_cvt_pk_bf16_f32 v53, v62, v63
	ds_write_b64 v19, v[52:53] offset:80
	ds_read_b32 v50, v31
	ds_read_b32 v52, v33
	s_waitcnt lgkmcnt(3)
	v_lshlrev_b32_e32 v62, 16, v68
	v_and_b32_e32 v63, 0xffff0000, v68
	v_lshlrev_b32_e32 v64, 16, v69
	v_and_b32_e32 v65, 0xffff0000, v69
	v_lshlrev_b32_e32 v68, 16, v51
	v_and_b32_e32 v69, 0xffff0000, v51
	s_waitcnt lgkmcnt(1)
	v_pk_add_f32 v[62:63], v[62:63], v[50:51] op_sel_hi:[1,0] neg_lo:[0,1] neg_hi:[0,1]
	v_pk_add_f32 v[50:51], v[64:65], v[50:51] op_sel_hi:[1,0] neg_lo:[0,1] neg_hi:[0,1]
	s_waitcnt lgkmcnt(0)
	v_pk_mul_f32 v[62:63], v[52:53], v[62:63] op_sel_hi:[0,1]
	v_pk_mul_f32 v[50:51], v[52:53], v[50:51] op_sel_hi:[0,1]
	v_lshlrev_b32_e32 v66, 16, v49
	v_and_b32_e32 v67, 0xffff0000, v49
	v_pk_fma_f32 v[54:55], v[54:55], v[62:63], v[58:59]
	v_pk_fma_f32 v[50:51], v[56:57], v[50:51], v[60:61]
	v_pk_add_f32 v[54:55], v[54:55], v[66:67]
	v_pk_add_f32 v[50:51], v[50:51], v[68:69]
	v_cvt_pk_bf16_f32 v52, v54, v55
	v_cvt_pk_bf16_f32 v53, v50, v51
	ds_write_b64 v19, v[52:53] offset:16720
	v_add_u32_e32 v54, 0x254c0, v27
	v_add_u32_e32 v49, 0x250c0, v27
	ds_read_b64 v[58:59], v19 offset:96
	ds_read_b128 v[50:53], v49
	ds_read_b128 v[54:57], v54
	ds_read_b32 v60, v29
	ds_read_b32 v62, v30
	ds_read_b64 v[64:65], v19 offset:16736
	s_waitcnt lgkmcnt(5)
	v_lshlrev_b32_e32 v66, 16, v58
	v_and_b32_e32 v67, 0xffff0000, v58
	v_lshlrev_b32_e32 v58, 16, v59
	v_and_b32_e32 v59, 0xffff0000, v59
	v_lshlrev_b32_e32 v70, 16, v48
	v_and_b32_e32 v71, 0xffff0000, v48
	s_waitcnt lgkmcnt(2)
	v_pk_add_f32 v[48:49], v[66:67], v[60:61] op_sel_hi:[1,0] neg_lo:[0,1] neg_hi:[0,1]
	v_pk_add_f32 v[58:59], v[58:59], v[60:61] op_sel_hi:[1,0] neg_lo:[0,1] neg_hi:[0,1]
	s_waitcnt lgkmcnt(1)
	v_pk_mul_f32 v[48:49], v[62:63], v[48:49] op_sel_hi:[0,1]
	v_pk_mul_f32 v[58:59], v[62:63], v[58:59] op_sel_hi:[0,1]
	v_lshlrev_b32_e32 v68, 16, v46
	v_and_b32_e32 v69, 0xffff0000, v46
	v_pk_fma_f32 v[48:49], v[50:51], v[48:49], v[54:55]
	v_pk_fma_f32 v[58:59], v[52:53], v[58:59], v[56:57]
	v_pk_add_f32 v[48:49], v[48:49], v[68:69]
	v_pk_add_f32 v[58:59], v[58:59], v[70:71]
	v_cvt_pk_bf16_f32 v48, v48, v49
	v_cvt_pk_bf16_f32 v49, v58, v59
	ds_write_b64 v19, v[48:49] offset:96
	ds_read_b32 v46, v31
	ds_read_b32 v48, v33
	s_waitcnt lgkmcnt(3)
	v_lshlrev_b32_e32 v58, 16, v64
	v_and_b32_e32 v59, 0xffff0000, v64
	v_lshlrev_b32_e32 v60, 16, v65
	v_and_b32_e32 v61, 0xffff0000, v65
	v_lshlrev_b32_e32 v64, 16, v47
	v_and_b32_e32 v65, 0xffff0000, v47
	s_waitcnt lgkmcnt(1)
	v_pk_add_f32 v[58:59], v[58:59], v[46:47] op_sel_hi:[1,0] neg_lo:[0,1] neg_hi:[0,1]
	v_pk_add_f32 v[46:47], v[60:61], v[46:47] op_sel_hi:[1,0] neg_lo:[0,1] neg_hi:[0,1]
	s_waitcnt lgkmcnt(0)
	v_pk_mul_f32 v[58:59], v[48:49], v[58:59] op_sel_hi:[0,1]
	v_pk_mul_f32 v[46:47], v[48:49], v[46:47] op_sel_hi:[0,1]
	v_lshlrev_b32_e32 v62, 16, v45
	v_and_b32_e32 v63, 0xffff0000, v45
	v_pk_fma_f32 v[50:51], v[50:51], v[58:59], v[54:55]
	v_pk_fma_f32 v[46:47], v[52:53], v[46:47], v[56:57]
	v_pk_add_f32 v[50:51], v[50:51], v[62:63]
	v_pk_add_f32 v[46:47], v[46:47], v[64:65]
	v_cvt_pk_bf16_f32 v48, v50, v51
	v_cvt_pk_bf16_f32 v49, v46, v47
	ds_write_b64 v19, v[48:49] offset:16736
	v_add_u32_e32 v50, 0x254e0, v27
	v_add_u32_e32 v45, 0x250e0, v27
	ds_read_b64 v[54:55], v19 offset:112
	ds_read_b128 v[46:49], v45
	ds_read_b128 v[50:53], v50
	ds_read_b32 v56, v29
	ds_read_b32 v58, v30
	ds_read_b64 v[60:61], v19 offset:16752
	s_waitcnt lgkmcnt(5)
	v_lshlrev_b32_e32 v62, 16, v54
	v_and_b32_e32 v63, 0xffff0000, v54
	v_lshlrev_b32_e32 v54, 16, v55
	v_and_b32_e32 v55, 0xffff0000, v55
	v_lshlrev_b32_e32 v66, 16, v44
	v_and_b32_e32 v67, 0xffff0000, v44
	s_waitcnt lgkmcnt(2)
	v_pk_add_f32 v[44:45], v[62:63], v[56:57] op_sel_hi:[1,0] neg_lo:[0,1] neg_hi:[0,1]
	v_pk_add_f32 v[54:55], v[54:55], v[56:57] op_sel_hi:[1,0] neg_lo:[0,1] neg_hi:[0,1]
	s_waitcnt lgkmcnt(1)
	v_pk_mul_f32 v[44:45], v[58:59], v[44:45] op_sel_hi:[0,1]
	v_pk_mul_f32 v[54:55], v[58:59], v[54:55] op_sel_hi:[0,1]
	v_lshlrev_b32_e32 v64, 16, v42
	v_and_b32_e32 v65, 0xffff0000, v42
	v_pk_fma_f32 v[44:45], v[46:47], v[44:45], v[50:51]
	v_pk_fma_f32 v[54:55], v[48:49], v[54:55], v[52:53]
	v_pk_add_f32 v[44:45], v[44:45], v[64:65]
	v_pk_add_f32 v[54:55], v[54:55], v[66:67]
	v_cvt_pk_bf16_f32 v44, v44, v45
	v_cvt_pk_bf16_f32 v45, v54, v55
	ds_write_b64 v19, v[44:45] offset:112
	ds_read_b32 v42, v31
	ds_read_b32 v44, v33
	s_waitcnt lgkmcnt(3)
	v_lshlrev_b32_e32 v54, 16, v60
	v_and_b32_e32 v55, 0xffff0000, v60
	v_lshlrev_b32_e32 v56, 16, v61
	v_and_b32_e32 v57, 0xffff0000, v61
	v_lshlrev_b32_e32 v60, 16, v43
	v_and_b32_e32 v61, 0xffff0000, v43
	s_waitcnt lgkmcnt(1)
	v_pk_add_f32 v[54:55], v[54:55], v[42:43] op_sel_hi:[1,0] neg_lo:[0,1] neg_hi:[0,1]
	v_pk_add_f32 v[42:43], v[56:57], v[42:43] op_sel_hi:[1,0] neg_lo:[0,1] neg_hi:[0,1]
	s_waitcnt lgkmcnt(0)
; DI unsigned pack2(float a, float b) { f32x2_t v = {a, b}; bf16x2_t r = __builtin_convertvector(v, bf16x2_t); return __builtin_bit_cast(unsigned, r); }
; DI float bflo(unsigned u) { return __uint_as_float(u << 16); }
; DI float bfhi(unsigned u) { return __uint_as_float(u & 0xffff0000u); }
; template <bool LAST>
; DI void phase_gate(const Params& P, int layer, unsigned char* smem, int L, int G) {
;     ...
; #pragma unroll
;     for (int i = 0; i < 4; ++i)
; #pragma unroll
;       for (int q4 = 0; q4 < 4; ++q4) {
;         const int fl = wm2 * 128 + i * 32 + 8 * q4 + 4 * h2;
;         const int f0 = nt * 256 + fl;
;         const f32x4 gv = *(const f32x4*)(vecL + 512 + fl), bv = *(const f32x4*)(vecL + 768 + fl);
;         const float ga[4] = {gv.x, gv.y, gv.z, gv.w}, ba[4] = {bv.x, bv.y, bv.z, bv.w};
; #pragma unroll
;         for (int j = 0; j < 2; ++j) {
;           const int lrow = wn2 * 64 + j * 32 + r2;
;           const float mu = rowA[lrow], rstd = rowB[lrow];
;           uint2* sp = (uint2*)(stg + lrow * STG + fl);
;           const uint2 sv = *sp;
;           const float sa[4] = {bflo(sv.x), bfhi(sv.x), bflo(sv.y), bfhi(sv.y)};
;           float y[4];
;           const float gg[4] = {bflo(gq[i][j][2 * q4]), bfhi(gq[i][j][2 * q4]), bflo(gq[i][j][2 * q4 + 1]), bfhi(gq[i][j][2 * q4 + 1])};
; #pragma unroll
;           for (int e = 0; e < 4; ++e) y[e] = (sa[e] - mu) * rstd * ga[e] + ba[e] + gg[e];
;           if (LAST) { f32x4 o = {y[0], y[1], y[2], y[3]}; *(f32x4*)(P.out + (size_t)(mt * 256 + lrow) * 1024 + f0) = o; }
;           else { uint2 pk; pk.x = pack2(y[0], y[1]); pk.y = pack2(y[2], y[3]); *sp = pk; }
;         }
;         __builtin_amdgcn_sched_barrier(0);
;       }
	v_pk_mul_f32 v[54:55], v[44:45], v[54:55] op_sel_hi:[0,1]
	v_pk_mul_f32 v[42:43], v[44:45], v[42:43] op_sel_hi:[0,1]
	v_lshlrev_b32_e32 v58, 16, v41
	v_and_b32_e32 v59, 0xffff0000, v41
	v_pk_fma_f32 v[46:47], v[46:47], v[54:55], v[50:51]
	v_pk_fma_f32 v[42:43], v[48:49], v[42:43], v[52:53]
	v_pk_add_f32 v[46:47], v[46:47], v[58:59]
	v_pk_add_f32 v[42:43], v[42:43], v[60:61]
	v_cvt_pk_bf16_f32 v44, v46, v47
	v_cvt_pk_bf16_f32 v45, v42, v43
	ds_write_b64 v19, v[44:45] offset:16752
	v_add_u32_e32 v46, 0x25500, v27
	v_add_u32_e32 v41, 0x25100, v27
	ds_read_b64 v[50:51], v19 offset:128
	ds_read_b128 v[42:45], v41
	ds_read_b128 v[46:49], v46
	ds_read_b32 v52, v29
	ds_read_b32 v54, v30
	ds_read_b64 v[56:57], v19 offset:16768
	s_waitcnt lgkmcnt(5)
	v_lshlrev_b32_e32 v58, 16, v50
	v_and_b32_e32 v59, 0xffff0000, v50
	v_lshlrev_b32_e32 v50, 16, v51
	v_and_b32_e32 v51, 0xffff0000, v51
	v_lshlrev_b32_e32 v62, 16, v40
	v_and_b32_e32 v63, 0xffff0000, v40
	s_waitcnt lgkmcnt(2)
	v_pk_add_f32 v[40:41], v[58:59], v[52:53] op_sel_hi:[1,0] neg_lo:[0,1] neg_hi:[0,1]
	v_pk_add_f32 v[50:51], v[50:51], v[52:53] op_sel_hi:[1,0] neg_lo:[0,1] neg_hi:[0,1]
	s_waitcnt lgkmcnt(1)
	v_pk_mul_f32 v[40:41], v[54:55], v[40:41] op_sel_hi:[0,1]
	v_pk_mul_f32 v[50:51], v[54:55], v[50:51] op_sel_hi:[0,1]
	v_lshlrev_b32_e32 v60, 16, v38
	v_and_b32_e32 v61, 0xffff0000, v38
	v_pk_fma_f32 v[40:41], v[42:43], v[40:41], v[46:47]
	v_pk_fma_f32 v[50:51], v[44:45], v[50:51], v[48:49]
	v_pk_add_f32 v[40:41], v[40:41], v[60:61]
	v_pk_add_f32 v[50:51], v[50:51], v[62:63]
	v_cvt_pk_bf16_f32 v40, v40, v41
	v_cvt_pk_bf16_f32 v41, v50, v51
	ds_write_b64 v19, v[40:41] offset:128
	ds_read_b32 v38, v31
	ds_read_b32 v40, v33
	s_waitcnt lgkmcnt(3)
	v_lshlrev_b32_e32 v50, 16, v56
	v_and_b32_e32 v51, 0xffff0000, v56
	v_lshlrev_b32_e32 v52, 16, v57
	v_and_b32_e32 v53, 0xffff0000, v57
	v_lshlrev_b32_e32 v56, 16, v39
	v_and_b32_e32 v57, 0xffff0000, v39
	s_waitcnt lgkmcnt(1)
	v_pk_add_f32 v[50:51], v[50:51], v[38:39] op_sel_hi:[1,0] neg_lo:[0,1] neg_hi:[0,1]
	v_pk_add_f32 v[38:39], v[52:53], v[38:39] op_sel_hi:[1,0] neg_lo:[0,1] neg_hi:[0,1]
	s_waitcnt lgkmcnt(0)
	v_pk_mul_f32 v[50:51], v[40:41], v[50:51] op_sel_hi:[0,1]
	v_pk_mul_f32 v[38:39], v[40:41], v[38:39] op_sel_hi:[0,1]
	v_lshlrev_b32_e32 v54, 16, v37
	v_and_b32_e32 v55, 0xffff0000, v37
	v_pk_fma_f32 v[42:43], v[42:43], v[50:51], v[46:47]
	v_pk_fma_f32 v[38:39], v[44:45], v[38:39], v[48:49]
	v_pk_add_f32 v[42:43], v[42:43], v[54:55]
	v_pk_add_f32 v[38:39], v[38:39], v[56:57]
	v_cvt_pk_bf16_f32 v40, v42, v43
	v_cvt_pk_bf16_f32 v41, v38, v39
	ds_write_b64 v19, v[40:41] offset:16768
	v_add_u32_e32 v42, 0x25520, v27
	v_add_u32_e32 v37, 0x25120, v27
	ds_read_b64 v[46:47], v19 offset:144
	ds_read_b128 v[38:41], v37
	ds_read_b128 v[42:45], v42
	ds_read_b32 v48, v29
	ds_read_b32 v50, v30
	ds_read_b64 v[52:53], v19 offset:16784
	s_waitcnt lgkmcnt(5)
	v_lshlrev_b32_e32 v54, 16, v46
	v_and_b32_e32 v55, 0xffff0000, v46
	v_lshlrev_b32_e32 v46, 16, v47
	v_and_b32_e32 v47, 0xffff0000, v47
	v_lshlrev_b32_e32 v58, 16, v36
	v_and_b32_e32 v59, 0xffff0000, v36
	s_waitcnt lgkmcnt(2)
	v_pk_add_f32 v[36:37], v[54:55], v[48:49] op_sel_hi:[1,0] neg_lo:[0,1] neg_hi:[0,1]
	v_pk_add_f32 v[46:47], v[46:47], v[48:49] op_sel_hi:[1,0] neg_lo:[0,1] neg_hi:[0,1]
	s_waitcnt lgkmcnt(1)
	v_pk_mul_f32 v[36:37], v[50:51], v[36:37] op_sel_hi:[0,1]
	v_pk_mul_f32 v[46:47], v[50:51], v[46:47] op_sel_hi:[0,1]
	v_lshlrev_b32_e32 v56, 16, v34
	v_and_b32_e32 v57, 0xffff0000, v34
	v_pk_fma_f32 v[36:37], v[38:39], v[36:37], v[42:43]
	v_pk_fma_f32 v[46:47], v[40:41], v[46:47], v[44:45]
	v_pk_add_f32 v[36:37], v[36:37], v[56:57]
	v_pk_add_f32 v[46:47], v[46:47], v[58:59]
	v_cvt_pk_bf16_f32 v36, v36, v37
	v_cvt_pk_bf16_f32 v37, v46, v47
	ds_write_b64 v19, v[36:37] offset:144
	ds_read_b32 v34, v31
	ds_read_b32 v36, v33
	s_waitcnt lgkmcnt(3)
	v_lshlrev_b32_e32 v46, 16, v52
	v_and_b32_e32 v47, 0xffff0000, v52
	v_lshlrev_b32_e32 v48, 16, v53
	v_and_b32_e32 v49, 0xffff0000, v53
	v_lshlrev_b32_e32 v52, 16, v35
	v_and_b32_e32 v53, 0xffff0000, v35
	s_waitcnt lgkmcnt(1)
	v_pk_add_f32 v[46:47], v[46:47], v[34:35] op_sel_hi:[1,0] neg_lo:[0,1] neg_hi:[0,1]
	v_pk_add_f32 v[34:35], v[48:49], v[34:35] op_sel_hi:[1,0] neg_lo:[0,1] neg_hi:[0,1]
	s_waitcnt lgkmcnt(0)
	v_pk_mul_f32 v[46:47], v[36:37], v[46:47] op_sel_hi:[0,1]
	v_pk_mul_f32 v[34:35], v[36:37], v[34:35] op_sel_hi:[0,1]
	v_lshlrev_b32_e32 v50, 16, v32
	v_and_b32_e32 v51, 0xffff0000, v32
	v_pk_fma_f32 v[38:39], v[38:39], v[46:47], v[42:43]
	v_pk_fma_f32 v[34:35], v[40:41], v[34:35], v[44:45]
	v_pk_add_f32 v[38:39], v[38:39], v[50:51]
	v_pk_add_f32 v[34:35], v[34:35], v[52:53]
	v_cvt_pk_bf16_f32 v36, v38, v39
	v_cvt_pk_bf16_f32 v37, v34, v35
	ds_write_b64 v19, v[36:37] offset:16784
	v_add_u32_e32 v32, 0x25140, v27
	v_add_u32_e32 v38, 0x25540, v27
	ds_read_b64 v[42:43], v19 offset:160
	ds_read_b128 v[34:37], v32
	ds_read_b128 v[38:41], v38
	ds_read_b32 v32, v29
	ds_read_b32 v44, v30
	ds_read_b64 v[46:47], v19 offset:16800
	s_waitcnt lgkmcnt(5)
	v_lshlrev_b32_e32 v48, 16, v42
	v_and_b32_e32 v49, 0xffff0000, v42
	v_lshlrev_b32_e32 v42, 16, v43
	v_and_b32_e32 v43, 0xffff0000, v43
	s_waitcnt lgkmcnt(2)
	v_pk_add_f32 v[48:49], v[48:49], v[32:33] op_sel_hi:[1,0] neg_lo:[0,1] neg_hi:[0,1]
	v_pk_add_f32 v[42:43], v[42:43], v[32:33] op_sel_hi:[1,0] neg_lo:[0,1] neg_hi:[0,1]
	s_waitcnt lgkmcnt(1)
; DI unsigned pack2(float a, float b) { f32x2_t v = {a, b}; bf16x2_t r = __builtin_convertvector(v, bf16x2_t); return __builtin_bit_cast(unsigned, r); }
; DI float bflo(unsigned u) { return __uint_as_float(u << 16); }
; DI float bfhi(unsigned u) { return __uint_as_float(u & 0xffff0000u); }
; template <bool LAST>
; DI void phase_gate(const Params& P, int layer, unsigned char* smem, int L, int G) {
;     ...
; #pragma unroll
;     for (int i = 0; i < 4; ++i)
; #pragma unroll
;       for (int q4 = 0; q4 < 4; ++q4) {
;         const int fl = wm2 * 128 + i * 32 + 8 * q4 + 4 * h2;
;         const int f0 = nt * 256 + fl;
;         const f32x4 gv = *(const f32x4*)(vecL + 512 + fl), bv = *(const f32x4*)(vecL + 768 + fl);
;         const float ga[4] = {gv.x, gv.y, gv.z, gv.w}, ba[4] = {bv.x, bv.y, bv.z, bv.w};
; #pragma unroll
;         for (int j = 0; j < 2; ++j) {
;           const int lrow = wn2 * 64 + j * 32 + r2;
;           const float mu = rowA[lrow], rstd = rowB[lrow];
;           uint2* sp = (uint2*)(stg + lrow * STG + fl);
;           const uint2 sv = *sp;
;           const float sa[4] = {bflo(sv.x), bfhi(sv.x), bflo(sv.y), bfhi(sv.y)};
;           float y[4];
;           const float gg[4] = {bflo(gq[i][j][2 * q4]), bfhi(gq[i][j][2 * q4]), bflo(gq[i][j][2 * q4 + 1]), bfhi(gq[i][j][2 * q4 + 1])};
; #pragma unroll
;           for (int e = 0; e < 4; ++e) y[e] = (sa[e] - mu) * rstd * ga[e] + ba[e] + gg[e];
;           if (LAST) { f32x4 o = {y[0], y[1], y[2], y[3]}; *(f32x4*)(P.out + (size_t)(mt * 256 + lrow) * 1024 + f0) = o; }
;           else { uint2 pk; pk.x = pack2(y[0], y[1]); pk.y = pack2(y[2], y[3]); *sp = pk; }
;         }
;         __builtin_amdgcn_sched_barrier(0);
;       }
	v_pk_mul_f32 v[48:49], v[44:45], v[48:49] op_sel_hi:[0,1]
	v_pk_mul_f32 v[42:43], v[44:45], v[42:43] op_sel_hi:[0,1]
	v_lshlrev_b32_e32 v50, 16, v24
	v_and_b32_e32 v51, 0xffff0000, v24
	v_lshlrev_b32_e32 v52, 16, v26
	v_and_b32_e32 v53, 0xffff0000, v26
	v_pk_fma_f32 v[48:49], v[34:35], v[48:49], v[38:39]
	v_pk_fma_f32 v[42:43], v[36:37], v[42:43], v[40:41]
	v_pk_add_f32 v[48:49], v[48:49], v[50:51]
	v_pk_add_f32 v[42:43], v[42:43], v[52:53]
	v_cvt_pk_bf16_f32 v44, v48, v49
	v_cvt_pk_bf16_f32 v45, v42, v43
	ds_write_b64 v19, v[44:45] offset:160
	ds_read_b32 v24, v31
	ds_read_b32 v26, v33
	s_waitcnt lgkmcnt(3)
	v_lshlrev_b32_e32 v42, 16, v46
	v_and_b32_e32 v43, 0xffff0000, v46
	v_lshlrev_b32_e32 v44, 16, v47
	v_and_b32_e32 v45, 0xffff0000, v47
	v_lshlrev_b32_e32 v48, 16, v25
	v_and_b32_e32 v49, 0xffff0000, v25
	s_waitcnt lgkmcnt(1)
	v_pk_add_f32 v[42:43], v[42:43], v[24:25] op_sel_hi:[1,0] neg_lo:[0,1] neg_hi:[0,1]
	v_pk_add_f32 v[24:25], v[44:45], v[24:25] op_sel_hi:[1,0] neg_lo:[0,1] neg_hi:[0,1]
	s_waitcnt lgkmcnt(0)
	v_pk_mul_f32 v[42:43], v[26:27], v[42:43] op_sel_hi:[0,1]
	v_pk_mul_f32 v[24:25], v[26:27], v[24:25] op_sel_hi:[0,1]
	v_lshlrev_b32_e32 v46, 16, v23
	v_and_b32_e32 v47, 0xffff0000, v23
	v_pk_fma_f32 v[34:35], v[34:35], v[42:43], v[38:39]
	v_pk_fma_f32 v[24:25], v[36:37], v[24:25], v[40:41]
	v_pk_add_f32 v[34:35], v[34:35], v[46:47]
	v_pk_add_f32 v[24:25], v[24:25], v[48:49]
	v_cvt_pk_bf16_f32 v34, v34, v35
	v_cvt_pk_bf16_f32 v35, v24, v25
	ds_write_b64 v19, v[34:35] offset:16800
	v_add_u32_e32 v26, 0x25560, v27
	v_add_u32_e32 v23, 0x25160, v27
	ds_read_b64 v[24:25], v19 offset:176
	ds_read_b128 v[34:37], v23
	ds_read_b128 v[38:41], v26
	ds_read_b32 v26, v29
	ds_read_b32 v32, v30
	ds_read_b64 v[42:43], v19 offset:16816
	s_waitcnt lgkmcnt(5)
	v_lshlrev_b32_e32 v44, 16, v24
	v_and_b32_e32 v45, 0xffff0000, v24
	v_lshlrev_b32_e32 v24, 16, v25
	v_and_b32_e32 v25, 0xffff0000, v25
	v_lshlrev_b32_e32 v48, 16, v22
	v_and_b32_e32 v49, 0xffff0000, v22
	s_waitcnt lgkmcnt(2)
	v_pk_add_f32 v[22:23], v[44:45], v[26:27] op_sel_hi:[1,0] neg_lo:[0,1] neg_hi:[0,1]
	v_pk_add_f32 v[24:25], v[24:25], v[26:27] op_sel_hi:[1,0] neg_lo:[0,1] neg_hi:[0,1]
	s_waitcnt lgkmcnt(1)
	v_pk_mul_f32 v[22:23], v[32:33], v[22:23] op_sel_hi:[0,1]
	v_pk_mul_f32 v[24:25], v[32:33], v[24:25] op_sel_hi:[0,1]
	v_lshlrev_b32_e32 v46, 16, v20
	v_and_b32_e32 v47, 0xffff0000, v20
	v_pk_fma_f32 v[22:23], v[34:35], v[22:23], v[38:39]
	v_pk_fma_f32 v[24:25], v[36:37], v[24:25], v[40:41]
	v_pk_add_f32 v[22:23], v[22:23], v[46:47]
	v_pk_add_f32 v[24:25], v[24:25], v[48:49]
	v_cvt_pk_bf16_f32 v22, v22, v23
	v_cvt_pk_bf16_f32 v23, v24, v25
	ds_write_b64 v19, v[22:23] offset:176
	ds_read_b32 v20, v31
	ds_read_b32 v22, v33
	s_waitcnt lgkmcnt(3)
	v_lshlrev_b32_e32 v24, 16, v42
	v_and_b32_e32 v25, 0xffff0000, v42
	v_lshlrev_b32_e32 v42, 16, v43
	v_and_b32_e32 v43, 0xffff0000, v43
	v_lshlrev_b32_e32 v46, 16, v21
	v_and_b32_e32 v47, 0xffff0000, v21
	s_waitcnt lgkmcnt(1)
	v_pk_add_f32 v[24:25], v[24:25], v[20:21] op_sel_hi:[1,0] neg_lo:[0,1] neg_hi:[0,1]
	v_pk_add_f32 v[20:21], v[42:43], v[20:21] op_sel_hi:[1,0] neg_lo:[0,1] neg_hi:[0,1]
	s_waitcnt lgkmcnt(0)
	v_pk_mul_f32 v[24:25], v[22:23], v[24:25] op_sel_hi:[0,1]
	v_pk_mul_f32 v[20:21], v[22:23], v[20:21] op_sel_hi:[0,1]
	v_lshlrev_b32_e32 v44, 16, v18
	v_and_b32_e32 v45, 0xffff0000, v18
	v_pk_fma_f32 v[24:25], v[34:35], v[24:25], v[38:39]
	v_pk_fma_f32 v[20:21], v[36:37], v[20:21], v[40:41]
	v_pk_add_f32 v[24:25], v[24:25], v[44:45]
	v_pk_add_f32 v[20:21], v[20:21], v[46:47]
	v_cvt_pk_bf16_f32 v22, v24, v25
	v_cvt_pk_bf16_f32 v23, v20, v21
	ds_write_b64 v19, v[22:23] offset:16816
	v_add_u32_e32 v18, 0x25180, v27
	v_add_u32_e32 v26, 0x25580, v27
	ds_read_b64 v[24:25], v19 offset:192
	ds_read_b128 v[20:23], v18
	ds_read_b128 v[34:37], v26
	ds_read_b32 v18, v29
	ds_read_b32 v26, v30
	ds_read_b64 v[38:39], v19 offset:16832
	s_waitcnt lgkmcnt(5)
	v_lshlrev_b32_e32 v40, 16, v24
	v_and_b32_e32 v41, 0xffff0000, v24
	v_lshlrev_b32_e32 v24, 16, v25
	v_and_b32_e32 v25, 0xffff0000, v25
	s_waitcnt lgkmcnt(2)
	v_pk_add_f32 v[40:41], v[40:41], v[18:19] op_sel_hi:[1,0] neg_lo:[0,1] neg_hi:[0,1]
	v_pk_add_f32 v[24:25], v[24:25], v[18:19] op_sel_hi:[1,0] neg_lo:[0,1] neg_hi:[0,1]
	s_waitcnt lgkmcnt(1)
	v_pk_mul_f32 v[40:41], v[26:27], v[40:41] op_sel_hi:[0,1]
	v_pk_mul_f32 v[24:25], v[26:27], v[24:25] op_sel_hi:[0,1]
	v_lshlrev_b32_e32 v42, 16, v15
	v_and_b32_e32 v43, 0xffff0000, v15
	v_lshlrev_b32_e32 v44, 16, v17
	v_and_b32_e32 v45, 0xffff0000, v17
	v_pk_fma_f32 v[40:41], v[20:21], v[40:41], v[34:35]
	v_pk_fma_f32 v[24:25], v[22:23], v[24:25], v[36:37]
	v_pk_add_f32 v[40:41], v[40:41], v[42:43]
	v_pk_add_f32 v[24:25], v[24:25], v[44:45]
	v_cvt_pk_bf16_f32 v40, v40, v41
	v_cvt_pk_bf16_f32 v41, v24, v25
	ds_write_b64 v19, v[40:41] offset:192
	ds_read_b32 v18, v31
	ds_read_b32 v24, v33
	s_waitcnt lgkmcnt(3)
	v_lshlrev_b32_e32 v40, 16, v38
	v_and_b32_e32 v41, 0xffff0000, v38
	v_lshlrev_b32_e32 v42, 16, v14
	v_and_b32_e32 v43, 0xffff0000, v14
	v_lshlrev_b32_e32 v14, 16, v16
	v_and_b32_e32 v15, 0xffff0000, v16
	s_waitcnt lgkmcnt(1)
	v_pk_add_f32 v[16:17], v[40:41], v[18:19] op_sel_hi:[1,0] neg_lo:[0,1] neg_hi:[0,1]
	v_lshlrev_b32_e32 v38, 16, v39
	v_and_b32_e32 v39, 0xffff0000, v39
	s_waitcnt lgkmcnt(0)
; DI unsigned pack2(float a, float b) { f32x2_t v = {a, b}; bf16x2_t r = __builtin_convertvector(v, bf16x2_t); return __builtin_bit_cast(unsigned, r); }
; DI float bflo(unsigned u) { return __uint_as_float(u << 16); }
; DI float bfhi(unsigned u) { return __uint_as_float(u & 0xffff0000u); }
; template <bool LAST>
; DI void phase_gate(const Params& P, int layer, unsigned char* smem, int L, int G) {
;     ...
; #pragma unroll
;     for (int i = 0; i < 4; ++i)
; #pragma unroll
;       for (int q4 = 0; q4 < 4; ++q4) {
;         const int fl = wm2 * 128 + i * 32 + 8 * q4 + 4 * h2;
;         const int f0 = nt * 256 + fl;
;         const f32x4 gv = *(const f32x4*)(vecL + 512 + fl), bv = *(const f32x4*)(vecL + 768 + fl);
;         const float ga[4] = {gv.x, gv.y, gv.z, gv.w}, ba[4] = {bv.x, bv.y, bv.z, bv.w};
; #pragma unroll
;         for (int j = 0; j < 2; ++j) {
;           const int lrow = wn2 * 64 + j * 32 + r2;
;           const float mu = rowA[lrow], rstd = rowB[lrow];
;           uint2* sp = (uint2*)(stg + lrow * STG + fl);
;           const uint2 sv = *sp;
;           const float sa[4] = {bflo(sv.x), bfhi(sv.x), bflo(sv.y), bfhi(sv.y)};
;           float y[4];
;           const float gg[4] = {bflo(gq[i][j][2 * q4]), bfhi(gq[i][j][2 * q4]), bflo(gq[i][j][2 * q4 + 1]), bfhi(gq[i][j][2 * q4 + 1])};
; #pragma unroll
;           for (int e = 0; e < 4; ++e) y[e] = (sa[e] - mu) * rstd * ga[e] + ba[e] + gg[e];
;           if (LAST) { f32x4 o = {y[0], y[1], y[2], y[3]}; *(f32x4*)(P.out + (size_t)(mt * 256 + lrow) * 1024 + f0) = o; }
;           else { uint2 pk; pk.x = pack2(y[0], y[1]); pk.y = pack2(y[2], y[3]); *sp = pk; }
;         }
;         __builtin_amdgcn_sched_barrier(0);
;       }
;     __syncthreads();
;     if (!LAST) stage_store_tile(stg, xb + (size_t)mt * 256 * 1024 + nt * 256);
;     __syncthreads();
	v_pk_mul_f32 v[16:17], v[24:25], v[16:17] op_sel_hi:[0,1]
	v_pk_fma_f32 v[16:17], v[20:21], v[16:17], v[34:35]
	v_pk_add_f32 v[20:21], v[38:39], v[18:19] op_sel_hi:[1,0] neg_lo:[0,1] neg_hi:[0,1]
	v_pk_add_f32 v[16:17], v[16:17], v[42:43]
	v_pk_mul_f32 v[20:21], v[24:25], v[20:21] op_sel_hi:[0,1]
	v_pk_fma_f32 v[20:21], v[22:23], v[20:21], v[36:37]
	v_cvt_pk_bf16_f32 v16, v16, v17
	v_pk_add_f32 v[14:15], v[20:21], v[14:15]
	s_nop 0
	v_cvt_pk_bf16_f32 v17, v14, v15
	ds_write_b64 v19, v[16:17] offset:16832
	v_add_u32_e32 v14, 0x251a0, v27
	v_add_u32_e32 v18, 0x255a0, v27
	ds_read_b64 v[24:25], v19 offset:208
	ds_read_b128 v[14:17], v14
	ds_read_b128 v[20:23], v18
	ds_read_b32 v18, v29
	ds_read_b32 v26, v30
	ds_read_b64 v[34:35], v19 offset:16848
	s_waitcnt lgkmcnt(5)
	v_lshlrev_b32_e32 v36, 16, v24
	v_and_b32_e32 v37, 0xffff0000, v24
	v_lshlrev_b32_e32 v24, 16, v25
	v_and_b32_e32 v25, 0xffff0000, v25
	s_waitcnt lgkmcnt(2)
	v_pk_add_f32 v[36:37], v[36:37], v[18:19] op_sel_hi:[1,0] neg_lo:[0,1] neg_hi:[0,1]
	v_pk_add_f32 v[24:25], v[24:25], v[18:19] op_sel_hi:[1,0] neg_lo:[0,1] neg_hi:[0,1]
	s_waitcnt lgkmcnt(1)
	v_pk_mul_f32 v[36:37], v[26:27], v[36:37] op_sel_hi:[0,1]
	v_pk_mul_f32 v[24:25], v[26:27], v[24:25] op_sel_hi:[0,1]
	v_lshlrev_b32_e32 v38, 16, v11
	v_and_b32_e32 v39, 0xffff0000, v11
	v_lshlrev_b32_e32 v40, 16, v13
	v_and_b32_e32 v41, 0xffff0000, v13
	v_pk_fma_f32 v[36:37], v[14:15], v[36:37], v[20:21]
	v_pk_fma_f32 v[24:25], v[16:17], v[24:25], v[22:23]
	v_pk_add_f32 v[36:37], v[36:37], v[38:39]
	v_pk_add_f32 v[24:25], v[24:25], v[40:41]
	v_cvt_pk_bf16_f32 v36, v36, v37
	v_cvt_pk_bf16_f32 v37, v24, v25
	ds_write_b64 v19, v[36:37] offset:208
	ds_read_b32 v18, v31
	ds_read_b32 v24, v33
	s_waitcnt lgkmcnt(3)
	v_lshlrev_b32_e32 v36, 16, v34
	v_and_b32_e32 v37, 0xffff0000, v34
	v_lshlrev_b32_e32 v38, 16, v10
	v_and_b32_e32 v39, 0xffff0000, v10
	v_lshlrev_b32_e32 v10, 16, v12
	v_and_b32_e32 v11, 0xffff0000, v12
	s_waitcnt lgkmcnt(1)
	v_pk_add_f32 v[12:13], v[36:37], v[18:19] op_sel_hi:[1,0] neg_lo:[0,1] neg_hi:[0,1]
	v_lshlrev_b32_e32 v34, 16, v35
	v_and_b32_e32 v35, 0xffff0000, v35
	s_waitcnt lgkmcnt(0)
	v_pk_mul_f32 v[12:13], v[24:25], v[12:13] op_sel_hi:[0,1]
	v_pk_fma_f32 v[12:13], v[14:15], v[12:13], v[20:21]
	v_pk_add_f32 v[14:15], v[34:35], v[18:19] op_sel_hi:[1,0] neg_lo:[0,1] neg_hi:[0,1]
	v_pk_add_f32 v[12:13], v[12:13], v[38:39]
	v_pk_mul_f32 v[14:15], v[24:25], v[14:15] op_sel_hi:[0,1]
	v_pk_fma_f32 v[14:15], v[16:17], v[14:15], v[22:23]
	v_cvt_pk_bf16_f32 v12, v12, v13
	v_pk_add_f32 v[10:11], v[14:15], v[10:11]
	s_nop 0
	v_cvt_pk_bf16_f32 v13, v10, v11
	ds_write_b64 v19, v[12:13] offset:16848
	v_add_u32_e32 v10, 0x251c0, v27
	v_add_u32_e32 v14, 0x255c0, v27
	ds_read_b64 v[20:21], v19 offset:224
	ds_read_b128 v[10:13], v10
	ds_read_b128 v[14:17], v14
	ds_read_b32 v18, v29
	ds_read_b32 v22, v30
	ds_read_b64 v[24:25], v19 offset:16864
	s_waitcnt lgkmcnt(5)
	v_lshlrev_b32_e32 v34, 16, v20
	v_and_b32_e32 v35, 0xffff0000, v20
	v_lshlrev_b32_e32 v20, 16, v21
	v_and_b32_e32 v21, 0xffff0000, v21
	s_waitcnt lgkmcnt(2)
	v_pk_add_f32 v[34:35], v[34:35], v[18:19] op_sel_hi:[1,0] neg_lo:[0,1] neg_hi:[0,1]
	v_pk_add_f32 v[20:21], v[20:21], v[18:19] op_sel_hi:[1,0] neg_lo:[0,1] neg_hi:[0,1]
	s_waitcnt lgkmcnt(1)
	v_pk_mul_f32 v[34:35], v[22:23], v[34:35] op_sel_hi:[0,1]
	v_pk_mul_f32 v[20:21], v[22:23], v[20:21] op_sel_hi:[0,1]
	v_lshlrev_b32_e32 v36, 16, v7
	v_and_b32_e32 v37, 0xffff0000, v7
	v_lshlrev_b32_e32 v38, 16, v9
	v_and_b32_e32 v39, 0xffff0000, v9
	v_pk_fma_f32 v[34:35], v[10:11], v[34:35], v[14:15]
	v_pk_fma_f32 v[20:21], v[12:13], v[20:21], v[16:17]
	v_pk_add_f32 v[34:35], v[34:35], v[36:37]
	v_pk_add_f32 v[20:21], v[20:21], v[38:39]
	v_cvt_pk_bf16_f32 v22, v34, v35
	v_cvt_pk_bf16_f32 v23, v20, v21
	ds_write_b64 v19, v[22:23] offset:224
	ds_read_b32 v18, v31
	ds_read_b32 v20, v33
	s_waitcnt lgkmcnt(3)
	v_lshlrev_b32_e32 v22, 16, v24
	v_and_b32_e32 v23, 0xffff0000, v24
	v_lshlrev_b32_e32 v34, 16, v6
	v_and_b32_e32 v35, 0xffff0000, v6
	v_lshlrev_b32_e32 v6, 16, v8
	v_and_b32_e32 v7, 0xffff0000, v8
	s_waitcnt lgkmcnt(1)
	v_pk_add_f32 v[8:9], v[22:23], v[18:19] op_sel_hi:[1,0] neg_lo:[0,1] neg_hi:[0,1]
	v_lshlrev_b32_e32 v24, 16, v25
	v_and_b32_e32 v25, 0xffff0000, v25
	s_waitcnt lgkmcnt(0)
	v_pk_mul_f32 v[8:9], v[20:21], v[8:9] op_sel_hi:[0,1]
	v_pk_fma_f32 v[8:9], v[10:11], v[8:9], v[14:15]
	v_pk_add_f32 v[10:11], v[24:25], v[18:19] op_sel_hi:[1,0] neg_lo:[0,1] neg_hi:[0,1]
	v_pk_add_f32 v[8:9], v[8:9], v[34:35]
	v_pk_mul_f32 v[10:11], v[20:21], v[10:11] op_sel_hi:[0,1]
	v_pk_fma_f32 v[10:11], v[12:13], v[10:11], v[16:17]
	v_cvt_pk_bf16_f32 v8, v8, v9
	v_pk_add_f32 v[6:7], v[10:11], v[6:7]
	s_nop 0
	v_cvt_pk_bf16_f32 v9, v6, v7
	ds_write_b64 v19, v[8:9] offset:16864
	ds_read_b128 v[6:9], v28 offset:480
	ds_read_b64 v[14:15], v19 offset:240
	ds_read_b32 v16, v29
	ds_read_b32 v18, v30
	v_add_u32_e32 v10, 0x255e0, v27
	ds_read_b128 v[10:13], v10
	s_waitcnt lgkmcnt(3)
	v_lshlrev_b32_e32 v20, 16, v14
	v_and_b32_e32 v21, 0xffff0000, v14
	v_lshlrev_b32_e32 v14, 16, v15
	v_and_b32_e32 v15, 0xffff0000, v15
	s_waitcnt lgkmcnt(2)
	v_pk_add_f32 v[20:21], v[20:21], v[16:17] op_sel_hi:[1,0] neg_lo:[0,1] neg_hi:[0,1]
	v_pk_add_f32 v[14:15], v[14:15], v[16:17] op_sel_hi:[1,0] neg_lo:[0,1] neg_hi:[0,1]
	s_waitcnt lgkmcnt(1)
	v_pk_mul_f32 v[20:21], v[18:19], v[20:21] op_sel_hi:[0,1]
	v_pk_mul_f32 v[14:15], v[18:19], v[14:15] op_sel_hi:[0,1]
	v_lshlrev_b32_e32 v22, 16, v4
	v_and_b32_e32 v23, 0xffff0000, v4
	v_lshlrev_b32_e32 v4, 16, v5
	v_and_b32_e32 v5, 0xffff0000, v5
	s_waitcnt lgkmcnt(0)
	v_pk_fma_f32 v[20:21], v[6:7], v[20:21], v[10:11]
	v_pk_fma_f32 v[14:15], v[8:9], v[14:15], v[12:13]
	v_pk_add_f32 v[20:21], v[20:21], v[22:23]
	v_pk_add_f32 v[4:5], v[14:15], v[4:5]
	v_cvt_pk_bf16_f32 v14, v20, v21
	v_cvt_pk_bf16_f32 v15, v4, v5
	ds_write_b64 v19, v[14:15] offset:240
	ds_read_b32 v4, v33
	ds_read_b64 v[14:15], v19 offset:16880
	ds_read_b32 v16, v31
	v_lshlrev_b32_e32 v22, 16, v2
	v_and_b32_e32 v23, 0xffff0000, v2
	v_lshlrev_b32_e32 v2, 16, v3
	s_waitcnt lgkmcnt(1)
	v_lshlrev_b32_e32 v20, 16, v14
	v_and_b32_e32 v21, 0xffff0000, v14
	s_waitcnt lgkmcnt(0)
	v_pk_add_f32 v[20:21], v[20:21], v[16:17] op_sel_hi:[1,0] neg_lo:[0,1] neg_hi:[0,1]
	v_lshlrev_b32_e32 v14, 16, v15
	v_and_b32_e32 v15, 0xffff0000, v15
	v_pk_mul_f32 v[20:21], v[4:5], v[20:21] op_sel_hi:[0,1]
	v_pk_fma_f32 v[6:7], v[6:7], v[20:21], v[10:11]
	v_pk_add_f32 v[10:11], v[14:15], v[16:17] op_sel_hi:[1,0] neg_lo:[0,1] neg_hi:[0,1]
	v_and_b32_e32 v3, 0xffff0000, v3
	v_pk_mul_f32 v[4:5], v[4:5], v[10:11] op_sel_hi:[0,1]
	v_pk_fma_f32 v[4:5], v[8:9], v[4:5], v[12:13]
	v_pk_add_f32 v[6:7], v[6:7], v[22:23]
	v_pk_add_f32 v[2:3], v[4:5], v[2:3]
	v_cvt_pk_bf16_f32 v4, v6, v7
	v_cvt_pk_bf16_f32 v5, v2, v3
	ds_write_b64 v19, v[4:5] offset:16880
	s_add_u32 s18, s80, s18
	s_addc_u32 s19, s81, s19
	v_lshl_add_u64 v[8:9], s[18:19], 0, v[0:1]
	v_mov_b32_e32 v0, v192
	s_waitcnt lgkmcnt(0)
	s_barrier
; DI int otid() { int t = threadIdx.x; asm volatile("" : "+v"(t)); return t; }
; DI void stg16_nt(void* p, u32x4 v) { __builtin_nontemporal_store(v, (u32x4*)p); }
; DI void stage_store_tile(const bf16_t* stg, bf16_t* tilebase) {
;   const int tid = otid();
;   const int r0 = tid >> 5, c = tid & 31;
;   const unsigned o0 = (unsigned)(r0 * 1024 + c * 8);
; #pragma unroll
;   for (int it = 0; it < 16; ++it) stg16_nt(tilebase + (o0 + (unsigned)(it * 16 * 1024)), stage_read16(stg, r0 + 16 * it, c));
; }
; template <bool LAST>
; DI void phase_gate(const Params& P, int layer, unsigned char* smem, int L, int G) {
;     ...
;     if (!LAST) stage_store_tile(stg, xb + (size_t)mt * 256 * 1024 + nt * 256);
;     __syncthreads();
	s_add_i32 s25, s25, s74
	v_ashrrev_i32_e32 v4, 5, v0
	v_and_b32_e32 v0, 31, v0
	v_mul_lo_u32 v1, v4, s34
	v_lshl_add_u32 v12, v0, 4, v1
	v_lshlrev_b32_e32 v5, 3, v0
	ds_read2_b64 v[0:3], v12 offset1:1
	v_lshl_or_b32 v160, v4, 10, v5
	v_add_u32_e32 v4, 0x2080, v12
	ds_read2_b64 v[4:7], v4 offset1:1
	v_lshl_add_u64 v[10:11], v[160:161], 1, v[8:9]
	s_waitcnt lgkmcnt(1)
	global_store_dwordx4 v[10:11], v[0:3], off
	s_add_i32 s22, s22, s69
	s_add_i32 s23, s23, s24
	v_add_u32_e32 v0, 0x4000, v160
	v_mov_b32_e32 v1, v161
	v_lshl_add_u64 v[0:1], v[0:1], 1, v[8:9]
	s_waitcnt lgkmcnt(0)
	global_store_dwordx4 v[0:1], v[4:7], off
	v_add_u32_e32 v0, 0x4100, v12
	ds_read2_b64 v[0:3], v0 offset1:1
	v_add_u32_e32 v4, 0x8000, v160
	v_mov_b32_e32 v5, v161
	v_lshl_add_u64 v[10:11], v[4:5], 1, v[8:9]
	v_add_u32_e32 v4, 0x6180, v12
	ds_read2_b64 v[4:7], v4 offset1:1
	s_waitcnt lgkmcnt(1)
	global_store_dwordx4 v[10:11], v[0:3], off
	s_add_i32 s18, s70, s25
	s_cmpk_lt_i32 s18, 0x400
	v_add_u32_e32 v0, 0xc000, v160
	v_mov_b32_e32 v1, v161
	v_lshl_add_u64 v[0:1], v[0:1], 1, v[8:9]
	s_waitcnt lgkmcnt(0)
	global_store_dwordx4 v[0:1], v[4:7], off
	v_add_u32_e32 v0, 0x8200, v12
	ds_read2_b64 v[0:3], v0 offset1:1
	v_add_u32_e32 v4, 0x10000, v160
	v_mov_b32_e32 v5, v161
	v_lshl_add_u64 v[10:11], v[4:5], 1, v[8:9]
	v_add_u32_e32 v4, 0xa280, v12
	ds_read2_b64 v[4:7], v4 offset1:1
	s_waitcnt lgkmcnt(1)
	global_store_dwordx4 v[10:11], v[0:3], off
	s_nop 1
	v_add_u32_e32 v0, 0x14000, v160
	v_mov_b32_e32 v1, v161
	v_lshl_add_u64 v[0:1], v[0:1], 1, v[8:9]
	s_waitcnt lgkmcnt(0)
	global_store_dwordx4 v[0:1], v[4:7], off
	v_add_u32_e32 v0, 0xc300, v12
	ds_read2_b64 v[0:3], v0 offset1:1
	v_add_u32_e32 v4, 0x18000, v160
	v_mov_b32_e32 v5, v161
	v_lshl_add_u64 v[10:11], v[4:5], 1, v[8:9]
	v_add_u32_e32 v4, 0xe380, v12
	ds_read2_b64 v[4:7], v4 offset1:1
	s_waitcnt lgkmcnt(1)
	global_store_dwordx4 v[10:11], v[0:3], off
	s_nop 1
	v_add_u32_e32 v0, 0x1c000, v160
	v_mov_b32_e32 v1, v161
	v_lshl_add_u64 v[0:1], v[0:1], 1, v[8:9]
	s_waitcnt lgkmcnt(0)
	global_store_dwordx4 v[0:1], v[4:7], off
	v_add_u32_e32 v0, 0x10400, v12
	ds_read2_b64 v[0:3], v0 offset1:1
	v_add_u32_e32 v4, 0x20000, v160
	v_mov_b32_e32 v5, v161
	v_lshl_add_u64 v[10:11], v[4:5], 1, v[8:9]
	v_add_u32_e32 v4, 0x12480, v12
	ds_read2_b64 v[4:7], v4 offset1:1
	s_waitcnt lgkmcnt(1)
	global_store_dwordx4 v[10:11], v[0:3], off
	s_nop 1
	v_add_u32_e32 v0, 0x24000, v160
	v_mov_b32_e32 v1, v161
	v_lshl_add_u64 v[0:1], v[0:1], 1, v[8:9]
	s_waitcnt lgkmcnt(0)
	global_store_dwordx4 v[0:1], v[4:7], off
	v_add_u32_e32 v0, 0x14500, v12
	ds_read2_b64 v[0:3], v0 offset1:1
	v_add_u32_e32 v4, 0x28000, v160
	v_mov_b32_e32 v5, v161
	v_lshl_add_u64 v[10:11], v[4:5], 1, v[8:9]
	v_add_u32_e32 v4, 0x16580, v12
	ds_read2_b64 v[4:7], v4 offset1:1
	s_waitcnt lgkmcnt(1)
	global_store_dwordx4 v[10:11], v[0:3], off
	s_nop 1
	v_add_u32_e32 v0, 0x2c000, v160
	v_mov_b32_e32 v1, v161
	v_lshl_add_u64 v[0:1], v[0:1], 1, v[8:9]
	s_waitcnt lgkmcnt(0)
	global_store_dwordx4 v[0:1], v[4:7], off
	v_add_u32_e32 v0, 0x18600, v12
	ds_read2_b64 v[0:3], v0 offset1:1
	v_add_u32_e32 v4, 0x30000, v160
	v_mov_b32_e32 v5, v161
	v_lshl_add_u64 v[10:11], v[4:5], 1, v[8:9]
	v_add_u32_e32 v4, 0x1a680, v12
	ds_read2_b64 v[4:7], v4 offset1:1
	s_waitcnt lgkmcnt(1)
	global_store_dwordx4 v[10:11], v[0:3], off
	v_add_u32_e32 v10, 0x38000, v160
	v_mov_b32_e32 v11, v161
	v_add_u32_e32 v0, 0x34000, v160
	v_mov_b32_e32 v1, v161
	v_lshl_add_u64 v[0:1], v[0:1], 1, v[8:9]
	s_waitcnt lgkmcnt(0)
	global_store_dwordx4 v[0:1], v[4:7], off
	v_add_u32_e32 v0, 0x1c700, v12
	ds_read2_b64 v[0:3], v0 offset1:1
	v_add_u32_e32 v4, 0x1e780, v12
	ds_read2_b64 v[4:7], v4 offset1:1
	v_lshl_add_u64 v[10:11], v[10:11], 1, v[8:9]
	v_add_u32_e32 v160, 0x3c000, v160
	s_waitcnt lgkmcnt(1)
	global_store_dwordx4 v[10:11], v[0:3], off
	s_nop 1
	v_lshl_add_u64 v[0:1], v[160:161], 1, v[8:9]
	s_waitcnt lgkmcnt(0)
	global_store_dwordx4 v[0:1], v[4:7], off
	s_barrier
	s_cbranch_scc0 .LBB0_1507

; DI void stg16_nt(void* p, u32x4 v) { __builtin_nontemporal_store(v, (u32x4*)p); }
; DI void epi_seg(const f32x16 (&acc)[4][2], const Seg& sg0, const Seg& sg1, int m0, int n0, const float* rs, const float2* cs64, const float2* cs32, bf16_t* stg) {
;     ...
;   __syncthreads();
; #pragma unroll
;   for (int it = 0; it < 16; ++it) {
;     const int idx = tid + NTHR * it, rr = idx >> 5, c = idx & 31;
;     const Seg& fs = (c >> 4) ? sg1 : sg0;
;     const int lcc = n0 + c * 8 - fs.cbase;
;     if (fs.kind != K_NONE && lcc < fs.nvalid) {
;       const int row = m0 + rr;
;       size_t off;
;       if (fs.kind == K_KC2) { const int b = row >> 9, n = (row >> 2) & 127, g = row & 3; off = ((size_t)((b * 4 + g) * 128 + n)) * 64 + lcc; }
;       else off = (size_t)row * fs.ld + lcc;
;       stg16_nt(fs.dst + off, stage_read16(stg, rr, c));
;     }
;   }
.LBB0_1590:
	s_or_b64 exec, exec, s[24:25]
	v_mov_b32_e32 v162, s49
	v_mov_b32_e32 v163, s48
	v_cmp_gt_u32_e32 vcc, 16, v167
	v_lshl_or_b32 v160, v167, 3, s17
	s_waitcnt lgkmcnt(0)
	v_cndmask_b32_e32 v162, v162, v163, vcc
	v_sub_u32_e32 v162, v160, v162
	v_cmp_gt_i32_e64 s[0:1], 2.0, v162
	s_barrier
	s_and_saveexec_b64 s[24:25], s[0:1]
	s_cbranch_execz .LBB0_1592
	v_ashrrev_i32_e32 v170, 5, v166
	v_mov_b32_e32 v164, s16
	v_mov_b32_e32 v165, s18
	v_mov_b32_e32 v171, s21
	v_mov_b32_e32 v172, s15
	v_add_u32_e32 v163, s19, v170
	v_cndmask_b32_e32 v180, v164, v165, vcc
	v_cndmask_b32_e32 v175, v171, v172, vcc
	v_mov_b32_e32 v171, s20
	v_mov_b32_e32 v172, s14
	v_lshlrev_b32_e32 v160, 4, v167
	v_mad_i64_i32 v[164:165], s[0:1], v180, v163, 0
	v_ashrrev_i32_e32 v163, 31, v162
	v_cndmask_b32_e32 v174, v171, v172, vcc
	v_lshl_add_u64 v[164:165], v[164:165], 1, v[174:175]
	v_lshlrev_b64 v[176:177], 1, v[162:163]
	v_mad_u64_u32 v[162:163], s[0:1], v170, s45, v[160:161]
	v_lshl_add_u64 v[178:179], v[164:165], 0, v[176:177]
	ds_read2_b64 v[162:165], v162 offset1:1
	v_add_u32_e32 v170, 0x200, v166
	v_ashrrev_i32_e32 v181, 5, v170
	v_mad_u64_u32 v[170:171], s[0:1], v181, s45, v[160:161]
	ds_read2_b64 v[170:173], v170 offset1:1
	s_waitcnt lgkmcnt(1)
	global_store_dwordx4 v[178:179], v[162:165], off
	s_nop 1
	v_add_u32_e32 v162, s19, v181
	v_mad_i64_i32 v[162:163], s[0:1], v180, v162, 0
	v_lshl_add_u64 v[162:163], v[162:163], 1, v[174:175]
	v_lshl_add_u64 v[162:163], v[162:163], 0, v[176:177]
	s_waitcnt lgkmcnt(0)
	global_store_dwordx4 v[162:163], v[170:173], off
	v_add_u32_e32 v162, 0x400, v166
	v_ashrrev_i32_e32 v164, 5, v162
	v_add_u32_e32 v162, s19, v164
	v_mad_i64_i32 v[162:163], s[0:1], v180, v162, 0
	v_lshl_add_u64 v[162:163], v[162:163], 1, v[174:175]
	v_lshl_add_u64 v[178:179], v[162:163], 0, v[176:177]
	v_mad_u64_u32 v[162:163], s[0:1], v164, s45, v[160:161]
	ds_read2_b64 v[162:165], v162 offset1:1
	v_add_u32_e32 v170, 0x600, v166
	v_ashrrev_i32_e32 v181, 5, v170
	v_mad_u64_u32 v[170:171], s[0:1], v181, s45, v[160:161]
	ds_read2_b64 v[170:173], v170 offset1:1
	s_waitcnt lgkmcnt(1)
	global_store_dwordx4 v[178:179], v[162:165], off
	s_nop 1
	v_add_u32_e32 v162, s19, v181
	v_mad_i64_i32 v[162:163], s[0:1], v180, v162, 0
	v_lshl_add_u64 v[162:163], v[162:163], 1, v[174:175]
	v_lshl_add_u64 v[162:163], v[162:163], 0, v[176:177]
	s_waitcnt lgkmcnt(0)
	global_store_dwordx4 v[162:163], v[170:173], off
	v_add_u32_e32 v162, 0x800, v166
	v_ashrrev_i32_e32 v164, 5, v162
	v_add_u32_e32 v162, s19, v164
	v_mad_i64_i32 v[162:163], s[0:1], v180, v162, 0
	v_lshl_add_u64 v[162:163], v[162:163], 1, v[174:175]
	v_lshl_add_u64 v[178:179], v[162:163], 0, v[176:177]
	v_mad_u64_u32 v[162:163], s[0:1], v164, s45, v[160:161]
	ds_read2_b64 v[162:165], v162 offset1:1
	v_add_u32_e32 v170, 0xa00, v166
	v_ashrrev_i32_e32 v181, 5, v170
	v_mad_u64_u32 v[170:171], s[0:1], v181, s45, v[160:161]
	ds_read2_b64 v[170:173], v170 offset1:1
	s_waitcnt lgkmcnt(1)
	global_store_dwordx4 v[178:179], v[162:165], off
	s_nop 1
	v_add_u32_e32 v162, s19, v181
	v_mad_i64_i32 v[162:163], s[0:1], v180, v162, 0
	v_lshl_add_u64 v[162:163], v[162:163], 1, v[174:175]
	v_lshl_add_u64 v[162:163], v[162:163], 0, v[176:177]
	s_waitcnt lgkmcnt(0)
	global_store_dwordx4 v[162:163], v[170:173], off
	v_add_u32_e32 v162, 0xc00, v166
	v_ashrrev_i32_e32 v164, 5, v162
	v_add_u32_e32 v162, s19, v164
	v_mad_i64_i32 v[162:163], s[0:1], v180, v162, 0
	v_lshl_add_u64 v[162:163], v[162:163], 1, v[174:175]
	v_lshl_add_u64 v[178:179], v[162:163], 0, v[176:177]
	v_mad_u64_u32 v[162:163], s[0:1], v164, s45, v[160:161]
	ds_read2_b64 v[162:165], v162 offset1:1
	v_add_u32_e32 v170, 0xe00, v166
	v_ashrrev_i32_e32 v181, 5, v170
	v_mad_u64_u32 v[170:171], s[0:1], v181, s45, v[160:161]
	ds_read2_b64 v[170:173], v170 offset1:1
	s_waitcnt lgkmcnt(1)
; DI void stg16_nt(void* p, u32x4 v) { __builtin_nontemporal_store(v, (u32x4*)p); }
; DI void epi_seg(const f32x16 (&acc)[4][2], const Seg& sg0, const Seg& sg1, int m0, int n0, const float* rs, const float2* cs64, const float2* cs32, bf16_t* stg) {
;     ...
;   __syncthreads();
; #pragma unroll
;   for (int it = 0; it < 16; ++it) {
;     const int idx = tid + NTHR * it, rr = idx >> 5, c = idx & 31;
;     const Seg& fs = (c >> 4) ? sg1 : sg0;
;     const int lcc = n0 + c * 8 - fs.cbase;
;     if (fs.kind != K_NONE && lcc < fs.nvalid) {
;       const int row = m0 + rr;
;       size_t off;
;       if (fs.kind == K_KC2) { const int b = row >> 9, n = (row >> 2) & 127, g = row & 3; off = ((size_t)((b * 4 + g) * 128 + n)) * 64 + lcc; }
;       else off = (size_t)row * fs.ld + lcc;
;       stg16_nt(fs.dst + off, stage_read16(stg, rr, c));
;     }
;   }
	global_store_dwordx4 v[178:179], v[162:165], off
	s_nop 1
	v_add_u32_e32 v162, s19, v181
	v_mad_i64_i32 v[162:163], s[0:1], v180, v162, 0
	v_lshl_add_u64 v[162:163], v[162:163], 1, v[174:175]
	v_lshl_add_u64 v[162:163], v[162:163], 0, v[176:177]
	s_waitcnt lgkmcnt(0)
	global_store_dwordx4 v[162:163], v[170:173], off
	v_add_u32_e32 v162, 0x1000, v166
	v_ashrrev_i32_e32 v164, 5, v162
	v_add_u32_e32 v162, s19, v164
	v_mad_i64_i32 v[162:163], s[0:1], v180, v162, 0
	v_lshl_add_u64 v[162:163], v[162:163], 1, v[174:175]
	v_lshl_add_u64 v[178:179], v[162:163], 0, v[176:177]
	v_mad_u64_u32 v[162:163], s[0:1], v164, s45, v[160:161]
	ds_read2_b64 v[162:165], v162 offset1:1
	v_add_u32_e32 v170, 0x1200, v166
	v_ashrrev_i32_e32 v181, 5, v170
	v_mad_u64_u32 v[170:171], s[0:1], v181, s45, v[160:161]
	ds_read2_b64 v[170:173], v170 offset1:1
	s_waitcnt lgkmcnt(1)
	global_store_dwordx4 v[178:179], v[162:165], off
	s_nop 1
	v_add_u32_e32 v162, s19, v181
	v_mad_i64_i32 v[162:163], s[0:1], v180, v162, 0
	v_lshl_add_u64 v[162:163], v[162:163], 1, v[174:175]
	v_lshl_add_u64 v[162:163], v[162:163], 0, v[176:177]
	s_waitcnt lgkmcnt(0)
	global_store_dwordx4 v[162:163], v[170:173], off
	v_add_u32_e32 v162, 0x1400, v166
	v_ashrrev_i32_e32 v164, 5, v162
	v_add_u32_e32 v162, s19, v164
	v_mad_i64_i32 v[162:163], s[0:1], v180, v162, 0
	v_lshl_add_u64 v[162:163], v[162:163], 1, v[174:175]
	v_lshl_add_u64 v[178:179], v[162:163], 0, v[176:177]
	v_mad_u64_u32 v[162:163], s[0:1], v164, s45, v[160:161]
	ds_read2_b64 v[162:165], v162 offset1:1
	v_add_u32_e32 v170, 0x1600, v166
	v_ashrrev_i32_e32 v181, 5, v170
	v_mad_u64_u32 v[170:171], s[0:1], v181, s45, v[160:161]
	ds_read2_b64 v[170:173], v170 offset1:1
	s_waitcnt lgkmcnt(1)
	global_store_dwordx4 v[178:179], v[162:165], off
	s_nop 1
	v_add_u32_e32 v162, s19, v181
	v_mad_i64_i32 v[162:163], s[0:1], v180, v162, 0
	v_lshl_add_u64 v[162:163], v[162:163], 1, v[174:175]
	v_lshl_add_u64 v[162:163], v[162:163], 0, v[176:177]
	s_waitcnt lgkmcnt(0)
	global_store_dwordx4 v[162:163], v[170:173], off
	v_add_u32_e32 v162, 0x1800, v166
	v_ashrrev_i32_e32 v164, 5, v162
	v_add_u32_e32 v162, s19, v164
	v_mad_i64_i32 v[162:163], s[0:1], v180, v162, 0
	v_lshl_add_u64 v[162:163], v[162:163], 1, v[174:175]
	v_lshl_add_u64 v[178:179], v[162:163], 0, v[176:177]
	v_mad_u64_u32 v[162:163], s[0:1], v164, s45, v[160:161]
	ds_read2_b64 v[162:165], v162 offset1:1
	v_add_u32_e32 v170, 0x1a00, v166
	v_ashrrev_i32_e32 v181, 5, v170
	v_mad_u64_u32 v[170:171], s[0:1], v181, s45, v[160:161]
	ds_read2_b64 v[170:173], v170 offset1:1
	s_waitcnt lgkmcnt(1)
	global_store_dwordx4 v[178:179], v[162:165], off
	s_nop 1
	v_add_u32_e32 v162, s19, v181
	v_mad_i64_i32 v[162:163], s[0:1], v180, v162, 0
	v_lshl_add_u64 v[162:163], v[162:163], 1, v[174:175]
	v_lshl_add_u64 v[162:163], v[162:163], 0, v[176:177]
	s_waitcnt lgkmcnt(0)
	global_store_dwordx4 v[162:163], v[170:173], off
	v_add_u32_e32 v162, 0x1c00, v166
	v_ashrrev_i32_e32 v164, 5, v162
	v_add_u32_e32 v162, s19, v164
	v_mad_i64_i32 v[162:163], s[0:1], v180, v162, 0
	v_lshl_add_u64 v[162:163], v[162:163], 1, v[174:175]
	v_lshl_add_u64 v[178:179], v[162:163], 0, v[176:177]
	v_mad_u64_u32 v[162:163], s[0:1], v164, s45, v[160:161]
	ds_read2_b64 v[162:165], v162 offset1:1
	v_add_u32_e32 v170, 0x1e00, v166
	v_ashrrev_i32_e32 v181, 5, v170
	v_mad_u64_u32 v[170:171], s[0:1], v181, s45, v[160:161]
	ds_read2_b64 v[170:173], v170 offset1:1
	v_add_u32_e32 v160, s19, v181
	s_waitcnt lgkmcnt(1)
	global_store_dwordx4 v[178:179], v[162:165], off
	s_nop 1
	v_mad_i64_i32 v[162:163], s[0:1], v180, v160, 0
	v_lshl_add_u64 v[162:163], v[162:163], 1, v[174:175]
	v_lshl_add_u64 v[162:163], v[162:163], 0, v[176:177]
	s_waitcnt lgkmcnt(0)
	global_store_dwordx4 v[162:163], v[170:173], off

; DI unsigned pack2(float a, float b) { f32x2_t v = {a, b}; bf16x2_t r = __builtin_convertvector(v, bf16x2_t); return __builtin_bit_cast(unsigned, r); }
; DI void epi_seg(const f32x16 (&acc)[4][2], const Seg& sg0, const Seg& sg1, int m0, int n0, const float* rs, const float2* cs64, const float2* cs32, bf16_t* stg) {
;     ...
;   if (kind0 == K_VT) {
; #pragma unroll
;     for (int i = 0; i < 4; ++i)
; #pragma unroll
;       for (int q4 = 0; q4 < 4; ++q4) {
;         const int t0l = wm * 128 + i * 32 + 8 * q4 + 4 * h;
;         float s0 = 1.f, s1 = 1.f, s2 = 1.f, s3 = 1.f;
;         if (rs) { s0 = rs[t0l]; s1 = rs[t0l + 1]; s2 = rs[t0l + 2]; s3 = rs[t0l + 3]; }
; #pragma unroll
;         for (int j = 0; j < 2; ++j)
;           *(uint2*)(stg + (wn * 64 + j * 32 + r) * STG + t0l) =
;               make_uint2(pack2(acc[i][j][4 * q4] * s0, acc[i][j][4 * q4 + 1] * s1), pack2(acc[i][j][4 * q4 + 2] * s2, acc[i][j][4 * q4 + 3] * s3));
;       }
;     __syncthreads();
;     const int b = m0 >> 11, s0 = m0 & (SEQ - 1);
.LBB0_1593:
	v_and_b32_e32 v162, 0xffffff00, v166
	v_lshl_or_b32 v160, v169, 6, v167
	v_lshl_or_b32 v162, v168, 3, v162
	v_cvt_pk_bf16_f32 v0, v0, v1
	v_cvt_pk_bf16_f32 v1, v2, v3
	v_mad_u32_u24 v160, v160, s45, v162
	v_cvt_pk_bf16_f32 v4, v4, v5
	v_cvt_pk_bf16_f32 v5, v6, v7
	v_cvt_pk_bf16_f32 v2, v112, v113
	v_cvt_pk_bf16_f32 v3, v114, v115
	ds_write2_b64 v160, v[0:1], v[4:5] offset1:2
	v_cvt_pk_bf16_f32 v0, v116, v117
	v_cvt_pk_bf16_f32 v1, v118, v119
	v_add_u32_e32 v6, 0x4000, v160
	ds_write2_b64 v6, v[2:3], v[0:1] offset0:32 offset1:34
	v_cvt_pk_bf16_f32 v0, v8, v9
	v_cvt_pk_bf16_f32 v1, v10, v11
	v_cvt_pk_bf16_f32 v4, v12, v13
	v_cvt_pk_bf16_f32 v5, v14, v15
	v_cvt_pk_bf16_f32 v2, v120, v121
	v_cvt_pk_bf16_f32 v3, v122, v123
	ds_write2_b64 v160, v[0:1], v[4:5] offset0:4 offset1:6
	v_cvt_pk_bf16_f32 v0, v124, v125
	v_cvt_pk_bf16_f32 v1, v126, v127
	ds_write2_b64 v6, v[2:3], v[0:1] offset0:36 offset1:38
	v_cvt_pk_bf16_f32 v0, v48, v49
	v_cvt_pk_bf16_f32 v1, v50, v51
	v_cvt_pk_bf16_f32 v4, v52, v53
	v_cvt_pk_bf16_f32 v5, v54, v55
	v_cvt_pk_bf16_f32 v2, v96, v97
	v_cvt_pk_bf16_f32 v3, v98, v99
	ds_write2_b64 v160, v[0:1], v[4:5] offset0:8 offset1:10
	v_cvt_pk_bf16_f32 v0, v100, v101
	v_cvt_pk_bf16_f32 v1, v102, v103
	ds_write2_b64 v6, v[2:3], v[0:1] offset0:40 offset1:42
	v_cvt_pk_bf16_f32 v0, v56, v57
	v_cvt_pk_bf16_f32 v1, v58, v59
	v_cvt_pk_bf16_f32 v4, v60, v61
	v_cvt_pk_bf16_f32 v5, v62, v63
	v_cvt_pk_bf16_f32 v2, v104, v105
	v_cvt_pk_bf16_f32 v3, v106, v107
	ds_write2_b64 v160, v[0:1], v[4:5] offset0:12 offset1:14
	v_cvt_pk_bf16_f32 v0, v108, v109
	v_cvt_pk_bf16_f32 v1, v110, v111
	ds_write2_b64 v6, v[2:3], v[0:1] offset0:44 offset1:46
	v_cvt_pk_bf16_f32 v0, v32, v33
	v_cvt_pk_bf16_f32 v1, v34, v35
	v_cvt_pk_bf16_f32 v4, v36, v37
	v_cvt_pk_bf16_f32 v5, v38, v39
	v_cvt_pk_bf16_f32 v2, v80, v81
	v_cvt_pk_bf16_f32 v3, v82, v83
	ds_write2_b64 v160, v[0:1], v[4:5] offset0:16 offset1:18
	v_cvt_pk_bf16_f32 v0, v84, v85
	v_cvt_pk_bf16_f32 v1, v86, v87
	ds_write2_b64 v6, v[2:3], v[0:1] offset0:48 offset1:50
	v_cvt_pk_bf16_f32 v0, v40, v41
	v_cvt_pk_bf16_f32 v1, v42, v43
	v_cvt_pk_bf16_f32 v4, v44, v45
	v_cvt_pk_bf16_f32 v5, v46, v47
	v_cvt_pk_bf16_f32 v2, v88, v89
	v_cvt_pk_bf16_f32 v3, v90, v91
	ds_write2_b64 v160, v[0:1], v[4:5] offset0:20 offset1:22
	v_cvt_pk_bf16_f32 v0, v92, v93
	v_cvt_pk_bf16_f32 v1, v94, v95
	ds_write2_b64 v6, v[2:3], v[0:1] offset0:52 offset1:54
	v_cvt_pk_bf16_f32 v0, v16, v17
	v_cvt_pk_bf16_f32 v1, v18, v19
	v_cvt_pk_bf16_f32 v4, v20, v21
	v_cvt_pk_bf16_f32 v5, v22, v23
	v_cvt_pk_bf16_f32 v2, v64, v65
	v_cvt_pk_bf16_f32 v3, v66, v67
	ds_write2_b64 v160, v[0:1], v[4:5] offset0:24 offset1:26
	v_cvt_pk_bf16_f32 v0, v68, v69
	v_cvt_pk_bf16_f32 v1, v70, v71
	ds_write2_b64 v6, v[2:3], v[0:1] offset0:56 offset1:58
	v_cvt_pk_bf16_f32 v0, v24, v25
	v_cvt_pk_bf16_f32 v1, v26, v27
	v_cvt_pk_bf16_f32 v4, v28, v29
	v_cvt_pk_bf16_f32 v5, v30, v31
	s_lshl_b32 s0, s6, 5
	v_cvt_pk_bf16_f32 v2, v72, v73
	v_cvt_pk_bf16_f32 v3, v74, v75
	ds_write2_b64 v160, v[0:1], v[4:5] offset0:28 offset1:30
	v_cvt_pk_bf16_f32 v0, v76, v77
	v_cvt_pk_bf16_f32 v1, v78, v79
	s_and_b32 s0, s0, 0xffffff00
	s_sub_i32 s6, s17, s48
	ds_write2_b64 v6, v[2:3], v[0:1] offset0:60 offset1:62
	v_ashrrev_i32_e32 v2, 5, v166
	s_add_i32 s0, s6, s0
	v_add_u32_e32 v0, s0, v2
	v_ashrrev_i32_e32 v1, 31, v0
	s_and_b32 s1, s19, 0x700
	v_lshlrev_b64 v[0:1], 12, v[0:1]
	v_lshl_add_u64 v[0:1], s[14:15], 0, v[0:1]
	s_lshl_b32 s6, s1, 1
	v_lshlrev_b32_e32 v160, 4, v167
	v_lshl_add_u64 v[0:1], v[0:1], 0, s[6:7]
	v_lshl_add_u64 v[8:9], v[0:1], 0, v[160:161]
	v_mad_u64_u32 v[0:1], s[16:17], v2, s45, v[160:161]
	s_waitcnt lgkmcnt(0)
	s_barrier
; DI void stg16_nt(void* p, u32x4 v) { __builtin_nontemporal_store(v, (u32x4*)p); }
; DI void epi_seg(const f32x16 (&acc)[4][2], const Seg& sg0, const Seg& sg1, int m0, int n0, const float* rs, const float2* cs64, const float2* cs32, bf16_t* stg) {
;     ...
; #pragma unroll
;     for (int it = 0; it < 16; ++it) {
;       const int idx = tid + NTHR * it, rr = idx >> 5, c = idx & 31;
;       const int lc = n0 + rr - sg0.cbase, g = lc >> 6, d = lc & 63;
;       stg16_nt(sg0.dst + ((size_t)((b * sg0.G + g) * 64 + d)) * SEQ + s0 + c * 8, stage_read16(stg, rr, c));
;     }
;     __syncthreads();
;     return;
	ds_read2_b64 v[0:3], v0 offset1:1
	v_add_u32_e32 v4, 0x200, v166
	v_ashrrev_i32_e32 v10, 5, v4
	v_mad_u64_u32 v[4:5], s[16:17], v10, s45, v[160:161]
	ds_read2_b64 v[4:7], v4 offset1:1
	s_waitcnt lgkmcnt(1)
	global_store_dwordx4 v[8:9], v[0:3], off
	s_nop 1
	v_add_u32_e32 v0, s0, v10
	v_ashrrev_i32_e32 v1, 31, v0
	v_lshlrev_b64 v[0:1], 12, v[0:1]
	v_lshl_add_u64 v[0:1], s[14:15], 0, v[0:1]
	v_lshl_add_u64 v[0:1], v[0:1], 0, s[6:7]
	v_lshl_add_u64 v[0:1], v[0:1], 0, v[160:161]
	s_waitcnt lgkmcnt(0)
	global_store_dwordx4 v[0:1], v[4:7], off
	v_add_u32_e32 v0, 0x400, v166
	v_ashrrev_i32_e32 v2, 5, v0
	v_add_u32_e32 v0, s0, v2
	v_ashrrev_i32_e32 v1, 31, v0
	v_lshlrev_b64 v[0:1], 12, v[0:1]
	v_lshl_add_u64 v[0:1], s[14:15], 0, v[0:1]
	v_lshl_add_u64 v[0:1], v[0:1], 0, s[6:7]
	v_lshl_add_u64 v[8:9], v[0:1], 0, v[160:161]
	v_mad_u64_u32 v[0:1], s[16:17], v2, s45, v[160:161]
	ds_read2_b64 v[0:3], v0 offset1:1
	v_add_u32_e32 v4, 0x600, v166
	v_ashrrev_i32_e32 v10, 5, v4
	v_mad_u64_u32 v[4:5], s[16:17], v10, s45, v[160:161]
	ds_read2_b64 v[4:7], v4 offset1:1
	s_waitcnt lgkmcnt(1)
	global_store_dwordx4 v[8:9], v[0:3], off
	s_nop 1
	v_add_u32_e32 v0, s0, v10
	v_ashrrev_i32_e32 v1, 31, v0
	v_lshlrev_b64 v[0:1], 12, v[0:1]
	v_lshl_add_u64 v[0:1], s[14:15], 0, v[0:1]
	v_lshl_add_u64 v[0:1], v[0:1], 0, s[6:7]
	v_lshl_add_u64 v[0:1], v[0:1], 0, v[160:161]
	s_waitcnt lgkmcnt(0)
	global_store_dwordx4 v[0:1], v[4:7], off
	v_add_u32_e32 v0, 0x800, v166
	v_ashrrev_i32_e32 v2, 5, v0
	v_add_u32_e32 v0, s0, v2
	v_ashrrev_i32_e32 v1, 31, v0
	v_lshlrev_b64 v[0:1], 12, v[0:1]
	v_lshl_add_u64 v[0:1], s[14:15], 0, v[0:1]
	v_lshl_add_u64 v[0:1], v[0:1], 0, s[6:7]
	v_lshl_add_u64 v[8:9], v[0:1], 0, v[160:161]
	v_mad_u64_u32 v[0:1], s[16:17], v2, s45, v[160:161]
	ds_read2_b64 v[0:3], v0 offset1:1
	v_add_u32_e32 v4, 0xa00, v166
	v_ashrrev_i32_e32 v10, 5, v4
	v_mad_u64_u32 v[4:5], s[16:17], v10, s45, v[160:161]
	ds_read2_b64 v[4:7], v4 offset1:1
	s_waitcnt lgkmcnt(1)
	global_store_dwordx4 v[8:9], v[0:3], off
	s_nop 1
	v_add_u32_e32 v0, s0, v10
	v_ashrrev_i32_e32 v1, 31, v0
	v_lshlrev_b64 v[0:1], 12, v[0:1]
	v_lshl_add_u64 v[0:1], s[14:15], 0, v[0:1]
	v_lshl_add_u64 v[0:1], v[0:1], 0, s[6:7]
	v_lshl_add_u64 v[0:1], v[0:1], 0, v[160:161]
	s_waitcnt lgkmcnt(0)
	global_store_dwordx4 v[0:1], v[4:7], off
	v_add_u32_e32 v0, 0xc00, v166
	v_ashrrev_i32_e32 v2, 5, v0
	v_add_u32_e32 v0, s0, v2
	v_ashrrev_i32_e32 v1, 31, v0
	v_lshlrev_b64 v[0:1], 12, v[0:1]
	v_lshl_add_u64 v[0:1], s[14:15], 0, v[0:1]
	v_lshl_add_u64 v[0:1], v[0:1], 0, s[6:7]
	v_lshl_add_u64 v[8:9], v[0:1], 0, v[160:161]
	v_mad_u64_u32 v[0:1], s[16:17], v2, s45, v[160:161]
	ds_read2_b64 v[0:3], v0 offset1:1
	v_add_u32_e32 v4, 0xe00, v166
	v_ashrrev_i32_e32 v10, 5, v4
	v_mad_u64_u32 v[4:5], s[16:17], v10, s45, v[160:161]
	ds_read2_b64 v[4:7], v4 offset1:1
	s_waitcnt lgkmcnt(1)
	global_store_dwordx4 v[8:9], v[0:3], off
	s_nop 1
	v_add_u32_e32 v0, s0, v10
	v_ashrrev_i32_e32 v1, 31, v0
	v_lshlrev_b64 v[0:1], 12, v[0:1]
	v_lshl_add_u64 v[0:1], s[14:15], 0, v[0:1]
	v_lshl_add_u64 v[0:1], v[0:1], 0, s[6:7]
	v_lshl_add_u64 v[0:1], v[0:1], 0, v[160:161]
	s_waitcnt lgkmcnt(0)
	global_store_dwordx4 v[0:1], v[4:7], off
	v_add_u32_e32 v0, 0x1000, v166
	v_ashrrev_i32_e32 v2, 5, v0
	v_add_u32_e32 v0, s0, v2
	v_ashrrev_i32_e32 v1, 31, v0
	v_lshlrev_b64 v[0:1], 12, v[0:1]
	v_lshl_add_u64 v[0:1], s[14:15], 0, v[0:1]
	v_lshl_add_u64 v[0:1], v[0:1], 0, s[6:7]
	v_lshl_add_u64 v[8:9], v[0:1], 0, v[160:161]
	v_mad_u64_u32 v[0:1], s[16:17], v2, s45, v[160:161]
	ds_read2_b64 v[0:3], v0 offset1:1
	v_add_u32_e32 v4, 0x1200, v166
	v_ashrrev_i32_e32 v10, 5, v4
	v_mad_u64_u32 v[4:5], s[16:17], v10, s45, v[160:161]
	ds_read2_b64 v[4:7], v4 offset1:1
	s_waitcnt lgkmcnt(1)
	global_store_dwordx4 v[8:9], v[0:3], off
	s_nop 1
	v_add_u32_e32 v0, s0, v10
	v_ashrrev_i32_e32 v1, 31, v0
	v_lshlrev_b64 v[0:1], 12, v[0:1]
	v_lshl_add_u64 v[0:1], s[14:15], 0, v[0:1]
	v_lshl_add_u64 v[0:1], v[0:1], 0, s[6:7]
	v_lshl_add_u64 v[0:1], v[0:1], 0, v[160:161]
	s_waitcnt lgkmcnt(0)
	global_store_dwordx4 v[0:1], v[4:7], off
	v_add_u32_e32 v0, 0x1400, v166
	v_ashrrev_i32_e32 v2, 5, v0
	v_add_u32_e32 v0, s0, v2
	v_ashrrev_i32_e32 v1, 31, v0
	v_lshlrev_b64 v[0:1], 12, v[0:1]
	v_lshl_add_u64 v[0:1], s[14:15], 0, v[0:1]
	v_lshl_add_u64 v[0:1], v[0:1], 0, s[6:7]
	v_lshl_add_u64 v[8:9], v[0:1], 0, v[160:161]
	v_mad_u64_u32 v[0:1], s[16:17], v2, s45, v[160:161]
	ds_read2_b64 v[0:3], v0 offset1:1
	v_add_u32_e32 v4, 0x1600, v166
	v_ashrrev_i32_e32 v10, 5, v4
	v_mad_u64_u32 v[4:5], s[16:17], v10, s45, v[160:161]
	ds_read2_b64 v[4:7], v4 offset1:1
	s_waitcnt lgkmcnt(1)
	global_store_dwordx4 v[8:9], v[0:3], off
	s_nop 1
	v_add_u32_e32 v0, s0, v10
	v_ashrrev_i32_e32 v1, 31, v0
	v_lshlrev_b64 v[0:1], 12, v[0:1]
	v_lshl_add_u64 v[0:1], s[14:15], 0, v[0:1]
	v_lshl_add_u64 v[0:1], v[0:1], 0, s[6:7]
	v_lshl_add_u64 v[0:1], v[0:1], 0, v[160:161]
	s_waitcnt lgkmcnt(0)
	global_store_dwordx4 v[0:1], v[4:7], off
	v_add_u32_e32 v0, 0x1800, v166
	v_ashrrev_i32_e32 v2, 5, v0
	v_add_u32_e32 v0, s0, v2
	v_ashrrev_i32_e32 v1, 31, v0
	v_lshlrev_b64 v[0:1], 12, v[0:1]
	v_lshl_add_u64 v[0:1], s[14:15], 0, v[0:1]
	v_lshl_add_u64 v[0:1], v[0:1], 0, s[6:7]
	v_lshl_add_u64 v[8:9], v[0:1], 0, v[160:161]
	v_mad_u64_u32 v[0:1], s[16:17], v2, s45, v[160:161]
	ds_read2_b64 v[0:3], v0 offset1:1
	v_add_u32_e32 v4, 0x1a00, v166
	v_ashrrev_i32_e32 v10, 5, v4
	v_mad_u64_u32 v[4:5], s[16:17], v10, s45, v[160:161]
	ds_read2_b64 v[4:7], v4 offset1:1
	s_waitcnt lgkmcnt(1)
	global_store_dwordx4 v[8:9], v[0:3], off
	s_nop 1
	v_add_u32_e32 v0, s0, v10
	v_ashrrev_i32_e32 v1, 31, v0
	v_lshlrev_b64 v[0:1], 12, v[0:1]
	v_lshl_add_u64 v[0:1], s[14:15], 0, v[0:1]
	v_lshl_add_u64 v[0:1], v[0:1], 0, s[6:7]
	v_lshl_add_u64 v[0:1], v[0:1], 0, v[160:161]
	s_waitcnt lgkmcnt(0)
	global_store_dwordx4 v[0:1], v[4:7], off
	v_add_u32_e32 v0, 0x1c00, v166
	v_ashrrev_i32_e32 v2, 5, v0
	v_add_u32_e32 v0, s0, v2
	v_ashrrev_i32_e32 v1, 31, v0
	v_lshlrev_b64 v[0:1], 12, v[0:1]
	v_lshl_add_u64 v[0:1], s[14:15], 0, v[0:1]
	v_lshl_add_u64 v[0:1], v[0:1], 0, s[6:7]
	v_lshl_add_u64 v[8:9], v[0:1], 0, v[160:161]
	v_mad_u64_u32 v[0:1], s[16:17], v2, s45, v[160:161]
	ds_read2_b64 v[0:3], v0 offset1:1
	v_add_u32_e32 v4, 0x1e00, v166
	v_ashrrev_i32_e32 v10, 5, v4
	v_mad_u64_u32 v[4:5], s[16:17], v10, s45, v[160:161]
	ds_read2_b64 v[4:7], v4 offset1:1
	s_waitcnt lgkmcnt(1)
	global_store_dwordx4 v[8:9], v[0:3], off
	s_nop 1
	v_add_u32_e32 v0, s0, v10
	v_ashrrev_i32_e32 v1, 31, v0
	v_lshlrev_b64 v[0:1], 12, v[0:1]
	v_lshl_add_u64 v[0:1], s[14:15], 0, v[0:1]
	v_lshl_add_u64 v[0:1], v[0:1], 0, s[6:7]
	v_lshl_add_u64 v[0:1], v[0:1], 0, v[160:161]
	s_waitcnt lgkmcnt(0)
	global_store_dwordx4 v[0:1], v[4:7], off
	s_barrier
	s_branch .LBB0_1563
